# early L1 invalidate in grid barrier non-leader path; counted waits in slab norm phases; nt stores for converted weights
# speedup vs baseline: 1.0046x; 1.0046x over previous
.LBB0_124:
	s_cmpk_gt_u32 s4, 0x5fff
	s_cbranch_scc0 .LBB0_141
	s_cmp_gt_u32 s4, 0x167ff
	s_cbranch_scc0 .LBB0_131
	s_cmp_gt_u32 s4, 0x177ff
	s_cbranch_scc0 .LBB0_128
	s_add_i32 s0, s4, 0xfffe8800
	s_lshr_b32 s20, s0, 12
	v_readlane_b32 s48, v251, 6
	s_bfe_u32 s2, s0, 0x1000b
	s_lshl_b64 s[0:1], s[20:21], 25
	v_readlane_b32 s52, v251, 10
	v_readlane_b32 s53, v251, 11
	s_add_u32 s0, s52, s0
	s_addc_u32 s1, s53, s1
	s_lshl_b32 s3, s2, 13
	s_add_u32 s8, s0, s3
	s_addc_u32 s9, s1, 0
	s_lshl_b64 s[0:1], s[20:21], 24
	v_readlane_b32 s10, v251, 50
	v_readlane_b32 s11, v251, 51
	s_add_u32 s5, s10, s0
	s_addc_u32 s3, s11, s1
	s_lshl_b32 s1, s4, 5
	s_lshl_b32 s10, s4, 6
	s_and_b32 s1, s1, 0x60
	s_lshl_b32 s2, s2, 7
	s_and_b32 s0, s4, 63
	s_and_b32 s10, s10, 0xf00
	s_or_b32 s1, s2, s1
	s_and_b32 s7, s4, 0x7c0
	s_or_b32 s2, s1, s10
	s_lshl_b32 s0, s0, 7
	s_add_u32 s0, s8, s0
	v_or_b32_e32 v12, s7, v1
	s_addc_u32 s1, s9, 0
	v_lshlrev_b32_e32 v46, 2, v2
	v_lshl_add_u64 v[10:11], s[0:1], 0, v[46:47]
	v_lshlrev_b32_e32 v46, 14, v12
	v_lshl_add_u64 v[10:11], v[10:11], 0, v[46:47]
	v_add_co_u32_e32 v12, vcc, s25, v10
	s_mov_b32 s48, 0x10000
	s_nop 0
	v_addc_co_u32_e32 v13, vcc, 0, v11, vcc
	v_readlane_b32 s49, v251, 7
	v_add_co_u32_e32 v14, vcc, s48, v10
	s_mov_b32 s49, 0x18000
	s_nop 0
	v_addc_co_u32_e32 v15, vcc, 0, v11, vcc
	v_add_co_u32_e32 v16, vcc, s49, v10
	s_mov_b32 s0, 0x20000
	s_nop 0
	v_addc_co_u32_e32 v17, vcc, 0, v11, vcc
	v_add_co_u32_e32 v18, vcc, s0, v10
	s_mov_b32 s0, 0x28000
	s_nop 0
	v_addc_co_u32_e32 v19, vcc, 0, v11, vcc
	v_add_co_u32_e32 v20, vcc, s0, v10
	s_mov_b32 s0, 0x30000
	s_nop 0
	v_addc_co_u32_e32 v21, vcc, 0, v11, vcc
	v_add_co_u32_e32 v22, vcc, s0, v10
	s_mov_b32 s0, 0x38000
	s_nop 0
	v_addc_co_u32_e32 v23, vcc, 0, v11, vcc
	v_add_co_u32_e32 v24, vcc, s0, v10
	s_mov_b32 s0, 0x40000
	s_nop 0
	v_addc_co_u32_e32 v25, vcc, 0, v11, vcc
	global_load_dword v28, v[10:11], off nt
	global_load_dword v29, v[12:13], off nt
	global_load_dword v30, v[14:15], off nt
	global_load_dword v31, v[16:17], off nt
	global_load_dword v32, v[18:19], off nt
	global_load_dword v33, v[20:21], off nt
	global_load_dword v34, v[22:23], off nt
	global_load_dword v35, v[24:25], off nt
	v_add_co_u32_e32 v12, vcc, s0, v10
	s_mov_b32 s0, 0x48000
	s_nop 0
	v_addc_co_u32_e32 v13, vcc, 0, v11, vcc
	v_add_co_u32_e32 v14, vcc, s0, v10
	s_mov_b32 s0, 0x50000
	s_nop 0
	v_addc_co_u32_e32 v15, vcc, 0, v11, vcc
	v_add_co_u32_e32 v16, vcc, s0, v10
	s_mov_b32 s0, 0x58000
	s_nop 0
	v_addc_co_u32_e32 v17, vcc, 0, v11, vcc
	v_add_co_u32_e32 v18, vcc, s0, v10
	s_mov_b32 s0, 0x60000
	s_nop 0
	v_addc_co_u32_e32 v19, vcc, 0, v11, vcc
	v_add_co_u32_e32 v20, vcc, s0, v10
	s_mov_b32 s0, 0x68000
	s_nop 0
	v_addc_co_u32_e32 v21, vcc, 0, v11, vcc
	v_add_co_u32_e32 v22, vcc, s0, v10
	s_mov_b32 s0, 0x70000
	s_nop 0
	v_addc_co_u32_e32 v23, vcc, 0, v11, vcc
	v_add_co_u32_e32 v24, vcc, s0, v10
	s_mov_b32 s0, 0x78000
	s_nop 0
	v_addc_co_u32_e32 v25, vcc, 0, v11, vcc
	v_add_co_u32_e32 v26, vcc, s0, v10
	s_mov_b32 s0, 0x80000
	s_nop 0
	v_addc_co_u32_e32 v27, vcc, 0, v11, vcc
	global_load_dword v36, v[12:13], off nt
	global_load_dword v37, v[14:15], off nt
	global_load_dword v38, v[16:17], off nt
	global_load_dword v39, v[18:19], off nt
	global_load_dword v40, v[20:21], off nt
	global_load_dword v41, v[22:23], off nt
	global_load_dword v42, v[24:25], off nt
	global_load_dword v43, v[26:27], off nt
	v_add_co_u32_e32 v12, vcc, s0, v10
	s_mov_b32 s0, 0x88000
	s_nop 0
	v_addc_co_u32_e32 v13, vcc, 0, v11, vcc
	v_add_co_u32_e32 v14, vcc, s0, v10
	s_mov_b32 s0, 0x90000
	s_nop 0
	v_addc_co_u32_e32 v15, vcc, 0, v11, vcc
	v_add_co_u32_e32 v16, vcc, s0, v10
	s_mov_b32 s0, 0x98000
	s_nop 0
	v_addc_co_u32_e32 v17, vcc, 0, v11, vcc
	v_add_co_u32_e32 v18, vcc, s0, v10
	s_mov_b32 s0, 0xa0000
	s_nop 0
	v_addc_co_u32_e32 v19, vcc, 0, v11, vcc
	v_add_co_u32_e32 v20, vcc, s0, v10
	s_mov_b32 s0, 0xa8000
	s_nop 0
	v_addc_co_u32_e32 v21, vcc, 0, v11, vcc
	v_add_co_u32_e32 v22, vcc, s0, v10
	s_mov_b32 s0, 0xb0000
	s_nop 0
	v_addc_co_u32_e32 v23, vcc, 0, v11, vcc
	v_add_co_u32_e32 v24, vcc, s0, v10
	s_mov_b32 s0, 0xb8000
	s_nop 0
	v_addc_co_u32_e32 v25, vcc, 0, v11, vcc
	v_add_co_u32_e32 v26, vcc, s0, v10
	s_mov_b32 s0, 0xc0000
	s_nop 0
	v_addc_co_u32_e32 v27, vcc, 0, v11, vcc
	global_load_dword v44, v[12:13], off nt
	global_load_dword v45, v[14:15], off nt
	global_load_dword v46, v[16:17], off nt
	global_load_dword v48, v[18:19], off nt
	global_load_dword v50, v[20:21], off nt
	global_load_dword v51, v[22:23], off nt
	global_load_dword v52, v[24:25], off nt
	s_nop 0
	global_load_dword v26, v[26:27], off nt
	v_add_co_u32_e32 v12, vcc, s0, v10
	s_mov_b32 s0, 0xc8000
	s_nop 0
	v_addc_co_u32_e32 v13, vcc, 0, v11, vcc
	v_add_co_u32_e32 v14, vcc, s0, v10
	s_mov_b32 s0, 0xd0000
	s_nop 0
	v_addc_co_u32_e32 v15, vcc, 0, v11, vcc
	v_add_co_u32_e32 v16, vcc, s0, v10
	s_mov_b32 s0, 0xd8000
	s_nop 0
	v_addc_co_u32_e32 v17, vcc, 0, v11, vcc
	v_add_co_u32_e32 v18, vcc, s0, v10
	s_mov_b32 s0, 0xe0000
	s_nop 0
	v_addc_co_u32_e32 v19, vcc, 0, v11, vcc
	v_add_co_u32_e32 v20, vcc, s0, v10
	s_mov_b32 s0, 0xe8000
	s_nop 0
	v_addc_co_u32_e32 v21, vcc, 0, v11, vcc
	v_add_co_u32_e32 v22, vcc, s0, v10
	s_mov_b32 s0, 0xf0000
	s_nop 0
	v_addc_co_u32_e32 v23, vcc, 0, v11, vcc
	v_add_co_u32_e32 v24, vcc, s0, v10
	s_mov_b32 s0, 0xf8000
	s_nop 0
	v_addc_co_u32_e32 v25, vcc, 0, v11, vcc
	v_add_co_u32_e32 v10, vcc, s0, v10
	s_lshl_b32 s0, s7, 1
	s_nop 0
	v_addc_co_u32_e32 v11, vcc, 0, v11, vcc
	global_load_dword v12, v[12:13], off nt
	s_nop 0
	global_load_dword v13, v[14:15], off nt
	s_nop 0
	global_load_dword v14, v[16:17], off nt
	global_load_dword v15, v[18:19], off nt
	s_nop 0
	global_load_dword v16, v[20:21], off nt
	global_load_dword v17, v[22:23], off nt
	global_load_dword v18, v[24:25], off nt
	s_nop 0
	global_load_dword v10, v[10:11], off nt
	v_add_u32_e32 v11, 0x400, v3
	s_waitcnt vmcnt(30)
	ds_write2_b32 v3, v28, v29 offset1:66
	s_waitcnt vmcnt(28)
	ds_write2_b32 v3, v30, v31 offset0:132 offset1:198
	s_waitcnt vmcnt(26)
	ds_write2_b32 v11, v32, v33 offset0:8 offset1:74
	s_waitcnt vmcnt(24)
	ds_write2_b32 v11, v34, v35 offset0:140 offset1:206
	v_add_u32_e32 v11, 0x800, v3
	s_waitcnt vmcnt(22)
	ds_write2_b32 v11, v36, v37 offset0:16 offset1:82
	s_waitcnt vmcnt(20)
	ds_write2_b32 v11, v38, v39 offset0:148 offset1:214
	v_add_u32_e32 v11, 0xc00, v3
	s_waitcnt vmcnt(18)
	ds_write2_b32 v11, v40, v41 offset0:24 offset1:90
	s_waitcnt vmcnt(16)
	ds_write2_b32 v11, v42, v43 offset0:156 offset1:222
	v_add_u32_e32 v11, 0x1000, v3
	s_waitcnt vmcnt(14)
	ds_write2_b32 v11, v44, v45 offset0:32 offset1:98
	s_waitcnt vmcnt(12)
	ds_write2_b32 v11, v46, v48 offset0:164 offset1:230
	v_add_u32_e32 v11, 0x1400, v3
	s_waitcnt vmcnt(10)
	ds_write2_b32 v11, v50, v51 offset0:40 offset1:106
	s_waitcnt vmcnt(8)
	ds_write2_b32 v11, v52, v26 offset0:172 offset1:238
	v_add_u32_e32 v11, 0x1800, v3
	s_waitcnt vmcnt(6)
	ds_write2_b32 v11, v12, v13 offset0:48 offset1:114
	s_waitcnt vmcnt(4)
	ds_write2_b32 v11, v14, v15 offset0:180 offset1:246
	v_add_u32_e32 v11, 0x1c00, v3
	s_waitcnt vmcnt(2)
	ds_write2_b32 v11, v16, v17 offset0:56 offset1:122
	s_waitcnt vmcnt(0)
	ds_write2_b32 v11, v18, v10 offset0:188 offset1:254
	s_waitcnt lgkmcnt(0)
	ds_read2_b32 v[14:15], v6 offset1:8
	ds_read2_b32 v[18:19], v6 offset0:33 offset1:41
	ds_read2_b32 v[20:21], v6 offset0:66 offset1:74
	ds_read2_b32 v[22:23], v6 offset0:99 offset1:107
	ds_read2_b32 v[24:25], v6 offset0:132 offset1:140
	s_waitcnt lgkmcnt(4)
	v_bfe_u32 v10, v14, 16, 1
	v_add3_u32 v10, v14, v10, s22
	s_waitcnt lgkmcnt(3)
	v_bfe_u32 v11, v18, 16, 1
	v_lshrrev_b32_e32 v10, 16, v10
	v_add3_u32 v11, v18, v11, s22
	ds_read2_b32 v[26:27], v6 offset0:165 offset1:173
	v_and_or_b32 v10, v11, s23, v10
	s_waitcnt lgkmcnt(3)
	v_bfe_u32 v11, v20, 16, 1
	v_add3_u32 v11, v20, v11, s22
	s_waitcnt lgkmcnt(2)
	v_bfe_u32 v12, v22, 16, 1
	ds_read2_b32 v[28:29], v6 offset0:198 offset1:206
	v_lshrrev_b32_e32 v11, 16, v11
	v_add3_u32 v12, v22, v12, s22
	ds_read2_b32 v[30:31], v6 offset0:231 offset1:239
	v_and_or_b32 v11, v12, s23, v11
	s_waitcnt lgkmcnt(3)
	v_bfe_u32 v12, v24, 16, 1
	v_add3_u32 v12, v24, v12, s22
	s_waitcnt lgkmcnt(2)
	v_bfe_u32 v13, v26, 16, 1
	v_lshrrev_b32_e32 v12, 16, v12
	v_add3_u32 v13, v26, v13, s22
	v_and_or_b32 v12, v13, s23, v12
	s_waitcnt lgkmcnt(1)
	v_bfe_u32 v13, v28, 16, 1
	v_add3_u32 v13, v28, v13, s22
	s_waitcnt lgkmcnt(0)
	v_bfe_u32 v14, v30, 16, 1
	s_add_u32 s0, s5, s0
	v_lshrrev_b32_e32 v13, 16, v13
	v_add3_u32 v14, v30, v14, s22
	s_addc_u32 s1, s3, 0
	v_lshlrev_b32_e32 v46, 1, v4
	v_and_or_b32 v13, v14, s23, v13
	v_or_b32_e32 v14, s2, v5
	v_lshl_add_u64 v[16:17], s[0:1], 0, v[46:47]
	v_lshlrev_b32_e32 v46, 12, v14
	v_lshl_add_u64 v[32:33], v[16:17], 0, v[46:47]
	global_store_dwordx4 v[32:33], v[10:13], off nt
	v_bfe_u32 v14, v31, 16, 1
	v_or_b32_e32 v18, s2, v7
	v_bfe_u32 v10, v15, 16, 1
	v_add3_u32 v10, v15, v10, s22
	v_bfe_u32 v11, v19, 16, 1
	v_lshrrev_b32_e32 v10, 16, v10
	v_add3_u32 v11, v19, v11, s22
	v_and_or_b32 v10, v11, s23, v10
	v_bfe_u32 v11, v21, 16, 1
	v_add3_u32 v11, v21, v11, s22
	v_bfe_u32 v12, v23, 16, 1
	v_lshrrev_b32_e32 v11, 16, v11
	v_add3_u32 v12, v23, v12, s22
	v_and_or_b32 v11, v12, s23, v11
	v_bfe_u32 v12, v25, 16, 1
	v_add3_u32 v12, v25, v12, s22
	v_bfe_u32 v13, v27, 16, 1
	v_lshrrev_b32_e32 v12, 16, v12
	v_add3_u32 v13, v27, v13, s22
	v_and_or_b32 v12, v13, s23, v12
	v_bfe_u32 v13, v29, 16, 1
	v_add3_u32 v13, v29, v13, s22
	v_lshrrev_b32_e32 v13, 16, v13
	v_add3_u32 v14, v31, v14, s22
	v_lshlrev_b32_e32 v46, 12, v18
	v_and_or_b32 v13, v14, s23, v13
	ds_read2_b32 v[14:15], v6 offset0:16 offset1:24
	v_lshl_add_u64 v[18:19], v[16:17], 0, v[46:47]
	global_store_dwordx4 v[18:19], v[10:13], off nt
	ds_read2_b32 v[18:19], v6 offset0:49 offset1:57
	ds_read2_b32 v[20:21], v6 offset0:82 offset1:90
	ds_read2_b32 v[22:23], v6 offset0:115 offset1:123
	s_waitcnt lgkmcnt(3)
	v_bfe_u32 v10, v14, 16, 1
	v_add3_u32 v10, v14, v10, s22
	s_waitcnt lgkmcnt(2)
	v_bfe_u32 v11, v18, 16, 1
	ds_read2_b32 v[24:25], v6 offset0:148 offset1:156
	v_lshrrev_b32_e32 v10, 16, v10
	v_add3_u32 v11, v18, v11, s22
	ds_read2_b32 v[26:27], v6 offset0:181 offset1:189
	v_and_or_b32 v10, v11, s23, v10
	s_waitcnt lgkmcnt(3)
	v_bfe_u32 v11, v20, 16, 1
	v_add3_u32 v11, v20, v11, s22
	s_waitcnt lgkmcnt(2)
	v_bfe_u32 v12, v22, 16, 1
	ds_read2_b32 v[28:29], v6 offset0:214 offset1:222
	v_lshrrev_b32_e32 v11, 16, v11
	v_add3_u32 v12, v22, v12, s22
	ds_read2_b32 v[30:31], v6 offset0:247 offset1:255
	v_and_or_b32 v11, v12, s23, v11
	s_waitcnt lgkmcnt(3)
	v_bfe_u32 v12, v24, 16, 1
	v_add3_u32 v12, v24, v12, s22
	s_waitcnt lgkmcnt(2)
	v_bfe_u32 v13, v26, 16, 1
	v_lshrrev_b32_e32 v12, 16, v12
	v_add3_u32 v13, v26, v13, s22
	v_and_or_b32 v12, v13, s23, v12
	s_waitcnt lgkmcnt(1)
	v_bfe_u32 v13, v28, 16, 1
	v_add3_u32 v13, v28, v13, s22
	s_waitcnt lgkmcnt(0)
	v_bfe_u32 v14, v30, 16, 1
	v_lshrrev_b32_e32 v13, 16, v13
	v_add3_u32 v14, v30, v14, s22
	v_and_or_b32 v13, v14, s23, v13
	v_or_b32_e32 v14, s2, v8
	v_lshlrev_b32_e32 v46, 12, v14
	v_lshl_add_u64 v[32:33], v[16:17], 0, v[46:47]
	global_store_dwordx4 v[32:33], v[10:13], off nt
	v_bfe_u32 v14, v31, 16, 1
	v_add3_u32 v14, v31, v14, s22
	v_bfe_u32 v10, v15, 16, 1
	v_add3_u32 v10, v15, v10, s22
	v_bfe_u32 v11, v19, 16, 1
	v_lshrrev_b32_e32 v10, 16, v10
	v_add3_u32 v11, v19, v11, s22
	v_and_or_b32 v10, v11, s23, v10
	v_bfe_u32 v11, v21, 16, 1
	v_add3_u32 v11, v21, v11, s22
	v_bfe_u32 v12, v23, 16, 1
	v_lshrrev_b32_e32 v11, 16, v11
	v_add3_u32 v12, v23, v12, s22
	v_and_or_b32 v11, v12, s23, v11
	v_bfe_u32 v12, v25, 16, 1
	v_add3_u32 v12, v25, v12, s22
	v_bfe_u32 v13, v27, 16, 1
	v_lshrrev_b32_e32 v12, 16, v12
	v_add3_u32 v13, v27, v13, s22
	v_and_or_b32 v12, v13, s23, v12
	v_bfe_u32 v13, v29, 16, 1
	v_add3_u32 v13, v29, v13, s22
	v_lshrrev_b32_e32 v13, 16, v13
	v_and_or_b32 v13, v14, s23, v13
	v_or_b32_e32 v14, s2, v9
	v_lshlrev_b32_e32 v46, 12, v14
	v_lshl_add_u64 v[14:15], v[16:17], 0, v[46:47]
	global_store_dwordx4 v[14:15], v[10:13], off nt
	s_waitcnt lgkmcnt(0)
	v_readlane_b32 s50, v251, 8
	v_readlane_b32 s51, v251, 9
	v_readlane_b32 s54, v251, 12
	v_readlane_b32 s55, v251, 13
	s_mov_b32 s19, 0xc000
	s_mov_b64 s[2:3], 0
.LBB0_128:
	s_andn2_b64 vcc, exec, s[2:3]
	s_cbranch_vccnz .LBB0_130
	s_and_b32 s0, s4, 0x1f800
	s_add_i32 s20, s0, 0xfffe9800
	v_readlane_b32 s68, v251, 30
	s_lshl_b64 s[0:1], s[20:21], 13
	v_readlane_b32 s70, v251, 32
	v_readlane_b32 s71, v251, 33
	s_add_u32 s8, s70, s0
	s_addc_u32 s9, s71, s1
	s_lshl_b64 s[0:1], s[20:21], 12
	v_readlane_b32 s2, v251, 52
	s_add_u32 s5, s2, s0
	v_readlane_b32 s0, v251, 53
	s_addc_u32 s3, s0, s1
	s_lshl_b32 s0, s4, 5
	s_and_b32 s2, s0, 0x7e0
	s_and_b32 s7, s4, 0x7c0
	s_lshl_b32 s0, s2, 2
	s_add_u32 s0, s8, s0
	v_or_b32_e32 v12, s7, v1
	s_addc_u32 s1, s9, 0
	v_lshlrev_b32_e32 v46, 2, v2
	v_lshl_add_u64 v[10:11], s[0:1], 0, v[46:47]
	v_lshlrev_b32_e32 v46, 13, v12
	v_lshl_add_u64 v[10:11], v[10:11], 0, v[46:47]
	s_movk_i32 s0, 0x4000
	v_add_co_u32_e32 v12, vcc, s0, v10
	s_mov_b32 s0, 0x14000
	s_nop 0
	v_addc_co_u32_e32 v13, vcc, 0, v11, vcc
	v_add_co_u32_e32 v14, vcc, s25, v10
	v_readlane_b32 s69, v251, 31
	s_nop 0
	v_addc_co_u32_e32 v15, vcc, 0, v11, vcc
	v_add_co_u32_e32 v16, vcc, s19, v10
	v_readlane_b32 s72, v251, 34
	s_nop 0
	v_addc_co_u32_e32 v17, vcc, 0, v11, vcc
	v_add_co_u32_e32 v18, vcc, s48, v10
	v_readlane_b32 s73, v251, 35
	s_nop 0
	v_addc_co_u32_e32 v19, vcc, 0, v11, vcc
	v_add_co_u32_e32 v20, vcc, s0, v10
	s_mov_b32 s0, 0x1c000
	s_nop 0
	v_addc_co_u32_e32 v21, vcc, 0, v11, vcc
	v_add_co_u32_e32 v22, vcc, s49, v10
	v_readlane_b32 s74, v251, 36
	s_nop 0
	v_addc_co_u32_e32 v23, vcc, 0, v11, vcc
	v_add_co_u32_e32 v24, vcc, s0, v10
	s_mov_b32 s0, 0x20000
	s_nop 0
	v_addc_co_u32_e32 v25, vcc, 0, v11, vcc
	global_load_dword v28, v[10:11], off nt
	global_load_dword v29, v[12:13], off nt
	global_load_dword v30, v[14:15], off nt
	global_load_dword v31, v[16:17], off nt
	global_load_dword v32, v[18:19], off nt
	global_load_dword v33, v[20:21], off nt
	global_load_dword v34, v[22:23], off nt
	global_load_dword v35, v[24:25], off nt
	v_add_co_u32_e32 v12, vcc, s0, v10
	s_mov_b32 s0, 0x24000
	s_nop 0
	v_addc_co_u32_e32 v13, vcc, 0, v11, vcc
	v_add_co_u32_e32 v14, vcc, s0, v10
	s_mov_b32 s0, 0x28000
	s_nop 0
	v_addc_co_u32_e32 v15, vcc, 0, v11, vcc
	v_add_co_u32_e32 v16, vcc, s0, v10
	s_mov_b32 s0, 0x2c000
	s_nop 0
	v_addc_co_u32_e32 v17, vcc, 0, v11, vcc
	v_add_co_u32_e32 v18, vcc, s0, v10
	s_mov_b32 s0, 0x30000
	s_nop 0
	v_addc_co_u32_e32 v19, vcc, 0, v11, vcc
	v_add_co_u32_e32 v20, vcc, s0, v10
	s_mov_b32 s0, 0x34000
	s_nop 0
	v_addc_co_u32_e32 v21, vcc, 0, v11, vcc
	v_add_co_u32_e32 v22, vcc, s0, v10
	s_mov_b32 s0, 0x38000
	s_nop 0
	v_addc_co_u32_e32 v23, vcc, 0, v11, vcc
	v_add_co_u32_e32 v24, vcc, s0, v10
	s_mov_b32 s0, 0x3c000
	s_nop 0
	v_addc_co_u32_e32 v25, vcc, 0, v11, vcc
	v_add_co_u32_e32 v26, vcc, s0, v10
	s_mov_b32 s0, 0x40000
	s_nop 0
	v_addc_co_u32_e32 v27, vcc, 0, v11, vcc
	global_load_dword v36, v[12:13], off nt
	global_load_dword v37, v[14:15], off nt
	global_load_dword v38, v[16:17], off nt
	global_load_dword v39, v[18:19], off nt
	global_load_dword v40, v[20:21], off nt
	global_load_dword v41, v[22:23], off nt
	global_load_dword v42, v[24:25], off nt
	global_load_dword v43, v[26:27], off nt
	v_add_co_u32_e32 v12, vcc, s0, v10
	s_mov_b32 s0, 0x44000
	s_nop 0
	v_addc_co_u32_e32 v13, vcc, 0, v11, vcc
	v_add_co_u32_e32 v14, vcc, s0, v10
	s_mov_b32 s0, 0x48000
	s_nop 0
	v_addc_co_u32_e32 v15, vcc, 0, v11, vcc
	v_add_co_u32_e32 v16, vcc, s0, v10
	s_mov_b32 s0, 0x4c000
	s_nop 0
	v_addc_co_u32_e32 v17, vcc, 0, v11, vcc
	v_add_co_u32_e32 v18, vcc, s0, v10
	s_mov_b32 s0, 0x50000
	s_nop 0
	v_addc_co_u32_e32 v19, vcc, 0, v11, vcc
	v_add_co_u32_e32 v20, vcc, s0, v10
	s_mov_b32 s0, 0x54000
	s_nop 0
	v_addc_co_u32_e32 v21, vcc, 0, v11, vcc
	v_add_co_u32_e32 v22, vcc, s0, v10
	s_mov_b32 s0, 0x58000
	s_nop 0
	v_addc_co_u32_e32 v23, vcc, 0, v11, vcc
	v_add_co_u32_e32 v24, vcc, s0, v10
	s_mov_b32 s0, 0x5c000
	s_nop 0
	v_addc_co_u32_e32 v25, vcc, 0, v11, vcc
	v_add_co_u32_e32 v26, vcc, s0, v10
	s_mov_b32 s0, 0x60000
	s_nop 0
	v_addc_co_u32_e32 v27, vcc, 0, v11, vcc
	global_load_dword v44, v[12:13], off nt
	global_load_dword v45, v[14:15], off nt
	global_load_dword v46, v[16:17], off nt
	global_load_dword v48, v[18:19], off nt
	global_load_dword v50, v[20:21], off nt
	global_load_dword v51, v[22:23], off nt
	global_load_dword v52, v[24:25], off nt
	s_nop 0
	global_load_dword v26, v[26:27], off nt
	v_add_co_u32_e32 v12, vcc, s0, v10
	s_mov_b32 s0, 0x64000
	s_nop 0
	v_addc_co_u32_e32 v13, vcc, 0, v11, vcc
	v_add_co_u32_e32 v14, vcc, s0, v10
	s_mov_b32 s0, 0x68000
	s_nop 0
	v_addc_co_u32_e32 v15, vcc, 0, v11, vcc
	v_add_co_u32_e32 v16, vcc, s0, v10
	s_mov_b32 s0, 0x6c000
	s_nop 0
	v_addc_co_u32_e32 v17, vcc, 0, v11, vcc
	v_add_co_u32_e32 v18, vcc, s0, v10
	s_mov_b32 s0, 0x70000
	s_nop 0
	v_addc_co_u32_e32 v19, vcc, 0, v11, vcc
	v_add_co_u32_e32 v20, vcc, s0, v10
	s_mov_b32 s0, 0x74000
	s_nop 0
	v_addc_co_u32_e32 v21, vcc, 0, v11, vcc
	v_add_co_u32_e32 v22, vcc, s0, v10
	s_mov_b32 s0, 0x78000
	s_nop 0
	v_addc_co_u32_e32 v23, vcc, 0, v11, vcc
	v_add_co_u32_e32 v24, vcc, s0, v10
	s_mov_b32 s0, 0x7c000
	s_nop 0
	v_addc_co_u32_e32 v25, vcc, 0, v11, vcc
	v_add_co_u32_e32 v10, vcc, s0, v10
	s_lshl_b32 s0, s7, 1
	s_nop 0
	v_addc_co_u32_e32 v11, vcc, 0, v11, vcc
	global_load_dword v12, v[12:13], off nt
	s_nop 0
	global_load_dword v13, v[14:15], off nt
	s_nop 0
	global_load_dword v14, v[16:17], off nt
	global_load_dword v15, v[18:19], off nt
	s_nop 0
	global_load_dword v16, v[20:21], off nt
	global_load_dword v17, v[22:23], off nt
	global_load_dword v18, v[24:25], off nt
	s_nop 0
	global_load_dword v10, v[10:11], off nt
	v_add_u32_e32 v11, 0x400, v3
	s_waitcnt vmcnt(30)
	ds_write2_b32 v3, v28, v29 offset1:66
	s_waitcnt vmcnt(28)
	ds_write2_b32 v3, v30, v31 offset0:132 offset1:198
	s_waitcnt vmcnt(26)
	ds_write2_b32 v11, v32, v33 offset0:8 offset1:74
	s_waitcnt vmcnt(24)
	ds_write2_b32 v11, v34, v35 offset0:140 offset1:206
	v_add_u32_e32 v11, 0x800, v3
	s_waitcnt vmcnt(22)
	ds_write2_b32 v11, v36, v37 offset0:16 offset1:82
	s_waitcnt vmcnt(20)
	ds_write2_b32 v11, v38, v39 offset0:148 offset1:214
	v_add_u32_e32 v11, 0xc00, v3
	s_waitcnt vmcnt(18)
	ds_write2_b32 v11, v40, v41 offset0:24 offset1:90
	s_waitcnt vmcnt(16)
	ds_write2_b32 v11, v42, v43 offset0:156 offset1:222
	v_add_u32_e32 v11, 0x1000, v3
	s_waitcnt vmcnt(14)
	ds_write2_b32 v11, v44, v45 offset0:32 offset1:98
	s_waitcnt vmcnt(12)
	ds_write2_b32 v11, v46, v48 offset0:164 offset1:230
	v_add_u32_e32 v11, 0x1400, v3
	s_waitcnt vmcnt(10)
	ds_write2_b32 v11, v50, v51 offset0:40 offset1:106
	s_waitcnt vmcnt(8)
	ds_write2_b32 v11, v52, v26 offset0:172 offset1:238
	v_add_u32_e32 v11, 0x1800, v3
	s_waitcnt vmcnt(6)
	ds_write2_b32 v11, v12, v13 offset0:48 offset1:114
	s_waitcnt vmcnt(4)
	ds_write2_b32 v11, v14, v15 offset0:180 offset1:246
	v_add_u32_e32 v11, 0x1c00, v3
	s_waitcnt vmcnt(2)
	ds_write2_b32 v11, v16, v17 offset0:56 offset1:122
	s_waitcnt vmcnt(0)
	ds_write2_b32 v11, v18, v10 offset0:188 offset1:254
	s_waitcnt lgkmcnt(0)
	ds_read2_b32 v[14:15], v6 offset1:8
	ds_read2_b32 v[18:19], v6 offset0:33 offset1:41
	ds_read2_b32 v[20:21], v6 offset0:66 offset1:74
	ds_read2_b32 v[22:23], v6 offset0:99 offset1:107
	ds_read2_b32 v[24:25], v6 offset0:132 offset1:140
	s_waitcnt lgkmcnt(4)
	v_bfe_u32 v10, v14, 16, 1
	v_add3_u32 v10, v14, v10, s22
	s_waitcnt lgkmcnt(3)
	v_bfe_u32 v11, v18, 16, 1
	v_lshrrev_b32_e32 v10, 16, v10
	v_add3_u32 v11, v18, v11, s22
	ds_read2_b32 v[26:27], v6 offset0:165 offset1:173
	v_and_or_b32 v10, v11, s23, v10
	s_waitcnt lgkmcnt(3)
	v_bfe_u32 v11, v20, 16, 1
	v_add3_u32 v11, v20, v11, s22
	s_waitcnt lgkmcnt(2)
	v_bfe_u32 v12, v22, 16, 1
	ds_read2_b32 v[28:29], v6 offset0:198 offset1:206
	v_lshrrev_b32_e32 v11, 16, v11
	v_add3_u32 v12, v22, v12, s22
	ds_read2_b32 v[30:31], v6 offset0:231 offset1:239
	v_and_or_b32 v11, v12, s23, v11
	s_waitcnt lgkmcnt(3)
	v_bfe_u32 v12, v24, 16, 1
	v_add3_u32 v12, v24, v12, s22
	s_waitcnt lgkmcnt(2)
	v_bfe_u32 v13, v26, 16, 1
	v_lshrrev_b32_e32 v12, 16, v12
	v_add3_u32 v13, v26, v13, s22
	v_and_or_b32 v12, v13, s23, v12
	s_waitcnt lgkmcnt(1)
	v_bfe_u32 v13, v28, 16, 1
	v_add3_u32 v13, v28, v13, s22
	s_waitcnt lgkmcnt(0)
	v_bfe_u32 v14, v30, 16, 1
	s_add_u32 s0, s5, s0
	v_lshrrev_b32_e32 v13, 16, v13
	v_add3_u32 v14, v30, v14, s22
	s_addc_u32 s1, s3, 0
	v_lshlrev_b32_e32 v46, 1, v4
	v_and_or_b32 v13, v14, s23, v13
	v_or_b32_e32 v14, s2, v5
	v_lshl_add_u64 v[16:17], s[0:1], 0, v[46:47]
	v_lshlrev_b32_e32 v46, 12, v14
	v_lshl_add_u64 v[32:33], v[16:17], 0, v[46:47]
	global_store_dwordx4 v[32:33], v[10:13], off nt
	v_bfe_u32 v14, v31, 16, 1
	v_or_b32_e32 v18, s2, v7
	v_bfe_u32 v10, v15, 16, 1
	v_add3_u32 v10, v15, v10, s22
	v_bfe_u32 v11, v19, 16, 1
	v_lshrrev_b32_e32 v10, 16, v10
	v_add3_u32 v11, v19, v11, s22
	v_and_or_b32 v10, v11, s23, v10
	v_bfe_u32 v11, v21, 16, 1
	v_add3_u32 v11, v21, v11, s22
	v_bfe_u32 v12, v23, 16, 1
	v_lshrrev_b32_e32 v11, 16, v11
	v_add3_u32 v12, v23, v12, s22
	v_and_or_b32 v11, v12, s23, v11
	v_bfe_u32 v12, v25, 16, 1
	v_add3_u32 v12, v25, v12, s22
	v_bfe_u32 v13, v27, 16, 1
	v_lshrrev_b32_e32 v12, 16, v12
	v_add3_u32 v13, v27, v13, s22
	v_and_or_b32 v12, v13, s23, v12
	v_bfe_u32 v13, v29, 16, 1
	v_add3_u32 v13, v29, v13, s22
	v_lshrrev_b32_e32 v13, 16, v13
	v_add3_u32 v14, v31, v14, s22
	v_lshlrev_b32_e32 v46, 12, v18
	v_and_or_b32 v13, v14, s23, v13
	ds_read2_b32 v[14:15], v6 offset0:16 offset1:24
	v_lshl_add_u64 v[18:19], v[16:17], 0, v[46:47]
	global_store_dwordx4 v[18:19], v[10:13], off nt
	ds_read2_b32 v[18:19], v6 offset0:49 offset1:57
	ds_read2_b32 v[20:21], v6 offset0:82 offset1:90
	ds_read2_b32 v[22:23], v6 offset0:115 offset1:123
	s_waitcnt lgkmcnt(3)
	v_bfe_u32 v10, v14, 16, 1
	v_add3_u32 v10, v14, v10, s22
	s_waitcnt lgkmcnt(2)
	v_bfe_u32 v11, v18, 16, 1
	ds_read2_b32 v[24:25], v6 offset0:148 offset1:156
	v_lshrrev_b32_e32 v10, 16, v10
	v_add3_u32 v11, v18, v11, s22
	ds_read2_b32 v[26:27], v6 offset0:181 offset1:189
	v_and_or_b32 v10, v11, s23, v10
	s_waitcnt lgkmcnt(3)
	v_bfe_u32 v11, v20, 16, 1
	v_add3_u32 v11, v20, v11, s22
	s_waitcnt lgkmcnt(2)
	v_bfe_u32 v12, v22, 16, 1
	ds_read2_b32 v[28:29], v6 offset0:214 offset1:222
	v_lshrrev_b32_e32 v11, 16, v11
	v_add3_u32 v12, v22, v12, s22
	ds_read2_b32 v[30:31], v6 offset0:247 offset1:255
	v_and_or_b32 v11, v12, s23, v11
	s_waitcnt lgkmcnt(3)
	v_bfe_u32 v12, v24, 16, 1
	v_add3_u32 v12, v24, v12, s22
	s_waitcnt lgkmcnt(2)
	v_bfe_u32 v13, v26, 16, 1
	v_lshrrev_b32_e32 v12, 16, v12
	v_add3_u32 v13, v26, v13, s22
	v_and_or_b32 v12, v13, s23, v12
	s_waitcnt lgkmcnt(1)
	v_bfe_u32 v13, v28, 16, 1
	v_add3_u32 v13, v28, v13, s22
	s_waitcnt lgkmcnt(0)
	v_bfe_u32 v14, v30, 16, 1
	v_lshrrev_b32_e32 v13, 16, v13
	v_add3_u32 v14, v30, v14, s22
	v_and_or_b32 v13, v14, s23, v13
	v_or_b32_e32 v14, s2, v8
	v_lshlrev_b32_e32 v46, 12, v14
	v_lshl_add_u64 v[32:33], v[16:17], 0, v[46:47]
	global_store_dwordx4 v[32:33], v[10:13], off nt
	v_bfe_u32 v14, v31, 16, 1
	v_add3_u32 v14, v31, v14, s22
	v_bfe_u32 v10, v15, 16, 1
	v_add3_u32 v10, v15, v10, s22
	v_bfe_u32 v11, v19, 16, 1
	v_lshrrev_b32_e32 v10, 16, v10
	v_add3_u32 v11, v19, v11, s22
	v_and_or_b32 v10, v11, s23, v10
	v_bfe_u32 v11, v21, 16, 1
	v_add3_u32 v11, v21, v11, s22
	v_bfe_u32 v12, v23, 16, 1
	v_lshrrev_b32_e32 v11, 16, v11
	v_add3_u32 v12, v23, v12, s22
	v_and_or_b32 v11, v12, s23, v11
	v_bfe_u32 v12, v25, 16, 1
	v_add3_u32 v12, v25, v12, s22
	v_bfe_u32 v13, v27, 16, 1
	v_lshrrev_b32_e32 v12, 16, v12
	v_add3_u32 v13, v27, v13, s22
	v_and_or_b32 v12, v13, s23, v12
	v_bfe_u32 v13, v29, 16, 1
	v_add3_u32 v13, v29, v13, s22
	v_lshrrev_b32_e32 v13, 16, v13
	v_and_or_b32 v13, v14, s23, v13
	v_or_b32_e32 v14, s2, v9
	v_lshlrev_b32_e32 v46, 12, v14
	v_lshl_add_u64 v[14:15], v[16:17], 0, v[46:47]
	global_store_dwordx4 v[14:15], v[10:13], off nt
	s_waitcnt lgkmcnt(0)
	v_readlane_b32 s75, v251, 37
	v_readlane_b32 s76, v251, 38
	v_readlane_b32 s77, v251, 39
	v_readlane_b32 s78, v251, 40
	v_readlane_b32 s79, v251, 41
	v_readlane_b32 s80, v251, 42
	v_readlane_b32 s81, v251, 43
	v_readlane_b32 s82, v251, 44
	v_readlane_b32 s83, v251, 45

.LBB0_131:
	s_andn2_b64 vcc, exec, s[2:3]
	s_cbranch_vccnz .LBB0_140
	s_add_i32 s1, s4, 0xffffa000
	s_mul_hi_u32 s0, s1, 0x3e0f83e1
	s_lshr_b32 s0, s0, 12
	s_mul_i32 s2, s0, 0x4200
	s_sub_i32 s1, s1, s2
	s_mul_i32 s2, s1, 0xba2f
	s_lshr_b32 s2, s2, 28
	s_mulk_i32 s2, 0x1600
	s_sub_i32 s5, s1, s2
	s_cmpk_gt_u32 s1, 0x15ff
	s_mul_hi_u32 s7, s0, 0x2c00000
	s_mul_i32 s8, s0, 0x2c00000
	s_mov_b64 s[2:3], -1
	s_cbranch_scc0 .LBB0_138
	s_addk_i32 s1, 0xea00
	s_cmpk_gt_u32 s1, 0x15ff
	s_cbranch_scc0 .LBB0_135
	v_readlane_b32 s68, v251, 14
	v_readlane_b32 s72, v251, 18
	v_readlane_b32 s73, v251, 19
	s_add_u32 s1, s72, s8
	s_addc_u32 s11, s73, s7
	s_mul_hi_u32 s2, s0, 0x1600000
	s_mul_i32 s0, s0, 0x1600000
	v_readlane_b32 s3, v251, 54
	s_add_u32 s9, s3, s0
	v_readlane_b32 s0, v251, 55
	s_addc_u32 s3, s0, s2
	s_lshl_b32 s0, s5, 5
	s_and_b32 s2, s0, 0x7e0
	s_and_b32 s10, s5, 0x1fc0
	s_lshl_b32 s0, s2, 2
	s_add_u32 s0, s1, s0
	v_or_b32_e32 v12, s10, v1
	s_addc_u32 s1, s11, 0
	v_lshlrev_b32_e32 v46, 2, v2
	v_lshl_add_u64 v[10:11], s[0:1], 0, v[46:47]
	v_lshlrev_b32_e32 v46, 13, v12
	v_lshl_add_u64 v[10:11], v[10:11], 0, v[46:47]
	s_movk_i32 s0, 0x4000
	v_add_co_u32_e32 v12, vcc, s0, v10
	s_mov_b32 s0, 0x14000
	s_nop 0
	v_addc_co_u32_e32 v13, vcc, 0, v11, vcc
	v_add_co_u32_e32 v14, vcc, s25, v10
	v_readlane_b32 s69, v251, 15
	s_nop 0
	v_addc_co_u32_e32 v15, vcc, 0, v11, vcc
	v_add_co_u32_e32 v16, vcc, s19, v10
	v_readlane_b32 s70, v251, 16
	s_nop 0
	v_addc_co_u32_e32 v17, vcc, 0, v11, vcc
	v_add_co_u32_e32 v18, vcc, s48, v10
	v_readlane_b32 s71, v251, 17
	s_nop 0
	v_addc_co_u32_e32 v19, vcc, 0, v11, vcc
	v_add_co_u32_e32 v20, vcc, s0, v10
	s_mov_b32 s0, 0x1c000
	s_nop 0
	v_addc_co_u32_e32 v21, vcc, 0, v11, vcc
	v_add_co_u32_e32 v22, vcc, s49, v10
	v_readlane_b32 s74, v251, 20
	s_nop 0
	v_addc_co_u32_e32 v23, vcc, 0, v11, vcc
	v_add_co_u32_e32 v24, vcc, s0, v10
	s_mov_b32 s0, 0x20000
	s_nop 0
	v_addc_co_u32_e32 v25, vcc, 0, v11, vcc
	global_load_dword v28, v[10:11], off nt
	global_load_dword v29, v[12:13], off nt
	global_load_dword v30, v[14:15], off nt
	global_load_dword v31, v[16:17], off nt
	global_load_dword v32, v[18:19], off nt
	global_load_dword v33, v[20:21], off nt
	global_load_dword v34, v[22:23], off nt
	global_load_dword v35, v[24:25], off nt
	v_add_co_u32_e32 v12, vcc, s0, v10
	s_mov_b32 s0, 0x24000
	s_nop 0
	v_addc_co_u32_e32 v13, vcc, 0, v11, vcc
	v_add_co_u32_e32 v14, vcc, s0, v10
	s_mov_b32 s0, 0x28000
	s_nop 0
	v_addc_co_u32_e32 v15, vcc, 0, v11, vcc
	v_add_co_u32_e32 v16, vcc, s0, v10
	s_mov_b32 s0, 0x2c000
	s_nop 0
	v_addc_co_u32_e32 v17, vcc, 0, v11, vcc
	v_add_co_u32_e32 v18, vcc, s0, v10
	s_mov_b32 s0, 0x30000
	s_nop 0
	v_addc_co_u32_e32 v19, vcc, 0, v11, vcc
	v_add_co_u32_e32 v20, vcc, s0, v10
	s_mov_b32 s0, 0x34000
	s_nop 0
	v_addc_co_u32_e32 v21, vcc, 0, v11, vcc
	v_add_co_u32_e32 v22, vcc, s0, v10
	s_mov_b32 s0, 0x38000
	s_nop 0
	v_addc_co_u32_e32 v23, vcc, 0, v11, vcc
	v_add_co_u32_e32 v24, vcc, s0, v10
	s_mov_b32 s0, 0x3c000
	s_nop 0
	v_addc_co_u32_e32 v25, vcc, 0, v11, vcc
	v_add_co_u32_e32 v26, vcc, s0, v10
	s_mov_b32 s0, 0x40000
	s_nop 0
	v_addc_co_u32_e32 v27, vcc, 0, v11, vcc
	global_load_dword v36, v[12:13], off nt
	global_load_dword v37, v[14:15], off nt
	global_load_dword v38, v[16:17], off nt
	global_load_dword v39, v[18:19], off nt
	global_load_dword v40, v[20:21], off nt
	global_load_dword v41, v[22:23], off nt
	global_load_dword v42, v[24:25], off nt
	global_load_dword v43, v[26:27], off nt
	v_add_co_u32_e32 v12, vcc, s0, v10
	s_mov_b32 s0, 0x44000
	s_nop 0
	v_addc_co_u32_e32 v13, vcc, 0, v11, vcc
	v_add_co_u32_e32 v14, vcc, s0, v10
	s_mov_b32 s0, 0x48000
	s_nop 0
	v_addc_co_u32_e32 v15, vcc, 0, v11, vcc
	v_add_co_u32_e32 v16, vcc, s0, v10
	s_mov_b32 s0, 0x4c000
	s_nop 0
	v_addc_co_u32_e32 v17, vcc, 0, v11, vcc
	v_add_co_u32_e32 v18, vcc, s0, v10
	s_mov_b32 s0, 0x50000
	s_nop 0
	v_addc_co_u32_e32 v19, vcc, 0, v11, vcc
	v_add_co_u32_e32 v20, vcc, s0, v10
	s_mov_b32 s0, 0x54000
	s_nop 0
	v_addc_co_u32_e32 v21, vcc, 0, v11, vcc
	v_add_co_u32_e32 v22, vcc, s0, v10
	s_mov_b32 s0, 0x58000
	s_nop 0
	v_addc_co_u32_e32 v23, vcc, 0, v11, vcc
	v_add_co_u32_e32 v24, vcc, s0, v10
	s_mov_b32 s0, 0x5c000
	s_nop 0
	v_addc_co_u32_e32 v25, vcc, 0, v11, vcc
	v_add_co_u32_e32 v26, vcc, s0, v10
	s_mov_b32 s0, 0x60000
	s_nop 0
	v_addc_co_u32_e32 v27, vcc, 0, v11, vcc
	global_load_dword v44, v[12:13], off nt
	global_load_dword v45, v[14:15], off nt
	global_load_dword v46, v[16:17], off nt
	global_load_dword v48, v[18:19], off nt
	global_load_dword v50, v[20:21], off nt
	global_load_dword v51, v[22:23], off nt
	global_load_dword v52, v[24:25], off nt
	s_nop 0
	global_load_dword v26, v[26:27], off nt
	v_add_co_u32_e32 v12, vcc, s0, v10
	s_mov_b32 s0, 0x64000
	s_nop 0
	v_addc_co_u32_e32 v13, vcc, 0, v11, vcc
	v_add_co_u32_e32 v14, vcc, s0, v10
	s_mov_b32 s0, 0x68000
	s_nop 0
	v_addc_co_u32_e32 v15, vcc, 0, v11, vcc
	v_add_co_u32_e32 v16, vcc, s0, v10
	s_mov_b32 s0, 0x6c000
	s_nop 0
	v_addc_co_u32_e32 v17, vcc, 0, v11, vcc
	v_add_co_u32_e32 v18, vcc, s0, v10
	s_mov_b32 s0, 0x70000
	s_nop 0
	v_addc_co_u32_e32 v19, vcc, 0, v11, vcc
	v_add_co_u32_e32 v20, vcc, s0, v10
	s_mov_b32 s0, 0x74000
	s_nop 0
	v_addc_co_u32_e32 v21, vcc, 0, v11, vcc
	v_add_co_u32_e32 v22, vcc, s0, v10
	s_mov_b32 s0, 0x78000
	s_nop 0
	v_addc_co_u32_e32 v23, vcc, 0, v11, vcc
	v_add_co_u32_e32 v24, vcc, s0, v10
	s_mov_b32 s0, 0x7c000
	s_nop 0
	v_addc_co_u32_e32 v25, vcc, 0, v11, vcc
	v_add_co_u32_e32 v10, vcc, s0, v10
	s_lshl_b32 s0, s10, 1
	s_nop 0
	v_addc_co_u32_e32 v11, vcc, 0, v11, vcc
	global_load_dword v12, v[12:13], off nt
	s_nop 0
	global_load_dword v13, v[14:15], off nt
	s_nop 0
	global_load_dword v14, v[16:17], off nt
	global_load_dword v15, v[18:19], off nt
	s_nop 0
	global_load_dword v16, v[20:21], off nt
	global_load_dword v17, v[22:23], off nt
	global_load_dword v18, v[24:25], off nt
	s_nop 0
	global_load_dword v10, v[10:11], off nt
	v_add_u32_e32 v11, 0x400, v3
	s_waitcnt vmcnt(30)
	ds_write2_b32 v3, v28, v29 offset1:66
	s_waitcnt vmcnt(28)
	ds_write2_b32 v3, v30, v31 offset0:132 offset1:198
	s_waitcnt vmcnt(26)
	ds_write2_b32 v11, v32, v33 offset0:8 offset1:74
	s_waitcnt vmcnt(24)
	ds_write2_b32 v11, v34, v35 offset0:140 offset1:206
	v_add_u32_e32 v11, 0x800, v3
	s_waitcnt vmcnt(22)
	ds_write2_b32 v11, v36, v37 offset0:16 offset1:82
	s_waitcnt vmcnt(20)
	ds_write2_b32 v11, v38, v39 offset0:148 offset1:214
	v_add_u32_e32 v11, 0xc00, v3
	s_waitcnt vmcnt(18)
	ds_write2_b32 v11, v40, v41 offset0:24 offset1:90
	s_waitcnt vmcnt(16)
	ds_write2_b32 v11, v42, v43 offset0:156 offset1:222
	v_add_u32_e32 v11, 0x1000, v3
	s_waitcnt vmcnt(14)
	ds_write2_b32 v11, v44, v45 offset0:32 offset1:98
	s_waitcnt vmcnt(12)
	ds_write2_b32 v11, v46, v48 offset0:164 offset1:230
	v_add_u32_e32 v11, 0x1400, v3
	s_waitcnt vmcnt(10)
	ds_write2_b32 v11, v50, v51 offset0:40 offset1:106
	s_waitcnt vmcnt(8)
	ds_write2_b32 v11, v52, v26 offset0:172 offset1:238
	v_add_u32_e32 v11, 0x1800, v3
	s_waitcnt vmcnt(6)
	ds_write2_b32 v11, v12, v13 offset0:48 offset1:114
	s_waitcnt vmcnt(4)
	ds_write2_b32 v11, v14, v15 offset0:180 offset1:246
	v_add_u32_e32 v11, 0x1c00, v3
	s_waitcnt vmcnt(2)
	ds_write2_b32 v11, v16, v17 offset0:56 offset1:122
	s_waitcnt vmcnt(0)
	ds_write2_b32 v11, v18, v10 offset0:188 offset1:254
	s_waitcnt lgkmcnt(0)
	ds_read2_b32 v[14:15], v6 offset1:8
	ds_read2_b32 v[18:19], v6 offset0:33 offset1:41
	ds_read2_b32 v[20:21], v6 offset0:66 offset1:74
	ds_read2_b32 v[22:23], v6 offset0:99 offset1:107
	ds_read2_b32 v[24:25], v6 offset0:132 offset1:140
	s_waitcnt lgkmcnt(4)
	v_bfe_u32 v10, v14, 16, 1
	v_add3_u32 v10, v14, v10, s22
	s_waitcnt lgkmcnt(3)
	v_bfe_u32 v11, v18, 16, 1
	v_lshrrev_b32_e32 v10, 16, v10
	v_add3_u32 v11, v18, v11, s22
	ds_read2_b32 v[26:27], v6 offset0:165 offset1:173
	v_and_or_b32 v10, v11, s23, v10
	s_waitcnt lgkmcnt(3)
	v_bfe_u32 v11, v20, 16, 1
	v_add3_u32 v11, v20, v11, s22
	s_waitcnt lgkmcnt(2)
	v_bfe_u32 v12, v22, 16, 1
	ds_read2_b32 v[28:29], v6 offset0:198 offset1:206
	v_lshrrev_b32_e32 v11, 16, v11
	v_add3_u32 v12, v22, v12, s22
	ds_read2_b32 v[30:31], v6 offset0:231 offset1:239
	v_and_or_b32 v11, v12, s23, v11
	s_waitcnt lgkmcnt(3)
	v_bfe_u32 v12, v24, 16, 1
	v_add3_u32 v12, v24, v12, s22
	s_waitcnt lgkmcnt(2)
	v_bfe_u32 v13, v26, 16, 1
	v_lshrrev_b32_e32 v12, 16, v12
	v_add3_u32 v13, v26, v13, s22
	v_and_or_b32 v12, v13, s23, v12
	s_waitcnt lgkmcnt(1)
	v_bfe_u32 v13, v28, 16, 1
	v_add3_u32 v13, v28, v13, s22
	s_waitcnt lgkmcnt(0)
	v_bfe_u32 v14, v30, 16, 1
	v_lshrrev_b32_e32 v13, 16, v13
	v_add3_u32 v14, v30, v14, s22
	s_add_u32 s0, s9, s0
	v_and_or_b32 v13, v14, s23, v13
	v_or_b32_e32 v14, s2, v5
	s_addc_u32 s1, s3, 0
	v_lshlrev_b32_e32 v46, 1, v4
	v_mul_u32_u24_e32 v14, 0x1600, v14
	v_lshl_add_u64 v[16:17], s[0:1], 0, v[46:47]
	v_lshlrev_b32_e32 v46, 1, v14
	v_lshl_add_u64 v[32:33], v[16:17], 0, v[46:47]
	global_store_dwordx4 v[32:33], v[10:13], off nt
	v_bfe_u32 v14, v31, 16, 1
	v_add3_u32 v14, v31, v14, s22
	v_bfe_u32 v10, v15, 16, 1
	v_add3_u32 v10, v15, v10, s22
	v_bfe_u32 v11, v19, 16, 1
	v_lshrrev_b32_e32 v10, 16, v10
	v_add3_u32 v11, v19, v11, s22
	v_and_or_b32 v10, v11, s23, v10
	v_bfe_u32 v11, v21, 16, 1
	v_add3_u32 v11, v21, v11, s22
	v_bfe_u32 v12, v23, 16, 1
	v_lshrrev_b32_e32 v11, 16, v11
	v_add3_u32 v12, v23, v12, s22
	v_and_or_b32 v11, v12, s23, v11
	v_bfe_u32 v12, v25, 16, 1
	v_add3_u32 v12, v25, v12, s22
	v_bfe_u32 v13, v27, 16, 1
	v_lshrrev_b32_e32 v12, 16, v12
	v_add3_u32 v13, v27, v13, s22
	v_and_or_b32 v12, v13, s23, v12
	v_bfe_u32 v13, v29, 16, 1
	v_add3_u32 v13, v29, v13, s22
	v_lshrrev_b32_e32 v13, 16, v13
	v_and_or_b32 v13, v14, s23, v13
	v_or_b32_e32 v14, s2, v7
	v_mul_u32_u24_e32 v18, 0x1600, v14
	v_lshlrev_b32_e32 v46, 1, v18
	ds_read2_b32 v[14:15], v6 offset0:16 offset1:24
	v_lshl_add_u64 v[18:19], v[16:17], 0, v[46:47]
	global_store_dwordx4 v[18:19], v[10:13], off nt
	ds_read2_b32 v[18:19], v6 offset0:49 offset1:57
	ds_read2_b32 v[20:21], v6 offset0:82 offset1:90
	ds_read2_b32 v[22:23], v6 offset0:115 offset1:123
	s_waitcnt lgkmcnt(3)
	v_bfe_u32 v10, v14, 16, 1
	v_add3_u32 v10, v14, v10, s22
	s_waitcnt lgkmcnt(2)
	v_bfe_u32 v11, v18, 16, 1
	ds_read2_b32 v[24:25], v6 offset0:148 offset1:156
	v_lshrrev_b32_e32 v10, 16, v10
	v_add3_u32 v11, v18, v11, s22
	ds_read2_b32 v[26:27], v6 offset0:181 offset1:189
	v_and_or_b32 v10, v11, s23, v10
	s_waitcnt lgkmcnt(3)
	v_bfe_u32 v11, v20, 16, 1
	v_add3_u32 v11, v20, v11, s22
	s_waitcnt lgkmcnt(2)
	v_bfe_u32 v12, v22, 16, 1
	ds_read2_b32 v[28:29], v6 offset0:214 offset1:222
	v_lshrrev_b32_e32 v11, 16, v11
	v_add3_u32 v12, v22, v12, s22
	ds_read2_b32 v[30:31], v6 offset0:247 offset1:255
	v_and_or_b32 v11, v12, s23, v11
	s_waitcnt lgkmcnt(3)
	v_bfe_u32 v12, v24, 16, 1
	v_add3_u32 v12, v24, v12, s22
	s_waitcnt lgkmcnt(2)
	v_bfe_u32 v13, v26, 16, 1
	v_lshrrev_b32_e32 v12, 16, v12
	v_add3_u32 v13, v26, v13, s22
	v_and_or_b32 v12, v13, s23, v12
	s_waitcnt lgkmcnt(1)
	v_bfe_u32 v13, v28, 16, 1
	v_add3_u32 v13, v28, v13, s22
	s_waitcnt lgkmcnt(0)
	v_bfe_u32 v14, v30, 16, 1
	v_lshrrev_b32_e32 v13, 16, v13
	v_add3_u32 v14, v30, v14, s22
	v_and_or_b32 v13, v14, s23, v13
	v_or_b32_e32 v14, s2, v8
	v_mul_u32_u24_e32 v14, 0x1600, v14
	v_lshlrev_b32_e32 v46, 1, v14
	v_lshl_add_u64 v[32:33], v[16:17], 0, v[46:47]
	global_store_dwordx4 v[32:33], v[10:13], off nt
	v_bfe_u32 v14, v31, 16, 1
	v_add3_u32 v14, v31, v14, s22
	v_bfe_u32 v10, v15, 16, 1
	v_add3_u32 v10, v15, v10, s22
	v_bfe_u32 v11, v19, 16, 1
	v_lshrrev_b32_e32 v10, 16, v10
	v_add3_u32 v11, v19, v11, s22
	v_and_or_b32 v10, v11, s23, v10
	v_bfe_u32 v11, v21, 16, 1
	v_add3_u32 v11, v21, v11, s22
	v_bfe_u32 v12, v23, 16, 1
	v_lshrrev_b32_e32 v11, 16, v11
	v_add3_u32 v12, v23, v12, s22
	v_and_or_b32 v11, v12, s23, v11
	v_bfe_u32 v12, v25, 16, 1
	v_add3_u32 v12, v25, v12, s22
	v_bfe_u32 v13, v27, 16, 1
	v_lshrrev_b32_e32 v12, 16, v12
	v_add3_u32 v13, v27, v13, s22
	v_and_or_b32 v12, v13, s23, v12
	v_bfe_u32 v13, v29, 16, 1
	v_add3_u32 v13, v29, v13, s22
	v_lshrrev_b32_e32 v13, 16, v13
	v_and_or_b32 v13, v14, s23, v13
	v_or_b32_e32 v14, s2, v9
	v_mul_u32_u24_e32 v14, 0x1600, v14
	v_lshlrev_b32_e32 v46, 1, v14
	v_lshl_add_u64 v[14:15], v[16:17], 0, v[46:47]
	global_store_dwordx4 v[14:15], v[10:13], off nt
	s_waitcnt lgkmcnt(0)
	v_readlane_b32 s75, v251, 21
	v_readlane_b32 s76, v251, 22
	v_readlane_b32 s77, v251, 23
	v_readlane_b32 s78, v251, 24
	v_readlane_b32 s79, v251, 25
	v_readlane_b32 s80, v251, 26
	v_readlane_b32 s81, v251, 27
	v_readlane_b32 s82, v251, 28
	v_readlane_b32 s83, v251, 29
	s_mov_b64 s[2:3], 0
.LBB0_135:
	s_andn2_b64 vcc, exec, s[2:3]
	s_cbranch_vccnz .LBB0_137
	v_readlane_b32 s68, v251, 14
	v_readlane_b32 s70, v251, 16
	v_readlane_b32 s71, v251, 17
	s_add_u32 s0, s70, s8
	s_addc_u32 s1, s71, s7
	v_readlane_b32 s2, v251, 56
	s_add_u32 s9, s2, s8
	v_readlane_b32 s2, v251, 57
	s_addc_u32 s3, s2, s7
	s_and_b32 s2, 0xffff, s5
	s_mul_i32 s2, s2, 0xba2f
	s_lshr_b32 s10, s2, 23
	s_mul_i32 s2, s10, 0xb0
	s_sub_i32 s2, s5, s2
	s_and_b32 s11, s2, 0xffff
	s_lshl_b32 s2, s11, 5
	s_lshl_b32 s14, s11, 6
	s_and_b32 s14, s14, 0x3f00
	s_and_b32 s2, s2, 0x60
	s_or_b32 s2, s14, s2
	s_bitset1_b32 s2, 7
	s_lshl_b32 s11, s11, 7
	v_lshl_or_b32 v12, s10, 6, v1
	s_add_u32 s0, s0, s11
	s_addc_u32 s1, s1, 0
	v_lshlrev_b32_e32 v46, 2, v2
	v_mul_u32_u24_e32 v12, 0x1600, v12
	v_lshl_add_u64 v[10:11], s[0:1], 0, v[46:47]
	v_lshlrev_b32_e32 v46, 2, v12
	v_lshl_add_u64 v[10:11], v[10:11], 0, v[46:47]
	s_mov_b32 s0, 0xb000
	v_add_co_u32_e32 v12, vcc, s0, v10
	s_mov_b32 s0, 0x16000
	s_nop 0
	v_addc_co_u32_e32 v13, vcc, 0, v11, vcc
	v_add_co_u32_e32 v14, vcc, s0, v10
	s_mov_b32 s0, 0x21000
	s_nop 0
	v_addc_co_u32_e32 v15, vcc, 0, v11, vcc
	v_add_co_u32_e32 v16, vcc, s0, v10
	s_mov_b32 s0, 0x2c000
	s_nop 0
	v_addc_co_u32_e32 v17, vcc, 0, v11, vcc
	v_add_co_u32_e32 v18, vcc, s0, v10
	s_mov_b32 s0, 0x37000
	s_nop 0
	v_addc_co_u32_e32 v19, vcc, 0, v11, vcc
	v_add_co_u32_e32 v20, vcc, s0, v10
	s_mov_b32 s0, 0x42000
	s_nop 0
	v_addc_co_u32_e32 v21, vcc, 0, v11, vcc
	v_add_co_u32_e32 v22, vcc, s0, v10
	s_mov_b32 s0, 0x4d000
	s_nop 0
	v_addc_co_u32_e32 v23, vcc, 0, v11, vcc
	v_add_co_u32_e32 v24, vcc, s0, v10
	s_mov_b32 s0, 0x58000
	s_nop 0
	v_addc_co_u32_e32 v25, vcc, 0, v11, vcc
	global_load_dword v28, v[10:11], off nt
	global_load_dword v29, v[12:13], off nt
	global_load_dword v30, v[14:15], off nt
	global_load_dword v31, v[16:17], off nt
	global_load_dword v32, v[18:19], off nt
	global_load_dword v33, v[20:21], off nt
	global_load_dword v34, v[22:23], off nt
	global_load_dword v35, v[24:25], off nt
	v_add_co_u32_e32 v12, vcc, s0, v10
	s_mov_b32 s0, 0x63000
	s_nop 0
	v_addc_co_u32_e32 v13, vcc, 0, v11, vcc
	v_add_co_u32_e32 v14, vcc, s0, v10
	s_mov_b32 s0, 0x6e000
	s_nop 0
	v_addc_co_u32_e32 v15, vcc, 0, v11, vcc
	v_add_co_u32_e32 v16, vcc, s0, v10
	s_mov_b32 s0, 0x79000
	s_nop 0
	v_addc_co_u32_e32 v17, vcc, 0, v11, vcc
	v_add_co_u32_e32 v18, vcc, s0, v10
	s_mov_b32 s0, 0x84000
	s_nop 0
	v_addc_co_u32_e32 v19, vcc, 0, v11, vcc
	v_add_co_u32_e32 v20, vcc, s0, v10
	s_mov_b32 s0, 0x8f000
	s_nop 0
	v_addc_co_u32_e32 v21, vcc, 0, v11, vcc
	v_add_co_u32_e32 v22, vcc, s0, v10
	s_mov_b32 s0, 0x9a000
	s_nop 0
	v_addc_co_u32_e32 v23, vcc, 0, v11, vcc
	v_add_co_u32_e32 v24, vcc, s0, v10
	s_mov_b32 s0, 0xa5000
	s_nop 0
	v_addc_co_u32_e32 v25, vcc, 0, v11, vcc
	v_add_co_u32_e32 v26, vcc, s0, v10
	s_mov_b32 s0, 0xb0000
	s_nop 0
	v_addc_co_u32_e32 v27, vcc, 0, v11, vcc
	global_load_dword v36, v[12:13], off nt
	global_load_dword v37, v[14:15], off nt
	global_load_dword v38, v[16:17], off nt
	global_load_dword v39, v[18:19], off nt
	global_load_dword v40, v[20:21], off nt
	global_load_dword v41, v[22:23], off nt
	global_load_dword v42, v[24:25], off nt
	global_load_dword v43, v[26:27], off nt
	v_add_co_u32_e32 v12, vcc, s0, v10
	s_mov_b32 s0, 0xbb000
	s_nop 0
	v_addc_co_u32_e32 v13, vcc, 0, v11, vcc
	v_add_co_u32_e32 v14, vcc, s0, v10
	s_mov_b32 s0, 0xc6000
	s_nop 0
	v_addc_co_u32_e32 v15, vcc, 0, v11, vcc
	v_add_co_u32_e32 v16, vcc, s0, v10
	s_mov_b32 s0, 0xd1000
	s_nop 0
	v_addc_co_u32_e32 v17, vcc, 0, v11, vcc
	v_add_co_u32_e32 v18, vcc, s0, v10
	s_mov_b32 s0, 0xdc000
	s_nop 0
	v_addc_co_u32_e32 v19, vcc, 0, v11, vcc
	v_add_co_u32_e32 v20, vcc, s0, v10
	s_mov_b32 s0, 0xe7000
	s_nop 0
	v_addc_co_u32_e32 v21, vcc, 0, v11, vcc
	v_add_co_u32_e32 v22, vcc, s0, v10
	s_mov_b32 s0, 0xf2000
	s_nop 0
	v_addc_co_u32_e32 v23, vcc, 0, v11, vcc
	v_add_co_u32_e32 v24, vcc, s0, v10
	s_mov_b32 s0, 0xfd000
	s_nop 0
	v_addc_co_u32_e32 v25, vcc, 0, v11, vcc
	v_add_co_u32_e32 v26, vcc, s0, v10
	s_mov_b32 s0, 0x108000
	s_nop 0
	v_addc_co_u32_e32 v27, vcc, 0, v11, vcc
	global_load_dword v44, v[12:13], off nt
	global_load_dword v45, v[14:15], off nt
	global_load_dword v46, v[16:17], off nt
	global_load_dword v48, v[18:19], off nt
	global_load_dword v50, v[20:21], off nt
	global_load_dword v51, v[22:23], off nt
	global_load_dword v52, v[24:25], off nt
	s_nop 0
	global_load_dword v26, v[26:27], off nt
	v_add_co_u32_e32 v12, vcc, s0, v10
	s_mov_b32 s0, 0x113000
	s_nop 0
	v_addc_co_u32_e32 v13, vcc, 0, v11, vcc
	v_add_co_u32_e32 v14, vcc, s0, v10
	s_mov_b32 s0, 0x11e000
	s_nop 0
	v_addc_co_u32_e32 v15, vcc, 0, v11, vcc
	v_add_co_u32_e32 v16, vcc, s0, v10
	s_mov_b32 s0, 0x129000
	s_nop 0
	v_addc_co_u32_e32 v17, vcc, 0, v11, vcc
	v_add_co_u32_e32 v18, vcc, s0, v10
	s_mov_b32 s0, 0x134000
	s_nop 0
	v_addc_co_u32_e32 v19, vcc, 0, v11, vcc
	v_add_co_u32_e32 v20, vcc, s0, v10
	s_mov_b32 s0, 0x13f000
	s_nop 0
	v_addc_co_u32_e32 v21, vcc, 0, v11, vcc
	v_add_co_u32_e32 v22, vcc, s0, v10
	s_mov_b32 s0, 0x14a000
	s_nop 0
	v_addc_co_u32_e32 v23, vcc, 0, v11, vcc
	v_add_co_u32_e32 v24, vcc, s0, v10
	s_mov_b32 s0, 0x155000
	s_nop 0
	v_addc_co_u32_e32 v25, vcc, 0, v11, vcc
	v_add_co_u32_e32 v10, vcc, s0, v10
	s_lshl_b32 s0, s10, 7
	s_nop 0
	v_addc_co_u32_e32 v11, vcc, 0, v11, vcc
	global_load_dword v12, v[12:13], off nt
	s_nop 0
	global_load_dword v13, v[14:15], off nt
	s_nop 0
	global_load_dword v14, v[16:17], off nt
	global_load_dword v15, v[18:19], off nt
	s_nop 0
	global_load_dword v16, v[20:21], off nt
	global_load_dword v17, v[22:23], off nt
	global_load_dword v18, v[24:25], off nt
	s_nop 0
	global_load_dword v10, v[10:11], off nt
	v_add_u32_e32 v11, 0x400, v3
	s_waitcnt vmcnt(30)
	ds_write2_b32 v3, v28, v29 offset1:66
	s_waitcnt vmcnt(28)
	ds_write2_b32 v3, v30, v31 offset0:132 offset1:198
	s_waitcnt vmcnt(26)
	ds_write2_b32 v11, v32, v33 offset0:8 offset1:74
	s_waitcnt vmcnt(24)
	ds_write2_b32 v11, v34, v35 offset0:140 offset1:206
	v_add_u32_e32 v11, 0x800, v3
	s_waitcnt vmcnt(22)
	ds_write2_b32 v11, v36, v37 offset0:16 offset1:82
	s_waitcnt vmcnt(20)
	ds_write2_b32 v11, v38, v39 offset0:148 offset1:214
	v_add_u32_e32 v11, 0xc00, v3
	s_waitcnt vmcnt(18)
	ds_write2_b32 v11, v40, v41 offset0:24 offset1:90
	s_waitcnt vmcnt(16)
	ds_write2_b32 v11, v42, v43 offset0:156 offset1:222
	v_add_u32_e32 v11, 0x1000, v3
	s_waitcnt vmcnt(14)
	ds_write2_b32 v11, v44, v45 offset0:32 offset1:98
	s_waitcnt vmcnt(12)
	ds_write2_b32 v11, v46, v48 offset0:164 offset1:230
	v_add_u32_e32 v11, 0x1400, v3
	s_waitcnt vmcnt(10)
	ds_write2_b32 v11, v50, v51 offset0:40 offset1:106
	s_waitcnt vmcnt(8)
	ds_write2_b32 v11, v52, v26 offset0:172 offset1:238
	v_add_u32_e32 v11, 0x1800, v3
	s_waitcnt vmcnt(6)
	ds_write2_b32 v11, v12, v13 offset0:48 offset1:114
	s_waitcnt vmcnt(4)
	ds_write2_b32 v11, v14, v15 offset0:180 offset1:246
	v_add_u32_e32 v11, 0x1c00, v3
	s_waitcnt vmcnt(2)
	ds_write2_b32 v11, v16, v17 offset0:56 offset1:122
	s_waitcnt vmcnt(0)
	ds_write2_b32 v11, v18, v10 offset0:188 offset1:254
	s_waitcnt lgkmcnt(0)
	ds_read2_b32 v[14:15], v6 offset1:8
	ds_read2_b32 v[18:19], v6 offset0:33 offset1:41
	ds_read2_b32 v[20:21], v6 offset0:66 offset1:74
	ds_read2_b32 v[22:23], v6 offset0:99 offset1:107
	ds_read2_b32 v[24:25], v6 offset0:132 offset1:140
	s_waitcnt lgkmcnt(4)
	v_bfe_u32 v10, v14, 16, 1
	v_add3_u32 v10, v14, v10, s22
	s_waitcnt lgkmcnt(3)
	v_bfe_u32 v11, v18, 16, 1
	v_lshrrev_b32_e32 v10, 16, v10
	v_add3_u32 v11, v18, v11, s22
	ds_read2_b32 v[26:27], v6 offset0:165 offset1:173
	v_and_or_b32 v10, v11, s23, v10
	s_waitcnt lgkmcnt(3)
	v_bfe_u32 v11, v20, 16, 1
	v_add3_u32 v11, v20, v11, s22
	s_waitcnt lgkmcnt(2)
	v_bfe_u32 v12, v22, 16, 1
	ds_read2_b32 v[28:29], v6 offset0:198 offset1:206
	v_lshrrev_b32_e32 v11, 16, v11
	v_add3_u32 v12, v22, v12, s22
	ds_read2_b32 v[30:31], v6 offset0:231 offset1:239
	v_and_or_b32 v11, v12, s23, v11
	s_waitcnt lgkmcnt(3)
	v_bfe_u32 v12, v24, 16, 1
	v_add3_u32 v12, v24, v12, s22
	s_waitcnt lgkmcnt(2)
	v_bfe_u32 v13, v26, 16, 1
	v_lshrrev_b32_e32 v12, 16, v12
	v_add3_u32 v13, v26, v13, s22
	v_and_or_b32 v12, v13, s23, v12
	s_waitcnt lgkmcnt(1)
	v_bfe_u32 v13, v28, 16, 1
	v_add3_u32 v13, v28, v13, s22
	s_waitcnt lgkmcnt(0)
	v_bfe_u32 v14, v30, 16, 1
	s_add_u32 s0, s9, s0
	v_lshrrev_b32_e32 v13, 16, v13
	v_add3_u32 v14, v30, v14, s22
	s_addc_u32 s1, s3, 0
	v_lshlrev_b32_e32 v46, 1, v4
	v_and_or_b32 v13, v14, s23, v13
	v_or_b32_e32 v14, s2, v5
	v_lshl_add_u64 v[16:17], s[0:1], 0, v[46:47]
	v_lshlrev_b32_e32 v46, 12, v14
	v_lshl_add_u64 v[32:33], v[16:17], 0, v[46:47]
	global_store_dwordx4 v[32:33], v[10:13], off nt
	v_bfe_u32 v14, v31, 16, 1
	v_or_b32_e32 v18, s2, v7
	v_bfe_u32 v10, v15, 16, 1
	v_add3_u32 v10, v15, v10, s22
	v_bfe_u32 v11, v19, 16, 1
	v_lshrrev_b32_e32 v10, 16, v10
	v_add3_u32 v11, v19, v11, s22
	v_and_or_b32 v10, v11, s23, v10
	v_bfe_u32 v11, v21, 16, 1
	v_add3_u32 v11, v21, v11, s22
	v_bfe_u32 v12, v23, 16, 1
	v_lshrrev_b32_e32 v11, 16, v11
	v_add3_u32 v12, v23, v12, s22
	v_and_or_b32 v11, v12, s23, v11
	v_bfe_u32 v12, v25, 16, 1
	v_add3_u32 v12, v25, v12, s22
	v_bfe_u32 v13, v27, 16, 1
	v_lshrrev_b32_e32 v12, 16, v12
	v_add3_u32 v13, v27, v13, s22
	v_and_or_b32 v12, v13, s23, v12
	v_bfe_u32 v13, v29, 16, 1
	v_add3_u32 v13, v29, v13, s22
	v_lshrrev_b32_e32 v13, 16, v13
	v_add3_u32 v14, v31, v14, s22
	v_lshlrev_b32_e32 v46, 12, v18
	v_and_or_b32 v13, v14, s23, v13
	ds_read2_b32 v[14:15], v6 offset0:16 offset1:24
	v_lshl_add_u64 v[18:19], v[16:17], 0, v[46:47]
	global_store_dwordx4 v[18:19], v[10:13], off nt
	ds_read2_b32 v[18:19], v6 offset0:49 offset1:57
	ds_read2_b32 v[20:21], v6 offset0:82 offset1:90
	ds_read2_b32 v[22:23], v6 offset0:115 offset1:123
	s_waitcnt lgkmcnt(3)
	v_bfe_u32 v10, v14, 16, 1
	v_add3_u32 v10, v14, v10, s22
	s_waitcnt lgkmcnt(2)
	v_bfe_u32 v11, v18, 16, 1
	ds_read2_b32 v[24:25], v6 offset0:148 offset1:156
	v_lshrrev_b32_e32 v10, 16, v10
	v_add3_u32 v11, v18, v11, s22
	ds_read2_b32 v[26:27], v6 offset0:181 offset1:189
	v_and_or_b32 v10, v11, s23, v10
	s_waitcnt lgkmcnt(3)
	v_bfe_u32 v11, v20, 16, 1
	v_add3_u32 v11, v20, v11, s22
	s_waitcnt lgkmcnt(2)
	v_bfe_u32 v12, v22, 16, 1
	ds_read2_b32 v[28:29], v6 offset0:214 offset1:222
	v_lshrrev_b32_e32 v11, 16, v11
	v_add3_u32 v12, v22, v12, s22
	ds_read2_b32 v[30:31], v6 offset0:247 offset1:255
	v_and_or_b32 v11, v12, s23, v11
	s_waitcnt lgkmcnt(3)
	v_bfe_u32 v12, v24, 16, 1
	v_add3_u32 v12, v24, v12, s22
	s_waitcnt lgkmcnt(2)
	v_bfe_u32 v13, v26, 16, 1
	v_lshrrev_b32_e32 v12, 16, v12
	v_add3_u32 v13, v26, v13, s22
	v_and_or_b32 v12, v13, s23, v12
	s_waitcnt lgkmcnt(1)
	v_bfe_u32 v13, v28, 16, 1
	v_add3_u32 v13, v28, v13, s22
	s_waitcnt lgkmcnt(0)
	v_bfe_u32 v14, v30, 16, 1
	v_lshrrev_b32_e32 v13, 16, v13
	v_add3_u32 v14, v30, v14, s22
	v_and_or_b32 v13, v14, s23, v13
	v_or_b32_e32 v14, s2, v8
	v_lshlrev_b32_e32 v46, 12, v14
	v_lshl_add_u64 v[32:33], v[16:17], 0, v[46:47]
	global_store_dwordx4 v[32:33], v[10:13], off nt
	v_bfe_u32 v14, v31, 16, 1
	v_add3_u32 v14, v31, v14, s22
	v_bfe_u32 v10, v15, 16, 1
	v_add3_u32 v10, v15, v10, s22
	v_bfe_u32 v11, v19, 16, 1
	v_lshrrev_b32_e32 v10, 16, v10
	v_add3_u32 v11, v19, v11, s22
	v_and_or_b32 v10, v11, s23, v10
	v_bfe_u32 v11, v21, 16, 1
	v_add3_u32 v11, v21, v11, s22
	v_bfe_u32 v12, v23, 16, 1
	v_lshrrev_b32_e32 v11, 16, v11
	v_add3_u32 v12, v23, v12, s22
	v_and_or_b32 v11, v12, s23, v11
	v_bfe_u32 v12, v25, 16, 1
	v_add3_u32 v12, v25, v12, s22
	v_bfe_u32 v13, v27, 16, 1
	v_lshrrev_b32_e32 v12, 16, v12
	v_add3_u32 v13, v27, v13, s22
	v_and_or_b32 v12, v13, s23, v12
	v_bfe_u32 v13, v29, 16, 1
	v_add3_u32 v13, v29, v13, s22
	v_lshrrev_b32_e32 v13, 16, v13
	v_and_or_b32 v13, v14, s23, v13
	v_or_b32_e32 v14, s2, v9
	v_lshlrev_b32_e32 v46, 12, v14
	v_lshl_add_u64 v[14:15], v[16:17], 0, v[46:47]
	global_store_dwordx4 v[14:15], v[10:13], off nt
	s_waitcnt lgkmcnt(0)
	v_readlane_b32 s69, v251, 15
	v_readlane_b32 s72, v251, 18
	v_readlane_b32 s73, v251, 19
	v_readlane_b32 s74, v251, 20
	v_readlane_b32 s75, v251, 21
	v_readlane_b32 s76, v251, 22
	v_readlane_b32 s77, v251, 23
	v_readlane_b32 s78, v251, 24
	v_readlane_b32 s79, v251, 25
	v_readlane_b32 s80, v251, 26
	v_readlane_b32 s81, v251, 27
	v_readlane_b32 s82, v251, 28
	v_readlane_b32 s83, v251, 29

.LBB0_138:
	s_andn2_b64 vcc, exec, s[2:3]
	s_cbranch_vccnz .LBB0_140
	v_readlane_b32 s68, v251, 14
	v_readlane_b32 s69, v251, 15
	s_add_u32 s0, s68, s8
	s_addc_u32 s1, s69, s7
	v_readlane_b32 s2, v251, 56
	s_add_u32 s8, s2, s8
	v_readlane_b32 s2, v251, 57
	s_addc_u32 s3, s2, s7
	s_and_b32 s2, 0xffff, s5
	s_mul_i32 s2, s2, 0xba2f
	s_lshr_b32 s7, s2, 23
	s_mul_i32 s2, s7, 0xb0
	s_sub_i32 s2, s5, s2
	s_and_b32 s5, s2, 0xffff
	s_lshl_b32 s2, s5, 5
	s_lshl_b32 s9, s5, 6
	s_and_b32 s9, s9, 0x3f00
	s_and_b32 s2, s2, 0x60
	s_or_b32 s2, s2, s9
	s_lshl_b32 s5, s5, 7
	v_lshl_or_b32 v12, s7, 6, v1
	s_add_u32 s0, s0, s5
	s_addc_u32 s1, s1, 0
	v_lshlrev_b32_e32 v46, 2, v2
	v_mul_u32_u24_e32 v12, 0x1600, v12
	v_lshl_add_u64 v[10:11], s[0:1], 0, v[46:47]
	v_lshlrev_b32_e32 v46, 2, v12
	v_lshl_add_u64 v[10:11], v[10:11], 0, v[46:47]
	s_mov_b32 s0, 0xb000
	v_add_co_u32_e32 v12, vcc, s0, v10
	s_mov_b32 s0, 0x16000
	s_nop 0
	v_addc_co_u32_e32 v13, vcc, 0, v11, vcc
	v_add_co_u32_e32 v14, vcc, s0, v10
	s_mov_b32 s0, 0x21000
	s_nop 0
	v_addc_co_u32_e32 v15, vcc, 0, v11, vcc
	v_add_co_u32_e32 v16, vcc, s0, v10
	s_mov_b32 s0, 0x2c000
	s_nop 0
	v_addc_co_u32_e32 v17, vcc, 0, v11, vcc
	v_add_co_u32_e32 v18, vcc, s0, v10
	s_mov_b32 s0, 0x37000
	s_nop 0
	v_addc_co_u32_e32 v19, vcc, 0, v11, vcc
	v_add_co_u32_e32 v20, vcc, s0, v10
	s_mov_b32 s0, 0x42000
	s_nop 0
	v_addc_co_u32_e32 v21, vcc, 0, v11, vcc
	v_add_co_u32_e32 v22, vcc, s0, v10
	s_mov_b32 s0, 0x4d000
	s_nop 0
	v_addc_co_u32_e32 v23, vcc, 0, v11, vcc
	v_add_co_u32_e32 v24, vcc, s0, v10
	s_mov_b32 s0, 0x58000
	s_nop 0
	v_addc_co_u32_e32 v25, vcc, 0, v11, vcc
	global_load_dword v28, v[10:11], off nt
	global_load_dword v29, v[12:13], off nt
	global_load_dword v30, v[14:15], off nt
	global_load_dword v31, v[16:17], off nt
	global_load_dword v32, v[18:19], off nt
	global_load_dword v33, v[20:21], off nt
	global_load_dword v34, v[22:23], off nt
	global_load_dword v35, v[24:25], off nt
	v_add_co_u32_e32 v12, vcc, s0, v10
	s_mov_b32 s0, 0x63000
	s_nop 0
	v_addc_co_u32_e32 v13, vcc, 0, v11, vcc
	v_add_co_u32_e32 v14, vcc, s0, v10
	s_mov_b32 s0, 0x6e000
	s_nop 0
	v_addc_co_u32_e32 v15, vcc, 0, v11, vcc
	v_add_co_u32_e32 v16, vcc, s0, v10
	s_mov_b32 s0, 0x79000
	s_nop 0
	v_addc_co_u32_e32 v17, vcc, 0, v11, vcc
	v_add_co_u32_e32 v18, vcc, s0, v10
	s_mov_b32 s0, 0x84000
	s_nop 0
	v_addc_co_u32_e32 v19, vcc, 0, v11, vcc
	v_add_co_u32_e32 v20, vcc, s0, v10
	s_mov_b32 s0, 0x8f000
	s_nop 0
	v_addc_co_u32_e32 v21, vcc, 0, v11, vcc
	v_add_co_u32_e32 v22, vcc, s0, v10
	s_mov_b32 s0, 0x9a000
	s_nop 0
	v_addc_co_u32_e32 v23, vcc, 0, v11, vcc
	v_add_co_u32_e32 v24, vcc, s0, v10
	s_mov_b32 s0, 0xa5000
	s_nop 0
	v_addc_co_u32_e32 v25, vcc, 0, v11, vcc
	v_add_co_u32_e32 v26, vcc, s0, v10
	s_mov_b32 s0, 0xb0000
	s_nop 0
	v_addc_co_u32_e32 v27, vcc, 0, v11, vcc
	global_load_dword v36, v[12:13], off nt
	global_load_dword v37, v[14:15], off nt
	global_load_dword v38, v[16:17], off nt
	global_load_dword v39, v[18:19], off nt
	global_load_dword v40, v[20:21], off nt
	global_load_dword v41, v[22:23], off nt
	global_load_dword v42, v[24:25], off nt
	global_load_dword v43, v[26:27], off nt
	v_add_co_u32_e32 v12, vcc, s0, v10
	s_mov_b32 s0, 0xbb000
	s_nop 0
	v_addc_co_u32_e32 v13, vcc, 0, v11, vcc
	v_add_co_u32_e32 v14, vcc, s0, v10
	s_mov_b32 s0, 0xc6000
	s_nop 0
	v_addc_co_u32_e32 v15, vcc, 0, v11, vcc
	v_add_co_u32_e32 v16, vcc, s0, v10
	s_mov_b32 s0, 0xd1000
	s_nop 0
	v_addc_co_u32_e32 v17, vcc, 0, v11, vcc
	v_add_co_u32_e32 v18, vcc, s0, v10
	s_mov_b32 s0, 0xdc000
	s_nop 0
	v_addc_co_u32_e32 v19, vcc, 0, v11, vcc
	v_add_co_u32_e32 v20, vcc, s0, v10
	s_mov_b32 s0, 0xe7000
	s_nop 0
	v_addc_co_u32_e32 v21, vcc, 0, v11, vcc
	v_add_co_u32_e32 v22, vcc, s0, v10
	s_mov_b32 s0, 0xf2000
	s_nop 0
	v_addc_co_u32_e32 v23, vcc, 0, v11, vcc
	v_add_co_u32_e32 v24, vcc, s0, v10
	s_mov_b32 s0, 0xfd000
	s_nop 0
	v_addc_co_u32_e32 v25, vcc, 0, v11, vcc
	v_add_co_u32_e32 v26, vcc, s0, v10
	s_mov_b32 s0, 0x108000
	s_nop 0
	v_addc_co_u32_e32 v27, vcc, 0, v11, vcc
	global_load_dword v44, v[12:13], off nt
	global_load_dword v45, v[14:15], off nt
	global_load_dword v46, v[16:17], off nt
	global_load_dword v48, v[18:19], off nt
	global_load_dword v50, v[20:21], off nt
	global_load_dword v51, v[22:23], off nt
	global_load_dword v52, v[24:25], off nt
	s_nop 0
	global_load_dword v26, v[26:27], off nt
	v_add_co_u32_e32 v12, vcc, s0, v10
	s_mov_b32 s0, 0x113000
	s_nop 0
	v_addc_co_u32_e32 v13, vcc, 0, v11, vcc
	v_add_co_u32_e32 v14, vcc, s0, v10
	s_mov_b32 s0, 0x11e000
	s_nop 0
	v_addc_co_u32_e32 v15, vcc, 0, v11, vcc
	v_add_co_u32_e32 v16, vcc, s0, v10
	s_mov_b32 s0, 0x129000
	s_nop 0
	v_addc_co_u32_e32 v17, vcc, 0, v11, vcc
	v_add_co_u32_e32 v18, vcc, s0, v10
	s_mov_b32 s0, 0x134000
	s_nop 0
	v_addc_co_u32_e32 v19, vcc, 0, v11, vcc
	v_add_co_u32_e32 v20, vcc, s0, v10
	s_mov_b32 s0, 0x13f000
	s_nop 0
	v_addc_co_u32_e32 v21, vcc, 0, v11, vcc
	v_add_co_u32_e32 v22, vcc, s0, v10
	s_mov_b32 s0, 0x14a000
	s_nop 0
	v_addc_co_u32_e32 v23, vcc, 0, v11, vcc
	v_add_co_u32_e32 v24, vcc, s0, v10
	s_mov_b32 s0, 0x155000
	s_nop 0
	v_addc_co_u32_e32 v25, vcc, 0, v11, vcc
	v_add_co_u32_e32 v10, vcc, s0, v10
	s_lshl_b32 s0, s7, 7
	s_nop 0
	v_addc_co_u32_e32 v11, vcc, 0, v11, vcc
	global_load_dword v12, v[12:13], off nt
	s_nop 0
	global_load_dword v13, v[14:15], off nt
	s_nop 0
	global_load_dword v14, v[16:17], off nt
	global_load_dword v15, v[18:19], off nt
	s_nop 0
	global_load_dword v16, v[20:21], off nt
	global_load_dword v17, v[22:23], off nt
	global_load_dword v18, v[24:25], off nt
	s_nop 0
	global_load_dword v10, v[10:11], off nt
	v_add_u32_e32 v11, 0x400, v3
	s_waitcnt vmcnt(30)
	ds_write2_b32 v3, v28, v29 offset1:66
	s_waitcnt vmcnt(28)
	ds_write2_b32 v3, v30, v31 offset0:132 offset1:198
	s_waitcnt vmcnt(26)
	ds_write2_b32 v11, v32, v33 offset0:8 offset1:74
	s_waitcnt vmcnt(24)
	ds_write2_b32 v11, v34, v35 offset0:140 offset1:206
	v_add_u32_e32 v11, 0x800, v3
	s_waitcnt vmcnt(22)
	ds_write2_b32 v11, v36, v37 offset0:16 offset1:82
	s_waitcnt vmcnt(20)
	ds_write2_b32 v11, v38, v39 offset0:148 offset1:214
	v_add_u32_e32 v11, 0xc00, v3
	s_waitcnt vmcnt(18)
	ds_write2_b32 v11, v40, v41 offset0:24 offset1:90
	s_waitcnt vmcnt(16)
	ds_write2_b32 v11, v42, v43 offset0:156 offset1:222
	v_add_u32_e32 v11, 0x1000, v3
	s_waitcnt vmcnt(14)
	ds_write2_b32 v11, v44, v45 offset0:32 offset1:98
	s_waitcnt vmcnt(12)
	ds_write2_b32 v11, v46, v48 offset0:164 offset1:230
	v_add_u32_e32 v11, 0x1400, v3
	s_waitcnt vmcnt(10)
	ds_write2_b32 v11, v50, v51 offset0:40 offset1:106
	s_waitcnt vmcnt(8)
	ds_write2_b32 v11, v52, v26 offset0:172 offset1:238
	v_add_u32_e32 v11, 0x1800, v3
	s_waitcnt vmcnt(6)
	ds_write2_b32 v11, v12, v13 offset0:48 offset1:114
	s_waitcnt vmcnt(4)
	ds_write2_b32 v11, v14, v15 offset0:180 offset1:246
	v_add_u32_e32 v11, 0x1c00, v3
	s_waitcnt vmcnt(2)
	ds_write2_b32 v11, v16, v17 offset0:56 offset1:122
	s_waitcnt vmcnt(0)
	ds_write2_b32 v11, v18, v10 offset0:188 offset1:254
	s_waitcnt lgkmcnt(0)
	ds_read2_b32 v[14:15], v6 offset1:8
	ds_read2_b32 v[18:19], v6 offset0:33 offset1:41
	ds_read2_b32 v[20:21], v6 offset0:66 offset1:74
	ds_read2_b32 v[22:23], v6 offset0:99 offset1:107
	ds_read2_b32 v[24:25], v6 offset0:132 offset1:140
	s_waitcnt lgkmcnt(4)
	v_bfe_u32 v10, v14, 16, 1
	v_add3_u32 v10, v14, v10, s22
	s_waitcnt lgkmcnt(3)
	v_bfe_u32 v11, v18, 16, 1
	v_lshrrev_b32_e32 v10, 16, v10
	v_add3_u32 v11, v18, v11, s22
	ds_read2_b32 v[26:27], v6 offset0:165 offset1:173
	v_and_or_b32 v10, v11, s23, v10
	s_waitcnt lgkmcnt(3)
	v_bfe_u32 v11, v20, 16, 1
	v_add3_u32 v11, v20, v11, s22
	s_waitcnt lgkmcnt(2)
	v_bfe_u32 v12, v22, 16, 1
	ds_read2_b32 v[28:29], v6 offset0:198 offset1:206
	v_lshrrev_b32_e32 v11, 16, v11
	v_add3_u32 v12, v22, v12, s22
	ds_read2_b32 v[30:31], v6 offset0:231 offset1:239
	v_and_or_b32 v11, v12, s23, v11
	s_waitcnt lgkmcnt(3)
	v_bfe_u32 v12, v24, 16, 1
	v_add3_u32 v12, v24, v12, s22
	s_waitcnt lgkmcnt(2)
	v_bfe_u32 v13, v26, 16, 1
	v_lshrrev_b32_e32 v12, 16, v12
	v_add3_u32 v13, v26, v13, s22
	v_and_or_b32 v12, v13, s23, v12
	s_waitcnt lgkmcnt(1)
	v_bfe_u32 v13, v28, 16, 1
	v_add3_u32 v13, v28, v13, s22
	s_waitcnt lgkmcnt(0)
	v_bfe_u32 v14, v30, 16, 1
	s_add_u32 s0, s8, s0
	v_lshrrev_b32_e32 v13, 16, v13
	v_add3_u32 v14, v30, v14, s22
	s_addc_u32 s1, s3, 0
	v_lshlrev_b32_e32 v46, 1, v4
	v_and_or_b32 v13, v14, s23, v13
	v_or_b32_e32 v14, s2, v5
	v_lshl_add_u64 v[16:17], s[0:1], 0, v[46:47]
	v_lshlrev_b32_e32 v46, 12, v14
	v_lshl_add_u64 v[32:33], v[16:17], 0, v[46:47]
	global_store_dwordx4 v[32:33], v[10:13], off nt
	v_bfe_u32 v14, v31, 16, 1
	v_or_b32_e32 v18, s2, v7
	v_bfe_u32 v10, v15, 16, 1
	v_add3_u32 v10, v15, v10, s22
	v_bfe_u32 v11, v19, 16, 1
	v_lshrrev_b32_e32 v10, 16, v10
	v_add3_u32 v11, v19, v11, s22
	v_and_or_b32 v10, v11, s23, v10
	v_bfe_u32 v11, v21, 16, 1
	v_add3_u32 v11, v21, v11, s22
	v_bfe_u32 v12, v23, 16, 1
	v_lshrrev_b32_e32 v11, 16, v11
	v_add3_u32 v12, v23, v12, s22
	v_and_or_b32 v11, v12, s23, v11
	v_bfe_u32 v12, v25, 16, 1
	v_add3_u32 v12, v25, v12, s22
	v_bfe_u32 v13, v27, 16, 1
	v_lshrrev_b32_e32 v12, 16, v12
	v_add3_u32 v13, v27, v13, s22
	v_and_or_b32 v12, v13, s23, v12
	v_bfe_u32 v13, v29, 16, 1
	v_add3_u32 v13, v29, v13, s22
	v_lshrrev_b32_e32 v13, 16, v13
	v_add3_u32 v14, v31, v14, s22
	v_lshlrev_b32_e32 v46, 12, v18
	v_and_or_b32 v13, v14, s23, v13
	ds_read2_b32 v[14:15], v6 offset0:16 offset1:24
	v_lshl_add_u64 v[18:19], v[16:17], 0, v[46:47]
	global_store_dwordx4 v[18:19], v[10:13], off nt
	ds_read2_b32 v[18:19], v6 offset0:49 offset1:57
	ds_read2_b32 v[20:21], v6 offset0:82 offset1:90
	ds_read2_b32 v[22:23], v6 offset0:115 offset1:123
	s_waitcnt lgkmcnt(3)
	v_bfe_u32 v10, v14, 16, 1
	v_add3_u32 v10, v14, v10, s22
	s_waitcnt lgkmcnt(2)
	v_bfe_u32 v11, v18, 16, 1
	ds_read2_b32 v[24:25], v6 offset0:148 offset1:156
	v_lshrrev_b32_e32 v10, 16, v10
	v_add3_u32 v11, v18, v11, s22
	ds_read2_b32 v[26:27], v6 offset0:181 offset1:189
	v_and_or_b32 v10, v11, s23, v10
	s_waitcnt lgkmcnt(3)
	v_bfe_u32 v11, v20, 16, 1
	v_add3_u32 v11, v20, v11, s22
	s_waitcnt lgkmcnt(2)
	v_bfe_u32 v12, v22, 16, 1
	ds_read2_b32 v[28:29], v6 offset0:214 offset1:222
	v_lshrrev_b32_e32 v11, 16, v11
	v_add3_u32 v12, v22, v12, s22
	ds_read2_b32 v[30:31], v6 offset0:247 offset1:255
	v_and_or_b32 v11, v12, s23, v11
	s_waitcnt lgkmcnt(3)
	v_bfe_u32 v12, v24, 16, 1
	v_add3_u32 v12, v24, v12, s22
	s_waitcnt lgkmcnt(2)
	v_bfe_u32 v13, v26, 16, 1
	v_lshrrev_b32_e32 v12, 16, v12
	v_add3_u32 v13, v26, v13, s22
	v_and_or_b32 v12, v13, s23, v12
	s_waitcnt lgkmcnt(1)
	v_bfe_u32 v13, v28, 16, 1
	v_add3_u32 v13, v28, v13, s22
	s_waitcnt lgkmcnt(0)
	v_bfe_u32 v14, v30, 16, 1
	v_lshrrev_b32_e32 v13, 16, v13
	v_add3_u32 v14, v30, v14, s22
	v_and_or_b32 v13, v14, s23, v13
	v_or_b32_e32 v14, s2, v8
	v_lshlrev_b32_e32 v46, 12, v14
	v_lshl_add_u64 v[32:33], v[16:17], 0, v[46:47]
	global_store_dwordx4 v[32:33], v[10:13], off nt
	v_bfe_u32 v14, v31, 16, 1
	v_add3_u32 v14, v31, v14, s22
	v_bfe_u32 v10, v15, 16, 1
	v_add3_u32 v10, v15, v10, s22
	v_bfe_u32 v11, v19, 16, 1
	v_lshrrev_b32_e32 v10, 16, v10
	v_add3_u32 v11, v19, v11, s22
	v_and_or_b32 v10, v11, s23, v10
	v_bfe_u32 v11, v21, 16, 1
	v_add3_u32 v11, v21, v11, s22
	v_bfe_u32 v12, v23, 16, 1
	v_lshrrev_b32_e32 v11, 16, v11
	v_add3_u32 v12, v23, v12, s22
	v_and_or_b32 v11, v12, s23, v11
	v_bfe_u32 v12, v25, 16, 1
	v_add3_u32 v12, v25, v12, s22
	v_bfe_u32 v13, v27, 16, 1
	v_lshrrev_b32_e32 v12, 16, v12
	v_add3_u32 v13, v27, v13, s22
	v_and_or_b32 v12, v13, s23, v12
	v_bfe_u32 v13, v29, 16, 1
	v_add3_u32 v13, v29, v13, s22
	v_lshrrev_b32_e32 v13, 16, v13
	v_and_or_b32 v13, v14, s23, v13
	v_or_b32_e32 v14, s2, v9
	v_lshlrev_b32_e32 v46, 12, v14
	v_lshl_add_u64 v[14:15], v[16:17], 0, v[46:47]
	global_store_dwordx4 v[14:15], v[10:13], off nt
	s_waitcnt lgkmcnt(0)
	v_readlane_b32 s70, v251, 16
	v_readlane_b32 s71, v251, 17
	v_readlane_b32 s72, v251, 18
	v_readlane_b32 s73, v251, 19
	v_readlane_b32 s74, v251, 20
	v_readlane_b32 s75, v251, 21
	v_readlane_b32 s76, v251, 22
	v_readlane_b32 s77, v251, 23
	v_readlane_b32 s78, v251, 24
	v_readlane_b32 s79, v251, 25
	v_readlane_b32 s80, v251, 26
	v_readlane_b32 s81, v251, 27
	v_readlane_b32 s82, v251, 28
	v_readlane_b32 s83, v251, 29

.LBB0_141:
	s_andn2_b64 vcc, exec, s[2:3]
	s_cbranch_vccnz .LBB0_143
	s_add_i32 s0, s4, 0xffffc000
	s_lshr_b32 s20, s0, 12
	s_lshl_b64 s[0:1], s[20:21], 25
	v_readlane_b32 s68, v251, 30
	v_readlane_b32 s69, v251, 31
	s_add_u32 s8, s68, s0
	s_addc_u32 s9, s69, s1
	s_lshl_b64 s[0:1], s[20:21], 24
	v_readlane_b32 s2, v251, 58
	s_add_u32 s5, s2, s0
	v_readlane_b32 s0, v251, 59
	s_addc_u32 s3, s0, s1
	s_lshl_b32 s0, s4, 5
	s_and_b32 s2, s0, 0x7e0
	s_and_b32 s7, s4, 0xfc0
	s_lshl_b32 s0, s2, 2
	s_add_u32 s0, s8, s0
	v_or_b32_e32 v12, s7, v1
	s_addc_u32 s1, s9, 0
	v_lshlrev_b32_e32 v46, 2, v2
	v_lshl_add_u64 v[10:11], s[0:1], 0, v[46:47]
	v_lshlrev_b32_e32 v46, 13, v12
	v_lshl_add_u64 v[10:11], v[10:11], 0, v[46:47]
	s_movk_i32 s0, 0x4000
	v_add_co_u32_e32 v12, vcc, s0, v10
	s_mov_b32 s0, 0x14000
	s_nop 0
	v_addc_co_u32_e32 v13, vcc, 0, v11, vcc
	v_add_co_u32_e32 v14, vcc, s25, v10
	v_readlane_b32 s70, v251, 32
	s_nop 0
	v_addc_co_u32_e32 v15, vcc, 0, v11, vcc
	v_add_co_u32_e32 v16, vcc, s19, v10
	v_readlane_b32 s71, v251, 33
	s_nop 0
	v_addc_co_u32_e32 v17, vcc, 0, v11, vcc
	v_add_co_u32_e32 v18, vcc, s48, v10
	v_readlane_b32 s72, v251, 34
	s_nop 0
	v_addc_co_u32_e32 v19, vcc, 0, v11, vcc
	v_add_co_u32_e32 v20, vcc, s0, v10
	s_mov_b32 s0, 0x1c000
	s_nop 0
	v_addc_co_u32_e32 v21, vcc, 0, v11, vcc
	v_add_co_u32_e32 v22, vcc, s49, v10
	v_readlane_b32 s73, v251, 35
	s_nop 0
	v_addc_co_u32_e32 v23, vcc, 0, v11, vcc
	v_add_co_u32_e32 v24, vcc, s0, v10
	s_mov_b32 s0, 0x20000
	s_nop 0
	v_addc_co_u32_e32 v25, vcc, 0, v11, vcc
	global_load_dword v28, v[10:11], off nt
	global_load_dword v29, v[12:13], off nt
	global_load_dword v30, v[14:15], off nt
	global_load_dword v31, v[16:17], off nt
	global_load_dword v32, v[18:19], off nt
	global_load_dword v33, v[20:21], off nt
	global_load_dword v34, v[22:23], off nt
	global_load_dword v35, v[24:25], off nt
	v_add_co_u32_e32 v12, vcc, s0, v10
	s_mov_b32 s0, 0x24000
	s_nop 0
	v_addc_co_u32_e32 v13, vcc, 0, v11, vcc
	v_add_co_u32_e32 v14, vcc, s0, v10
	s_mov_b32 s0, 0x28000
	s_nop 0
	v_addc_co_u32_e32 v15, vcc, 0, v11, vcc
	v_add_co_u32_e32 v16, vcc, s0, v10
	s_mov_b32 s0, 0x2c000
	s_nop 0
	v_addc_co_u32_e32 v17, vcc, 0, v11, vcc
	v_add_co_u32_e32 v18, vcc, s0, v10
	s_mov_b32 s0, 0x30000
	s_nop 0
	v_addc_co_u32_e32 v19, vcc, 0, v11, vcc
	v_add_co_u32_e32 v20, vcc, s0, v10
	s_mov_b32 s0, 0x34000
	s_nop 0
	v_addc_co_u32_e32 v21, vcc, 0, v11, vcc
	v_add_co_u32_e32 v22, vcc, s0, v10
	s_mov_b32 s0, 0x38000
	s_nop 0
	v_addc_co_u32_e32 v23, vcc, 0, v11, vcc
	v_add_co_u32_e32 v24, vcc, s0, v10
	s_mov_b32 s0, 0x3c000
	s_nop 0
	v_addc_co_u32_e32 v25, vcc, 0, v11, vcc
	v_add_co_u32_e32 v26, vcc, s0, v10
	s_mov_b32 s0, 0x40000
	s_nop 0
	v_addc_co_u32_e32 v27, vcc, 0, v11, vcc
	global_load_dword v36, v[12:13], off nt
	global_load_dword v37, v[14:15], off nt
	global_load_dword v38, v[16:17], off nt
	global_load_dword v39, v[18:19], off nt
	global_load_dword v40, v[20:21], off nt
	global_load_dword v41, v[22:23], off nt
	global_load_dword v42, v[24:25], off nt
	global_load_dword v43, v[26:27], off nt
	v_add_co_u32_e32 v12, vcc, s0, v10
	s_mov_b32 s0, 0x44000
	s_nop 0
	v_addc_co_u32_e32 v13, vcc, 0, v11, vcc
	v_add_co_u32_e32 v14, vcc, s0, v10
	s_mov_b32 s0, 0x48000
	s_nop 0
	v_addc_co_u32_e32 v15, vcc, 0, v11, vcc
	v_add_co_u32_e32 v16, vcc, s0, v10
	s_mov_b32 s0, 0x4c000
	s_nop 0
	v_addc_co_u32_e32 v17, vcc, 0, v11, vcc
	v_add_co_u32_e32 v18, vcc, s0, v10
	s_mov_b32 s0, 0x50000
	s_nop 0
	v_addc_co_u32_e32 v19, vcc, 0, v11, vcc
	v_add_co_u32_e32 v20, vcc, s0, v10
	s_mov_b32 s0, 0x54000
	s_nop 0
	v_addc_co_u32_e32 v21, vcc, 0, v11, vcc
	v_add_co_u32_e32 v22, vcc, s0, v10
	s_mov_b32 s0, 0x58000
	s_nop 0
	v_addc_co_u32_e32 v23, vcc, 0, v11, vcc
	v_add_co_u32_e32 v24, vcc, s0, v10
	s_mov_b32 s0, 0x5c000
	s_nop 0
	v_addc_co_u32_e32 v25, vcc, 0, v11, vcc
	v_add_co_u32_e32 v26, vcc, s0, v10
	s_mov_b32 s0, 0x60000
	s_nop 0
	v_addc_co_u32_e32 v27, vcc, 0, v11, vcc
	global_load_dword v44, v[12:13], off nt
	global_load_dword v45, v[14:15], off nt
	global_load_dword v46, v[16:17], off nt
	global_load_dword v48, v[18:19], off nt
	global_load_dword v50, v[20:21], off nt
	global_load_dword v51, v[22:23], off nt
	global_load_dword v52, v[24:25], off nt
	s_nop 0
	global_load_dword v26, v[26:27], off nt
	v_add_co_u32_e32 v12, vcc, s0, v10
	s_mov_b32 s0, 0x64000
	s_nop 0
	v_addc_co_u32_e32 v13, vcc, 0, v11, vcc
	v_add_co_u32_e32 v14, vcc, s0, v10
	s_mov_b32 s0, 0x68000
	s_nop 0
	v_addc_co_u32_e32 v15, vcc, 0, v11, vcc
	v_add_co_u32_e32 v16, vcc, s0, v10
	s_mov_b32 s0, 0x6c000
	s_nop 0
	v_addc_co_u32_e32 v17, vcc, 0, v11, vcc
	v_add_co_u32_e32 v18, vcc, s0, v10
	s_mov_b32 s0, 0x70000
	s_nop 0
	v_addc_co_u32_e32 v19, vcc, 0, v11, vcc
	v_add_co_u32_e32 v20, vcc, s0, v10
	s_mov_b32 s0, 0x74000
	s_nop 0
	v_addc_co_u32_e32 v21, vcc, 0, v11, vcc
	v_add_co_u32_e32 v22, vcc, s0, v10
	s_mov_b32 s0, 0x78000
	s_nop 0
	v_addc_co_u32_e32 v23, vcc, 0, v11, vcc
	v_add_co_u32_e32 v24, vcc, s0, v10
	s_mov_b32 s0, 0x7c000
	s_nop 0
	v_addc_co_u32_e32 v25, vcc, 0, v11, vcc
	v_add_co_u32_e32 v10, vcc, s0, v10
	s_lshl_b32 s0, s7, 1
	s_nop 0
	v_addc_co_u32_e32 v11, vcc, 0, v11, vcc
	global_load_dword v12, v[12:13], off nt
	s_nop 0
	global_load_dword v13, v[14:15], off nt
	s_nop 0
	global_load_dword v14, v[16:17], off nt
	global_load_dword v15, v[18:19], off nt
	s_nop 0
	global_load_dword v16, v[20:21], off nt
	global_load_dword v17, v[22:23], off nt
	global_load_dword v18, v[24:25], off nt
	s_nop 0
	global_load_dword v10, v[10:11], off nt
	v_add_u32_e32 v11, 0x400, v3
	s_waitcnt vmcnt(30)
	ds_write2_b32 v3, v28, v29 offset1:66
	s_waitcnt vmcnt(28)
	ds_write2_b32 v3, v30, v31 offset0:132 offset1:198
	s_waitcnt vmcnt(26)
	ds_write2_b32 v11, v32, v33 offset0:8 offset1:74
	s_waitcnt vmcnt(24)
	ds_write2_b32 v11, v34, v35 offset0:140 offset1:206
	v_add_u32_e32 v11, 0x800, v3
	s_waitcnt vmcnt(22)
	ds_write2_b32 v11, v36, v37 offset0:16 offset1:82
	s_waitcnt vmcnt(20)
	ds_write2_b32 v11, v38, v39 offset0:148 offset1:214
	v_add_u32_e32 v11, 0xc00, v3
	s_waitcnt vmcnt(18)
	ds_write2_b32 v11, v40, v41 offset0:24 offset1:90
	s_waitcnt vmcnt(16)
	ds_write2_b32 v11, v42, v43 offset0:156 offset1:222
	v_add_u32_e32 v11, 0x1000, v3
	s_waitcnt vmcnt(14)
	ds_write2_b32 v11, v44, v45 offset0:32 offset1:98
	s_waitcnt vmcnt(12)
	ds_write2_b32 v11, v46, v48 offset0:164 offset1:230
	v_add_u32_e32 v11, 0x1400, v3
	s_waitcnt vmcnt(10)
	ds_write2_b32 v11, v50, v51 offset0:40 offset1:106
	s_waitcnt vmcnt(8)
	ds_write2_b32 v11, v52, v26 offset0:172 offset1:238
	v_add_u32_e32 v11, 0x1800, v3
	s_waitcnt vmcnt(6)
	ds_write2_b32 v11, v12, v13 offset0:48 offset1:114
	s_waitcnt vmcnt(4)
	ds_write2_b32 v11, v14, v15 offset0:180 offset1:246
	v_add_u32_e32 v11, 0x1c00, v3
	s_waitcnt vmcnt(2)
	ds_write2_b32 v11, v16, v17 offset0:56 offset1:122
	s_waitcnt vmcnt(0)
	ds_write2_b32 v11, v18, v10 offset0:188 offset1:254
	s_waitcnt lgkmcnt(0)
	ds_read2_b32 v[14:15], v6 offset1:8
	ds_read2_b32 v[18:19], v6 offset0:33 offset1:41
	ds_read2_b32 v[20:21], v6 offset0:66 offset1:74
	ds_read2_b32 v[22:23], v6 offset0:99 offset1:107
	ds_read2_b32 v[24:25], v6 offset0:132 offset1:140
	s_waitcnt lgkmcnt(4)
	v_bfe_u32 v10, v14, 16, 1
	v_add3_u32 v10, v14, v10, s22
	s_waitcnt lgkmcnt(3)
	v_bfe_u32 v11, v18, 16, 1
	v_lshrrev_b32_e32 v10, 16, v10
	v_add3_u32 v11, v18, v11, s22
	ds_read2_b32 v[26:27], v6 offset0:165 offset1:173
	v_and_or_b32 v10, v11, s23, v10
	s_waitcnt lgkmcnt(3)
	v_bfe_u32 v11, v20, 16, 1
	v_add3_u32 v11, v20, v11, s22
	s_waitcnt lgkmcnt(2)
	v_bfe_u32 v12, v22, 16, 1
	ds_read2_b32 v[28:29], v6 offset0:198 offset1:206
	v_lshrrev_b32_e32 v11, 16, v11
	v_add3_u32 v12, v22, v12, s22
	ds_read2_b32 v[30:31], v6 offset0:231 offset1:239
	v_and_or_b32 v11, v12, s23, v11
	s_waitcnt lgkmcnt(3)
	v_bfe_u32 v12, v24, 16, 1
	v_add3_u32 v12, v24, v12, s22
	s_waitcnt lgkmcnt(2)
	v_bfe_u32 v13, v26, 16, 1
	v_lshrrev_b32_e32 v12, 16, v12
	v_add3_u32 v13, v26, v13, s22
	v_and_or_b32 v12, v13, s23, v12
	s_waitcnt lgkmcnt(1)
	v_bfe_u32 v13, v28, 16, 1
	v_add3_u32 v13, v28, v13, s22
	s_waitcnt lgkmcnt(0)
	v_bfe_u32 v14, v30, 16, 1
	s_add_u32 s0, s5, s0
	v_lshrrev_b32_e32 v13, 16, v13
	v_add3_u32 v14, v30, v14, s22
	s_addc_u32 s1, s3, 0
	v_lshlrev_b32_e32 v46, 1, v4
	v_and_or_b32 v13, v14, s23, v13
	v_or_b32_e32 v14, s2, v5
	v_lshl_add_u64 v[16:17], s[0:1], 0, v[46:47]
	v_lshlrev_b32_e32 v46, 13, v14
	v_lshl_add_u64 v[32:33], v[16:17], 0, v[46:47]
	global_store_dwordx4 v[32:33], v[10:13], off nt
	v_bfe_u32 v14, v31, 16, 1
	v_or_b32_e32 v18, s2, v7
	v_bfe_u32 v10, v15, 16, 1
	v_add3_u32 v10, v15, v10, s22
	v_bfe_u32 v11, v19, 16, 1
	v_lshrrev_b32_e32 v10, 16, v10
	v_add3_u32 v11, v19, v11, s22
	v_and_or_b32 v10, v11, s23, v10
	v_bfe_u32 v11, v21, 16, 1
	v_add3_u32 v11, v21, v11, s22
	v_bfe_u32 v12, v23, 16, 1
	v_lshrrev_b32_e32 v11, 16, v11
	v_add3_u32 v12, v23, v12, s22
	v_and_or_b32 v11, v12, s23, v11
	v_bfe_u32 v12, v25, 16, 1
	v_add3_u32 v12, v25, v12, s22
	v_bfe_u32 v13, v27, 16, 1
	v_lshrrev_b32_e32 v12, 16, v12
	v_add3_u32 v13, v27, v13, s22
	v_and_or_b32 v12, v13, s23, v12
	v_bfe_u32 v13, v29, 16, 1
	v_add3_u32 v13, v29, v13, s22
	v_lshrrev_b32_e32 v13, 16, v13
	v_add3_u32 v14, v31, v14, s22
	v_lshlrev_b32_e32 v46, 13, v18
	v_and_or_b32 v13, v14, s23, v13
	ds_read2_b32 v[14:15], v6 offset0:16 offset1:24
	v_lshl_add_u64 v[18:19], v[16:17], 0, v[46:47]
	global_store_dwordx4 v[18:19], v[10:13], off nt
	ds_read2_b32 v[18:19], v6 offset0:49 offset1:57
	ds_read2_b32 v[20:21], v6 offset0:82 offset1:90
	ds_read2_b32 v[22:23], v6 offset0:115 offset1:123
	s_waitcnt lgkmcnt(3)
	v_bfe_u32 v10, v14, 16, 1
	v_add3_u32 v10, v14, v10, s22
	s_waitcnt lgkmcnt(2)
	v_bfe_u32 v11, v18, 16, 1
	ds_read2_b32 v[24:25], v6 offset0:148 offset1:156
	v_lshrrev_b32_e32 v10, 16, v10
	v_add3_u32 v11, v18, v11, s22
	ds_read2_b32 v[26:27], v6 offset0:181 offset1:189
	v_and_or_b32 v10, v11, s23, v10
	s_waitcnt lgkmcnt(3)
	v_bfe_u32 v11, v20, 16, 1
	v_add3_u32 v11, v20, v11, s22
	s_waitcnt lgkmcnt(2)
	v_bfe_u32 v12, v22, 16, 1
	ds_read2_b32 v[28:29], v6 offset0:214 offset1:222
	v_lshrrev_b32_e32 v11, 16, v11
	v_add3_u32 v12, v22, v12, s22
	ds_read2_b32 v[30:31], v6 offset0:247 offset1:255
	v_and_or_b32 v11, v12, s23, v11
	s_waitcnt lgkmcnt(3)
	v_bfe_u32 v12, v24, 16, 1
	v_add3_u32 v12, v24, v12, s22
	s_waitcnt lgkmcnt(2)
	v_bfe_u32 v13, v26, 16, 1
	v_lshrrev_b32_e32 v12, 16, v12
	v_add3_u32 v13, v26, v13, s22
	v_and_or_b32 v12, v13, s23, v12
	s_waitcnt lgkmcnt(1)
	v_bfe_u32 v13, v28, 16, 1
	v_add3_u32 v13, v28, v13, s22
	s_waitcnt lgkmcnt(0)
	v_bfe_u32 v14, v30, 16, 1
	v_lshrrev_b32_e32 v13, 16, v13
	v_add3_u32 v14, v30, v14, s22
	v_and_or_b32 v13, v14, s23, v13
	v_or_b32_e32 v14, s2, v8
	v_lshlrev_b32_e32 v46, 13, v14
	v_lshl_add_u64 v[32:33], v[16:17], 0, v[46:47]
	global_store_dwordx4 v[32:33], v[10:13], off nt
	v_bfe_u32 v14, v31, 16, 1
	v_add3_u32 v14, v31, v14, s22
	v_bfe_u32 v10, v15, 16, 1
	v_add3_u32 v10, v15, v10, s22
	v_bfe_u32 v11, v19, 16, 1
	v_lshrrev_b32_e32 v10, 16, v10
	v_add3_u32 v11, v19, v11, s22
	v_and_or_b32 v10, v11, s23, v10
	v_bfe_u32 v11, v21, 16, 1
	v_add3_u32 v11, v21, v11, s22
	v_bfe_u32 v12, v23, 16, 1
	v_lshrrev_b32_e32 v11, 16, v11
	v_add3_u32 v12, v23, v12, s22
	v_and_or_b32 v11, v12, s23, v11
	v_bfe_u32 v12, v25, 16, 1
	v_add3_u32 v12, v25, v12, s22
	v_bfe_u32 v13, v27, 16, 1
	v_lshrrev_b32_e32 v12, 16, v12
	v_add3_u32 v13, v27, v13, s22
	v_and_or_b32 v12, v13, s23, v12
	v_bfe_u32 v13, v29, 16, 1
	v_add3_u32 v13, v29, v13, s22
	v_lshrrev_b32_e32 v13, 16, v13
	v_and_or_b32 v13, v14, s23, v13
	v_or_b32_e32 v14, s2, v9
	v_lshlrev_b32_e32 v46, 13, v14
	v_lshl_add_u64 v[14:15], v[16:17], 0, v[46:47]
	global_store_dwordx4 v[14:15], v[10:13], off nt
	s_waitcnt lgkmcnt(0)
	v_readlane_b32 s74, v251, 36
	v_readlane_b32 s75, v251, 37
	v_readlane_b32 s76, v251, 38
	v_readlane_b32 s77, v251, 39
	v_readlane_b32 s78, v251, 40
	v_readlane_b32 s79, v251, 41
	v_readlane_b32 s80, v251, 42
	v_readlane_b32 s81, v251, 43
	v_readlane_b32 s82, v251, 44
	v_readlane_b32 s83, v251, 45

.LBB0_144:
	s_ashr_i32 s0, s4, 31
	s_lshr_b32 s0, s0, 19
	s_add_i32 s1, s4, s0
	s_ashr_i32 s0, s1, 13
	s_and_b32 s1, s1, 0xe000
	s_sub_i32 s4, s4, s1
	s_ashr_i32 s1, s0, 31
	v_readlane_b32 s68, v251, 14
	s_lshl_b64 s[2:3], s[0:1], 26
	v_readlane_b32 s74, v251, 20
	v_readlane_b32 s75, v251, 21
	s_add_u32 s5, s74, s2
	s_addc_u32 s9, s75, s3
	s_lshl_b64 s[0:1], s[0:1], 25
	v_readlane_b32 s2, v251, 60
	s_add_u32 s8, s2, s0
	v_readlane_b32 s0, v251, 61
	s_addc_u32 s7, s0, s1
	s_sext_i32_i16 s0, s4
	s_bfe_u32 s0, s0, 0x80017
	s_add_i32 s0, s4, s0
	s_sext_i32_i16 s1, s0
	s_and_b32 s0, s0, 0xff00
	s_sub_i32 s0, s4, s0
	s_sext_i32_i16 s0, s0
	s_ashr_i32 s1, s1, 8
	s_lshl_b32 s2, s0, 5
	s_lshl_b32 s4, s1, 6
	s_ashr_i32 s3, s2, 31
	v_or_b32_e32 v10, s4, v1
	s_lshl_b64 s[0:1], s[2:3], 2
	s_add_u32 s0, s5, s0
	v_or_b32_e32 v16, 2, v10
	v_or_b32_e32 v18, 4, v10
	v_or_b32_e32 v20, 6, v10
	v_or_b32_e32 v22, 8, v10
	v_or_b32_e32 v24, 10, v10
	v_or_b32_e32 v26, 12, v10
	v_or_b32_e32 v28, 14, v10
	s_addc_u32 s1, s9, s1
	v_lshlrev_b32_e32 v46, 2, v2
	v_ashrrev_i32_e32 v11, 31, v10
	v_ashrrev_i32_e32 v17, 31, v16
	v_ashrrev_i32_e32 v19, 31, v18
	v_ashrrev_i32_e32 v21, 31, v20
	v_ashrrev_i32_e32 v23, 31, v22
	v_ashrrev_i32_e32 v25, 31, v24
	v_ashrrev_i32_e32 v27, 31, v26
	v_ashrrev_i32_e32 v29, 31, v28
	v_lshl_add_u64 v[12:13], s[0:1], 0, v[46:47]
	v_lshlrev_b64 v[14:15], 15, v[10:11]
	v_lshlrev_b64 v[16:17], 15, v[16:17]
	v_lshlrev_b64 v[18:19], 15, v[18:19]
	v_lshlrev_b64 v[20:21], 15, v[20:21]
	v_lshlrev_b64 v[22:23], 15, v[22:23]
	v_lshlrev_b64 v[24:25], 15, v[24:25]
	v_lshlrev_b64 v[26:27], 15, v[26:27]
	v_lshlrev_b64 v[28:29], 15, v[28:29]
	v_lshl_add_u64 v[14:15], v[12:13], 0, v[14:15]
	v_lshl_add_u64 v[16:17], v[12:13], 0, v[16:17]
	v_lshl_add_u64 v[18:19], v[12:13], 0, v[18:19]
	v_lshl_add_u64 v[20:21], v[12:13], 0, v[20:21]
	v_lshl_add_u64 v[22:23], v[12:13], 0, v[22:23]
	v_lshl_add_u64 v[24:25], v[12:13], 0, v[24:25]
	v_lshl_add_u64 v[26:27], v[12:13], 0, v[26:27]
	v_lshl_add_u64 v[28:29], v[12:13], 0, v[28:29]
	global_load_dword v30, v[14:15], off nt
	global_load_dword v31, v[16:17], off nt
	global_load_dword v32, v[18:19], off nt
	global_load_dword v33, v[20:21], off nt
	global_load_dword v34, v[22:23], off nt
	global_load_dword v35, v[24:25], off nt
	global_load_dword v36, v[26:27], off nt
	global_load_dword v37, v[28:29], off nt
	v_or_b32_e32 v14, 16, v10
	v_or_b32_e32 v16, 18, v10
	v_or_b32_e32 v18, 20, v10
	v_or_b32_e32 v20, 22, v10
	v_or_b32_e32 v22, 24, v10
	v_or_b32_e32 v24, 26, v10
	v_or_b32_e32 v26, 28, v10
	v_or_b32_e32 v28, 30, v10
	v_ashrrev_i32_e32 v15, 31, v14
	v_ashrrev_i32_e32 v17, 31, v16
	v_ashrrev_i32_e32 v19, 31, v18
	v_ashrrev_i32_e32 v21, 31, v20
	v_ashrrev_i32_e32 v23, 31, v22
	v_ashrrev_i32_e32 v25, 31, v24
	v_ashrrev_i32_e32 v27, 31, v26
	v_ashrrev_i32_e32 v29, 31, v28
	v_lshlrev_b64 v[14:15], 15, v[14:15]
	v_lshlrev_b64 v[16:17], 15, v[16:17]
	v_lshlrev_b64 v[18:19], 15, v[18:19]
	v_lshlrev_b64 v[20:21], 15, v[20:21]
	v_lshlrev_b64 v[22:23], 15, v[22:23]
	v_lshlrev_b64 v[24:25], 15, v[24:25]
	v_lshlrev_b64 v[26:27], 15, v[26:27]
	v_lshlrev_b64 v[28:29], 15, v[28:29]
	v_lshl_add_u64 v[14:15], v[12:13], 0, v[14:15]
	v_lshl_add_u64 v[16:17], v[12:13], 0, v[16:17]
	v_lshl_add_u64 v[18:19], v[12:13], 0, v[18:19]
	v_lshl_add_u64 v[20:21], v[12:13], 0, v[20:21]
	v_lshl_add_u64 v[22:23], v[12:13], 0, v[22:23]
	v_lshl_add_u64 v[24:25], v[12:13], 0, v[24:25]
	v_lshl_add_u64 v[26:27], v[12:13], 0, v[26:27]
	v_lshl_add_u64 v[28:29], v[12:13], 0, v[28:29]
	global_load_dword v38, v[14:15], off nt
	global_load_dword v39, v[16:17], off nt
	global_load_dword v40, v[18:19], off nt
	global_load_dword v41, v[20:21], off nt
	global_load_dword v42, v[22:23], off nt
	global_load_dword v43, v[24:25], off nt
	global_load_dword v44, v[26:27], off nt
	global_load_dword v45, v[28:29], off nt
	v_or_b32_e32 v14, 32, v10
	v_or_b32_e32 v16, 34, v10
	v_or_b32_e32 v18, 36, v10
	v_or_b32_e32 v20, 38, v10
	v_or_b32_e32 v22, 40, v10
	v_or_b32_e32 v24, 42, v10
	v_or_b32_e32 v26, 44, v10
	v_or_b32_e32 v28, 46, v10
	v_ashrrev_i32_e32 v15, 31, v14
	v_ashrrev_i32_e32 v17, 31, v16
	v_ashrrev_i32_e32 v19, 31, v18
	v_ashrrev_i32_e32 v21, 31, v20
	v_ashrrev_i32_e32 v23, 31, v22
	v_ashrrev_i32_e32 v25, 31, v24
	v_ashrrev_i32_e32 v27, 31, v26
	v_ashrrev_i32_e32 v29, 31, v28
	v_lshlrev_b64 v[14:15], 15, v[14:15]
	v_lshlrev_b64 v[16:17], 15, v[16:17]
	v_lshlrev_b64 v[18:19], 15, v[18:19]
	v_lshlrev_b64 v[20:21], 15, v[20:21]
	v_lshlrev_b64 v[22:23], 15, v[22:23]
	v_lshlrev_b64 v[24:25], 15, v[24:25]
	v_lshlrev_b64 v[26:27], 15, v[26:27]
	v_lshlrev_b64 v[28:29], 15, v[28:29]
	v_lshl_add_u64 v[14:15], v[12:13], 0, v[14:15]
	v_lshl_add_u64 v[16:17], v[12:13], 0, v[16:17]
	v_lshl_add_u64 v[18:19], v[12:13], 0, v[18:19]
	v_lshl_add_u64 v[20:21], v[12:13], 0, v[20:21]
	v_lshl_add_u64 v[22:23], v[12:13], 0, v[22:23]
	v_lshl_add_u64 v[24:25], v[12:13], 0, v[24:25]
	v_lshl_add_u64 v[26:27], v[12:13], 0, v[26:27]
	v_lshl_add_u64 v[28:29], v[12:13], 0, v[28:29]
	global_load_dword v46, v[14:15], off nt
	global_load_dword v48, v[16:17], off nt
	global_load_dword v50, v[18:19], off nt
	global_load_dword v51, v[20:21], off nt
	global_load_dword v52, v[22:23], off nt
	global_load_dword v54, v[24:25], off nt
	global_load_dword v55, v[26:27], off nt
	s_nop 0
	global_load_dword v28, v[28:29], off nt
	v_or_b32_e32 v14, 48, v10
	v_or_b32_e32 v16, 50, v10
	v_or_b32_e32 v18, 52, v10
	v_or_b32_e32 v20, 54, v10
	v_or_b32_e32 v22, 56, v10
	v_or_b32_e32 v24, 58, v10
	v_or_b32_e32 v26, 60, v10
	v_or_b32_e32 v10, 62, v10
	v_ashrrev_i32_e32 v15, 31, v14
	v_ashrrev_i32_e32 v17, 31, v16
	v_ashrrev_i32_e32 v19, 31, v18
	v_ashrrev_i32_e32 v11, 31, v10
	v_lshlrev_b64 v[14:15], 15, v[14:15]
	v_lshlrev_b64 v[16:17], 15, v[16:17]
	v_lshlrev_b64 v[18:19], 15, v[18:19]
	v_ashrrev_i32_e32 v21, 31, v20
	v_ashrrev_i32_e32 v23, 31, v22
	v_ashrrev_i32_e32 v25, 31, v24
	v_ashrrev_i32_e32 v27, 31, v26
	v_lshlrev_b64 v[10:11], 15, v[10:11]
	v_lshl_add_u64 v[14:15], v[12:13], 0, v[14:15]
	v_lshl_add_u64 v[16:17], v[12:13], 0, v[16:17]
	v_lshl_add_u64 v[18:19], v[12:13], 0, v[18:19]
	v_lshlrev_b64 v[20:21], 15, v[20:21]
	v_lshlrev_b64 v[22:23], 15, v[22:23]
	v_lshlrev_b64 v[24:25], 15, v[24:25]
	v_lshlrev_b64 v[26:27], 15, v[26:27]
	v_lshl_add_u64 v[10:11], v[12:13], 0, v[10:11]
	v_lshl_add_u64 v[20:21], v[12:13], 0, v[20:21]
	v_lshl_add_u64 v[22:23], v[12:13], 0, v[22:23]
	v_lshl_add_u64 v[24:25], v[12:13], 0, v[24:25]
	v_lshl_add_u64 v[26:27], v[12:13], 0, v[26:27]
	global_load_dword v12, v[14:15], off nt
	global_load_dword v13, v[16:17], off nt
	s_nop 0
	global_load_dword v14, v[18:19], off nt
	global_load_dword v15, v[20:21], off nt
	global_load_dword v16, v[22:23], off nt
	global_load_dword v17, v[24:25], off nt
	s_nop 0
	global_load_dword v18, v[26:27], off nt
	s_nop 0
	global_load_dword v10, v[10:11], off nt
	v_add_u32_e32 v11, 0x400, v3
	s_waitcnt vmcnt(30)
	ds_write2_b32 v3, v30, v31 offset1:66
	s_waitcnt vmcnt(28)
	ds_write2_b32 v3, v32, v33 offset0:132 offset1:198
	s_waitcnt vmcnt(26)
	ds_write2_b32 v11, v34, v35 offset0:8 offset1:74
	s_waitcnt vmcnt(24)
	ds_write2_b32 v11, v36, v37 offset0:140 offset1:206
	v_add_u32_e32 v11, 0x800, v3
	s_waitcnt vmcnt(22)
	ds_write2_b32 v11, v38, v39 offset0:16 offset1:82
	s_waitcnt vmcnt(20)
	ds_write2_b32 v11, v40, v41 offset0:148 offset1:214
	v_add_u32_e32 v11, 0xc00, v3
	s_waitcnt vmcnt(18)
	ds_write2_b32 v11, v42, v43 offset0:24 offset1:90
	s_waitcnt vmcnt(16)
	ds_write2_b32 v11, v44, v45 offset0:156 offset1:222
	v_add_u32_e32 v11, 0x1000, v3
	s_waitcnt vmcnt(14)
	ds_write2_b32 v11, v46, v48 offset0:32 offset1:98
	s_waitcnt vmcnt(12)
	ds_write2_b32 v11, v50, v51 offset0:164 offset1:230
	v_add_u32_e32 v11, 0x1400, v3
	s_waitcnt vmcnt(10)
	ds_write2_b32 v11, v52, v54 offset0:40 offset1:106
	s_waitcnt vmcnt(8)
	ds_write2_b32 v11, v55, v28 offset0:172 offset1:238
	v_add_u32_e32 v11, 0x1800, v3
	s_waitcnt vmcnt(6)
	ds_write2_b32 v11, v12, v13 offset0:48 offset1:114
	s_waitcnt vmcnt(4)
	ds_write2_b32 v11, v14, v15 offset0:180 offset1:246
	v_add_u32_e32 v11, 0x1c00, v3
	s_waitcnt vmcnt(2)
	ds_write2_b32 v11, v16, v17 offset0:56 offset1:122
	s_waitcnt vmcnt(0)
	ds_write2_b32 v11, v18, v10 offset0:188 offset1:254
	s_waitcnt lgkmcnt(0)
	ds_read2_b32 v[14:15], v6 offset1:8
	ds_read2_b32 v[18:19], v6 offset0:33 offset1:41
	ds_read2_b32 v[20:21], v6 offset0:66 offset1:74
	ds_read2_b32 v[22:23], v6 offset0:99 offset1:107
	ds_read2_b32 v[24:25], v6 offset0:132 offset1:140
	s_waitcnt lgkmcnt(4)
	v_bfe_u32 v10, v14, 16, 1
	v_add3_u32 v10, v14, v10, s22
	s_waitcnt lgkmcnt(3)
	v_bfe_u32 v11, v18, 16, 1
	v_lshrrev_b32_e32 v10, 16, v10
	v_add3_u32 v11, v18, v11, s22
	ds_read2_b32 v[26:27], v6 offset0:165 offset1:173
	v_and_or_b32 v10, v11, s23, v10
	s_waitcnt lgkmcnt(3)
	v_bfe_u32 v11, v20, 16, 1
	v_add3_u32 v11, v20, v11, s22
	s_waitcnt lgkmcnt(2)
	v_bfe_u32 v12, v22, 16, 1
	ds_read2_b32 v[28:29], v6 offset0:198 offset1:206
	v_lshrrev_b32_e32 v11, 16, v11
	v_add3_u32 v12, v22, v12, s22
	ds_read2_b32 v[30:31], v6 offset0:231 offset1:239
	v_and_or_b32 v11, v12, s23, v11
	s_waitcnt lgkmcnt(3)
	v_bfe_u32 v12, v24, 16, 1
	s_ashr_i32 s5, s4, 31
	v_add3_u32 v12, v24, v12, s22
	s_waitcnt lgkmcnt(2)
	v_bfe_u32 v13, v26, 16, 1
	s_lshl_b64 s[0:1], s[4:5], 1
	v_lshrrev_b32_e32 v12, 16, v12
	v_add3_u32 v13, v26, v13, s22
	s_add_u32 s0, s8, s0
	v_and_or_b32 v12, v13, s23, v12
	s_waitcnt lgkmcnt(1)
	v_bfe_u32 v13, v28, 16, 1
	v_or_b32_e32 v32, s2, v5
	s_addc_u32 s1, s7, s1
	v_lshlrev_b32_e32 v46, 1, v4
	v_add3_u32 v13, v28, v13, s22
	s_waitcnt lgkmcnt(0)
	v_bfe_u32 v14, v30, 16, 1
	v_ashrrev_i32_e32 v33, 31, v32
	v_lshl_add_u64 v[16:17], s[0:1], 0, v[46:47]
	v_lshrrev_b32_e32 v13, 16, v13
	v_add3_u32 v14, v30, v14, s22
	v_lshlrev_b64 v[32:33], 12, v[32:33]
	v_and_or_b32 v13, v14, s23, v13
	v_lshl_add_u64 v[32:33], v[16:17], 0, v[32:33]
	global_store_dwordx4 v[32:33], v[10:13], off nt
	v_bfe_u32 v14, v31, 16, 1
	v_add3_u32 v14, v31, v14, s22
	v_bfe_u32 v10, v15, 16, 1
	v_add3_u32 v10, v15, v10, s22
	v_bfe_u32 v11, v19, 16, 1
	v_lshrrev_b32_e32 v10, 16, v10
	v_add3_u32 v11, v19, v11, s22
	v_and_or_b32 v10, v11, s23, v10
	v_bfe_u32 v11, v21, 16, 1
	v_add3_u32 v11, v21, v11, s22
	v_bfe_u32 v12, v23, 16, 1
	v_lshrrev_b32_e32 v11, 16, v11
	v_add3_u32 v12, v23, v12, s22
	v_and_or_b32 v11, v12, s23, v11
	v_bfe_u32 v12, v25, 16, 1
	v_add3_u32 v12, v25, v12, s22
	v_bfe_u32 v13, v27, 16, 1
	v_lshrrev_b32_e32 v12, 16, v12
	v_add3_u32 v13, v27, v13, s22
	v_and_or_b32 v12, v13, s23, v12
	v_bfe_u32 v13, v29, 16, 1
	v_add3_u32 v13, v29, v13, s22
	v_lshrrev_b32_e32 v13, 16, v13
	v_and_or_b32 v13, v14, s23, v13
	v_or_b32_e32 v14, s2, v7
	v_ashrrev_i32_e32 v15, 31, v14
	v_lshlrev_b64 v[14:15], 12, v[14:15]
	ds_read2_b32 v[18:19], v6 offset0:16 offset1:24
	v_lshl_add_u64 v[14:15], v[16:17], 0, v[14:15]
	global_store_dwordx4 v[14:15], v[10:13], off nt
	ds_read2_b32 v[14:15], v6 offset0:49 offset1:57
	ds_read2_b32 v[20:21], v6 offset0:82 offset1:90
	ds_read2_b32 v[22:23], v6 offset0:115 offset1:123
	s_waitcnt lgkmcnt(3)
	v_bfe_u32 v10, v18, 16, 1
	v_add3_u32 v10, v18, v10, s22
	s_waitcnt lgkmcnt(2)
	v_bfe_u32 v11, v14, 16, 1
	ds_read2_b32 v[24:25], v6 offset0:148 offset1:156
	v_lshrrev_b32_e32 v10, 16, v10
	v_add3_u32 v11, v14, v11, s22
	ds_read2_b32 v[26:27], v6 offset0:181 offset1:189
	v_and_or_b32 v10, v11, s23, v10
	s_waitcnt lgkmcnt(3)
	v_bfe_u32 v11, v20, 16, 1
	v_add3_u32 v11, v20, v11, s22
	s_waitcnt lgkmcnt(2)
	v_bfe_u32 v12, v22, 16, 1
	ds_read2_b32 v[28:29], v6 offset0:214 offset1:222
	v_lshrrev_b32_e32 v11, 16, v11
	v_add3_u32 v12, v22, v12, s22
	ds_read2_b32 v[30:31], v6 offset0:247 offset1:255
	v_and_or_b32 v11, v12, s23, v11
	s_waitcnt lgkmcnt(3)
	v_bfe_u32 v12, v24, 16, 1
	v_add3_u32 v12, v24, v12, s22
	s_waitcnt lgkmcnt(2)
	v_bfe_u32 v13, v26, 16, 1
	v_lshrrev_b32_e32 v12, 16, v12
	v_add3_u32 v13, v26, v13, s22
	v_and_or_b32 v12, v13, s23, v12
	s_waitcnt lgkmcnt(1)
	v_bfe_u32 v13, v28, 16, 1
	v_or_b32_e32 v32, s2, v8
	v_add3_u32 v13, v28, v13, s22
	s_waitcnt lgkmcnt(0)
	v_bfe_u32 v14, v30, 16, 1
	v_ashrrev_i32_e32 v33, 31, v32
	v_lshrrev_b32_e32 v13, 16, v13
	v_add3_u32 v14, v30, v14, s22
	v_lshlrev_b64 v[32:33], 12, v[32:33]
	v_and_or_b32 v13, v14, s23, v13
	v_lshl_add_u64 v[32:33], v[16:17], 0, v[32:33]
	global_store_dwordx4 v[32:33], v[10:13], off nt
	v_bfe_u32 v14, v31, 16, 1
	v_add3_u32 v14, v31, v14, s22
	v_bfe_u32 v10, v19, 16, 1
	v_add3_u32 v10, v19, v10, s22
	v_bfe_u32 v11, v15, 16, 1
	v_lshrrev_b32_e32 v10, 16, v10
	v_add3_u32 v11, v15, v11, s22
	v_and_or_b32 v10, v11, s23, v10
	v_bfe_u32 v11, v21, 16, 1
	v_add3_u32 v11, v21, v11, s22
	v_bfe_u32 v12, v23, 16, 1
	v_lshrrev_b32_e32 v11, 16, v11
	v_add3_u32 v12, v23, v12, s22
	v_and_or_b32 v11, v12, s23, v11
	v_bfe_u32 v12, v25, 16, 1
	v_add3_u32 v12, v25, v12, s22
	v_bfe_u32 v13, v27, 16, 1
	v_lshrrev_b32_e32 v12, 16, v12
	v_add3_u32 v13, v27, v13, s22
	v_and_or_b32 v12, v13, s23, v12
	v_bfe_u32 v13, v29, 16, 1
	v_add3_u32 v13, v29, v13, s22
	v_lshrrev_b32_e32 v13, 16, v13
	v_and_or_b32 v13, v14, s23, v13
	v_or_b32_e32 v14, s2, v9
	v_ashrrev_i32_e32 v15, 31, v14
	v_lshlrev_b64 v[14:15], 12, v[14:15]
	v_lshl_add_u64 v[14:15], v[16:17], 0, v[14:15]
	global_store_dwordx4 v[14:15], v[10:13], off nt
	s_waitcnt lgkmcnt(0)
	v_readlane_b32 s69, v251, 15
	v_readlane_b32 s70, v251, 16
	v_readlane_b32 s71, v251, 17
	v_readlane_b32 s72, v251, 18
	v_readlane_b32 s73, v251, 19
	v_readlane_b32 s76, v251, 22
	v_readlane_b32 s77, v251, 23
	v_readlane_b32 s78, v251, 24
	v_readlane_b32 s79, v251, 25
	v_readlane_b32 s80, v251, 26
	v_readlane_b32 s81, v251, 27
	v_readlane_b32 s82, v251, 28
	v_readlane_b32 s83, v251, 29
	s_branch .LBB0_79

.LBB0_506:
	s_cmpk_gt_i32 s4, 0x3fff
	s_mov_b64 s[2:3], -1
	s_cbranch_scc0 .LBB0_527
	s_cmpk_gt_u32 s4, 0x5fff
	s_cbranch_scc0 .LBB0_524
	s_cmp_gt_u32 s4, 0x167ff
	s_cbranch_scc0 .LBB0_514
	s_cmp_gt_u32 s4, 0x177ff
	s_cbranch_scc0 .LBB0_511
	s_add_i32 s2, s4, 0xfffe8800
	v_readlane_b32 s16, v251, 6
	s_and_b32 s86, s2, 0xfffff800
	v_readlane_b32 s20, v251, 10
	v_readlane_b32 s21, v251, 11
	s_lshl_b64 s[0:1], s[86:87], 2
	v_readlane_b32 s22, v251, 12
	v_readlane_b32 s23, v251, 13
	s_mov_b64 s[8:9], s[20:21]
	s_add_u32 s0, s8, s0
	s_addc_u32 s1, s9, s1
	s_lshl_b32 s7, s4, 5
	s_lshr_b32 s2, s2, 4
	s_lshl_b32 s8, s4, 6
	s_and_b32 s7, s7, 0x60
	s_and_b32 s2, s2, 0xfffff80
	s_and_b32 s5, s4, 63
	s_and_b32 s8, s8, 0xf00
	s_or_b32 s2, s2, s7
	s_and_b32 s3, s4, 0x7c0
	s_or_b32 s2, s2, s8
	s_lshl_b32 s5, s5, 7
	s_add_u32 s0, s0, s5
	v_or_b32_e32 v10, s3, v3
	s_addc_u32 s1, s1, 0
	v_lshlrev_b32_e32 v202, 2, v2
	v_lshl_add_u64 v[8:9], s[0:1], 0, v[202:203]
	v_lshlrev_b32_e32 v202, 14, v10
	v_lshl_add_u64 v[8:9], v[8:9], 0, v[202:203]
	s_mov_b32 s0, 0x8000
	v_add_co_u32_e32 v10, vcc, s0, v8
	s_mov_b32 s0, 0x10000
	s_nop 0
	v_addc_co_u32_e32 v11, vcc, 0, v9, vcc
	global_load_dword v17, v[8:9], off nt
	global_load_dword v18, v[10:11], off nt
	v_add_co_u32_e32 v10, vcc, s0, v8
	s_mov_b32 s0, 0x18000
	s_nop 0
	v_addc_co_u32_e32 v11, vcc, 0, v9, vcc
	global_load_dword v19, v[10:11], off nt
	v_add_co_u32_e32 v10, vcc, s0, v8
	s_mov_b32 s0, 0x20000
	s_nop 0
	v_addc_co_u32_e32 v11, vcc, 0, v9, vcc
	global_load_dword v20, v[10:11], off nt
	v_add_co_u32_e32 v10, vcc, s0, v8
	s_mov_b32 s0, 0x28000
	s_nop 0
	v_addc_co_u32_e32 v11, vcc, 0, v9, vcc
	global_load_dword v21, v[10:11], off nt
	v_add_co_u32_e32 v10, vcc, s0, v8
	s_mov_b32 s0, 0x30000
	s_nop 0
	v_addc_co_u32_e32 v11, vcc, 0, v9, vcc
	global_load_dword v22, v[10:11], off nt
	v_add_co_u32_e32 v10, vcc, s0, v8
	s_mov_b32 s0, 0x38000
	s_nop 0
	v_addc_co_u32_e32 v11, vcc, 0, v9, vcc
	global_load_dword v23, v[10:11], off nt
	v_add_co_u32_e32 v10, vcc, s0, v8
	s_mov_b32 s0, 0x40000
	s_nop 0
	v_addc_co_u32_e32 v11, vcc, 0, v9, vcc
	global_load_dword v24, v[10:11], off nt
	v_add_co_u32_e32 v10, vcc, s0, v8
	s_mov_b32 s0, 0x48000
	s_nop 0
	v_addc_co_u32_e32 v11, vcc, 0, v9, vcc
	global_load_dword v25, v[10:11], off nt
	v_add_co_u32_e32 v10, vcc, s0, v8
	s_mov_b32 s0, 0x50000
	s_nop 0
	v_addc_co_u32_e32 v11, vcc, 0, v9, vcc
	global_load_dword v26, v[10:11], off nt
	v_add_co_u32_e32 v10, vcc, s0, v8
	s_mov_b32 s0, 0x58000
	s_nop 0
	v_addc_co_u32_e32 v11, vcc, 0, v9, vcc
	global_load_dword v27, v[10:11], off nt
	v_add_co_u32_e32 v10, vcc, s0, v8
	s_mov_b32 s0, 0x60000
	s_nop 0
	v_addc_co_u32_e32 v11, vcc, 0, v9, vcc
	global_load_dword v28, v[10:11], off nt
	v_add_co_u32_e32 v10, vcc, s0, v8
	s_mov_b32 s0, 0x68000
	s_nop 0
	v_addc_co_u32_e32 v11, vcc, 0, v9, vcc
	global_load_dword v29, v[10:11], off nt
	v_add_co_u32_e32 v10, vcc, s0, v8
	s_mov_b32 s0, 0x70000
	s_nop 0
	v_addc_co_u32_e32 v11, vcc, 0, v9, vcc
	global_load_dword v30, v[10:11], off nt
	v_add_co_u32_e32 v10, vcc, s0, v8
	s_mov_b32 s0, 0x78000
	s_nop 0
	v_addc_co_u32_e32 v11, vcc, 0, v9, vcc
	global_load_dword v31, v[10:11], off nt
	v_add_co_u32_e32 v10, vcc, s0, v8
	s_mov_b32 s0, 0x80000
	s_nop 0
	v_addc_co_u32_e32 v11, vcc, 0, v9, vcc
	global_load_dword v32, v[10:11], off nt
	v_add_co_u32_e32 v10, vcc, s0, v8
	s_mov_b32 s0, 0x88000
	s_nop 0
	v_addc_co_u32_e32 v11, vcc, 0, v9, vcc
	global_load_dword v33, v[10:11], off nt
	v_add_co_u32_e32 v10, vcc, s0, v8
	s_mov_b32 s0, 0x90000
	s_nop 0
	v_addc_co_u32_e32 v11, vcc, 0, v9, vcc
	global_load_dword v34, v[10:11], off nt
	v_add_co_u32_e32 v10, vcc, s0, v8
	s_mov_b32 s0, 0x98000
	s_nop 0
	v_addc_co_u32_e32 v11, vcc, 0, v9, vcc
	global_load_dword v35, v[10:11], off nt
	v_add_co_u32_e32 v10, vcc, s0, v8
	s_mov_b32 s0, 0xa0000
	s_nop 0
	v_addc_co_u32_e32 v11, vcc, 0, v9, vcc
	global_load_dword v36, v[10:11], off nt
	v_add_co_u32_e32 v10, vcc, s0, v8
	s_mov_b32 s0, 0xa8000
	s_nop 0
	v_addc_co_u32_e32 v11, vcc, 0, v9, vcc
	global_load_dword v37, v[10:11], off nt
	v_add_co_u32_e32 v10, vcc, s0, v8
	s_mov_b32 s0, 0xb0000
	s_nop 0
	v_addc_co_u32_e32 v11, vcc, 0, v9, vcc
	global_load_dword v38, v[10:11], off nt
	v_add_co_u32_e32 v10, vcc, s0, v8
	s_mov_b32 s0, 0xb8000
	s_nop 0
	v_addc_co_u32_e32 v11, vcc, 0, v9, vcc
	global_load_dword v39, v[10:11], off nt
	v_add_co_u32_e32 v10, vcc, s0, v8
	s_mov_b32 s0, 0xc0000
	s_nop 0
	v_addc_co_u32_e32 v11, vcc, 0, v9, vcc
	global_load_dword v40, v[10:11], off nt
	v_add_co_u32_e32 v10, vcc, s0, v8
	s_mov_b32 s0, 0xc8000
	s_nop 0
	v_addc_co_u32_e32 v11, vcc, 0, v9, vcc
	global_load_dword v41, v[10:11], off nt
	v_add_co_u32_e32 v10, vcc, s0, v8
	s_mov_b32 s0, 0xd0000
	s_nop 0
	v_addc_co_u32_e32 v11, vcc, 0, v9, vcc
	global_load_dword v42, v[10:11], off nt
	v_add_co_u32_e32 v10, vcc, s0, v8
	s_mov_b32 s0, 0xd8000
	s_nop 0
	v_addc_co_u32_e32 v11, vcc, 0, v9, vcc
	global_load_dword v43, v[10:11], off nt
	v_add_co_u32_e32 v10, vcc, s0, v8
	s_mov_b32 s0, 0xe0000
	s_nop 0
	v_addc_co_u32_e32 v11, vcc, 0, v9, vcc
	global_load_dword v44, v[10:11], off nt
	v_add_co_u32_e32 v10, vcc, s0, v8
	s_mov_b32 s0, 0xe8000
	s_nop 0
	v_addc_co_u32_e32 v11, vcc, 0, v9, vcc
	global_load_dword v45, v[10:11], off nt
	v_add_co_u32_e32 v10, vcc, s0, v8
	s_mov_b32 s0, 0xf0000
	s_nop 0
	v_addc_co_u32_e32 v11, vcc, 0, v9, vcc
	global_load_dword v46, v[10:11], off nt
	v_add_co_u32_e32 v10, vcc, s0, v8
	s_mov_b32 s0, 0xf8000
	s_nop 0
	v_addc_co_u32_e32 v11, vcc, 0, v9, vcc
	v_add_co_u32_e32 v8, vcc, s0, v8
	global_load_dword v10, v[10:11], off nt
	s_nop 0
	v_addc_co_u32_e32 v9, vcc, 0, v9, vcc
	global_load_dword v8, v[8:9], off nt
	v_add_u32_e32 v9, 0x400, v5
	s_waitcnt vmcnt(0)
	ds_write2_b32 v5, v17, v18 offset1:66
	ds_write2_b32 v5, v19, v20 offset0:132 offset1:198
	ds_write2_b32 v9, v21, v22 offset0:8 offset1:74
	ds_write2_b32 v9, v23, v24 offset0:140 offset1:206
	v_add_u32_e32 v9, 0x800, v5
	ds_write2_b32 v9, v25, v26 offset0:16 offset1:82
	ds_write2_b32 v9, v27, v28 offset0:148 offset1:214
	v_add_u32_e32 v9, 0xc00, v5
	ds_write2_b32 v9, v29, v30 offset0:24 offset1:90
	ds_write2_b32 v9, v31, v32 offset0:156 offset1:222
	v_add_u32_e32 v9, 0x1000, v5
	ds_write2_b32 v9, v33, v34 offset0:32 offset1:98
	ds_write2_b32 v9, v35, v36 offset0:164 offset1:230
	v_add_u32_e32 v9, 0x1400, v5
	ds_write2_b32 v9, v37, v38 offset0:40 offset1:106
	ds_write2_b32 v9, v39, v40 offset0:172 offset1:238
	v_add_u32_e32 v9, 0x1800, v5
	ds_write2_b32 v9, v41, v42 offset0:48 offset1:114
	ds_write2_b32 v9, v43, v44 offset0:180 offset1:246
	v_add_u32_e32 v9, 0x1c00, v5
	ds_write2_b32 v9, v45, v46 offset0:56 offset1:122
	ds_write2_b32 v9, v10, v8 offset0:188 offset1:254
	s_waitcnt lgkmcnt(0)
	ds_read2_b32 v[10:11], v13 offset0:33 offset1:41
	ds_read2_b32 v[22:23], v13 offset1:8
	ds_read2_b32 v[24:25], v13 offset0:66 offset1:74
	ds_read2_b32 v[26:27], v13 offset0:99 offset1:107
	ds_read2_b32 v[28:29], v13 offset0:132 offset1:140
	ds_read2_b32 v[30:31], v13 offset0:165 offset1:173
	ds_read2_b32 v[32:33], v13 offset0:198 offset1:206
	ds_read2_b32 v[34:35], v13 offset0:231 offset1:239
	s_waitcnt lgkmcnt(7)
	v_bfe_u32 v18, v10, 16, 1
	s_waitcnt lgkmcnt(6)
	v_bfe_u32 v17, v22, 16, 1
	v_add3_u32 v17, v22, v17, s53
	v_lshrrev_b32_e32 v17, 16, v17
	v_add3_u32 v10, v10, v18, s53
	v_and_or_b32 v18, v10, s77, v17
	s_waitcnt lgkmcnt(5)
	v_bfe_u32 v10, v24, 16, 1
	v_add3_u32 v10, v24, v10, s53
	s_waitcnt lgkmcnt(4)
	v_bfe_u32 v17, v26, 16, 1
	v_lshrrev_b32_e32 v10, 16, v10
	v_add3_u32 v17, v26, v17, s53
	v_and_or_b32 v19, v17, s77, v10
	s_waitcnt lgkmcnt(3)
	v_bfe_u32 v10, v28, 16, 1
	v_add3_u32 v10, v28, v10, s53
	s_waitcnt lgkmcnt(2)
	v_bfe_u32 v17, v30, 16, 1
	v_lshrrev_b32_e32 v10, 16, v10
	v_add3_u32 v17, v30, v17, s53
	v_and_or_b32 v20, v17, s77, v10
	s_waitcnt lgkmcnt(1)
	v_bfe_u32 v10, v32, 16, 1
	v_add3_u32 v10, v32, v10, s53
	s_waitcnt lgkmcnt(0)
	v_bfe_u32 v17, v34, 16, 1
	v_lshrrev_b32_e32 v10, 16, v10
	v_add3_u32 v17, v34, v17, s53
	v_and_or_b32 v21, v17, s77, v10
	v_or_b32_e32 v10, s2, v12
	s_lshl_b32 s86, s3, 1
	v_lshlrev_b32_e32 v202, 12, v10
	v_bfe_u32 v10, v23, 16, 1
	v_lshl_add_u64 v[8:9], v[6:7], 0, s[86:87]
	v_add3_u32 v10, v23, v10, s53
	v_bfe_u32 v17, v11, 16, 1
	v_lshl_add_u64 v[36:37], v[8:9], 0, v[202:203]
	v_lshrrev_b32_e32 v10, 16, v10
	v_add3_u32 v11, v11, v17, s53
	global_store_dwordx4 v[36:37], v[18:21], off nt
	v_readlane_b32 s17, v251, 7
	v_readlane_b32 s18, v251, 8
	v_and_or_b32 v18, v11, s77, v10
	v_bfe_u32 v10, v25, 16, 1
	v_add3_u32 v10, v25, v10, s53
	v_bfe_u32 v11, v27, 16, 1
	v_lshrrev_b32_e32 v10, 16, v10
	v_add3_u32 v11, v27, v11, s53
	v_and_or_b32 v19, v11, s77, v10
	v_bfe_u32 v10, v29, 16, 1
	v_add3_u32 v10, v29, v10, s53
	v_bfe_u32 v11, v31, 16, 1
	v_lshrrev_b32_e32 v10, 16, v10
	v_add3_u32 v11, v31, v11, s53
	v_and_or_b32 v20, v11, s77, v10
	v_bfe_u32 v10, v33, 16, 1
	v_add3_u32 v10, v33, v10, s53
	v_bfe_u32 v11, v35, 16, 1
	v_lshrrev_b32_e32 v10, 16, v10
	v_add3_u32 v11, v35, v11, s53
	v_and_or_b32 v21, v11, s77, v10
	v_or_b32_e32 v10, s2, v14
	v_lshlrev_b32_e32 v202, 12, v10
	v_lshl_add_u64 v[10:11], v[8:9], 0, v[202:203]
	global_store_dwordx4 v[10:11], v[18:21], off nt
	ds_read2_b32 v[10:11], v13 offset0:49 offset1:57
	ds_read2_b32 v[22:23], v13 offset0:16 offset1:24
	ds_read2_b32 v[24:25], v13 offset0:82 offset1:90
	ds_read2_b32 v[26:27], v13 offset0:115 offset1:123
	ds_read2_b32 v[28:29], v13 offset0:148 offset1:156
	ds_read2_b32 v[30:31], v13 offset0:181 offset1:189
	ds_read2_b32 v[32:33], v13 offset0:214 offset1:222
	ds_read2_b32 v[34:35], v13 offset0:247 offset1:255
	s_waitcnt lgkmcnt(7)
	v_bfe_u32 v18, v10, 16, 1
	s_waitcnt lgkmcnt(6)
	v_bfe_u32 v17, v22, 16, 1
	v_add3_u32 v17, v22, v17, s53
	v_lshrrev_b32_e32 v17, 16, v17
	v_add3_u32 v10, v10, v18, s53
	v_and_or_b32 v18, v10, s77, v17
	s_waitcnt lgkmcnt(5)
	v_bfe_u32 v10, v24, 16, 1
	v_add3_u32 v10, v24, v10, s53
	s_waitcnt lgkmcnt(4)
	v_bfe_u32 v17, v26, 16, 1
	v_lshrrev_b32_e32 v10, 16, v10
	v_add3_u32 v17, v26, v17, s53
	v_and_or_b32 v19, v17, s77, v10
	s_waitcnt lgkmcnt(3)
	v_bfe_u32 v10, v28, 16, 1
	v_add3_u32 v10, v28, v10, s53
	s_waitcnt lgkmcnt(2)
	v_bfe_u32 v17, v30, 16, 1
	v_lshrrev_b32_e32 v10, 16, v10
	v_add3_u32 v17, v30, v17, s53
	v_and_or_b32 v20, v17, s77, v10
	s_waitcnt lgkmcnt(1)
	v_bfe_u32 v10, v32, 16, 1
	v_add3_u32 v10, v32, v10, s53
	s_waitcnt lgkmcnt(0)
	v_bfe_u32 v17, v34, 16, 1
	v_lshrrev_b32_e32 v10, 16, v10
	v_add3_u32 v17, v34, v17, s53
	v_and_or_b32 v21, v17, s77, v10
	v_or_b32_e32 v10, s2, v15
	v_lshlrev_b32_e32 v202, 12, v10
	v_bfe_u32 v10, v23, 16, 1
	v_add3_u32 v10, v23, v10, s53
	v_bfe_u32 v17, v11, 16, 1
	v_lshl_add_u64 v[36:37], v[8:9], 0, v[202:203]
	v_lshrrev_b32_e32 v10, 16, v10
	v_add3_u32 v11, v11, v17, s53
	global_store_dwordx4 v[36:37], v[18:21], off nt
	v_readlane_b32 s19, v251, 9
	s_mov_b64 s[10:11], s[22:23]
	v_and_or_b32 v18, v11, s77, v10
	v_bfe_u32 v10, v25, 16, 1
	v_add3_u32 v10, v25, v10, s53
	v_bfe_u32 v11, v27, 16, 1
	v_lshrrev_b32_e32 v10, 16, v10
	v_add3_u32 v11, v27, v11, s53
	v_and_or_b32 v19, v11, s77, v10
	v_bfe_u32 v10, v29, 16, 1
	v_add3_u32 v10, v29, v10, s53
	v_bfe_u32 v11, v31, 16, 1
	v_lshrrev_b32_e32 v10, 16, v10
	v_add3_u32 v11, v31, v11, s53
	v_and_or_b32 v20, v11, s77, v10
	v_bfe_u32 v10, v33, 16, 1
	v_add3_u32 v10, v33, v10, s53
	v_bfe_u32 v11, v35, 16, 1
	v_lshrrev_b32_e32 v10, 16, v10
	v_add3_u32 v11, v35, v11, s53
	v_and_or_b32 v21, v11, s77, v10
	v_or_b32_e32 v10, s2, v16
	v_lshlrev_b32_e32 v202, 11, v10
	v_lshl_add_u64 v[8:9], v[202:203], 1, v[8:9]
	global_store_dwordx4 v[8:9], v[18:21], off nt
	s_waitcnt lgkmcnt(0)
	s_mov_b64 s[2:3], 0
.LBB0_511:
	s_andn2_b64 vcc, exec, s[2:3]
	s_cbranch_vccnz .LBB0_513
	v_readlane_b32 s16, v251, 30
	s_and_b32 s0, s4, 0x1f800
	v_readlane_b32 s17, v251, 31
	s_add_i32 s86, s0, 0xfffe9800
	v_readlane_b32 s18, v251, 32
	v_readlane_b32 s19, v251, 33
	s_mov_b64 s[8:9], s[16:17]
	s_lshl_b64 s[0:1], s[86:87], 13
	s_mov_b64 s[10:11], s[18:19]
	s_add_u32 s8, s10, s0
	s_addc_u32 s9, s11, s1
	s_lshl_b64 s[0:1], s[86:87], 12
	v_readlane_b32 s2, v251, 52
	s_add_u32 s3, s2, s0
	v_readlane_b32 s0, v251, 53
	s_addc_u32 s5, s0, s1
	s_lshl_b32 s0, s4, 5
	s_and_b32 s2, s0, 0x7e0
	s_and_b32 s7, s4, 0x7c0
	s_lshl_b32 s0, s2, 2
	s_add_u32 s0, s8, s0
	v_or_b32_e32 v10, s7, v3
	s_addc_u32 s1, s9, 0
	v_lshlrev_b32_e32 v202, 2, v2
	v_lshl_add_u64 v[8:9], s[0:1], 0, v[202:203]
	v_lshlrev_b32_e32 v202, 13, v10
	v_lshl_add_u64 v[8:9], v[8:9], 0, v[202:203]
	v_add_co_u32_e32 v10, vcc, s89, v8
	s_mov_b32 s0, 0x8000
	s_nop 0
	v_addc_co_u32_e32 v11, vcc, 0, v9, vcc
	global_load_dword v17, v[8:9], off nt
	global_load_dword v18, v[10:11], off nt
	v_add_co_u32_e32 v10, vcc, s0, v8
	s_mov_b32 s0, 0xc000
	s_nop 0
	v_addc_co_u32_e32 v11, vcc, 0, v9, vcc
	global_load_dword v19, v[10:11], off nt
	v_add_co_u32_e32 v10, vcc, s0, v8
	s_mov_b32 s0, 0x10000
	s_nop 0
	v_addc_co_u32_e32 v11, vcc, 0, v9, vcc
	global_load_dword v20, v[10:11], off nt
	v_add_co_u32_e32 v10, vcc, s0, v8
	s_mov_b32 s0, 0x14000
	s_nop 0
	v_addc_co_u32_e32 v11, vcc, 0, v9, vcc
	global_load_dword v21, v[10:11], off nt
	v_add_co_u32_e32 v10, vcc, s0, v8
	s_mov_b32 s0, 0x18000
	s_nop 0
	v_addc_co_u32_e32 v11, vcc, 0, v9, vcc
	global_load_dword v22, v[10:11], off nt
	v_add_co_u32_e32 v10, vcc, s0, v8
	s_mov_b32 s0, 0x1c000
	s_nop 0
	v_addc_co_u32_e32 v11, vcc, 0, v9, vcc
	global_load_dword v23, v[10:11], off nt
	v_add_co_u32_e32 v10, vcc, s0, v8
	s_mov_b32 s0, 0x20000
	s_nop 0
	v_addc_co_u32_e32 v11, vcc, 0, v9, vcc
	global_load_dword v24, v[10:11], off nt
	v_add_co_u32_e32 v10, vcc, s0, v8
	s_mov_b32 s0, 0x24000
	s_nop 0
	v_addc_co_u32_e32 v11, vcc, 0, v9, vcc
	global_load_dword v25, v[10:11], off nt
	v_add_co_u32_e32 v10, vcc, s0, v8
	s_mov_b32 s0, 0x28000
	s_nop 0
	v_addc_co_u32_e32 v11, vcc, 0, v9, vcc
	global_load_dword v26, v[10:11], off nt
	v_add_co_u32_e32 v10, vcc, s0, v8
	s_mov_b32 s0, 0x2c000
	s_nop 0
	v_addc_co_u32_e32 v11, vcc, 0, v9, vcc
	global_load_dword v27, v[10:11], off nt
	v_add_co_u32_e32 v10, vcc, s0, v8
	s_mov_b32 s0, 0x30000
	s_nop 0
	v_addc_co_u32_e32 v11, vcc, 0, v9, vcc
	global_load_dword v28, v[10:11], off nt
	v_add_co_u32_e32 v10, vcc, s0, v8
	s_mov_b32 s0, 0x34000
	s_nop 0
	v_addc_co_u32_e32 v11, vcc, 0, v9, vcc
	global_load_dword v29, v[10:11], off nt
	v_add_co_u32_e32 v10, vcc, s0, v8
	s_mov_b32 s0, 0x38000
	s_nop 0
	v_addc_co_u32_e32 v11, vcc, 0, v9, vcc
	global_load_dword v30, v[10:11], off nt
	v_add_co_u32_e32 v10, vcc, s0, v8
	s_mov_b32 s0, 0x3c000
	s_nop 0
	v_addc_co_u32_e32 v11, vcc, 0, v9, vcc
	global_load_dword v31, v[10:11], off nt
	v_add_co_u32_e32 v10, vcc, s0, v8
	s_mov_b32 s0, 0x40000
	s_nop 0
	v_addc_co_u32_e32 v11, vcc, 0, v9, vcc
	global_load_dword v32, v[10:11], off nt
	v_add_co_u32_e32 v10, vcc, s0, v8
	s_mov_b32 s0, 0x44000
	s_nop 0
	v_addc_co_u32_e32 v11, vcc, 0, v9, vcc
	global_load_dword v33, v[10:11], off nt
	v_add_co_u32_e32 v10, vcc, s0, v8
	s_mov_b32 s0, 0x48000
	s_nop 0
	v_addc_co_u32_e32 v11, vcc, 0, v9, vcc
	global_load_dword v34, v[10:11], off nt
	v_add_co_u32_e32 v10, vcc, s0, v8
	s_mov_b32 s0, 0x4c000
	s_nop 0
	v_addc_co_u32_e32 v11, vcc, 0, v9, vcc
	global_load_dword v35, v[10:11], off nt
	v_add_co_u32_e32 v10, vcc, s0, v8
	s_mov_b32 s0, 0x50000
	s_nop 0
	v_addc_co_u32_e32 v11, vcc, 0, v9, vcc
	global_load_dword v36, v[10:11], off nt
	v_add_co_u32_e32 v10, vcc, s0, v8
	s_mov_b32 s0, 0x54000
	s_nop 0
	v_addc_co_u32_e32 v11, vcc, 0, v9, vcc
	global_load_dword v37, v[10:11], off nt
	v_add_co_u32_e32 v10, vcc, s0, v8
	s_mov_b32 s0, 0x58000
	s_nop 0
	v_addc_co_u32_e32 v11, vcc, 0, v9, vcc
	global_load_dword v38, v[10:11], off nt
	v_add_co_u32_e32 v10, vcc, s0, v8
	s_mov_b32 s0, 0x5c000
	s_nop 0
	v_addc_co_u32_e32 v11, vcc, 0, v9, vcc
	global_load_dword v39, v[10:11], off nt
	v_add_co_u32_e32 v10, vcc, s0, v8
	s_mov_b32 s0, 0x60000
	s_nop 0
	v_addc_co_u32_e32 v11, vcc, 0, v9, vcc
	global_load_dword v40, v[10:11], off nt
	v_add_co_u32_e32 v10, vcc, s0, v8
	s_mov_b32 s0, 0x64000
	s_nop 0
	v_addc_co_u32_e32 v11, vcc, 0, v9, vcc
	global_load_dword v41, v[10:11], off nt
	v_add_co_u32_e32 v10, vcc, s0, v8
	s_mov_b32 s0, 0x68000
	s_nop 0
	v_addc_co_u32_e32 v11, vcc, 0, v9, vcc
	global_load_dword v42, v[10:11], off nt
	v_add_co_u32_e32 v10, vcc, s0, v8
	s_mov_b32 s0, 0x6c000
	s_nop 0
	v_addc_co_u32_e32 v11, vcc, 0, v9, vcc
	global_load_dword v43, v[10:11], off nt
	v_add_co_u32_e32 v10, vcc, s0, v8
	s_mov_b32 s0, 0x70000
	s_nop 0
	v_addc_co_u32_e32 v11, vcc, 0, v9, vcc
	global_load_dword v44, v[10:11], off nt
	v_add_co_u32_e32 v10, vcc, s0, v8
	s_mov_b32 s0, 0x74000
	s_nop 0
	v_addc_co_u32_e32 v11, vcc, 0, v9, vcc
	global_load_dword v45, v[10:11], off nt
	v_add_co_u32_e32 v10, vcc, s0, v8
	s_mov_b32 s0, 0x78000
	s_nop 0
	v_addc_co_u32_e32 v11, vcc, 0, v9, vcc
	global_load_dword v46, v[10:11], off nt
	v_add_co_u32_e32 v10, vcc, s0, v8
	s_mov_b32 s0, 0x7c000
	s_nop 0
	v_addc_co_u32_e32 v11, vcc, 0, v9, vcc
	v_add_co_u32_e32 v8, vcc, s0, v8
	global_load_dword v10, v[10:11], off nt
	s_nop 0
	v_addc_co_u32_e32 v9, vcc, 0, v9, vcc
	global_load_dword v8, v[8:9], off nt
	v_add_u32_e32 v9, 0x400, v5
	s_waitcnt vmcnt(0)
	ds_write2_b32 v5, v17, v18 offset1:66
	ds_write2_b32 v5, v19, v20 offset0:132 offset1:198
	ds_write2_b32 v9, v21, v22 offset0:8 offset1:74
	ds_write2_b32 v9, v23, v24 offset0:140 offset1:206
	v_add_u32_e32 v9, 0x800, v5
	ds_write2_b32 v9, v25, v26 offset0:16 offset1:82
	ds_write2_b32 v9, v27, v28 offset0:148 offset1:214
	v_add_u32_e32 v9, 0xc00, v5
	ds_write2_b32 v9, v29, v30 offset0:24 offset1:90
	ds_write2_b32 v9, v31, v32 offset0:156 offset1:222
	v_add_u32_e32 v9, 0x1000, v5
	ds_write2_b32 v9, v33, v34 offset0:32 offset1:98
	ds_write2_b32 v9, v35, v36 offset0:164 offset1:230
	v_add_u32_e32 v9, 0x1400, v5
	ds_write2_b32 v9, v37, v38 offset0:40 offset1:106
	ds_write2_b32 v9, v39, v40 offset0:172 offset1:238
	v_add_u32_e32 v9, 0x1800, v5
	ds_write2_b32 v9, v41, v42 offset0:48 offset1:114
	ds_write2_b32 v9, v43, v44 offset0:180 offset1:246
	v_add_u32_e32 v9, 0x1c00, v5
	ds_write2_b32 v9, v45, v46 offset0:56 offset1:122
	ds_write2_b32 v9, v10, v8 offset0:188 offset1:254
	s_waitcnt lgkmcnt(0)
	ds_read2_b32 v[10:11], v13 offset0:33 offset1:41
	ds_read2_b32 v[22:23], v13 offset1:8
	ds_read2_b32 v[24:25], v13 offset0:66 offset1:74
	ds_read2_b32 v[26:27], v13 offset0:99 offset1:107
	ds_read2_b32 v[28:29], v13 offset0:132 offset1:140
	ds_read2_b32 v[30:31], v13 offset0:165 offset1:173
	ds_read2_b32 v[32:33], v13 offset0:198 offset1:206
	ds_read2_b32 v[34:35], v13 offset0:231 offset1:239
	s_waitcnt lgkmcnt(7)
	v_bfe_u32 v18, v10, 16, 1
	s_waitcnt lgkmcnt(6)
	v_bfe_u32 v17, v22, 16, 1
	v_add3_u32 v17, v22, v17, s53
	v_lshrrev_b32_e32 v17, 16, v17
	v_add3_u32 v10, v10, v18, s53
	v_and_or_b32 v18, v10, s77, v17
	s_waitcnt lgkmcnt(5)
	v_bfe_u32 v10, v24, 16, 1
	v_add3_u32 v10, v24, v10, s53
	s_waitcnt lgkmcnt(4)
	v_bfe_u32 v17, v26, 16, 1
	v_lshrrev_b32_e32 v10, 16, v10
	v_add3_u32 v17, v26, v17, s53
	v_and_or_b32 v19, v17, s77, v10
	s_waitcnt lgkmcnt(3)
	v_bfe_u32 v10, v28, 16, 1
	v_add3_u32 v10, v28, v10, s53
	s_waitcnt lgkmcnt(2)
	v_bfe_u32 v17, v30, 16, 1
	v_lshrrev_b32_e32 v10, 16, v10
	v_add3_u32 v17, v30, v17, s53
	v_and_or_b32 v20, v17, s77, v10
	s_waitcnt lgkmcnt(1)
	v_bfe_u32 v10, v32, 16, 1
	s_lshl_b32 s0, s7, 1
	v_add3_u32 v10, v32, v10, s53
	s_waitcnt lgkmcnt(0)
	v_bfe_u32 v17, v34, 16, 1
	s_add_u32 s0, s3, s0
	v_lshrrev_b32_e32 v10, 16, v10
	v_add3_u32 v17, v34, v17, s53
	s_addc_u32 s1, s5, 0
	v_lshlrev_b32_e32 v202, 1, v4
	v_and_or_b32 v21, v17, s77, v10
	v_or_b32_e32 v10, s2, v12
	v_lshl_add_u64 v[8:9], s[0:1], 0, v[202:203]
	v_lshlrev_b32_e32 v202, 12, v10
	v_bfe_u32 v10, v23, 16, 1
	v_add3_u32 v10, v23, v10, s53
	v_bfe_u32 v17, v11, 16, 1
	v_lshl_add_u64 v[36:37], v[8:9], 0, v[202:203]
	v_lshrrev_b32_e32 v10, 16, v10
	v_add3_u32 v11, v11, v17, s53
	global_store_dwordx4 v[36:37], v[18:21], off nt
	v_readlane_b32 s20, v251, 34
	v_readlane_b32 s21, v251, 35
	v_and_or_b32 v18, v11, s77, v10
	v_bfe_u32 v10, v25, 16, 1
	v_add3_u32 v10, v25, v10, s53
	v_bfe_u32 v11, v27, 16, 1
	v_lshrrev_b32_e32 v10, 16, v10
	v_add3_u32 v11, v27, v11, s53
	v_and_or_b32 v19, v11, s77, v10
	v_bfe_u32 v10, v29, 16, 1
	v_add3_u32 v10, v29, v10, s53
	v_bfe_u32 v11, v31, 16, 1
	v_lshrrev_b32_e32 v10, 16, v10
	v_add3_u32 v11, v31, v11, s53
	v_and_or_b32 v20, v11, s77, v10
	v_bfe_u32 v10, v33, 16, 1
	v_add3_u32 v10, v33, v10, s53
	v_bfe_u32 v11, v35, 16, 1
	v_lshrrev_b32_e32 v10, 16, v10
	v_add3_u32 v11, v35, v11, s53
	v_and_or_b32 v21, v11, s77, v10
	v_or_b32_e32 v10, s2, v14
	v_lshlrev_b32_e32 v202, 12, v10
	v_lshl_add_u64 v[10:11], v[8:9], 0, v[202:203]
	global_store_dwordx4 v[10:11], v[18:21], off nt
	ds_read2_b32 v[10:11], v13 offset0:49 offset1:57
	ds_read2_b32 v[22:23], v13 offset0:16 offset1:24
	ds_read2_b32 v[24:25], v13 offset0:82 offset1:90
	ds_read2_b32 v[26:27], v13 offset0:115 offset1:123
	ds_read2_b32 v[28:29], v13 offset0:148 offset1:156
	ds_read2_b32 v[30:31], v13 offset0:181 offset1:189
	ds_read2_b32 v[32:33], v13 offset0:214 offset1:222
	ds_read2_b32 v[34:35], v13 offset0:247 offset1:255
	s_waitcnt lgkmcnt(7)
	v_bfe_u32 v18, v10, 16, 1
	s_waitcnt lgkmcnt(6)
	v_bfe_u32 v17, v22, 16, 1
	v_add3_u32 v17, v22, v17, s53
	v_lshrrev_b32_e32 v17, 16, v17
	v_add3_u32 v10, v10, v18, s53
	v_and_or_b32 v18, v10, s77, v17
	s_waitcnt lgkmcnt(5)
	v_bfe_u32 v10, v24, 16, 1
	v_add3_u32 v10, v24, v10, s53
	s_waitcnt lgkmcnt(4)
	v_bfe_u32 v17, v26, 16, 1
	v_lshrrev_b32_e32 v10, 16, v10
	v_add3_u32 v17, v26, v17, s53
	v_and_or_b32 v19, v17, s77, v10
	s_waitcnt lgkmcnt(3)
	v_bfe_u32 v10, v28, 16, 1
	v_add3_u32 v10, v28, v10, s53
	s_waitcnt lgkmcnt(2)
	v_bfe_u32 v17, v30, 16, 1
	v_lshrrev_b32_e32 v10, 16, v10
	v_add3_u32 v17, v30, v17, s53
	v_and_or_b32 v20, v17, s77, v10
	s_waitcnt lgkmcnt(1)
	v_bfe_u32 v10, v32, 16, 1
	v_add3_u32 v10, v32, v10, s53
	s_waitcnt lgkmcnt(0)
	v_bfe_u32 v17, v34, 16, 1
	v_lshrrev_b32_e32 v10, 16, v10
	v_add3_u32 v17, v34, v17, s53
	v_and_or_b32 v21, v17, s77, v10
	v_or_b32_e32 v10, s2, v15
	v_lshlrev_b32_e32 v202, 12, v10
	v_bfe_u32 v10, v23, 16, 1
	v_add3_u32 v10, v23, v10, s53
	v_bfe_u32 v17, v11, 16, 1
	v_lshl_add_u64 v[36:37], v[8:9], 0, v[202:203]
	v_lshrrev_b32_e32 v10, 16, v10
	v_add3_u32 v11, v11, v17, s53
	global_store_dwordx4 v[36:37], v[18:21], off nt
	v_readlane_b32 s22, v251, 36
	v_readlane_b32 s23, v251, 37
	v_and_or_b32 v18, v11, s77, v10
	v_bfe_u32 v10, v25, 16, 1
	v_add3_u32 v10, v25, v10, s53
	v_bfe_u32 v11, v27, 16, 1
	v_lshrrev_b32_e32 v10, 16, v10
	v_add3_u32 v11, v27, v11, s53
	v_and_or_b32 v19, v11, s77, v10
	v_bfe_u32 v10, v29, 16, 1
	v_add3_u32 v10, v29, v10, s53
	v_bfe_u32 v11, v31, 16, 1
	v_lshrrev_b32_e32 v10, 16, v10
	v_add3_u32 v11, v31, v11, s53
	v_and_or_b32 v20, v11, s77, v10
	v_bfe_u32 v10, v33, 16, 1
	v_add3_u32 v10, v33, v10, s53
	v_bfe_u32 v11, v35, 16, 1
	v_lshrrev_b32_e32 v10, 16, v10
	v_add3_u32 v11, v35, v11, s53
	v_and_or_b32 v21, v11, s77, v10
	v_or_b32_e32 v10, s2, v16
	v_lshlrev_b32_e32 v202, 12, v10
	v_lshl_add_u64 v[8:9], v[8:9], 0, v[202:203]
	global_store_dwordx4 v[8:9], v[18:21], off nt
	s_waitcnt lgkmcnt(0)
	v_readlane_b32 s24, v251, 38
	v_readlane_b32 s25, v251, 39
	v_readlane_b32 s26, v251, 40
	v_readlane_b32 s27, v251, 41
	v_readlane_b32 s28, v251, 42
	v_readlane_b32 s29, v251, 43
	v_readlane_b32 s30, v251, 44
	v_readlane_b32 s31, v251, 45

.LBB0_514:
	s_andn2_b64 vcc, exec, s[2:3]
	s_cbranch_vccnz .LBB0_523
	s_add_i32 s1, s4, 0xffffa000
	s_mul_hi_u32 s0, s1, 0x3e0f83e1
	s_lshr_b32 s0, s0, 12
	s_mul_i32 s2, s0, 0x4200
	s_sub_i32 s1, s1, s2
	s_mul_i32 s2, s1, 0xba2f
	s_lshr_b32 s2, s2, 28
	s_mulk_i32 s2, 0x1600
	s_sub_i32 s5, s1, s2
	s_cmpk_gt_u32 s1, 0x15ff
	s_mul_hi_u32 s7, s0, 0x2c00000
	s_mul_i32 s8, s0, 0x2c00000
	s_mov_b64 s[2:3], -1
	s_cbranch_scc0 .LBB0_521
	s_addk_i32 s1, 0xea00
	s_cmpk_gt_u32 s1, 0x15ff
	s_cbranch_scc0 .LBB0_518
	v_readlane_b32 s16, v251, 14
	v_readlane_b32 s20, v251, 18
	v_readlane_b32 s21, v251, 19
	s_add_u32 s1, s20, s8
	s_addc_u32 s11, s21, s7
	s_mul_hi_u32 s2, s0, 0x1600000
	s_mul_i32 s0, s0, 0x1600000
	v_readlane_b32 s3, v251, 54
	s_add_u32 s3, s3, s0
	v_readlane_b32 s0, v251, 55
	s_addc_u32 s9, s0, s2
	s_lshl_b32 s0, s5, 5
	s_and_b32 s2, s0, 0x7e0
	s_and_b32 s10, s5, 0x1fc0
	s_lshl_b32 s0, s2, 2
	s_add_u32 s0, s1, s0
	v_or_b32_e32 v10, s10, v3
	s_addc_u32 s1, s11, 0
	v_lshlrev_b32_e32 v202, 2, v2
	v_lshl_add_u64 v[8:9], s[0:1], 0, v[202:203]
	v_lshlrev_b32_e32 v202, 13, v10
	v_lshl_add_u64 v[8:9], v[8:9], 0, v[202:203]
	v_add_co_u32_e32 v10, vcc, s89, v8
	s_mov_b32 s0, 0x8000
	s_nop 0
	v_addc_co_u32_e32 v11, vcc, 0, v9, vcc
	global_load_dword v17, v[8:9], off nt
	global_load_dword v18, v[10:11], off nt
	v_add_co_u32_e32 v10, vcc, s0, v8
	s_mov_b32 s0, 0xc000
	s_nop 0
	v_addc_co_u32_e32 v11, vcc, 0, v9, vcc
	global_load_dword v19, v[10:11], off nt
	v_add_co_u32_e32 v10, vcc, s0, v8
	s_mov_b32 s0, 0x10000
	s_nop 0
	v_addc_co_u32_e32 v11, vcc, 0, v9, vcc
	global_load_dword v20, v[10:11], off nt
	v_add_co_u32_e32 v10, vcc, s0, v8
	s_mov_b32 s0, 0x14000
	s_nop 0
	v_addc_co_u32_e32 v11, vcc, 0, v9, vcc
	global_load_dword v21, v[10:11], off nt
	v_add_co_u32_e32 v10, vcc, s0, v8
	s_mov_b32 s0, 0x18000
	s_nop 0
	v_addc_co_u32_e32 v11, vcc, 0, v9, vcc
	global_load_dword v22, v[10:11], off nt
	v_add_co_u32_e32 v10, vcc, s0, v8
	s_mov_b32 s0, 0x1c000
	s_nop 0
	v_addc_co_u32_e32 v11, vcc, 0, v9, vcc
	global_load_dword v23, v[10:11], off nt
	v_add_co_u32_e32 v10, vcc, s0, v8
	s_mov_b32 s0, 0x20000
	s_nop 0
	v_addc_co_u32_e32 v11, vcc, 0, v9, vcc
	global_load_dword v24, v[10:11], off nt
	v_add_co_u32_e32 v10, vcc, s0, v8
	s_mov_b32 s0, 0x24000
	s_nop 0
	v_addc_co_u32_e32 v11, vcc, 0, v9, vcc
	global_load_dword v25, v[10:11], off nt
	v_add_co_u32_e32 v10, vcc, s0, v8
	s_mov_b32 s0, 0x28000
	s_nop 0
	v_addc_co_u32_e32 v11, vcc, 0, v9, vcc
	global_load_dword v26, v[10:11], off nt
	v_add_co_u32_e32 v10, vcc, s0, v8
	s_mov_b32 s0, 0x2c000
	s_nop 0
	v_addc_co_u32_e32 v11, vcc, 0, v9, vcc
	global_load_dword v27, v[10:11], off nt
	v_add_co_u32_e32 v10, vcc, s0, v8
	s_mov_b32 s0, 0x30000
	s_nop 0
	v_addc_co_u32_e32 v11, vcc, 0, v9, vcc
	global_load_dword v28, v[10:11], off nt
	v_add_co_u32_e32 v10, vcc, s0, v8
	s_mov_b32 s0, 0x34000
	s_nop 0
	v_addc_co_u32_e32 v11, vcc, 0, v9, vcc
	global_load_dword v29, v[10:11], off nt
	v_add_co_u32_e32 v10, vcc, s0, v8
	s_mov_b32 s0, 0x38000
	s_nop 0
	v_addc_co_u32_e32 v11, vcc, 0, v9, vcc
	global_load_dword v30, v[10:11], off nt
	v_add_co_u32_e32 v10, vcc, s0, v8
	s_mov_b32 s0, 0x3c000
	s_nop 0
	v_addc_co_u32_e32 v11, vcc, 0, v9, vcc
	global_load_dword v31, v[10:11], off nt
	v_add_co_u32_e32 v10, vcc, s0, v8
	s_mov_b32 s0, 0x40000
	s_nop 0
	v_addc_co_u32_e32 v11, vcc, 0, v9, vcc
	global_load_dword v32, v[10:11], off nt
	v_add_co_u32_e32 v10, vcc, s0, v8
	s_mov_b32 s0, 0x44000
	s_nop 0
	v_addc_co_u32_e32 v11, vcc, 0, v9, vcc
	global_load_dword v33, v[10:11], off nt
	v_add_co_u32_e32 v10, vcc, s0, v8
	s_mov_b32 s0, 0x48000
	s_nop 0
	v_addc_co_u32_e32 v11, vcc, 0, v9, vcc
	global_load_dword v34, v[10:11], off nt
	v_add_co_u32_e32 v10, vcc, s0, v8
	s_mov_b32 s0, 0x4c000
	s_nop 0
	v_addc_co_u32_e32 v11, vcc, 0, v9, vcc
	global_load_dword v35, v[10:11], off nt
	v_add_co_u32_e32 v10, vcc, s0, v8
	s_mov_b32 s0, 0x50000
	s_nop 0
	v_addc_co_u32_e32 v11, vcc, 0, v9, vcc
	global_load_dword v36, v[10:11], off nt
	v_add_co_u32_e32 v10, vcc, s0, v8
	s_mov_b32 s0, 0x54000
	s_nop 0
	v_addc_co_u32_e32 v11, vcc, 0, v9, vcc
	global_load_dword v37, v[10:11], off nt
	v_add_co_u32_e32 v10, vcc, s0, v8
	s_mov_b32 s0, 0x58000
	s_nop 0
	v_addc_co_u32_e32 v11, vcc, 0, v9, vcc
	global_load_dword v38, v[10:11], off nt
	v_add_co_u32_e32 v10, vcc, s0, v8
	s_mov_b32 s0, 0x5c000
	s_nop 0
	v_addc_co_u32_e32 v11, vcc, 0, v9, vcc
	global_load_dword v39, v[10:11], off nt
	v_add_co_u32_e32 v10, vcc, s0, v8
	s_mov_b32 s0, 0x60000
	s_nop 0
	v_addc_co_u32_e32 v11, vcc, 0, v9, vcc
	global_load_dword v40, v[10:11], off nt
	v_add_co_u32_e32 v10, vcc, s0, v8
	s_mov_b32 s0, 0x64000
	s_nop 0
	v_addc_co_u32_e32 v11, vcc, 0, v9, vcc
	global_load_dword v41, v[10:11], off nt
	v_add_co_u32_e32 v10, vcc, s0, v8
	s_mov_b32 s0, 0x68000
	s_nop 0
	v_addc_co_u32_e32 v11, vcc, 0, v9, vcc
	global_load_dword v42, v[10:11], off nt
	v_add_co_u32_e32 v10, vcc, s0, v8
	s_mov_b32 s0, 0x6c000
	s_nop 0
	v_addc_co_u32_e32 v11, vcc, 0, v9, vcc
	global_load_dword v43, v[10:11], off nt
	v_add_co_u32_e32 v10, vcc, s0, v8
	s_mov_b32 s0, 0x70000
	s_nop 0
	v_addc_co_u32_e32 v11, vcc, 0, v9, vcc
	global_load_dword v44, v[10:11], off nt
	v_add_co_u32_e32 v10, vcc, s0, v8
	s_mov_b32 s0, 0x74000
	s_nop 0
	v_addc_co_u32_e32 v11, vcc, 0, v9, vcc
	global_load_dword v45, v[10:11], off nt
	v_add_co_u32_e32 v10, vcc, s0, v8
	s_mov_b32 s0, 0x78000
	s_nop 0
	v_addc_co_u32_e32 v11, vcc, 0, v9, vcc
	global_load_dword v46, v[10:11], off nt
	v_add_co_u32_e32 v10, vcc, s0, v8
	s_mov_b32 s0, 0x7c000
	s_nop 0
	v_addc_co_u32_e32 v11, vcc, 0, v9, vcc
	v_add_co_u32_e32 v8, vcc, s0, v8
	global_load_dword v10, v[10:11], off nt
	s_nop 0
	v_addc_co_u32_e32 v9, vcc, 0, v9, vcc
	global_load_dword v8, v[8:9], off nt
	v_add_u32_e32 v9, 0x400, v5
	s_waitcnt vmcnt(0)
	ds_write2_b32 v5, v17, v18 offset1:66
	ds_write2_b32 v5, v19, v20 offset0:132 offset1:198
	ds_write2_b32 v9, v21, v22 offset0:8 offset1:74
	ds_write2_b32 v9, v23, v24 offset0:140 offset1:206
	v_add_u32_e32 v9, 0x800, v5
	ds_write2_b32 v9, v25, v26 offset0:16 offset1:82
	ds_write2_b32 v9, v27, v28 offset0:148 offset1:214
	v_add_u32_e32 v9, 0xc00, v5
	ds_write2_b32 v9, v29, v30 offset0:24 offset1:90
	ds_write2_b32 v9, v31, v32 offset0:156 offset1:222
	v_add_u32_e32 v9, 0x1000, v5
	ds_write2_b32 v9, v33, v34 offset0:32 offset1:98
	ds_write2_b32 v9, v35, v36 offset0:164 offset1:230
	v_add_u32_e32 v9, 0x1400, v5
	ds_write2_b32 v9, v37, v38 offset0:40 offset1:106
	ds_write2_b32 v9, v39, v40 offset0:172 offset1:238
	v_add_u32_e32 v9, 0x1800, v5
	ds_write2_b32 v9, v41, v42 offset0:48 offset1:114
	ds_write2_b32 v9, v43, v44 offset0:180 offset1:246
	v_add_u32_e32 v9, 0x1c00, v5
	ds_write2_b32 v9, v45, v46 offset0:56 offset1:122
	ds_write2_b32 v9, v10, v8 offset0:188 offset1:254
	s_waitcnt lgkmcnt(0)
	ds_read2_b32 v[10:11], v13 offset0:33 offset1:41
	ds_read2_b32 v[22:23], v13 offset1:8
	ds_read2_b32 v[24:25], v13 offset0:66 offset1:74
	ds_read2_b32 v[26:27], v13 offset0:99 offset1:107
	ds_read2_b32 v[28:29], v13 offset0:132 offset1:140
	ds_read2_b32 v[30:31], v13 offset0:165 offset1:173
	ds_read2_b32 v[32:33], v13 offset0:198 offset1:206
	ds_read2_b32 v[34:35], v13 offset0:231 offset1:239
	s_waitcnt lgkmcnt(7)
	v_bfe_u32 v18, v10, 16, 1
	s_waitcnt lgkmcnt(6)
	v_bfe_u32 v17, v22, 16, 1
	v_add3_u32 v17, v22, v17, s53
	v_lshrrev_b32_e32 v17, 16, v17
	v_add3_u32 v10, v10, v18, s53
	v_and_or_b32 v18, v10, s77, v17
	s_waitcnt lgkmcnt(5)
	v_bfe_u32 v10, v24, 16, 1
	v_add3_u32 v10, v24, v10, s53
	s_waitcnt lgkmcnt(4)
	v_bfe_u32 v17, v26, 16, 1
	v_lshrrev_b32_e32 v10, 16, v10
	v_add3_u32 v17, v26, v17, s53
	v_and_or_b32 v19, v17, s77, v10
	s_waitcnt lgkmcnt(3)
	v_bfe_u32 v10, v28, 16, 1
	v_add3_u32 v10, v28, v10, s53
	s_waitcnt lgkmcnt(2)
	v_bfe_u32 v17, v30, 16, 1
	v_lshrrev_b32_e32 v10, 16, v10
	v_add3_u32 v17, v30, v17, s53
	v_and_or_b32 v20, v17, s77, v10
	s_waitcnt lgkmcnt(1)
	v_bfe_u32 v10, v32, 16, 1
	v_add3_u32 v10, v32, v10, s53
	s_waitcnt lgkmcnt(0)
	v_bfe_u32 v17, v34, 16, 1
	s_lshl_b32 s0, s10, 1
	v_lshrrev_b32_e32 v10, 16, v10
	v_add3_u32 v17, v34, v17, s53
	s_add_u32 s0, s3, s0
	v_and_or_b32 v21, v17, s77, v10
	v_or_b32_e32 v10, s2, v12
	s_addc_u32 s1, s9, 0
	v_lshlrev_b32_e32 v202, 1, v4
	v_mul_u32_u24_e32 v10, 0x1600, v10
	v_lshl_add_u64 v[8:9], s[0:1], 0, v[202:203]
	v_lshlrev_b32_e32 v202, 1, v10
	v_bfe_u32 v10, v23, 16, 1
	v_add3_u32 v10, v23, v10, s53
	v_bfe_u32 v17, v11, 16, 1
	v_lshl_add_u64 v[36:37], v[8:9], 0, v[202:203]
	v_lshrrev_b32_e32 v10, 16, v10
	v_add3_u32 v11, v11, v17, s53
	global_store_dwordx4 v[36:37], v[18:21], off nt
	v_readlane_b32 s17, v251, 15
	v_readlane_b32 s18, v251, 16
	v_and_or_b32 v18, v11, s77, v10
	v_bfe_u32 v10, v25, 16, 1
	v_add3_u32 v10, v25, v10, s53
	v_bfe_u32 v11, v27, 16, 1
	v_lshrrev_b32_e32 v10, 16, v10
	v_add3_u32 v11, v27, v11, s53
	v_and_or_b32 v19, v11, s77, v10
	v_bfe_u32 v10, v29, 16, 1
	v_add3_u32 v10, v29, v10, s53
	v_bfe_u32 v11, v31, 16, 1
	v_lshrrev_b32_e32 v10, 16, v10
	v_add3_u32 v11, v31, v11, s53
	v_and_or_b32 v20, v11, s77, v10
	v_bfe_u32 v10, v33, 16, 1
	v_add3_u32 v10, v33, v10, s53
	v_bfe_u32 v11, v35, 16, 1
	v_lshrrev_b32_e32 v10, 16, v10
	v_add3_u32 v11, v35, v11, s53
	v_and_or_b32 v21, v11, s77, v10
	v_or_b32_e32 v10, s2, v14
	v_mul_u32_u24_e32 v10, 0x1600, v10
	v_lshlrev_b32_e32 v202, 1, v10
	v_lshl_add_u64 v[10:11], v[8:9], 0, v[202:203]
	global_store_dwordx4 v[10:11], v[18:21], off nt
	ds_read2_b32 v[10:11], v13 offset0:16 offset1:24
	ds_read2_b32 v[22:23], v13 offset0:49 offset1:57
	ds_read2_b32 v[24:25], v13 offset0:82 offset1:90
	ds_read2_b32 v[26:27], v13 offset0:115 offset1:123
	ds_read2_b32 v[28:29], v13 offset0:148 offset1:156
	ds_read2_b32 v[30:31], v13 offset0:181 offset1:189
	ds_read2_b32 v[32:33], v13 offset0:214 offset1:222
	ds_read2_b32 v[34:35], v13 offset0:247 offset1:255
	s_waitcnt lgkmcnt(7)
	v_bfe_u32 v17, v10, 16, 1
	v_add3_u32 v10, v10, v17, s53
	s_waitcnt lgkmcnt(6)
	v_bfe_u32 v17, v22, 16, 1
	v_lshrrev_b32_e32 v10, 16, v10
	v_add3_u32 v17, v22, v17, s53
	v_and_or_b32 v18, v17, s77, v10
	s_waitcnt lgkmcnt(5)
	v_bfe_u32 v10, v24, 16, 1
	v_add3_u32 v10, v24, v10, s53
	s_waitcnt lgkmcnt(4)
	v_bfe_u32 v17, v26, 16, 1
	v_lshrrev_b32_e32 v10, 16, v10
	v_add3_u32 v17, v26, v17, s53
	v_and_or_b32 v19, v17, s77, v10
	s_waitcnt lgkmcnt(3)
	v_bfe_u32 v10, v28, 16, 1
	v_add3_u32 v10, v28, v10, s53
	s_waitcnt lgkmcnt(2)
	v_bfe_u32 v17, v30, 16, 1
	v_lshrrev_b32_e32 v10, 16, v10
	v_add3_u32 v17, v30, v17, s53
	v_and_or_b32 v20, v17, s77, v10
	s_waitcnt lgkmcnt(1)
	v_bfe_u32 v10, v32, 16, 1
	v_add3_u32 v10, v32, v10, s53
	s_waitcnt lgkmcnt(0)
	v_bfe_u32 v17, v34, 16, 1
	v_lshrrev_b32_e32 v10, 16, v10
	v_add3_u32 v17, v34, v17, s53
	v_and_or_b32 v21, v17, s77, v10
	v_or_b32_e32 v10, s2, v15
	v_mul_u32_u24_e32 v10, 0x1600, v10
	v_lshlrev_b32_e32 v202, 1, v10
	v_bfe_u32 v10, v11, 16, 1
	v_add3_u32 v10, v11, v10, s53
	v_bfe_u32 v11, v23, 16, 1
	v_lshl_add_u64 v[36:37], v[8:9], 0, v[202:203]
	v_lshrrev_b32_e32 v10, 16, v10
	v_add3_u32 v11, v23, v11, s53
	global_store_dwordx4 v[36:37], v[18:21], off nt
	v_readlane_b32 s19, v251, 17
	v_readlane_b32 s22, v251, 20
	v_and_or_b32 v18, v11, s77, v10
	v_bfe_u32 v10, v25, 16, 1
	v_add3_u32 v10, v25, v10, s53
	v_bfe_u32 v11, v27, 16, 1
	v_lshrrev_b32_e32 v10, 16, v10
	v_add3_u32 v11, v27, v11, s53
	v_and_or_b32 v19, v11, s77, v10
	v_bfe_u32 v10, v29, 16, 1
	v_add3_u32 v10, v29, v10, s53
	v_bfe_u32 v11, v31, 16, 1
	v_lshrrev_b32_e32 v10, 16, v10
	v_add3_u32 v11, v31, v11, s53
	v_and_or_b32 v20, v11, s77, v10
	v_bfe_u32 v10, v33, 16, 1
	v_add3_u32 v10, v33, v10, s53
	v_bfe_u32 v11, v35, 16, 1
	v_lshrrev_b32_e32 v10, 16, v10
	v_add3_u32 v11, v35, v11, s53
	v_and_or_b32 v21, v11, s77, v10
	v_or_b32_e32 v10, s2, v16
	v_mul_u32_u24_e32 v10, 0x1600, v10
	v_lshlrev_b32_e32 v202, 1, v10
	v_lshl_add_u64 v[8:9], v[8:9], 0, v[202:203]
	global_store_dwordx4 v[8:9], v[18:21], off nt
	s_waitcnt lgkmcnt(0)
	v_readlane_b32 s23, v251, 21
	v_readlane_b32 s24, v251, 22
	v_readlane_b32 s25, v251, 23
	v_readlane_b32 s26, v251, 24
	v_readlane_b32 s27, v251, 25
	v_readlane_b32 s28, v251, 26
	v_readlane_b32 s29, v251, 27
	v_readlane_b32 s30, v251, 28
	v_readlane_b32 s31, v251, 29
	s_mov_b64 s[2:3], 0
.LBB0_518:
	s_andn2_b64 vcc, exec, s[2:3]
	s_cbranch_vccnz .LBB0_520
	v_readlane_b32 s16, v251, 14
	v_readlane_b32 s18, v251, 16
	v_readlane_b32 s19, v251, 17
	s_add_u32 s0, s18, s8
	s_addc_u32 s1, s19, s7
	v_readlane_b32 s2, v251, 56
	s_add_u32 s3, s2, s8
	v_readlane_b32 s2, v251, 57
	s_addc_u32 s9, s2, s7
	s_and_b32 s2, 0xffff, s5
	s_mul_i32 s2, s2, 0xba2f
	s_lshr_b32 s10, s2, 23
	s_mul_i32 s2, s10, 0xb0
	s_sub_i32 s2, s5, s2
	s_and_b32 s11, s2, 0xffff
	s_lshl_b32 s2, s11, 5
	s_lshl_b32 s14, s11, 6
	s_and_b32 s14, s14, 0x3f00
	s_and_b32 s2, s2, 0x60
	s_or_b32 s2, s14, s2
	s_bitset1_b32 s2, 7
	s_lshl_b32 s11, s11, 7
	v_lshl_or_b32 v10, s10, 6, v3
	s_add_u32 s0, s0, s11
	s_addc_u32 s1, s1, 0
	v_lshlrev_b32_e32 v202, 2, v2
	v_mul_u32_u24_e32 v10, 0x1600, v10
	v_lshl_add_u64 v[8:9], s[0:1], 0, v[202:203]
	v_lshlrev_b32_e32 v202, 2, v10
	v_lshl_add_u64 v[8:9], v[8:9], 0, v[202:203]
	s_mov_b32 s0, 0xb000
	v_add_co_u32_e32 v10, vcc, s0, v8
	s_mov_b32 s0, 0x16000
	s_nop 0
	v_addc_co_u32_e32 v11, vcc, 0, v9, vcc
	global_load_dword v17, v[8:9], off nt
	global_load_dword v18, v[10:11], off nt
	v_add_co_u32_e32 v10, vcc, s0, v8
	s_mov_b32 s0, 0x21000
	s_nop 0
	v_addc_co_u32_e32 v11, vcc, 0, v9, vcc
	global_load_dword v19, v[10:11], off nt
	v_add_co_u32_e32 v10, vcc, s0, v8
	s_mov_b32 s0, 0x2c000
	s_nop 0
	v_addc_co_u32_e32 v11, vcc, 0, v9, vcc
	global_load_dword v20, v[10:11], off nt
	v_add_co_u32_e32 v10, vcc, s0, v8
	s_mov_b32 s0, 0x37000
	s_nop 0
	v_addc_co_u32_e32 v11, vcc, 0, v9, vcc
	global_load_dword v21, v[10:11], off nt
	v_add_co_u32_e32 v10, vcc, s0, v8
	s_mov_b32 s0, 0x42000
	s_nop 0
	v_addc_co_u32_e32 v11, vcc, 0, v9, vcc
	global_load_dword v22, v[10:11], off nt
	v_add_co_u32_e32 v10, vcc, s0, v8
	s_mov_b32 s0, 0x4d000
	s_nop 0
	v_addc_co_u32_e32 v11, vcc, 0, v9, vcc
	global_load_dword v23, v[10:11], off nt
	v_add_co_u32_e32 v10, vcc, s0, v8
	s_mov_b32 s0, 0x58000
	s_nop 0
	v_addc_co_u32_e32 v11, vcc, 0, v9, vcc
	global_load_dword v24, v[10:11], off nt
	v_add_co_u32_e32 v10, vcc, s0, v8
	s_mov_b32 s0, 0x63000
	s_nop 0
	v_addc_co_u32_e32 v11, vcc, 0, v9, vcc
	global_load_dword v25, v[10:11], off nt
	v_add_co_u32_e32 v10, vcc, s0, v8
	s_mov_b32 s0, 0x6e000
	s_nop 0
	v_addc_co_u32_e32 v11, vcc, 0, v9, vcc
	global_load_dword v26, v[10:11], off nt
	v_add_co_u32_e32 v10, vcc, s0, v8
	s_mov_b32 s0, 0x79000
	s_nop 0
	v_addc_co_u32_e32 v11, vcc, 0, v9, vcc
	global_load_dword v27, v[10:11], off nt
	v_add_co_u32_e32 v10, vcc, s0, v8
	s_mov_b32 s0, 0x84000
	s_nop 0
	v_addc_co_u32_e32 v11, vcc, 0, v9, vcc
	global_load_dword v28, v[10:11], off nt
	v_add_co_u32_e32 v10, vcc, s0, v8
	s_mov_b32 s0, 0x8f000
	s_nop 0
	v_addc_co_u32_e32 v11, vcc, 0, v9, vcc
	global_load_dword v29, v[10:11], off nt
	v_add_co_u32_e32 v10, vcc, s0, v8
	s_mov_b32 s0, 0x9a000
	s_nop 0
	v_addc_co_u32_e32 v11, vcc, 0, v9, vcc
	global_load_dword v30, v[10:11], off nt
	v_add_co_u32_e32 v10, vcc, s0, v8
	s_mov_b32 s0, 0xa5000
	s_nop 0
	v_addc_co_u32_e32 v11, vcc, 0, v9, vcc
	global_load_dword v31, v[10:11], off nt
	v_add_co_u32_e32 v10, vcc, s0, v8
	s_mov_b32 s0, 0xb0000
	s_nop 0
	v_addc_co_u32_e32 v11, vcc, 0, v9, vcc
	global_load_dword v32, v[10:11], off nt
	v_add_co_u32_e32 v10, vcc, s0, v8
	s_mov_b32 s0, 0xbb000
	s_nop 0
	v_addc_co_u32_e32 v11, vcc, 0, v9, vcc
	global_load_dword v33, v[10:11], off nt
	v_add_co_u32_e32 v10, vcc, s0, v8
	s_mov_b32 s0, 0xc6000
	s_nop 0
	v_addc_co_u32_e32 v11, vcc, 0, v9, vcc
	global_load_dword v34, v[10:11], off nt
	v_add_co_u32_e32 v10, vcc, s0, v8
	s_mov_b32 s0, 0xd1000
	s_nop 0
	v_addc_co_u32_e32 v11, vcc, 0, v9, vcc
	global_load_dword v35, v[10:11], off nt
	v_add_co_u32_e32 v10, vcc, s0, v8
	s_mov_b32 s0, 0xdc000
	s_nop 0
	v_addc_co_u32_e32 v11, vcc, 0, v9, vcc
	global_load_dword v36, v[10:11], off nt
	v_add_co_u32_e32 v10, vcc, s0, v8
	s_mov_b32 s0, 0xe7000
	s_nop 0
	v_addc_co_u32_e32 v11, vcc, 0, v9, vcc
	global_load_dword v37, v[10:11], off nt
	v_add_co_u32_e32 v10, vcc, s0, v8
	s_mov_b32 s0, 0xf2000
	s_nop 0
	v_addc_co_u32_e32 v11, vcc, 0, v9, vcc
	global_load_dword v38, v[10:11], off nt
	v_add_co_u32_e32 v10, vcc, s0, v8
	s_mov_b32 s0, 0xfd000
	s_nop 0
	v_addc_co_u32_e32 v11, vcc, 0, v9, vcc
	global_load_dword v39, v[10:11], off nt
	v_add_co_u32_e32 v10, vcc, s0, v8
	s_mov_b32 s0, 0x108000
	s_nop 0
	v_addc_co_u32_e32 v11, vcc, 0, v9, vcc
	global_load_dword v40, v[10:11], off nt
	v_add_co_u32_e32 v10, vcc, s0, v8
	s_mov_b32 s0, 0x113000
	s_nop 0
	v_addc_co_u32_e32 v11, vcc, 0, v9, vcc
	global_load_dword v41, v[10:11], off nt
	v_add_co_u32_e32 v10, vcc, s0, v8
	s_mov_b32 s0, 0x11e000
	s_nop 0
	v_addc_co_u32_e32 v11, vcc, 0, v9, vcc
	global_load_dword v42, v[10:11], off nt
	v_add_co_u32_e32 v10, vcc, s0, v8
	s_mov_b32 s0, 0x129000
	s_nop 0
	v_addc_co_u32_e32 v11, vcc, 0, v9, vcc
	global_load_dword v43, v[10:11], off nt
	v_add_co_u32_e32 v10, vcc, s0, v8
	s_mov_b32 s0, 0x134000
	s_nop 0
	v_addc_co_u32_e32 v11, vcc, 0, v9, vcc
	global_load_dword v44, v[10:11], off nt
	v_add_co_u32_e32 v10, vcc, s0, v8
	s_mov_b32 s0, 0x13f000
	s_nop 0
	v_addc_co_u32_e32 v11, vcc, 0, v9, vcc
	global_load_dword v45, v[10:11], off nt
	v_add_co_u32_e32 v10, vcc, s0, v8
	s_mov_b32 s0, 0x14a000
	s_nop 0
	v_addc_co_u32_e32 v11, vcc, 0, v9, vcc
	global_load_dword v46, v[10:11], off nt
	v_add_co_u32_e32 v10, vcc, s0, v8
	s_mov_b32 s0, 0x155000
	s_nop 0
	v_addc_co_u32_e32 v11, vcc, 0, v9, vcc
	v_add_co_u32_e32 v8, vcc, s0, v8
	global_load_dword v10, v[10:11], off nt
	s_nop 0
	v_addc_co_u32_e32 v9, vcc, 0, v9, vcc
	global_load_dword v8, v[8:9], off nt
	v_add_u32_e32 v9, 0x400, v5
	s_waitcnt vmcnt(0)
	ds_write2_b32 v5, v17, v18 offset1:66
	ds_write2_b32 v5, v19, v20 offset0:132 offset1:198
	ds_write2_b32 v9, v21, v22 offset0:8 offset1:74
	ds_write2_b32 v9, v23, v24 offset0:140 offset1:206
	v_add_u32_e32 v9, 0x800, v5
	ds_write2_b32 v9, v25, v26 offset0:16 offset1:82
	ds_write2_b32 v9, v27, v28 offset0:148 offset1:214
	v_add_u32_e32 v9, 0xc00, v5
	ds_write2_b32 v9, v29, v30 offset0:24 offset1:90
	ds_write2_b32 v9, v31, v32 offset0:156 offset1:222
	v_add_u32_e32 v9, 0x1000, v5
	ds_write2_b32 v9, v33, v34 offset0:32 offset1:98
	ds_write2_b32 v9, v35, v36 offset0:164 offset1:230
	v_add_u32_e32 v9, 0x1400, v5
	ds_write2_b32 v9, v37, v38 offset0:40 offset1:106
	ds_write2_b32 v9, v39, v40 offset0:172 offset1:238
	v_add_u32_e32 v9, 0x1800, v5
	ds_write2_b32 v9, v41, v42 offset0:48 offset1:114
	ds_write2_b32 v9, v43, v44 offset0:180 offset1:246
	v_add_u32_e32 v9, 0x1c00, v5
	ds_write2_b32 v9, v45, v46 offset0:56 offset1:122
	ds_write2_b32 v9, v10, v8 offset0:188 offset1:254
	s_waitcnt lgkmcnt(0)
	ds_read2_b32 v[10:11], v13 offset0:33 offset1:41
	ds_read2_b32 v[22:23], v13 offset1:8
	ds_read2_b32 v[24:25], v13 offset0:66 offset1:74
	ds_read2_b32 v[26:27], v13 offset0:99 offset1:107
	ds_read2_b32 v[28:29], v13 offset0:132 offset1:140
	ds_read2_b32 v[30:31], v13 offset0:165 offset1:173
	ds_read2_b32 v[32:33], v13 offset0:198 offset1:206
	ds_read2_b32 v[34:35], v13 offset0:231 offset1:239
	s_waitcnt lgkmcnt(7)
	v_bfe_u32 v18, v10, 16, 1
	s_waitcnt lgkmcnt(6)
	v_bfe_u32 v17, v22, 16, 1
	v_add3_u32 v17, v22, v17, s53
	v_lshrrev_b32_e32 v17, 16, v17
	v_add3_u32 v10, v10, v18, s53
	v_and_or_b32 v18, v10, s77, v17
	s_waitcnt lgkmcnt(5)
	v_bfe_u32 v10, v24, 16, 1
	v_add3_u32 v10, v24, v10, s53
	s_waitcnt lgkmcnt(4)
	v_bfe_u32 v17, v26, 16, 1
	v_lshrrev_b32_e32 v10, 16, v10
	v_add3_u32 v17, v26, v17, s53
	v_and_or_b32 v19, v17, s77, v10
	s_waitcnt lgkmcnt(3)
	v_bfe_u32 v10, v28, 16, 1
	v_add3_u32 v10, v28, v10, s53
	s_waitcnt lgkmcnt(2)
	v_bfe_u32 v17, v30, 16, 1
	v_lshrrev_b32_e32 v10, 16, v10
	v_add3_u32 v17, v30, v17, s53
	v_and_or_b32 v20, v17, s77, v10
	s_waitcnt lgkmcnt(1)
	v_bfe_u32 v10, v32, 16, 1
	s_lshl_b32 s0, s10, 7
	v_add3_u32 v10, v32, v10, s53
	s_waitcnt lgkmcnt(0)
	v_bfe_u32 v17, v34, 16, 1
	s_add_u32 s0, s3, s0
	v_lshrrev_b32_e32 v10, 16, v10
	v_add3_u32 v17, v34, v17, s53
	s_addc_u32 s1, s9, 0
	v_lshlrev_b32_e32 v202, 1, v4
	v_and_or_b32 v21, v17, s77, v10
	v_or_b32_e32 v10, s2, v12
	v_lshl_add_u64 v[8:9], s[0:1], 0, v[202:203]
	v_lshlrev_b32_e32 v202, 12, v10
	v_bfe_u32 v10, v23, 16, 1
	v_add3_u32 v10, v23, v10, s53
	v_bfe_u32 v17, v11, 16, 1
	v_lshl_add_u64 v[36:37], v[8:9], 0, v[202:203]
	v_lshrrev_b32_e32 v10, 16, v10
	v_add3_u32 v11, v11, v17, s53
	global_store_dwordx4 v[36:37], v[18:21], off nt
	v_readlane_b32 s17, v251, 15
	v_readlane_b32 s20, v251, 18
	v_and_or_b32 v18, v11, s77, v10
	v_bfe_u32 v10, v25, 16, 1
	v_add3_u32 v10, v25, v10, s53
	v_bfe_u32 v11, v27, 16, 1
	v_lshrrev_b32_e32 v10, 16, v10
	v_add3_u32 v11, v27, v11, s53
	v_and_or_b32 v19, v11, s77, v10
	v_bfe_u32 v10, v29, 16, 1
	v_add3_u32 v10, v29, v10, s53
	v_bfe_u32 v11, v31, 16, 1
	v_lshrrev_b32_e32 v10, 16, v10
	v_add3_u32 v11, v31, v11, s53
	v_and_or_b32 v20, v11, s77, v10
	v_bfe_u32 v10, v33, 16, 1
	v_add3_u32 v10, v33, v10, s53
	v_bfe_u32 v11, v35, 16, 1
	v_lshrrev_b32_e32 v10, 16, v10
	v_add3_u32 v11, v35, v11, s53
	v_and_or_b32 v21, v11, s77, v10
	v_or_b32_e32 v10, s2, v14
	v_lshlrev_b32_e32 v202, 12, v10
	v_lshl_add_u64 v[10:11], v[8:9], 0, v[202:203]
	global_store_dwordx4 v[10:11], v[18:21], off nt
	ds_read2_b32 v[10:11], v13 offset0:49 offset1:57
	ds_read2_b32 v[22:23], v13 offset0:16 offset1:24
	ds_read2_b32 v[24:25], v13 offset0:82 offset1:90
	ds_read2_b32 v[26:27], v13 offset0:115 offset1:123
	ds_read2_b32 v[28:29], v13 offset0:148 offset1:156
	ds_read2_b32 v[30:31], v13 offset0:181 offset1:189
	ds_read2_b32 v[32:33], v13 offset0:214 offset1:222
	ds_read2_b32 v[34:35], v13 offset0:247 offset1:255
	s_waitcnt lgkmcnt(7)
	v_bfe_u32 v18, v10, 16, 1
	s_waitcnt lgkmcnt(6)
	v_bfe_u32 v17, v22, 16, 1
	v_add3_u32 v17, v22, v17, s53
	v_lshrrev_b32_e32 v17, 16, v17
	v_add3_u32 v10, v10, v18, s53
	v_and_or_b32 v18, v10, s77, v17
	s_waitcnt lgkmcnt(5)
	v_bfe_u32 v10, v24, 16, 1
	v_add3_u32 v10, v24, v10, s53
	s_waitcnt lgkmcnt(4)
	v_bfe_u32 v17, v26, 16, 1
	v_lshrrev_b32_e32 v10, 16, v10
	v_add3_u32 v17, v26, v17, s53
	v_and_or_b32 v19, v17, s77, v10
	s_waitcnt lgkmcnt(3)
	v_bfe_u32 v10, v28, 16, 1
	v_add3_u32 v10, v28, v10, s53
	s_waitcnt lgkmcnt(2)
	v_bfe_u32 v17, v30, 16, 1
	v_lshrrev_b32_e32 v10, 16, v10
	v_add3_u32 v17, v30, v17, s53
	v_and_or_b32 v20, v17, s77, v10
	s_waitcnt lgkmcnt(1)
	v_bfe_u32 v10, v32, 16, 1
	v_add3_u32 v10, v32, v10, s53
	s_waitcnt lgkmcnt(0)
	v_bfe_u32 v17, v34, 16, 1
	v_lshrrev_b32_e32 v10, 16, v10
	v_add3_u32 v17, v34, v17, s53
	v_and_or_b32 v21, v17, s77, v10
	v_or_b32_e32 v10, s2, v15
	v_lshlrev_b32_e32 v202, 12, v10
	v_bfe_u32 v10, v23, 16, 1
	v_add3_u32 v10, v23, v10, s53
	v_bfe_u32 v17, v11, 16, 1
	v_lshl_add_u64 v[36:37], v[8:9], 0, v[202:203]
	v_lshrrev_b32_e32 v10, 16, v10
	v_add3_u32 v11, v11, v17, s53
	global_store_dwordx4 v[36:37], v[18:21], off nt
	v_readlane_b32 s21, v251, 19
	v_readlane_b32 s22, v251, 20
	v_and_or_b32 v18, v11, s77, v10
	v_bfe_u32 v10, v25, 16, 1
	v_add3_u32 v10, v25, v10, s53
	v_bfe_u32 v11, v27, 16, 1
	v_lshrrev_b32_e32 v10, 16, v10
	v_add3_u32 v11, v27, v11, s53
	v_and_or_b32 v19, v11, s77, v10
	v_bfe_u32 v10, v29, 16, 1
	v_add3_u32 v10, v29, v10, s53
	v_bfe_u32 v11, v31, 16, 1
	v_lshrrev_b32_e32 v10, 16, v10
	v_add3_u32 v11, v31, v11, s53
	v_and_or_b32 v20, v11, s77, v10
	v_bfe_u32 v10, v33, 16, 1
	v_add3_u32 v10, v33, v10, s53
	v_bfe_u32 v11, v35, 16, 1
	v_lshrrev_b32_e32 v10, 16, v10
	v_add3_u32 v11, v35, v11, s53
	v_and_or_b32 v21, v11, s77, v10
	v_or_b32_e32 v10, s2, v16
	v_lshlrev_b32_e32 v202, 12, v10
	v_lshl_add_u64 v[8:9], v[8:9], 0, v[202:203]
	global_store_dwordx4 v[8:9], v[18:21], off nt
	s_waitcnt lgkmcnt(0)
	v_readlane_b32 s23, v251, 21
	v_readlane_b32 s24, v251, 22
	v_readlane_b32 s25, v251, 23
	v_readlane_b32 s26, v251, 24
	v_readlane_b32 s27, v251, 25
	v_readlane_b32 s28, v251, 26
	v_readlane_b32 s29, v251, 27
	v_readlane_b32 s30, v251, 28
	v_readlane_b32 s31, v251, 29

.LBB0_521:
	s_andn2_b64 vcc, exec, s[2:3]
	s_cbranch_vccnz .LBB0_523
	v_readlane_b32 s16, v251, 14
	v_readlane_b32 s17, v251, 15
	s_add_u32 s0, s16, s8
	s_addc_u32 s1, s17, s7
	v_readlane_b32 s2, v251, 56
	s_add_u32 s3, s2, s8
	v_readlane_b32 s2, v251, 57
	s_addc_u32 s7, s2, s7
	s_and_b32 s2, 0xffff, s5
	s_mul_i32 s2, s2, 0xba2f
	s_lshr_b32 s8, s2, 23
	s_mul_i32 s2, s8, 0xb0
	s_sub_i32 s2, s5, s2
	s_and_b32 s5, s2, 0xffff
	s_lshl_b32 s2, s5, 5
	s_lshl_b32 s9, s5, 6
	s_and_b32 s9, s9, 0x3f00
	s_and_b32 s2, s2, 0x60
	s_or_b32 s2, s2, s9
	s_lshl_b32 s5, s5, 7
	v_lshl_or_b32 v10, s8, 6, v3
	s_add_u32 s0, s0, s5
	s_addc_u32 s1, s1, 0
	v_lshlrev_b32_e32 v202, 2, v2
	v_mul_u32_u24_e32 v10, 0x1600, v10
	v_lshl_add_u64 v[8:9], s[0:1], 0, v[202:203]
	v_lshlrev_b32_e32 v202, 2, v10
	v_lshl_add_u64 v[8:9], v[8:9], 0, v[202:203]
	s_mov_b32 s0, 0xb000
	v_add_co_u32_e32 v10, vcc, s0, v8
	s_mov_b32 s0, 0x16000
	s_nop 0
	v_addc_co_u32_e32 v11, vcc, 0, v9, vcc
	global_load_dword v17, v[8:9], off nt
	global_load_dword v18, v[10:11], off nt
	v_add_co_u32_e32 v10, vcc, s0, v8
	s_mov_b32 s0, 0x21000
	s_nop 0
	v_addc_co_u32_e32 v11, vcc, 0, v9, vcc
	global_load_dword v19, v[10:11], off nt
	v_add_co_u32_e32 v10, vcc, s0, v8
	s_mov_b32 s0, 0x2c000
	s_nop 0
	v_addc_co_u32_e32 v11, vcc, 0, v9, vcc
	global_load_dword v20, v[10:11], off nt
	v_add_co_u32_e32 v10, vcc, s0, v8
	s_mov_b32 s0, 0x37000
	s_nop 0
	v_addc_co_u32_e32 v11, vcc, 0, v9, vcc
	global_load_dword v21, v[10:11], off nt
	v_add_co_u32_e32 v10, vcc, s0, v8
	s_mov_b32 s0, 0x42000
	s_nop 0
	v_addc_co_u32_e32 v11, vcc, 0, v9, vcc
	global_load_dword v22, v[10:11], off nt
	v_add_co_u32_e32 v10, vcc, s0, v8
	s_mov_b32 s0, 0x4d000
	s_nop 0
	v_addc_co_u32_e32 v11, vcc, 0, v9, vcc
	global_load_dword v23, v[10:11], off nt
	v_add_co_u32_e32 v10, vcc, s0, v8
	s_mov_b32 s0, 0x58000
	s_nop 0
	v_addc_co_u32_e32 v11, vcc, 0, v9, vcc
	global_load_dword v24, v[10:11], off nt
	v_add_co_u32_e32 v10, vcc, s0, v8
	s_mov_b32 s0, 0x63000
	s_nop 0
	v_addc_co_u32_e32 v11, vcc, 0, v9, vcc
	global_load_dword v25, v[10:11], off nt
	v_add_co_u32_e32 v10, vcc, s0, v8
	s_mov_b32 s0, 0x6e000
	s_nop 0
	v_addc_co_u32_e32 v11, vcc, 0, v9, vcc
	global_load_dword v26, v[10:11], off nt
	v_add_co_u32_e32 v10, vcc, s0, v8
	s_mov_b32 s0, 0x79000
	s_nop 0
	v_addc_co_u32_e32 v11, vcc, 0, v9, vcc
	global_load_dword v27, v[10:11], off nt
	v_add_co_u32_e32 v10, vcc, s0, v8
	s_mov_b32 s0, 0x84000
	s_nop 0
	v_addc_co_u32_e32 v11, vcc, 0, v9, vcc
	global_load_dword v28, v[10:11], off nt
	v_add_co_u32_e32 v10, vcc, s0, v8
	s_mov_b32 s0, 0x8f000
	s_nop 0
	v_addc_co_u32_e32 v11, vcc, 0, v9, vcc
	global_load_dword v29, v[10:11], off nt
	v_add_co_u32_e32 v10, vcc, s0, v8
	s_mov_b32 s0, 0x9a000
	s_nop 0
	v_addc_co_u32_e32 v11, vcc, 0, v9, vcc
	global_load_dword v30, v[10:11], off nt
	v_add_co_u32_e32 v10, vcc, s0, v8
	s_mov_b32 s0, 0xa5000
	s_nop 0
	v_addc_co_u32_e32 v11, vcc, 0, v9, vcc
	global_load_dword v31, v[10:11], off nt
	v_add_co_u32_e32 v10, vcc, s0, v8
	s_mov_b32 s0, 0xb0000
	s_nop 0
	v_addc_co_u32_e32 v11, vcc, 0, v9, vcc
	global_load_dword v32, v[10:11], off nt
	v_add_co_u32_e32 v10, vcc, s0, v8
	s_mov_b32 s0, 0xbb000
	s_nop 0
	v_addc_co_u32_e32 v11, vcc, 0, v9, vcc
	global_load_dword v33, v[10:11], off nt
	v_add_co_u32_e32 v10, vcc, s0, v8
	s_mov_b32 s0, 0xc6000
	s_nop 0
	v_addc_co_u32_e32 v11, vcc, 0, v9, vcc
	global_load_dword v34, v[10:11], off nt
	v_add_co_u32_e32 v10, vcc, s0, v8
	s_mov_b32 s0, 0xd1000
	s_nop 0
	v_addc_co_u32_e32 v11, vcc, 0, v9, vcc
	global_load_dword v35, v[10:11], off nt
	v_add_co_u32_e32 v10, vcc, s0, v8
	s_mov_b32 s0, 0xdc000
	s_nop 0
	v_addc_co_u32_e32 v11, vcc, 0, v9, vcc
	global_load_dword v36, v[10:11], off nt
	v_add_co_u32_e32 v10, vcc, s0, v8
	s_mov_b32 s0, 0xe7000
	s_nop 0
	v_addc_co_u32_e32 v11, vcc, 0, v9, vcc
	global_load_dword v37, v[10:11], off nt
	v_add_co_u32_e32 v10, vcc, s0, v8
	s_mov_b32 s0, 0xf2000
	s_nop 0
	v_addc_co_u32_e32 v11, vcc, 0, v9, vcc
	global_load_dword v38, v[10:11], off nt
	v_add_co_u32_e32 v10, vcc, s0, v8
	s_mov_b32 s0, 0xfd000
	s_nop 0
	v_addc_co_u32_e32 v11, vcc, 0, v9, vcc
	global_load_dword v39, v[10:11], off nt
	v_add_co_u32_e32 v10, vcc, s0, v8
	s_mov_b32 s0, 0x108000
	s_nop 0
	v_addc_co_u32_e32 v11, vcc, 0, v9, vcc
	global_load_dword v40, v[10:11], off nt
	v_add_co_u32_e32 v10, vcc, s0, v8
	s_mov_b32 s0, 0x113000
	s_nop 0
	v_addc_co_u32_e32 v11, vcc, 0, v9, vcc
	global_load_dword v41, v[10:11], off nt
	v_add_co_u32_e32 v10, vcc, s0, v8
	s_mov_b32 s0, 0x11e000
	s_nop 0
	v_addc_co_u32_e32 v11, vcc, 0, v9, vcc
	global_load_dword v42, v[10:11], off nt
	v_add_co_u32_e32 v10, vcc, s0, v8
	s_mov_b32 s0, 0x129000
	s_nop 0
	v_addc_co_u32_e32 v11, vcc, 0, v9, vcc
	global_load_dword v43, v[10:11], off nt
	v_add_co_u32_e32 v10, vcc, s0, v8
	s_mov_b32 s0, 0x134000
	s_nop 0
	v_addc_co_u32_e32 v11, vcc, 0, v9, vcc
	global_load_dword v44, v[10:11], off nt
	v_add_co_u32_e32 v10, vcc, s0, v8
	s_mov_b32 s0, 0x13f000
	s_nop 0
	v_addc_co_u32_e32 v11, vcc, 0, v9, vcc
	global_load_dword v45, v[10:11], off nt
	v_add_co_u32_e32 v10, vcc, s0, v8
	s_mov_b32 s0, 0x14a000
	s_nop 0
	v_addc_co_u32_e32 v11, vcc, 0, v9, vcc
	global_load_dword v46, v[10:11], off nt
	v_add_co_u32_e32 v10, vcc, s0, v8
	s_mov_b32 s0, 0x155000
	s_nop 0
	v_addc_co_u32_e32 v11, vcc, 0, v9, vcc
	v_add_co_u32_e32 v8, vcc, s0, v8
	global_load_dword v10, v[10:11], off nt
	s_nop 0
	v_addc_co_u32_e32 v9, vcc, 0, v9, vcc
	global_load_dword v8, v[8:9], off nt
	v_add_u32_e32 v9, 0x400, v5
	s_waitcnt vmcnt(0)
	ds_write2_b32 v5, v17, v18 offset1:66
	ds_write2_b32 v5, v19, v20 offset0:132 offset1:198
	ds_write2_b32 v9, v21, v22 offset0:8 offset1:74
	ds_write2_b32 v9, v23, v24 offset0:140 offset1:206
	v_add_u32_e32 v9, 0x800, v5
	ds_write2_b32 v9, v25, v26 offset0:16 offset1:82
	ds_write2_b32 v9, v27, v28 offset0:148 offset1:214
	v_add_u32_e32 v9, 0xc00, v5
	ds_write2_b32 v9, v29, v30 offset0:24 offset1:90
	ds_write2_b32 v9, v31, v32 offset0:156 offset1:222
	v_add_u32_e32 v9, 0x1000, v5
	ds_write2_b32 v9, v33, v34 offset0:32 offset1:98
	ds_write2_b32 v9, v35, v36 offset0:164 offset1:230
	v_add_u32_e32 v9, 0x1400, v5
	ds_write2_b32 v9, v37, v38 offset0:40 offset1:106
	ds_write2_b32 v9, v39, v40 offset0:172 offset1:238
	v_add_u32_e32 v9, 0x1800, v5
	ds_write2_b32 v9, v41, v42 offset0:48 offset1:114
	ds_write2_b32 v9, v43, v44 offset0:180 offset1:246
	v_add_u32_e32 v9, 0x1c00, v5
	ds_write2_b32 v9, v45, v46 offset0:56 offset1:122
	ds_write2_b32 v9, v10, v8 offset0:188 offset1:254
	s_waitcnt lgkmcnt(0)
	ds_read2_b32 v[10:11], v13 offset0:33 offset1:41
	ds_read2_b32 v[22:23], v13 offset1:8
	ds_read2_b32 v[24:25], v13 offset0:66 offset1:74
	ds_read2_b32 v[26:27], v13 offset0:99 offset1:107
	ds_read2_b32 v[28:29], v13 offset0:132 offset1:140
	ds_read2_b32 v[30:31], v13 offset0:165 offset1:173
	ds_read2_b32 v[32:33], v13 offset0:198 offset1:206
	ds_read2_b32 v[34:35], v13 offset0:231 offset1:239
	s_waitcnt lgkmcnt(7)
	v_bfe_u32 v18, v10, 16, 1
	s_waitcnt lgkmcnt(6)
	v_bfe_u32 v17, v22, 16, 1
	v_add3_u32 v17, v22, v17, s53
	v_lshrrev_b32_e32 v17, 16, v17
	v_add3_u32 v10, v10, v18, s53
	v_and_or_b32 v18, v10, s77, v17
	s_waitcnt lgkmcnt(5)
	v_bfe_u32 v10, v24, 16, 1
	v_add3_u32 v10, v24, v10, s53
	s_waitcnt lgkmcnt(4)
	v_bfe_u32 v17, v26, 16, 1
	v_lshrrev_b32_e32 v10, 16, v10
	v_add3_u32 v17, v26, v17, s53
	v_and_or_b32 v19, v17, s77, v10
	s_waitcnt lgkmcnt(3)
	v_bfe_u32 v10, v28, 16, 1
	v_add3_u32 v10, v28, v10, s53
	s_waitcnt lgkmcnt(2)
	v_bfe_u32 v17, v30, 16, 1
	v_lshrrev_b32_e32 v10, 16, v10
	v_add3_u32 v17, v30, v17, s53
	v_and_or_b32 v20, v17, s77, v10
	s_waitcnt lgkmcnt(1)
	v_bfe_u32 v10, v32, 16, 1
	s_lshl_b32 s0, s8, 7
	v_add3_u32 v10, v32, v10, s53
	s_waitcnt lgkmcnt(0)
	v_bfe_u32 v17, v34, 16, 1
	s_add_u32 s0, s3, s0
	v_lshrrev_b32_e32 v10, 16, v10
	v_add3_u32 v17, v34, v17, s53
	s_addc_u32 s1, s7, 0
	v_lshlrev_b32_e32 v202, 1, v4
	v_and_or_b32 v21, v17, s77, v10
	v_or_b32_e32 v10, s2, v12
	v_lshl_add_u64 v[8:9], s[0:1], 0, v[202:203]
	v_lshlrev_b32_e32 v202, 12, v10
	v_bfe_u32 v10, v23, 16, 1
	v_add3_u32 v10, v23, v10, s53
	v_bfe_u32 v17, v11, 16, 1
	v_lshl_add_u64 v[36:37], v[8:9], 0, v[202:203]
	v_lshrrev_b32_e32 v10, 16, v10
	v_add3_u32 v11, v11, v17, s53
	global_store_dwordx4 v[36:37], v[18:21], off nt
	v_readlane_b32 s18, v251, 16
	v_readlane_b32 s19, v251, 17
	v_and_or_b32 v18, v11, s77, v10
	v_bfe_u32 v10, v25, 16, 1
	v_add3_u32 v10, v25, v10, s53
	v_bfe_u32 v11, v27, 16, 1
	v_lshrrev_b32_e32 v10, 16, v10
	v_add3_u32 v11, v27, v11, s53
	v_and_or_b32 v19, v11, s77, v10
	v_bfe_u32 v10, v29, 16, 1
	v_add3_u32 v10, v29, v10, s53
	v_bfe_u32 v11, v31, 16, 1
	v_lshrrev_b32_e32 v10, 16, v10
	v_add3_u32 v11, v31, v11, s53
	v_and_or_b32 v20, v11, s77, v10
	v_bfe_u32 v10, v33, 16, 1
	v_add3_u32 v10, v33, v10, s53
	v_bfe_u32 v11, v35, 16, 1
	v_lshrrev_b32_e32 v10, 16, v10
	v_add3_u32 v11, v35, v11, s53
	v_and_or_b32 v21, v11, s77, v10
	v_or_b32_e32 v10, s2, v14
	v_lshlrev_b32_e32 v202, 12, v10
	v_lshl_add_u64 v[10:11], v[8:9], 0, v[202:203]
	global_store_dwordx4 v[10:11], v[18:21], off nt
	ds_read2_b32 v[10:11], v13 offset0:49 offset1:57
	ds_read2_b32 v[22:23], v13 offset0:16 offset1:24
	ds_read2_b32 v[24:25], v13 offset0:82 offset1:90
	ds_read2_b32 v[26:27], v13 offset0:115 offset1:123
	ds_read2_b32 v[28:29], v13 offset0:148 offset1:156
	ds_read2_b32 v[30:31], v13 offset0:181 offset1:189
	ds_read2_b32 v[32:33], v13 offset0:214 offset1:222
	ds_read2_b32 v[34:35], v13 offset0:247 offset1:255
	s_waitcnt lgkmcnt(7)
	v_bfe_u32 v18, v10, 16, 1
	s_waitcnt lgkmcnt(6)
	v_bfe_u32 v17, v22, 16, 1
	v_add3_u32 v17, v22, v17, s53
	v_lshrrev_b32_e32 v17, 16, v17
	v_add3_u32 v10, v10, v18, s53
	v_and_or_b32 v18, v10, s77, v17
	s_waitcnt lgkmcnt(5)
	v_bfe_u32 v10, v24, 16, 1
	v_add3_u32 v10, v24, v10, s53
	s_waitcnt lgkmcnt(4)
	v_bfe_u32 v17, v26, 16, 1
	v_lshrrev_b32_e32 v10, 16, v10
	v_add3_u32 v17, v26, v17, s53
	v_and_or_b32 v19, v17, s77, v10
	s_waitcnt lgkmcnt(3)
	v_bfe_u32 v10, v28, 16, 1
	v_add3_u32 v10, v28, v10, s53
	s_waitcnt lgkmcnt(2)
	v_bfe_u32 v17, v30, 16, 1
	v_lshrrev_b32_e32 v10, 16, v10
	v_add3_u32 v17, v30, v17, s53
	v_and_or_b32 v20, v17, s77, v10
	s_waitcnt lgkmcnt(1)
	v_bfe_u32 v10, v32, 16, 1
	v_add3_u32 v10, v32, v10, s53
	s_waitcnt lgkmcnt(0)
	v_bfe_u32 v17, v34, 16, 1
	v_lshrrev_b32_e32 v10, 16, v10
	v_add3_u32 v17, v34, v17, s53
	v_and_or_b32 v21, v17, s77, v10
	v_or_b32_e32 v10, s2, v15
	v_lshlrev_b32_e32 v202, 12, v10
	v_bfe_u32 v10, v23, 16, 1
	v_add3_u32 v10, v23, v10, s53
	v_bfe_u32 v17, v11, 16, 1
	v_lshl_add_u64 v[36:37], v[8:9], 0, v[202:203]
	v_lshrrev_b32_e32 v10, 16, v10
	v_add3_u32 v11, v11, v17, s53
	global_store_dwordx4 v[36:37], v[18:21], off nt
	v_readlane_b32 s20, v251, 18
	v_readlane_b32 s21, v251, 19
	v_and_or_b32 v18, v11, s77, v10
	v_bfe_u32 v10, v25, 16, 1
	v_add3_u32 v10, v25, v10, s53
	v_bfe_u32 v11, v27, 16, 1
	v_lshrrev_b32_e32 v10, 16, v10
	v_add3_u32 v11, v27, v11, s53
	v_and_or_b32 v19, v11, s77, v10
	v_bfe_u32 v10, v29, 16, 1
	v_add3_u32 v10, v29, v10, s53
	v_bfe_u32 v11, v31, 16, 1
	v_lshrrev_b32_e32 v10, 16, v10
	v_add3_u32 v11, v31, v11, s53
	v_and_or_b32 v20, v11, s77, v10
	v_bfe_u32 v10, v33, 16, 1
	v_add3_u32 v10, v33, v10, s53
	v_bfe_u32 v11, v35, 16, 1
	v_lshrrev_b32_e32 v10, 16, v10
	v_add3_u32 v11, v35, v11, s53
	v_and_or_b32 v21, v11, s77, v10
	v_or_b32_e32 v10, s2, v16
	v_lshlrev_b32_e32 v202, 12, v10
	v_lshl_add_u64 v[8:9], v[8:9], 0, v[202:203]
	global_store_dwordx4 v[8:9], v[18:21], off nt
	s_waitcnt lgkmcnt(0)
	v_readlane_b32 s22, v251, 20
	v_readlane_b32 s23, v251, 21
	v_readlane_b32 s24, v251, 22
	v_readlane_b32 s25, v251, 23
	v_readlane_b32 s26, v251, 24
	v_readlane_b32 s27, v251, 25
	v_readlane_b32 s28, v251, 26
	v_readlane_b32 s29, v251, 27
	v_readlane_b32 s30, v251, 28
	v_readlane_b32 s31, v251, 29

.LBB0_524:
	s_andn2_b64 vcc, exec, s[2:3]
	s_cbranch_vccnz .LBB0_526
	s_add_i32 s0, s4, 0xffffc000
	v_readlane_b32 s16, v251, 30
	s_lshr_b32 s86, s0, 12
	v_readlane_b32 s17, v251, 31
	s_lshl_b64 s[0:1], s[86:87], 25
	v_readlane_b32 s18, v251, 32
	v_readlane_b32 s19, v251, 33
	s_mov_b64 s[8:9], s[16:17]
	s_add_u32 s8, s8, s0
	s_addc_u32 s9, s9, s1
	s_lshl_b64 s[0:1], s[86:87], 24
	v_readlane_b32 s2, v251, 58
	s_add_u32 s3, s2, s0
	v_readlane_b32 s0, v251, 59
	s_addc_u32 s5, s0, s1
	s_lshl_b32 s0, s4, 5
	s_and_b32 s2, s0, 0x7e0
	s_and_b32 s7, s4, 0xfc0
	s_lshl_b32 s0, s2, 2
	s_add_u32 s0, s8, s0
	v_or_b32_e32 v10, s7, v3
	s_addc_u32 s1, s9, 0
	v_lshlrev_b32_e32 v202, 2, v2
	v_lshl_add_u64 v[8:9], s[0:1], 0, v[202:203]
	v_lshlrev_b32_e32 v202, 13, v10
	v_lshl_add_u64 v[8:9], v[8:9], 0, v[202:203]
	v_add_co_u32_e32 v10, vcc, s89, v8
	s_mov_b32 s0, 0x8000
	s_nop 0
	v_addc_co_u32_e32 v11, vcc, 0, v9, vcc
	global_load_dword v17, v[8:9], off nt
	global_load_dword v18, v[10:11], off nt
	v_add_co_u32_e32 v10, vcc, s0, v8
	s_mov_b32 s0, 0xc000
	s_nop 0
	v_addc_co_u32_e32 v11, vcc, 0, v9, vcc
	global_load_dword v19, v[10:11], off nt
	v_add_co_u32_e32 v10, vcc, s0, v8
	s_mov_b32 s0, 0x10000
	s_nop 0
	v_addc_co_u32_e32 v11, vcc, 0, v9, vcc
	global_load_dword v20, v[10:11], off nt
	v_add_co_u32_e32 v10, vcc, s0, v8
	s_mov_b32 s0, 0x14000
	s_nop 0
	v_addc_co_u32_e32 v11, vcc, 0, v9, vcc
	global_load_dword v21, v[10:11], off nt
	v_add_co_u32_e32 v10, vcc, s0, v8
	s_mov_b32 s0, 0x18000
	s_nop 0
	v_addc_co_u32_e32 v11, vcc, 0, v9, vcc
	global_load_dword v22, v[10:11], off nt
	v_add_co_u32_e32 v10, vcc, s0, v8
	s_mov_b32 s0, 0x1c000
	s_nop 0
	v_addc_co_u32_e32 v11, vcc, 0, v9, vcc
	global_load_dword v23, v[10:11], off nt
	v_add_co_u32_e32 v10, vcc, s0, v8
	s_mov_b32 s0, 0x20000
	s_nop 0
	v_addc_co_u32_e32 v11, vcc, 0, v9, vcc
	global_load_dword v24, v[10:11], off nt
	v_add_co_u32_e32 v10, vcc, s0, v8
	s_mov_b32 s0, 0x24000
	s_nop 0
	v_addc_co_u32_e32 v11, vcc, 0, v9, vcc
	global_load_dword v25, v[10:11], off nt
	v_add_co_u32_e32 v10, vcc, s0, v8
	s_mov_b32 s0, 0x28000
	s_nop 0
	v_addc_co_u32_e32 v11, vcc, 0, v9, vcc
	global_load_dword v26, v[10:11], off nt
	v_add_co_u32_e32 v10, vcc, s0, v8
	s_mov_b32 s0, 0x2c000
	s_nop 0
	v_addc_co_u32_e32 v11, vcc, 0, v9, vcc
	global_load_dword v27, v[10:11], off nt
	v_add_co_u32_e32 v10, vcc, s0, v8
	s_mov_b32 s0, 0x30000
	s_nop 0
	v_addc_co_u32_e32 v11, vcc, 0, v9, vcc
	global_load_dword v28, v[10:11], off nt
	v_add_co_u32_e32 v10, vcc, s0, v8
	s_mov_b32 s0, 0x34000
	s_nop 0
	v_addc_co_u32_e32 v11, vcc, 0, v9, vcc
	global_load_dword v29, v[10:11], off nt
	v_add_co_u32_e32 v10, vcc, s0, v8
	s_mov_b32 s0, 0x38000
	s_nop 0
	v_addc_co_u32_e32 v11, vcc, 0, v9, vcc
	global_load_dword v30, v[10:11], off nt
	v_add_co_u32_e32 v10, vcc, s0, v8
	s_mov_b32 s0, 0x3c000
	s_nop 0
	v_addc_co_u32_e32 v11, vcc, 0, v9, vcc
	global_load_dword v31, v[10:11], off nt
	v_add_co_u32_e32 v10, vcc, s0, v8
	s_mov_b32 s0, 0x40000
	s_nop 0
	v_addc_co_u32_e32 v11, vcc, 0, v9, vcc
	global_load_dword v32, v[10:11], off nt
	v_add_co_u32_e32 v10, vcc, s0, v8
	s_mov_b32 s0, 0x44000
	s_nop 0
	v_addc_co_u32_e32 v11, vcc, 0, v9, vcc
	global_load_dword v33, v[10:11], off nt
	v_add_co_u32_e32 v10, vcc, s0, v8
	s_mov_b32 s0, 0x48000
	s_nop 0
	v_addc_co_u32_e32 v11, vcc, 0, v9, vcc
	global_load_dword v34, v[10:11], off nt
	v_add_co_u32_e32 v10, vcc, s0, v8
	s_mov_b32 s0, 0x4c000
	s_nop 0
	v_addc_co_u32_e32 v11, vcc, 0, v9, vcc
	global_load_dword v35, v[10:11], off nt
	v_add_co_u32_e32 v10, vcc, s0, v8
	s_mov_b32 s0, 0x50000
	s_nop 0
	v_addc_co_u32_e32 v11, vcc, 0, v9, vcc
	global_load_dword v36, v[10:11], off nt
	v_add_co_u32_e32 v10, vcc, s0, v8
	s_mov_b32 s0, 0x54000
	s_nop 0
	v_addc_co_u32_e32 v11, vcc, 0, v9, vcc
	global_load_dword v37, v[10:11], off nt
	v_add_co_u32_e32 v10, vcc, s0, v8
	s_mov_b32 s0, 0x58000
	s_nop 0
	v_addc_co_u32_e32 v11, vcc, 0, v9, vcc
	global_load_dword v38, v[10:11], off nt
	v_add_co_u32_e32 v10, vcc, s0, v8
	s_mov_b32 s0, 0x5c000
	s_nop 0
	v_addc_co_u32_e32 v11, vcc, 0, v9, vcc
	global_load_dword v39, v[10:11], off nt
	v_add_co_u32_e32 v10, vcc, s0, v8
	s_mov_b32 s0, 0x60000
	s_nop 0
	v_addc_co_u32_e32 v11, vcc, 0, v9, vcc
	global_load_dword v40, v[10:11], off nt
	v_add_co_u32_e32 v10, vcc, s0, v8
	s_mov_b32 s0, 0x64000
	s_nop 0
	v_addc_co_u32_e32 v11, vcc, 0, v9, vcc
	global_load_dword v41, v[10:11], off nt
	v_add_co_u32_e32 v10, vcc, s0, v8
	s_mov_b32 s0, 0x68000
	s_nop 0
	v_addc_co_u32_e32 v11, vcc, 0, v9, vcc
	global_load_dword v42, v[10:11], off nt
	v_add_co_u32_e32 v10, vcc, s0, v8
	s_mov_b32 s0, 0x6c000
	s_nop 0
	v_addc_co_u32_e32 v11, vcc, 0, v9, vcc
	global_load_dword v43, v[10:11], off nt
	v_add_co_u32_e32 v10, vcc, s0, v8
	s_mov_b32 s0, 0x70000
	s_nop 0
	v_addc_co_u32_e32 v11, vcc, 0, v9, vcc
	global_load_dword v44, v[10:11], off nt
	v_add_co_u32_e32 v10, vcc, s0, v8
	s_mov_b32 s0, 0x74000
	s_nop 0
	v_addc_co_u32_e32 v11, vcc, 0, v9, vcc
	global_load_dword v45, v[10:11], off nt
	v_add_co_u32_e32 v10, vcc, s0, v8
	s_mov_b32 s0, 0x78000
	s_nop 0
	v_addc_co_u32_e32 v11, vcc, 0, v9, vcc
	global_load_dword v46, v[10:11], off nt
	v_add_co_u32_e32 v10, vcc, s0, v8
	s_mov_b32 s0, 0x7c000
	s_nop 0
	v_addc_co_u32_e32 v11, vcc, 0, v9, vcc
	v_add_co_u32_e32 v8, vcc, s0, v8
	global_load_dword v10, v[10:11], off nt
	s_nop 0
	v_addc_co_u32_e32 v9, vcc, 0, v9, vcc
	global_load_dword v8, v[8:9], off nt
	v_add_u32_e32 v9, 0x400, v5
	s_waitcnt vmcnt(0)
	ds_write2_b32 v5, v17, v18 offset1:66
	ds_write2_b32 v5, v19, v20 offset0:132 offset1:198
	ds_write2_b32 v9, v21, v22 offset0:8 offset1:74
	ds_write2_b32 v9, v23, v24 offset0:140 offset1:206
	v_add_u32_e32 v9, 0x800, v5
	ds_write2_b32 v9, v25, v26 offset0:16 offset1:82
	ds_write2_b32 v9, v27, v28 offset0:148 offset1:214
	v_add_u32_e32 v9, 0xc00, v5
	ds_write2_b32 v9, v29, v30 offset0:24 offset1:90
	ds_write2_b32 v9, v31, v32 offset0:156 offset1:222
	v_add_u32_e32 v9, 0x1000, v5
	ds_write2_b32 v9, v33, v34 offset0:32 offset1:98
	ds_write2_b32 v9, v35, v36 offset0:164 offset1:230
	v_add_u32_e32 v9, 0x1400, v5
	ds_write2_b32 v9, v37, v38 offset0:40 offset1:106
	ds_write2_b32 v9, v39, v40 offset0:172 offset1:238
	v_add_u32_e32 v9, 0x1800, v5
	ds_write2_b32 v9, v41, v42 offset0:48 offset1:114
	ds_write2_b32 v9, v43, v44 offset0:180 offset1:246
	v_add_u32_e32 v9, 0x1c00, v5
	ds_write2_b32 v9, v45, v46 offset0:56 offset1:122
	ds_write2_b32 v9, v10, v8 offset0:188 offset1:254
	s_waitcnt lgkmcnt(0)
	ds_read2_b32 v[10:11], v13 offset0:33 offset1:41
	ds_read2_b32 v[22:23], v13 offset1:8
	ds_read2_b32 v[24:25], v13 offset0:66 offset1:74
	ds_read2_b32 v[26:27], v13 offset0:99 offset1:107
	ds_read2_b32 v[28:29], v13 offset0:132 offset1:140
	ds_read2_b32 v[30:31], v13 offset0:165 offset1:173
	ds_read2_b32 v[32:33], v13 offset0:198 offset1:206
	ds_read2_b32 v[34:35], v13 offset0:231 offset1:239
	s_waitcnt lgkmcnt(7)
	v_bfe_u32 v18, v10, 16, 1
	s_waitcnt lgkmcnt(6)
	v_bfe_u32 v17, v22, 16, 1
	v_add3_u32 v17, v22, v17, s53
	v_lshrrev_b32_e32 v17, 16, v17
	v_add3_u32 v10, v10, v18, s53
	v_and_or_b32 v18, v10, s77, v17
	s_waitcnt lgkmcnt(5)
	v_bfe_u32 v10, v24, 16, 1
	v_add3_u32 v10, v24, v10, s53
	s_waitcnt lgkmcnt(4)
	v_bfe_u32 v17, v26, 16, 1
	v_lshrrev_b32_e32 v10, 16, v10
	v_add3_u32 v17, v26, v17, s53
	v_and_or_b32 v19, v17, s77, v10
	s_waitcnt lgkmcnt(3)
	v_bfe_u32 v10, v28, 16, 1
	v_add3_u32 v10, v28, v10, s53
	s_waitcnt lgkmcnt(2)
	v_bfe_u32 v17, v30, 16, 1
	v_lshrrev_b32_e32 v10, 16, v10
	v_add3_u32 v17, v30, v17, s53
	v_and_or_b32 v20, v17, s77, v10
	s_waitcnt lgkmcnt(1)
	v_bfe_u32 v10, v32, 16, 1
	s_lshl_b32 s0, s7, 1
	v_add3_u32 v10, v32, v10, s53
	s_waitcnt lgkmcnt(0)
	v_bfe_u32 v17, v34, 16, 1
	s_add_u32 s0, s3, s0
	v_lshrrev_b32_e32 v10, 16, v10
	v_add3_u32 v17, v34, v17, s53
	s_addc_u32 s1, s5, 0
	v_lshlrev_b32_e32 v202, 1, v4
	v_and_or_b32 v21, v17, s77, v10
	v_or_b32_e32 v10, s2, v12
	v_lshl_add_u64 v[8:9], s[0:1], 0, v[202:203]
	v_lshlrev_b32_e32 v202, 13, v10
	v_bfe_u32 v10, v23, 16, 1
	v_add3_u32 v10, v23, v10, s53
	v_bfe_u32 v17, v11, 16, 1
	v_lshl_add_u64 v[36:37], v[8:9], 0, v[202:203]
	v_lshrrev_b32_e32 v10, 16, v10
	v_add3_u32 v11, v11, v17, s53
	global_store_dwordx4 v[36:37], v[18:21], off nt
	v_readlane_b32 s20, v251, 34
	v_readlane_b32 s21, v251, 35
	v_and_or_b32 v18, v11, s77, v10
	v_bfe_u32 v10, v25, 16, 1
	v_add3_u32 v10, v25, v10, s53
	v_bfe_u32 v11, v27, 16, 1
	v_lshrrev_b32_e32 v10, 16, v10
	v_add3_u32 v11, v27, v11, s53
	v_and_or_b32 v19, v11, s77, v10
	v_bfe_u32 v10, v29, 16, 1
	v_add3_u32 v10, v29, v10, s53
	v_bfe_u32 v11, v31, 16, 1
	v_lshrrev_b32_e32 v10, 16, v10
	v_add3_u32 v11, v31, v11, s53
	v_and_or_b32 v20, v11, s77, v10
	v_bfe_u32 v10, v33, 16, 1
	v_add3_u32 v10, v33, v10, s53
	v_bfe_u32 v11, v35, 16, 1
	v_lshrrev_b32_e32 v10, 16, v10
	v_add3_u32 v11, v35, v11, s53
	v_and_or_b32 v21, v11, s77, v10
	v_or_b32_e32 v10, s2, v14
	v_lshlrev_b32_e32 v202, 13, v10
	v_lshl_add_u64 v[10:11], v[8:9], 0, v[202:203]
	global_store_dwordx4 v[10:11], v[18:21], off nt
	ds_read2_b32 v[10:11], v13 offset0:49 offset1:57
	ds_read2_b32 v[22:23], v13 offset0:16 offset1:24
	ds_read2_b32 v[24:25], v13 offset0:82 offset1:90
	ds_read2_b32 v[26:27], v13 offset0:115 offset1:123
	ds_read2_b32 v[28:29], v13 offset0:148 offset1:156
	ds_read2_b32 v[30:31], v13 offset0:181 offset1:189
	ds_read2_b32 v[32:33], v13 offset0:214 offset1:222
	ds_read2_b32 v[34:35], v13 offset0:247 offset1:255
	s_waitcnt lgkmcnt(7)
	v_bfe_u32 v18, v10, 16, 1
	s_waitcnt lgkmcnt(6)
	v_bfe_u32 v17, v22, 16, 1
	v_add3_u32 v17, v22, v17, s53
	v_lshrrev_b32_e32 v17, 16, v17
	v_add3_u32 v10, v10, v18, s53
	v_and_or_b32 v18, v10, s77, v17
	s_waitcnt lgkmcnt(5)
	v_bfe_u32 v10, v24, 16, 1
	v_add3_u32 v10, v24, v10, s53
	s_waitcnt lgkmcnt(4)
	v_bfe_u32 v17, v26, 16, 1
	v_lshrrev_b32_e32 v10, 16, v10
	v_add3_u32 v17, v26, v17, s53
	v_and_or_b32 v19, v17, s77, v10
	s_waitcnt lgkmcnt(3)
	v_bfe_u32 v10, v28, 16, 1
	v_add3_u32 v10, v28, v10, s53
	s_waitcnt lgkmcnt(2)
	v_bfe_u32 v17, v30, 16, 1
	v_lshrrev_b32_e32 v10, 16, v10
	v_add3_u32 v17, v30, v17, s53
	v_and_or_b32 v20, v17, s77, v10
	s_waitcnt lgkmcnt(1)
	v_bfe_u32 v10, v32, 16, 1
	v_add3_u32 v10, v32, v10, s53
	s_waitcnt lgkmcnt(0)
	v_bfe_u32 v17, v34, 16, 1
	v_lshrrev_b32_e32 v10, 16, v10
	v_add3_u32 v17, v34, v17, s53
	v_and_or_b32 v21, v17, s77, v10
	v_or_b32_e32 v10, s2, v15
	v_lshlrev_b32_e32 v202, 13, v10
	v_bfe_u32 v10, v23, 16, 1
	v_add3_u32 v10, v23, v10, s53
	v_bfe_u32 v17, v11, 16, 1
	v_lshl_add_u64 v[36:37], v[8:9], 0, v[202:203]
	v_lshrrev_b32_e32 v10, 16, v10
	v_add3_u32 v11, v11, v17, s53
	global_store_dwordx4 v[36:37], v[18:21], off nt
	v_readlane_b32 s22, v251, 36
	v_readlane_b32 s23, v251, 37
	v_and_or_b32 v18, v11, s77, v10
	v_bfe_u32 v10, v25, 16, 1
	v_add3_u32 v10, v25, v10, s53
	v_bfe_u32 v11, v27, 16, 1
	v_lshrrev_b32_e32 v10, 16, v10
	v_add3_u32 v11, v27, v11, s53
	v_and_or_b32 v19, v11, s77, v10
	v_bfe_u32 v10, v29, 16, 1
	v_add3_u32 v10, v29, v10, s53
	v_bfe_u32 v11, v31, 16, 1
	v_lshrrev_b32_e32 v10, 16, v10
	v_add3_u32 v11, v31, v11, s53
	v_and_or_b32 v20, v11, s77, v10
	v_bfe_u32 v10, v33, 16, 1
	v_add3_u32 v10, v33, v10, s53
	v_bfe_u32 v11, v35, 16, 1
	v_lshrrev_b32_e32 v10, 16, v10
	v_add3_u32 v11, v35, v11, s53
	v_and_or_b32 v21, v11, s77, v10
	v_or_b32_e32 v10, s2, v16
	v_lshlrev_b32_e32 v202, 13, v10
	v_lshl_add_u64 v[8:9], v[8:9], 0, v[202:203]
	global_store_dwordx4 v[8:9], v[18:21], off nt
	s_waitcnt lgkmcnt(0)
	v_readlane_b32 s24, v251, 38
	v_readlane_b32 s25, v251, 39
	v_readlane_b32 s26, v251, 40
	v_readlane_b32 s27, v251, 41
	v_readlane_b32 s28, v251, 42
	v_readlane_b32 s29, v251, 43
	v_readlane_b32 s30, v251, 44
	v_readlane_b32 s31, v251, 45
	s_mov_b64 s[10:11], s[18:19]

.LBB0_527:
	s_andn2_b64 vcc, exec, s[2:3]
	s_cbranch_vccnz .LBB0_476
	s_ashr_i32 s0, s4, 31
	s_lshr_b32 s0, s0, 19
	s_add_i32 s1, s4, s0
	s_ashr_i32 s0, s1, 13
	s_and_b32 s1, s1, 0xe000
	s_sub_i32 s4, s4, s1
	s_ashr_i32 s1, s0, 31
	v_readlane_b32 s16, v251, 14
	s_lshl_b64 s[2:3], s[0:1], 26
	v_readlane_b32 s22, v251, 20
	v_readlane_b32 s23, v251, 21
	s_add_u32 s5, s22, s2
	s_addc_u32 s9, s23, s3
	s_lshl_b64 s[0:1], s[0:1], 25
	v_readlane_b32 s2, v251, 60
	s_add_u32 s7, s2, s0
	v_readlane_b32 s0, v251, 61
	s_addc_u32 s8, s0, s1
	s_sext_i32_i16 s0, s4
	s_bfe_u32 s0, s0, 0x80017
	s_add_i32 s0, s4, s0
	s_sext_i32_i16 s1, s0
	s_and_b32 s0, s0, 0xff00
	s_sub_i32 s0, s4, s0
	s_sext_i32_i16 s0, s0
	s_lshl_b32 s2, s0, 5
	s_ashr_i32 s1, s1, 8
	s_ashr_i32 s3, s2, 31
	s_lshl_b32 s4, s1, 6
	s_lshl_b64 s[0:1], s[2:3], 2
	v_or_b32_e32 v8, s4, v3
	s_add_u32 s0, s5, s0
	s_addc_u32 s1, s9, s1
	v_lshlrev_b32_e32 v202, 2, v2
	v_ashrrev_i32_e32 v9, 31, v8
	v_lshl_add_u64 v[10:11], s[0:1], 0, v[202:203]
	v_lshlrev_b64 v[18:19], 15, v[8:9]
	v_lshl_add_u64 v[18:19], v[10:11], 0, v[18:19]
	global_load_dword v17, v[18:19], off nt
	v_or_b32_e32 v18, 2, v8
	v_ashrrev_i32_e32 v19, 31, v18
	v_lshlrev_b64 v[18:19], 15, v[18:19]
	v_lshl_add_u64 v[18:19], v[10:11], 0, v[18:19]
	global_load_dword v20, v[18:19], off nt
	v_or_b32_e32 v18, 4, v8
	v_ashrrev_i32_e32 v19, 31, v18
	v_lshlrev_b64 v[18:19], 15, v[18:19]
	v_lshl_add_u64 v[18:19], v[10:11], 0, v[18:19]
	global_load_dword v21, v[18:19], off nt
	v_or_b32_e32 v18, 6, v8
	v_ashrrev_i32_e32 v19, 31, v18
	v_lshlrev_b64 v[18:19], 15, v[18:19]
	v_lshl_add_u64 v[18:19], v[10:11], 0, v[18:19]
	global_load_dword v22, v[18:19], off nt
	v_or_b32_e32 v18, 8, v8
	v_ashrrev_i32_e32 v19, 31, v18
	v_lshlrev_b64 v[18:19], 15, v[18:19]
	v_lshl_add_u64 v[18:19], v[10:11], 0, v[18:19]
	global_load_dword v23, v[18:19], off nt
	v_or_b32_e32 v18, 10, v8
	v_ashrrev_i32_e32 v19, 31, v18
	v_lshlrev_b64 v[18:19], 15, v[18:19]
	v_lshl_add_u64 v[18:19], v[10:11], 0, v[18:19]
	global_load_dword v24, v[18:19], off nt
	v_or_b32_e32 v18, 12, v8
	v_ashrrev_i32_e32 v19, 31, v18
	v_lshlrev_b64 v[18:19], 15, v[18:19]
	v_lshl_add_u64 v[18:19], v[10:11], 0, v[18:19]
	global_load_dword v25, v[18:19], off nt
	v_or_b32_e32 v18, 14, v8
	v_ashrrev_i32_e32 v19, 31, v18
	v_lshlrev_b64 v[18:19], 15, v[18:19]
	v_lshl_add_u64 v[18:19], v[10:11], 0, v[18:19]
	global_load_dword v26, v[18:19], off nt
	v_or_b32_e32 v18, 16, v8
	v_ashrrev_i32_e32 v19, 31, v18
	v_lshlrev_b64 v[18:19], 15, v[18:19]
	v_lshl_add_u64 v[18:19], v[10:11], 0, v[18:19]
	global_load_dword v27, v[18:19], off nt
	v_or_b32_e32 v18, 18, v8
	v_ashrrev_i32_e32 v19, 31, v18
	v_lshlrev_b64 v[18:19], 15, v[18:19]
	v_lshl_add_u64 v[18:19], v[10:11], 0, v[18:19]
	global_load_dword v28, v[18:19], off nt
	v_or_b32_e32 v18, 20, v8
	v_ashrrev_i32_e32 v19, 31, v18
	v_lshlrev_b64 v[18:19], 15, v[18:19]
	v_lshl_add_u64 v[18:19], v[10:11], 0, v[18:19]
	global_load_dword v29, v[18:19], off nt
	v_or_b32_e32 v18, 22, v8
	v_ashrrev_i32_e32 v19, 31, v18
	v_lshlrev_b64 v[18:19], 15, v[18:19]
	v_lshl_add_u64 v[18:19], v[10:11], 0, v[18:19]
	global_load_dword v30, v[18:19], off nt
	v_or_b32_e32 v18, 24, v8
	v_ashrrev_i32_e32 v19, 31, v18
	v_lshlrev_b64 v[18:19], 15, v[18:19]
	v_lshl_add_u64 v[18:19], v[10:11], 0, v[18:19]
	global_load_dword v31, v[18:19], off nt
	v_or_b32_e32 v18, 26, v8
	v_ashrrev_i32_e32 v19, 31, v18
	v_lshlrev_b64 v[18:19], 15, v[18:19]
	v_lshl_add_u64 v[18:19], v[10:11], 0, v[18:19]
	global_load_dword v32, v[18:19], off nt
	v_or_b32_e32 v18, 28, v8
	v_ashrrev_i32_e32 v19, 31, v18
	v_lshlrev_b64 v[18:19], 15, v[18:19]
	v_lshl_add_u64 v[18:19], v[10:11], 0, v[18:19]
	global_load_dword v33, v[18:19], off nt
	v_or_b32_e32 v18, 30, v8
	v_ashrrev_i32_e32 v19, 31, v18
	v_lshlrev_b64 v[18:19], 15, v[18:19]
	v_lshl_add_u64 v[18:19], v[10:11], 0, v[18:19]
	global_load_dword v34, v[18:19], off nt
	v_or_b32_e32 v18, 32, v8
	v_ashrrev_i32_e32 v19, 31, v18
	v_lshlrev_b64 v[18:19], 15, v[18:19]
	v_lshl_add_u64 v[18:19], v[10:11], 0, v[18:19]
	global_load_dword v35, v[18:19], off nt
	v_or_b32_e32 v18, 34, v8
	v_ashrrev_i32_e32 v19, 31, v18
	v_lshlrev_b64 v[18:19], 15, v[18:19]
	v_lshl_add_u64 v[18:19], v[10:11], 0, v[18:19]
	global_load_dword v36, v[18:19], off nt
	v_or_b32_e32 v18, 36, v8
	v_ashrrev_i32_e32 v19, 31, v18
	v_lshlrev_b64 v[18:19], 15, v[18:19]
	v_lshl_add_u64 v[18:19], v[10:11], 0, v[18:19]
	global_load_dword v37, v[18:19], off nt
	v_or_b32_e32 v18, 38, v8
	v_ashrrev_i32_e32 v19, 31, v18
	v_lshlrev_b64 v[18:19], 15, v[18:19]
	v_lshl_add_u64 v[18:19], v[10:11], 0, v[18:19]
	global_load_dword v38, v[18:19], off nt
	v_or_b32_e32 v18, 40, v8
	v_ashrrev_i32_e32 v19, 31, v18
	v_lshlrev_b64 v[18:19], 15, v[18:19]
	v_lshl_add_u64 v[18:19], v[10:11], 0, v[18:19]
	global_load_dword v39, v[18:19], off nt
	v_or_b32_e32 v18, 42, v8
	v_ashrrev_i32_e32 v19, 31, v18
	v_lshlrev_b64 v[18:19], 15, v[18:19]
	v_lshl_add_u64 v[18:19], v[10:11], 0, v[18:19]
	global_load_dword v40, v[18:19], off nt
	v_or_b32_e32 v18, 44, v8
	v_ashrrev_i32_e32 v19, 31, v18
	v_lshlrev_b64 v[18:19], 15, v[18:19]
	v_lshl_add_u64 v[18:19], v[10:11], 0, v[18:19]
	global_load_dword v41, v[18:19], off nt
	v_or_b32_e32 v18, 46, v8
	v_ashrrev_i32_e32 v19, 31, v18
	v_lshlrev_b64 v[18:19], 15, v[18:19]
	v_lshl_add_u64 v[18:19], v[10:11], 0, v[18:19]
	global_load_dword v42, v[18:19], off nt
	v_or_b32_e32 v18, 48, v8
	v_ashrrev_i32_e32 v19, 31, v18
	v_lshlrev_b64 v[18:19], 15, v[18:19]
	v_lshl_add_u64 v[18:19], v[10:11], 0, v[18:19]
	global_load_dword v43, v[18:19], off nt
	v_or_b32_e32 v18, 50, v8
	v_ashrrev_i32_e32 v19, 31, v18
	v_lshlrev_b64 v[18:19], 15, v[18:19]
	v_lshl_add_u64 v[18:19], v[10:11], 0, v[18:19]
	global_load_dword v44, v[18:19], off nt
	v_or_b32_e32 v18, 52, v8
	v_ashrrev_i32_e32 v19, 31, v18
	v_lshlrev_b64 v[18:19], 15, v[18:19]
	v_lshl_add_u64 v[18:19], v[10:11], 0, v[18:19]
	global_load_dword v45, v[18:19], off nt
	v_or_b32_e32 v18, 54, v8
	v_ashrrev_i32_e32 v19, 31, v18
	v_lshlrev_b64 v[18:19], 15, v[18:19]
	v_lshl_add_u64 v[18:19], v[10:11], 0, v[18:19]
	global_load_dword v46, v[18:19], off nt
	v_or_b32_e32 v18, 56, v8
	v_ashrrev_i32_e32 v19, 31, v18
	v_lshlrev_b64 v[18:19], 15, v[18:19]
	v_lshl_add_u64 v[18:19], v[10:11], 0, v[18:19]
	global_load_dword v47, v[18:19], off nt
	v_or_b32_e32 v18, 58, v8
	v_ashrrev_i32_e32 v19, 31, v18
	v_lshlrev_b64 v[18:19], 15, v[18:19]
	v_lshl_add_u64 v[18:19], v[10:11], 0, v[18:19]
	global_load_dword v48, v[18:19], off nt
	v_or_b32_e32 v18, 60, v8
	v_or_b32_e32 v8, 62, v8
	v_ashrrev_i32_e32 v19, 31, v18
	v_ashrrev_i32_e32 v9, 31, v8
	v_lshlrev_b64 v[18:19], 15, v[18:19]
	v_lshlrev_b64 v[8:9], 15, v[8:9]
	v_lshl_add_u64 v[18:19], v[10:11], 0, v[18:19]
	v_lshl_add_u64 v[8:9], v[10:11], 0, v[8:9]
	global_load_dword v18, v[18:19], off nt
	s_ashr_i32 s5, s4, 31
	global_load_dword v8, v[8:9], off nt
	v_add_u32_e32 v9, 0x400, v5
	s_waitcnt vmcnt(0)
	ds_write2_b32 v5, v17, v20 offset1:66
	ds_write2_b32 v5, v21, v22 offset0:132 offset1:198
	ds_write2_b32 v9, v23, v24 offset0:8 offset1:74
	ds_write2_b32 v9, v25, v26 offset0:140 offset1:206
	v_add_u32_e32 v9, 0x800, v5
	ds_write2_b32 v9, v27, v28 offset0:16 offset1:82
	ds_write2_b32 v9, v29, v30 offset0:148 offset1:214
	v_add_u32_e32 v9, 0xc00, v5
	ds_write2_b32 v9, v31, v32 offset0:24 offset1:90
	ds_write2_b32 v9, v33, v34 offset0:156 offset1:222
	v_add_u32_e32 v9, 0x1000, v5
	ds_write2_b32 v9, v35, v36 offset0:32 offset1:98
	ds_write2_b32 v9, v37, v38 offset0:164 offset1:230
	v_add_u32_e32 v9, 0x1400, v5
	ds_write2_b32 v9, v39, v40 offset0:40 offset1:106
	ds_write2_b32 v9, v41, v42 offset0:172 offset1:238
	v_add_u32_e32 v9, 0x1800, v5
	ds_write2_b32 v9, v43, v44 offset0:48 offset1:114
	ds_write2_b32 v9, v45, v46 offset0:180 offset1:246
	v_add_u32_e32 v9, 0x1c00, v5
	ds_write2_b32 v9, v47, v48 offset0:56 offset1:122
	ds_write2_b32 v9, v18, v8 offset0:188 offset1:254
	s_waitcnt lgkmcnt(0)
	ds_read2_b32 v[10:11], v13 offset0:33 offset1:41
	ds_read2_b32 v[22:23], v13 offset1:8
	ds_read2_b32 v[24:25], v13 offset0:66 offset1:74
	ds_read2_b32 v[26:27], v13 offset0:99 offset1:107
	ds_read2_b32 v[28:29], v13 offset0:132 offset1:140
	ds_read2_b32 v[30:31], v13 offset0:165 offset1:173
	ds_read2_b32 v[32:33], v13 offset0:198 offset1:206
	ds_read2_b32 v[34:35], v13 offset0:231 offset1:239
	s_waitcnt lgkmcnt(7)
	v_bfe_u32 v18, v10, 16, 1
	s_waitcnt lgkmcnt(6)
	v_bfe_u32 v17, v22, 16, 1
	v_add3_u32 v17, v22, v17, s53
	v_lshrrev_b32_e32 v17, 16, v17
	v_add3_u32 v10, v10, v18, s53
	v_and_or_b32 v18, v10, s77, v17
	s_waitcnt lgkmcnt(5)
	v_bfe_u32 v10, v24, 16, 1
	v_add3_u32 v10, v24, v10, s53
	s_waitcnt lgkmcnt(4)
	v_bfe_u32 v17, v26, 16, 1
	v_lshrrev_b32_e32 v10, 16, v10
	v_add3_u32 v17, v26, v17, s53
	v_and_or_b32 v19, v17, s77, v10
	s_waitcnt lgkmcnt(3)
	v_bfe_u32 v10, v28, 16, 1
	v_add3_u32 v10, v28, v10, s53
	s_waitcnt lgkmcnt(2)
	v_bfe_u32 v17, v30, 16, 1
	v_lshrrev_b32_e32 v10, 16, v10
	v_add3_u32 v17, v30, v17, s53
	v_and_or_b32 v20, v17, s77, v10
	s_waitcnt lgkmcnt(1)
	v_bfe_u32 v10, v32, 16, 1
	s_lshl_b64 s[0:1], s[4:5], 1
	v_add3_u32 v10, v32, v10, s53
	s_waitcnt lgkmcnt(0)
	v_bfe_u32 v17, v34, 16, 1
	s_add_u32 s0, s7, s0
	v_lshrrev_b32_e32 v10, 16, v10
	v_add3_u32 v17, v34, v17, s53
	v_or_b32_e32 v36, s2, v12
	s_addc_u32 s1, s8, s1
	v_lshlrev_b32_e32 v202, 1, v4
	v_and_or_b32 v21, v17, s77, v10
	v_ashrrev_i32_e32 v37, 31, v36
	v_bfe_u32 v10, v23, 16, 1
	v_lshl_add_u64 v[8:9], s[0:1], 0, v[202:203]
	v_lshlrev_b64 v[36:37], 12, v[36:37]
	v_add3_u32 v10, v23, v10, s53
	v_bfe_u32 v17, v11, 16, 1
	v_lshl_add_u64 v[36:37], v[8:9], 0, v[36:37]
	v_lshrrev_b32_e32 v10, 16, v10
	v_add3_u32 v11, v11, v17, s53
	global_store_dwordx4 v[36:37], v[18:21], off nt
	v_or_b32_e32 v36, s2, v15
	v_ashrrev_i32_e32 v37, 31, v36
	v_and_or_b32 v18, v11, s77, v10
	v_bfe_u32 v10, v25, 16, 1
	v_add3_u32 v10, v25, v10, s53
	v_bfe_u32 v11, v27, 16, 1
	v_lshrrev_b32_e32 v10, 16, v10
	v_add3_u32 v11, v27, v11, s53
	v_and_or_b32 v19, v11, s77, v10
	v_bfe_u32 v10, v29, 16, 1
	v_add3_u32 v10, v29, v10, s53
	v_bfe_u32 v11, v31, 16, 1
	v_lshrrev_b32_e32 v10, 16, v10
	v_add3_u32 v11, v31, v11, s53
	v_and_or_b32 v20, v11, s77, v10
	v_bfe_u32 v10, v33, 16, 1
	v_add3_u32 v10, v33, v10, s53
	v_bfe_u32 v11, v35, 16, 1
	v_lshrrev_b32_e32 v10, 16, v10
	v_add3_u32 v11, v35, v11, s53
	v_and_or_b32 v21, v11, s77, v10
	v_or_b32_e32 v10, s2, v14
	v_ashrrev_i32_e32 v11, 31, v10
	v_lshlrev_b64 v[10:11], 12, v[10:11]
	v_lshl_add_u64 v[10:11], v[8:9], 0, v[10:11]
	global_store_dwordx4 v[10:11], v[18:21], off nt
	ds_read2_b32 v[10:11], v13 offset0:49 offset1:57
	ds_read2_b32 v[22:23], v13 offset0:16 offset1:24
	ds_read2_b32 v[24:25], v13 offset0:82 offset1:90
	ds_read2_b32 v[26:27], v13 offset0:115 offset1:123
	ds_read2_b32 v[28:29], v13 offset0:148 offset1:156
	ds_read2_b32 v[30:31], v13 offset0:181 offset1:189
	ds_read2_b32 v[32:33], v13 offset0:214 offset1:222
	ds_read2_b32 v[34:35], v13 offset0:247 offset1:255
	s_waitcnt lgkmcnt(7)
	v_bfe_u32 v18, v10, 16, 1
	s_waitcnt lgkmcnt(6)
	v_bfe_u32 v17, v22, 16, 1
	v_add3_u32 v17, v22, v17, s53
	v_lshrrev_b32_e32 v17, 16, v17
	v_add3_u32 v10, v10, v18, s53
	v_and_or_b32 v18, v10, s77, v17
	s_waitcnt lgkmcnt(5)
	v_bfe_u32 v10, v24, 16, 1
	v_add3_u32 v10, v24, v10, s53
	s_waitcnt lgkmcnt(4)
	v_bfe_u32 v17, v26, 16, 1
	v_lshrrev_b32_e32 v10, 16, v10
	v_add3_u32 v17, v26, v17, s53
	v_and_or_b32 v19, v17, s77, v10
	s_waitcnt lgkmcnt(3)
	v_bfe_u32 v10, v28, 16, 1
	v_add3_u32 v10, v28, v10, s53
	s_waitcnt lgkmcnt(2)
	v_bfe_u32 v17, v30, 16, 1
	v_lshrrev_b32_e32 v10, 16, v10
	v_add3_u32 v17, v30, v17, s53
	v_and_or_b32 v20, v17, s77, v10
	s_waitcnt lgkmcnt(1)
	v_bfe_u32 v10, v32, 16, 1
	v_add3_u32 v10, v32, v10, s53
	s_waitcnt lgkmcnt(0)
	v_bfe_u32 v17, v34, 16, 1
	v_lshrrev_b32_e32 v10, 16, v10
	v_add3_u32 v17, v34, v17, s53
	v_and_or_b32 v21, v17, s77, v10
	v_bfe_u32 v10, v23, 16, 1
	v_lshlrev_b64 v[36:37], 12, v[36:37]
	v_add3_u32 v10, v23, v10, s53
	v_bfe_u32 v17, v11, 16, 1
	v_lshl_add_u64 v[36:37], v[8:9], 0, v[36:37]
	v_lshrrev_b32_e32 v10, 16, v10
	v_add3_u32 v11, v11, v17, s53
	global_store_dwordx4 v[36:37], v[18:21], off nt
	v_readlane_b32 s17, v251, 15
	v_readlane_b32 s18, v251, 16
	v_and_or_b32 v18, v11, s77, v10
	v_bfe_u32 v10, v25, 16, 1
	v_add3_u32 v10, v25, v10, s53
	v_bfe_u32 v11, v27, 16, 1
	v_lshrrev_b32_e32 v10, 16, v10
	v_add3_u32 v11, v27, v11, s53
	v_and_or_b32 v19, v11, s77, v10
	v_bfe_u32 v10, v29, 16, 1
	v_add3_u32 v10, v29, v10, s53
	v_bfe_u32 v11, v31, 16, 1
	v_lshrrev_b32_e32 v10, 16, v10
	v_add3_u32 v11, v31, v11, s53
	v_and_or_b32 v20, v11, s77, v10
	v_bfe_u32 v10, v33, 16, 1
	v_add3_u32 v10, v33, v10, s53
	v_bfe_u32 v11, v35, 16, 1
	v_lshrrev_b32_e32 v10, 16, v10
	v_add3_u32 v11, v35, v11, s53
	v_and_or_b32 v21, v11, s77, v10
	v_or_b32_e32 v10, s2, v16
	v_ashrrev_i32_e32 v11, 31, v10
	v_lshlrev_b64 v[10:11], 12, v[10:11]
	v_lshl_add_u64 v[8:9], v[8:9], 0, v[10:11]
	global_store_dwordx4 v[8:9], v[18:21], off nt
	s_waitcnt lgkmcnt(0)
	v_readlane_b32 s19, v251, 17
	v_readlane_b32 s20, v251, 18
	v_readlane_b32 s21, v251, 19
	v_readlane_b32 s24, v251, 22
	v_readlane_b32 s25, v251, 23
	v_readlane_b32 s26, v251, 24
	v_readlane_b32 s27, v251, 25
	v_readlane_b32 s28, v251, 26
	v_readlane_b32 s29, v251, 27
	v_readlane_b32 s30, v251, 28
	v_readlane_b32 s31, v251, 29
	s_branch .LBB0_476

.LBB0_885:
	s_cmpk_gt_i32 s4, 0x3fff
	s_mov_b64 s[2:3], -1
	s_cbranch_scc0 .LBB0_906
	s_cmpk_gt_u32 s4, 0x5fff
	s_cbranch_scc0 .LBB0_903
	s_cmp_gt_u32 s4, 0x167ff
	s_cbranch_scc0 .LBB0_893
	s_cmp_gt_u32 s4, 0x177ff
	s_cbranch_scc0 .LBB0_890
	s_add_i32 s0, s4, 0xfffe8800
	v_readlane_b32 s16, v251, 6
	s_lshr_b32 s86, s0, 12
	v_readlane_b32 s20, v251, 10
	v_readlane_b32 s21, v251, 11
	s_bfe_u32 s2, s0, 0x1000b
	s_lshl_b64 s[0:1], s[86:87], 25
	v_readlane_b32 s22, v251, 12
	v_readlane_b32 s23, v251, 13
	s_mov_b64 s[8:9], s[20:21]
	s_add_u32 s0, s8, s0
	s_addc_u32 s1, s9, s1
	s_lshl_b32 s3, s2, 13
	s_mov_b64 s[10:11], s[22:23]
	s_add_u32 s8, s0, s3
	s_addc_u32 s9, s1, 0
	s_lshl_b64 s[0:1], s[86:87], 24
	v_readlane_b32 s10, v251, 50
	v_readlane_b32 s11, v251, 51
	s_add_u32 s3, s10, s0
	s_addc_u32 s5, s11, s1
	s_lshl_b32 s1, s4, 5
	s_lshl_b32 s10, s4, 6
	s_and_b32 s1, s1, 0x60
	s_lshl_b32 s2, s2, 7
	s_and_b32 s0, s4, 63
	s_and_b32 s10, s10, 0xf00
	s_or_b32 s1, s2, s1
	s_and_b32 s7, s4, 0x7c0
	s_or_b32 s2, s1, s10
	s_lshl_b32 s0, s0, 7
	s_add_u32 s0, s8, s0
	v_or_b32_e32 v8, s7, v3
	s_addc_u32 s1, s9, 0
	v_lshlrev_b32_e32 v202, 2, v2
	v_lshl_add_u64 v[6:7], s[0:1], 0, v[202:203]
	v_lshlrev_b32_e32 v202, 14, v8
	v_lshl_add_u64 v[6:7], v[6:7], 0, v[202:203]
	s_mov_b32 s0, 0x8000
	v_add_co_u32_e32 v8, vcc, s0, v6
	s_mov_b32 s0, 0x10000
	s_nop 0
	v_addc_co_u32_e32 v9, vcc, 0, v7, vcc
	global_load_dword v15, v[6:7], off nt
	global_load_dword v16, v[8:9], off nt
	v_add_co_u32_e32 v8, vcc, s0, v6
	s_mov_b32 s0, 0x18000
	s_nop 0
	v_addc_co_u32_e32 v9, vcc, 0, v7, vcc
	global_load_dword v17, v[8:9], off nt
	v_add_co_u32_e32 v8, vcc, s0, v6
	s_mov_b32 s0, 0x28000
	s_nop 0
	v_addc_co_u32_e32 v9, vcc, 0, v7, vcc
	global_load_dword v18, v[8:9], off nt
	v_add_co_u32_e32 v8, vcc, s57, v6
	v_lshlrev_b32_e32 v202, 1, v4
	s_nop 0
	v_addc_co_u32_e32 v9, vcc, 0, v7, vcc
	global_load_dword v19, v[8:9], off nt
	v_add_co_u32_e32 v8, vcc, s0, v6
	s_mov_b32 s0, 0x30000
	s_nop 0
	v_addc_co_u32_e32 v9, vcc, 0, v7, vcc
	global_load_dword v20, v[8:9], off nt
	v_add_co_u32_e32 v8, vcc, s0, v6
	s_mov_b32 s0, 0x38000
	s_nop 0
	v_addc_co_u32_e32 v9, vcc, 0, v7, vcc
	global_load_dword v21, v[8:9], off nt
	v_add_co_u32_e32 v8, vcc, s0, v6
	s_mov_b32 s0, 0x48000
	s_nop 0
	v_addc_co_u32_e32 v9, vcc, 0, v7, vcc
	global_load_dword v22, v[8:9], off nt
	v_add_co_u32_e32 v8, vcc, s88, v6
	v_readlane_b32 s17, v251, 7
	s_nop 0
	v_addc_co_u32_e32 v9, vcc, 0, v7, vcc
	global_load_dword v23, v[8:9], off nt
	v_add_co_u32_e32 v8, vcc, s0, v6
	s_mov_b32 s0, 0x50000
	s_nop 0
	v_addc_co_u32_e32 v9, vcc, 0, v7, vcc
	global_load_dword v24, v[8:9], off nt
	v_add_co_u32_e32 v8, vcc, s0, v6
	s_mov_b32 s0, 0x58000
	s_nop 0
	v_addc_co_u32_e32 v9, vcc, 0, v7, vcc
	global_load_dword v25, v[8:9], off nt
	v_add_co_u32_e32 v8, vcc, s0, v6
	s_mov_b32 s0, 0x60000
	s_nop 0
	v_addc_co_u32_e32 v9, vcc, 0, v7, vcc
	global_load_dword v26, v[8:9], off nt
	v_add_co_u32_e32 v8, vcc, s0, v6
	s_mov_b32 s0, 0x68000
	s_nop 0
	v_addc_co_u32_e32 v9, vcc, 0, v7, vcc
	global_load_dword v27, v[8:9], off nt
	v_add_co_u32_e32 v8, vcc, s0, v6
	s_mov_b32 s0, 0x70000
	s_nop 0
	v_addc_co_u32_e32 v9, vcc, 0, v7, vcc
	global_load_dword v28, v[8:9], off nt
	v_add_co_u32_e32 v8, vcc, s0, v6
	s_mov_b32 s0, 0x78000
	s_nop 0
	v_addc_co_u32_e32 v9, vcc, 0, v7, vcc
	global_load_dword v29, v[8:9], off nt
	v_add_co_u32_e32 v8, vcc, s0, v6
	s_mov_b32 s0, 0x80000
	s_nop 0
	v_addc_co_u32_e32 v9, vcc, 0, v7, vcc
	global_load_dword v30, v[8:9], off nt
	v_add_co_u32_e32 v8, vcc, s0, v6
	s_mov_b32 s0, 0x88000
	s_nop 0
	v_addc_co_u32_e32 v9, vcc, 0, v7, vcc
	global_load_dword v31, v[8:9], off nt
	v_add_co_u32_e32 v8, vcc, s0, v6
	s_mov_b32 s0, 0x90000
	s_nop 0
	v_addc_co_u32_e32 v9, vcc, 0, v7, vcc
	global_load_dword v32, v[8:9], off nt
	v_add_co_u32_e32 v8, vcc, s0, v6
	s_mov_b32 s0, 0x98000
	s_nop 0
	v_addc_co_u32_e32 v9, vcc, 0, v7, vcc
	global_load_dword v33, v[8:9], off nt
	v_add_co_u32_e32 v8, vcc, s0, v6
	s_mov_b32 s0, 0xa0000
	s_nop 0
	v_addc_co_u32_e32 v9, vcc, 0, v7, vcc
	global_load_dword v34, v[8:9], off nt
	v_add_co_u32_e32 v8, vcc, s0, v6
	s_mov_b32 s0, 0xa8000
	s_nop 0
	v_addc_co_u32_e32 v9, vcc, 0, v7, vcc
	global_load_dword v35, v[8:9], off nt
	v_add_co_u32_e32 v8, vcc, s0, v6
	s_mov_b32 s0, 0xb0000
	s_nop 0
	v_addc_co_u32_e32 v9, vcc, 0, v7, vcc
	global_load_dword v36, v[8:9], off nt
	v_add_co_u32_e32 v8, vcc, s0, v6
	s_mov_b32 s0, 0xb8000
	s_nop 0
	v_addc_co_u32_e32 v9, vcc, 0, v7, vcc
	global_load_dword v37, v[8:9], off nt
	v_add_co_u32_e32 v8, vcc, s0, v6
	s_mov_b32 s0, 0xc0000
	s_nop 0
	v_addc_co_u32_e32 v9, vcc, 0, v7, vcc
	global_load_dword v38, v[8:9], off nt
	v_add_co_u32_e32 v8, vcc, s0, v6
	s_mov_b32 s0, 0xc8000
	s_nop 0
	v_addc_co_u32_e32 v9, vcc, 0, v7, vcc
	global_load_dword v39, v[8:9], off nt
	v_add_co_u32_e32 v8, vcc, s0, v6
	s_mov_b32 s0, 0xd0000
	s_nop 0
	v_addc_co_u32_e32 v9, vcc, 0, v7, vcc
	global_load_dword v40, v[8:9], off nt
	v_add_co_u32_e32 v8, vcc, s0, v6
	s_mov_b32 s0, 0xd8000
	s_nop 0
	v_addc_co_u32_e32 v9, vcc, 0, v7, vcc
	global_load_dword v41, v[8:9], off nt
	v_add_co_u32_e32 v8, vcc, s0, v6
	s_mov_b32 s0, 0xe0000
	s_nop 0
	v_addc_co_u32_e32 v9, vcc, 0, v7, vcc
	global_load_dword v42, v[8:9], off nt
	v_add_co_u32_e32 v8, vcc, s0, v6
	s_mov_b32 s0, 0xe8000
	s_nop 0
	v_addc_co_u32_e32 v9, vcc, 0, v7, vcc
	global_load_dword v43, v[8:9], off nt
	v_add_co_u32_e32 v8, vcc, s0, v6
	s_mov_b32 s0, 0xf0000
	s_nop 0
	v_addc_co_u32_e32 v9, vcc, 0, v7, vcc
	global_load_dword v44, v[8:9], off nt
	v_add_co_u32_e32 v8, vcc, s0, v6
	s_mov_b32 s0, 0xf8000
	s_nop 0
	v_addc_co_u32_e32 v9, vcc, 0, v7, vcc
	v_add_co_u32_e32 v6, vcc, s0, v6
	global_load_dword v8, v[8:9], off nt
	s_nop 0
	v_addc_co_u32_e32 v7, vcc, 0, v7, vcc
	global_load_dword v6, v[6:7], off nt
	v_add_u32_e32 v7, 0x400, v5
	s_waitcnt vmcnt(0)
	ds_write2_b32 v5, v15, v16 offset1:66
	ds_write2_b32 v5, v17, v18 offset0:132 offset1:198
	ds_write2_b32 v7, v19, v20 offset0:8 offset1:74
	ds_write2_b32 v7, v21, v22 offset0:140 offset1:206
	v_add_u32_e32 v7, 0x800, v5
	ds_write2_b32 v7, v23, v24 offset0:16 offset1:82
	ds_write2_b32 v7, v25, v26 offset0:148 offset1:214
	v_add_u32_e32 v7, 0xc00, v5
	ds_write2_b32 v7, v27, v28 offset0:24 offset1:90
	ds_write2_b32 v7, v29, v30 offset0:156 offset1:222
	v_add_u32_e32 v7, 0x1000, v5
	ds_write2_b32 v7, v31, v32 offset0:32 offset1:98
	ds_write2_b32 v7, v33, v34 offset0:164 offset1:230
	v_add_u32_e32 v7, 0x1400, v5
	ds_write2_b32 v7, v35, v36 offset0:40 offset1:106
	ds_write2_b32 v7, v37, v38 offset0:172 offset1:238
	v_add_u32_e32 v7, 0x1800, v5
	ds_write2_b32 v7, v39, v40 offset0:48 offset1:114
	ds_write2_b32 v7, v41, v42 offset0:180 offset1:246
	v_add_u32_e32 v7, 0x1c00, v5
	ds_write2_b32 v7, v43, v44 offset0:56 offset1:122
	ds_write2_b32 v7, v8, v6 offset0:188 offset1:254
	s_waitcnt lgkmcnt(0)
	ds_read2_b32 v[8:9], v11 offset0:33 offset1:41
	ds_read2_b32 v[20:21], v11 offset1:8
	ds_read2_b32 v[22:23], v11 offset0:66 offset1:74
	ds_read2_b32 v[24:25], v11 offset0:99 offset1:107
	ds_read2_b32 v[26:27], v11 offset0:132 offset1:140
	ds_read2_b32 v[28:29], v11 offset0:165 offset1:173
	ds_read2_b32 v[30:31], v11 offset0:198 offset1:206
	ds_read2_b32 v[32:33], v11 offset0:231 offset1:239
	s_waitcnt lgkmcnt(7)
	v_bfe_u32 v16, v8, 16, 1
	s_waitcnt lgkmcnt(6)
	v_bfe_u32 v15, v20, 16, 1
	v_add3_u32 v15, v20, v15, s53
	v_lshrrev_b32_e32 v15, 16, v15
	v_add3_u32 v8, v8, v16, s53
	v_and_or_b32 v16, v8, s77, v15
	s_waitcnt lgkmcnt(5)
	v_bfe_u32 v8, v22, 16, 1
	v_add3_u32 v8, v22, v8, s53
	s_waitcnt lgkmcnt(4)
	v_bfe_u32 v15, v24, 16, 1
	v_lshrrev_b32_e32 v8, 16, v8
	v_add3_u32 v15, v24, v15, s53
	v_and_or_b32 v17, v15, s77, v8
	s_waitcnt lgkmcnt(3)
	v_bfe_u32 v8, v26, 16, 1
	v_add3_u32 v8, v26, v8, s53
	s_waitcnt lgkmcnt(2)
	v_bfe_u32 v15, v28, 16, 1
	v_lshrrev_b32_e32 v8, 16, v8
	v_add3_u32 v15, v28, v15, s53
	v_and_or_b32 v18, v15, s77, v8
	s_waitcnt lgkmcnt(1)
	v_bfe_u32 v8, v30, 16, 1
	s_lshl_b32 s0, s7, 1
	v_add3_u32 v8, v30, v8, s53
	s_waitcnt lgkmcnt(0)
	v_bfe_u32 v15, v32, 16, 1
	s_add_u32 s0, s3, s0
	v_lshrrev_b32_e32 v8, 16, v8
	v_add3_u32 v15, v32, v15, s53
	s_addc_u32 s1, s5, 0
	v_and_or_b32 v19, v15, s77, v8
	v_or_b32_e32 v8, s2, v10
	v_lshl_add_u64 v[6:7], s[0:1], 0, v[202:203]
	v_lshlrev_b32_e32 v202, 12, v8
	v_bfe_u32 v8, v21, 16, 1
	v_add3_u32 v8, v21, v8, s53
	v_bfe_u32 v15, v9, 16, 1
	v_lshl_add_u64 v[34:35], v[6:7], 0, v[202:203]
	v_lshrrev_b32_e32 v8, 16, v8
	v_add3_u32 v9, v9, v15, s53
	global_store_dwordx4 v[34:35], v[16:19], off nt
	v_readlane_b32 s18, v251, 8
	v_readlane_b32 s19, v251, 9
	v_and_or_b32 v16, v9, s77, v8
	v_bfe_u32 v8, v23, 16, 1
	v_add3_u32 v8, v23, v8, s53
	v_bfe_u32 v9, v25, 16, 1
	v_lshrrev_b32_e32 v8, 16, v8
	v_add3_u32 v9, v25, v9, s53
	v_and_or_b32 v17, v9, s77, v8
	v_bfe_u32 v8, v27, 16, 1
	v_add3_u32 v8, v27, v8, s53
	v_bfe_u32 v9, v29, 16, 1
	v_lshrrev_b32_e32 v8, 16, v8
	v_add3_u32 v9, v29, v9, s53
	v_and_or_b32 v18, v9, s77, v8
	v_bfe_u32 v8, v31, 16, 1
	v_add3_u32 v8, v31, v8, s53
	v_bfe_u32 v9, v33, 16, 1
	v_lshrrev_b32_e32 v8, 16, v8
	v_add3_u32 v9, v33, v9, s53
	v_and_or_b32 v19, v9, s77, v8
	v_or_b32_e32 v8, s2, v12
	v_lshlrev_b32_e32 v202, 12, v8
	v_lshl_add_u64 v[8:9], v[6:7], 0, v[202:203]
	global_store_dwordx4 v[8:9], v[16:19], off nt
	ds_read2_b32 v[8:9], v11 offset0:49 offset1:57
	ds_read2_b32 v[20:21], v11 offset0:16 offset1:24
	ds_read2_b32 v[22:23], v11 offset0:82 offset1:90
	ds_read2_b32 v[24:25], v11 offset0:115 offset1:123
	ds_read2_b32 v[26:27], v11 offset0:148 offset1:156
	ds_read2_b32 v[28:29], v11 offset0:181 offset1:189
	ds_read2_b32 v[30:31], v11 offset0:214 offset1:222
	ds_read2_b32 v[32:33], v11 offset0:247 offset1:255
	s_waitcnt lgkmcnt(7)
	v_bfe_u32 v16, v8, 16, 1
	s_waitcnt lgkmcnt(6)
	v_bfe_u32 v15, v20, 16, 1
	v_add3_u32 v15, v20, v15, s53
	v_lshrrev_b32_e32 v15, 16, v15
	v_add3_u32 v8, v8, v16, s53
	v_and_or_b32 v16, v8, s77, v15
	s_waitcnt lgkmcnt(5)
	v_bfe_u32 v8, v22, 16, 1
	v_add3_u32 v8, v22, v8, s53
	s_waitcnt lgkmcnt(4)
	v_bfe_u32 v15, v24, 16, 1
	v_lshrrev_b32_e32 v8, 16, v8
	v_add3_u32 v15, v24, v15, s53
	v_and_or_b32 v17, v15, s77, v8
	s_waitcnt lgkmcnt(3)
	v_bfe_u32 v8, v26, 16, 1
	v_add3_u32 v8, v26, v8, s53
	s_waitcnt lgkmcnt(2)
	v_bfe_u32 v15, v28, 16, 1
	v_lshrrev_b32_e32 v8, 16, v8
	v_add3_u32 v15, v28, v15, s53
	v_and_or_b32 v18, v15, s77, v8
	s_waitcnt lgkmcnt(1)
	v_bfe_u32 v8, v30, 16, 1
	v_add3_u32 v8, v30, v8, s53
	s_waitcnt lgkmcnt(0)
	v_bfe_u32 v15, v32, 16, 1
	v_lshrrev_b32_e32 v8, 16, v8
	v_add3_u32 v15, v32, v15, s53
	v_and_or_b32 v19, v15, s77, v8
	v_or_b32_e32 v8, s2, v13
	v_lshlrev_b32_e32 v202, 12, v8
	v_bfe_u32 v8, v21, 16, 1
	v_add3_u32 v8, v21, v8, s53
	v_bfe_u32 v15, v9, 16, 1
	v_lshl_add_u64 v[34:35], v[6:7], 0, v[202:203]
	v_lshrrev_b32_e32 v8, 16, v8
	v_add3_u32 v9, v9, v15, s53
	global_store_dwordx4 v[34:35], v[16:19], off nt
	s_nop 1
	v_and_or_b32 v16, v9, s77, v8
	v_bfe_u32 v8, v23, 16, 1
	v_add3_u32 v8, v23, v8, s53
	v_bfe_u32 v9, v25, 16, 1
	v_lshrrev_b32_e32 v8, 16, v8
	v_add3_u32 v9, v25, v9, s53
	v_and_or_b32 v17, v9, s77, v8
	v_bfe_u32 v8, v27, 16, 1
	v_add3_u32 v8, v27, v8, s53
	v_bfe_u32 v9, v29, 16, 1
	v_lshrrev_b32_e32 v8, 16, v8
	v_add3_u32 v9, v29, v9, s53
	v_and_or_b32 v18, v9, s77, v8
	v_bfe_u32 v8, v31, 16, 1
	v_add3_u32 v8, v31, v8, s53
	v_bfe_u32 v9, v33, 16, 1
	v_lshrrev_b32_e32 v8, 16, v8
	v_add3_u32 v9, v33, v9, s53
	v_and_or_b32 v19, v9, s77, v8
	v_or_b32_e32 v8, s2, v14
	v_lshlrev_b32_e32 v202, 12, v8
	v_lshl_add_u64 v[6:7], v[6:7], 0, v[202:203]
	global_store_dwordx4 v[6:7], v[16:19], off nt
	s_waitcnt lgkmcnt(0)
	s_mov_b64 s[2:3], 0
.LBB0_890:
	s_andn2_b64 vcc, exec, s[2:3]
	s_cbranch_vccnz .LBB0_892
	v_readlane_b32 s16, v251, 30
	s_and_b32 s0, s4, 0x1f800
	v_readlane_b32 s17, v251, 31
	s_add_i32 s86, s0, 0xfffe9800
	v_readlane_b32 s18, v251, 32
	v_readlane_b32 s19, v251, 33
	s_mov_b64 s[8:9], s[16:17]
	s_lshl_b64 s[0:1], s[86:87], 13
	s_mov_b64 s[10:11], s[18:19]
	s_add_u32 s8, s10, s0
	s_addc_u32 s9, s11, s1
	s_lshl_b64 s[0:1], s[86:87], 12
	v_readlane_b32 s2, v251, 52
	s_add_u32 s3, s2, s0
	v_readlane_b32 s0, v251, 53
	s_addc_u32 s5, s0, s1
	s_lshl_b32 s0, s4, 5
	s_and_b32 s2, s0, 0x7e0
	s_and_b32 s7, s4, 0x7c0
	s_lshl_b32 s0, s2, 2
	s_add_u32 s0, s8, s0
	v_or_b32_e32 v8, s7, v3
	s_addc_u32 s1, s9, 0
	v_lshlrev_b32_e32 v202, 2, v2
	v_lshl_add_u64 v[6:7], s[0:1], 0, v[202:203]
	v_lshlrev_b32_e32 v202, 13, v8
	v_lshl_add_u64 v[6:7], v[6:7], 0, v[202:203]
	v_add_co_u32_e32 v8, vcc, s33, v6
	s_mov_b32 s0, 0x8000
	s_nop 0
	v_addc_co_u32_e32 v9, vcc, 0, v7, vcc
	global_load_dword v15, v[6:7], off nt
	global_load_dword v16, v[8:9], off nt
	v_add_co_u32_e32 v8, vcc, s0, v6
	s_mov_b32 s0, 0xc000
	s_nop 0
	v_addc_co_u32_e32 v9, vcc, 0, v7, vcc
	global_load_dword v17, v[8:9], off nt
	v_add_co_u32_e32 v8, vcc, s0, v6
	s_mov_b32 s0, 0x10000
	s_nop 0
	v_addc_co_u32_e32 v9, vcc, 0, v7, vcc
	global_load_dword v18, v[8:9], off nt
	v_add_co_u32_e32 v8, vcc, s0, v6
	s_mov_b32 s0, 0x14000
	s_nop 0
	v_addc_co_u32_e32 v9, vcc, 0, v7, vcc
	global_load_dword v19, v[8:9], off nt
	v_add_co_u32_e32 v8, vcc, s0, v6
	s_mov_b32 s0, 0x18000
	s_nop 0
	v_addc_co_u32_e32 v9, vcc, 0, v7, vcc
	global_load_dword v20, v[8:9], off nt
	v_add_co_u32_e32 v8, vcc, s0, v6
	s_mov_b32 s0, 0x1c000
	s_nop 0
	v_addc_co_u32_e32 v9, vcc, 0, v7, vcc
	global_load_dword v21, v[8:9], off nt
	v_add_co_u32_e32 v8, vcc, s0, v6
	s_mov_b32 s0, 0x24000
	s_nop 0
	v_addc_co_u32_e32 v9, vcc, 0, v7, vcc
	global_load_dword v22, v[8:9], off nt
	v_add_co_u32_e32 v8, vcc, s57, v6
	v_lshlrev_b32_e32 v202, 1, v4
	s_nop 0
	v_addc_co_u32_e32 v9, vcc, 0, v7, vcc
	global_load_dword v23, v[8:9], off nt
	v_add_co_u32_e32 v8, vcc, s0, v6
	s_mov_b32 s0, 0x28000
	s_nop 0
	v_addc_co_u32_e32 v9, vcc, 0, v7, vcc
	global_load_dword v24, v[8:9], off nt
	v_add_co_u32_e32 v8, vcc, s0, v6
	s_mov_b32 s0, 0x2c000
	s_nop 0
	v_addc_co_u32_e32 v9, vcc, 0, v7, vcc
	global_load_dword v25, v[8:9], off nt
	v_add_co_u32_e32 v8, vcc, s0, v6
	s_mov_b32 s0, 0x30000
	s_nop 0
	v_addc_co_u32_e32 v9, vcc, 0, v7, vcc
	global_load_dword v26, v[8:9], off nt
	v_add_co_u32_e32 v8, vcc, s0, v6
	s_mov_b32 s0, 0x34000
	s_nop 0
	v_addc_co_u32_e32 v9, vcc, 0, v7, vcc
	global_load_dword v27, v[8:9], off nt
	v_add_co_u32_e32 v8, vcc, s0, v6
	s_mov_b32 s0, 0x38000
	s_nop 0
	v_addc_co_u32_e32 v9, vcc, 0, v7, vcc
	global_load_dword v28, v[8:9], off nt
	v_add_co_u32_e32 v8, vcc, s0, v6
	s_mov_b32 s0, 0x3c000
	s_nop 0
	v_addc_co_u32_e32 v9, vcc, 0, v7, vcc
	global_load_dword v29, v[8:9], off nt
	v_add_co_u32_e32 v8, vcc, s0, v6
	s_mov_b32 s0, 0x44000
	s_nop 0
	v_addc_co_u32_e32 v9, vcc, 0, v7, vcc
	global_load_dword v30, v[8:9], off nt
	v_add_co_u32_e32 v8, vcc, s88, v6
	v_readlane_b32 s20, v251, 34
	s_nop 0
	v_addc_co_u32_e32 v9, vcc, 0, v7, vcc
	global_load_dword v31, v[8:9], off nt
	v_add_co_u32_e32 v8, vcc, s0, v6
	s_mov_b32 s0, 0x48000
	s_nop 0
	v_addc_co_u32_e32 v9, vcc, 0, v7, vcc
	global_load_dword v32, v[8:9], off nt
	v_add_co_u32_e32 v8, vcc, s0, v6
	s_mov_b32 s0, 0x4c000
	s_nop 0
	v_addc_co_u32_e32 v9, vcc, 0, v7, vcc
	global_load_dword v33, v[8:9], off nt
	v_add_co_u32_e32 v8, vcc, s0, v6
	s_mov_b32 s0, 0x50000
	s_nop 0
	v_addc_co_u32_e32 v9, vcc, 0, v7, vcc
	global_load_dword v34, v[8:9], off nt
	v_add_co_u32_e32 v8, vcc, s0, v6
	s_mov_b32 s0, 0x54000
	s_nop 0
	v_addc_co_u32_e32 v9, vcc, 0, v7, vcc
	global_load_dword v35, v[8:9], off nt
	v_add_co_u32_e32 v8, vcc, s0, v6
	s_mov_b32 s0, 0x58000
	s_nop 0
	v_addc_co_u32_e32 v9, vcc, 0, v7, vcc
	global_load_dword v36, v[8:9], off nt
	v_add_co_u32_e32 v8, vcc, s0, v6
	s_mov_b32 s0, 0x5c000
	s_nop 0
	v_addc_co_u32_e32 v9, vcc, 0, v7, vcc
	global_load_dword v37, v[8:9], off nt
	v_add_co_u32_e32 v8, vcc, s0, v6
	s_mov_b32 s0, 0x60000
	s_nop 0
	v_addc_co_u32_e32 v9, vcc, 0, v7, vcc
	global_load_dword v38, v[8:9], off nt
	v_add_co_u32_e32 v8, vcc, s0, v6
	s_mov_b32 s0, 0x64000
	s_nop 0
	v_addc_co_u32_e32 v9, vcc, 0, v7, vcc
	global_load_dword v39, v[8:9], off nt
	v_add_co_u32_e32 v8, vcc, s0, v6
	s_mov_b32 s0, 0x68000
	s_nop 0
	v_addc_co_u32_e32 v9, vcc, 0, v7, vcc
	global_load_dword v40, v[8:9], off nt
	v_add_co_u32_e32 v8, vcc, s0, v6
	s_mov_b32 s0, 0x6c000
	s_nop 0
	v_addc_co_u32_e32 v9, vcc, 0, v7, vcc
	global_load_dword v41, v[8:9], off nt
	v_add_co_u32_e32 v8, vcc, s0, v6
	s_mov_b32 s0, 0x70000
	s_nop 0
	v_addc_co_u32_e32 v9, vcc, 0, v7, vcc
	global_load_dword v42, v[8:9], off nt
	v_add_co_u32_e32 v8, vcc, s0, v6
	s_mov_b32 s0, 0x74000
	s_nop 0
	v_addc_co_u32_e32 v9, vcc, 0, v7, vcc
	global_load_dword v43, v[8:9], off nt
	v_add_co_u32_e32 v8, vcc, s0, v6
	s_mov_b32 s0, 0x78000
	s_nop 0
	v_addc_co_u32_e32 v9, vcc, 0, v7, vcc
	global_load_dword v44, v[8:9], off nt
	v_add_co_u32_e32 v8, vcc, s0, v6
	s_mov_b32 s0, 0x7c000
	s_nop 0
	v_addc_co_u32_e32 v9, vcc, 0, v7, vcc
	v_add_co_u32_e32 v6, vcc, s0, v6
	global_load_dword v8, v[8:9], off nt
	s_nop 0
	v_addc_co_u32_e32 v7, vcc, 0, v7, vcc
	global_load_dword v6, v[6:7], off nt
	v_add_u32_e32 v7, 0x400, v5
	s_waitcnt vmcnt(0)
	ds_write2_b32 v5, v15, v16 offset1:66
	ds_write2_b32 v5, v17, v18 offset0:132 offset1:198
	ds_write2_b32 v7, v19, v20 offset0:8 offset1:74
	ds_write2_b32 v7, v21, v22 offset0:140 offset1:206
	v_add_u32_e32 v7, 0x800, v5
	ds_write2_b32 v7, v23, v24 offset0:16 offset1:82
	ds_write2_b32 v7, v25, v26 offset0:148 offset1:214
	v_add_u32_e32 v7, 0xc00, v5
	ds_write2_b32 v7, v27, v28 offset0:24 offset1:90
	ds_write2_b32 v7, v29, v30 offset0:156 offset1:222
	v_add_u32_e32 v7, 0x1000, v5
	ds_write2_b32 v7, v31, v32 offset0:32 offset1:98
	ds_write2_b32 v7, v33, v34 offset0:164 offset1:230
	v_add_u32_e32 v7, 0x1400, v5
	ds_write2_b32 v7, v35, v36 offset0:40 offset1:106
	ds_write2_b32 v7, v37, v38 offset0:172 offset1:238
	v_add_u32_e32 v7, 0x1800, v5
	ds_write2_b32 v7, v39, v40 offset0:48 offset1:114
	ds_write2_b32 v7, v41, v42 offset0:180 offset1:246
	v_add_u32_e32 v7, 0x1c00, v5
	ds_write2_b32 v7, v43, v44 offset0:56 offset1:122
	ds_write2_b32 v7, v8, v6 offset0:188 offset1:254
	s_waitcnt lgkmcnt(0)
	ds_read2_b32 v[8:9], v11 offset0:33 offset1:41
	ds_read2_b32 v[20:21], v11 offset1:8
	ds_read2_b32 v[22:23], v11 offset0:66 offset1:74
	ds_read2_b32 v[24:25], v11 offset0:99 offset1:107
	ds_read2_b32 v[26:27], v11 offset0:132 offset1:140
	ds_read2_b32 v[28:29], v11 offset0:165 offset1:173
	ds_read2_b32 v[30:31], v11 offset0:198 offset1:206
	ds_read2_b32 v[32:33], v11 offset0:231 offset1:239
	s_waitcnt lgkmcnt(7)
	v_bfe_u32 v16, v8, 16, 1
	s_waitcnt lgkmcnt(6)
	v_bfe_u32 v15, v20, 16, 1
	v_add3_u32 v15, v20, v15, s53
	v_lshrrev_b32_e32 v15, 16, v15
	v_add3_u32 v8, v8, v16, s53
	v_and_or_b32 v16, v8, s77, v15
	s_waitcnt lgkmcnt(5)
	v_bfe_u32 v8, v22, 16, 1
	v_add3_u32 v8, v22, v8, s53
	s_waitcnt lgkmcnt(4)
	v_bfe_u32 v15, v24, 16, 1
	v_lshrrev_b32_e32 v8, 16, v8
	v_add3_u32 v15, v24, v15, s53
	v_and_or_b32 v17, v15, s77, v8
	s_waitcnt lgkmcnt(3)
	v_bfe_u32 v8, v26, 16, 1
	v_add3_u32 v8, v26, v8, s53
	s_waitcnt lgkmcnt(2)
	v_bfe_u32 v15, v28, 16, 1
	v_lshrrev_b32_e32 v8, 16, v8
	v_add3_u32 v15, v28, v15, s53
	v_and_or_b32 v18, v15, s77, v8
	s_waitcnt lgkmcnt(1)
	v_bfe_u32 v8, v30, 16, 1
	s_lshl_b32 s0, s7, 1
	v_add3_u32 v8, v30, v8, s53
	s_waitcnt lgkmcnt(0)
	v_bfe_u32 v15, v32, 16, 1
	s_add_u32 s0, s3, s0
	v_lshrrev_b32_e32 v8, 16, v8
	v_add3_u32 v15, v32, v15, s53
	s_addc_u32 s1, s5, 0
	v_and_or_b32 v19, v15, s77, v8
	v_or_b32_e32 v8, s2, v10
	v_lshl_add_u64 v[6:7], s[0:1], 0, v[202:203]
	v_lshlrev_b32_e32 v202, 12, v8
	v_bfe_u32 v8, v21, 16, 1
	v_add3_u32 v8, v21, v8, s53
	v_bfe_u32 v15, v9, 16, 1
	v_lshl_add_u64 v[34:35], v[6:7], 0, v[202:203]
	v_lshrrev_b32_e32 v8, 16, v8
	v_add3_u32 v9, v9, v15, s53
	global_store_dwordx4 v[34:35], v[16:19], off nt
	v_readlane_b32 s21, v251, 35
	v_readlane_b32 s22, v251, 36
	v_and_or_b32 v16, v9, s77, v8
	v_bfe_u32 v8, v23, 16, 1
	v_add3_u32 v8, v23, v8, s53
	v_bfe_u32 v9, v25, 16, 1
	v_lshrrev_b32_e32 v8, 16, v8
	v_add3_u32 v9, v25, v9, s53
	v_and_or_b32 v17, v9, s77, v8
	v_bfe_u32 v8, v27, 16, 1
	v_add3_u32 v8, v27, v8, s53
	v_bfe_u32 v9, v29, 16, 1
	v_lshrrev_b32_e32 v8, 16, v8
	v_add3_u32 v9, v29, v9, s53
	v_and_or_b32 v18, v9, s77, v8
	v_bfe_u32 v8, v31, 16, 1
	v_add3_u32 v8, v31, v8, s53
	v_bfe_u32 v9, v33, 16, 1
	v_lshrrev_b32_e32 v8, 16, v8
	v_add3_u32 v9, v33, v9, s53
	v_and_or_b32 v19, v9, s77, v8
	v_or_b32_e32 v8, s2, v12
	v_lshlrev_b32_e32 v202, 12, v8
	v_lshl_add_u64 v[8:9], v[6:7], 0, v[202:203]
	global_store_dwordx4 v[8:9], v[16:19], off nt
	ds_read2_b32 v[8:9], v11 offset0:49 offset1:57
	ds_read2_b32 v[20:21], v11 offset0:16 offset1:24
	ds_read2_b32 v[22:23], v11 offset0:82 offset1:90
	ds_read2_b32 v[24:25], v11 offset0:115 offset1:123
	ds_read2_b32 v[26:27], v11 offset0:148 offset1:156
	ds_read2_b32 v[28:29], v11 offset0:181 offset1:189
	ds_read2_b32 v[30:31], v11 offset0:214 offset1:222
	ds_read2_b32 v[32:33], v11 offset0:247 offset1:255
	s_waitcnt lgkmcnt(7)
	v_bfe_u32 v16, v8, 16, 1
	s_waitcnt lgkmcnt(6)
	v_bfe_u32 v15, v20, 16, 1
	v_add3_u32 v15, v20, v15, s53
	v_lshrrev_b32_e32 v15, 16, v15
	v_add3_u32 v8, v8, v16, s53
	v_and_or_b32 v16, v8, s77, v15
	s_waitcnt lgkmcnt(5)
	v_bfe_u32 v8, v22, 16, 1
	v_add3_u32 v8, v22, v8, s53
	s_waitcnt lgkmcnt(4)
	v_bfe_u32 v15, v24, 16, 1
	v_lshrrev_b32_e32 v8, 16, v8
	v_add3_u32 v15, v24, v15, s53
	v_and_or_b32 v17, v15, s77, v8
	s_waitcnt lgkmcnt(3)
	v_bfe_u32 v8, v26, 16, 1
	v_add3_u32 v8, v26, v8, s53
	s_waitcnt lgkmcnt(2)
	v_bfe_u32 v15, v28, 16, 1
	v_lshrrev_b32_e32 v8, 16, v8
	v_add3_u32 v15, v28, v15, s53
	v_and_or_b32 v18, v15, s77, v8
	s_waitcnt lgkmcnt(1)
	v_bfe_u32 v8, v30, 16, 1
	v_add3_u32 v8, v30, v8, s53
	s_waitcnt lgkmcnt(0)
	v_bfe_u32 v15, v32, 16, 1
	v_lshrrev_b32_e32 v8, 16, v8
	v_add3_u32 v15, v32, v15, s53
	v_and_or_b32 v19, v15, s77, v8
	v_or_b32_e32 v8, s2, v13
	v_lshlrev_b32_e32 v202, 12, v8
	v_bfe_u32 v8, v21, 16, 1
	v_add3_u32 v8, v21, v8, s53
	v_bfe_u32 v15, v9, 16, 1
	v_lshl_add_u64 v[34:35], v[6:7], 0, v[202:203]
	v_lshrrev_b32_e32 v8, 16, v8
	v_add3_u32 v9, v9, v15, s53
	global_store_dwordx4 v[34:35], v[16:19], off nt
	v_readlane_b32 s23, v251, 37
	v_readlane_b32 s24, v251, 38
	v_and_or_b32 v16, v9, s77, v8
	v_bfe_u32 v8, v23, 16, 1
	v_add3_u32 v8, v23, v8, s53
	v_bfe_u32 v9, v25, 16, 1
	v_lshrrev_b32_e32 v8, 16, v8
	v_add3_u32 v9, v25, v9, s53
	v_and_or_b32 v17, v9, s77, v8
	v_bfe_u32 v8, v27, 16, 1
	v_add3_u32 v8, v27, v8, s53
	v_bfe_u32 v9, v29, 16, 1
	v_lshrrev_b32_e32 v8, 16, v8
	v_add3_u32 v9, v29, v9, s53
	v_and_or_b32 v18, v9, s77, v8
	v_bfe_u32 v8, v31, 16, 1
	v_add3_u32 v8, v31, v8, s53
	v_bfe_u32 v9, v33, 16, 1
	v_lshrrev_b32_e32 v8, 16, v8
	v_add3_u32 v9, v33, v9, s53
	v_and_or_b32 v19, v9, s77, v8
	v_or_b32_e32 v8, s2, v14
	v_lshlrev_b32_e32 v202, 12, v8
	v_lshl_add_u64 v[6:7], v[6:7], 0, v[202:203]
	global_store_dwordx4 v[6:7], v[16:19], off nt
	s_waitcnt lgkmcnt(0)
	v_readlane_b32 s25, v251, 39
	v_readlane_b32 s26, v251, 40
	v_readlane_b32 s27, v251, 41
	v_readlane_b32 s28, v251, 42
	v_readlane_b32 s29, v251, 43
	v_readlane_b32 s30, v251, 44
	v_readlane_b32 s31, v251, 45

.LBB0_893:
	s_andn2_b64 vcc, exec, s[2:3]
	s_cbranch_vccnz .LBB0_902
	s_add_i32 s1, s4, 0xffffa000
	s_mul_hi_u32 s0, s1, 0x3e0f83e1
	s_lshr_b32 s0, s0, 12
	s_mul_i32 s2, s0, 0x4200
	s_sub_i32 s1, s1, s2
	s_mul_i32 s2, s1, 0xba2f
	s_lshr_b32 s2, s2, 28
	s_mulk_i32 s2, 0x1600
	s_sub_i32 s5, s1, s2
	s_cmpk_gt_u32 s1, 0x15ff
	s_mul_hi_u32 s7, s0, 0x2c00000
	s_mul_i32 s8, s0, 0x2c00000
	s_mov_b64 s[2:3], -1
	s_cbranch_scc0 .LBB0_900
	s_addk_i32 s1, 0xea00
	s_cmpk_gt_u32 s1, 0x15ff
	s_cbranch_scc0 .LBB0_897
	v_readlane_b32 s16, v251, 14
	v_readlane_b32 s20, v251, 18
	v_readlane_b32 s21, v251, 19
	s_add_u32 s1, s20, s8
	s_addc_u32 s11, s21, s7
	s_mul_hi_u32 s2, s0, 0x1600000
	s_mul_i32 s0, s0, 0x1600000
	v_readlane_b32 s3, v251, 54
	s_add_u32 s3, s3, s0
	v_readlane_b32 s0, v251, 55
	s_addc_u32 s9, s0, s2
	s_lshl_b32 s0, s5, 5
	s_and_b32 s2, s0, 0x7e0
	s_and_b32 s10, s5, 0x1fc0
	s_lshl_b32 s0, s2, 2
	s_add_u32 s0, s1, s0
	v_or_b32_e32 v8, s10, v3
	s_addc_u32 s1, s11, 0
	v_lshlrev_b32_e32 v202, 2, v2
	v_lshl_add_u64 v[6:7], s[0:1], 0, v[202:203]
	v_lshlrev_b32_e32 v202, 13, v8
	v_lshl_add_u64 v[6:7], v[6:7], 0, v[202:203]
	v_add_co_u32_e32 v8, vcc, s33, v6
	s_mov_b32 s0, 0x8000
	s_nop 0
	v_addc_co_u32_e32 v9, vcc, 0, v7, vcc
	global_load_dword v15, v[6:7], off nt
	global_load_dword v16, v[8:9], off nt
	v_add_co_u32_e32 v8, vcc, s0, v6
	s_mov_b32 s0, 0xc000
	s_nop 0
	v_addc_co_u32_e32 v9, vcc, 0, v7, vcc
	global_load_dword v17, v[8:9], off nt
	v_add_co_u32_e32 v8, vcc, s0, v6
	s_mov_b32 s0, 0x10000
	s_nop 0
	v_addc_co_u32_e32 v9, vcc, 0, v7, vcc
	global_load_dword v18, v[8:9], off nt
	v_add_co_u32_e32 v8, vcc, s0, v6
	s_mov_b32 s0, 0x14000
	s_nop 0
	v_addc_co_u32_e32 v9, vcc, 0, v7, vcc
	global_load_dword v19, v[8:9], off nt
	v_add_co_u32_e32 v8, vcc, s0, v6
	s_mov_b32 s0, 0x18000
	s_nop 0
	v_addc_co_u32_e32 v9, vcc, 0, v7, vcc
	global_load_dword v20, v[8:9], off nt
	v_add_co_u32_e32 v8, vcc, s0, v6
	s_mov_b32 s0, 0x1c000
	s_nop 0
	v_addc_co_u32_e32 v9, vcc, 0, v7, vcc
	global_load_dword v21, v[8:9], off nt
	v_add_co_u32_e32 v8, vcc, s0, v6
	s_mov_b32 s0, 0x24000
	s_nop 0
	v_addc_co_u32_e32 v9, vcc, 0, v7, vcc
	global_load_dword v22, v[8:9], off nt
	v_add_co_u32_e32 v8, vcc, s57, v6
	v_lshlrev_b32_e32 v202, 1, v4
	s_nop 0
	v_addc_co_u32_e32 v9, vcc, 0, v7, vcc
	global_load_dword v23, v[8:9], off nt
	v_add_co_u32_e32 v8, vcc, s0, v6
	s_mov_b32 s0, 0x28000
	s_nop 0
	v_addc_co_u32_e32 v9, vcc, 0, v7, vcc
	global_load_dword v24, v[8:9], off nt
	v_add_co_u32_e32 v8, vcc, s0, v6
	s_mov_b32 s0, 0x2c000
	s_nop 0
	v_addc_co_u32_e32 v9, vcc, 0, v7, vcc
	global_load_dword v25, v[8:9], off nt
	v_add_co_u32_e32 v8, vcc, s0, v6
	s_mov_b32 s0, 0x30000
	s_nop 0
	v_addc_co_u32_e32 v9, vcc, 0, v7, vcc
	global_load_dword v26, v[8:9], off nt
	v_add_co_u32_e32 v8, vcc, s0, v6
	s_mov_b32 s0, 0x34000
	s_nop 0
	v_addc_co_u32_e32 v9, vcc, 0, v7, vcc
	global_load_dword v27, v[8:9], off nt
	v_add_co_u32_e32 v8, vcc, s0, v6
	s_mov_b32 s0, 0x38000
	s_nop 0
	v_addc_co_u32_e32 v9, vcc, 0, v7, vcc
	global_load_dword v28, v[8:9], off nt
	v_add_co_u32_e32 v8, vcc, s0, v6
	s_mov_b32 s0, 0x3c000
	s_nop 0
	v_addc_co_u32_e32 v9, vcc, 0, v7, vcc
	global_load_dword v29, v[8:9], off nt
	v_add_co_u32_e32 v8, vcc, s0, v6
	s_mov_b32 s0, 0x44000
	s_nop 0
	v_addc_co_u32_e32 v9, vcc, 0, v7, vcc
	global_load_dword v30, v[8:9], off nt
	v_add_co_u32_e32 v8, vcc, s88, v6
	v_readlane_b32 s17, v251, 15
	s_nop 0
	v_addc_co_u32_e32 v9, vcc, 0, v7, vcc
	global_load_dword v31, v[8:9], off nt
	v_add_co_u32_e32 v8, vcc, s0, v6
	s_mov_b32 s0, 0x48000
	s_nop 0
	v_addc_co_u32_e32 v9, vcc, 0, v7, vcc
	global_load_dword v32, v[8:9], off nt
	v_add_co_u32_e32 v8, vcc, s0, v6
	s_mov_b32 s0, 0x4c000
	s_nop 0
	v_addc_co_u32_e32 v9, vcc, 0, v7, vcc
	global_load_dword v33, v[8:9], off nt
	v_add_co_u32_e32 v8, vcc, s0, v6
	s_mov_b32 s0, 0x50000
	s_nop 0
	v_addc_co_u32_e32 v9, vcc, 0, v7, vcc
	global_load_dword v34, v[8:9], off nt
	v_add_co_u32_e32 v8, vcc, s0, v6
	s_mov_b32 s0, 0x54000
	s_nop 0
	v_addc_co_u32_e32 v9, vcc, 0, v7, vcc
	global_load_dword v35, v[8:9], off nt
	v_add_co_u32_e32 v8, vcc, s0, v6
	s_mov_b32 s0, 0x58000
	s_nop 0
	v_addc_co_u32_e32 v9, vcc, 0, v7, vcc
	global_load_dword v36, v[8:9], off nt
	v_add_co_u32_e32 v8, vcc, s0, v6
	s_mov_b32 s0, 0x5c000
	s_nop 0
	v_addc_co_u32_e32 v9, vcc, 0, v7, vcc
	global_load_dword v37, v[8:9], off nt
	v_add_co_u32_e32 v8, vcc, s0, v6
	s_mov_b32 s0, 0x60000
	s_nop 0
	v_addc_co_u32_e32 v9, vcc, 0, v7, vcc
	global_load_dword v38, v[8:9], off nt
	v_add_co_u32_e32 v8, vcc, s0, v6
	s_mov_b32 s0, 0x64000
	s_nop 0
	v_addc_co_u32_e32 v9, vcc, 0, v7, vcc
	global_load_dword v39, v[8:9], off nt
	v_add_co_u32_e32 v8, vcc, s0, v6
	s_mov_b32 s0, 0x68000
	s_nop 0
	v_addc_co_u32_e32 v9, vcc, 0, v7, vcc
	global_load_dword v40, v[8:9], off nt
	v_add_co_u32_e32 v8, vcc, s0, v6
	s_mov_b32 s0, 0x6c000
	s_nop 0
	v_addc_co_u32_e32 v9, vcc, 0, v7, vcc
	global_load_dword v41, v[8:9], off nt
	v_add_co_u32_e32 v8, vcc, s0, v6
	s_mov_b32 s0, 0x70000
	s_nop 0
	v_addc_co_u32_e32 v9, vcc, 0, v7, vcc
	global_load_dword v42, v[8:9], off nt
	v_add_co_u32_e32 v8, vcc, s0, v6
	s_mov_b32 s0, 0x74000
	s_nop 0
	v_addc_co_u32_e32 v9, vcc, 0, v7, vcc
	global_load_dword v43, v[8:9], off nt
	v_add_co_u32_e32 v8, vcc, s0, v6
	s_mov_b32 s0, 0x78000
	s_nop 0
	v_addc_co_u32_e32 v9, vcc, 0, v7, vcc
	global_load_dword v44, v[8:9], off nt
	v_add_co_u32_e32 v8, vcc, s0, v6
	s_mov_b32 s0, 0x7c000
	s_nop 0
	v_addc_co_u32_e32 v9, vcc, 0, v7, vcc
	v_add_co_u32_e32 v6, vcc, s0, v6
	global_load_dword v8, v[8:9], off nt
	s_nop 0
	v_addc_co_u32_e32 v7, vcc, 0, v7, vcc
	global_load_dword v6, v[6:7], off nt
	v_add_u32_e32 v7, 0x400, v5
	s_waitcnt vmcnt(0)
	ds_write2_b32 v5, v15, v16 offset1:66
	ds_write2_b32 v5, v17, v18 offset0:132 offset1:198
	ds_write2_b32 v7, v19, v20 offset0:8 offset1:74
	ds_write2_b32 v7, v21, v22 offset0:140 offset1:206
	v_add_u32_e32 v7, 0x800, v5
	ds_write2_b32 v7, v23, v24 offset0:16 offset1:82
	ds_write2_b32 v7, v25, v26 offset0:148 offset1:214
	v_add_u32_e32 v7, 0xc00, v5
	ds_write2_b32 v7, v27, v28 offset0:24 offset1:90
	ds_write2_b32 v7, v29, v30 offset0:156 offset1:222
	v_add_u32_e32 v7, 0x1000, v5
	ds_write2_b32 v7, v31, v32 offset0:32 offset1:98
	ds_write2_b32 v7, v33, v34 offset0:164 offset1:230
	v_add_u32_e32 v7, 0x1400, v5
	ds_write2_b32 v7, v35, v36 offset0:40 offset1:106
	ds_write2_b32 v7, v37, v38 offset0:172 offset1:238
	v_add_u32_e32 v7, 0x1800, v5
	ds_write2_b32 v7, v39, v40 offset0:48 offset1:114
	ds_write2_b32 v7, v41, v42 offset0:180 offset1:246
	v_add_u32_e32 v7, 0x1c00, v5
	ds_write2_b32 v7, v43, v44 offset0:56 offset1:122
	ds_write2_b32 v7, v8, v6 offset0:188 offset1:254
	s_waitcnt lgkmcnt(0)
	ds_read2_b32 v[8:9], v11 offset0:33 offset1:41
	ds_read2_b32 v[20:21], v11 offset1:8
	ds_read2_b32 v[22:23], v11 offset0:66 offset1:74
	ds_read2_b32 v[24:25], v11 offset0:99 offset1:107
	ds_read2_b32 v[26:27], v11 offset0:132 offset1:140
	ds_read2_b32 v[28:29], v11 offset0:165 offset1:173
	ds_read2_b32 v[30:31], v11 offset0:198 offset1:206
	ds_read2_b32 v[32:33], v11 offset0:231 offset1:239
	s_waitcnt lgkmcnt(7)
	v_bfe_u32 v16, v8, 16, 1
	s_waitcnt lgkmcnt(6)
	v_bfe_u32 v15, v20, 16, 1
	v_add3_u32 v15, v20, v15, s53
	v_lshrrev_b32_e32 v15, 16, v15
	v_add3_u32 v8, v8, v16, s53
	v_and_or_b32 v16, v8, s77, v15
	s_waitcnt lgkmcnt(5)
	v_bfe_u32 v8, v22, 16, 1
	v_add3_u32 v8, v22, v8, s53
	s_waitcnt lgkmcnt(4)
	v_bfe_u32 v15, v24, 16, 1
	v_lshrrev_b32_e32 v8, 16, v8
	v_add3_u32 v15, v24, v15, s53
	v_and_or_b32 v17, v15, s77, v8
	s_waitcnt lgkmcnt(3)
	v_bfe_u32 v8, v26, 16, 1
	v_add3_u32 v8, v26, v8, s53
	s_waitcnt lgkmcnt(2)
	v_bfe_u32 v15, v28, 16, 1
	v_lshrrev_b32_e32 v8, 16, v8
	v_add3_u32 v15, v28, v15, s53
	v_and_or_b32 v18, v15, s77, v8
	s_waitcnt lgkmcnt(1)
	v_bfe_u32 v8, v30, 16, 1
	v_add3_u32 v8, v30, v8, s53
	s_waitcnt lgkmcnt(0)
	v_bfe_u32 v15, v32, 16, 1
	s_lshl_b32 s0, s10, 1
	v_lshrrev_b32_e32 v8, 16, v8
	v_add3_u32 v15, v32, v15, s53
	s_add_u32 s0, s3, s0
	v_and_or_b32 v19, v15, s77, v8
	v_or_b32_e32 v8, s2, v10
	s_addc_u32 s1, s9, 0
	v_mul_u32_u24_e32 v8, 0x1600, v8
	v_lshl_add_u64 v[6:7], s[0:1], 0, v[202:203]
	v_lshlrev_b32_e32 v202, 1, v8
	v_bfe_u32 v8, v21, 16, 1
	v_add3_u32 v8, v21, v8, s53
	v_bfe_u32 v15, v9, 16, 1
	v_lshl_add_u64 v[34:35], v[6:7], 0, v[202:203]
	v_lshrrev_b32_e32 v8, 16, v8
	v_add3_u32 v9, v9, v15, s53
	global_store_dwordx4 v[34:35], v[16:19], off nt
	v_readlane_b32 s18, v251, 16
	v_readlane_b32 s19, v251, 17
	v_and_or_b32 v16, v9, s77, v8
	v_bfe_u32 v8, v23, 16, 1
	v_add3_u32 v8, v23, v8, s53
	v_bfe_u32 v9, v25, 16, 1
	v_lshrrev_b32_e32 v8, 16, v8
	v_add3_u32 v9, v25, v9, s53
	v_and_or_b32 v17, v9, s77, v8
	v_bfe_u32 v8, v27, 16, 1
	v_add3_u32 v8, v27, v8, s53
	v_bfe_u32 v9, v29, 16, 1
	v_lshrrev_b32_e32 v8, 16, v8
	v_add3_u32 v9, v29, v9, s53
	v_and_or_b32 v18, v9, s77, v8
	v_bfe_u32 v8, v31, 16, 1
	v_add3_u32 v8, v31, v8, s53
	v_bfe_u32 v9, v33, 16, 1
	v_lshrrev_b32_e32 v8, 16, v8
	v_add3_u32 v9, v33, v9, s53
	v_and_or_b32 v19, v9, s77, v8
	v_or_b32_e32 v8, s2, v12
	v_mul_u32_u24_e32 v8, 0x1600, v8
	v_lshlrev_b32_e32 v202, 1, v8
	v_lshl_add_u64 v[8:9], v[6:7], 0, v[202:203]
	global_store_dwordx4 v[8:9], v[16:19], off nt
	ds_read2_b32 v[8:9], v11 offset0:16 offset1:24
	ds_read2_b32 v[20:21], v11 offset0:49 offset1:57
	ds_read2_b32 v[22:23], v11 offset0:82 offset1:90
	ds_read2_b32 v[24:25], v11 offset0:115 offset1:123
	ds_read2_b32 v[26:27], v11 offset0:148 offset1:156
	ds_read2_b32 v[28:29], v11 offset0:181 offset1:189
	ds_read2_b32 v[30:31], v11 offset0:214 offset1:222
	ds_read2_b32 v[32:33], v11 offset0:247 offset1:255
	s_waitcnt lgkmcnt(7)
	v_bfe_u32 v15, v8, 16, 1
	v_add3_u32 v8, v8, v15, s53
	s_waitcnt lgkmcnt(6)
	v_bfe_u32 v15, v20, 16, 1
	v_lshrrev_b32_e32 v8, 16, v8
	v_add3_u32 v15, v20, v15, s53
	v_and_or_b32 v16, v15, s77, v8
	s_waitcnt lgkmcnt(5)
	v_bfe_u32 v8, v22, 16, 1
	v_add3_u32 v8, v22, v8, s53
	s_waitcnt lgkmcnt(4)
	v_bfe_u32 v15, v24, 16, 1
	v_lshrrev_b32_e32 v8, 16, v8
	v_add3_u32 v15, v24, v15, s53
	v_and_or_b32 v17, v15, s77, v8
	s_waitcnt lgkmcnt(3)
	v_bfe_u32 v8, v26, 16, 1
	v_add3_u32 v8, v26, v8, s53
	s_waitcnt lgkmcnt(2)
	v_bfe_u32 v15, v28, 16, 1
	v_lshrrev_b32_e32 v8, 16, v8
	v_add3_u32 v15, v28, v15, s53
	v_and_or_b32 v18, v15, s77, v8
	s_waitcnt lgkmcnt(1)
	v_bfe_u32 v8, v30, 16, 1
	v_add3_u32 v8, v30, v8, s53
	s_waitcnt lgkmcnt(0)
	v_bfe_u32 v15, v32, 16, 1
	v_lshrrev_b32_e32 v8, 16, v8
	v_add3_u32 v15, v32, v15, s53
	v_and_or_b32 v19, v15, s77, v8
	v_or_b32_e32 v8, s2, v13
	v_mul_u32_u24_e32 v8, 0x1600, v8
	v_lshlrev_b32_e32 v202, 1, v8
	v_bfe_u32 v8, v9, 16, 1
	v_add3_u32 v8, v9, v8, s53
	v_bfe_u32 v9, v21, 16, 1
	v_lshl_add_u64 v[34:35], v[6:7], 0, v[202:203]
	v_lshrrev_b32_e32 v8, 16, v8
	v_add3_u32 v9, v21, v9, s53
	global_store_dwordx4 v[34:35], v[16:19], off nt
	v_readlane_b32 s22, v251, 20
	v_readlane_b32 s23, v251, 21
	v_and_or_b32 v16, v9, s77, v8
	v_bfe_u32 v8, v23, 16, 1
	v_add3_u32 v8, v23, v8, s53
	v_bfe_u32 v9, v25, 16, 1
	v_lshrrev_b32_e32 v8, 16, v8
	v_add3_u32 v9, v25, v9, s53
	v_and_or_b32 v17, v9, s77, v8
	v_bfe_u32 v8, v27, 16, 1
	v_add3_u32 v8, v27, v8, s53
	v_bfe_u32 v9, v29, 16, 1
	v_lshrrev_b32_e32 v8, 16, v8
	v_add3_u32 v9, v29, v9, s53
	v_and_or_b32 v18, v9, s77, v8
	v_bfe_u32 v8, v31, 16, 1
	v_add3_u32 v8, v31, v8, s53
	v_bfe_u32 v9, v33, 16, 1
	v_lshrrev_b32_e32 v8, 16, v8
	v_add3_u32 v9, v33, v9, s53
	v_and_or_b32 v19, v9, s77, v8
	v_or_b32_e32 v8, s2, v14
	v_mul_u32_u24_e32 v8, 0x1600, v8
	v_lshlrev_b32_e32 v202, 1, v8
	v_lshl_add_u64 v[6:7], v[6:7], 0, v[202:203]
	global_store_dwordx4 v[6:7], v[16:19], off nt
	s_waitcnt lgkmcnt(0)
	v_readlane_b32 s24, v251, 22
	v_readlane_b32 s25, v251, 23
	v_readlane_b32 s26, v251, 24
	v_readlane_b32 s27, v251, 25
	v_readlane_b32 s28, v251, 26
	v_readlane_b32 s29, v251, 27
	v_readlane_b32 s30, v251, 28
	v_readlane_b32 s31, v251, 29
	s_mov_b64 s[2:3], 0
.LBB0_897:
	s_andn2_b64 vcc, exec, s[2:3]
	s_cbranch_vccnz .LBB0_899
	v_readlane_b32 s16, v251, 14
	v_readlane_b32 s18, v251, 16
	v_readlane_b32 s19, v251, 17
	s_add_u32 s0, s18, s8
	s_addc_u32 s1, s19, s7
	v_readlane_b32 s2, v251, 56
	s_add_u32 s3, s2, s8
	v_readlane_b32 s2, v251, 57
	s_addc_u32 s9, s2, s7
	s_and_b32 s2, 0xffff, s5
	s_mul_i32 s2, s2, 0xba2f
	s_lshr_b32 s10, s2, 23
	s_mul_i32 s2, s10, 0xb0
	s_sub_i32 s2, s5, s2
	s_and_b32 s11, s2, 0xffff
	s_lshl_b32 s2, s11, 5
	s_lshl_b32 s14, s11, 6
	s_and_b32 s14, s14, 0x3f00
	s_and_b32 s2, s2, 0x60
	s_or_b32 s2, s14, s2
	s_bitset1_b32 s2, 7
	s_lshl_b32 s11, s11, 7
	v_lshl_or_b32 v8, s10, 6, v3
	s_add_u32 s0, s0, s11
	s_addc_u32 s1, s1, 0
	v_lshlrev_b32_e32 v202, 2, v2
	v_mul_u32_u24_e32 v8, 0x1600, v8
	v_lshl_add_u64 v[6:7], s[0:1], 0, v[202:203]
	v_lshlrev_b32_e32 v202, 2, v8
	v_lshl_add_u64 v[6:7], v[6:7], 0, v[202:203]
	s_mov_b32 s0, 0xb000
	v_add_co_u32_e32 v8, vcc, s0, v6
	s_mov_b32 s0, 0x16000
	s_nop 0
	v_addc_co_u32_e32 v9, vcc, 0, v7, vcc
	global_load_dword v15, v[6:7], off nt
	global_load_dword v16, v[8:9], off nt
	v_add_co_u32_e32 v8, vcc, s0, v6
	s_mov_b32 s0, 0x21000
	s_nop 0
	v_addc_co_u32_e32 v9, vcc, 0, v7, vcc
	global_load_dword v17, v[8:9], off nt
	v_add_co_u32_e32 v8, vcc, s0, v6
	s_mov_b32 s0, 0x2c000
	s_nop 0
	v_addc_co_u32_e32 v9, vcc, 0, v7, vcc
	global_load_dword v18, v[8:9], off nt
	v_add_co_u32_e32 v8, vcc, s0, v6
	s_mov_b32 s0, 0x37000
	s_nop 0
	v_addc_co_u32_e32 v9, vcc, 0, v7, vcc
	global_load_dword v19, v[8:9], off nt
	v_add_co_u32_e32 v8, vcc, s0, v6
	s_mov_b32 s0, 0x42000
	s_nop 0
	v_addc_co_u32_e32 v9, vcc, 0, v7, vcc
	global_load_dword v20, v[8:9], off nt
	v_add_co_u32_e32 v8, vcc, s0, v6
	s_mov_b32 s0, 0x4d000
	s_nop 0
	v_addc_co_u32_e32 v9, vcc, 0, v7, vcc
	global_load_dword v21, v[8:9], off nt
	v_add_co_u32_e32 v8, vcc, s0, v6
	s_mov_b32 s0, 0x58000
	s_nop 0
	v_addc_co_u32_e32 v9, vcc, 0, v7, vcc
	global_load_dword v22, v[8:9], off nt
	v_add_co_u32_e32 v8, vcc, s0, v6
	s_mov_b32 s0, 0x63000
	s_nop 0
	v_addc_co_u32_e32 v9, vcc, 0, v7, vcc
	global_load_dword v23, v[8:9], off nt
	v_add_co_u32_e32 v8, vcc, s0, v6
	s_mov_b32 s0, 0x6e000
	s_nop 0
	v_addc_co_u32_e32 v9, vcc, 0, v7, vcc
	global_load_dword v24, v[8:9], off nt
	v_add_co_u32_e32 v8, vcc, s0, v6
	s_mov_b32 s0, 0x79000
	s_nop 0
	v_addc_co_u32_e32 v9, vcc, 0, v7, vcc
	global_load_dword v25, v[8:9], off nt
	v_add_co_u32_e32 v8, vcc, s0, v6
	s_mov_b32 s0, 0x84000
	s_nop 0
	v_addc_co_u32_e32 v9, vcc, 0, v7, vcc
	global_load_dword v26, v[8:9], off nt
	v_add_co_u32_e32 v8, vcc, s0, v6
	s_mov_b32 s0, 0x8f000
	s_nop 0
	v_addc_co_u32_e32 v9, vcc, 0, v7, vcc
	global_load_dword v27, v[8:9], off nt
	v_add_co_u32_e32 v8, vcc, s0, v6
	s_mov_b32 s0, 0x9a000
	s_nop 0
	v_addc_co_u32_e32 v9, vcc, 0, v7, vcc
	global_load_dword v28, v[8:9], off nt
	v_add_co_u32_e32 v8, vcc, s0, v6
	s_mov_b32 s0, 0xa5000
	s_nop 0
	v_addc_co_u32_e32 v9, vcc, 0, v7, vcc
	global_load_dword v29, v[8:9], off nt
	v_add_co_u32_e32 v8, vcc, s0, v6
	s_mov_b32 s0, 0xb0000
	s_nop 0
	v_addc_co_u32_e32 v9, vcc, 0, v7, vcc
	global_load_dword v30, v[8:9], off nt
	v_add_co_u32_e32 v8, vcc, s0, v6
	s_mov_b32 s0, 0xbb000
	s_nop 0
	v_addc_co_u32_e32 v9, vcc, 0, v7, vcc
	global_load_dword v31, v[8:9], off nt
	v_add_co_u32_e32 v8, vcc, s0, v6
	s_mov_b32 s0, 0xc6000
	s_nop 0
	v_addc_co_u32_e32 v9, vcc, 0, v7, vcc
	global_load_dword v32, v[8:9], off nt
	v_add_co_u32_e32 v8, vcc, s0, v6
	s_mov_b32 s0, 0xd1000
	s_nop 0
	v_addc_co_u32_e32 v9, vcc, 0, v7, vcc
	global_load_dword v33, v[8:9], off nt
	v_add_co_u32_e32 v8, vcc, s0, v6
	s_mov_b32 s0, 0xdc000
	s_nop 0
	v_addc_co_u32_e32 v9, vcc, 0, v7, vcc
	global_load_dword v34, v[8:9], off nt
	v_add_co_u32_e32 v8, vcc, s0, v6
	s_mov_b32 s0, 0xe7000
	s_nop 0
	v_addc_co_u32_e32 v9, vcc, 0, v7, vcc
	global_load_dword v35, v[8:9], off nt
	v_add_co_u32_e32 v8, vcc, s0, v6
	s_mov_b32 s0, 0xf2000
	s_nop 0
	v_addc_co_u32_e32 v9, vcc, 0, v7, vcc
	global_load_dword v36, v[8:9], off nt
	v_add_co_u32_e32 v8, vcc, s0, v6
	s_mov_b32 s0, 0xfd000
	s_nop 0
	v_addc_co_u32_e32 v9, vcc, 0, v7, vcc
	global_load_dword v37, v[8:9], off nt
	v_add_co_u32_e32 v8, vcc, s0, v6
	s_mov_b32 s0, 0x108000
	s_nop 0
	v_addc_co_u32_e32 v9, vcc, 0, v7, vcc
	global_load_dword v38, v[8:9], off nt
	v_add_co_u32_e32 v8, vcc, s0, v6
	s_mov_b32 s0, 0x113000
	s_nop 0
	v_addc_co_u32_e32 v9, vcc, 0, v7, vcc
	global_load_dword v39, v[8:9], off nt
	v_add_co_u32_e32 v8, vcc, s0, v6
	s_mov_b32 s0, 0x11e000
	s_nop 0
	v_addc_co_u32_e32 v9, vcc, 0, v7, vcc
	global_load_dword v40, v[8:9], off nt
	v_add_co_u32_e32 v8, vcc, s0, v6
	s_mov_b32 s0, 0x129000
	s_nop 0
	v_addc_co_u32_e32 v9, vcc, 0, v7, vcc
	global_load_dword v41, v[8:9], off nt
	v_add_co_u32_e32 v8, vcc, s0, v6
	s_mov_b32 s0, 0x134000
	s_nop 0
	v_addc_co_u32_e32 v9, vcc, 0, v7, vcc
	global_load_dword v42, v[8:9], off nt
	v_add_co_u32_e32 v8, vcc, s0, v6
	s_mov_b32 s0, 0x13f000
	s_nop 0
	v_addc_co_u32_e32 v9, vcc, 0, v7, vcc
	global_load_dword v43, v[8:9], off nt
	v_add_co_u32_e32 v8, vcc, s0, v6
	s_mov_b32 s0, 0x14a000
	s_nop 0
	v_addc_co_u32_e32 v9, vcc, 0, v7, vcc
	global_load_dword v44, v[8:9], off nt
	v_add_co_u32_e32 v8, vcc, s0, v6
	s_mov_b32 s0, 0x155000
	s_nop 0
	v_addc_co_u32_e32 v9, vcc, 0, v7, vcc
	v_add_co_u32_e32 v6, vcc, s0, v6
	global_load_dword v8, v[8:9], off nt
	s_nop 0
	v_addc_co_u32_e32 v7, vcc, 0, v7, vcc
	global_load_dword v6, v[6:7], off nt
	v_add_u32_e32 v7, 0x400, v5
	s_waitcnt vmcnt(0)
	ds_write2_b32 v5, v15, v16 offset1:66
	ds_write2_b32 v5, v17, v18 offset0:132 offset1:198
	ds_write2_b32 v7, v19, v20 offset0:8 offset1:74
	ds_write2_b32 v7, v21, v22 offset0:140 offset1:206
	v_add_u32_e32 v7, 0x800, v5
	ds_write2_b32 v7, v23, v24 offset0:16 offset1:82
	ds_write2_b32 v7, v25, v26 offset0:148 offset1:214
	v_add_u32_e32 v7, 0xc00, v5
	ds_write2_b32 v7, v27, v28 offset0:24 offset1:90
	ds_write2_b32 v7, v29, v30 offset0:156 offset1:222
	v_add_u32_e32 v7, 0x1000, v5
	ds_write2_b32 v7, v31, v32 offset0:32 offset1:98
	ds_write2_b32 v7, v33, v34 offset0:164 offset1:230
	v_add_u32_e32 v7, 0x1400, v5
	ds_write2_b32 v7, v35, v36 offset0:40 offset1:106
	ds_write2_b32 v7, v37, v38 offset0:172 offset1:238
	v_add_u32_e32 v7, 0x1800, v5
	ds_write2_b32 v7, v39, v40 offset0:48 offset1:114
	ds_write2_b32 v7, v41, v42 offset0:180 offset1:246
	v_add_u32_e32 v7, 0x1c00, v5
	ds_write2_b32 v7, v43, v44 offset0:56 offset1:122
	ds_write2_b32 v7, v8, v6 offset0:188 offset1:254
	s_waitcnt lgkmcnt(0)
	ds_read2_b32 v[8:9], v11 offset0:33 offset1:41
	ds_read2_b32 v[20:21], v11 offset1:8
	ds_read2_b32 v[22:23], v11 offset0:66 offset1:74
	ds_read2_b32 v[24:25], v11 offset0:99 offset1:107
	ds_read2_b32 v[26:27], v11 offset0:132 offset1:140
	ds_read2_b32 v[28:29], v11 offset0:165 offset1:173
	ds_read2_b32 v[30:31], v11 offset0:198 offset1:206
	ds_read2_b32 v[32:33], v11 offset0:231 offset1:239
	s_waitcnt lgkmcnt(7)
	v_bfe_u32 v16, v8, 16, 1
	s_waitcnt lgkmcnt(6)
	v_bfe_u32 v15, v20, 16, 1
	v_add3_u32 v15, v20, v15, s53
	v_lshrrev_b32_e32 v15, 16, v15
	v_add3_u32 v8, v8, v16, s53
	v_and_or_b32 v16, v8, s77, v15
	s_waitcnt lgkmcnt(5)
	v_bfe_u32 v8, v22, 16, 1
	v_add3_u32 v8, v22, v8, s53
	s_waitcnt lgkmcnt(4)
	v_bfe_u32 v15, v24, 16, 1
	v_lshrrev_b32_e32 v8, 16, v8
	v_add3_u32 v15, v24, v15, s53
	v_and_or_b32 v17, v15, s77, v8
	s_waitcnt lgkmcnt(3)
	v_bfe_u32 v8, v26, 16, 1
	v_add3_u32 v8, v26, v8, s53
	s_waitcnt lgkmcnt(2)
	v_bfe_u32 v15, v28, 16, 1
	v_lshrrev_b32_e32 v8, 16, v8
	v_add3_u32 v15, v28, v15, s53
	v_and_or_b32 v18, v15, s77, v8
	s_waitcnt lgkmcnt(1)
	v_bfe_u32 v8, v30, 16, 1
	s_lshl_b32 s0, s10, 7
	v_add3_u32 v8, v30, v8, s53
	s_waitcnt lgkmcnt(0)
	v_bfe_u32 v15, v32, 16, 1
	s_add_u32 s0, s3, s0
	v_lshrrev_b32_e32 v8, 16, v8
	v_add3_u32 v15, v32, v15, s53
	s_addc_u32 s1, s9, 0
	v_lshlrev_b32_e32 v202, 1, v4
	v_and_or_b32 v19, v15, s77, v8
	v_or_b32_e32 v8, s2, v10
	v_lshl_add_u64 v[6:7], s[0:1], 0, v[202:203]
	v_lshlrev_b32_e32 v202, 12, v8
	v_bfe_u32 v8, v21, 16, 1
	v_add3_u32 v8, v21, v8, s53
	v_bfe_u32 v15, v9, 16, 1
	v_lshl_add_u64 v[34:35], v[6:7], 0, v[202:203]
	v_lshrrev_b32_e32 v8, 16, v8
	v_add3_u32 v9, v9, v15, s53
	global_store_dwordx4 v[34:35], v[16:19], off nt
	v_readlane_b32 s17, v251, 15
	v_readlane_b32 s20, v251, 18
	v_and_or_b32 v16, v9, s77, v8
	v_bfe_u32 v8, v23, 16, 1
	v_add3_u32 v8, v23, v8, s53
	v_bfe_u32 v9, v25, 16, 1
	v_lshrrev_b32_e32 v8, 16, v8
	v_add3_u32 v9, v25, v9, s53
	v_and_or_b32 v17, v9, s77, v8
	v_bfe_u32 v8, v27, 16, 1
	v_add3_u32 v8, v27, v8, s53
	v_bfe_u32 v9, v29, 16, 1
	v_lshrrev_b32_e32 v8, 16, v8
	v_add3_u32 v9, v29, v9, s53
	v_and_or_b32 v18, v9, s77, v8
	v_bfe_u32 v8, v31, 16, 1
	v_add3_u32 v8, v31, v8, s53
	v_bfe_u32 v9, v33, 16, 1
	v_lshrrev_b32_e32 v8, 16, v8
	v_add3_u32 v9, v33, v9, s53
	v_and_or_b32 v19, v9, s77, v8
	v_or_b32_e32 v8, s2, v12
	v_lshlrev_b32_e32 v202, 12, v8
	v_lshl_add_u64 v[8:9], v[6:7], 0, v[202:203]
	global_store_dwordx4 v[8:9], v[16:19], off nt
	ds_read2_b32 v[8:9], v11 offset0:49 offset1:57
	ds_read2_b32 v[20:21], v11 offset0:16 offset1:24
	ds_read2_b32 v[22:23], v11 offset0:82 offset1:90
	ds_read2_b32 v[24:25], v11 offset0:115 offset1:123
	ds_read2_b32 v[26:27], v11 offset0:148 offset1:156
	ds_read2_b32 v[28:29], v11 offset0:181 offset1:189
	ds_read2_b32 v[30:31], v11 offset0:214 offset1:222
	ds_read2_b32 v[32:33], v11 offset0:247 offset1:255
	s_waitcnt lgkmcnt(7)
	v_bfe_u32 v16, v8, 16, 1
	s_waitcnt lgkmcnt(6)
	v_bfe_u32 v15, v20, 16, 1
	v_add3_u32 v15, v20, v15, s53
	v_lshrrev_b32_e32 v15, 16, v15
	v_add3_u32 v8, v8, v16, s53
	v_and_or_b32 v16, v8, s77, v15
	s_waitcnt lgkmcnt(5)
	v_bfe_u32 v8, v22, 16, 1
	v_add3_u32 v8, v22, v8, s53
	s_waitcnt lgkmcnt(4)
	v_bfe_u32 v15, v24, 16, 1
	v_lshrrev_b32_e32 v8, 16, v8
	v_add3_u32 v15, v24, v15, s53
	v_and_or_b32 v17, v15, s77, v8
	s_waitcnt lgkmcnt(3)
	v_bfe_u32 v8, v26, 16, 1
	v_add3_u32 v8, v26, v8, s53
	s_waitcnt lgkmcnt(2)
	v_bfe_u32 v15, v28, 16, 1
	v_lshrrev_b32_e32 v8, 16, v8
	v_add3_u32 v15, v28, v15, s53
	v_and_or_b32 v18, v15, s77, v8
	s_waitcnt lgkmcnt(1)
	v_bfe_u32 v8, v30, 16, 1
	v_add3_u32 v8, v30, v8, s53
	s_waitcnt lgkmcnt(0)
	v_bfe_u32 v15, v32, 16, 1
	v_lshrrev_b32_e32 v8, 16, v8
	v_add3_u32 v15, v32, v15, s53
	v_and_or_b32 v19, v15, s77, v8
	v_or_b32_e32 v8, s2, v13
	v_lshlrev_b32_e32 v202, 12, v8
	v_bfe_u32 v8, v21, 16, 1
	v_add3_u32 v8, v21, v8, s53
	v_bfe_u32 v15, v9, 16, 1
	v_lshl_add_u64 v[34:35], v[6:7], 0, v[202:203]
	v_lshrrev_b32_e32 v8, 16, v8
	v_add3_u32 v9, v9, v15, s53
	global_store_dwordx4 v[34:35], v[16:19], off nt
	v_readlane_b32 s21, v251, 19
	v_readlane_b32 s22, v251, 20
	v_and_or_b32 v16, v9, s77, v8
	v_bfe_u32 v8, v23, 16, 1
	v_add3_u32 v8, v23, v8, s53
	v_bfe_u32 v9, v25, 16, 1
	v_lshrrev_b32_e32 v8, 16, v8
	v_add3_u32 v9, v25, v9, s53
	v_and_or_b32 v17, v9, s77, v8
	v_bfe_u32 v8, v27, 16, 1
	v_add3_u32 v8, v27, v8, s53
	v_bfe_u32 v9, v29, 16, 1
	v_lshrrev_b32_e32 v8, 16, v8
	v_add3_u32 v9, v29, v9, s53
	v_and_or_b32 v18, v9, s77, v8
	v_bfe_u32 v8, v31, 16, 1
	v_add3_u32 v8, v31, v8, s53
	v_bfe_u32 v9, v33, 16, 1
	v_lshrrev_b32_e32 v8, 16, v8
	v_add3_u32 v9, v33, v9, s53
	v_and_or_b32 v19, v9, s77, v8
	v_or_b32_e32 v8, s2, v14
	v_lshlrev_b32_e32 v202, 12, v8
	v_lshl_add_u64 v[6:7], v[6:7], 0, v[202:203]
	global_store_dwordx4 v[6:7], v[16:19], off nt
	s_waitcnt lgkmcnt(0)
	v_readlane_b32 s23, v251, 21
	v_readlane_b32 s24, v251, 22
	v_readlane_b32 s25, v251, 23
	v_readlane_b32 s26, v251, 24
	v_readlane_b32 s27, v251, 25
	v_readlane_b32 s28, v251, 26
	v_readlane_b32 s29, v251, 27
	v_readlane_b32 s30, v251, 28
	v_readlane_b32 s31, v251, 29

.LBB0_900:
	s_andn2_b64 vcc, exec, s[2:3]
	s_cbranch_vccnz .LBB0_902
	v_readlane_b32 s16, v251, 14
	v_readlane_b32 s17, v251, 15
	s_add_u32 s0, s16, s8
	s_addc_u32 s1, s17, s7
	v_readlane_b32 s2, v251, 56
	s_add_u32 s3, s2, s8
	v_readlane_b32 s2, v251, 57
	s_addc_u32 s7, s2, s7
	s_and_b32 s2, 0xffff, s5
	s_mul_i32 s2, s2, 0xba2f
	s_lshr_b32 s8, s2, 23
	s_mul_i32 s2, s8, 0xb0
	s_sub_i32 s2, s5, s2
	s_and_b32 s5, s2, 0xffff
	s_lshl_b32 s2, s5, 5
	s_lshl_b32 s9, s5, 6
	s_and_b32 s9, s9, 0x3f00
	s_and_b32 s2, s2, 0x60
	s_or_b32 s2, s2, s9
	s_lshl_b32 s5, s5, 7
	v_lshl_or_b32 v8, s8, 6, v3
	s_add_u32 s0, s0, s5
	s_addc_u32 s1, s1, 0
	v_lshlrev_b32_e32 v202, 2, v2
	v_mul_u32_u24_e32 v8, 0x1600, v8
	v_lshl_add_u64 v[6:7], s[0:1], 0, v[202:203]
	v_lshlrev_b32_e32 v202, 2, v8
	v_lshl_add_u64 v[6:7], v[6:7], 0, v[202:203]
	s_mov_b32 s0, 0xb000
	v_add_co_u32_e32 v8, vcc, s0, v6
	s_mov_b32 s0, 0x16000
	s_nop 0
	v_addc_co_u32_e32 v9, vcc, 0, v7, vcc
	global_load_dword v15, v[6:7], off nt
	global_load_dword v16, v[8:9], off nt
	v_add_co_u32_e32 v8, vcc, s0, v6
	s_mov_b32 s0, 0x21000
	s_nop 0
	v_addc_co_u32_e32 v9, vcc, 0, v7, vcc
	global_load_dword v17, v[8:9], off nt
	v_add_co_u32_e32 v8, vcc, s0, v6
	s_mov_b32 s0, 0x2c000
	s_nop 0
	v_addc_co_u32_e32 v9, vcc, 0, v7, vcc
	global_load_dword v18, v[8:9], off nt
	v_add_co_u32_e32 v8, vcc, s0, v6
	s_mov_b32 s0, 0x37000
	s_nop 0
	v_addc_co_u32_e32 v9, vcc, 0, v7, vcc
	global_load_dword v19, v[8:9], off nt
	v_add_co_u32_e32 v8, vcc, s0, v6
	s_mov_b32 s0, 0x42000
	s_nop 0
	v_addc_co_u32_e32 v9, vcc, 0, v7, vcc
	global_load_dword v20, v[8:9], off nt
	v_add_co_u32_e32 v8, vcc, s0, v6
	s_mov_b32 s0, 0x4d000
	s_nop 0
	v_addc_co_u32_e32 v9, vcc, 0, v7, vcc
	global_load_dword v21, v[8:9], off nt
	v_add_co_u32_e32 v8, vcc, s0, v6
	s_mov_b32 s0, 0x58000
	s_nop 0
	v_addc_co_u32_e32 v9, vcc, 0, v7, vcc
	global_load_dword v22, v[8:9], off nt
	v_add_co_u32_e32 v8, vcc, s0, v6
	s_mov_b32 s0, 0x63000
	s_nop 0
	v_addc_co_u32_e32 v9, vcc, 0, v7, vcc
	global_load_dword v23, v[8:9], off nt
	v_add_co_u32_e32 v8, vcc, s0, v6
	s_mov_b32 s0, 0x6e000
	s_nop 0
	v_addc_co_u32_e32 v9, vcc, 0, v7, vcc
	global_load_dword v24, v[8:9], off nt
	v_add_co_u32_e32 v8, vcc, s0, v6
	s_mov_b32 s0, 0x79000
	s_nop 0
	v_addc_co_u32_e32 v9, vcc, 0, v7, vcc
	global_load_dword v25, v[8:9], off nt
	v_add_co_u32_e32 v8, vcc, s0, v6
	s_mov_b32 s0, 0x84000
	s_nop 0
	v_addc_co_u32_e32 v9, vcc, 0, v7, vcc
	global_load_dword v26, v[8:9], off nt
	v_add_co_u32_e32 v8, vcc, s0, v6
	s_mov_b32 s0, 0x8f000
	s_nop 0
	v_addc_co_u32_e32 v9, vcc, 0, v7, vcc
	global_load_dword v27, v[8:9], off nt
	v_add_co_u32_e32 v8, vcc, s0, v6
	s_mov_b32 s0, 0x9a000
	s_nop 0
	v_addc_co_u32_e32 v9, vcc, 0, v7, vcc
	global_load_dword v28, v[8:9], off nt
	v_add_co_u32_e32 v8, vcc, s0, v6
	s_mov_b32 s0, 0xa5000
	s_nop 0
	v_addc_co_u32_e32 v9, vcc, 0, v7, vcc
	global_load_dword v29, v[8:9], off nt
	v_add_co_u32_e32 v8, vcc, s0, v6
	s_mov_b32 s0, 0xb0000
	s_nop 0
	v_addc_co_u32_e32 v9, vcc, 0, v7, vcc
	global_load_dword v30, v[8:9], off nt
	v_add_co_u32_e32 v8, vcc, s0, v6
	s_mov_b32 s0, 0xbb000
	s_nop 0
	v_addc_co_u32_e32 v9, vcc, 0, v7, vcc
	global_load_dword v31, v[8:9], off nt
	v_add_co_u32_e32 v8, vcc, s0, v6
	s_mov_b32 s0, 0xc6000
	s_nop 0
	v_addc_co_u32_e32 v9, vcc, 0, v7, vcc
	global_load_dword v32, v[8:9], off nt
	v_add_co_u32_e32 v8, vcc, s0, v6
	s_mov_b32 s0, 0xd1000
	s_nop 0
	v_addc_co_u32_e32 v9, vcc, 0, v7, vcc
	global_load_dword v33, v[8:9], off nt
	v_add_co_u32_e32 v8, vcc, s0, v6
	s_mov_b32 s0, 0xdc000
	s_nop 0
	v_addc_co_u32_e32 v9, vcc, 0, v7, vcc
	global_load_dword v34, v[8:9], off nt
	v_add_co_u32_e32 v8, vcc, s0, v6
	s_mov_b32 s0, 0xe7000
	s_nop 0
	v_addc_co_u32_e32 v9, vcc, 0, v7, vcc
	global_load_dword v35, v[8:9], off nt
	v_add_co_u32_e32 v8, vcc, s0, v6
	s_mov_b32 s0, 0xf2000
	s_nop 0
	v_addc_co_u32_e32 v9, vcc, 0, v7, vcc
	global_load_dword v36, v[8:9], off nt
	v_add_co_u32_e32 v8, vcc, s0, v6
	s_mov_b32 s0, 0xfd000
	s_nop 0
	v_addc_co_u32_e32 v9, vcc, 0, v7, vcc
	global_load_dword v37, v[8:9], off nt
	v_add_co_u32_e32 v8, vcc, s0, v6
	s_mov_b32 s0, 0x108000
	s_nop 0
	v_addc_co_u32_e32 v9, vcc, 0, v7, vcc
	global_load_dword v38, v[8:9], off nt
	v_add_co_u32_e32 v8, vcc, s0, v6
	s_mov_b32 s0, 0x113000
	s_nop 0
	v_addc_co_u32_e32 v9, vcc, 0, v7, vcc
	global_load_dword v39, v[8:9], off nt
	v_add_co_u32_e32 v8, vcc, s0, v6
	s_mov_b32 s0, 0x11e000
	s_nop 0
	v_addc_co_u32_e32 v9, vcc, 0, v7, vcc
	global_load_dword v40, v[8:9], off nt
	v_add_co_u32_e32 v8, vcc, s0, v6
	s_mov_b32 s0, 0x129000
	s_nop 0
	v_addc_co_u32_e32 v9, vcc, 0, v7, vcc
	global_load_dword v41, v[8:9], off nt
	v_add_co_u32_e32 v8, vcc, s0, v6
	s_mov_b32 s0, 0x134000
	s_nop 0
	v_addc_co_u32_e32 v9, vcc, 0, v7, vcc
	global_load_dword v42, v[8:9], off nt
	v_add_co_u32_e32 v8, vcc, s0, v6
	s_mov_b32 s0, 0x13f000
	s_nop 0
	v_addc_co_u32_e32 v9, vcc, 0, v7, vcc
	global_load_dword v43, v[8:9], off nt
	v_add_co_u32_e32 v8, vcc, s0, v6
	s_mov_b32 s0, 0x14a000
	s_nop 0
	v_addc_co_u32_e32 v9, vcc, 0, v7, vcc
	global_load_dword v44, v[8:9], off nt
	v_add_co_u32_e32 v8, vcc, s0, v6
	s_mov_b32 s0, 0x155000
	s_nop 0
	v_addc_co_u32_e32 v9, vcc, 0, v7, vcc
	v_add_co_u32_e32 v6, vcc, s0, v6
	global_load_dword v8, v[8:9], off nt
	s_nop 0
	v_addc_co_u32_e32 v7, vcc, 0, v7, vcc
	global_load_dword v6, v[6:7], off nt
	v_add_u32_e32 v7, 0x400, v5
	s_waitcnt vmcnt(0)
	ds_write2_b32 v5, v15, v16 offset1:66
	ds_write2_b32 v5, v17, v18 offset0:132 offset1:198
	ds_write2_b32 v7, v19, v20 offset0:8 offset1:74
	ds_write2_b32 v7, v21, v22 offset0:140 offset1:206
	v_add_u32_e32 v7, 0x800, v5
	ds_write2_b32 v7, v23, v24 offset0:16 offset1:82
	ds_write2_b32 v7, v25, v26 offset0:148 offset1:214
	v_add_u32_e32 v7, 0xc00, v5
	ds_write2_b32 v7, v27, v28 offset0:24 offset1:90
	ds_write2_b32 v7, v29, v30 offset0:156 offset1:222
	v_add_u32_e32 v7, 0x1000, v5
	ds_write2_b32 v7, v31, v32 offset0:32 offset1:98
	ds_write2_b32 v7, v33, v34 offset0:164 offset1:230
	v_add_u32_e32 v7, 0x1400, v5
	ds_write2_b32 v7, v35, v36 offset0:40 offset1:106
	ds_write2_b32 v7, v37, v38 offset0:172 offset1:238
	v_add_u32_e32 v7, 0x1800, v5
	ds_write2_b32 v7, v39, v40 offset0:48 offset1:114
	ds_write2_b32 v7, v41, v42 offset0:180 offset1:246
	v_add_u32_e32 v7, 0x1c00, v5
	ds_write2_b32 v7, v43, v44 offset0:56 offset1:122
	ds_write2_b32 v7, v8, v6 offset0:188 offset1:254
	s_waitcnt lgkmcnt(0)
	ds_read2_b32 v[8:9], v11 offset0:33 offset1:41
	ds_read2_b32 v[20:21], v11 offset1:8
	ds_read2_b32 v[22:23], v11 offset0:66 offset1:74
	ds_read2_b32 v[24:25], v11 offset0:99 offset1:107
	ds_read2_b32 v[26:27], v11 offset0:132 offset1:140
	ds_read2_b32 v[28:29], v11 offset0:165 offset1:173
	ds_read2_b32 v[30:31], v11 offset0:198 offset1:206
	ds_read2_b32 v[32:33], v11 offset0:231 offset1:239
	s_waitcnt lgkmcnt(7)
	v_bfe_u32 v16, v8, 16, 1
	s_waitcnt lgkmcnt(6)
	v_bfe_u32 v15, v20, 16, 1
	v_add3_u32 v15, v20, v15, s53
	v_lshrrev_b32_e32 v15, 16, v15
	v_add3_u32 v8, v8, v16, s53
	v_and_or_b32 v16, v8, s77, v15
	s_waitcnt lgkmcnt(5)
	v_bfe_u32 v8, v22, 16, 1
	v_add3_u32 v8, v22, v8, s53
	s_waitcnt lgkmcnt(4)
	v_bfe_u32 v15, v24, 16, 1
	v_lshrrev_b32_e32 v8, 16, v8
	v_add3_u32 v15, v24, v15, s53
	v_and_or_b32 v17, v15, s77, v8
	s_waitcnt lgkmcnt(3)
	v_bfe_u32 v8, v26, 16, 1
	v_add3_u32 v8, v26, v8, s53
	s_waitcnt lgkmcnt(2)
	v_bfe_u32 v15, v28, 16, 1
	v_lshrrev_b32_e32 v8, 16, v8
	v_add3_u32 v15, v28, v15, s53
	v_and_or_b32 v18, v15, s77, v8
	s_waitcnt lgkmcnt(1)
	v_bfe_u32 v8, v30, 16, 1
	s_lshl_b32 s0, s8, 7
	v_add3_u32 v8, v30, v8, s53
	s_waitcnt lgkmcnt(0)
	v_bfe_u32 v15, v32, 16, 1
	s_add_u32 s0, s3, s0
	v_lshrrev_b32_e32 v8, 16, v8
	v_add3_u32 v15, v32, v15, s53
	s_addc_u32 s1, s7, 0
	v_lshlrev_b32_e32 v202, 1, v4
	v_and_or_b32 v19, v15, s77, v8
	v_or_b32_e32 v8, s2, v10
	v_lshl_add_u64 v[6:7], s[0:1], 0, v[202:203]
	v_lshlrev_b32_e32 v202, 12, v8
	v_bfe_u32 v8, v21, 16, 1
	v_add3_u32 v8, v21, v8, s53
	v_bfe_u32 v15, v9, 16, 1
	v_lshl_add_u64 v[34:35], v[6:7], 0, v[202:203]
	v_lshrrev_b32_e32 v8, 16, v8
	v_add3_u32 v9, v9, v15, s53
	global_store_dwordx4 v[34:35], v[16:19], off nt
	v_readlane_b32 s18, v251, 16
	v_readlane_b32 s19, v251, 17
	v_and_or_b32 v16, v9, s77, v8
	v_bfe_u32 v8, v23, 16, 1
	v_add3_u32 v8, v23, v8, s53
	v_bfe_u32 v9, v25, 16, 1
	v_lshrrev_b32_e32 v8, 16, v8
	v_add3_u32 v9, v25, v9, s53
	v_and_or_b32 v17, v9, s77, v8
	v_bfe_u32 v8, v27, 16, 1
	v_add3_u32 v8, v27, v8, s53
	v_bfe_u32 v9, v29, 16, 1
	v_lshrrev_b32_e32 v8, 16, v8
	v_add3_u32 v9, v29, v9, s53
	v_and_or_b32 v18, v9, s77, v8
	v_bfe_u32 v8, v31, 16, 1
	v_add3_u32 v8, v31, v8, s53
	v_bfe_u32 v9, v33, 16, 1
	v_lshrrev_b32_e32 v8, 16, v8
	v_add3_u32 v9, v33, v9, s53
	v_and_or_b32 v19, v9, s77, v8
	v_or_b32_e32 v8, s2, v12
	v_lshlrev_b32_e32 v202, 12, v8
	v_lshl_add_u64 v[8:9], v[6:7], 0, v[202:203]
	global_store_dwordx4 v[8:9], v[16:19], off nt
	ds_read2_b32 v[8:9], v11 offset0:49 offset1:57
	ds_read2_b32 v[20:21], v11 offset0:16 offset1:24
	ds_read2_b32 v[22:23], v11 offset0:82 offset1:90
	ds_read2_b32 v[24:25], v11 offset0:115 offset1:123
	ds_read2_b32 v[26:27], v11 offset0:148 offset1:156
	ds_read2_b32 v[28:29], v11 offset0:181 offset1:189
	ds_read2_b32 v[30:31], v11 offset0:214 offset1:222
	ds_read2_b32 v[32:33], v11 offset0:247 offset1:255
	s_waitcnt lgkmcnt(7)
	v_bfe_u32 v16, v8, 16, 1
	s_waitcnt lgkmcnt(6)
	v_bfe_u32 v15, v20, 16, 1
	v_add3_u32 v15, v20, v15, s53
	v_lshrrev_b32_e32 v15, 16, v15
	v_add3_u32 v8, v8, v16, s53
	v_and_or_b32 v16, v8, s77, v15
	s_waitcnt lgkmcnt(5)
	v_bfe_u32 v8, v22, 16, 1
	v_add3_u32 v8, v22, v8, s53
	s_waitcnt lgkmcnt(4)
	v_bfe_u32 v15, v24, 16, 1
	v_lshrrev_b32_e32 v8, 16, v8
	v_add3_u32 v15, v24, v15, s53
	v_and_or_b32 v17, v15, s77, v8
	s_waitcnt lgkmcnt(3)
	v_bfe_u32 v8, v26, 16, 1
	v_add3_u32 v8, v26, v8, s53
	s_waitcnt lgkmcnt(2)
	v_bfe_u32 v15, v28, 16, 1
	v_lshrrev_b32_e32 v8, 16, v8
	v_add3_u32 v15, v28, v15, s53
	v_and_or_b32 v18, v15, s77, v8
	s_waitcnt lgkmcnt(1)
	v_bfe_u32 v8, v30, 16, 1
	v_add3_u32 v8, v30, v8, s53
	s_waitcnt lgkmcnt(0)
	v_bfe_u32 v15, v32, 16, 1
	v_lshrrev_b32_e32 v8, 16, v8
	v_add3_u32 v15, v32, v15, s53
	v_and_or_b32 v19, v15, s77, v8
	v_or_b32_e32 v8, s2, v13
	v_lshlrev_b32_e32 v202, 12, v8
	v_bfe_u32 v8, v21, 16, 1
	v_add3_u32 v8, v21, v8, s53
	v_bfe_u32 v15, v9, 16, 1
	v_lshl_add_u64 v[34:35], v[6:7], 0, v[202:203]
	v_lshrrev_b32_e32 v8, 16, v8
	v_add3_u32 v9, v9, v15, s53
	global_store_dwordx4 v[34:35], v[16:19], off nt
	v_readlane_b32 s20, v251, 18
	v_readlane_b32 s21, v251, 19
	v_and_or_b32 v16, v9, s77, v8
	v_bfe_u32 v8, v23, 16, 1
	v_add3_u32 v8, v23, v8, s53
	v_bfe_u32 v9, v25, 16, 1
	v_lshrrev_b32_e32 v8, 16, v8
	v_add3_u32 v9, v25, v9, s53
	v_and_or_b32 v17, v9, s77, v8
	v_bfe_u32 v8, v27, 16, 1
	v_add3_u32 v8, v27, v8, s53
	v_bfe_u32 v9, v29, 16, 1
	v_lshrrev_b32_e32 v8, 16, v8
	v_add3_u32 v9, v29, v9, s53
	v_and_or_b32 v18, v9, s77, v8
	v_bfe_u32 v8, v31, 16, 1
	v_add3_u32 v8, v31, v8, s53
	v_bfe_u32 v9, v33, 16, 1
	v_lshrrev_b32_e32 v8, 16, v8
	v_add3_u32 v9, v33, v9, s53
	v_and_or_b32 v19, v9, s77, v8
	v_or_b32_e32 v8, s2, v14
	v_lshlrev_b32_e32 v202, 12, v8
	v_lshl_add_u64 v[6:7], v[6:7], 0, v[202:203]
	global_store_dwordx4 v[6:7], v[16:19], off nt
	s_waitcnt lgkmcnt(0)
	v_readlane_b32 s22, v251, 20
	v_readlane_b32 s23, v251, 21
	v_readlane_b32 s24, v251, 22
	v_readlane_b32 s25, v251, 23
	v_readlane_b32 s26, v251, 24
	v_readlane_b32 s27, v251, 25
	v_readlane_b32 s28, v251, 26
	v_readlane_b32 s29, v251, 27
	v_readlane_b32 s30, v251, 28
	v_readlane_b32 s31, v251, 29

.LBB0_903:
	s_andn2_b64 vcc, exec, s[2:3]
	s_cbranch_vccnz .LBB0_905
	s_add_i32 s0, s4, 0xffffc000
	v_readlane_b32 s16, v251, 30
	s_lshr_b32 s86, s0, 12
	v_readlane_b32 s17, v251, 31
	s_lshl_b64 s[0:1], s[86:87], 25
	v_readlane_b32 s18, v251, 32
	v_readlane_b32 s19, v251, 33
	s_mov_b64 s[8:9], s[16:17]
	s_add_u32 s8, s8, s0
	s_addc_u32 s9, s9, s1
	s_lshl_b64 s[0:1], s[86:87], 24
	v_readlane_b32 s2, v251, 58
	s_add_u32 s3, s2, s0
	v_readlane_b32 s0, v251, 59
	s_addc_u32 s5, s0, s1
	s_lshl_b32 s0, s4, 5
	s_and_b32 s2, s0, 0x7e0
	s_and_b32 s7, s4, 0xfc0
	s_lshl_b32 s0, s2, 2
	s_add_u32 s0, s8, s0
	v_or_b32_e32 v8, s7, v3
	s_addc_u32 s1, s9, 0
	v_lshlrev_b32_e32 v202, 2, v2
	v_lshl_add_u64 v[6:7], s[0:1], 0, v[202:203]
	v_lshlrev_b32_e32 v202, 13, v8
	v_lshl_add_u64 v[6:7], v[6:7], 0, v[202:203]
	v_add_co_u32_e32 v8, vcc, s33, v6
	s_mov_b32 s0, 0x8000
	s_nop 0
	v_addc_co_u32_e32 v9, vcc, 0, v7, vcc
	global_load_dword v15, v[6:7], off nt
	global_load_dword v16, v[8:9], off nt
	v_add_co_u32_e32 v8, vcc, s0, v6
	s_mov_b32 s0, 0xc000
	s_nop 0
	v_addc_co_u32_e32 v9, vcc, 0, v7, vcc
	global_load_dword v17, v[8:9], off nt
	v_add_co_u32_e32 v8, vcc, s0, v6
	s_mov_b32 s0, 0x10000
	s_nop 0
	v_addc_co_u32_e32 v9, vcc, 0, v7, vcc
	global_load_dword v18, v[8:9], off nt
	v_add_co_u32_e32 v8, vcc, s0, v6
	s_mov_b32 s0, 0x14000
	s_nop 0
	v_addc_co_u32_e32 v9, vcc, 0, v7, vcc
	global_load_dword v19, v[8:9], off nt
	v_add_co_u32_e32 v8, vcc, s0, v6
	s_mov_b32 s0, 0x18000
	s_nop 0
	v_addc_co_u32_e32 v9, vcc, 0, v7, vcc
	global_load_dword v20, v[8:9], off nt
	v_add_co_u32_e32 v8, vcc, s0, v6
	s_mov_b32 s0, 0x1c000
	s_nop 0
	v_addc_co_u32_e32 v9, vcc, 0, v7, vcc
	global_load_dword v21, v[8:9], off nt
	v_add_co_u32_e32 v8, vcc, s0, v6
	s_mov_b32 s0, 0x24000
	s_nop 0
	v_addc_co_u32_e32 v9, vcc, 0, v7, vcc
	global_load_dword v22, v[8:9], off nt
	v_add_co_u32_e32 v8, vcc, s57, v6
	v_lshlrev_b32_e32 v202, 1, v4
	s_nop 0
	v_addc_co_u32_e32 v9, vcc, 0, v7, vcc
	global_load_dword v23, v[8:9], off nt
	v_add_co_u32_e32 v8, vcc, s0, v6
	s_mov_b32 s0, 0x28000
	s_nop 0
	v_addc_co_u32_e32 v9, vcc, 0, v7, vcc
	global_load_dword v24, v[8:9], off nt
	v_add_co_u32_e32 v8, vcc, s0, v6
	s_mov_b32 s0, 0x2c000
	s_nop 0
	v_addc_co_u32_e32 v9, vcc, 0, v7, vcc
	global_load_dword v25, v[8:9], off nt
	v_add_co_u32_e32 v8, vcc, s0, v6
	s_mov_b32 s0, 0x30000
	s_nop 0
	v_addc_co_u32_e32 v9, vcc, 0, v7, vcc
	global_load_dword v26, v[8:9], off nt
	v_add_co_u32_e32 v8, vcc, s0, v6
	s_mov_b32 s0, 0x34000
	s_nop 0
	v_addc_co_u32_e32 v9, vcc, 0, v7, vcc
	global_load_dword v27, v[8:9], off nt
	v_add_co_u32_e32 v8, vcc, s0, v6
	s_mov_b32 s0, 0x38000
	s_nop 0
	v_addc_co_u32_e32 v9, vcc, 0, v7, vcc
	global_load_dword v28, v[8:9], off nt
	v_add_co_u32_e32 v8, vcc, s0, v6
	s_mov_b32 s0, 0x3c000
	s_nop 0
	v_addc_co_u32_e32 v9, vcc, 0, v7, vcc
	global_load_dword v29, v[8:9], off nt
	v_add_co_u32_e32 v8, vcc, s0, v6
	s_mov_b32 s0, 0x44000
	s_nop 0
	v_addc_co_u32_e32 v9, vcc, 0, v7, vcc
	global_load_dword v30, v[8:9], off nt
	v_add_co_u32_e32 v8, vcc, s88, v6
	v_readlane_b32 s20, v251, 34
	s_nop 0
	v_addc_co_u32_e32 v9, vcc, 0, v7, vcc
	global_load_dword v31, v[8:9], off nt
	v_add_co_u32_e32 v8, vcc, s0, v6
	s_mov_b32 s0, 0x48000
	s_nop 0
	v_addc_co_u32_e32 v9, vcc, 0, v7, vcc
	global_load_dword v32, v[8:9], off nt
	v_add_co_u32_e32 v8, vcc, s0, v6
	s_mov_b32 s0, 0x4c000
	s_nop 0
	v_addc_co_u32_e32 v9, vcc, 0, v7, vcc
	global_load_dword v33, v[8:9], off nt
	v_add_co_u32_e32 v8, vcc, s0, v6
	s_mov_b32 s0, 0x50000
	s_nop 0
	v_addc_co_u32_e32 v9, vcc, 0, v7, vcc
	global_load_dword v34, v[8:9], off nt
	v_add_co_u32_e32 v8, vcc, s0, v6
	s_mov_b32 s0, 0x54000
	s_nop 0
	v_addc_co_u32_e32 v9, vcc, 0, v7, vcc
	global_load_dword v35, v[8:9], off nt
	v_add_co_u32_e32 v8, vcc, s0, v6
	s_mov_b32 s0, 0x58000
	s_nop 0
	v_addc_co_u32_e32 v9, vcc, 0, v7, vcc
	global_load_dword v36, v[8:9], off nt
	v_add_co_u32_e32 v8, vcc, s0, v6
	s_mov_b32 s0, 0x5c000
	s_nop 0
	v_addc_co_u32_e32 v9, vcc, 0, v7, vcc
	global_load_dword v37, v[8:9], off nt
	v_add_co_u32_e32 v8, vcc, s0, v6
	s_mov_b32 s0, 0x60000
	s_nop 0
	v_addc_co_u32_e32 v9, vcc, 0, v7, vcc
	global_load_dword v38, v[8:9], off nt
	v_add_co_u32_e32 v8, vcc, s0, v6
	s_mov_b32 s0, 0x64000
	s_nop 0
	v_addc_co_u32_e32 v9, vcc, 0, v7, vcc
	global_load_dword v39, v[8:9], off nt
	v_add_co_u32_e32 v8, vcc, s0, v6
	s_mov_b32 s0, 0x68000
	s_nop 0
	v_addc_co_u32_e32 v9, vcc, 0, v7, vcc
	global_load_dword v40, v[8:9], off nt
	v_add_co_u32_e32 v8, vcc, s0, v6
	s_mov_b32 s0, 0x6c000
	s_nop 0
	v_addc_co_u32_e32 v9, vcc, 0, v7, vcc
	global_load_dword v41, v[8:9], off nt
	v_add_co_u32_e32 v8, vcc, s0, v6
	s_mov_b32 s0, 0x70000
	s_nop 0
	v_addc_co_u32_e32 v9, vcc, 0, v7, vcc
	global_load_dword v42, v[8:9], off nt
	v_add_co_u32_e32 v8, vcc, s0, v6
	s_mov_b32 s0, 0x74000
	s_nop 0
	v_addc_co_u32_e32 v9, vcc, 0, v7, vcc
	global_load_dword v43, v[8:9], off nt
	v_add_co_u32_e32 v8, vcc, s0, v6
	s_mov_b32 s0, 0x78000
	s_nop 0
	v_addc_co_u32_e32 v9, vcc, 0, v7, vcc
	global_load_dword v44, v[8:9], off nt
	v_add_co_u32_e32 v8, vcc, s0, v6
	s_mov_b32 s0, 0x7c000
	s_nop 0
	v_addc_co_u32_e32 v9, vcc, 0, v7, vcc
	v_add_co_u32_e32 v6, vcc, s0, v6
	global_load_dword v8, v[8:9], off nt
	s_nop 0
	v_addc_co_u32_e32 v7, vcc, 0, v7, vcc
	global_load_dword v6, v[6:7], off nt
	v_add_u32_e32 v7, 0x400, v5
	s_waitcnt vmcnt(0)
	ds_write2_b32 v5, v15, v16 offset1:66
	ds_write2_b32 v5, v17, v18 offset0:132 offset1:198
	ds_write2_b32 v7, v19, v20 offset0:8 offset1:74
	ds_write2_b32 v7, v21, v22 offset0:140 offset1:206
	v_add_u32_e32 v7, 0x800, v5
	ds_write2_b32 v7, v23, v24 offset0:16 offset1:82
	ds_write2_b32 v7, v25, v26 offset0:148 offset1:214
	v_add_u32_e32 v7, 0xc00, v5
	ds_write2_b32 v7, v27, v28 offset0:24 offset1:90
	ds_write2_b32 v7, v29, v30 offset0:156 offset1:222
	v_add_u32_e32 v7, 0x1000, v5
	ds_write2_b32 v7, v31, v32 offset0:32 offset1:98
	ds_write2_b32 v7, v33, v34 offset0:164 offset1:230
	v_add_u32_e32 v7, 0x1400, v5
	ds_write2_b32 v7, v35, v36 offset0:40 offset1:106
	ds_write2_b32 v7, v37, v38 offset0:172 offset1:238
	v_add_u32_e32 v7, 0x1800, v5
	ds_write2_b32 v7, v39, v40 offset0:48 offset1:114
	ds_write2_b32 v7, v41, v42 offset0:180 offset1:246
	v_add_u32_e32 v7, 0x1c00, v5
	ds_write2_b32 v7, v43, v44 offset0:56 offset1:122
	ds_write2_b32 v7, v8, v6 offset0:188 offset1:254
	s_waitcnt lgkmcnt(0)
	ds_read2_b32 v[8:9], v11 offset0:33 offset1:41
	ds_read2_b32 v[20:21], v11 offset1:8
	ds_read2_b32 v[22:23], v11 offset0:66 offset1:74
	ds_read2_b32 v[24:25], v11 offset0:99 offset1:107
	ds_read2_b32 v[26:27], v11 offset0:132 offset1:140
	ds_read2_b32 v[28:29], v11 offset0:165 offset1:173
	ds_read2_b32 v[30:31], v11 offset0:198 offset1:206
	ds_read2_b32 v[32:33], v11 offset0:231 offset1:239
	s_waitcnt lgkmcnt(7)
	v_bfe_u32 v16, v8, 16, 1
	s_waitcnt lgkmcnt(6)
	v_bfe_u32 v15, v20, 16, 1
	v_add3_u32 v15, v20, v15, s53
	v_lshrrev_b32_e32 v15, 16, v15
	v_add3_u32 v8, v8, v16, s53
	v_and_or_b32 v16, v8, s77, v15
	s_waitcnt lgkmcnt(5)
	v_bfe_u32 v8, v22, 16, 1
	v_add3_u32 v8, v22, v8, s53
	s_waitcnt lgkmcnt(4)
	v_bfe_u32 v15, v24, 16, 1
	v_lshrrev_b32_e32 v8, 16, v8
	v_add3_u32 v15, v24, v15, s53
	v_and_or_b32 v17, v15, s77, v8
	s_waitcnt lgkmcnt(3)
	v_bfe_u32 v8, v26, 16, 1
	v_add3_u32 v8, v26, v8, s53
	s_waitcnt lgkmcnt(2)
	v_bfe_u32 v15, v28, 16, 1
	v_lshrrev_b32_e32 v8, 16, v8
	v_add3_u32 v15, v28, v15, s53
	v_and_or_b32 v18, v15, s77, v8
	s_waitcnt lgkmcnt(1)
	v_bfe_u32 v8, v30, 16, 1
	s_lshl_b32 s0, s7, 1
	v_add3_u32 v8, v30, v8, s53
	s_waitcnt lgkmcnt(0)
	v_bfe_u32 v15, v32, 16, 1
	s_add_u32 s0, s3, s0
	v_lshrrev_b32_e32 v8, 16, v8
	v_add3_u32 v15, v32, v15, s53
	s_addc_u32 s1, s5, 0
	v_and_or_b32 v19, v15, s77, v8
	v_or_b32_e32 v8, s2, v10
	v_lshl_add_u64 v[6:7], s[0:1], 0, v[202:203]
	v_lshlrev_b32_e32 v202, 13, v8
	v_bfe_u32 v8, v21, 16, 1
	v_add3_u32 v8, v21, v8, s53
	v_bfe_u32 v15, v9, 16, 1
	v_lshl_add_u64 v[34:35], v[6:7], 0, v[202:203]
	v_lshrrev_b32_e32 v8, 16, v8
	v_add3_u32 v9, v9, v15, s53
	global_store_dwordx4 v[34:35], v[16:19], off nt
	v_readlane_b32 s21, v251, 35
	v_readlane_b32 s22, v251, 36
	v_and_or_b32 v16, v9, s77, v8
	v_bfe_u32 v8, v23, 16, 1
	v_add3_u32 v8, v23, v8, s53
	v_bfe_u32 v9, v25, 16, 1
	v_lshrrev_b32_e32 v8, 16, v8
	v_add3_u32 v9, v25, v9, s53
	v_and_or_b32 v17, v9, s77, v8
	v_bfe_u32 v8, v27, 16, 1
	v_add3_u32 v8, v27, v8, s53
	v_bfe_u32 v9, v29, 16, 1
	v_lshrrev_b32_e32 v8, 16, v8
	v_add3_u32 v9, v29, v9, s53
	v_and_or_b32 v18, v9, s77, v8
	v_bfe_u32 v8, v31, 16, 1
	v_add3_u32 v8, v31, v8, s53
	v_bfe_u32 v9, v33, 16, 1
	v_lshrrev_b32_e32 v8, 16, v8
	v_add3_u32 v9, v33, v9, s53
	v_and_or_b32 v19, v9, s77, v8
	v_or_b32_e32 v8, s2, v12
	v_lshlrev_b32_e32 v202, 13, v8
	v_lshl_add_u64 v[8:9], v[6:7], 0, v[202:203]
	global_store_dwordx4 v[8:9], v[16:19], off nt
	ds_read2_b32 v[8:9], v11 offset0:49 offset1:57
	ds_read2_b32 v[20:21], v11 offset0:16 offset1:24
	ds_read2_b32 v[22:23], v11 offset0:82 offset1:90
	ds_read2_b32 v[24:25], v11 offset0:115 offset1:123
	ds_read2_b32 v[26:27], v11 offset0:148 offset1:156
	ds_read2_b32 v[28:29], v11 offset0:181 offset1:189
	ds_read2_b32 v[30:31], v11 offset0:214 offset1:222
	ds_read2_b32 v[32:33], v11 offset0:247 offset1:255
	s_waitcnt lgkmcnt(7)
	v_bfe_u32 v16, v8, 16, 1
	s_waitcnt lgkmcnt(6)
	v_bfe_u32 v15, v20, 16, 1
	v_add3_u32 v15, v20, v15, s53
	v_lshrrev_b32_e32 v15, 16, v15
	v_add3_u32 v8, v8, v16, s53
	v_and_or_b32 v16, v8, s77, v15
	s_waitcnt lgkmcnt(5)
	v_bfe_u32 v8, v22, 16, 1
	v_add3_u32 v8, v22, v8, s53
	s_waitcnt lgkmcnt(4)
	v_bfe_u32 v15, v24, 16, 1
	v_lshrrev_b32_e32 v8, 16, v8
	v_add3_u32 v15, v24, v15, s53
	v_and_or_b32 v17, v15, s77, v8
	s_waitcnt lgkmcnt(3)
	v_bfe_u32 v8, v26, 16, 1
	v_add3_u32 v8, v26, v8, s53
	s_waitcnt lgkmcnt(2)
	v_bfe_u32 v15, v28, 16, 1
	v_lshrrev_b32_e32 v8, 16, v8
	v_add3_u32 v15, v28, v15, s53
	v_and_or_b32 v18, v15, s77, v8
	s_waitcnt lgkmcnt(1)
	v_bfe_u32 v8, v30, 16, 1
	v_add3_u32 v8, v30, v8, s53
	s_waitcnt lgkmcnt(0)
	v_bfe_u32 v15, v32, 16, 1
	v_lshrrev_b32_e32 v8, 16, v8
	v_add3_u32 v15, v32, v15, s53
	v_and_or_b32 v19, v15, s77, v8
	v_or_b32_e32 v8, s2, v13
	v_lshlrev_b32_e32 v202, 13, v8
	v_bfe_u32 v8, v21, 16, 1
	v_add3_u32 v8, v21, v8, s53
	v_bfe_u32 v15, v9, 16, 1
	v_lshl_add_u64 v[34:35], v[6:7], 0, v[202:203]
	v_lshrrev_b32_e32 v8, 16, v8
	v_add3_u32 v9, v9, v15, s53
	global_store_dwordx4 v[34:35], v[16:19], off nt
	v_readlane_b32 s23, v251, 37
	v_readlane_b32 s24, v251, 38
	v_and_or_b32 v16, v9, s77, v8
	v_bfe_u32 v8, v23, 16, 1
	v_add3_u32 v8, v23, v8, s53
	v_bfe_u32 v9, v25, 16, 1
	v_lshrrev_b32_e32 v8, 16, v8
	v_add3_u32 v9, v25, v9, s53
	v_and_or_b32 v17, v9, s77, v8
	v_bfe_u32 v8, v27, 16, 1
	v_add3_u32 v8, v27, v8, s53
	v_bfe_u32 v9, v29, 16, 1
	v_lshrrev_b32_e32 v8, 16, v8
	v_add3_u32 v9, v29, v9, s53
	v_and_or_b32 v18, v9, s77, v8
	v_bfe_u32 v8, v31, 16, 1
	v_add3_u32 v8, v31, v8, s53
	v_bfe_u32 v9, v33, 16, 1
	v_lshrrev_b32_e32 v8, 16, v8
	v_add3_u32 v9, v33, v9, s53
	v_and_or_b32 v19, v9, s77, v8
	v_or_b32_e32 v8, s2, v14
	v_lshlrev_b32_e32 v202, 13, v8
	v_lshl_add_u64 v[6:7], v[6:7], 0, v[202:203]
	global_store_dwordx4 v[6:7], v[16:19], off nt
	s_waitcnt lgkmcnt(0)
	v_readlane_b32 s25, v251, 39
	v_readlane_b32 s26, v251, 40
	v_readlane_b32 s27, v251, 41
	v_readlane_b32 s28, v251, 42
	v_readlane_b32 s29, v251, 43
	v_readlane_b32 s30, v251, 44
	v_readlane_b32 s31, v251, 45
	s_mov_b64 s[10:11], s[18:19]

.LBB0_907:
	s_ashr_i32 s0, s4, 31
	s_lshr_b32 s0, s0, 19
	s_add_i32 s1, s4, s0
	s_ashr_i32 s0, s1, 13
	s_and_b32 s1, s1, 0xe000
	s_sub_i32 s4, s4, s1
	s_ashr_i32 s1, s0, 31
	v_readlane_b32 s16, v251, 14
	s_lshl_b64 s[2:3], s[0:1], 26
	v_readlane_b32 s22, v251, 20
	v_readlane_b32 s23, v251, 21
	s_add_u32 s5, s22, s2
	s_addc_u32 s9, s23, s3
	s_lshl_b64 s[0:1], s[0:1], 25
	v_readlane_b32 s2, v251, 60
	s_add_u32 s7, s2, s0
	v_readlane_b32 s0, v251, 61
	s_addc_u32 s8, s0, s1
	s_sext_i32_i16 s0, s4
	s_bfe_u32 s0, s0, 0x80017
	s_add_i32 s0, s4, s0
	s_sext_i32_i16 s1, s0
	s_and_b32 s0, s0, 0xff00
	s_sub_i32 s0, s4, s0
	s_sext_i32_i16 s0, s0
	s_lshl_b32 s2, s0, 5
	s_ashr_i32 s1, s1, 8
	s_ashr_i32 s3, s2, 31
	s_lshl_b32 s4, s1, 6
	s_lshl_b64 s[0:1], s[2:3], 2
	v_or_b32_e32 v6, s4, v3
	s_add_u32 s0, s5, s0
	s_addc_u32 s1, s9, s1
	v_lshlrev_b32_e32 v202, 2, v2
	v_ashrrev_i32_e32 v7, 31, v6
	v_lshl_add_u64 v[8:9], s[0:1], 0, v[202:203]
	v_lshlrev_b64 v[16:17], 15, v[6:7]
	v_lshl_add_u64 v[16:17], v[8:9], 0, v[16:17]
	global_load_dword v15, v[16:17], off nt
	v_or_b32_e32 v16, 2, v6
	v_ashrrev_i32_e32 v17, 31, v16
	v_lshlrev_b64 v[16:17], 15, v[16:17]
	v_lshl_add_u64 v[16:17], v[8:9], 0, v[16:17]
	global_load_dword v18, v[16:17], off nt
	v_or_b32_e32 v16, 4, v6
	v_ashrrev_i32_e32 v17, 31, v16
	v_lshlrev_b64 v[16:17], 15, v[16:17]
	v_lshl_add_u64 v[16:17], v[8:9], 0, v[16:17]
	global_load_dword v19, v[16:17], off nt
	v_or_b32_e32 v16, 6, v6
	v_ashrrev_i32_e32 v17, 31, v16
	v_lshlrev_b64 v[16:17], 15, v[16:17]
	v_lshl_add_u64 v[16:17], v[8:9], 0, v[16:17]
	global_load_dword v20, v[16:17], off nt
	v_or_b32_e32 v16, 8, v6
	v_ashrrev_i32_e32 v17, 31, v16
	v_lshlrev_b64 v[16:17], 15, v[16:17]
	v_lshl_add_u64 v[16:17], v[8:9], 0, v[16:17]
	global_load_dword v21, v[16:17], off nt
	v_or_b32_e32 v16, 10, v6
	v_ashrrev_i32_e32 v17, 31, v16
	v_lshlrev_b64 v[16:17], 15, v[16:17]
	v_lshl_add_u64 v[16:17], v[8:9], 0, v[16:17]
	global_load_dword v22, v[16:17], off nt
	v_or_b32_e32 v16, 12, v6
	v_ashrrev_i32_e32 v17, 31, v16
	v_lshlrev_b64 v[16:17], 15, v[16:17]
	v_lshl_add_u64 v[16:17], v[8:9], 0, v[16:17]
	global_load_dword v23, v[16:17], off nt
	v_or_b32_e32 v16, 14, v6
	v_ashrrev_i32_e32 v17, 31, v16
	v_lshlrev_b64 v[16:17], 15, v[16:17]
	v_lshl_add_u64 v[16:17], v[8:9], 0, v[16:17]
	global_load_dword v24, v[16:17], off nt
	v_or_b32_e32 v16, 16, v6
	v_ashrrev_i32_e32 v17, 31, v16
	v_lshlrev_b64 v[16:17], 15, v[16:17]
	v_lshl_add_u64 v[16:17], v[8:9], 0, v[16:17]
	global_load_dword v25, v[16:17], off nt
	v_or_b32_e32 v16, 18, v6
	v_ashrrev_i32_e32 v17, 31, v16
	v_lshlrev_b64 v[16:17], 15, v[16:17]
	v_lshl_add_u64 v[16:17], v[8:9], 0, v[16:17]
	global_load_dword v26, v[16:17], off nt
	v_or_b32_e32 v16, 20, v6
	v_ashrrev_i32_e32 v17, 31, v16
	v_lshlrev_b64 v[16:17], 15, v[16:17]
	v_lshl_add_u64 v[16:17], v[8:9], 0, v[16:17]
	global_load_dword v27, v[16:17], off nt
	v_or_b32_e32 v16, 22, v6
	v_ashrrev_i32_e32 v17, 31, v16
	v_lshlrev_b64 v[16:17], 15, v[16:17]
	v_lshl_add_u64 v[16:17], v[8:9], 0, v[16:17]
	global_load_dword v28, v[16:17], off nt
	v_or_b32_e32 v16, 24, v6
	v_ashrrev_i32_e32 v17, 31, v16
	v_lshlrev_b64 v[16:17], 15, v[16:17]
	v_lshl_add_u64 v[16:17], v[8:9], 0, v[16:17]
	global_load_dword v29, v[16:17], off nt
	v_or_b32_e32 v16, 26, v6
	v_ashrrev_i32_e32 v17, 31, v16
	v_lshlrev_b64 v[16:17], 15, v[16:17]
	v_lshl_add_u64 v[16:17], v[8:9], 0, v[16:17]
	global_load_dword v30, v[16:17], off nt
	v_or_b32_e32 v16, 28, v6
	v_ashrrev_i32_e32 v17, 31, v16
	v_lshlrev_b64 v[16:17], 15, v[16:17]
	v_lshl_add_u64 v[16:17], v[8:9], 0, v[16:17]
	global_load_dword v31, v[16:17], off nt
	v_or_b32_e32 v16, 30, v6
	v_ashrrev_i32_e32 v17, 31, v16
	v_lshlrev_b64 v[16:17], 15, v[16:17]
	v_lshl_add_u64 v[16:17], v[8:9], 0, v[16:17]
	global_load_dword v32, v[16:17], off nt
	v_or_b32_e32 v16, 32, v6
	v_ashrrev_i32_e32 v17, 31, v16
	v_lshlrev_b64 v[16:17], 15, v[16:17]
	v_lshl_add_u64 v[16:17], v[8:9], 0, v[16:17]
	global_load_dword v33, v[16:17], off nt
	v_or_b32_e32 v16, 34, v6
	v_ashrrev_i32_e32 v17, 31, v16
	v_lshlrev_b64 v[16:17], 15, v[16:17]
	v_lshl_add_u64 v[16:17], v[8:9], 0, v[16:17]
	global_load_dword v34, v[16:17], off nt
	v_or_b32_e32 v16, 36, v6
	v_ashrrev_i32_e32 v17, 31, v16
	v_lshlrev_b64 v[16:17], 15, v[16:17]
	v_lshl_add_u64 v[16:17], v[8:9], 0, v[16:17]
	global_load_dword v35, v[16:17], off nt
	v_or_b32_e32 v16, 38, v6
	v_ashrrev_i32_e32 v17, 31, v16
	v_lshlrev_b64 v[16:17], 15, v[16:17]
	v_lshl_add_u64 v[16:17], v[8:9], 0, v[16:17]
	global_load_dword v36, v[16:17], off nt
	v_or_b32_e32 v16, 40, v6
	v_ashrrev_i32_e32 v17, 31, v16
	v_lshlrev_b64 v[16:17], 15, v[16:17]
	v_lshl_add_u64 v[16:17], v[8:9], 0, v[16:17]
	global_load_dword v37, v[16:17], off nt
	v_or_b32_e32 v16, 42, v6
	v_ashrrev_i32_e32 v17, 31, v16
	v_lshlrev_b64 v[16:17], 15, v[16:17]
	v_lshl_add_u64 v[16:17], v[8:9], 0, v[16:17]
	global_load_dword v38, v[16:17], off nt
	v_or_b32_e32 v16, 44, v6
	v_ashrrev_i32_e32 v17, 31, v16
	v_lshlrev_b64 v[16:17], 15, v[16:17]
	v_lshl_add_u64 v[16:17], v[8:9], 0, v[16:17]
	global_load_dword v39, v[16:17], off nt
	v_or_b32_e32 v16, 46, v6
	v_ashrrev_i32_e32 v17, 31, v16
	v_lshlrev_b64 v[16:17], 15, v[16:17]
	v_lshl_add_u64 v[16:17], v[8:9], 0, v[16:17]
	global_load_dword v40, v[16:17], off nt
	v_or_b32_e32 v16, 48, v6
	v_ashrrev_i32_e32 v17, 31, v16
	v_lshlrev_b64 v[16:17], 15, v[16:17]
	v_lshl_add_u64 v[16:17], v[8:9], 0, v[16:17]
	global_load_dword v41, v[16:17], off nt
	v_or_b32_e32 v16, 50, v6
	v_ashrrev_i32_e32 v17, 31, v16
	v_lshlrev_b64 v[16:17], 15, v[16:17]
	v_lshl_add_u64 v[16:17], v[8:9], 0, v[16:17]
	global_load_dword v42, v[16:17], off nt
	v_or_b32_e32 v16, 52, v6
	v_ashrrev_i32_e32 v17, 31, v16
	v_lshlrev_b64 v[16:17], 15, v[16:17]
	v_lshl_add_u64 v[16:17], v[8:9], 0, v[16:17]
	global_load_dword v43, v[16:17], off nt
	v_or_b32_e32 v16, 54, v6
	v_ashrrev_i32_e32 v17, 31, v16
	v_lshlrev_b64 v[16:17], 15, v[16:17]
	v_lshl_add_u64 v[16:17], v[8:9], 0, v[16:17]
	global_load_dword v44, v[16:17], off nt
	v_or_b32_e32 v16, 56, v6
	v_ashrrev_i32_e32 v17, 31, v16
	v_lshlrev_b64 v[16:17], 15, v[16:17]
	v_lshl_add_u64 v[16:17], v[8:9], 0, v[16:17]
	global_load_dword v45, v[16:17], off nt
	v_or_b32_e32 v16, 58, v6
	v_ashrrev_i32_e32 v17, 31, v16
	v_lshlrev_b64 v[16:17], 15, v[16:17]
	v_lshl_add_u64 v[16:17], v[8:9], 0, v[16:17]
	global_load_dword v46, v[16:17], off nt
	v_or_b32_e32 v16, 60, v6
	v_or_b32_e32 v6, 62, v6
	v_ashrrev_i32_e32 v17, 31, v16
	v_ashrrev_i32_e32 v7, 31, v6
	v_lshlrev_b64 v[16:17], 15, v[16:17]
	v_lshlrev_b64 v[6:7], 15, v[6:7]
	v_lshl_add_u64 v[16:17], v[8:9], 0, v[16:17]
	v_lshl_add_u64 v[6:7], v[8:9], 0, v[6:7]
	global_load_dword v16, v[16:17], off nt
	s_ashr_i32 s5, s4, 31
	global_load_dword v6, v[6:7], off nt
	v_add_u32_e32 v7, 0x400, v5
	s_waitcnt vmcnt(0)
	ds_write2_b32 v5, v15, v18 offset1:66
	ds_write2_b32 v5, v19, v20 offset0:132 offset1:198
	ds_write2_b32 v7, v21, v22 offset0:8 offset1:74
	ds_write2_b32 v7, v23, v24 offset0:140 offset1:206
	v_add_u32_e32 v7, 0x800, v5
	ds_write2_b32 v7, v25, v26 offset0:16 offset1:82
	ds_write2_b32 v7, v27, v28 offset0:148 offset1:214
	v_add_u32_e32 v7, 0xc00, v5
	ds_write2_b32 v7, v29, v30 offset0:24 offset1:90
	ds_write2_b32 v7, v31, v32 offset0:156 offset1:222
	v_add_u32_e32 v7, 0x1000, v5
	ds_write2_b32 v7, v33, v34 offset0:32 offset1:98
	ds_write2_b32 v7, v35, v36 offset0:164 offset1:230
	v_add_u32_e32 v7, 0x1400, v5
	ds_write2_b32 v7, v37, v38 offset0:40 offset1:106
	ds_write2_b32 v7, v39, v40 offset0:172 offset1:238
	v_add_u32_e32 v7, 0x1800, v5
	ds_write2_b32 v7, v41, v42 offset0:48 offset1:114
	ds_write2_b32 v7, v43, v44 offset0:180 offset1:246
	v_add_u32_e32 v7, 0x1c00, v5
	ds_write2_b32 v7, v45, v46 offset0:56 offset1:122
	ds_write2_b32 v7, v16, v6 offset0:188 offset1:254
	s_waitcnt lgkmcnt(0)
	ds_read2_b32 v[8:9], v11 offset0:33 offset1:41
	ds_read2_b32 v[20:21], v11 offset1:8
	ds_read2_b32 v[22:23], v11 offset0:66 offset1:74
	ds_read2_b32 v[24:25], v11 offset0:99 offset1:107
	ds_read2_b32 v[26:27], v11 offset0:132 offset1:140
	ds_read2_b32 v[28:29], v11 offset0:165 offset1:173
	ds_read2_b32 v[30:31], v11 offset0:198 offset1:206
	ds_read2_b32 v[32:33], v11 offset0:231 offset1:239
	s_waitcnt lgkmcnt(7)
	v_bfe_u32 v16, v8, 16, 1
	s_waitcnt lgkmcnt(6)
	v_bfe_u32 v15, v20, 16, 1
	v_add3_u32 v15, v20, v15, s53
	v_lshrrev_b32_e32 v15, 16, v15
	v_add3_u32 v8, v8, v16, s53
	v_and_or_b32 v16, v8, s77, v15
	s_waitcnt lgkmcnt(5)
	v_bfe_u32 v8, v22, 16, 1
	v_add3_u32 v8, v22, v8, s53
	s_waitcnt lgkmcnt(4)
	v_bfe_u32 v15, v24, 16, 1
	v_lshrrev_b32_e32 v8, 16, v8
	v_add3_u32 v15, v24, v15, s53
	v_and_or_b32 v17, v15, s77, v8
	s_waitcnt lgkmcnt(3)
	v_bfe_u32 v8, v26, 16, 1
	v_add3_u32 v8, v26, v8, s53
	s_waitcnt lgkmcnt(2)
	v_bfe_u32 v15, v28, 16, 1
	v_lshrrev_b32_e32 v8, 16, v8
	v_add3_u32 v15, v28, v15, s53
	v_and_or_b32 v18, v15, s77, v8
	s_waitcnt lgkmcnt(1)
	v_bfe_u32 v8, v30, 16, 1
	s_lshl_b64 s[0:1], s[4:5], 1
	v_add3_u32 v8, v30, v8, s53
	s_waitcnt lgkmcnt(0)
	v_bfe_u32 v15, v32, 16, 1
	s_add_u32 s0, s7, s0
	v_lshrrev_b32_e32 v8, 16, v8
	v_add3_u32 v15, v32, v15, s53
	v_or_b32_e32 v34, s2, v10
	s_addc_u32 s1, s8, s1
	v_lshlrev_b32_e32 v202, 1, v4
	v_and_or_b32 v19, v15, s77, v8
	v_ashrrev_i32_e32 v35, 31, v34
	v_bfe_u32 v8, v21, 16, 1
	v_lshl_add_u64 v[6:7], s[0:1], 0, v[202:203]
	v_lshlrev_b64 v[34:35], 12, v[34:35]
	v_add3_u32 v8, v21, v8, s53
	v_bfe_u32 v15, v9, 16, 1
	v_lshl_add_u64 v[34:35], v[6:7], 0, v[34:35]
	v_lshrrev_b32_e32 v8, 16, v8
	v_add3_u32 v9, v9, v15, s53
	global_store_dwordx4 v[34:35], v[16:19], off nt
	v_or_b32_e32 v34, s2, v13
	v_ashrrev_i32_e32 v35, 31, v34
	v_and_or_b32 v16, v9, s77, v8
	v_bfe_u32 v8, v23, 16, 1
	v_add3_u32 v8, v23, v8, s53
	v_bfe_u32 v9, v25, 16, 1
	v_lshrrev_b32_e32 v8, 16, v8
	v_add3_u32 v9, v25, v9, s53
	v_and_or_b32 v17, v9, s77, v8
	v_bfe_u32 v8, v27, 16, 1
	v_add3_u32 v8, v27, v8, s53
	v_bfe_u32 v9, v29, 16, 1
	v_lshrrev_b32_e32 v8, 16, v8
	v_add3_u32 v9, v29, v9, s53
	v_and_or_b32 v18, v9, s77, v8
	v_bfe_u32 v8, v31, 16, 1
	v_add3_u32 v8, v31, v8, s53
	v_bfe_u32 v9, v33, 16, 1
	v_lshrrev_b32_e32 v8, 16, v8
	v_add3_u32 v9, v33, v9, s53
	v_and_or_b32 v19, v9, s77, v8
	v_or_b32_e32 v8, s2, v12
	v_ashrrev_i32_e32 v9, 31, v8
	v_lshlrev_b64 v[8:9], 12, v[8:9]
	v_lshl_add_u64 v[8:9], v[6:7], 0, v[8:9]
	global_store_dwordx4 v[8:9], v[16:19], off nt
	ds_read2_b32 v[8:9], v11 offset0:49 offset1:57
	ds_read2_b32 v[20:21], v11 offset0:16 offset1:24
	ds_read2_b32 v[22:23], v11 offset0:82 offset1:90
	ds_read2_b32 v[24:25], v11 offset0:115 offset1:123
	ds_read2_b32 v[26:27], v11 offset0:148 offset1:156
	ds_read2_b32 v[28:29], v11 offset0:181 offset1:189
	ds_read2_b32 v[30:31], v11 offset0:214 offset1:222
	ds_read2_b32 v[32:33], v11 offset0:247 offset1:255
	s_waitcnt lgkmcnt(7)
	v_bfe_u32 v16, v8, 16, 1
	s_waitcnt lgkmcnt(6)
	v_bfe_u32 v15, v20, 16, 1
	v_add3_u32 v15, v20, v15, s53
	v_lshrrev_b32_e32 v15, 16, v15
	v_add3_u32 v8, v8, v16, s53
	v_and_or_b32 v16, v8, s77, v15
	s_waitcnt lgkmcnt(5)
	v_bfe_u32 v8, v22, 16, 1
	v_add3_u32 v8, v22, v8, s53
	s_waitcnt lgkmcnt(4)
	v_bfe_u32 v15, v24, 16, 1
	v_lshrrev_b32_e32 v8, 16, v8
	v_add3_u32 v15, v24, v15, s53
	v_and_or_b32 v17, v15, s77, v8
	s_waitcnt lgkmcnt(3)
	v_bfe_u32 v8, v26, 16, 1
	v_add3_u32 v8, v26, v8, s53
	s_waitcnt lgkmcnt(2)
	v_bfe_u32 v15, v28, 16, 1
	v_lshrrev_b32_e32 v8, 16, v8
	v_add3_u32 v15, v28, v15, s53
	v_and_or_b32 v18, v15, s77, v8
	s_waitcnt lgkmcnt(1)
	v_bfe_u32 v8, v30, 16, 1
	v_add3_u32 v8, v30, v8, s53
	s_waitcnt lgkmcnt(0)
	v_bfe_u32 v15, v32, 16, 1
	v_lshrrev_b32_e32 v8, 16, v8
	v_add3_u32 v15, v32, v15, s53
	v_and_or_b32 v19, v15, s77, v8
	v_bfe_u32 v8, v21, 16, 1
	v_lshlrev_b64 v[34:35], 12, v[34:35]
	v_add3_u32 v8, v21, v8, s53
	v_bfe_u32 v15, v9, 16, 1
	v_lshl_add_u64 v[34:35], v[6:7], 0, v[34:35]
	v_lshrrev_b32_e32 v8, 16, v8
	v_add3_u32 v9, v9, v15, s53
	global_store_dwordx4 v[34:35], v[16:19], off nt
	v_readlane_b32 s17, v251, 15
	v_readlane_b32 s18, v251, 16
	v_and_or_b32 v16, v9, s77, v8
	v_bfe_u32 v8, v23, 16, 1
	v_add3_u32 v8, v23, v8, s53
	v_bfe_u32 v9, v25, 16, 1
	v_lshrrev_b32_e32 v8, 16, v8
	v_add3_u32 v9, v25, v9, s53
	v_and_or_b32 v17, v9, s77, v8
	v_bfe_u32 v8, v27, 16, 1
	v_add3_u32 v8, v27, v8, s53
	v_bfe_u32 v9, v29, 16, 1
	v_lshrrev_b32_e32 v8, 16, v8
	v_add3_u32 v9, v29, v9, s53
	v_and_or_b32 v18, v9, s77, v8
	v_bfe_u32 v8, v31, 16, 1
	v_add3_u32 v8, v31, v8, s53
	v_bfe_u32 v9, v33, 16, 1
	v_lshrrev_b32_e32 v8, 16, v8
	v_add3_u32 v9, v33, v9, s53
	v_and_or_b32 v19, v9, s77, v8
	v_or_b32_e32 v8, s2, v14
	v_ashrrev_i32_e32 v9, 31, v8
	v_lshlrev_b64 v[8:9], 12, v[8:9]
	v_lshl_add_u64 v[6:7], v[6:7], 0, v[8:9]
	global_store_dwordx4 v[6:7], v[16:19], off nt
	s_waitcnt lgkmcnt(0)
	v_readlane_b32 s19, v251, 17
	v_readlane_b32 s20, v251, 18
	v_readlane_b32 s21, v251, 19
	v_readlane_b32 s24, v251, 22
	v_readlane_b32 s25, v251, 23
	v_readlane_b32 s26, v251, 24
	v_readlane_b32 s27, v251, 25
	v_readlane_b32 s28, v251, 26
	v_readlane_b32 s29, v251, 27
	v_readlane_b32 s30, v251, 28
	v_readlane_b32 s31, v251, 29
	s_branch .LBB0_847

.LBB0_1167:
	s_cmpk_gt_i32 s4, 0x3fff
	s_mov_b64 s[2:3], -1
	s_cbranch_scc0 .LBB0_1188
	s_cmpk_gt_u32 s4, 0x5fff
	s_cbranch_scc0 .LBB0_1185
	s_cmp_gt_u32 s4, 0x167ff
	s_cbranch_scc0 .LBB0_1175
	s_cmp_gt_u32 s4, 0x177ff
	s_cbranch_scc0 .LBB0_1172
	s_add_i32 s0, s4, 0xfffe8800
	v_readlane_b32 s16, v251, 6
	s_lshr_b32 s86, s0, 12
	v_readlane_b32 s20, v251, 10
	v_readlane_b32 s21, v251, 11
	s_bfe_u32 s2, s0, 0x1000b
	s_lshl_b64 s[0:1], s[86:87], 25
	v_readlane_b32 s22, v251, 12
	v_readlane_b32 s23, v251, 13
	s_mov_b64 s[8:9], s[20:21]
	s_add_u32 s0, s8, s0
	s_addc_u32 s1, s9, s1
	s_lshl_b32 s3, s2, 13
	s_mov_b64 s[10:11], s[22:23]
	s_add_u32 s9, s0, s3
	s_addc_u32 s10, s1, 0
	s_lshl_b64 s[0:1], s[86:87], 24
	v_readlane_b32 s14, v251, 50
	v_readlane_b32 s15, v251, 51
	s_add_u32 s3, s14, s0
	s_addc_u32 s5, s15, s1
	s_lshl_b32 s1, s4, 5
	s_lshl_b32 s11, s4, 6
	s_and_b32 s1, s1, 0x60
	s_lshl_b32 s2, s2, 7
	s_and_b32 s0, s4, 63
	s_and_b32 s11, s11, 0xf00
	s_or_b32 s1, s2, s1
	s_and_b32 s8, s4, 0x7c0
	s_or_b32 s2, s1, s11
	s_lshl_b32 s0, s0, 7
	s_add_u32 s0, s9, s0
	v_or_b32_e32 v8, s8, v3
	s_addc_u32 s1, s10, 0
	v_lshlrev_b32_e32 v202, 2, v2
	v_lshl_add_u64 v[6:7], s[0:1], 0, v[202:203]
	v_lshlrev_b32_e32 v202, 14, v8
	v_lshl_add_u64 v[6:7], v[6:7], 0, v[202:203]
	s_mov_b32 s0, 0x8000
	v_add_co_u32_e32 v8, vcc, s0, v6
	s_mov_b32 s0, 0x10000
	s_nop 0
	v_addc_co_u32_e32 v9, vcc, 0, v7, vcc
	global_load_dword v15, v[6:7], off nt
	global_load_dword v16, v[8:9], off nt
	v_add_co_u32_e32 v8, vcc, s0, v6
	s_mov_b32 s0, 0x18000
	s_nop 0
	v_addc_co_u32_e32 v9, vcc, 0, v7, vcc
	global_load_dword v17, v[8:9], off nt
	v_add_co_u32_e32 v8, vcc, s0, v6
	s_mov_b32 s0, 0x20000
	s_nop 0
	v_addc_co_u32_e32 v9, vcc, 0, v7, vcc
	global_load_dword v18, v[8:9], off nt
	v_add_co_u32_e32 v8, vcc, s0, v6
	s_mov_b32 s0, 0x28000
	s_nop 0
	v_addc_co_u32_e32 v9, vcc, 0, v7, vcc
	global_load_dword v19, v[8:9], off nt
	v_add_co_u32_e32 v8, vcc, s0, v6
	s_mov_b32 s0, 0x30000
	s_nop 0
	v_addc_co_u32_e32 v9, vcc, 0, v7, vcc
	global_load_dword v20, v[8:9], off nt
	v_add_co_u32_e32 v8, vcc, s0, v6
	s_mov_b32 s0, 0x38000
	s_nop 0
	v_addc_co_u32_e32 v9, vcc, 0, v7, vcc
	global_load_dword v21, v[8:9], off nt
	v_add_co_u32_e32 v8, vcc, s0, v6
	s_mov_b32 s0, 0x40000
	s_nop 0
	v_addc_co_u32_e32 v9, vcc, 0, v7, vcc
	global_load_dword v22, v[8:9], off nt
	v_add_co_u32_e32 v8, vcc, s0, v6
	s_mov_b32 s0, 0x48000
	s_nop 0
	v_addc_co_u32_e32 v9, vcc, 0, v7, vcc
	global_load_dword v23, v[8:9], off nt
	v_add_co_u32_e32 v8, vcc, s0, v6
	s_mov_b32 s0, 0x50000
	s_nop 0
	v_addc_co_u32_e32 v9, vcc, 0, v7, vcc
	global_load_dword v24, v[8:9], off nt
	v_add_co_u32_e32 v8, vcc, s0, v6
	s_mov_b32 s0, 0x58000
	s_nop 0
	v_addc_co_u32_e32 v9, vcc, 0, v7, vcc
	global_load_dword v25, v[8:9], off nt
	v_add_co_u32_e32 v8, vcc, s0, v6
	s_mov_b32 s0, 0x60000
	s_nop 0
	v_addc_co_u32_e32 v9, vcc, 0, v7, vcc
	global_load_dword v26, v[8:9], off nt
	v_add_co_u32_e32 v8, vcc, s0, v6
	s_mov_b32 s0, 0x68000
	s_nop 0
	v_addc_co_u32_e32 v9, vcc, 0, v7, vcc
	global_load_dword v27, v[8:9], off nt
	v_add_co_u32_e32 v8, vcc, s0, v6
	s_mov_b32 s0, 0x70000
	s_nop 0
	v_addc_co_u32_e32 v9, vcc, 0, v7, vcc
	global_load_dword v28, v[8:9], off nt
	v_add_co_u32_e32 v8, vcc, s0, v6
	s_mov_b32 s0, 0x78000
	s_nop 0
	v_addc_co_u32_e32 v9, vcc, 0, v7, vcc
	global_load_dword v29, v[8:9], off nt
	v_add_co_u32_e32 v8, vcc, s0, v6
	s_mov_b32 s0, 0x80000
	s_nop 0
	v_addc_co_u32_e32 v9, vcc, 0, v7, vcc
	global_load_dword v30, v[8:9], off nt
	v_add_co_u32_e32 v8, vcc, s0, v6
	s_mov_b32 s0, 0x88000
	s_nop 0
	v_addc_co_u32_e32 v9, vcc, 0, v7, vcc
	global_load_dword v31, v[8:9], off nt
	v_add_co_u32_e32 v8, vcc, s0, v6
	s_mov_b32 s0, 0x90000
	s_nop 0
	v_addc_co_u32_e32 v9, vcc, 0, v7, vcc
	global_load_dword v32, v[8:9], off nt
	v_add_co_u32_e32 v8, vcc, s0, v6
	s_mov_b32 s0, 0x98000
	s_nop 0
	v_addc_co_u32_e32 v9, vcc, 0, v7, vcc
	global_load_dword v33, v[8:9], off nt
	v_add_co_u32_e32 v8, vcc, s0, v6
	s_mov_b32 s0, 0xa0000
	s_nop 0
	v_addc_co_u32_e32 v9, vcc, 0, v7, vcc
	global_load_dword v34, v[8:9], off nt
	v_add_co_u32_e32 v8, vcc, s0, v6
	s_mov_b32 s0, 0xa8000
	s_nop 0
	v_addc_co_u32_e32 v9, vcc, 0, v7, vcc
	global_load_dword v35, v[8:9], off nt
	v_add_co_u32_e32 v8, vcc, s0, v6
	s_mov_b32 s0, 0xb0000
	s_nop 0
	v_addc_co_u32_e32 v9, vcc, 0, v7, vcc
	global_load_dword v36, v[8:9], off nt
	v_add_co_u32_e32 v8, vcc, s0, v6
	s_mov_b32 s0, 0xb8000
	s_nop 0
	v_addc_co_u32_e32 v9, vcc, 0, v7, vcc
	global_load_dword v37, v[8:9], off nt
	v_add_co_u32_e32 v8, vcc, s0, v6
	s_mov_b32 s0, 0xc0000
	s_nop 0
	v_addc_co_u32_e32 v9, vcc, 0, v7, vcc
	global_load_dword v38, v[8:9], off nt
	v_add_co_u32_e32 v8, vcc, s0, v6
	s_mov_b32 s0, 0xc8000
	s_nop 0
	v_addc_co_u32_e32 v9, vcc, 0, v7, vcc
	global_load_dword v39, v[8:9], off nt
	v_add_co_u32_e32 v8, vcc, s0, v6
	s_mov_b32 s0, 0xd0000
	s_nop 0
	v_addc_co_u32_e32 v9, vcc, 0, v7, vcc
	global_load_dword v40, v[8:9], off nt
	v_add_co_u32_e32 v8, vcc, s0, v6
	s_mov_b32 s0, 0xd8000
	s_nop 0
	v_addc_co_u32_e32 v9, vcc, 0, v7, vcc
	global_load_dword v41, v[8:9], off nt
	v_add_co_u32_e32 v8, vcc, s0, v6
	s_mov_b32 s0, 0xe0000
	s_nop 0
	v_addc_co_u32_e32 v9, vcc, 0, v7, vcc
	global_load_dword v42, v[8:9], off nt
	v_add_co_u32_e32 v8, vcc, s0, v6
	s_mov_b32 s0, 0xe8000
	s_nop 0
	v_addc_co_u32_e32 v9, vcc, 0, v7, vcc
	global_load_dword v43, v[8:9], off nt
	v_add_co_u32_e32 v8, vcc, s0, v6
	s_mov_b32 s0, 0xf0000
	s_nop 0
	v_addc_co_u32_e32 v9, vcc, 0, v7, vcc
	global_load_dword v44, v[8:9], off nt
	v_add_co_u32_e32 v8, vcc, s0, v6
	s_mov_b32 s0, 0xf8000
	s_nop 0
	v_addc_co_u32_e32 v9, vcc, 0, v7, vcc
	v_add_co_u32_e32 v6, vcc, s0, v6
	global_load_dword v8, v[8:9], off nt
	s_nop 0
	v_addc_co_u32_e32 v7, vcc, 0, v7, vcc
	global_load_dword v6, v[6:7], off nt
	v_add_u32_e32 v7, 0x400, v5
	s_waitcnt vmcnt(0)
	ds_write2_b32 v5, v15, v16 offset1:66
	ds_write2_b32 v5, v17, v18 offset0:132 offset1:198
	ds_write2_b32 v7, v19, v20 offset0:8 offset1:74
	ds_write2_b32 v7, v21, v22 offset0:140 offset1:206
	v_add_u32_e32 v7, 0x800, v5
	ds_write2_b32 v7, v23, v24 offset0:16 offset1:82
	ds_write2_b32 v7, v25, v26 offset0:148 offset1:214
	v_add_u32_e32 v7, 0xc00, v5
	ds_write2_b32 v7, v27, v28 offset0:24 offset1:90
	ds_write2_b32 v7, v29, v30 offset0:156 offset1:222
	v_add_u32_e32 v7, 0x1000, v5
	ds_write2_b32 v7, v31, v32 offset0:32 offset1:98
	ds_write2_b32 v7, v33, v34 offset0:164 offset1:230
	v_add_u32_e32 v7, 0x1400, v5
	ds_write2_b32 v7, v35, v36 offset0:40 offset1:106
	ds_write2_b32 v7, v37, v38 offset0:172 offset1:238
	v_add_u32_e32 v7, 0x1800, v5
	ds_write2_b32 v7, v39, v40 offset0:48 offset1:114
	ds_write2_b32 v7, v41, v42 offset0:180 offset1:246
	v_add_u32_e32 v7, 0x1c00, v5
	ds_write2_b32 v7, v43, v44 offset0:56 offset1:122
	ds_write2_b32 v7, v8, v6 offset0:188 offset1:254
	s_waitcnt lgkmcnt(0)
	ds_read2_b32 v[8:9], v11 offset0:33 offset1:41
	ds_read2_b32 v[20:21], v11 offset1:8
	ds_read2_b32 v[22:23], v11 offset0:66 offset1:74
	ds_read2_b32 v[24:25], v11 offset0:99 offset1:107
	ds_read2_b32 v[26:27], v11 offset0:132 offset1:140
	ds_read2_b32 v[28:29], v11 offset0:165 offset1:173
	ds_read2_b32 v[30:31], v11 offset0:198 offset1:206
	ds_read2_b32 v[32:33], v11 offset0:231 offset1:239
	s_waitcnt lgkmcnt(7)
	v_bfe_u32 v16, v8, 16, 1
	s_waitcnt lgkmcnt(6)
	v_bfe_u32 v15, v20, 16, 1
	v_add3_u32 v15, v20, v15, s53
	v_lshrrev_b32_e32 v15, 16, v15
	v_add3_u32 v8, v8, v16, s53
	v_and_or_b32 v16, v8, s77, v15
	s_waitcnt lgkmcnt(5)
	v_bfe_u32 v8, v22, 16, 1
	v_add3_u32 v8, v22, v8, s53
	s_waitcnt lgkmcnt(4)
	v_bfe_u32 v15, v24, 16, 1
	v_lshrrev_b32_e32 v8, 16, v8
	v_add3_u32 v15, v24, v15, s53
	v_and_or_b32 v17, v15, s77, v8
	s_waitcnt lgkmcnt(3)
	v_bfe_u32 v8, v26, 16, 1
	v_add3_u32 v8, v26, v8, s53
	s_waitcnt lgkmcnt(2)
	v_bfe_u32 v15, v28, 16, 1
	v_lshrrev_b32_e32 v8, 16, v8
	v_add3_u32 v15, v28, v15, s53
	v_and_or_b32 v18, v15, s77, v8
	s_waitcnt lgkmcnt(1)
	v_bfe_u32 v8, v30, 16, 1
	s_lshl_b32 s0, s8, 1
	v_add3_u32 v8, v30, v8, s53
	s_waitcnt lgkmcnt(0)
	v_bfe_u32 v15, v32, 16, 1
	s_add_u32 s0, s3, s0
	v_lshrrev_b32_e32 v8, 16, v8
	v_add3_u32 v15, v32, v15, s53
	s_addc_u32 s1, s5, 0
	v_lshlrev_b32_e32 v202, 1, v4
	v_and_or_b32 v19, v15, s77, v8
	v_or_b32_e32 v8, s2, v10
	v_lshl_add_u64 v[6:7], s[0:1], 0, v[202:203]
	v_lshlrev_b32_e32 v202, 12, v8
	v_bfe_u32 v8, v21, 16, 1
	v_add3_u32 v8, v21, v8, s53
	v_bfe_u32 v15, v9, 16, 1
	v_lshl_add_u64 v[34:35], v[6:7], 0, v[202:203]
	v_lshrrev_b32_e32 v8, 16, v8
	v_add3_u32 v9, v9, v15, s53
	global_store_dwordx4 v[34:35], v[16:19], off nt
	v_readlane_b32 s17, v251, 7
	v_readlane_b32 s18, v251, 8
	v_and_or_b32 v16, v9, s77, v8
	v_bfe_u32 v8, v23, 16, 1
	v_add3_u32 v8, v23, v8, s53
	v_bfe_u32 v9, v25, 16, 1
	v_lshrrev_b32_e32 v8, 16, v8
	v_add3_u32 v9, v25, v9, s53
	v_and_or_b32 v17, v9, s77, v8
	v_bfe_u32 v8, v27, 16, 1
	v_add3_u32 v8, v27, v8, s53
	v_bfe_u32 v9, v29, 16, 1
	v_lshrrev_b32_e32 v8, 16, v8
	v_add3_u32 v9, v29, v9, s53
	v_and_or_b32 v18, v9, s77, v8
	v_bfe_u32 v8, v31, 16, 1
	v_add3_u32 v8, v31, v8, s53
	v_bfe_u32 v9, v33, 16, 1
	v_lshrrev_b32_e32 v8, 16, v8
	v_add3_u32 v9, v33, v9, s53
	v_and_or_b32 v19, v9, s77, v8
	v_or_b32_e32 v8, s2, v12
	v_lshlrev_b32_e32 v202, 12, v8
	v_lshl_add_u64 v[8:9], v[6:7], 0, v[202:203]
	global_store_dwordx4 v[8:9], v[16:19], off nt
	ds_read2_b32 v[8:9], v11 offset0:49 offset1:57
	ds_read2_b32 v[20:21], v11 offset0:16 offset1:24
	ds_read2_b32 v[22:23], v11 offset0:82 offset1:90
	ds_read2_b32 v[24:25], v11 offset0:115 offset1:123
	ds_read2_b32 v[26:27], v11 offset0:148 offset1:156
	ds_read2_b32 v[28:29], v11 offset0:181 offset1:189
	ds_read2_b32 v[30:31], v11 offset0:214 offset1:222
	ds_read2_b32 v[32:33], v11 offset0:247 offset1:255
	s_waitcnt lgkmcnt(7)
	v_bfe_u32 v16, v8, 16, 1
	s_waitcnt lgkmcnt(6)
	v_bfe_u32 v15, v20, 16, 1
	v_add3_u32 v15, v20, v15, s53
	v_lshrrev_b32_e32 v15, 16, v15
	v_add3_u32 v8, v8, v16, s53
	v_and_or_b32 v16, v8, s77, v15
	s_waitcnt lgkmcnt(5)
	v_bfe_u32 v8, v22, 16, 1
	v_add3_u32 v8, v22, v8, s53
	s_waitcnt lgkmcnt(4)
	v_bfe_u32 v15, v24, 16, 1
	v_lshrrev_b32_e32 v8, 16, v8
	v_add3_u32 v15, v24, v15, s53
	v_and_or_b32 v17, v15, s77, v8
	s_waitcnt lgkmcnt(3)
	v_bfe_u32 v8, v26, 16, 1
	v_add3_u32 v8, v26, v8, s53
	s_waitcnt lgkmcnt(2)
	v_bfe_u32 v15, v28, 16, 1
	v_lshrrev_b32_e32 v8, 16, v8
	v_add3_u32 v15, v28, v15, s53
	v_and_or_b32 v18, v15, s77, v8
	s_waitcnt lgkmcnt(1)
	v_bfe_u32 v8, v30, 16, 1
	v_add3_u32 v8, v30, v8, s53
	s_waitcnt lgkmcnt(0)
	v_bfe_u32 v15, v32, 16, 1
	v_lshrrev_b32_e32 v8, 16, v8
	v_add3_u32 v15, v32, v15, s53
	v_and_or_b32 v19, v15, s77, v8
	v_or_b32_e32 v8, s2, v13
	v_lshlrev_b32_e32 v202, 12, v8
	v_bfe_u32 v8, v21, 16, 1
	v_add3_u32 v8, v21, v8, s53
	v_bfe_u32 v15, v9, 16, 1
	v_lshl_add_u64 v[34:35], v[6:7], 0, v[202:203]
	v_lshrrev_b32_e32 v8, 16, v8
	v_add3_u32 v9, v9, v15, s53
	global_store_dwordx4 v[34:35], v[16:19], off nt
	v_readlane_b32 s19, v251, 9
	s_nop 0
	v_and_or_b32 v16, v9, s77, v8
	v_bfe_u32 v8, v23, 16, 1
	v_add3_u32 v8, v23, v8, s53
	v_bfe_u32 v9, v25, 16, 1
	v_lshrrev_b32_e32 v8, 16, v8
	v_add3_u32 v9, v25, v9, s53
	v_and_or_b32 v17, v9, s77, v8
	v_bfe_u32 v8, v27, 16, 1
	v_add3_u32 v8, v27, v8, s53
	v_bfe_u32 v9, v29, 16, 1
	v_lshrrev_b32_e32 v8, 16, v8
	v_add3_u32 v9, v29, v9, s53
	v_and_or_b32 v18, v9, s77, v8
	v_bfe_u32 v8, v31, 16, 1
	v_add3_u32 v8, v31, v8, s53
	v_bfe_u32 v9, v33, 16, 1
	v_lshrrev_b32_e32 v8, 16, v8
	v_add3_u32 v9, v33, v9, s53
	v_and_or_b32 v19, v9, s77, v8
	v_or_b32_e32 v8, s2, v14
	v_lshlrev_b32_e32 v202, 12, v8
	v_lshl_add_u64 v[6:7], v[6:7], 0, v[202:203]
	global_store_dwordx4 v[6:7], v[16:19], off nt
	s_waitcnt lgkmcnt(0)
	s_mov_b64 s[2:3], 0
.LBB0_1172:
	s_andn2_b64 vcc, exec, s[2:3]
	s_cbranch_vccnz .LBB0_1174
	v_readlane_b32 s16, v251, 30
	s_and_b32 s0, s4, 0x1f800
	v_readlane_b32 s17, v251, 31
	s_add_i32 s86, s0, 0xfffe9800
	v_readlane_b32 s18, v251, 32
	v_readlane_b32 s19, v251, 33
	s_mov_b64 s[8:9], s[16:17]
	s_lshl_b64 s[0:1], s[86:87], 13
	s_mov_b64 s[10:11], s[18:19]
	s_add_u32 s9, s10, s0
	s_addc_u32 s10, s11, s1
	s_lshl_b64 s[0:1], s[86:87], 12
	v_readlane_b32 s2, v251, 52
	s_add_u32 s3, s2, s0
	v_readlane_b32 s0, v251, 53
	s_addc_u32 s5, s0, s1
	s_lshl_b32 s0, s4, 5
	s_and_b32 s2, s0, 0x7e0
	s_and_b32 s8, s4, 0x7c0
	s_lshl_b32 s0, s2, 2
	s_add_u32 s0, s9, s0
	v_or_b32_e32 v8, s8, v3
	s_addc_u32 s1, s10, 0
	v_lshlrev_b32_e32 v202, 2, v2
	v_lshl_add_u64 v[6:7], s[0:1], 0, v[202:203]
	v_lshlrev_b32_e32 v202, 13, v8
	v_lshl_add_u64 v[6:7], v[6:7], 0, v[202:203]
	v_add_co_u32_e32 v8, vcc, s88, v6
	s_mov_b32 s0, 0x8000
	s_nop 0
	v_addc_co_u32_e32 v9, vcc, 0, v7, vcc
	global_load_dword v15, v[6:7], off nt
	global_load_dword v16, v[8:9], off nt
	v_add_co_u32_e32 v8, vcc, s0, v6
	s_mov_b32 s0, 0xc000
	s_nop 0
	v_addc_co_u32_e32 v9, vcc, 0, v7, vcc
	global_load_dword v17, v[8:9], off nt
	v_add_co_u32_e32 v8, vcc, s0, v6
	s_mov_b32 s0, 0x10000
	s_nop 0
	v_addc_co_u32_e32 v9, vcc, 0, v7, vcc
	global_load_dword v18, v[8:9], off nt
	v_add_co_u32_e32 v8, vcc, s0, v6
	s_mov_b32 s0, 0x14000
	s_nop 0
	v_addc_co_u32_e32 v9, vcc, 0, v7, vcc
	global_load_dword v19, v[8:9], off nt
	v_add_co_u32_e32 v8, vcc, s0, v6
	s_mov_b32 s0, 0x18000
	s_nop 0
	v_addc_co_u32_e32 v9, vcc, 0, v7, vcc
	global_load_dword v20, v[8:9], off nt
	v_add_co_u32_e32 v8, vcc, s0, v6
	s_mov_b32 s0, 0x1c000
	s_nop 0
	v_addc_co_u32_e32 v9, vcc, 0, v7, vcc
	global_load_dword v21, v[8:9], off nt
	v_add_co_u32_e32 v8, vcc, s0, v6
	s_mov_b32 s0, 0x20000
	s_nop 0
	v_addc_co_u32_e32 v9, vcc, 0, v7, vcc
	global_load_dword v22, v[8:9], off nt
	v_add_co_u32_e32 v8, vcc, s0, v6
	s_mov_b32 s0, 0x24000
	s_nop 0
	v_addc_co_u32_e32 v9, vcc, 0, v7, vcc
	global_load_dword v23, v[8:9], off nt
	v_add_co_u32_e32 v8, vcc, s0, v6
	s_mov_b32 s0, 0x28000
	s_nop 0
	v_addc_co_u32_e32 v9, vcc, 0, v7, vcc
	global_load_dword v24, v[8:9], off nt
	v_add_co_u32_e32 v8, vcc, s0, v6
	s_mov_b32 s0, 0x2c000
	s_nop 0
	v_addc_co_u32_e32 v9, vcc, 0, v7, vcc
	global_load_dword v25, v[8:9], off nt
	v_add_co_u32_e32 v8, vcc, s0, v6
	s_mov_b32 s0, 0x30000
	s_nop 0
	v_addc_co_u32_e32 v9, vcc, 0, v7, vcc
	global_load_dword v26, v[8:9], off nt
	v_add_co_u32_e32 v8, vcc, s0, v6
	s_mov_b32 s0, 0x34000
	s_nop 0
	v_addc_co_u32_e32 v9, vcc, 0, v7, vcc
	global_load_dword v27, v[8:9], off nt
	v_add_co_u32_e32 v8, vcc, s0, v6
	s_mov_b32 s0, 0x38000
	s_nop 0
	v_addc_co_u32_e32 v9, vcc, 0, v7, vcc
	global_load_dword v28, v[8:9], off nt
	v_add_co_u32_e32 v8, vcc, s0, v6
	s_mov_b32 s0, 0x3c000
	s_nop 0
	v_addc_co_u32_e32 v9, vcc, 0, v7, vcc
	global_load_dword v29, v[8:9], off nt
	v_add_co_u32_e32 v8, vcc, s0, v6
	s_mov_b32 s0, 0x40000
	s_nop 0
	v_addc_co_u32_e32 v9, vcc, 0, v7, vcc
	global_load_dword v30, v[8:9], off nt
	v_add_co_u32_e32 v8, vcc, s0, v6
	s_mov_b32 s0, 0x44000
	s_nop 0
	v_addc_co_u32_e32 v9, vcc, 0, v7, vcc
	global_load_dword v31, v[8:9], off nt
	v_add_co_u32_e32 v8, vcc, s0, v6
	s_mov_b32 s0, 0x48000
	s_nop 0
	v_addc_co_u32_e32 v9, vcc, 0, v7, vcc
	global_load_dword v32, v[8:9], off nt
	v_add_co_u32_e32 v8, vcc, s0, v6
	s_mov_b32 s0, 0x4c000
	s_nop 0
	v_addc_co_u32_e32 v9, vcc, 0, v7, vcc
	global_load_dword v33, v[8:9], off nt
	v_add_co_u32_e32 v8, vcc, s0, v6
	s_mov_b32 s0, 0x50000
	s_nop 0
	v_addc_co_u32_e32 v9, vcc, 0, v7, vcc
	global_load_dword v34, v[8:9], off nt
	v_add_co_u32_e32 v8, vcc, s0, v6
	s_mov_b32 s0, 0x54000
	s_nop 0
	v_addc_co_u32_e32 v9, vcc, 0, v7, vcc
	global_load_dword v35, v[8:9], off nt
	v_add_co_u32_e32 v8, vcc, s0, v6
	s_mov_b32 s0, 0x58000
	s_nop 0
	v_addc_co_u32_e32 v9, vcc, 0, v7, vcc
	global_load_dword v36, v[8:9], off nt
	v_add_co_u32_e32 v8, vcc, s0, v6
	s_mov_b32 s0, 0x5c000
	s_nop 0
	v_addc_co_u32_e32 v9, vcc, 0, v7, vcc
	global_load_dword v37, v[8:9], off nt
	v_add_co_u32_e32 v8, vcc, s0, v6
	s_mov_b32 s0, 0x60000
	s_nop 0
	v_addc_co_u32_e32 v9, vcc, 0, v7, vcc
	global_load_dword v38, v[8:9], off nt
	v_add_co_u32_e32 v8, vcc, s0, v6
	s_mov_b32 s0, 0x64000
	s_nop 0
	v_addc_co_u32_e32 v9, vcc, 0, v7, vcc
	global_load_dword v39, v[8:9], off nt
	v_add_co_u32_e32 v8, vcc, s0, v6
	s_mov_b32 s0, 0x68000
	s_nop 0
	v_addc_co_u32_e32 v9, vcc, 0, v7, vcc
	global_load_dword v40, v[8:9], off nt
	v_add_co_u32_e32 v8, vcc, s0, v6
	s_mov_b32 s0, 0x6c000
	s_nop 0
	v_addc_co_u32_e32 v9, vcc, 0, v7, vcc
	global_load_dword v41, v[8:9], off nt
	v_add_co_u32_e32 v8, vcc, s0, v6
	s_mov_b32 s0, 0x70000
	s_nop 0
	v_addc_co_u32_e32 v9, vcc, 0, v7, vcc
	global_load_dword v42, v[8:9], off nt
	v_add_co_u32_e32 v8, vcc, s0, v6
	s_mov_b32 s0, 0x74000
	s_nop 0
	v_addc_co_u32_e32 v9, vcc, 0, v7, vcc
	global_load_dword v43, v[8:9], off nt
	v_add_co_u32_e32 v8, vcc, s0, v6
	s_mov_b32 s0, 0x78000
	s_nop 0
	v_addc_co_u32_e32 v9, vcc, 0, v7, vcc
	global_load_dword v44, v[8:9], off nt
	v_add_co_u32_e32 v8, vcc, s0, v6
	s_mov_b32 s0, 0x7c000
	s_nop 0
	v_addc_co_u32_e32 v9, vcc, 0, v7, vcc
	v_add_co_u32_e32 v6, vcc, s0, v6
	global_load_dword v8, v[8:9], off nt
	s_nop 0
	v_addc_co_u32_e32 v7, vcc, 0, v7, vcc
	global_load_dword v6, v[6:7], off nt
	v_add_u32_e32 v7, 0x400, v5
	s_waitcnt vmcnt(0)
	ds_write2_b32 v5, v15, v16 offset1:66
	ds_write2_b32 v5, v17, v18 offset0:132 offset1:198
	ds_write2_b32 v7, v19, v20 offset0:8 offset1:74
	ds_write2_b32 v7, v21, v22 offset0:140 offset1:206
	v_add_u32_e32 v7, 0x800, v5
	ds_write2_b32 v7, v23, v24 offset0:16 offset1:82
	ds_write2_b32 v7, v25, v26 offset0:148 offset1:214
	v_add_u32_e32 v7, 0xc00, v5
	ds_write2_b32 v7, v27, v28 offset0:24 offset1:90
	ds_write2_b32 v7, v29, v30 offset0:156 offset1:222
	v_add_u32_e32 v7, 0x1000, v5
	ds_write2_b32 v7, v31, v32 offset0:32 offset1:98
	ds_write2_b32 v7, v33, v34 offset0:164 offset1:230
	v_add_u32_e32 v7, 0x1400, v5
	ds_write2_b32 v7, v35, v36 offset0:40 offset1:106
	ds_write2_b32 v7, v37, v38 offset0:172 offset1:238
	v_add_u32_e32 v7, 0x1800, v5
	ds_write2_b32 v7, v39, v40 offset0:48 offset1:114
	ds_write2_b32 v7, v41, v42 offset0:180 offset1:246
	v_add_u32_e32 v7, 0x1c00, v5
	ds_write2_b32 v7, v43, v44 offset0:56 offset1:122
	ds_write2_b32 v7, v8, v6 offset0:188 offset1:254
	s_waitcnt lgkmcnt(0)
	ds_read2_b32 v[8:9], v11 offset0:33 offset1:41
	ds_read2_b32 v[20:21], v11 offset1:8
	ds_read2_b32 v[22:23], v11 offset0:66 offset1:74
	ds_read2_b32 v[24:25], v11 offset0:99 offset1:107
	ds_read2_b32 v[26:27], v11 offset0:132 offset1:140
	ds_read2_b32 v[28:29], v11 offset0:165 offset1:173
	ds_read2_b32 v[30:31], v11 offset0:198 offset1:206
	ds_read2_b32 v[32:33], v11 offset0:231 offset1:239
	s_waitcnt lgkmcnt(7)
	v_bfe_u32 v16, v8, 16, 1
	s_waitcnt lgkmcnt(6)
	v_bfe_u32 v15, v20, 16, 1
	v_add3_u32 v15, v20, v15, s53
	v_lshrrev_b32_e32 v15, 16, v15
	v_add3_u32 v8, v8, v16, s53
	v_and_or_b32 v16, v8, s77, v15
	s_waitcnt lgkmcnt(5)
	v_bfe_u32 v8, v22, 16, 1
	v_add3_u32 v8, v22, v8, s53
	s_waitcnt lgkmcnt(4)
	v_bfe_u32 v15, v24, 16, 1
	v_lshrrev_b32_e32 v8, 16, v8
	v_add3_u32 v15, v24, v15, s53
	v_and_or_b32 v17, v15, s77, v8
	s_waitcnt lgkmcnt(3)
	v_bfe_u32 v8, v26, 16, 1
	v_add3_u32 v8, v26, v8, s53
	s_waitcnt lgkmcnt(2)
	v_bfe_u32 v15, v28, 16, 1
	v_lshrrev_b32_e32 v8, 16, v8
	v_add3_u32 v15, v28, v15, s53
	v_and_or_b32 v18, v15, s77, v8
	s_waitcnt lgkmcnt(1)
	v_bfe_u32 v8, v30, 16, 1
	s_lshl_b32 s0, s8, 1
	v_add3_u32 v8, v30, v8, s53
	s_waitcnt lgkmcnt(0)
	v_bfe_u32 v15, v32, 16, 1
	s_add_u32 s0, s3, s0
	v_lshrrev_b32_e32 v8, 16, v8
	v_add3_u32 v15, v32, v15, s53
	s_addc_u32 s1, s5, 0
	v_lshlrev_b32_e32 v202, 1, v4
	v_and_or_b32 v19, v15, s77, v8
	v_or_b32_e32 v8, s2, v10
	v_lshl_add_u64 v[6:7], s[0:1], 0, v[202:203]
	v_lshlrev_b32_e32 v202, 12, v8
	v_bfe_u32 v8, v21, 16, 1
	v_add3_u32 v8, v21, v8, s53
	v_bfe_u32 v15, v9, 16, 1
	v_lshl_add_u64 v[34:35], v[6:7], 0, v[202:203]
	v_lshrrev_b32_e32 v8, 16, v8
	v_add3_u32 v9, v9, v15, s53
	global_store_dwordx4 v[34:35], v[16:19], off nt
	v_readlane_b32 s20, v251, 34
	v_readlane_b32 s21, v251, 35
	v_and_or_b32 v16, v9, s77, v8
	v_bfe_u32 v8, v23, 16, 1
	v_add3_u32 v8, v23, v8, s53
	v_bfe_u32 v9, v25, 16, 1
	v_lshrrev_b32_e32 v8, 16, v8
	v_add3_u32 v9, v25, v9, s53
	v_and_or_b32 v17, v9, s77, v8
	v_bfe_u32 v8, v27, 16, 1
	v_add3_u32 v8, v27, v8, s53
	v_bfe_u32 v9, v29, 16, 1
	v_lshrrev_b32_e32 v8, 16, v8
	v_add3_u32 v9, v29, v9, s53
	v_and_or_b32 v18, v9, s77, v8
	v_bfe_u32 v8, v31, 16, 1
	v_add3_u32 v8, v31, v8, s53
	v_bfe_u32 v9, v33, 16, 1
	v_lshrrev_b32_e32 v8, 16, v8
	v_add3_u32 v9, v33, v9, s53
	v_and_or_b32 v19, v9, s77, v8
	v_or_b32_e32 v8, s2, v12
	v_lshlrev_b32_e32 v202, 12, v8
	v_lshl_add_u64 v[8:9], v[6:7], 0, v[202:203]
	global_store_dwordx4 v[8:9], v[16:19], off nt
	ds_read2_b32 v[8:9], v11 offset0:49 offset1:57
	ds_read2_b32 v[20:21], v11 offset0:16 offset1:24
	ds_read2_b32 v[22:23], v11 offset0:82 offset1:90
	ds_read2_b32 v[24:25], v11 offset0:115 offset1:123
	ds_read2_b32 v[26:27], v11 offset0:148 offset1:156
	ds_read2_b32 v[28:29], v11 offset0:181 offset1:189
	ds_read2_b32 v[30:31], v11 offset0:214 offset1:222
	ds_read2_b32 v[32:33], v11 offset0:247 offset1:255
	s_waitcnt lgkmcnt(7)
	v_bfe_u32 v16, v8, 16, 1
	s_waitcnt lgkmcnt(6)
	v_bfe_u32 v15, v20, 16, 1
	v_add3_u32 v15, v20, v15, s53
	v_lshrrev_b32_e32 v15, 16, v15
	v_add3_u32 v8, v8, v16, s53
	v_and_or_b32 v16, v8, s77, v15
	s_waitcnt lgkmcnt(5)
	v_bfe_u32 v8, v22, 16, 1
	v_add3_u32 v8, v22, v8, s53
	s_waitcnt lgkmcnt(4)
	v_bfe_u32 v15, v24, 16, 1
	v_lshrrev_b32_e32 v8, 16, v8
	v_add3_u32 v15, v24, v15, s53
	v_and_or_b32 v17, v15, s77, v8
	s_waitcnt lgkmcnt(3)
	v_bfe_u32 v8, v26, 16, 1
	v_add3_u32 v8, v26, v8, s53
	s_waitcnt lgkmcnt(2)
	v_bfe_u32 v15, v28, 16, 1
	v_lshrrev_b32_e32 v8, 16, v8
	v_add3_u32 v15, v28, v15, s53
	v_and_or_b32 v18, v15, s77, v8
	s_waitcnt lgkmcnt(1)
	v_bfe_u32 v8, v30, 16, 1
	v_add3_u32 v8, v30, v8, s53
	s_waitcnt lgkmcnt(0)
	v_bfe_u32 v15, v32, 16, 1
	v_lshrrev_b32_e32 v8, 16, v8
	v_add3_u32 v15, v32, v15, s53
	v_and_or_b32 v19, v15, s77, v8
	v_or_b32_e32 v8, s2, v13
	v_lshlrev_b32_e32 v202, 12, v8
	v_bfe_u32 v8, v21, 16, 1
	v_add3_u32 v8, v21, v8, s53
	v_bfe_u32 v15, v9, 16, 1
	v_lshl_add_u64 v[34:35], v[6:7], 0, v[202:203]
	v_lshrrev_b32_e32 v8, 16, v8
	v_add3_u32 v9, v9, v15, s53
	global_store_dwordx4 v[34:35], v[16:19], off nt
	v_readlane_b32 s22, v251, 36
	v_readlane_b32 s23, v251, 37
	v_and_or_b32 v16, v9, s77, v8
	v_bfe_u32 v8, v23, 16, 1
	v_add3_u32 v8, v23, v8, s53
	v_bfe_u32 v9, v25, 16, 1
	v_lshrrev_b32_e32 v8, 16, v8
	v_add3_u32 v9, v25, v9, s53
	v_and_or_b32 v17, v9, s77, v8
	v_bfe_u32 v8, v27, 16, 1
	v_add3_u32 v8, v27, v8, s53
	v_bfe_u32 v9, v29, 16, 1
	v_lshrrev_b32_e32 v8, 16, v8
	v_add3_u32 v9, v29, v9, s53
	v_and_or_b32 v18, v9, s77, v8
	v_bfe_u32 v8, v31, 16, 1
	v_add3_u32 v8, v31, v8, s53
	v_bfe_u32 v9, v33, 16, 1
	v_lshrrev_b32_e32 v8, 16, v8
	v_add3_u32 v9, v33, v9, s53
	v_and_or_b32 v19, v9, s77, v8
	v_or_b32_e32 v8, s2, v14
	v_lshlrev_b32_e32 v202, 12, v8
	v_lshl_add_u64 v[6:7], v[6:7], 0, v[202:203]
	global_store_dwordx4 v[6:7], v[16:19], off nt
	s_waitcnt lgkmcnt(0)
	v_readlane_b32 s24, v251, 38
	v_readlane_b32 s25, v251, 39
	v_readlane_b32 s26, v251, 40
	v_readlane_b32 s27, v251, 41
	v_readlane_b32 s28, v251, 42
	v_readlane_b32 s29, v251, 43
	v_readlane_b32 s30, v251, 44
	v_readlane_b32 s31, v251, 45

.LBB0_1175:
	s_andn2_b64 vcc, exec, s[2:3]
	s_cbranch_vccnz .LBB0_1184
	s_add_i32 s1, s4, 0xffffa000
	s_mul_hi_u32 s0, s1, 0x3e0f83e1
	s_lshr_b32 s0, s0, 12
	s_mul_i32 s2, s0, 0x4200
	s_sub_i32 s1, s1, s2
	s_mul_i32 s2, s1, 0xba2f
	s_lshr_b32 s2, s2, 28
	s_mulk_i32 s2, 0x1600
	s_sub_i32 s5, s1, s2
	s_cmpk_gt_u32 s1, 0x15ff
	s_mul_hi_u32 s8, s0, 0x2c00000
	s_mul_i32 s9, s0, 0x2c00000
	s_mov_b64 s[2:3], -1
	s_cbranch_scc0 .LBB0_1182
	s_addk_i32 s1, 0xea00
	s_cmpk_gt_u32 s1, 0x15ff
	s_cbranch_scc0 .LBB0_1179
	v_readlane_b32 s16, v251, 14
	v_readlane_b32 s20, v251, 18
	v_readlane_b32 s21, v251, 19
	s_add_u32 s1, s20, s9
	s_addc_u32 s14, s21, s8
	s_mul_hi_u32 s2, s0, 0x1600000
	s_mul_i32 s0, s0, 0x1600000
	v_readlane_b32 s3, v251, 54
	s_add_u32 s3, s3, s0
	v_readlane_b32 s0, v251, 55
	s_addc_u32 s10, s0, s2
	s_lshl_b32 s0, s5, 5
	s_and_b32 s2, s0, 0x7e0
	s_and_b32 s11, s5, 0x1fc0
	s_lshl_b32 s0, s2, 2
	s_add_u32 s0, s1, s0
	v_or_b32_e32 v8, s11, v3
	s_addc_u32 s1, s14, 0
	v_lshlrev_b32_e32 v202, 2, v2
	v_lshl_add_u64 v[6:7], s[0:1], 0, v[202:203]
	v_lshlrev_b32_e32 v202, 13, v8
	v_lshl_add_u64 v[6:7], v[6:7], 0, v[202:203]
	v_add_co_u32_e32 v8, vcc, s88, v6
	s_mov_b32 s0, 0x8000
	s_nop 0
	v_addc_co_u32_e32 v9, vcc, 0, v7, vcc
	global_load_dword v15, v[6:7], off nt
	global_load_dword v16, v[8:9], off nt
	v_add_co_u32_e32 v8, vcc, s0, v6
	s_mov_b32 s0, 0xc000
	s_nop 0
	v_addc_co_u32_e32 v9, vcc, 0, v7, vcc
	global_load_dword v17, v[8:9], off nt
	v_add_co_u32_e32 v8, vcc, s0, v6
	s_mov_b32 s0, 0x10000
	s_nop 0
	v_addc_co_u32_e32 v9, vcc, 0, v7, vcc
	global_load_dword v18, v[8:9], off nt
	v_add_co_u32_e32 v8, vcc, s0, v6
	s_mov_b32 s0, 0x14000
	s_nop 0
	v_addc_co_u32_e32 v9, vcc, 0, v7, vcc
	global_load_dword v19, v[8:9], off nt
	v_add_co_u32_e32 v8, vcc, s0, v6
	s_mov_b32 s0, 0x18000
	s_nop 0
	v_addc_co_u32_e32 v9, vcc, 0, v7, vcc
	global_load_dword v20, v[8:9], off nt
	v_add_co_u32_e32 v8, vcc, s0, v6
	s_mov_b32 s0, 0x1c000
	s_nop 0
	v_addc_co_u32_e32 v9, vcc, 0, v7, vcc
	global_load_dword v21, v[8:9], off nt
	v_add_co_u32_e32 v8, vcc, s0, v6
	s_mov_b32 s0, 0x20000
	s_nop 0
	v_addc_co_u32_e32 v9, vcc, 0, v7, vcc
	global_load_dword v22, v[8:9], off nt
	v_add_co_u32_e32 v8, vcc, s0, v6
	s_mov_b32 s0, 0x24000
	s_nop 0
	v_addc_co_u32_e32 v9, vcc, 0, v7, vcc
	global_load_dword v23, v[8:9], off nt
	v_add_co_u32_e32 v8, vcc, s0, v6
	s_mov_b32 s0, 0x28000
	s_nop 0
	v_addc_co_u32_e32 v9, vcc, 0, v7, vcc
	global_load_dword v24, v[8:9], off nt
	v_add_co_u32_e32 v8, vcc, s0, v6
	s_mov_b32 s0, 0x2c000
	s_nop 0
	v_addc_co_u32_e32 v9, vcc, 0, v7, vcc
	global_load_dword v25, v[8:9], off nt
	v_add_co_u32_e32 v8, vcc, s0, v6
	s_mov_b32 s0, 0x30000
	s_nop 0
	v_addc_co_u32_e32 v9, vcc, 0, v7, vcc
	global_load_dword v26, v[8:9], off nt
	v_add_co_u32_e32 v8, vcc, s0, v6
	s_mov_b32 s0, 0x34000
	s_nop 0
	v_addc_co_u32_e32 v9, vcc, 0, v7, vcc
	global_load_dword v27, v[8:9], off nt
	v_add_co_u32_e32 v8, vcc, s0, v6
	s_mov_b32 s0, 0x38000
	s_nop 0
	v_addc_co_u32_e32 v9, vcc, 0, v7, vcc
	global_load_dword v28, v[8:9], off nt
	v_add_co_u32_e32 v8, vcc, s0, v6
	s_mov_b32 s0, 0x3c000
	s_nop 0
	v_addc_co_u32_e32 v9, vcc, 0, v7, vcc
	global_load_dword v29, v[8:9], off nt
	v_add_co_u32_e32 v8, vcc, s0, v6
	s_mov_b32 s0, 0x40000
	s_nop 0
	v_addc_co_u32_e32 v9, vcc, 0, v7, vcc
	global_load_dword v30, v[8:9], off nt
	v_add_co_u32_e32 v8, vcc, s0, v6
	s_mov_b32 s0, 0x44000
	s_nop 0
	v_addc_co_u32_e32 v9, vcc, 0, v7, vcc
	global_load_dword v31, v[8:9], off nt
	v_add_co_u32_e32 v8, vcc, s0, v6
	s_mov_b32 s0, 0x48000
	s_nop 0
	v_addc_co_u32_e32 v9, vcc, 0, v7, vcc
	global_load_dword v32, v[8:9], off nt
	v_add_co_u32_e32 v8, vcc, s0, v6
	s_mov_b32 s0, 0x4c000
	s_nop 0
	v_addc_co_u32_e32 v9, vcc, 0, v7, vcc
	global_load_dword v33, v[8:9], off nt
	v_add_co_u32_e32 v8, vcc, s0, v6
	s_mov_b32 s0, 0x50000
	s_nop 0
	v_addc_co_u32_e32 v9, vcc, 0, v7, vcc
	global_load_dword v34, v[8:9], off nt
	v_add_co_u32_e32 v8, vcc, s0, v6
	s_mov_b32 s0, 0x54000
	s_nop 0
	v_addc_co_u32_e32 v9, vcc, 0, v7, vcc
	global_load_dword v35, v[8:9], off nt
	v_add_co_u32_e32 v8, vcc, s0, v6
	s_mov_b32 s0, 0x58000
	s_nop 0
	v_addc_co_u32_e32 v9, vcc, 0, v7, vcc
	global_load_dword v36, v[8:9], off nt
	v_add_co_u32_e32 v8, vcc, s0, v6
	s_mov_b32 s0, 0x5c000
	s_nop 0
	v_addc_co_u32_e32 v9, vcc, 0, v7, vcc
	global_load_dword v37, v[8:9], off nt
	v_add_co_u32_e32 v8, vcc, s0, v6
	s_mov_b32 s0, 0x60000
	s_nop 0
	v_addc_co_u32_e32 v9, vcc, 0, v7, vcc
	global_load_dword v38, v[8:9], off nt
	v_add_co_u32_e32 v8, vcc, s0, v6
	s_mov_b32 s0, 0x64000
	s_nop 0
	v_addc_co_u32_e32 v9, vcc, 0, v7, vcc
	global_load_dword v39, v[8:9], off nt
	v_add_co_u32_e32 v8, vcc, s0, v6
	s_mov_b32 s0, 0x68000
	s_nop 0
	v_addc_co_u32_e32 v9, vcc, 0, v7, vcc
	global_load_dword v40, v[8:9], off nt
	v_add_co_u32_e32 v8, vcc, s0, v6
	s_mov_b32 s0, 0x6c000
	s_nop 0
	v_addc_co_u32_e32 v9, vcc, 0, v7, vcc
	global_load_dword v41, v[8:9], off nt
	v_add_co_u32_e32 v8, vcc, s0, v6
	s_mov_b32 s0, 0x70000
	s_nop 0
	v_addc_co_u32_e32 v9, vcc, 0, v7, vcc
	global_load_dword v42, v[8:9], off nt
	v_add_co_u32_e32 v8, vcc, s0, v6
	s_mov_b32 s0, 0x74000
	s_nop 0
	v_addc_co_u32_e32 v9, vcc, 0, v7, vcc
	global_load_dword v43, v[8:9], off nt
	v_add_co_u32_e32 v8, vcc, s0, v6
	s_mov_b32 s0, 0x78000
	s_nop 0
	v_addc_co_u32_e32 v9, vcc, 0, v7, vcc
	global_load_dword v44, v[8:9], off nt
	v_add_co_u32_e32 v8, vcc, s0, v6
	s_mov_b32 s0, 0x7c000
	s_nop 0
	v_addc_co_u32_e32 v9, vcc, 0, v7, vcc
	v_add_co_u32_e32 v6, vcc, s0, v6
	global_load_dword v8, v[8:9], off nt
	s_nop 0
	v_addc_co_u32_e32 v7, vcc, 0, v7, vcc
	global_load_dword v6, v[6:7], off nt
	v_add_u32_e32 v7, 0x400, v5
	s_waitcnt vmcnt(0)
	ds_write2_b32 v5, v15, v16 offset1:66
	ds_write2_b32 v5, v17, v18 offset0:132 offset1:198
	ds_write2_b32 v7, v19, v20 offset0:8 offset1:74
	ds_write2_b32 v7, v21, v22 offset0:140 offset1:206
	v_add_u32_e32 v7, 0x800, v5
	ds_write2_b32 v7, v23, v24 offset0:16 offset1:82
	ds_write2_b32 v7, v25, v26 offset0:148 offset1:214
	v_add_u32_e32 v7, 0xc00, v5
	ds_write2_b32 v7, v27, v28 offset0:24 offset1:90
	ds_write2_b32 v7, v29, v30 offset0:156 offset1:222
	v_add_u32_e32 v7, 0x1000, v5
	ds_write2_b32 v7, v31, v32 offset0:32 offset1:98
	ds_write2_b32 v7, v33, v34 offset0:164 offset1:230
	v_add_u32_e32 v7, 0x1400, v5
	ds_write2_b32 v7, v35, v36 offset0:40 offset1:106
	ds_write2_b32 v7, v37, v38 offset0:172 offset1:238
	v_add_u32_e32 v7, 0x1800, v5
	ds_write2_b32 v7, v39, v40 offset0:48 offset1:114
	ds_write2_b32 v7, v41, v42 offset0:180 offset1:246
	v_add_u32_e32 v7, 0x1c00, v5
	ds_write2_b32 v7, v43, v44 offset0:56 offset1:122
	ds_write2_b32 v7, v8, v6 offset0:188 offset1:254
	s_waitcnt lgkmcnt(0)
	ds_read2_b32 v[8:9], v11 offset0:33 offset1:41
	ds_read2_b32 v[20:21], v11 offset1:8
	ds_read2_b32 v[22:23], v11 offset0:66 offset1:74
	ds_read2_b32 v[24:25], v11 offset0:99 offset1:107
	ds_read2_b32 v[26:27], v11 offset0:132 offset1:140
	ds_read2_b32 v[28:29], v11 offset0:165 offset1:173
	ds_read2_b32 v[30:31], v11 offset0:198 offset1:206
	ds_read2_b32 v[32:33], v11 offset0:231 offset1:239
	s_waitcnt lgkmcnt(7)
	v_bfe_u32 v16, v8, 16, 1
	s_waitcnt lgkmcnt(6)
	v_bfe_u32 v15, v20, 16, 1
	v_add3_u32 v15, v20, v15, s53
	v_lshrrev_b32_e32 v15, 16, v15
	v_add3_u32 v8, v8, v16, s53
	v_and_or_b32 v16, v8, s77, v15
	s_waitcnt lgkmcnt(5)
	v_bfe_u32 v8, v22, 16, 1
	v_add3_u32 v8, v22, v8, s53
	s_waitcnt lgkmcnt(4)
	v_bfe_u32 v15, v24, 16, 1
	v_lshrrev_b32_e32 v8, 16, v8
	v_add3_u32 v15, v24, v15, s53
	v_and_or_b32 v17, v15, s77, v8
	s_waitcnt lgkmcnt(3)
	v_bfe_u32 v8, v26, 16, 1
	v_add3_u32 v8, v26, v8, s53
	s_waitcnt lgkmcnt(2)
	v_bfe_u32 v15, v28, 16, 1
	v_lshrrev_b32_e32 v8, 16, v8
	v_add3_u32 v15, v28, v15, s53
	v_and_or_b32 v18, v15, s77, v8
	s_waitcnt lgkmcnt(1)
	v_bfe_u32 v8, v30, 16, 1
	v_add3_u32 v8, v30, v8, s53
	s_waitcnt lgkmcnt(0)
	v_bfe_u32 v15, v32, 16, 1
	s_lshl_b32 s0, s11, 1
	v_lshrrev_b32_e32 v8, 16, v8
	v_add3_u32 v15, v32, v15, s53
	s_add_u32 s0, s3, s0
	v_and_or_b32 v19, v15, s77, v8
	v_or_b32_e32 v8, s2, v10
	s_addc_u32 s1, s10, 0
	v_lshlrev_b32_e32 v202, 1, v4
	v_mul_u32_u24_e32 v8, 0x1600, v8
	v_lshl_add_u64 v[6:7], s[0:1], 0, v[202:203]
	v_lshlrev_b32_e32 v202, 1, v8
	v_bfe_u32 v8, v21, 16, 1
	v_add3_u32 v8, v21, v8, s53
	v_bfe_u32 v15, v9, 16, 1
	v_lshl_add_u64 v[34:35], v[6:7], 0, v[202:203]
	v_lshrrev_b32_e32 v8, 16, v8
	v_add3_u32 v9, v9, v15, s53
	global_store_dwordx4 v[34:35], v[16:19], off nt
	v_readlane_b32 s17, v251, 15
	v_readlane_b32 s18, v251, 16
	v_and_or_b32 v16, v9, s77, v8
	v_bfe_u32 v8, v23, 16, 1
	v_add3_u32 v8, v23, v8, s53
	v_bfe_u32 v9, v25, 16, 1
	v_lshrrev_b32_e32 v8, 16, v8
	v_add3_u32 v9, v25, v9, s53
	v_and_or_b32 v17, v9, s77, v8
	v_bfe_u32 v8, v27, 16, 1
	v_add3_u32 v8, v27, v8, s53
	v_bfe_u32 v9, v29, 16, 1
	v_lshrrev_b32_e32 v8, 16, v8
	v_add3_u32 v9, v29, v9, s53
	v_and_or_b32 v18, v9, s77, v8
	v_bfe_u32 v8, v31, 16, 1
	v_add3_u32 v8, v31, v8, s53
	v_bfe_u32 v9, v33, 16, 1
	v_lshrrev_b32_e32 v8, 16, v8
	v_add3_u32 v9, v33, v9, s53
	v_and_or_b32 v19, v9, s77, v8
	v_or_b32_e32 v8, s2, v12
	v_mul_u32_u24_e32 v8, 0x1600, v8
	v_lshlrev_b32_e32 v202, 1, v8
	v_lshl_add_u64 v[8:9], v[6:7], 0, v[202:203]
	global_store_dwordx4 v[8:9], v[16:19], off nt
	ds_read2_b32 v[8:9], v11 offset0:16 offset1:24
	ds_read2_b32 v[20:21], v11 offset0:49 offset1:57
	ds_read2_b32 v[22:23], v11 offset0:82 offset1:90
	ds_read2_b32 v[24:25], v11 offset0:115 offset1:123
	ds_read2_b32 v[26:27], v11 offset0:148 offset1:156
	ds_read2_b32 v[28:29], v11 offset0:181 offset1:189
	ds_read2_b32 v[30:31], v11 offset0:214 offset1:222
	ds_read2_b32 v[32:33], v11 offset0:247 offset1:255
	s_waitcnt lgkmcnt(7)
	v_bfe_u32 v15, v8, 16, 1
	v_add3_u32 v8, v8, v15, s53
	s_waitcnt lgkmcnt(6)
	v_bfe_u32 v15, v20, 16, 1
	v_lshrrev_b32_e32 v8, 16, v8
	v_add3_u32 v15, v20, v15, s53
	v_and_or_b32 v16, v15, s77, v8
	s_waitcnt lgkmcnt(5)
	v_bfe_u32 v8, v22, 16, 1
	v_add3_u32 v8, v22, v8, s53
	s_waitcnt lgkmcnt(4)
	v_bfe_u32 v15, v24, 16, 1
	v_lshrrev_b32_e32 v8, 16, v8
	v_add3_u32 v15, v24, v15, s53
	v_and_or_b32 v17, v15, s77, v8
	s_waitcnt lgkmcnt(3)
	v_bfe_u32 v8, v26, 16, 1
	v_add3_u32 v8, v26, v8, s53
	s_waitcnt lgkmcnt(2)
	v_bfe_u32 v15, v28, 16, 1
	v_lshrrev_b32_e32 v8, 16, v8
	v_add3_u32 v15, v28, v15, s53
	v_and_or_b32 v18, v15, s77, v8
	s_waitcnt lgkmcnt(1)
	v_bfe_u32 v8, v30, 16, 1
	v_add3_u32 v8, v30, v8, s53
	s_waitcnt lgkmcnt(0)
	v_bfe_u32 v15, v32, 16, 1
	v_lshrrev_b32_e32 v8, 16, v8
	v_add3_u32 v15, v32, v15, s53
	v_and_or_b32 v19, v15, s77, v8
	v_or_b32_e32 v8, s2, v13
	v_mul_u32_u24_e32 v8, 0x1600, v8
	v_lshlrev_b32_e32 v202, 1, v8
	v_bfe_u32 v8, v9, 16, 1
	v_add3_u32 v8, v9, v8, s53
	v_bfe_u32 v9, v21, 16, 1
	v_lshl_add_u64 v[34:35], v[6:7], 0, v[202:203]
	v_lshrrev_b32_e32 v8, 16, v8
	v_add3_u32 v9, v21, v9, s53
	global_store_dwordx4 v[34:35], v[16:19], off nt
	v_readlane_b32 s19, v251, 17
	v_readlane_b32 s22, v251, 20
	v_and_or_b32 v16, v9, s77, v8
	v_bfe_u32 v8, v23, 16, 1
	v_add3_u32 v8, v23, v8, s53
	v_bfe_u32 v9, v25, 16, 1
	v_lshrrev_b32_e32 v8, 16, v8
	v_add3_u32 v9, v25, v9, s53
	v_and_or_b32 v17, v9, s77, v8
	v_bfe_u32 v8, v27, 16, 1
	v_add3_u32 v8, v27, v8, s53
	v_bfe_u32 v9, v29, 16, 1
	v_lshrrev_b32_e32 v8, 16, v8
	v_add3_u32 v9, v29, v9, s53
	v_and_or_b32 v18, v9, s77, v8
	v_bfe_u32 v8, v31, 16, 1
	v_add3_u32 v8, v31, v8, s53
	v_bfe_u32 v9, v33, 16, 1
	v_lshrrev_b32_e32 v8, 16, v8
	v_add3_u32 v9, v33, v9, s53
	v_and_or_b32 v19, v9, s77, v8
	v_or_b32_e32 v8, s2, v14
	v_mul_u32_u24_e32 v8, 0x1600, v8
	v_lshlrev_b32_e32 v202, 1, v8
	v_lshl_add_u64 v[6:7], v[6:7], 0, v[202:203]
	global_store_dwordx4 v[6:7], v[16:19], off nt
	s_waitcnt lgkmcnt(0)
	v_readlane_b32 s23, v251, 21
	v_readlane_b32 s24, v251, 22
	v_readlane_b32 s25, v251, 23
	v_readlane_b32 s26, v251, 24
	v_readlane_b32 s27, v251, 25
	v_readlane_b32 s28, v251, 26
	v_readlane_b32 s29, v251, 27
	v_readlane_b32 s30, v251, 28
	v_readlane_b32 s31, v251, 29
	s_mov_b64 s[2:3], 0
.LBB0_1179:
	s_andn2_b64 vcc, exec, s[2:3]
	s_cbranch_vccnz .LBB0_1181
	v_readlane_b32 s16, v251, 14
	v_readlane_b32 s18, v251, 16
	v_readlane_b32 s19, v251, 17
	s_add_u32 s0, s18, s9
	s_addc_u32 s1, s19, s8
	v_readlane_b32 s2, v251, 56
	s_add_u32 s3, s2, s9
	v_readlane_b32 s2, v251, 57
	s_addc_u32 s10, s2, s8
	s_and_b32 s2, 0xffff, s5
	s_mul_i32 s2, s2, 0xba2f
	s_lshr_b32 s11, s2, 23
	s_mul_i32 s2, s11, 0xb0
	s_sub_i32 s2, s5, s2
	s_and_b32 s14, s2, 0xffff
	s_lshl_b32 s2, s14, 5
	s_lshl_b32 s15, s14, 6
	s_and_b32 s15, s15, 0x3f00
	s_and_b32 s2, s2, 0x60
	s_or_b32 s2, s15, s2
	s_bitset1_b32 s2, 7
	s_lshl_b32 s14, s14, 7
	v_lshl_or_b32 v8, s11, 6, v3
	s_add_u32 s0, s0, s14
	s_addc_u32 s1, s1, 0
	v_lshlrev_b32_e32 v202, 2, v2
	v_mul_u32_u24_e32 v8, 0x1600, v8
	v_lshl_add_u64 v[6:7], s[0:1], 0, v[202:203]
	v_lshlrev_b32_e32 v202, 2, v8
	v_lshl_add_u64 v[6:7], v[6:7], 0, v[202:203]
	s_mov_b32 s0, 0xb000
	v_add_co_u32_e32 v8, vcc, s0, v6
	s_mov_b32 s0, 0x16000
	s_nop 0
	v_addc_co_u32_e32 v9, vcc, 0, v7, vcc
	global_load_dword v15, v[6:7], off nt
	global_load_dword v16, v[8:9], off nt
	v_add_co_u32_e32 v8, vcc, s0, v6
	s_mov_b32 s0, 0x21000
	s_nop 0
	v_addc_co_u32_e32 v9, vcc, 0, v7, vcc
	global_load_dword v17, v[8:9], off nt
	v_add_co_u32_e32 v8, vcc, s0, v6
	s_mov_b32 s0, 0x2c000
	s_nop 0
	v_addc_co_u32_e32 v9, vcc, 0, v7, vcc
	global_load_dword v18, v[8:9], off nt
	v_add_co_u32_e32 v8, vcc, s0, v6
	s_mov_b32 s0, 0x37000
	s_nop 0
	v_addc_co_u32_e32 v9, vcc, 0, v7, vcc
	global_load_dword v19, v[8:9], off nt
	v_add_co_u32_e32 v8, vcc, s0, v6
	s_mov_b32 s0, 0x42000
	s_nop 0
	v_addc_co_u32_e32 v9, vcc, 0, v7, vcc
	global_load_dword v20, v[8:9], off nt
	v_add_co_u32_e32 v8, vcc, s0, v6
	s_mov_b32 s0, 0x4d000
	s_nop 0
	v_addc_co_u32_e32 v9, vcc, 0, v7, vcc
	global_load_dword v21, v[8:9], off nt
	v_add_co_u32_e32 v8, vcc, s0, v6
	s_mov_b32 s0, 0x58000
	s_nop 0
	v_addc_co_u32_e32 v9, vcc, 0, v7, vcc
	global_load_dword v22, v[8:9], off nt
	v_add_co_u32_e32 v8, vcc, s0, v6
	s_mov_b32 s0, 0x63000
	s_nop 0
	v_addc_co_u32_e32 v9, vcc, 0, v7, vcc
	global_load_dword v23, v[8:9], off nt
	v_add_co_u32_e32 v8, vcc, s0, v6
	s_mov_b32 s0, 0x6e000
	s_nop 0
	v_addc_co_u32_e32 v9, vcc, 0, v7, vcc
	global_load_dword v24, v[8:9], off nt
	v_add_co_u32_e32 v8, vcc, s0, v6
	s_mov_b32 s0, 0x79000
	s_nop 0
	v_addc_co_u32_e32 v9, vcc, 0, v7, vcc
	global_load_dword v25, v[8:9], off nt
	v_add_co_u32_e32 v8, vcc, s0, v6
	s_mov_b32 s0, 0x84000
	s_nop 0
	v_addc_co_u32_e32 v9, vcc, 0, v7, vcc
	global_load_dword v26, v[8:9], off nt
	v_add_co_u32_e32 v8, vcc, s0, v6
	s_mov_b32 s0, 0x8f000
	s_nop 0
	v_addc_co_u32_e32 v9, vcc, 0, v7, vcc
	global_load_dword v27, v[8:9], off nt
	v_add_co_u32_e32 v8, vcc, s0, v6
	s_mov_b32 s0, 0x9a000
	s_nop 0
	v_addc_co_u32_e32 v9, vcc, 0, v7, vcc
	global_load_dword v28, v[8:9], off nt
	v_add_co_u32_e32 v8, vcc, s0, v6
	s_mov_b32 s0, 0xa5000
	s_nop 0
	v_addc_co_u32_e32 v9, vcc, 0, v7, vcc
	global_load_dword v29, v[8:9], off nt
	v_add_co_u32_e32 v8, vcc, s0, v6
	s_mov_b32 s0, 0xb0000
	s_nop 0
	v_addc_co_u32_e32 v9, vcc, 0, v7, vcc
	global_load_dword v30, v[8:9], off nt
	v_add_co_u32_e32 v8, vcc, s0, v6
	s_mov_b32 s0, 0xbb000
	s_nop 0
	v_addc_co_u32_e32 v9, vcc, 0, v7, vcc
	global_load_dword v31, v[8:9], off nt
	v_add_co_u32_e32 v8, vcc, s0, v6
	s_mov_b32 s0, 0xc6000
	s_nop 0
	v_addc_co_u32_e32 v9, vcc, 0, v7, vcc
	global_load_dword v32, v[8:9], off nt
	v_add_co_u32_e32 v8, vcc, s0, v6
	s_mov_b32 s0, 0xd1000
	s_nop 0
	v_addc_co_u32_e32 v9, vcc, 0, v7, vcc
	global_load_dword v33, v[8:9], off nt
	v_add_co_u32_e32 v8, vcc, s0, v6
	s_mov_b32 s0, 0xdc000
	s_nop 0
	v_addc_co_u32_e32 v9, vcc, 0, v7, vcc
	global_load_dword v34, v[8:9], off nt
	v_add_co_u32_e32 v8, vcc, s0, v6
	s_mov_b32 s0, 0xe7000
	s_nop 0
	v_addc_co_u32_e32 v9, vcc, 0, v7, vcc
	global_load_dword v35, v[8:9], off nt
	v_add_co_u32_e32 v8, vcc, s0, v6
	s_mov_b32 s0, 0xf2000
	s_nop 0
	v_addc_co_u32_e32 v9, vcc, 0, v7, vcc
	global_load_dword v36, v[8:9], off nt
	v_add_co_u32_e32 v8, vcc, s0, v6
	s_mov_b32 s0, 0xfd000
	s_nop 0
	v_addc_co_u32_e32 v9, vcc, 0, v7, vcc
	global_load_dword v37, v[8:9], off nt
	v_add_co_u32_e32 v8, vcc, s0, v6
	s_mov_b32 s0, 0x108000
	s_nop 0
	v_addc_co_u32_e32 v9, vcc, 0, v7, vcc
	global_load_dword v38, v[8:9], off nt
	v_add_co_u32_e32 v8, vcc, s0, v6
	s_mov_b32 s0, 0x113000
	s_nop 0
	v_addc_co_u32_e32 v9, vcc, 0, v7, vcc
	global_load_dword v39, v[8:9], off nt
	v_add_co_u32_e32 v8, vcc, s0, v6
	s_mov_b32 s0, 0x11e000
	s_nop 0
	v_addc_co_u32_e32 v9, vcc, 0, v7, vcc
	global_load_dword v40, v[8:9], off nt
	v_add_co_u32_e32 v8, vcc, s0, v6
	s_mov_b32 s0, 0x129000
	s_nop 0
	v_addc_co_u32_e32 v9, vcc, 0, v7, vcc
	global_load_dword v41, v[8:9], off nt
	v_add_co_u32_e32 v8, vcc, s0, v6
	s_mov_b32 s0, 0x134000
	s_nop 0
	v_addc_co_u32_e32 v9, vcc, 0, v7, vcc
	global_load_dword v42, v[8:9], off nt
	v_add_co_u32_e32 v8, vcc, s0, v6
	s_mov_b32 s0, 0x13f000
	s_nop 0
	v_addc_co_u32_e32 v9, vcc, 0, v7, vcc
	global_load_dword v43, v[8:9], off nt
	v_add_co_u32_e32 v8, vcc, s0, v6
	s_mov_b32 s0, 0x14a000
	s_nop 0
	v_addc_co_u32_e32 v9, vcc, 0, v7, vcc
	global_load_dword v44, v[8:9], off nt
	v_add_co_u32_e32 v8, vcc, s0, v6
	s_mov_b32 s0, 0x155000
	s_nop 0
	v_addc_co_u32_e32 v9, vcc, 0, v7, vcc
	v_add_co_u32_e32 v6, vcc, s0, v6
	global_load_dword v8, v[8:9], off nt
	s_nop 0
	v_addc_co_u32_e32 v7, vcc, 0, v7, vcc
	global_load_dword v6, v[6:7], off nt
	v_add_u32_e32 v7, 0x400, v5
	s_waitcnt vmcnt(0)
	ds_write2_b32 v5, v15, v16 offset1:66
	ds_write2_b32 v5, v17, v18 offset0:132 offset1:198
	ds_write2_b32 v7, v19, v20 offset0:8 offset1:74
	ds_write2_b32 v7, v21, v22 offset0:140 offset1:206
	v_add_u32_e32 v7, 0x800, v5
	ds_write2_b32 v7, v23, v24 offset0:16 offset1:82
	ds_write2_b32 v7, v25, v26 offset0:148 offset1:214
	v_add_u32_e32 v7, 0xc00, v5
	ds_write2_b32 v7, v27, v28 offset0:24 offset1:90
	ds_write2_b32 v7, v29, v30 offset0:156 offset1:222
	v_add_u32_e32 v7, 0x1000, v5
	ds_write2_b32 v7, v31, v32 offset0:32 offset1:98
	ds_write2_b32 v7, v33, v34 offset0:164 offset1:230
	v_add_u32_e32 v7, 0x1400, v5
	ds_write2_b32 v7, v35, v36 offset0:40 offset1:106
	ds_write2_b32 v7, v37, v38 offset0:172 offset1:238
	v_add_u32_e32 v7, 0x1800, v5
	ds_write2_b32 v7, v39, v40 offset0:48 offset1:114
	ds_write2_b32 v7, v41, v42 offset0:180 offset1:246
	v_add_u32_e32 v7, 0x1c00, v5
	ds_write2_b32 v7, v43, v44 offset0:56 offset1:122
	ds_write2_b32 v7, v8, v6 offset0:188 offset1:254
	s_waitcnt lgkmcnt(0)
	ds_read2_b32 v[8:9], v11 offset0:33 offset1:41
	ds_read2_b32 v[20:21], v11 offset1:8
	ds_read2_b32 v[22:23], v11 offset0:66 offset1:74
	ds_read2_b32 v[24:25], v11 offset0:99 offset1:107
	ds_read2_b32 v[26:27], v11 offset0:132 offset1:140
	ds_read2_b32 v[28:29], v11 offset0:165 offset1:173
	ds_read2_b32 v[30:31], v11 offset0:198 offset1:206
	ds_read2_b32 v[32:33], v11 offset0:231 offset1:239
	s_waitcnt lgkmcnt(7)
	v_bfe_u32 v16, v8, 16, 1
	s_waitcnt lgkmcnt(6)
	v_bfe_u32 v15, v20, 16, 1
	v_add3_u32 v15, v20, v15, s53
	v_lshrrev_b32_e32 v15, 16, v15
	v_add3_u32 v8, v8, v16, s53
	v_and_or_b32 v16, v8, s77, v15
	s_waitcnt lgkmcnt(5)
	v_bfe_u32 v8, v22, 16, 1
	v_add3_u32 v8, v22, v8, s53
	s_waitcnt lgkmcnt(4)
	v_bfe_u32 v15, v24, 16, 1
	v_lshrrev_b32_e32 v8, 16, v8
	v_add3_u32 v15, v24, v15, s53
	v_and_or_b32 v17, v15, s77, v8
	s_waitcnt lgkmcnt(3)
	v_bfe_u32 v8, v26, 16, 1
	v_add3_u32 v8, v26, v8, s53
	s_waitcnt lgkmcnt(2)
	v_bfe_u32 v15, v28, 16, 1
	v_lshrrev_b32_e32 v8, 16, v8
	v_add3_u32 v15, v28, v15, s53
	v_and_or_b32 v18, v15, s77, v8
	s_waitcnt lgkmcnt(1)
	v_bfe_u32 v8, v30, 16, 1
	s_lshl_b32 s0, s11, 7
	v_add3_u32 v8, v30, v8, s53
	s_waitcnt lgkmcnt(0)
	v_bfe_u32 v15, v32, 16, 1
	s_add_u32 s0, s3, s0
	v_lshrrev_b32_e32 v8, 16, v8
	v_add3_u32 v15, v32, v15, s53
	s_addc_u32 s1, s10, 0
	v_lshlrev_b32_e32 v202, 1, v4
	v_and_or_b32 v19, v15, s77, v8
	v_or_b32_e32 v8, s2, v10
	v_lshl_add_u64 v[6:7], s[0:1], 0, v[202:203]
	v_lshlrev_b32_e32 v202, 12, v8
	v_bfe_u32 v8, v21, 16, 1
	v_add3_u32 v8, v21, v8, s53
	v_bfe_u32 v15, v9, 16, 1
	v_lshl_add_u64 v[34:35], v[6:7], 0, v[202:203]
	v_lshrrev_b32_e32 v8, 16, v8
	v_add3_u32 v9, v9, v15, s53
	global_store_dwordx4 v[34:35], v[16:19], off nt
	v_readlane_b32 s17, v251, 15
	v_readlane_b32 s20, v251, 18
	v_and_or_b32 v16, v9, s77, v8
	v_bfe_u32 v8, v23, 16, 1
	v_add3_u32 v8, v23, v8, s53
	v_bfe_u32 v9, v25, 16, 1
	v_lshrrev_b32_e32 v8, 16, v8
	v_add3_u32 v9, v25, v9, s53
	v_and_or_b32 v17, v9, s77, v8
	v_bfe_u32 v8, v27, 16, 1
	v_add3_u32 v8, v27, v8, s53
	v_bfe_u32 v9, v29, 16, 1
	v_lshrrev_b32_e32 v8, 16, v8
	v_add3_u32 v9, v29, v9, s53
	v_and_or_b32 v18, v9, s77, v8
	v_bfe_u32 v8, v31, 16, 1
	v_add3_u32 v8, v31, v8, s53
	v_bfe_u32 v9, v33, 16, 1
	v_lshrrev_b32_e32 v8, 16, v8
	v_add3_u32 v9, v33, v9, s53
	v_and_or_b32 v19, v9, s77, v8
	v_or_b32_e32 v8, s2, v12
	v_lshlrev_b32_e32 v202, 12, v8
	v_lshl_add_u64 v[8:9], v[6:7], 0, v[202:203]
	global_store_dwordx4 v[8:9], v[16:19], off nt
	ds_read2_b32 v[8:9], v11 offset0:49 offset1:57
	ds_read2_b32 v[20:21], v11 offset0:16 offset1:24
	ds_read2_b32 v[22:23], v11 offset0:82 offset1:90
	ds_read2_b32 v[24:25], v11 offset0:115 offset1:123
	ds_read2_b32 v[26:27], v11 offset0:148 offset1:156
	ds_read2_b32 v[28:29], v11 offset0:181 offset1:189
	ds_read2_b32 v[30:31], v11 offset0:214 offset1:222
	ds_read2_b32 v[32:33], v11 offset0:247 offset1:255
	s_waitcnt lgkmcnt(7)
	v_bfe_u32 v16, v8, 16, 1
	s_waitcnt lgkmcnt(6)
	v_bfe_u32 v15, v20, 16, 1
	v_add3_u32 v15, v20, v15, s53
	v_lshrrev_b32_e32 v15, 16, v15
	v_add3_u32 v8, v8, v16, s53
	v_and_or_b32 v16, v8, s77, v15
	s_waitcnt lgkmcnt(5)
	v_bfe_u32 v8, v22, 16, 1
	v_add3_u32 v8, v22, v8, s53
	s_waitcnt lgkmcnt(4)
	v_bfe_u32 v15, v24, 16, 1
	v_lshrrev_b32_e32 v8, 16, v8
	v_add3_u32 v15, v24, v15, s53
	v_and_or_b32 v17, v15, s77, v8
	s_waitcnt lgkmcnt(3)
	v_bfe_u32 v8, v26, 16, 1
	v_add3_u32 v8, v26, v8, s53
	s_waitcnt lgkmcnt(2)
	v_bfe_u32 v15, v28, 16, 1
	v_lshrrev_b32_e32 v8, 16, v8
	v_add3_u32 v15, v28, v15, s53
	v_and_or_b32 v18, v15, s77, v8
	s_waitcnt lgkmcnt(1)
	v_bfe_u32 v8, v30, 16, 1
	v_add3_u32 v8, v30, v8, s53
	s_waitcnt lgkmcnt(0)
	v_bfe_u32 v15, v32, 16, 1
	v_lshrrev_b32_e32 v8, 16, v8
	v_add3_u32 v15, v32, v15, s53
	v_and_or_b32 v19, v15, s77, v8
	v_or_b32_e32 v8, s2, v13
	v_lshlrev_b32_e32 v202, 12, v8
	v_bfe_u32 v8, v21, 16, 1
	v_add3_u32 v8, v21, v8, s53
	v_bfe_u32 v15, v9, 16, 1
	v_lshl_add_u64 v[34:35], v[6:7], 0, v[202:203]
	v_lshrrev_b32_e32 v8, 16, v8
	v_add3_u32 v9, v9, v15, s53
	global_store_dwordx4 v[34:35], v[16:19], off nt
	v_readlane_b32 s21, v251, 19
	v_readlane_b32 s22, v251, 20
	v_and_or_b32 v16, v9, s77, v8
	v_bfe_u32 v8, v23, 16, 1
	v_add3_u32 v8, v23, v8, s53
	v_bfe_u32 v9, v25, 16, 1
	v_lshrrev_b32_e32 v8, 16, v8
	v_add3_u32 v9, v25, v9, s53
	v_and_or_b32 v17, v9, s77, v8
	v_bfe_u32 v8, v27, 16, 1
	v_add3_u32 v8, v27, v8, s53
	v_bfe_u32 v9, v29, 16, 1
	v_lshrrev_b32_e32 v8, 16, v8
	v_add3_u32 v9, v29, v9, s53
	v_and_or_b32 v18, v9, s77, v8
	v_bfe_u32 v8, v31, 16, 1
	v_add3_u32 v8, v31, v8, s53
	v_bfe_u32 v9, v33, 16, 1
	v_lshrrev_b32_e32 v8, 16, v8
	v_add3_u32 v9, v33, v9, s53
	v_and_or_b32 v19, v9, s77, v8
	v_or_b32_e32 v8, s2, v14
	v_lshlrev_b32_e32 v202, 12, v8
	v_lshl_add_u64 v[6:7], v[6:7], 0, v[202:203]
	global_store_dwordx4 v[6:7], v[16:19], off nt
	s_waitcnt lgkmcnt(0)
	v_readlane_b32 s23, v251, 21
	v_readlane_b32 s24, v251, 22
	v_readlane_b32 s25, v251, 23
	v_readlane_b32 s26, v251, 24
	v_readlane_b32 s27, v251, 25
	v_readlane_b32 s28, v251, 26
	v_readlane_b32 s29, v251, 27
	v_readlane_b32 s30, v251, 28
	v_readlane_b32 s31, v251, 29

.LBB0_1182:
	s_andn2_b64 vcc, exec, s[2:3]
	s_cbranch_vccnz .LBB0_1184
	v_readlane_b32 s16, v251, 14
	v_readlane_b32 s17, v251, 15
	s_add_u32 s0, s16, s9
	s_addc_u32 s1, s17, s8
	v_readlane_b32 s2, v251, 56
	s_add_u32 s3, s2, s9
	v_readlane_b32 s2, v251, 57
	s_addc_u32 s8, s2, s8
	s_and_b32 s2, 0xffff, s5
	s_mul_i32 s2, s2, 0xba2f
	s_lshr_b32 s9, s2, 23
	s_mul_i32 s2, s9, 0xb0
	s_sub_i32 s2, s5, s2
	s_and_b32 s5, s2, 0xffff
	s_lshl_b32 s2, s5, 5
	s_lshl_b32 s10, s5, 6
	s_and_b32 s10, s10, 0x3f00
	s_and_b32 s2, s2, 0x60
	s_or_b32 s2, s2, s10
	s_lshl_b32 s5, s5, 7
	v_lshl_or_b32 v8, s9, 6, v3
	s_add_u32 s0, s0, s5
	s_addc_u32 s1, s1, 0
	v_lshlrev_b32_e32 v202, 2, v2
	v_mul_u32_u24_e32 v8, 0x1600, v8
	v_lshl_add_u64 v[6:7], s[0:1], 0, v[202:203]
	v_lshlrev_b32_e32 v202, 2, v8
	v_lshl_add_u64 v[6:7], v[6:7], 0, v[202:203]
	s_mov_b32 s0, 0xb000
	v_add_co_u32_e32 v8, vcc, s0, v6
	s_mov_b32 s0, 0x16000
	s_nop 0
	v_addc_co_u32_e32 v9, vcc, 0, v7, vcc
	global_load_dword v15, v[6:7], off nt
	global_load_dword v16, v[8:9], off nt
	v_add_co_u32_e32 v8, vcc, s0, v6
	s_mov_b32 s0, 0x21000
	s_nop 0
	v_addc_co_u32_e32 v9, vcc, 0, v7, vcc
	global_load_dword v17, v[8:9], off nt
	v_add_co_u32_e32 v8, vcc, s0, v6
	s_mov_b32 s0, 0x2c000
	s_nop 0
	v_addc_co_u32_e32 v9, vcc, 0, v7, vcc
	global_load_dword v18, v[8:9], off nt
	v_add_co_u32_e32 v8, vcc, s0, v6
	s_mov_b32 s0, 0x37000
	s_nop 0
	v_addc_co_u32_e32 v9, vcc, 0, v7, vcc
	global_load_dword v19, v[8:9], off nt
	v_add_co_u32_e32 v8, vcc, s0, v6
	s_mov_b32 s0, 0x42000
	s_nop 0
	v_addc_co_u32_e32 v9, vcc, 0, v7, vcc
	global_load_dword v20, v[8:9], off nt
	v_add_co_u32_e32 v8, vcc, s0, v6
	s_mov_b32 s0, 0x4d000
	s_nop 0
	v_addc_co_u32_e32 v9, vcc, 0, v7, vcc
	global_load_dword v21, v[8:9], off nt
	v_add_co_u32_e32 v8, vcc, s0, v6
	s_mov_b32 s0, 0x58000
	s_nop 0
	v_addc_co_u32_e32 v9, vcc, 0, v7, vcc
	global_load_dword v22, v[8:9], off nt
	v_add_co_u32_e32 v8, vcc, s0, v6
	s_mov_b32 s0, 0x63000
	s_nop 0
	v_addc_co_u32_e32 v9, vcc, 0, v7, vcc
	global_load_dword v23, v[8:9], off nt
	v_add_co_u32_e32 v8, vcc, s0, v6
	s_mov_b32 s0, 0x6e000
	s_nop 0
	v_addc_co_u32_e32 v9, vcc, 0, v7, vcc
	global_load_dword v24, v[8:9], off nt
	v_add_co_u32_e32 v8, vcc, s0, v6
	s_mov_b32 s0, 0x79000
	s_nop 0
	v_addc_co_u32_e32 v9, vcc, 0, v7, vcc
	global_load_dword v25, v[8:9], off nt
	v_add_co_u32_e32 v8, vcc, s0, v6
	s_mov_b32 s0, 0x84000
	s_nop 0
	v_addc_co_u32_e32 v9, vcc, 0, v7, vcc
	global_load_dword v26, v[8:9], off nt
	v_add_co_u32_e32 v8, vcc, s0, v6
	s_mov_b32 s0, 0x8f000
	s_nop 0
	v_addc_co_u32_e32 v9, vcc, 0, v7, vcc
	global_load_dword v27, v[8:9], off nt
	v_add_co_u32_e32 v8, vcc, s0, v6
	s_mov_b32 s0, 0x9a000
	s_nop 0
	v_addc_co_u32_e32 v9, vcc, 0, v7, vcc
	global_load_dword v28, v[8:9], off nt
	v_add_co_u32_e32 v8, vcc, s0, v6
	s_mov_b32 s0, 0xa5000
	s_nop 0
	v_addc_co_u32_e32 v9, vcc, 0, v7, vcc
	global_load_dword v29, v[8:9], off nt
	v_add_co_u32_e32 v8, vcc, s0, v6
	s_mov_b32 s0, 0xb0000
	s_nop 0
	v_addc_co_u32_e32 v9, vcc, 0, v7, vcc
	global_load_dword v30, v[8:9], off nt
	v_add_co_u32_e32 v8, vcc, s0, v6
	s_mov_b32 s0, 0xbb000
	s_nop 0
	v_addc_co_u32_e32 v9, vcc, 0, v7, vcc
	global_load_dword v31, v[8:9], off nt
	v_add_co_u32_e32 v8, vcc, s0, v6
	s_mov_b32 s0, 0xc6000
	s_nop 0
	v_addc_co_u32_e32 v9, vcc, 0, v7, vcc
	global_load_dword v32, v[8:9], off nt
	v_add_co_u32_e32 v8, vcc, s0, v6
	s_mov_b32 s0, 0xd1000
	s_nop 0
	v_addc_co_u32_e32 v9, vcc, 0, v7, vcc
	global_load_dword v33, v[8:9], off nt
	v_add_co_u32_e32 v8, vcc, s0, v6
	s_mov_b32 s0, 0xdc000
	s_nop 0
	v_addc_co_u32_e32 v9, vcc, 0, v7, vcc
	global_load_dword v34, v[8:9], off nt
	v_add_co_u32_e32 v8, vcc, s0, v6
	s_mov_b32 s0, 0xe7000
	s_nop 0
	v_addc_co_u32_e32 v9, vcc, 0, v7, vcc
	global_load_dword v35, v[8:9], off nt
	v_add_co_u32_e32 v8, vcc, s0, v6
	s_mov_b32 s0, 0xf2000
	s_nop 0
	v_addc_co_u32_e32 v9, vcc, 0, v7, vcc
	global_load_dword v36, v[8:9], off nt
	v_add_co_u32_e32 v8, vcc, s0, v6
	s_mov_b32 s0, 0xfd000
	s_nop 0
	v_addc_co_u32_e32 v9, vcc, 0, v7, vcc
	global_load_dword v37, v[8:9], off nt
	v_add_co_u32_e32 v8, vcc, s0, v6
	s_mov_b32 s0, 0x108000
	s_nop 0
	v_addc_co_u32_e32 v9, vcc, 0, v7, vcc
	global_load_dword v38, v[8:9], off nt
	v_add_co_u32_e32 v8, vcc, s0, v6
	s_mov_b32 s0, 0x113000
	s_nop 0
	v_addc_co_u32_e32 v9, vcc, 0, v7, vcc
	global_load_dword v39, v[8:9], off nt
	v_add_co_u32_e32 v8, vcc, s0, v6
	s_mov_b32 s0, 0x11e000
	s_nop 0
	v_addc_co_u32_e32 v9, vcc, 0, v7, vcc
	global_load_dword v40, v[8:9], off nt
	v_add_co_u32_e32 v8, vcc, s0, v6
	s_mov_b32 s0, 0x129000
	s_nop 0
	v_addc_co_u32_e32 v9, vcc, 0, v7, vcc
	global_load_dword v41, v[8:9], off nt
	v_add_co_u32_e32 v8, vcc, s0, v6
	s_mov_b32 s0, 0x134000
	s_nop 0
	v_addc_co_u32_e32 v9, vcc, 0, v7, vcc
	global_load_dword v42, v[8:9], off nt
	v_add_co_u32_e32 v8, vcc, s0, v6
	s_mov_b32 s0, 0x13f000
	s_nop 0
	v_addc_co_u32_e32 v9, vcc, 0, v7, vcc
	global_load_dword v43, v[8:9], off nt
	v_add_co_u32_e32 v8, vcc, s0, v6
	s_mov_b32 s0, 0x14a000
	s_nop 0
	v_addc_co_u32_e32 v9, vcc, 0, v7, vcc
	global_load_dword v44, v[8:9], off nt
	v_add_co_u32_e32 v8, vcc, s0, v6
	s_mov_b32 s0, 0x155000
	s_nop 0
	v_addc_co_u32_e32 v9, vcc, 0, v7, vcc
	v_add_co_u32_e32 v6, vcc, s0, v6
	global_load_dword v8, v[8:9], off nt
	s_nop 0
	v_addc_co_u32_e32 v7, vcc, 0, v7, vcc
	global_load_dword v6, v[6:7], off nt
	v_add_u32_e32 v7, 0x400, v5
	s_waitcnt vmcnt(0)
	ds_write2_b32 v5, v15, v16 offset1:66
	ds_write2_b32 v5, v17, v18 offset0:132 offset1:198
	ds_write2_b32 v7, v19, v20 offset0:8 offset1:74
	ds_write2_b32 v7, v21, v22 offset0:140 offset1:206
	v_add_u32_e32 v7, 0x800, v5
	ds_write2_b32 v7, v23, v24 offset0:16 offset1:82
	ds_write2_b32 v7, v25, v26 offset0:148 offset1:214
	v_add_u32_e32 v7, 0xc00, v5
	ds_write2_b32 v7, v27, v28 offset0:24 offset1:90
	ds_write2_b32 v7, v29, v30 offset0:156 offset1:222
	v_add_u32_e32 v7, 0x1000, v5
	ds_write2_b32 v7, v31, v32 offset0:32 offset1:98
	ds_write2_b32 v7, v33, v34 offset0:164 offset1:230
	v_add_u32_e32 v7, 0x1400, v5
	ds_write2_b32 v7, v35, v36 offset0:40 offset1:106
	ds_write2_b32 v7, v37, v38 offset0:172 offset1:238
	v_add_u32_e32 v7, 0x1800, v5
	ds_write2_b32 v7, v39, v40 offset0:48 offset1:114
	ds_write2_b32 v7, v41, v42 offset0:180 offset1:246
	v_add_u32_e32 v7, 0x1c00, v5
	ds_write2_b32 v7, v43, v44 offset0:56 offset1:122
	ds_write2_b32 v7, v8, v6 offset0:188 offset1:254
	s_waitcnt lgkmcnt(0)
	ds_read2_b32 v[8:9], v11 offset0:33 offset1:41
	ds_read2_b32 v[20:21], v11 offset1:8
	ds_read2_b32 v[22:23], v11 offset0:66 offset1:74
	ds_read2_b32 v[24:25], v11 offset0:99 offset1:107
	ds_read2_b32 v[26:27], v11 offset0:132 offset1:140
	ds_read2_b32 v[28:29], v11 offset0:165 offset1:173
	ds_read2_b32 v[30:31], v11 offset0:198 offset1:206
	ds_read2_b32 v[32:33], v11 offset0:231 offset1:239
	s_waitcnt lgkmcnt(7)
	v_bfe_u32 v16, v8, 16, 1
	s_waitcnt lgkmcnt(6)
	v_bfe_u32 v15, v20, 16, 1
	v_add3_u32 v15, v20, v15, s53
	v_lshrrev_b32_e32 v15, 16, v15
	v_add3_u32 v8, v8, v16, s53
	v_and_or_b32 v16, v8, s77, v15
	s_waitcnt lgkmcnt(5)
	v_bfe_u32 v8, v22, 16, 1
	v_add3_u32 v8, v22, v8, s53
	s_waitcnt lgkmcnt(4)
	v_bfe_u32 v15, v24, 16, 1
	v_lshrrev_b32_e32 v8, 16, v8
	v_add3_u32 v15, v24, v15, s53
	v_and_or_b32 v17, v15, s77, v8
	s_waitcnt lgkmcnt(3)
	v_bfe_u32 v8, v26, 16, 1
	v_add3_u32 v8, v26, v8, s53
	s_waitcnt lgkmcnt(2)
	v_bfe_u32 v15, v28, 16, 1
	v_lshrrev_b32_e32 v8, 16, v8
	v_add3_u32 v15, v28, v15, s53
	v_and_or_b32 v18, v15, s77, v8
	s_waitcnt lgkmcnt(1)
	v_bfe_u32 v8, v30, 16, 1
	s_lshl_b32 s0, s9, 7
	v_add3_u32 v8, v30, v8, s53
	s_waitcnt lgkmcnt(0)
	v_bfe_u32 v15, v32, 16, 1
	s_add_u32 s0, s3, s0
	v_lshrrev_b32_e32 v8, 16, v8
	v_add3_u32 v15, v32, v15, s53
	s_addc_u32 s1, s8, 0
	v_lshlrev_b32_e32 v202, 1, v4
	v_and_or_b32 v19, v15, s77, v8
	v_or_b32_e32 v8, s2, v10
	v_lshl_add_u64 v[6:7], s[0:1], 0, v[202:203]
	v_lshlrev_b32_e32 v202, 12, v8
	v_bfe_u32 v8, v21, 16, 1
	v_add3_u32 v8, v21, v8, s53
	v_bfe_u32 v15, v9, 16, 1
	v_lshl_add_u64 v[34:35], v[6:7], 0, v[202:203]
	v_lshrrev_b32_e32 v8, 16, v8
	v_add3_u32 v9, v9, v15, s53
	global_store_dwordx4 v[34:35], v[16:19], off nt
	v_readlane_b32 s18, v251, 16
	v_readlane_b32 s19, v251, 17
	v_and_or_b32 v16, v9, s77, v8
	v_bfe_u32 v8, v23, 16, 1
	v_add3_u32 v8, v23, v8, s53
	v_bfe_u32 v9, v25, 16, 1
	v_lshrrev_b32_e32 v8, 16, v8
	v_add3_u32 v9, v25, v9, s53
	v_and_or_b32 v17, v9, s77, v8
	v_bfe_u32 v8, v27, 16, 1
	v_add3_u32 v8, v27, v8, s53
	v_bfe_u32 v9, v29, 16, 1
	v_lshrrev_b32_e32 v8, 16, v8
	v_add3_u32 v9, v29, v9, s53
	v_and_or_b32 v18, v9, s77, v8
	v_bfe_u32 v8, v31, 16, 1
	v_add3_u32 v8, v31, v8, s53
	v_bfe_u32 v9, v33, 16, 1
	v_lshrrev_b32_e32 v8, 16, v8
	v_add3_u32 v9, v33, v9, s53
	v_and_or_b32 v19, v9, s77, v8
	v_or_b32_e32 v8, s2, v12
	v_lshlrev_b32_e32 v202, 12, v8
	v_lshl_add_u64 v[8:9], v[6:7], 0, v[202:203]
	global_store_dwordx4 v[8:9], v[16:19], off nt
	ds_read2_b32 v[8:9], v11 offset0:49 offset1:57
	ds_read2_b32 v[20:21], v11 offset0:16 offset1:24
	ds_read2_b32 v[22:23], v11 offset0:82 offset1:90
	ds_read2_b32 v[24:25], v11 offset0:115 offset1:123
	ds_read2_b32 v[26:27], v11 offset0:148 offset1:156
	ds_read2_b32 v[28:29], v11 offset0:181 offset1:189
	ds_read2_b32 v[30:31], v11 offset0:214 offset1:222
	ds_read2_b32 v[32:33], v11 offset0:247 offset1:255
	s_waitcnt lgkmcnt(7)
	v_bfe_u32 v16, v8, 16, 1
	s_waitcnt lgkmcnt(6)
	v_bfe_u32 v15, v20, 16, 1
	v_add3_u32 v15, v20, v15, s53
	v_lshrrev_b32_e32 v15, 16, v15
	v_add3_u32 v8, v8, v16, s53
	v_and_or_b32 v16, v8, s77, v15
	s_waitcnt lgkmcnt(5)
	v_bfe_u32 v8, v22, 16, 1
	v_add3_u32 v8, v22, v8, s53
	s_waitcnt lgkmcnt(4)
	v_bfe_u32 v15, v24, 16, 1
	v_lshrrev_b32_e32 v8, 16, v8
	v_add3_u32 v15, v24, v15, s53
	v_and_or_b32 v17, v15, s77, v8
	s_waitcnt lgkmcnt(3)
	v_bfe_u32 v8, v26, 16, 1
	v_add3_u32 v8, v26, v8, s53
	s_waitcnt lgkmcnt(2)
	v_bfe_u32 v15, v28, 16, 1
	v_lshrrev_b32_e32 v8, 16, v8
	v_add3_u32 v15, v28, v15, s53
	v_and_or_b32 v18, v15, s77, v8
	s_waitcnt lgkmcnt(1)
	v_bfe_u32 v8, v30, 16, 1
	v_add3_u32 v8, v30, v8, s53
	s_waitcnt lgkmcnt(0)
	v_bfe_u32 v15, v32, 16, 1
	v_lshrrev_b32_e32 v8, 16, v8
	v_add3_u32 v15, v32, v15, s53
	v_and_or_b32 v19, v15, s77, v8
	v_or_b32_e32 v8, s2, v13
	v_lshlrev_b32_e32 v202, 12, v8
	v_bfe_u32 v8, v21, 16, 1
	v_add3_u32 v8, v21, v8, s53
	v_bfe_u32 v15, v9, 16, 1
	v_lshl_add_u64 v[34:35], v[6:7], 0, v[202:203]
	v_lshrrev_b32_e32 v8, 16, v8
	v_add3_u32 v9, v9, v15, s53
	global_store_dwordx4 v[34:35], v[16:19], off nt
	v_readlane_b32 s20, v251, 18
	v_readlane_b32 s21, v251, 19
	v_and_or_b32 v16, v9, s77, v8
	v_bfe_u32 v8, v23, 16, 1
	v_add3_u32 v8, v23, v8, s53
	v_bfe_u32 v9, v25, 16, 1
	v_lshrrev_b32_e32 v8, 16, v8
	v_add3_u32 v9, v25, v9, s53
	v_and_or_b32 v17, v9, s77, v8
	v_bfe_u32 v8, v27, 16, 1
	v_add3_u32 v8, v27, v8, s53
	v_bfe_u32 v9, v29, 16, 1
	v_lshrrev_b32_e32 v8, 16, v8
	v_add3_u32 v9, v29, v9, s53
	v_and_or_b32 v18, v9, s77, v8
	v_bfe_u32 v8, v31, 16, 1
	v_add3_u32 v8, v31, v8, s53
	v_bfe_u32 v9, v33, 16, 1
	v_lshrrev_b32_e32 v8, 16, v8
	v_add3_u32 v9, v33, v9, s53
	v_and_or_b32 v19, v9, s77, v8
	v_or_b32_e32 v8, s2, v14
	v_lshlrev_b32_e32 v202, 12, v8
	v_lshl_add_u64 v[6:7], v[6:7], 0, v[202:203]
	global_store_dwordx4 v[6:7], v[16:19], off nt
	s_waitcnt lgkmcnt(0)
	v_readlane_b32 s22, v251, 20
	v_readlane_b32 s23, v251, 21
	v_readlane_b32 s24, v251, 22
	v_readlane_b32 s25, v251, 23
	v_readlane_b32 s26, v251, 24
	v_readlane_b32 s27, v251, 25
	v_readlane_b32 s28, v251, 26
	v_readlane_b32 s29, v251, 27
	v_readlane_b32 s30, v251, 28
	v_readlane_b32 s31, v251, 29

.LBB0_1185:
	s_andn2_b64 vcc, exec, s[2:3]
	s_cbranch_vccnz .LBB0_1187
	s_add_i32 s0, s4, 0xffffc000
	s_lshr_b32 s86, s0, 12
	s_lshl_b64 s[0:1], s[86:87], 25
	v_readlane_b32 s16, v251, 30
	v_readlane_b32 s17, v251, 31
	s_add_u32 s9, s16, s0
	s_addc_u32 s10, s17, s1
	s_lshl_b64 s[0:1], s[86:87], 24
	v_readlane_b32 s2, v251, 58
	s_add_u32 s3, s2, s0
	v_readlane_b32 s0, v251, 59
	s_addc_u32 s5, s0, s1
	s_lshl_b32 s0, s4, 5
	s_and_b32 s2, s0, 0x7e0
	s_and_b32 s8, s4, 0xfc0
	s_lshl_b32 s0, s2, 2
	s_add_u32 s0, s9, s0
	v_or_b32_e32 v8, s8, v3
	s_addc_u32 s1, s10, 0
	v_lshlrev_b32_e32 v202, 2, v2
	v_lshl_add_u64 v[6:7], s[0:1], 0, v[202:203]
	v_lshlrev_b32_e32 v202, 13, v8
	v_lshl_add_u64 v[6:7], v[6:7], 0, v[202:203]
	v_add_co_u32_e32 v8, vcc, s88, v6
	s_mov_b32 s0, 0x8000
	s_nop 0
	v_addc_co_u32_e32 v9, vcc, 0, v7, vcc
	global_load_dword v15, v[6:7], off nt
	global_load_dword v16, v[8:9], off nt
	v_add_co_u32_e32 v8, vcc, s0, v6
	s_mov_b32 s0, 0xc000
	s_nop 0
	v_addc_co_u32_e32 v9, vcc, 0, v7, vcc
	global_load_dword v17, v[8:9], off nt
	v_add_co_u32_e32 v8, vcc, s0, v6
	s_mov_b32 s0, 0x10000
	s_nop 0
	v_addc_co_u32_e32 v9, vcc, 0, v7, vcc
	global_load_dword v18, v[8:9], off nt
	v_add_co_u32_e32 v8, vcc, s0, v6
	s_mov_b32 s0, 0x14000
	s_nop 0
	v_addc_co_u32_e32 v9, vcc, 0, v7, vcc
	global_load_dword v19, v[8:9], off nt
	v_add_co_u32_e32 v8, vcc, s0, v6
	s_mov_b32 s0, 0x18000
	s_nop 0
	v_addc_co_u32_e32 v9, vcc, 0, v7, vcc
	global_load_dword v20, v[8:9], off nt
	v_add_co_u32_e32 v8, vcc, s0, v6
	s_mov_b32 s0, 0x1c000
	s_nop 0
	v_addc_co_u32_e32 v9, vcc, 0, v7, vcc
	global_load_dword v21, v[8:9], off nt
	v_add_co_u32_e32 v8, vcc, s0, v6
	s_mov_b32 s0, 0x20000
	s_nop 0
	v_addc_co_u32_e32 v9, vcc, 0, v7, vcc
	global_load_dword v22, v[8:9], off nt
	v_add_co_u32_e32 v8, vcc, s0, v6
	s_mov_b32 s0, 0x24000
	s_nop 0
	v_addc_co_u32_e32 v9, vcc, 0, v7, vcc
	global_load_dword v23, v[8:9], off nt
	v_add_co_u32_e32 v8, vcc, s0, v6
	s_mov_b32 s0, 0x28000
	s_nop 0
	v_addc_co_u32_e32 v9, vcc, 0, v7, vcc
	global_load_dword v24, v[8:9], off nt
	v_add_co_u32_e32 v8, vcc, s0, v6
	s_mov_b32 s0, 0x2c000
	s_nop 0
	v_addc_co_u32_e32 v9, vcc, 0, v7, vcc
	global_load_dword v25, v[8:9], off nt
	v_add_co_u32_e32 v8, vcc, s0, v6
	s_mov_b32 s0, 0x30000
	s_nop 0
	v_addc_co_u32_e32 v9, vcc, 0, v7, vcc
	global_load_dword v26, v[8:9], off nt
	v_add_co_u32_e32 v8, vcc, s0, v6
	s_mov_b32 s0, 0x34000
	s_nop 0
	v_addc_co_u32_e32 v9, vcc, 0, v7, vcc
	global_load_dword v27, v[8:9], off nt
	v_add_co_u32_e32 v8, vcc, s0, v6
	s_mov_b32 s0, 0x38000
	s_nop 0
	v_addc_co_u32_e32 v9, vcc, 0, v7, vcc
	global_load_dword v28, v[8:9], off nt
	v_add_co_u32_e32 v8, vcc, s0, v6
	s_mov_b32 s0, 0x3c000
	s_nop 0
	v_addc_co_u32_e32 v9, vcc, 0, v7, vcc
	global_load_dword v29, v[8:9], off nt
	v_add_co_u32_e32 v8, vcc, s0, v6
	s_mov_b32 s0, 0x40000
	s_nop 0
	v_addc_co_u32_e32 v9, vcc, 0, v7, vcc
	global_load_dword v30, v[8:9], off nt
	v_add_co_u32_e32 v8, vcc, s0, v6
	s_mov_b32 s0, 0x44000
	s_nop 0
	v_addc_co_u32_e32 v9, vcc, 0, v7, vcc
	global_load_dword v31, v[8:9], off nt
	v_add_co_u32_e32 v8, vcc, s0, v6
	s_mov_b32 s0, 0x48000
	s_nop 0
	v_addc_co_u32_e32 v9, vcc, 0, v7, vcc
	global_load_dword v32, v[8:9], off nt
	v_add_co_u32_e32 v8, vcc, s0, v6
	s_mov_b32 s0, 0x4c000
	s_nop 0
	v_addc_co_u32_e32 v9, vcc, 0, v7, vcc
	global_load_dword v33, v[8:9], off nt
	v_add_co_u32_e32 v8, vcc, s0, v6
	s_mov_b32 s0, 0x50000
	s_nop 0
	v_addc_co_u32_e32 v9, vcc, 0, v7, vcc
	global_load_dword v34, v[8:9], off nt
	v_add_co_u32_e32 v8, vcc, s0, v6
	s_mov_b32 s0, 0x54000
	s_nop 0
	v_addc_co_u32_e32 v9, vcc, 0, v7, vcc
	global_load_dword v35, v[8:9], off nt
	v_add_co_u32_e32 v8, vcc, s0, v6
	s_mov_b32 s0, 0x58000
	s_nop 0
	v_addc_co_u32_e32 v9, vcc, 0, v7, vcc
	global_load_dword v36, v[8:9], off nt
	v_add_co_u32_e32 v8, vcc, s0, v6
	s_mov_b32 s0, 0x5c000
	s_nop 0
	v_addc_co_u32_e32 v9, vcc, 0, v7, vcc
	global_load_dword v37, v[8:9], off nt
	v_add_co_u32_e32 v8, vcc, s0, v6
	s_mov_b32 s0, 0x60000
	s_nop 0
	v_addc_co_u32_e32 v9, vcc, 0, v7, vcc
	global_load_dword v38, v[8:9], off nt
	v_add_co_u32_e32 v8, vcc, s0, v6
	s_mov_b32 s0, 0x64000
	s_nop 0
	v_addc_co_u32_e32 v9, vcc, 0, v7, vcc
	global_load_dword v39, v[8:9], off nt
	v_add_co_u32_e32 v8, vcc, s0, v6
	s_mov_b32 s0, 0x68000
	s_nop 0
	v_addc_co_u32_e32 v9, vcc, 0, v7, vcc
	global_load_dword v40, v[8:9], off nt
	v_add_co_u32_e32 v8, vcc, s0, v6
	s_mov_b32 s0, 0x6c000
	s_nop 0
	v_addc_co_u32_e32 v9, vcc, 0, v7, vcc
	global_load_dword v41, v[8:9], off nt
	v_add_co_u32_e32 v8, vcc, s0, v6
	s_mov_b32 s0, 0x70000
	s_nop 0
	v_addc_co_u32_e32 v9, vcc, 0, v7, vcc
	global_load_dword v42, v[8:9], off nt
	v_add_co_u32_e32 v8, vcc, s0, v6
	s_mov_b32 s0, 0x74000
	s_nop 0
	v_addc_co_u32_e32 v9, vcc, 0, v7, vcc
	global_load_dword v43, v[8:9], off nt
	v_add_co_u32_e32 v8, vcc, s0, v6
	s_mov_b32 s0, 0x78000
	s_nop 0
	v_addc_co_u32_e32 v9, vcc, 0, v7, vcc
	global_load_dword v44, v[8:9], off nt
	v_add_co_u32_e32 v8, vcc, s0, v6
	s_mov_b32 s0, 0x7c000
	s_nop 0
	v_addc_co_u32_e32 v9, vcc, 0, v7, vcc
	v_add_co_u32_e32 v6, vcc, s0, v6
	global_load_dword v8, v[8:9], off nt
	s_nop 0
	v_addc_co_u32_e32 v7, vcc, 0, v7, vcc
	global_load_dword v6, v[6:7], off nt
	v_add_u32_e32 v7, 0x400, v5
	s_waitcnt vmcnt(0)
	ds_write2_b32 v5, v15, v16 offset1:66
	ds_write2_b32 v5, v17, v18 offset0:132 offset1:198
	ds_write2_b32 v7, v19, v20 offset0:8 offset1:74
	ds_write2_b32 v7, v21, v22 offset0:140 offset1:206
	v_add_u32_e32 v7, 0x800, v5
	ds_write2_b32 v7, v23, v24 offset0:16 offset1:82
	ds_write2_b32 v7, v25, v26 offset0:148 offset1:214
	v_add_u32_e32 v7, 0xc00, v5
	ds_write2_b32 v7, v27, v28 offset0:24 offset1:90
	ds_write2_b32 v7, v29, v30 offset0:156 offset1:222
	v_add_u32_e32 v7, 0x1000, v5
	ds_write2_b32 v7, v31, v32 offset0:32 offset1:98
	ds_write2_b32 v7, v33, v34 offset0:164 offset1:230
	v_add_u32_e32 v7, 0x1400, v5
	ds_write2_b32 v7, v35, v36 offset0:40 offset1:106
	ds_write2_b32 v7, v37, v38 offset0:172 offset1:238
	v_add_u32_e32 v7, 0x1800, v5
	ds_write2_b32 v7, v39, v40 offset0:48 offset1:114
	ds_write2_b32 v7, v41, v42 offset0:180 offset1:246
	v_add_u32_e32 v7, 0x1c00, v5
	ds_write2_b32 v7, v43, v44 offset0:56 offset1:122
	ds_write2_b32 v7, v8, v6 offset0:188 offset1:254
	s_waitcnt lgkmcnt(0)
	ds_read2_b32 v[8:9], v11 offset0:33 offset1:41
	ds_read2_b32 v[20:21], v11 offset1:8
	ds_read2_b32 v[22:23], v11 offset0:66 offset1:74
	ds_read2_b32 v[24:25], v11 offset0:99 offset1:107
	ds_read2_b32 v[26:27], v11 offset0:132 offset1:140
	ds_read2_b32 v[28:29], v11 offset0:165 offset1:173
	ds_read2_b32 v[30:31], v11 offset0:198 offset1:206
	ds_read2_b32 v[32:33], v11 offset0:231 offset1:239
	s_waitcnt lgkmcnt(7)
	v_bfe_u32 v16, v8, 16, 1
	s_waitcnt lgkmcnt(6)
	v_bfe_u32 v15, v20, 16, 1
	v_add3_u32 v15, v20, v15, s53
	v_lshrrev_b32_e32 v15, 16, v15
	v_add3_u32 v8, v8, v16, s53
	v_and_or_b32 v16, v8, s77, v15
	s_waitcnt lgkmcnt(5)
	v_bfe_u32 v8, v22, 16, 1
	v_add3_u32 v8, v22, v8, s53
	s_waitcnt lgkmcnt(4)
	v_bfe_u32 v15, v24, 16, 1
	v_lshrrev_b32_e32 v8, 16, v8
	v_add3_u32 v15, v24, v15, s53
	v_and_or_b32 v17, v15, s77, v8
	s_waitcnt lgkmcnt(3)
	v_bfe_u32 v8, v26, 16, 1
	v_add3_u32 v8, v26, v8, s53
	s_waitcnt lgkmcnt(2)
	v_bfe_u32 v15, v28, 16, 1
	v_lshrrev_b32_e32 v8, 16, v8
	v_add3_u32 v15, v28, v15, s53
	v_and_or_b32 v18, v15, s77, v8
	s_waitcnt lgkmcnt(1)
	v_bfe_u32 v8, v30, 16, 1
	s_lshl_b32 s0, s8, 1
	v_add3_u32 v8, v30, v8, s53
	s_waitcnt lgkmcnt(0)
	v_bfe_u32 v15, v32, 16, 1
	s_add_u32 s0, s3, s0
	v_lshrrev_b32_e32 v8, 16, v8
	v_add3_u32 v15, v32, v15, s53
	s_addc_u32 s1, s5, 0
	v_lshlrev_b32_e32 v202, 1, v4
	v_and_or_b32 v19, v15, s77, v8
	v_or_b32_e32 v8, s2, v10
	v_lshl_add_u64 v[6:7], s[0:1], 0, v[202:203]
	v_lshlrev_b32_e32 v202, 13, v8
	v_bfe_u32 v8, v21, 16, 1
	v_add3_u32 v8, v21, v8, s53
	v_bfe_u32 v15, v9, 16, 1
	v_lshl_add_u64 v[34:35], v[6:7], 0, v[202:203]
	v_lshrrev_b32_e32 v8, 16, v8
	v_add3_u32 v9, v9, v15, s53
	global_store_dwordx4 v[34:35], v[16:19], off nt
	v_readlane_b32 s18, v251, 32
	v_readlane_b32 s19, v251, 33
	v_and_or_b32 v16, v9, s77, v8
	v_bfe_u32 v8, v23, 16, 1
	v_add3_u32 v8, v23, v8, s53
	v_bfe_u32 v9, v25, 16, 1
	v_lshrrev_b32_e32 v8, 16, v8
	v_add3_u32 v9, v25, v9, s53
	v_and_or_b32 v17, v9, s77, v8
	v_bfe_u32 v8, v27, 16, 1
	v_add3_u32 v8, v27, v8, s53
	v_bfe_u32 v9, v29, 16, 1
	v_lshrrev_b32_e32 v8, 16, v8
	v_add3_u32 v9, v29, v9, s53
	v_and_or_b32 v18, v9, s77, v8
	v_bfe_u32 v8, v31, 16, 1
	v_add3_u32 v8, v31, v8, s53
	v_bfe_u32 v9, v33, 16, 1
	v_lshrrev_b32_e32 v8, 16, v8
	v_add3_u32 v9, v33, v9, s53
	v_and_or_b32 v19, v9, s77, v8
	v_or_b32_e32 v8, s2, v12
	v_lshlrev_b32_e32 v202, 13, v8
	v_lshl_add_u64 v[8:9], v[6:7], 0, v[202:203]
	global_store_dwordx4 v[8:9], v[16:19], off nt
	ds_read2_b32 v[8:9], v11 offset0:49 offset1:57
	ds_read2_b32 v[20:21], v11 offset0:16 offset1:24
	ds_read2_b32 v[22:23], v11 offset0:82 offset1:90
	ds_read2_b32 v[24:25], v11 offset0:115 offset1:123
	ds_read2_b32 v[26:27], v11 offset0:148 offset1:156
	ds_read2_b32 v[28:29], v11 offset0:181 offset1:189
	ds_read2_b32 v[30:31], v11 offset0:214 offset1:222
	ds_read2_b32 v[32:33], v11 offset0:247 offset1:255
	s_waitcnt lgkmcnt(7)
	v_bfe_u32 v16, v8, 16, 1
	s_waitcnt lgkmcnt(6)
	v_bfe_u32 v15, v20, 16, 1
	v_add3_u32 v15, v20, v15, s53
	v_lshrrev_b32_e32 v15, 16, v15
	v_add3_u32 v8, v8, v16, s53
	v_and_or_b32 v16, v8, s77, v15
	s_waitcnt lgkmcnt(5)
	v_bfe_u32 v8, v22, 16, 1
	v_add3_u32 v8, v22, v8, s53
	s_waitcnt lgkmcnt(4)
	v_bfe_u32 v15, v24, 16, 1
	v_lshrrev_b32_e32 v8, 16, v8
	v_add3_u32 v15, v24, v15, s53
	v_and_or_b32 v17, v15, s77, v8
	s_waitcnt lgkmcnt(3)
	v_bfe_u32 v8, v26, 16, 1
	v_add3_u32 v8, v26, v8, s53
	s_waitcnt lgkmcnt(2)
	v_bfe_u32 v15, v28, 16, 1
	v_lshrrev_b32_e32 v8, 16, v8
	v_add3_u32 v15, v28, v15, s53
	v_and_or_b32 v18, v15, s77, v8
	s_waitcnt lgkmcnt(1)
	v_bfe_u32 v8, v30, 16, 1
	v_add3_u32 v8, v30, v8, s53
	s_waitcnt lgkmcnt(0)
	v_bfe_u32 v15, v32, 16, 1
	v_lshrrev_b32_e32 v8, 16, v8
	v_add3_u32 v15, v32, v15, s53
	v_and_or_b32 v19, v15, s77, v8
	v_or_b32_e32 v8, s2, v13
	v_lshlrev_b32_e32 v202, 13, v8
	v_bfe_u32 v8, v21, 16, 1
	v_add3_u32 v8, v21, v8, s53
	v_bfe_u32 v15, v9, 16, 1
	v_lshl_add_u64 v[34:35], v[6:7], 0, v[202:203]
	v_lshrrev_b32_e32 v8, 16, v8
	v_add3_u32 v9, v9, v15, s53
	global_store_dwordx4 v[34:35], v[16:19], off nt
	v_readlane_b32 s20, v251, 34
	v_readlane_b32 s21, v251, 35
	v_and_or_b32 v16, v9, s77, v8
	v_bfe_u32 v8, v23, 16, 1
	v_add3_u32 v8, v23, v8, s53
	v_bfe_u32 v9, v25, 16, 1
	v_lshrrev_b32_e32 v8, 16, v8
	v_add3_u32 v9, v25, v9, s53
	v_and_or_b32 v17, v9, s77, v8
	v_bfe_u32 v8, v27, 16, 1
	v_add3_u32 v8, v27, v8, s53
	v_bfe_u32 v9, v29, 16, 1
	v_lshrrev_b32_e32 v8, 16, v8
	v_add3_u32 v9, v29, v9, s53
	v_and_or_b32 v18, v9, s77, v8
	v_bfe_u32 v8, v31, 16, 1
	v_add3_u32 v8, v31, v8, s53
	v_bfe_u32 v9, v33, 16, 1
	v_lshrrev_b32_e32 v8, 16, v8
	v_add3_u32 v9, v33, v9, s53
	v_and_or_b32 v19, v9, s77, v8
	v_or_b32_e32 v8, s2, v14
	v_lshlrev_b32_e32 v202, 13, v8
	v_lshl_add_u64 v[6:7], v[6:7], 0, v[202:203]
	global_store_dwordx4 v[6:7], v[16:19], off nt
	s_waitcnt lgkmcnt(0)
	v_readlane_b32 s22, v251, 36
	v_readlane_b32 s23, v251, 37
	v_readlane_b32 s24, v251, 38
	v_readlane_b32 s25, v251, 39
	v_readlane_b32 s26, v251, 40
	v_readlane_b32 s27, v251, 41
	v_readlane_b32 s28, v251, 42
	v_readlane_b32 s29, v251, 43
	v_readlane_b32 s30, v251, 44
	v_readlane_b32 s31, v251, 45

.LBB0_1189:
	s_ashr_i32 s0, s4, 31
	s_lshr_b32 s0, s0, 19
	s_add_i32 s1, s4, s0
	s_ashr_i32 s0, s1, 13
	s_and_b32 s1, s1, 0xe000
	s_sub_i32 s4, s4, s1
	s_ashr_i32 s1, s0, 31
	v_readlane_b32 s16, v251, 14
	s_lshl_b64 s[2:3], s[0:1], 26
	v_readlane_b32 s22, v251, 20
	v_readlane_b32 s23, v251, 21
	s_add_u32 s5, s22, s2
	s_addc_u32 s10, s23, s3
	s_lshl_b64 s[0:1], s[0:1], 25
	v_readlane_b32 s2, v251, 60
	s_add_u32 s8, s2, s0
	v_readlane_b32 s0, v251, 61
	s_addc_u32 s9, s0, s1
	s_sext_i32_i16 s0, s4
	s_bfe_u32 s0, s0, 0x80017
	s_add_i32 s0, s4, s0
	s_sext_i32_i16 s1, s0
	s_and_b32 s0, s0, 0xff00
	s_sub_i32 s0, s4, s0
	s_sext_i32_i16 s0, s0
	s_lshl_b32 s2, s0, 5
	s_ashr_i32 s1, s1, 8
	s_ashr_i32 s3, s2, 31
	s_lshl_b32 s4, s1, 6
	s_lshl_b64 s[0:1], s[2:3], 2
	v_or_b32_e32 v6, s4, v3
	s_add_u32 s0, s5, s0
	s_addc_u32 s1, s10, s1
	v_lshlrev_b32_e32 v202, 2, v2
	v_ashrrev_i32_e32 v7, 31, v6
	v_lshl_add_u64 v[8:9], s[0:1], 0, v[202:203]
	v_lshlrev_b64 v[16:17], 15, v[6:7]
	v_lshl_add_u64 v[16:17], v[8:9], 0, v[16:17]
	global_load_dword v15, v[16:17], off nt
	v_or_b32_e32 v16, 2, v6
	v_ashrrev_i32_e32 v17, 31, v16
	v_lshlrev_b64 v[16:17], 15, v[16:17]
	v_lshl_add_u64 v[16:17], v[8:9], 0, v[16:17]
	global_load_dword v18, v[16:17], off nt
	v_or_b32_e32 v16, 4, v6
	v_ashrrev_i32_e32 v17, 31, v16
	v_lshlrev_b64 v[16:17], 15, v[16:17]
	v_lshl_add_u64 v[16:17], v[8:9], 0, v[16:17]
	global_load_dword v19, v[16:17], off nt
	v_or_b32_e32 v16, 6, v6
	v_ashrrev_i32_e32 v17, 31, v16
	v_lshlrev_b64 v[16:17], 15, v[16:17]
	v_lshl_add_u64 v[16:17], v[8:9], 0, v[16:17]
	global_load_dword v20, v[16:17], off nt
	v_or_b32_e32 v16, 8, v6
	v_ashrrev_i32_e32 v17, 31, v16
	v_lshlrev_b64 v[16:17], 15, v[16:17]
	v_lshl_add_u64 v[16:17], v[8:9], 0, v[16:17]
	global_load_dword v21, v[16:17], off nt
	v_or_b32_e32 v16, 10, v6
	v_ashrrev_i32_e32 v17, 31, v16
	v_lshlrev_b64 v[16:17], 15, v[16:17]
	v_lshl_add_u64 v[16:17], v[8:9], 0, v[16:17]
	global_load_dword v22, v[16:17], off nt
	v_or_b32_e32 v16, 12, v6
	v_ashrrev_i32_e32 v17, 31, v16
	v_lshlrev_b64 v[16:17], 15, v[16:17]
	v_lshl_add_u64 v[16:17], v[8:9], 0, v[16:17]
	global_load_dword v23, v[16:17], off nt
	v_or_b32_e32 v16, 14, v6
	v_ashrrev_i32_e32 v17, 31, v16
	v_lshlrev_b64 v[16:17], 15, v[16:17]
	v_lshl_add_u64 v[16:17], v[8:9], 0, v[16:17]
	global_load_dword v24, v[16:17], off nt
	v_or_b32_e32 v16, 16, v6
	v_ashrrev_i32_e32 v17, 31, v16
	v_lshlrev_b64 v[16:17], 15, v[16:17]
	v_lshl_add_u64 v[16:17], v[8:9], 0, v[16:17]
	global_load_dword v25, v[16:17], off nt
	v_or_b32_e32 v16, 18, v6
	v_ashrrev_i32_e32 v17, 31, v16
	v_lshlrev_b64 v[16:17], 15, v[16:17]
	v_lshl_add_u64 v[16:17], v[8:9], 0, v[16:17]
	global_load_dword v26, v[16:17], off nt
	v_or_b32_e32 v16, 20, v6
	v_ashrrev_i32_e32 v17, 31, v16
	v_lshlrev_b64 v[16:17], 15, v[16:17]
	v_lshl_add_u64 v[16:17], v[8:9], 0, v[16:17]
	global_load_dword v27, v[16:17], off nt
	v_or_b32_e32 v16, 22, v6
	v_ashrrev_i32_e32 v17, 31, v16
	v_lshlrev_b64 v[16:17], 15, v[16:17]
	v_lshl_add_u64 v[16:17], v[8:9], 0, v[16:17]
	global_load_dword v28, v[16:17], off nt
	v_or_b32_e32 v16, 24, v6
	v_ashrrev_i32_e32 v17, 31, v16
	v_lshlrev_b64 v[16:17], 15, v[16:17]
	v_lshl_add_u64 v[16:17], v[8:9], 0, v[16:17]
	global_load_dword v29, v[16:17], off nt
	v_or_b32_e32 v16, 26, v6
	v_ashrrev_i32_e32 v17, 31, v16
	v_lshlrev_b64 v[16:17], 15, v[16:17]
	v_lshl_add_u64 v[16:17], v[8:9], 0, v[16:17]
	global_load_dword v30, v[16:17], off nt
	v_or_b32_e32 v16, 28, v6
	v_ashrrev_i32_e32 v17, 31, v16
	v_lshlrev_b64 v[16:17], 15, v[16:17]
	v_lshl_add_u64 v[16:17], v[8:9], 0, v[16:17]
	global_load_dword v31, v[16:17], off nt
	v_or_b32_e32 v16, 30, v6
	v_ashrrev_i32_e32 v17, 31, v16
	v_lshlrev_b64 v[16:17], 15, v[16:17]
	v_lshl_add_u64 v[16:17], v[8:9], 0, v[16:17]
	global_load_dword v32, v[16:17], off nt
	v_or_b32_e32 v16, 32, v6
	v_ashrrev_i32_e32 v17, 31, v16
	v_lshlrev_b64 v[16:17], 15, v[16:17]
	v_lshl_add_u64 v[16:17], v[8:9], 0, v[16:17]
	global_load_dword v33, v[16:17], off nt
	v_or_b32_e32 v16, 34, v6
	v_ashrrev_i32_e32 v17, 31, v16
	v_lshlrev_b64 v[16:17], 15, v[16:17]
	v_lshl_add_u64 v[16:17], v[8:9], 0, v[16:17]
	global_load_dword v34, v[16:17], off nt
	v_or_b32_e32 v16, 36, v6
	v_ashrrev_i32_e32 v17, 31, v16
	v_lshlrev_b64 v[16:17], 15, v[16:17]
	v_lshl_add_u64 v[16:17], v[8:9], 0, v[16:17]
	global_load_dword v35, v[16:17], off nt
	v_or_b32_e32 v16, 38, v6
	v_ashrrev_i32_e32 v17, 31, v16
	v_lshlrev_b64 v[16:17], 15, v[16:17]
	v_lshl_add_u64 v[16:17], v[8:9], 0, v[16:17]
	global_load_dword v36, v[16:17], off nt
	v_or_b32_e32 v16, 40, v6
	v_ashrrev_i32_e32 v17, 31, v16
	v_lshlrev_b64 v[16:17], 15, v[16:17]
	v_lshl_add_u64 v[16:17], v[8:9], 0, v[16:17]
	global_load_dword v37, v[16:17], off nt
	v_or_b32_e32 v16, 42, v6
	v_ashrrev_i32_e32 v17, 31, v16
	v_lshlrev_b64 v[16:17], 15, v[16:17]
	v_lshl_add_u64 v[16:17], v[8:9], 0, v[16:17]
	global_load_dword v38, v[16:17], off nt
	v_or_b32_e32 v16, 44, v6
	v_ashrrev_i32_e32 v17, 31, v16
	v_lshlrev_b64 v[16:17], 15, v[16:17]
	v_lshl_add_u64 v[16:17], v[8:9], 0, v[16:17]
	global_load_dword v39, v[16:17], off nt
	v_or_b32_e32 v16, 46, v6
	v_ashrrev_i32_e32 v17, 31, v16
	v_lshlrev_b64 v[16:17], 15, v[16:17]
	v_lshl_add_u64 v[16:17], v[8:9], 0, v[16:17]
	global_load_dword v40, v[16:17], off nt
	v_or_b32_e32 v16, 48, v6
	v_ashrrev_i32_e32 v17, 31, v16
	v_lshlrev_b64 v[16:17], 15, v[16:17]
	v_lshl_add_u64 v[16:17], v[8:9], 0, v[16:17]
	global_load_dword v41, v[16:17], off nt
	v_or_b32_e32 v16, 50, v6
	v_ashrrev_i32_e32 v17, 31, v16
	v_lshlrev_b64 v[16:17], 15, v[16:17]
	v_lshl_add_u64 v[16:17], v[8:9], 0, v[16:17]
	global_load_dword v42, v[16:17], off nt
	v_or_b32_e32 v16, 52, v6
	v_ashrrev_i32_e32 v17, 31, v16
	v_lshlrev_b64 v[16:17], 15, v[16:17]
	v_lshl_add_u64 v[16:17], v[8:9], 0, v[16:17]
	global_load_dword v43, v[16:17], off nt
	v_or_b32_e32 v16, 54, v6
	v_ashrrev_i32_e32 v17, 31, v16
	v_lshlrev_b64 v[16:17], 15, v[16:17]
	v_lshl_add_u64 v[16:17], v[8:9], 0, v[16:17]
	global_load_dword v44, v[16:17], off nt
	v_or_b32_e32 v16, 56, v6
	v_ashrrev_i32_e32 v17, 31, v16
	v_lshlrev_b64 v[16:17], 15, v[16:17]
	v_lshl_add_u64 v[16:17], v[8:9], 0, v[16:17]
	global_load_dword v45, v[16:17], off nt
	v_or_b32_e32 v16, 58, v6
	v_ashrrev_i32_e32 v17, 31, v16
	v_lshlrev_b64 v[16:17], 15, v[16:17]
	v_lshl_add_u64 v[16:17], v[8:9], 0, v[16:17]
	global_load_dword v46, v[16:17], off nt
	v_or_b32_e32 v16, 60, v6
	v_or_b32_e32 v6, 62, v6
	v_ashrrev_i32_e32 v17, 31, v16
	v_ashrrev_i32_e32 v7, 31, v6
	v_lshlrev_b64 v[16:17], 15, v[16:17]
	v_lshlrev_b64 v[6:7], 15, v[6:7]
	v_lshl_add_u64 v[16:17], v[8:9], 0, v[16:17]
	v_lshl_add_u64 v[6:7], v[8:9], 0, v[6:7]
	global_load_dword v16, v[16:17], off nt
	s_ashr_i32 s5, s4, 31
	global_load_dword v6, v[6:7], off nt
	v_add_u32_e32 v7, 0x400, v5
	s_waitcnt vmcnt(0)
	ds_write2_b32 v5, v15, v18 offset1:66
	ds_write2_b32 v5, v19, v20 offset0:132 offset1:198
	ds_write2_b32 v7, v21, v22 offset0:8 offset1:74
	ds_write2_b32 v7, v23, v24 offset0:140 offset1:206
	v_add_u32_e32 v7, 0x800, v5
	ds_write2_b32 v7, v25, v26 offset0:16 offset1:82
	ds_write2_b32 v7, v27, v28 offset0:148 offset1:214
	v_add_u32_e32 v7, 0xc00, v5
	ds_write2_b32 v7, v29, v30 offset0:24 offset1:90
	ds_write2_b32 v7, v31, v32 offset0:156 offset1:222
	v_add_u32_e32 v7, 0x1000, v5
	ds_write2_b32 v7, v33, v34 offset0:32 offset1:98
	ds_write2_b32 v7, v35, v36 offset0:164 offset1:230
	v_add_u32_e32 v7, 0x1400, v5
	ds_write2_b32 v7, v37, v38 offset0:40 offset1:106
	ds_write2_b32 v7, v39, v40 offset0:172 offset1:238
	v_add_u32_e32 v7, 0x1800, v5
	ds_write2_b32 v7, v41, v42 offset0:48 offset1:114
	ds_write2_b32 v7, v43, v44 offset0:180 offset1:246
	v_add_u32_e32 v7, 0x1c00, v5
	ds_write2_b32 v7, v45, v46 offset0:56 offset1:122
	ds_write2_b32 v7, v16, v6 offset0:188 offset1:254
	s_waitcnt lgkmcnt(0)
	ds_read2_b32 v[8:9], v11 offset0:33 offset1:41
	ds_read2_b32 v[20:21], v11 offset1:8
	ds_read2_b32 v[22:23], v11 offset0:66 offset1:74
	ds_read2_b32 v[24:25], v11 offset0:99 offset1:107
	ds_read2_b32 v[26:27], v11 offset0:132 offset1:140
	ds_read2_b32 v[28:29], v11 offset0:165 offset1:173
	ds_read2_b32 v[30:31], v11 offset0:198 offset1:206
	ds_read2_b32 v[32:33], v11 offset0:231 offset1:239
	s_waitcnt lgkmcnt(7)
	v_bfe_u32 v16, v8, 16, 1
	s_waitcnt lgkmcnt(6)
	v_bfe_u32 v15, v20, 16, 1
	v_add3_u32 v15, v20, v15, s53
	v_lshrrev_b32_e32 v15, 16, v15
	v_add3_u32 v8, v8, v16, s53
	v_and_or_b32 v16, v8, s77, v15
	s_waitcnt lgkmcnt(5)
	v_bfe_u32 v8, v22, 16, 1
	v_add3_u32 v8, v22, v8, s53
	s_waitcnt lgkmcnt(4)
	v_bfe_u32 v15, v24, 16, 1
	v_lshrrev_b32_e32 v8, 16, v8
	v_add3_u32 v15, v24, v15, s53
	v_and_or_b32 v17, v15, s77, v8
	s_waitcnt lgkmcnt(3)
	v_bfe_u32 v8, v26, 16, 1
	v_add3_u32 v8, v26, v8, s53
	s_waitcnt lgkmcnt(2)
	v_bfe_u32 v15, v28, 16, 1
	v_lshrrev_b32_e32 v8, 16, v8
	v_add3_u32 v15, v28, v15, s53
	v_and_or_b32 v18, v15, s77, v8
	s_waitcnt lgkmcnt(1)
	v_bfe_u32 v8, v30, 16, 1
	s_lshl_b64 s[0:1], s[4:5], 1
	v_add3_u32 v8, v30, v8, s53
	s_waitcnt lgkmcnt(0)
	v_bfe_u32 v15, v32, 16, 1
	s_add_u32 s0, s8, s0
	v_lshrrev_b32_e32 v8, 16, v8
	v_add3_u32 v15, v32, v15, s53
	v_or_b32_e32 v34, s2, v10
	s_addc_u32 s1, s9, s1
	v_lshlrev_b32_e32 v202, 1, v4
	v_and_or_b32 v19, v15, s77, v8
	v_ashrrev_i32_e32 v35, 31, v34
	v_bfe_u32 v8, v21, 16, 1
	v_lshl_add_u64 v[6:7], s[0:1], 0, v[202:203]
	v_lshlrev_b64 v[34:35], 12, v[34:35]
	v_add3_u32 v8, v21, v8, s53
	v_bfe_u32 v15, v9, 16, 1
	v_lshl_add_u64 v[34:35], v[6:7], 0, v[34:35]
	v_lshrrev_b32_e32 v8, 16, v8
	v_add3_u32 v9, v9, v15, s53
	global_store_dwordx4 v[34:35], v[16:19], off nt
	v_or_b32_e32 v34, s2, v13
	v_ashrrev_i32_e32 v35, 31, v34
	v_and_or_b32 v16, v9, s77, v8
	v_bfe_u32 v8, v23, 16, 1
	v_add3_u32 v8, v23, v8, s53
	v_bfe_u32 v9, v25, 16, 1
	v_lshrrev_b32_e32 v8, 16, v8
	v_add3_u32 v9, v25, v9, s53
	v_and_or_b32 v17, v9, s77, v8
	v_bfe_u32 v8, v27, 16, 1
	v_add3_u32 v8, v27, v8, s53
	v_bfe_u32 v9, v29, 16, 1
	v_lshrrev_b32_e32 v8, 16, v8
	v_add3_u32 v9, v29, v9, s53
	v_and_or_b32 v18, v9, s77, v8
	v_bfe_u32 v8, v31, 16, 1
	v_add3_u32 v8, v31, v8, s53
	v_bfe_u32 v9, v33, 16, 1
	v_lshrrev_b32_e32 v8, 16, v8
	v_add3_u32 v9, v33, v9, s53
	v_and_or_b32 v19, v9, s77, v8
	v_or_b32_e32 v8, s2, v12
	v_ashrrev_i32_e32 v9, 31, v8
	v_lshlrev_b64 v[8:9], 12, v[8:9]
	v_lshl_add_u64 v[8:9], v[6:7], 0, v[8:9]
	global_store_dwordx4 v[8:9], v[16:19], off nt
	ds_read2_b32 v[8:9], v11 offset0:49 offset1:57
	ds_read2_b32 v[20:21], v11 offset0:16 offset1:24
	ds_read2_b32 v[22:23], v11 offset0:82 offset1:90
	ds_read2_b32 v[24:25], v11 offset0:115 offset1:123
	ds_read2_b32 v[26:27], v11 offset0:148 offset1:156
	ds_read2_b32 v[28:29], v11 offset0:181 offset1:189
	ds_read2_b32 v[30:31], v11 offset0:214 offset1:222
	ds_read2_b32 v[32:33], v11 offset0:247 offset1:255
	s_waitcnt lgkmcnt(7)
	v_bfe_u32 v16, v8, 16, 1
	s_waitcnt lgkmcnt(6)
	v_bfe_u32 v15, v20, 16, 1
	v_add3_u32 v15, v20, v15, s53
	v_lshrrev_b32_e32 v15, 16, v15
	v_add3_u32 v8, v8, v16, s53
	v_and_or_b32 v16, v8, s77, v15
	s_waitcnt lgkmcnt(5)
	v_bfe_u32 v8, v22, 16, 1
	v_add3_u32 v8, v22, v8, s53
	s_waitcnt lgkmcnt(4)
	v_bfe_u32 v15, v24, 16, 1
	v_lshrrev_b32_e32 v8, 16, v8
	v_add3_u32 v15, v24, v15, s53
	v_and_or_b32 v17, v15, s77, v8
	s_waitcnt lgkmcnt(3)
	v_bfe_u32 v8, v26, 16, 1
	v_add3_u32 v8, v26, v8, s53
	s_waitcnt lgkmcnt(2)
	v_bfe_u32 v15, v28, 16, 1
	v_lshrrev_b32_e32 v8, 16, v8
	v_add3_u32 v15, v28, v15, s53
	v_and_or_b32 v18, v15, s77, v8
	s_waitcnt lgkmcnt(1)
	v_bfe_u32 v8, v30, 16, 1
	v_add3_u32 v8, v30, v8, s53
	s_waitcnt lgkmcnt(0)
	v_bfe_u32 v15, v32, 16, 1
	v_lshrrev_b32_e32 v8, 16, v8
	v_add3_u32 v15, v32, v15, s53
	v_and_or_b32 v19, v15, s77, v8
	v_bfe_u32 v8, v21, 16, 1
	v_lshlrev_b64 v[34:35], 12, v[34:35]
	v_add3_u32 v8, v21, v8, s53
	v_bfe_u32 v15, v9, 16, 1
	v_lshl_add_u64 v[34:35], v[6:7], 0, v[34:35]
	v_lshrrev_b32_e32 v8, 16, v8
	v_add3_u32 v9, v9, v15, s53
	global_store_dwordx4 v[34:35], v[16:19], off nt
	v_readlane_b32 s17, v251, 15
	v_readlane_b32 s18, v251, 16
	v_and_or_b32 v16, v9, s77, v8
	v_bfe_u32 v8, v23, 16, 1
	v_add3_u32 v8, v23, v8, s53
	v_bfe_u32 v9, v25, 16, 1
	v_lshrrev_b32_e32 v8, 16, v8
	v_add3_u32 v9, v25, v9, s53
	v_and_or_b32 v17, v9, s77, v8
	v_bfe_u32 v8, v27, 16, 1
	v_add3_u32 v8, v27, v8, s53
	v_bfe_u32 v9, v29, 16, 1
	v_lshrrev_b32_e32 v8, 16, v8
	v_add3_u32 v9, v29, v9, s53
	v_and_or_b32 v18, v9, s77, v8
	v_bfe_u32 v8, v31, 16, 1
	v_add3_u32 v8, v31, v8, s53
	v_bfe_u32 v9, v33, 16, 1
	v_lshrrev_b32_e32 v8, 16, v8
	v_add3_u32 v9, v33, v9, s53
	v_and_or_b32 v19, v9, s77, v8
	v_or_b32_e32 v8, s2, v14
	v_ashrrev_i32_e32 v9, 31, v8
	v_lshlrev_b64 v[8:9], 12, v[8:9]
	v_lshl_add_u64 v[6:7], v[6:7], 0, v[8:9]
	global_store_dwordx4 v[6:7], v[16:19], off nt
	s_waitcnt lgkmcnt(0)
	v_readlane_b32 s19, v251, 17
	v_readlane_b32 s20, v251, 18
	v_readlane_b32 s21, v251, 19
	v_readlane_b32 s24, v251, 22
	v_readlane_b32 s25, v251, 23
	v_readlane_b32 s26, v251, 24
	v_readlane_b32 s27, v251, 25
	v_readlane_b32 s28, v251, 26
	v_readlane_b32 s29, v251, 27
	v_readlane_b32 s30, v251, 28
	v_readlane_b32 s31, v251, 29
	s_branch .LBB0_1125

.LBB0_1461:
	s_cmpk_gt_i32 s4, 0x3fff
	s_mov_b64 s[2:3], -1
	s_cbranch_scc0 .LBB0_1482
	s_cmpk_gt_u32 s4, 0x5fff
	s_cbranch_scc0 .LBB0_1479
	s_cmp_gt_u32 s4, 0x167ff
	s_cbranch_scc0 .LBB0_1469
	s_cmp_gt_u32 s4, 0x177ff
	s_cbranch_scc0 .LBB0_1466
	s_add_i32 s2, s4, 0xfffe8800
	v_readlane_b32 s16, v251, 6
	s_and_b32 s86, s2, 0xfffff800
	v_readlane_b32 s17, v251, 7
	v_readlane_b32 s18, v251, 8
	v_readlane_b32 s19, v251, 9
	v_readlane_b32 s20, v251, 10
	v_readlane_b32 s21, v251, 11
	s_lshl_b64 s[0:1], s[86:87], 2
	v_readlane_b32 s22, v251, 12
	v_readlane_b32 s23, v251, 13
	s_mov_b64 s[16:17], s[20:21]
	s_add_u32 s0, s16, s0
	s_addc_u32 s1, s17, s1
	s_lshl_b32 s9, s4, 5
	s_lshr_b32 s2, s2, 4
	s_lshl_b32 s10, s4, 6
	s_and_b32 s9, s9, 0x60
	s_and_b32 s2, s2, 0xfffff80
	s_and_b32 s5, s4, 63
	s_and_b32 s10, s10, 0xf00
	s_or_b32 s2, s2, s9
	s_and_b32 s3, s4, 0x7c0
	s_or_b32 s2, s2, s10
	s_lshl_b32 s5, s5, 7
	s_add_u32 s0, s0, s5
	v_or_b32_e32 v10, s3, v3
	s_addc_u32 s1, s1, 0
	v_lshlrev_b32_e32 v202, 2, v2
	v_lshl_add_u64 v[8:9], s[0:1], 0, v[202:203]
	v_lshlrev_b32_e32 v202, 14, v10
	v_lshl_add_u64 v[8:9], v[8:9], 0, v[202:203]
	s_mov_b32 s0, 0x8000
	v_add_co_u32_e32 v10, vcc, s0, v8
	s_mov_b32 s0, 0x10000
	s_nop 0
	v_addc_co_u32_e32 v11, vcc, 0, v9, vcc
	global_load_dword v17, v[8:9], off nt
	global_load_dword v18, v[10:11], off nt
	v_add_co_u32_e32 v10, vcc, s0, v8
	s_mov_b32 s0, 0x18000
	s_nop 0
	v_addc_co_u32_e32 v11, vcc, 0, v9, vcc
	global_load_dword v19, v[10:11], off nt
	v_add_co_u32_e32 v10, vcc, s0, v8
	s_mov_b32 s0, 0x20000
	s_nop 0
	v_addc_co_u32_e32 v11, vcc, 0, v9, vcc
	global_load_dword v20, v[10:11], off nt
	v_add_co_u32_e32 v10, vcc, s0, v8
	s_mov_b32 s0, 0x28000
	s_nop 0
	v_addc_co_u32_e32 v11, vcc, 0, v9, vcc
	global_load_dword v21, v[10:11], off nt
	v_add_co_u32_e32 v10, vcc, s0, v8
	s_mov_b32 s0, 0x30000
	s_nop 0
	v_addc_co_u32_e32 v11, vcc, 0, v9, vcc
	global_load_dword v22, v[10:11], off nt
	v_add_co_u32_e32 v10, vcc, s0, v8
	s_mov_b32 s0, 0x38000
	s_nop 0
	v_addc_co_u32_e32 v11, vcc, 0, v9, vcc
	global_load_dword v23, v[10:11], off nt
	v_add_co_u32_e32 v10, vcc, s0, v8
	s_mov_b32 s0, 0x40000
	s_nop 0
	v_addc_co_u32_e32 v11, vcc, 0, v9, vcc
	global_load_dword v24, v[10:11], off nt
	v_add_co_u32_e32 v10, vcc, s0, v8
	s_mov_b32 s0, 0x48000
	s_nop 0
	v_addc_co_u32_e32 v11, vcc, 0, v9, vcc
	global_load_dword v25, v[10:11], off nt
	v_add_co_u32_e32 v10, vcc, s0, v8
	s_mov_b32 s0, 0x50000
	s_nop 0
	v_addc_co_u32_e32 v11, vcc, 0, v9, vcc
	global_load_dword v26, v[10:11], off nt
	v_add_co_u32_e32 v10, vcc, s0, v8
	s_mov_b32 s0, 0x58000
	s_nop 0
	v_addc_co_u32_e32 v11, vcc, 0, v9, vcc
	global_load_dword v27, v[10:11], off nt
	v_add_co_u32_e32 v10, vcc, s0, v8
	s_mov_b32 s0, 0x60000
	s_nop 0
	v_addc_co_u32_e32 v11, vcc, 0, v9, vcc
	global_load_dword v28, v[10:11], off nt
	v_add_co_u32_e32 v10, vcc, s0, v8
	s_mov_b32 s0, 0x68000
	s_nop 0
	v_addc_co_u32_e32 v11, vcc, 0, v9, vcc
	global_load_dword v29, v[10:11], off nt
	v_add_co_u32_e32 v10, vcc, s0, v8
	s_mov_b32 s0, 0x70000
	s_nop 0
	v_addc_co_u32_e32 v11, vcc, 0, v9, vcc
	global_load_dword v30, v[10:11], off nt
	v_add_co_u32_e32 v10, vcc, s0, v8
	s_mov_b32 s0, 0x78000
	s_nop 0
	v_addc_co_u32_e32 v11, vcc, 0, v9, vcc
	global_load_dword v31, v[10:11], off nt
	v_add_co_u32_e32 v10, vcc, s0, v8
	s_mov_b32 s0, 0x80000
	s_nop 0
	v_addc_co_u32_e32 v11, vcc, 0, v9, vcc
	global_load_dword v32, v[10:11], off nt
	v_add_co_u32_e32 v10, vcc, s0, v8
	s_mov_b32 s0, 0x88000
	s_nop 0
	v_addc_co_u32_e32 v11, vcc, 0, v9, vcc
	global_load_dword v33, v[10:11], off nt
	v_add_co_u32_e32 v10, vcc, s0, v8
	s_mov_b32 s0, 0x90000
	s_nop 0
	v_addc_co_u32_e32 v11, vcc, 0, v9, vcc
	global_load_dword v34, v[10:11], off nt
	v_add_co_u32_e32 v10, vcc, s0, v8
	s_mov_b32 s0, 0x98000
	s_nop 0
	v_addc_co_u32_e32 v11, vcc, 0, v9, vcc
	global_load_dword v35, v[10:11], off nt
	v_add_co_u32_e32 v10, vcc, s0, v8
	s_mov_b32 s0, 0xa0000
	s_nop 0
	v_addc_co_u32_e32 v11, vcc, 0, v9, vcc
	global_load_dword v36, v[10:11], off nt
	v_add_co_u32_e32 v10, vcc, s0, v8
	s_mov_b32 s0, 0xa8000
	s_nop 0
	v_addc_co_u32_e32 v11, vcc, 0, v9, vcc
	global_load_dword v37, v[10:11], off nt
	v_add_co_u32_e32 v10, vcc, s0, v8
	s_mov_b32 s0, 0xb0000
	s_nop 0
	v_addc_co_u32_e32 v11, vcc, 0, v9, vcc
	global_load_dword v38, v[10:11], off nt
	v_add_co_u32_e32 v10, vcc, s0, v8
	s_mov_b32 s0, 0xb8000
	s_nop 0
	v_addc_co_u32_e32 v11, vcc, 0, v9, vcc
	global_load_dword v39, v[10:11], off nt
	v_add_co_u32_e32 v10, vcc, s0, v8
	s_mov_b32 s0, 0xc0000
	s_nop 0
	v_addc_co_u32_e32 v11, vcc, 0, v9, vcc
	global_load_dword v40, v[10:11], off nt
	v_add_co_u32_e32 v10, vcc, s0, v8
	s_mov_b32 s0, 0xc8000
	s_nop 0
	v_addc_co_u32_e32 v11, vcc, 0, v9, vcc
	global_load_dword v41, v[10:11], off nt
	v_add_co_u32_e32 v10, vcc, s0, v8
	s_mov_b32 s0, 0xd0000
	s_nop 0
	v_addc_co_u32_e32 v11, vcc, 0, v9, vcc
	global_load_dword v42, v[10:11], off nt
	v_add_co_u32_e32 v10, vcc, s0, v8
	s_mov_b32 s0, 0xd8000
	s_nop 0
	v_addc_co_u32_e32 v11, vcc, 0, v9, vcc
	global_load_dword v43, v[10:11], off nt
	v_add_co_u32_e32 v10, vcc, s0, v8
	s_mov_b32 s0, 0xe0000
	s_nop 0
	v_addc_co_u32_e32 v11, vcc, 0, v9, vcc
	global_load_dword v44, v[10:11], off nt
	v_add_co_u32_e32 v10, vcc, s0, v8
	s_mov_b32 s0, 0xe8000
	s_nop 0
	v_addc_co_u32_e32 v11, vcc, 0, v9, vcc
	global_load_dword v45, v[10:11], off nt
	v_add_co_u32_e32 v10, vcc, s0, v8
	s_mov_b32 s0, 0xf0000
	s_nop 0
	v_addc_co_u32_e32 v11, vcc, 0, v9, vcc
	global_load_dword v46, v[10:11], off nt
	v_add_co_u32_e32 v10, vcc, s0, v8
	s_mov_b32 s0, 0xf8000
	s_nop 0
	v_addc_co_u32_e32 v11, vcc, 0, v9, vcc
	v_add_co_u32_e32 v8, vcc, s0, v8
	global_load_dword v10, v[10:11], off nt
	s_nop 0
	v_addc_co_u32_e32 v9, vcc, 0, v9, vcc
	global_load_dword v8, v[8:9], off nt
	v_add_u32_e32 v9, 0x400, v5
	s_waitcnt vmcnt(0)
	ds_write2_b32 v5, v17, v18 offset1:66
	ds_write2_b32 v5, v19, v20 offset0:132 offset1:198
	ds_write2_b32 v9, v21, v22 offset0:8 offset1:74
	ds_write2_b32 v9, v23, v24 offset0:140 offset1:206
	v_add_u32_e32 v9, 0x800, v5
	ds_write2_b32 v9, v25, v26 offset0:16 offset1:82
	ds_write2_b32 v9, v27, v28 offset0:148 offset1:214
	v_add_u32_e32 v9, 0xc00, v5
	ds_write2_b32 v9, v29, v30 offset0:24 offset1:90
	ds_write2_b32 v9, v31, v32 offset0:156 offset1:222
	v_add_u32_e32 v9, 0x1000, v5
	ds_write2_b32 v9, v33, v34 offset0:32 offset1:98
	ds_write2_b32 v9, v35, v36 offset0:164 offset1:230
	v_add_u32_e32 v9, 0x1400, v5
	ds_write2_b32 v9, v37, v38 offset0:40 offset1:106
	ds_write2_b32 v9, v39, v40 offset0:172 offset1:238
	v_add_u32_e32 v9, 0x1800, v5
	ds_write2_b32 v9, v41, v42 offset0:48 offset1:114
	ds_write2_b32 v9, v43, v44 offset0:180 offset1:246
	v_add_u32_e32 v9, 0x1c00, v5
	ds_write2_b32 v9, v45, v46 offset0:56 offset1:122
	ds_write2_b32 v9, v10, v8 offset0:188 offset1:254
	s_waitcnt lgkmcnt(0)
	ds_read2_b32 v[10:11], v13 offset0:33 offset1:41
	ds_read2_b32 v[22:23], v13 offset1:8
	ds_read2_b32 v[24:25], v13 offset0:66 offset1:74
	ds_read2_b32 v[26:27], v13 offset0:99 offset1:107
	ds_read2_b32 v[28:29], v13 offset0:132 offset1:140
	ds_read2_b32 v[30:31], v13 offset0:165 offset1:173
	ds_read2_b32 v[32:33], v13 offset0:198 offset1:206
	ds_read2_b32 v[34:35], v13 offset0:231 offset1:239
	s_waitcnt lgkmcnt(7)
	v_bfe_u32 v18, v10, 16, 1
	s_waitcnt lgkmcnt(6)
	v_bfe_u32 v17, v22, 16, 1
	v_add3_u32 v17, v22, v17, s53
	v_lshrrev_b32_e32 v17, 16, v17
	v_add3_u32 v10, v10, v18, s53
	v_and_or_b32 v18, v10, s77, v17
	s_waitcnt lgkmcnt(5)
	v_bfe_u32 v10, v24, 16, 1
	v_add3_u32 v10, v24, v10, s53
	s_waitcnt lgkmcnt(4)
	v_bfe_u32 v17, v26, 16, 1
	v_lshrrev_b32_e32 v10, 16, v10
	v_add3_u32 v17, v26, v17, s53
	v_and_or_b32 v19, v17, s77, v10
	s_waitcnt lgkmcnt(3)
	v_bfe_u32 v10, v28, 16, 1
	v_add3_u32 v10, v28, v10, s53
	s_waitcnt lgkmcnt(2)
	v_bfe_u32 v17, v30, 16, 1
	v_lshrrev_b32_e32 v10, 16, v10
	v_add3_u32 v17, v30, v17, s53
	v_and_or_b32 v20, v17, s77, v10
	s_waitcnt lgkmcnt(1)
	v_bfe_u32 v10, v32, 16, 1
	v_add3_u32 v10, v32, v10, s53
	s_waitcnt lgkmcnt(0)
	v_bfe_u32 v17, v34, 16, 1
	v_lshrrev_b32_e32 v10, 16, v10
	v_add3_u32 v17, v34, v17, s53
	v_and_or_b32 v21, v17, s77, v10
	v_or_b32_e32 v10, s2, v12
	s_lshl_b32 s86, s3, 1
	v_lshlrev_b32_e32 v202, 12, v10
	v_bfe_u32 v10, v23, 16, 1
	v_lshl_add_u64 v[8:9], v[6:7], 0, s[86:87]
	v_add3_u32 v10, v23, v10, s53
	v_bfe_u32 v17, v11, 16, 1
	v_lshl_add_u64 v[36:37], v[8:9], 0, v[202:203]
	v_lshrrev_b32_e32 v10, 16, v10
	v_add3_u32 v11, v11, v17, s53
	global_store_dwordx4 v[36:37], v[18:21], off nt
	s_mov_b64 s[18:19], s[22:23]
	s_nop 0
	v_and_or_b32 v18, v11, s77, v10
	v_bfe_u32 v10, v25, 16, 1
	v_add3_u32 v10, v25, v10, s53
	v_bfe_u32 v11, v27, 16, 1
	v_lshrrev_b32_e32 v10, 16, v10
	v_add3_u32 v11, v27, v11, s53
	v_and_or_b32 v19, v11, s77, v10
	v_bfe_u32 v10, v29, 16, 1
	v_add3_u32 v10, v29, v10, s53
	v_bfe_u32 v11, v31, 16, 1
	v_lshrrev_b32_e32 v10, 16, v10
	v_add3_u32 v11, v31, v11, s53
	v_and_or_b32 v20, v11, s77, v10
	v_bfe_u32 v10, v33, 16, 1
	v_add3_u32 v10, v33, v10, s53
	v_bfe_u32 v11, v35, 16, 1
	v_lshrrev_b32_e32 v10, 16, v10
	v_add3_u32 v11, v35, v11, s53
	v_and_or_b32 v21, v11, s77, v10
	v_or_b32_e32 v10, s2, v14
	v_lshlrev_b32_e32 v202, 12, v10
	v_lshl_add_u64 v[10:11], v[8:9], 0, v[202:203]
	global_store_dwordx4 v[10:11], v[18:21], off nt
	ds_read2_b32 v[10:11], v13 offset0:49 offset1:57
	ds_read2_b32 v[22:23], v13 offset0:16 offset1:24
	ds_read2_b32 v[24:25], v13 offset0:82 offset1:90
	ds_read2_b32 v[26:27], v13 offset0:115 offset1:123
	ds_read2_b32 v[28:29], v13 offset0:148 offset1:156
	ds_read2_b32 v[30:31], v13 offset0:181 offset1:189
	ds_read2_b32 v[32:33], v13 offset0:214 offset1:222
	ds_read2_b32 v[34:35], v13 offset0:247 offset1:255
	s_waitcnt lgkmcnt(7)
	v_bfe_u32 v18, v10, 16, 1
	s_waitcnt lgkmcnt(6)
	v_bfe_u32 v17, v22, 16, 1
	v_add3_u32 v17, v22, v17, s53
	v_lshrrev_b32_e32 v17, 16, v17
	v_add3_u32 v10, v10, v18, s53
	v_and_or_b32 v18, v10, s77, v17
	s_waitcnt lgkmcnt(5)
	v_bfe_u32 v10, v24, 16, 1
	v_add3_u32 v10, v24, v10, s53
	s_waitcnt lgkmcnt(4)
	v_bfe_u32 v17, v26, 16, 1
	v_lshrrev_b32_e32 v10, 16, v10
	v_add3_u32 v17, v26, v17, s53
	v_and_or_b32 v19, v17, s77, v10
	s_waitcnt lgkmcnt(3)
	v_bfe_u32 v10, v28, 16, 1
	v_add3_u32 v10, v28, v10, s53
	s_waitcnt lgkmcnt(2)
	v_bfe_u32 v17, v30, 16, 1
	v_lshrrev_b32_e32 v10, 16, v10
	v_add3_u32 v17, v30, v17, s53
	v_and_or_b32 v20, v17, s77, v10
	s_waitcnt lgkmcnt(1)
	v_bfe_u32 v10, v32, 16, 1
	v_add3_u32 v10, v32, v10, s53
	s_waitcnt lgkmcnt(0)
	v_bfe_u32 v17, v34, 16, 1
	v_lshrrev_b32_e32 v10, 16, v10
	v_add3_u32 v17, v34, v17, s53
	v_and_or_b32 v21, v17, s77, v10
	v_or_b32_e32 v10, s2, v15
	v_lshlrev_b32_e32 v202, 12, v10
	v_bfe_u32 v10, v23, 16, 1
	v_add3_u32 v10, v23, v10, s53
	v_bfe_u32 v17, v11, 16, 1
	v_lshl_add_u64 v[36:37], v[8:9], 0, v[202:203]
	v_lshrrev_b32_e32 v10, 16, v10
	v_add3_u32 v11, v11, v17, s53
	global_store_dwordx4 v[36:37], v[18:21], off nt
	s_nop 1
	v_and_or_b32 v18, v11, s77, v10
	v_bfe_u32 v10, v25, 16, 1
	v_add3_u32 v10, v25, v10, s53
	v_bfe_u32 v11, v27, 16, 1
	v_lshrrev_b32_e32 v10, 16, v10
	v_add3_u32 v11, v27, v11, s53
	v_and_or_b32 v19, v11, s77, v10
	v_bfe_u32 v10, v29, 16, 1
	v_add3_u32 v10, v29, v10, s53
	v_bfe_u32 v11, v31, 16, 1
	v_lshrrev_b32_e32 v10, 16, v10
	v_add3_u32 v11, v31, v11, s53
	v_and_or_b32 v20, v11, s77, v10
	v_bfe_u32 v10, v33, 16, 1
	v_add3_u32 v10, v33, v10, s53
	v_bfe_u32 v11, v35, 16, 1
	v_lshrrev_b32_e32 v10, 16, v10
	v_add3_u32 v11, v35, v11, s53
	v_and_or_b32 v21, v11, s77, v10
	v_or_b32_e32 v10, s2, v16
	v_lshlrev_b32_e32 v202, 11, v10
	v_lshl_add_u64 v[8:9], v[202:203], 1, v[8:9]
	global_store_dwordx4 v[8:9], v[18:21], off nt
	s_waitcnt lgkmcnt(0)
	s_mov_b64 s[2:3], 0
.LBB0_1466:
	s_andn2_b64 vcc, exec, s[2:3]
	s_cbranch_vccnz .LBB0_1468
	s_and_b32 s0, s4, 0x1f800
	s_add_i32 s86, s0, 0xfffe9800
	v_readlane_b32 s16, v251, 30
	s_lshl_b64 s[0:1], s[86:87], 13
	v_readlane_b32 s18, v251, 32
	v_readlane_b32 s19, v251, 33
	s_add_u32 s10, s18, s0
	s_addc_u32 s11, s19, s1
	s_lshl_b64 s[0:1], s[86:87], 12
	v_readlane_b32 s2, v251, 52
	s_add_u32 s3, s2, s0
	v_readlane_b32 s0, v251, 53
	s_addc_u32 s5, s0, s1
	s_lshl_b32 s0, s4, 5
	s_and_b32 s2, s0, 0x7e0
	s_and_b32 s9, s4, 0x7c0
	s_lshl_b32 s0, s2, 2
	s_add_u32 s0, s10, s0
	v_or_b32_e32 v10, s9, v3
	s_addc_u32 s1, s11, 0
	v_lshlrev_b32_e32 v202, 2, v2
	v_lshl_add_u64 v[8:9], s[0:1], 0, v[202:203]
	v_lshlrev_b32_e32 v202, 13, v10
	v_lshl_add_u64 v[8:9], v[8:9], 0, v[202:203]
	v_add_co_u32_e32 v10, vcc, s89, v8
	s_mov_b32 s0, 0x8000
	s_nop 0
	v_addc_co_u32_e32 v11, vcc, 0, v9, vcc
	global_load_dword v17, v[8:9], off nt
	global_load_dword v18, v[10:11], off nt
	v_add_co_u32_e32 v10, vcc, s0, v8
	s_mov_b32 s0, 0xc000
	s_nop 0
	v_addc_co_u32_e32 v11, vcc, 0, v9, vcc
	global_load_dword v19, v[10:11], off nt
	v_add_co_u32_e32 v10, vcc, s0, v8
	s_mov_b32 s0, 0x10000
	s_nop 0
	v_addc_co_u32_e32 v11, vcc, 0, v9, vcc
	global_load_dword v20, v[10:11], off nt
	v_add_co_u32_e32 v10, vcc, s0, v8
	s_mov_b32 s0, 0x14000
	s_nop 0
	v_addc_co_u32_e32 v11, vcc, 0, v9, vcc
	global_load_dword v21, v[10:11], off nt
	v_add_co_u32_e32 v10, vcc, s0, v8
	s_mov_b32 s0, 0x18000
	s_nop 0
	v_addc_co_u32_e32 v11, vcc, 0, v9, vcc
	global_load_dword v22, v[10:11], off nt
	v_add_co_u32_e32 v10, vcc, s0, v8
	s_mov_b32 s0, 0x1c000
	s_nop 0
	v_addc_co_u32_e32 v11, vcc, 0, v9, vcc
	global_load_dword v23, v[10:11], off nt
	v_add_co_u32_e32 v10, vcc, s0, v8
	s_mov_b32 s0, 0x20000
	s_nop 0
	v_addc_co_u32_e32 v11, vcc, 0, v9, vcc
	global_load_dword v24, v[10:11], off nt
	v_add_co_u32_e32 v10, vcc, s0, v8
	s_mov_b32 s0, 0x24000
	s_nop 0
	v_addc_co_u32_e32 v11, vcc, 0, v9, vcc
	global_load_dword v25, v[10:11], off nt
	v_add_co_u32_e32 v10, vcc, s0, v8
	s_mov_b32 s0, 0x28000
	s_nop 0
	v_addc_co_u32_e32 v11, vcc, 0, v9, vcc
	global_load_dword v26, v[10:11], off nt
	v_add_co_u32_e32 v10, vcc, s0, v8
	s_mov_b32 s0, 0x2c000
	s_nop 0
	v_addc_co_u32_e32 v11, vcc, 0, v9, vcc
	global_load_dword v27, v[10:11], off nt
	v_add_co_u32_e32 v10, vcc, s0, v8
	s_mov_b32 s0, 0x30000
	s_nop 0
	v_addc_co_u32_e32 v11, vcc, 0, v9, vcc
	global_load_dword v28, v[10:11], off nt
	v_add_co_u32_e32 v10, vcc, s0, v8
	s_mov_b32 s0, 0x34000
	s_nop 0
	v_addc_co_u32_e32 v11, vcc, 0, v9, vcc
	global_load_dword v29, v[10:11], off nt
	v_add_co_u32_e32 v10, vcc, s0, v8
	s_mov_b32 s0, 0x38000
	s_nop 0
	v_addc_co_u32_e32 v11, vcc, 0, v9, vcc
	global_load_dword v30, v[10:11], off nt
	v_add_co_u32_e32 v10, vcc, s0, v8
	s_mov_b32 s0, 0x3c000
	s_nop 0
	v_addc_co_u32_e32 v11, vcc, 0, v9, vcc
	global_load_dword v31, v[10:11], off nt
	v_add_co_u32_e32 v10, vcc, s0, v8
	s_mov_b32 s0, 0x40000
	s_nop 0
	v_addc_co_u32_e32 v11, vcc, 0, v9, vcc
	global_load_dword v32, v[10:11], off nt
	v_add_co_u32_e32 v10, vcc, s0, v8
	s_mov_b32 s0, 0x44000
	s_nop 0
	v_addc_co_u32_e32 v11, vcc, 0, v9, vcc
	global_load_dword v33, v[10:11], off nt
	v_add_co_u32_e32 v10, vcc, s0, v8
	s_mov_b32 s0, 0x48000
	s_nop 0
	v_addc_co_u32_e32 v11, vcc, 0, v9, vcc
	global_load_dword v34, v[10:11], off nt
	v_add_co_u32_e32 v10, vcc, s0, v8
	s_mov_b32 s0, 0x4c000
	s_nop 0
	v_addc_co_u32_e32 v11, vcc, 0, v9, vcc
	global_load_dword v35, v[10:11], off nt
	v_add_co_u32_e32 v10, vcc, s0, v8
	s_mov_b32 s0, 0x50000
	s_nop 0
	v_addc_co_u32_e32 v11, vcc, 0, v9, vcc
	global_load_dword v36, v[10:11], off nt
	v_add_co_u32_e32 v10, vcc, s0, v8
	s_mov_b32 s0, 0x54000
	s_nop 0
	v_addc_co_u32_e32 v11, vcc, 0, v9, vcc
	global_load_dword v37, v[10:11], off nt
	v_add_co_u32_e32 v10, vcc, s0, v8
	s_mov_b32 s0, 0x58000
	s_nop 0
	v_addc_co_u32_e32 v11, vcc, 0, v9, vcc
	global_load_dword v38, v[10:11], off nt
	v_add_co_u32_e32 v10, vcc, s0, v8
	s_mov_b32 s0, 0x5c000
	s_nop 0
	v_addc_co_u32_e32 v11, vcc, 0, v9, vcc
	global_load_dword v39, v[10:11], off nt
	v_add_co_u32_e32 v10, vcc, s0, v8
	s_mov_b32 s0, 0x60000
	s_nop 0
	v_addc_co_u32_e32 v11, vcc, 0, v9, vcc
	global_load_dword v40, v[10:11], off nt
	v_add_co_u32_e32 v10, vcc, s0, v8
	s_mov_b32 s0, 0x64000
	s_nop 0
	v_addc_co_u32_e32 v11, vcc, 0, v9, vcc
	global_load_dword v41, v[10:11], off nt
	v_add_co_u32_e32 v10, vcc, s0, v8
	s_mov_b32 s0, 0x68000
	s_nop 0
	v_addc_co_u32_e32 v11, vcc, 0, v9, vcc
	global_load_dword v42, v[10:11], off nt
	v_add_co_u32_e32 v10, vcc, s0, v8
	s_mov_b32 s0, 0x6c000
	s_nop 0
	v_addc_co_u32_e32 v11, vcc, 0, v9, vcc
	global_load_dword v43, v[10:11], off nt
	v_add_co_u32_e32 v10, vcc, s0, v8
	s_mov_b32 s0, 0x70000
	s_nop 0
	v_addc_co_u32_e32 v11, vcc, 0, v9, vcc
	global_load_dword v44, v[10:11], off nt
	v_add_co_u32_e32 v10, vcc, s0, v8
	s_mov_b32 s0, 0x74000
	s_nop 0
	v_addc_co_u32_e32 v11, vcc, 0, v9, vcc
	global_load_dword v45, v[10:11], off nt
	v_add_co_u32_e32 v10, vcc, s0, v8
	s_mov_b32 s0, 0x78000
	s_nop 0
	v_addc_co_u32_e32 v11, vcc, 0, v9, vcc
	global_load_dword v46, v[10:11], off nt
	v_add_co_u32_e32 v10, vcc, s0, v8
	s_mov_b32 s0, 0x7c000
	s_nop 0
	v_addc_co_u32_e32 v11, vcc, 0, v9, vcc
	v_add_co_u32_e32 v8, vcc, s0, v8
	global_load_dword v10, v[10:11], off nt
	s_nop 0
	v_addc_co_u32_e32 v9, vcc, 0, v9, vcc
	global_load_dword v8, v[8:9], off nt
	v_add_u32_e32 v9, 0x400, v5
	s_waitcnt vmcnt(0)
	ds_write2_b32 v5, v17, v18 offset1:66
	ds_write2_b32 v5, v19, v20 offset0:132 offset1:198
	ds_write2_b32 v9, v21, v22 offset0:8 offset1:74
	ds_write2_b32 v9, v23, v24 offset0:140 offset1:206
	v_add_u32_e32 v9, 0x800, v5
	ds_write2_b32 v9, v25, v26 offset0:16 offset1:82
	ds_write2_b32 v9, v27, v28 offset0:148 offset1:214
	v_add_u32_e32 v9, 0xc00, v5
	ds_write2_b32 v9, v29, v30 offset0:24 offset1:90
	ds_write2_b32 v9, v31, v32 offset0:156 offset1:222
	v_add_u32_e32 v9, 0x1000, v5
	ds_write2_b32 v9, v33, v34 offset0:32 offset1:98
	ds_write2_b32 v9, v35, v36 offset0:164 offset1:230
	v_add_u32_e32 v9, 0x1400, v5
	ds_write2_b32 v9, v37, v38 offset0:40 offset1:106
	ds_write2_b32 v9, v39, v40 offset0:172 offset1:238
	v_add_u32_e32 v9, 0x1800, v5
	ds_write2_b32 v9, v41, v42 offset0:48 offset1:114
	ds_write2_b32 v9, v43, v44 offset0:180 offset1:246
	v_add_u32_e32 v9, 0x1c00, v5
	ds_write2_b32 v9, v45, v46 offset0:56 offset1:122
	ds_write2_b32 v9, v10, v8 offset0:188 offset1:254
	s_waitcnt lgkmcnt(0)
	ds_read2_b32 v[10:11], v13 offset0:33 offset1:41
	ds_read2_b32 v[22:23], v13 offset1:8
	ds_read2_b32 v[24:25], v13 offset0:66 offset1:74
	ds_read2_b32 v[26:27], v13 offset0:99 offset1:107
	ds_read2_b32 v[28:29], v13 offset0:132 offset1:140
	ds_read2_b32 v[30:31], v13 offset0:165 offset1:173
	ds_read2_b32 v[32:33], v13 offset0:198 offset1:206
	ds_read2_b32 v[34:35], v13 offset0:231 offset1:239
	s_waitcnt lgkmcnt(7)
	v_bfe_u32 v18, v10, 16, 1
	s_waitcnt lgkmcnt(6)
	v_bfe_u32 v17, v22, 16, 1
	v_add3_u32 v17, v22, v17, s53
	v_lshrrev_b32_e32 v17, 16, v17
	v_add3_u32 v10, v10, v18, s53
	v_and_or_b32 v18, v10, s77, v17
	s_waitcnt lgkmcnt(5)
	v_bfe_u32 v10, v24, 16, 1
	v_add3_u32 v10, v24, v10, s53
	s_waitcnt lgkmcnt(4)
	v_bfe_u32 v17, v26, 16, 1
	v_lshrrev_b32_e32 v10, 16, v10
	v_add3_u32 v17, v26, v17, s53
	v_and_or_b32 v19, v17, s77, v10
	s_waitcnt lgkmcnt(3)
	v_bfe_u32 v10, v28, 16, 1
	v_add3_u32 v10, v28, v10, s53
	s_waitcnt lgkmcnt(2)
	v_bfe_u32 v17, v30, 16, 1
	v_lshrrev_b32_e32 v10, 16, v10
	v_add3_u32 v17, v30, v17, s53
	v_and_or_b32 v20, v17, s77, v10
	s_waitcnt lgkmcnt(1)
	v_bfe_u32 v10, v32, 16, 1
	s_lshl_b32 s0, s9, 1
	v_add3_u32 v10, v32, v10, s53
	s_waitcnt lgkmcnt(0)
	v_bfe_u32 v17, v34, 16, 1
	s_add_u32 s0, s3, s0
	v_lshrrev_b32_e32 v10, 16, v10
	v_add3_u32 v17, v34, v17, s53
	s_addc_u32 s1, s5, 0
	v_lshlrev_b32_e32 v202, 1, v4
	v_and_or_b32 v21, v17, s77, v10
	v_or_b32_e32 v10, s2, v12
	v_lshl_add_u64 v[8:9], s[0:1], 0, v[202:203]
	v_lshlrev_b32_e32 v202, 12, v10
	v_bfe_u32 v10, v23, 16, 1
	v_add3_u32 v10, v23, v10, s53
	v_bfe_u32 v17, v11, 16, 1
	v_lshl_add_u64 v[36:37], v[8:9], 0, v[202:203]
	v_lshrrev_b32_e32 v10, 16, v10
	v_add3_u32 v11, v11, v17, s53
	global_store_dwordx4 v[36:37], v[18:21], off nt
	v_readlane_b32 s17, v251, 31
	v_readlane_b32 s20, v251, 34
	v_and_or_b32 v18, v11, s77, v10
	v_bfe_u32 v10, v25, 16, 1
	v_add3_u32 v10, v25, v10, s53
	v_bfe_u32 v11, v27, 16, 1
	v_lshrrev_b32_e32 v10, 16, v10
	v_add3_u32 v11, v27, v11, s53
	v_and_or_b32 v19, v11, s77, v10
	v_bfe_u32 v10, v29, 16, 1
	v_add3_u32 v10, v29, v10, s53
	v_bfe_u32 v11, v31, 16, 1
	v_lshrrev_b32_e32 v10, 16, v10
	v_add3_u32 v11, v31, v11, s53
	v_and_or_b32 v20, v11, s77, v10
	v_bfe_u32 v10, v33, 16, 1
	v_add3_u32 v10, v33, v10, s53
	v_bfe_u32 v11, v35, 16, 1
	v_lshrrev_b32_e32 v10, 16, v10
	v_add3_u32 v11, v35, v11, s53
	v_and_or_b32 v21, v11, s77, v10
	v_or_b32_e32 v10, s2, v14
	v_lshlrev_b32_e32 v202, 12, v10
	v_lshl_add_u64 v[10:11], v[8:9], 0, v[202:203]
	global_store_dwordx4 v[10:11], v[18:21], off nt
	ds_read2_b32 v[10:11], v13 offset0:49 offset1:57
	ds_read2_b32 v[22:23], v13 offset0:16 offset1:24
	ds_read2_b32 v[24:25], v13 offset0:82 offset1:90
	ds_read2_b32 v[26:27], v13 offset0:115 offset1:123
	ds_read2_b32 v[28:29], v13 offset0:148 offset1:156
	ds_read2_b32 v[30:31], v13 offset0:181 offset1:189
	ds_read2_b32 v[32:33], v13 offset0:214 offset1:222
	ds_read2_b32 v[34:35], v13 offset0:247 offset1:255
	s_waitcnt lgkmcnt(7)
	v_bfe_u32 v18, v10, 16, 1
	s_waitcnt lgkmcnt(6)
	v_bfe_u32 v17, v22, 16, 1
	v_add3_u32 v17, v22, v17, s53
	v_lshrrev_b32_e32 v17, 16, v17
	v_add3_u32 v10, v10, v18, s53
	v_and_or_b32 v18, v10, s77, v17
	s_waitcnt lgkmcnt(5)
	v_bfe_u32 v10, v24, 16, 1
	v_add3_u32 v10, v24, v10, s53
	s_waitcnt lgkmcnt(4)
	v_bfe_u32 v17, v26, 16, 1
	v_lshrrev_b32_e32 v10, 16, v10
	v_add3_u32 v17, v26, v17, s53
	v_and_or_b32 v19, v17, s77, v10
	s_waitcnt lgkmcnt(3)
	v_bfe_u32 v10, v28, 16, 1
	v_add3_u32 v10, v28, v10, s53
	s_waitcnt lgkmcnt(2)
	v_bfe_u32 v17, v30, 16, 1
	v_lshrrev_b32_e32 v10, 16, v10
	v_add3_u32 v17, v30, v17, s53
	v_and_or_b32 v20, v17, s77, v10
	s_waitcnt lgkmcnt(1)
	v_bfe_u32 v10, v32, 16, 1
	v_add3_u32 v10, v32, v10, s53
	s_waitcnt lgkmcnt(0)
	v_bfe_u32 v17, v34, 16, 1
	v_lshrrev_b32_e32 v10, 16, v10
	v_add3_u32 v17, v34, v17, s53
	v_and_or_b32 v21, v17, s77, v10
	v_or_b32_e32 v10, s2, v15
	v_lshlrev_b32_e32 v202, 12, v10
	v_bfe_u32 v10, v23, 16, 1
	v_add3_u32 v10, v23, v10, s53
	v_bfe_u32 v17, v11, 16, 1
	v_lshl_add_u64 v[36:37], v[8:9], 0, v[202:203]
	v_lshrrev_b32_e32 v10, 16, v10
	v_add3_u32 v11, v11, v17, s53
	global_store_dwordx4 v[36:37], v[18:21], off nt
	v_readlane_b32 s21, v251, 35
	v_readlane_b32 s22, v251, 36
	v_and_or_b32 v18, v11, s77, v10
	v_bfe_u32 v10, v25, 16, 1
	v_add3_u32 v10, v25, v10, s53
	v_bfe_u32 v11, v27, 16, 1
	v_lshrrev_b32_e32 v10, 16, v10
	v_add3_u32 v11, v27, v11, s53
	v_and_or_b32 v19, v11, s77, v10
	v_bfe_u32 v10, v29, 16, 1
	v_add3_u32 v10, v29, v10, s53
	v_bfe_u32 v11, v31, 16, 1
	v_lshrrev_b32_e32 v10, 16, v10
	v_add3_u32 v11, v31, v11, s53
	v_and_or_b32 v20, v11, s77, v10
	v_bfe_u32 v10, v33, 16, 1
	v_add3_u32 v10, v33, v10, s53
	v_bfe_u32 v11, v35, 16, 1
	v_lshrrev_b32_e32 v10, 16, v10
	v_add3_u32 v11, v35, v11, s53
	v_and_or_b32 v21, v11, s77, v10
	v_or_b32_e32 v10, s2, v16
	v_lshlrev_b32_e32 v202, 12, v10
	v_lshl_add_u64 v[8:9], v[8:9], 0, v[202:203]
	global_store_dwordx4 v[8:9], v[18:21], off nt
	s_waitcnt lgkmcnt(0)
	v_readlane_b32 s23, v251, 37
	v_readlane_b32 s24, v251, 38
	v_readlane_b32 s25, v251, 39
	v_readlane_b32 s26, v251, 40
	v_readlane_b32 s27, v251, 41
	v_readlane_b32 s28, v251, 42
	v_readlane_b32 s29, v251, 43
	v_readlane_b32 s30, v251, 44
	v_readlane_b32 s31, v251, 45

.LBB0_1469:
	s_andn2_b64 vcc, exec, s[2:3]
	s_cbranch_vccnz .LBB0_1478
	s_add_i32 s1, s4, 0xffffa000
	s_mul_hi_u32 s0, s1, 0x3e0f83e1
	s_lshr_b32 s0, s0, 12
	s_mul_i32 s2, s0, 0x4200
	s_sub_i32 s1, s1, s2
	s_mul_i32 s2, s1, 0xba2f
	s_lshr_b32 s2, s2, 28
	s_mulk_i32 s2, 0x1600
	s_sub_i32 s5, s1, s2
	s_cmpk_gt_u32 s1, 0x15ff
	s_mul_hi_u32 s9, s0, 0x2c00000
	s_mul_i32 s10, s0, 0x2c00000
	s_mov_b64 s[2:3], -1
	s_cbranch_scc0 .LBB0_1476
	s_addk_i32 s1, 0xea00
	s_cmpk_gt_u32 s1, 0x15ff
	s_cbranch_scc0 .LBB0_1473
	v_readlane_b32 s16, v251, 14
	v_readlane_b32 s20, v251, 18
	v_readlane_b32 s21, v251, 19
	s_add_u32 s1, s20, s10
	s_addc_u32 s15, s21, s9
	s_mul_hi_u32 s2, s0, 0x1600000
	s_mul_i32 s0, s0, 0x1600000
	v_readlane_b32 s3, v251, 54
	s_add_u32 s3, s3, s0
	v_readlane_b32 s0, v251, 55
	s_addc_u32 s11, s0, s2
	s_lshl_b32 s0, s5, 5
	s_and_b32 s2, s0, 0x7e0
	s_and_b32 s14, s5, 0x1fc0
	s_lshl_b32 s0, s2, 2
	s_add_u32 s0, s1, s0
	v_or_b32_e32 v10, s14, v3
	s_addc_u32 s1, s15, 0
	v_lshlrev_b32_e32 v202, 2, v2
	v_lshl_add_u64 v[8:9], s[0:1], 0, v[202:203]
	v_lshlrev_b32_e32 v202, 13, v10
	v_lshl_add_u64 v[8:9], v[8:9], 0, v[202:203]
	v_add_co_u32_e32 v10, vcc, s89, v8
	s_mov_b32 s0, 0x8000
	s_nop 0
	v_addc_co_u32_e32 v11, vcc, 0, v9, vcc
	global_load_dword v17, v[8:9], off nt
	global_load_dword v18, v[10:11], off nt
	v_add_co_u32_e32 v10, vcc, s0, v8
	s_mov_b32 s0, 0xc000
	s_nop 0
	v_addc_co_u32_e32 v11, vcc, 0, v9, vcc
	global_load_dword v19, v[10:11], off nt
	v_add_co_u32_e32 v10, vcc, s0, v8
	s_mov_b32 s0, 0x10000
	s_nop 0
	v_addc_co_u32_e32 v11, vcc, 0, v9, vcc
	global_load_dword v20, v[10:11], off nt
	v_add_co_u32_e32 v10, vcc, s0, v8
	s_mov_b32 s0, 0x14000
	s_nop 0
	v_addc_co_u32_e32 v11, vcc, 0, v9, vcc
	global_load_dword v21, v[10:11], off nt
	v_add_co_u32_e32 v10, vcc, s0, v8
	s_mov_b32 s0, 0x18000
	s_nop 0
	v_addc_co_u32_e32 v11, vcc, 0, v9, vcc
	global_load_dword v22, v[10:11], off nt
	v_add_co_u32_e32 v10, vcc, s0, v8
	s_mov_b32 s0, 0x1c000
	s_nop 0
	v_addc_co_u32_e32 v11, vcc, 0, v9, vcc
	global_load_dword v23, v[10:11], off nt
	v_add_co_u32_e32 v10, vcc, s0, v8
	s_mov_b32 s0, 0x20000
	s_nop 0
	v_addc_co_u32_e32 v11, vcc, 0, v9, vcc
	global_load_dword v24, v[10:11], off nt
	v_add_co_u32_e32 v10, vcc, s0, v8
	s_mov_b32 s0, 0x24000
	s_nop 0
	v_addc_co_u32_e32 v11, vcc, 0, v9, vcc
	global_load_dword v25, v[10:11], off nt
	v_add_co_u32_e32 v10, vcc, s0, v8
	s_mov_b32 s0, 0x28000
	s_nop 0
	v_addc_co_u32_e32 v11, vcc, 0, v9, vcc
	global_load_dword v26, v[10:11], off nt
	v_add_co_u32_e32 v10, vcc, s0, v8
	s_mov_b32 s0, 0x2c000
	s_nop 0
	v_addc_co_u32_e32 v11, vcc, 0, v9, vcc
	global_load_dword v27, v[10:11], off nt
	v_add_co_u32_e32 v10, vcc, s0, v8
	s_mov_b32 s0, 0x30000
	s_nop 0
	v_addc_co_u32_e32 v11, vcc, 0, v9, vcc
	global_load_dword v28, v[10:11], off nt
	v_add_co_u32_e32 v10, vcc, s0, v8
	s_mov_b32 s0, 0x34000
	s_nop 0
	v_addc_co_u32_e32 v11, vcc, 0, v9, vcc
	global_load_dword v29, v[10:11], off nt
	v_add_co_u32_e32 v10, vcc, s0, v8
	s_mov_b32 s0, 0x38000
	s_nop 0
	v_addc_co_u32_e32 v11, vcc, 0, v9, vcc
	global_load_dword v30, v[10:11], off nt
	v_add_co_u32_e32 v10, vcc, s0, v8
	s_mov_b32 s0, 0x3c000
	s_nop 0
	v_addc_co_u32_e32 v11, vcc, 0, v9, vcc
	global_load_dword v31, v[10:11], off nt
	v_add_co_u32_e32 v10, vcc, s0, v8
	s_mov_b32 s0, 0x40000
	s_nop 0
	v_addc_co_u32_e32 v11, vcc, 0, v9, vcc
	global_load_dword v32, v[10:11], off nt
	v_add_co_u32_e32 v10, vcc, s0, v8
	s_mov_b32 s0, 0x44000
	s_nop 0
	v_addc_co_u32_e32 v11, vcc, 0, v9, vcc
	global_load_dword v33, v[10:11], off nt
	v_add_co_u32_e32 v10, vcc, s0, v8
	s_mov_b32 s0, 0x48000
	s_nop 0
	v_addc_co_u32_e32 v11, vcc, 0, v9, vcc
	global_load_dword v34, v[10:11], off nt
	v_add_co_u32_e32 v10, vcc, s0, v8
	s_mov_b32 s0, 0x4c000
	s_nop 0
	v_addc_co_u32_e32 v11, vcc, 0, v9, vcc
	global_load_dword v35, v[10:11], off nt
	v_add_co_u32_e32 v10, vcc, s0, v8
	s_mov_b32 s0, 0x50000
	s_nop 0
	v_addc_co_u32_e32 v11, vcc, 0, v9, vcc
	global_load_dword v36, v[10:11], off nt
	v_add_co_u32_e32 v10, vcc, s0, v8
	s_mov_b32 s0, 0x54000
	s_nop 0
	v_addc_co_u32_e32 v11, vcc, 0, v9, vcc
	global_load_dword v37, v[10:11], off nt
	v_add_co_u32_e32 v10, vcc, s0, v8
	s_mov_b32 s0, 0x58000
	s_nop 0
	v_addc_co_u32_e32 v11, vcc, 0, v9, vcc
	global_load_dword v38, v[10:11], off nt
	v_add_co_u32_e32 v10, vcc, s0, v8
	s_mov_b32 s0, 0x5c000
	s_nop 0
	v_addc_co_u32_e32 v11, vcc, 0, v9, vcc
	global_load_dword v39, v[10:11], off nt
	v_add_co_u32_e32 v10, vcc, s0, v8
	s_mov_b32 s0, 0x60000
	s_nop 0
	v_addc_co_u32_e32 v11, vcc, 0, v9, vcc
	global_load_dword v40, v[10:11], off nt
	v_add_co_u32_e32 v10, vcc, s0, v8
	s_mov_b32 s0, 0x64000
	s_nop 0
	v_addc_co_u32_e32 v11, vcc, 0, v9, vcc
	global_load_dword v41, v[10:11], off nt
	v_add_co_u32_e32 v10, vcc, s0, v8
	s_mov_b32 s0, 0x68000
	s_nop 0
	v_addc_co_u32_e32 v11, vcc, 0, v9, vcc
	global_load_dword v42, v[10:11], off nt
	v_add_co_u32_e32 v10, vcc, s0, v8
	s_mov_b32 s0, 0x6c000
	s_nop 0
	v_addc_co_u32_e32 v11, vcc, 0, v9, vcc
	global_load_dword v43, v[10:11], off nt
	v_add_co_u32_e32 v10, vcc, s0, v8
	s_mov_b32 s0, 0x70000
	s_nop 0
	v_addc_co_u32_e32 v11, vcc, 0, v9, vcc
	global_load_dword v44, v[10:11], off nt
	v_add_co_u32_e32 v10, vcc, s0, v8
	s_mov_b32 s0, 0x74000
	s_nop 0
	v_addc_co_u32_e32 v11, vcc, 0, v9, vcc
	global_load_dword v45, v[10:11], off nt
	v_add_co_u32_e32 v10, vcc, s0, v8
	s_mov_b32 s0, 0x78000
	s_nop 0
	v_addc_co_u32_e32 v11, vcc, 0, v9, vcc
	global_load_dword v46, v[10:11], off nt
	v_add_co_u32_e32 v10, vcc, s0, v8
	s_mov_b32 s0, 0x7c000
	s_nop 0
	v_addc_co_u32_e32 v11, vcc, 0, v9, vcc
	v_add_co_u32_e32 v8, vcc, s0, v8
	global_load_dword v10, v[10:11], off nt
	s_nop 0
	v_addc_co_u32_e32 v9, vcc, 0, v9, vcc
	global_load_dword v8, v[8:9], off nt
	v_add_u32_e32 v9, 0x400, v5
	s_waitcnt vmcnt(0)
	ds_write2_b32 v5, v17, v18 offset1:66
	ds_write2_b32 v5, v19, v20 offset0:132 offset1:198
	ds_write2_b32 v9, v21, v22 offset0:8 offset1:74
	ds_write2_b32 v9, v23, v24 offset0:140 offset1:206
	v_add_u32_e32 v9, 0x800, v5
	ds_write2_b32 v9, v25, v26 offset0:16 offset1:82
	ds_write2_b32 v9, v27, v28 offset0:148 offset1:214
	v_add_u32_e32 v9, 0xc00, v5
	ds_write2_b32 v9, v29, v30 offset0:24 offset1:90
	ds_write2_b32 v9, v31, v32 offset0:156 offset1:222
	v_add_u32_e32 v9, 0x1000, v5
	ds_write2_b32 v9, v33, v34 offset0:32 offset1:98
	ds_write2_b32 v9, v35, v36 offset0:164 offset1:230
	v_add_u32_e32 v9, 0x1400, v5
	ds_write2_b32 v9, v37, v38 offset0:40 offset1:106
	ds_write2_b32 v9, v39, v40 offset0:172 offset1:238
	v_add_u32_e32 v9, 0x1800, v5
	ds_write2_b32 v9, v41, v42 offset0:48 offset1:114
	ds_write2_b32 v9, v43, v44 offset0:180 offset1:246
	v_add_u32_e32 v9, 0x1c00, v5
	ds_write2_b32 v9, v45, v46 offset0:56 offset1:122
	ds_write2_b32 v9, v10, v8 offset0:188 offset1:254
	s_waitcnt lgkmcnt(0)
	ds_read2_b32 v[10:11], v13 offset0:33 offset1:41
	ds_read2_b32 v[22:23], v13 offset1:8
	ds_read2_b32 v[24:25], v13 offset0:66 offset1:74
	ds_read2_b32 v[26:27], v13 offset0:99 offset1:107
	ds_read2_b32 v[28:29], v13 offset0:132 offset1:140
	ds_read2_b32 v[30:31], v13 offset0:165 offset1:173
	ds_read2_b32 v[32:33], v13 offset0:198 offset1:206
	ds_read2_b32 v[34:35], v13 offset0:231 offset1:239
	s_waitcnt lgkmcnt(7)
	v_bfe_u32 v18, v10, 16, 1
	s_waitcnt lgkmcnt(6)
	v_bfe_u32 v17, v22, 16, 1
	v_add3_u32 v17, v22, v17, s53
	v_lshrrev_b32_e32 v17, 16, v17
	v_add3_u32 v10, v10, v18, s53
	v_and_or_b32 v18, v10, s77, v17
	s_waitcnt lgkmcnt(5)
	v_bfe_u32 v10, v24, 16, 1
	v_add3_u32 v10, v24, v10, s53
	s_waitcnt lgkmcnt(4)
	v_bfe_u32 v17, v26, 16, 1
	v_lshrrev_b32_e32 v10, 16, v10
	v_add3_u32 v17, v26, v17, s53
	v_and_or_b32 v19, v17, s77, v10
	s_waitcnt lgkmcnt(3)
	v_bfe_u32 v10, v28, 16, 1
	v_add3_u32 v10, v28, v10, s53
	s_waitcnt lgkmcnt(2)
	v_bfe_u32 v17, v30, 16, 1
	v_lshrrev_b32_e32 v10, 16, v10
	v_add3_u32 v17, v30, v17, s53
	v_and_or_b32 v20, v17, s77, v10
	s_waitcnt lgkmcnt(1)
	v_bfe_u32 v10, v32, 16, 1
	v_add3_u32 v10, v32, v10, s53
	s_waitcnt lgkmcnt(0)
	v_bfe_u32 v17, v34, 16, 1
	s_lshl_b32 s0, s14, 1
	v_lshrrev_b32_e32 v10, 16, v10
	v_add3_u32 v17, v34, v17, s53
	s_add_u32 s0, s3, s0
	v_and_or_b32 v21, v17, s77, v10
	v_or_b32_e32 v10, s2, v12
	s_addc_u32 s1, s11, 0
	v_lshlrev_b32_e32 v202, 1, v4
	v_mul_u32_u24_e32 v10, 0x1600, v10
	v_lshl_add_u64 v[8:9], s[0:1], 0, v[202:203]
	v_lshlrev_b32_e32 v202, 1, v10
	v_bfe_u32 v10, v23, 16, 1
	v_add3_u32 v10, v23, v10, s53
	v_bfe_u32 v17, v11, 16, 1
	v_lshl_add_u64 v[36:37], v[8:9], 0, v[202:203]
	v_lshrrev_b32_e32 v10, 16, v10
	v_add3_u32 v11, v11, v17, s53
	global_store_dwordx4 v[36:37], v[18:21], off nt
	v_readlane_b32 s17, v251, 15
	v_readlane_b32 s18, v251, 16
	v_and_or_b32 v18, v11, s77, v10
	v_bfe_u32 v10, v25, 16, 1
	v_add3_u32 v10, v25, v10, s53
	v_bfe_u32 v11, v27, 16, 1
	v_lshrrev_b32_e32 v10, 16, v10
	v_add3_u32 v11, v27, v11, s53
	v_and_or_b32 v19, v11, s77, v10
	v_bfe_u32 v10, v29, 16, 1
	v_add3_u32 v10, v29, v10, s53
	v_bfe_u32 v11, v31, 16, 1
	v_lshrrev_b32_e32 v10, 16, v10
	v_add3_u32 v11, v31, v11, s53
	v_and_or_b32 v20, v11, s77, v10
	v_bfe_u32 v10, v33, 16, 1
	v_add3_u32 v10, v33, v10, s53
	v_bfe_u32 v11, v35, 16, 1
	v_lshrrev_b32_e32 v10, 16, v10
	v_add3_u32 v11, v35, v11, s53
	v_and_or_b32 v21, v11, s77, v10
	v_or_b32_e32 v10, s2, v14
	v_mul_u32_u24_e32 v10, 0x1600, v10
	v_lshlrev_b32_e32 v202, 1, v10
	v_lshl_add_u64 v[10:11], v[8:9], 0, v[202:203]
	global_store_dwordx4 v[10:11], v[18:21], off nt
	ds_read2_b32 v[10:11], v13 offset0:16 offset1:24
	ds_read2_b32 v[22:23], v13 offset0:49 offset1:57
	ds_read2_b32 v[24:25], v13 offset0:82 offset1:90
	ds_read2_b32 v[26:27], v13 offset0:115 offset1:123
	ds_read2_b32 v[28:29], v13 offset0:148 offset1:156
	ds_read2_b32 v[30:31], v13 offset0:181 offset1:189
	ds_read2_b32 v[32:33], v13 offset0:214 offset1:222
	ds_read2_b32 v[34:35], v13 offset0:247 offset1:255
	s_waitcnt lgkmcnt(7)
	v_bfe_u32 v17, v10, 16, 1
	v_add3_u32 v10, v10, v17, s53
	s_waitcnt lgkmcnt(6)
	v_bfe_u32 v17, v22, 16, 1
	v_lshrrev_b32_e32 v10, 16, v10
	v_add3_u32 v17, v22, v17, s53
	v_and_or_b32 v18, v17, s77, v10
	s_waitcnt lgkmcnt(5)
	v_bfe_u32 v10, v24, 16, 1
	v_add3_u32 v10, v24, v10, s53
	s_waitcnt lgkmcnt(4)
	v_bfe_u32 v17, v26, 16, 1
	v_lshrrev_b32_e32 v10, 16, v10
	v_add3_u32 v17, v26, v17, s53
	v_and_or_b32 v19, v17, s77, v10
	s_waitcnt lgkmcnt(3)
	v_bfe_u32 v10, v28, 16, 1
	v_add3_u32 v10, v28, v10, s53
	s_waitcnt lgkmcnt(2)
	v_bfe_u32 v17, v30, 16, 1
	v_lshrrev_b32_e32 v10, 16, v10
	v_add3_u32 v17, v30, v17, s53
	v_and_or_b32 v20, v17, s77, v10
	s_waitcnt lgkmcnt(1)
	v_bfe_u32 v10, v32, 16, 1
	v_add3_u32 v10, v32, v10, s53
	s_waitcnt lgkmcnt(0)
	v_bfe_u32 v17, v34, 16, 1
	v_lshrrev_b32_e32 v10, 16, v10
	v_add3_u32 v17, v34, v17, s53
	v_and_or_b32 v21, v17, s77, v10
	v_or_b32_e32 v10, s2, v15
	v_mul_u32_u24_e32 v10, 0x1600, v10
	v_lshlrev_b32_e32 v202, 1, v10
	v_bfe_u32 v10, v11, 16, 1
	v_add3_u32 v10, v11, v10, s53
	v_bfe_u32 v11, v23, 16, 1
	v_lshl_add_u64 v[36:37], v[8:9], 0, v[202:203]
	v_lshrrev_b32_e32 v10, 16, v10
	v_add3_u32 v11, v23, v11, s53
	global_store_dwordx4 v[36:37], v[18:21], off nt
	v_readlane_b32 s19, v251, 17
	v_readlane_b32 s22, v251, 20
	v_and_or_b32 v18, v11, s77, v10
	v_bfe_u32 v10, v25, 16, 1
	v_add3_u32 v10, v25, v10, s53
	v_bfe_u32 v11, v27, 16, 1
	v_lshrrev_b32_e32 v10, 16, v10
	v_add3_u32 v11, v27, v11, s53
	v_and_or_b32 v19, v11, s77, v10
	v_bfe_u32 v10, v29, 16, 1
	v_add3_u32 v10, v29, v10, s53
	v_bfe_u32 v11, v31, 16, 1
	v_lshrrev_b32_e32 v10, 16, v10
	v_add3_u32 v11, v31, v11, s53
	v_and_or_b32 v20, v11, s77, v10
	v_bfe_u32 v10, v33, 16, 1
	v_add3_u32 v10, v33, v10, s53
	v_bfe_u32 v11, v35, 16, 1
	v_lshrrev_b32_e32 v10, 16, v10
	v_add3_u32 v11, v35, v11, s53
	v_and_or_b32 v21, v11, s77, v10
	v_or_b32_e32 v10, s2, v16
	v_mul_u32_u24_e32 v10, 0x1600, v10
	v_lshlrev_b32_e32 v202, 1, v10
	v_lshl_add_u64 v[8:9], v[8:9], 0, v[202:203]
	global_store_dwordx4 v[8:9], v[18:21], off nt
	s_waitcnt lgkmcnt(0)
	v_readlane_b32 s23, v251, 21
	v_readlane_b32 s24, v251, 22
	v_readlane_b32 s25, v251, 23
	v_readlane_b32 s26, v251, 24
	v_readlane_b32 s27, v251, 25
	v_readlane_b32 s28, v251, 26
	v_readlane_b32 s29, v251, 27
	v_readlane_b32 s30, v251, 28
	v_readlane_b32 s31, v251, 29
	s_mov_b64 s[2:3], 0
.LBB0_1473:
	s_andn2_b64 vcc, exec, s[2:3]
	s_cbranch_vccnz .LBB0_1475
	v_readlane_b32 s16, v251, 14
	v_readlane_b32 s18, v251, 16
	v_readlane_b32 s19, v251, 17
	s_add_u32 s0, s18, s10
	s_addc_u32 s1, s19, s9
	v_readlane_b32 s2, v251, 56
	s_add_u32 s3, s2, s10
	v_readlane_b32 s2, v251, 57
	s_addc_u32 s11, s2, s9
	s_and_b32 s2, 0xffff, s5
	s_mul_i32 s2, s2, 0xba2f
	s_lshr_b32 s14, s2, 23
	s_mul_i32 s2, s14, 0xb0
	s_sub_i32 s2, s5, s2
	s_and_b32 s15, s2, 0xffff
	s_lshl_b32 s2, s15, 5
	s_lshl_b32 s16, s15, 6
	s_and_b32 s16, s16, 0x3f00
	s_and_b32 s2, s2, 0x60
	s_or_b32 s2, s16, s2
	s_bitset1_b32 s2, 7
	s_lshl_b32 s15, s15, 7
	v_lshl_or_b32 v10, s14, 6, v3
	s_add_u32 s0, s0, s15
	s_addc_u32 s1, s1, 0
	v_lshlrev_b32_e32 v202, 2, v2
	v_mul_u32_u24_e32 v10, 0x1600, v10
	v_lshl_add_u64 v[8:9], s[0:1], 0, v[202:203]
	v_lshlrev_b32_e32 v202, 2, v10
	v_lshl_add_u64 v[8:9], v[8:9], 0, v[202:203]
	s_mov_b32 s0, 0xb000
	v_add_co_u32_e32 v10, vcc, s0, v8
	s_mov_b32 s0, 0x16000
	s_nop 0
	v_addc_co_u32_e32 v11, vcc, 0, v9, vcc
	global_load_dword v17, v[8:9], off nt
	global_load_dword v18, v[10:11], off nt
	v_add_co_u32_e32 v10, vcc, s0, v8
	s_mov_b32 s0, 0x21000
	s_nop 0
	v_addc_co_u32_e32 v11, vcc, 0, v9, vcc
	global_load_dword v19, v[10:11], off nt
	v_add_co_u32_e32 v10, vcc, s0, v8
	s_mov_b32 s0, 0x2c000
	s_nop 0
	v_addc_co_u32_e32 v11, vcc, 0, v9, vcc
	global_load_dword v20, v[10:11], off nt
	v_add_co_u32_e32 v10, vcc, s0, v8
	s_mov_b32 s0, 0x37000
	s_nop 0
	v_addc_co_u32_e32 v11, vcc, 0, v9, vcc
	global_load_dword v21, v[10:11], off nt
	v_add_co_u32_e32 v10, vcc, s0, v8
	s_mov_b32 s0, 0x42000
	s_nop 0
	v_addc_co_u32_e32 v11, vcc, 0, v9, vcc
	global_load_dword v22, v[10:11], off nt
	v_add_co_u32_e32 v10, vcc, s0, v8
	s_mov_b32 s0, 0x4d000
	s_nop 0
	v_addc_co_u32_e32 v11, vcc, 0, v9, vcc
	global_load_dword v23, v[10:11], off nt
	v_add_co_u32_e32 v10, vcc, s0, v8
	s_mov_b32 s0, 0x58000
	s_nop 0
	v_addc_co_u32_e32 v11, vcc, 0, v9, vcc
	global_load_dword v24, v[10:11], off nt
	v_add_co_u32_e32 v10, vcc, s0, v8
	s_mov_b32 s0, 0x63000
	s_nop 0
	v_addc_co_u32_e32 v11, vcc, 0, v9, vcc
	global_load_dword v25, v[10:11], off nt
	v_add_co_u32_e32 v10, vcc, s0, v8
	s_mov_b32 s0, 0x6e000
	s_nop 0
	v_addc_co_u32_e32 v11, vcc, 0, v9, vcc
	global_load_dword v26, v[10:11], off nt
	v_add_co_u32_e32 v10, vcc, s0, v8
	s_mov_b32 s0, 0x79000
	s_nop 0
	v_addc_co_u32_e32 v11, vcc, 0, v9, vcc
	global_load_dword v27, v[10:11], off nt
	v_add_co_u32_e32 v10, vcc, s0, v8
	s_mov_b32 s0, 0x84000
	s_nop 0
	v_addc_co_u32_e32 v11, vcc, 0, v9, vcc
	global_load_dword v28, v[10:11], off nt
	v_add_co_u32_e32 v10, vcc, s0, v8
	s_mov_b32 s0, 0x8f000
	s_nop 0
	v_addc_co_u32_e32 v11, vcc, 0, v9, vcc
	global_load_dword v29, v[10:11], off nt
	v_add_co_u32_e32 v10, vcc, s0, v8
	s_mov_b32 s0, 0x9a000
	s_nop 0
	v_addc_co_u32_e32 v11, vcc, 0, v9, vcc
	global_load_dword v30, v[10:11], off nt
	v_add_co_u32_e32 v10, vcc, s0, v8
	s_mov_b32 s0, 0xa5000
	s_nop 0
	v_addc_co_u32_e32 v11, vcc, 0, v9, vcc
	global_load_dword v31, v[10:11], off nt
	v_add_co_u32_e32 v10, vcc, s0, v8
	s_mov_b32 s0, 0xb0000
	s_nop 0
	v_addc_co_u32_e32 v11, vcc, 0, v9, vcc
	global_load_dword v32, v[10:11], off nt
	v_add_co_u32_e32 v10, vcc, s0, v8
	s_mov_b32 s0, 0xbb000
	s_nop 0
	v_addc_co_u32_e32 v11, vcc, 0, v9, vcc
	global_load_dword v33, v[10:11], off nt
	v_add_co_u32_e32 v10, vcc, s0, v8
	s_mov_b32 s0, 0xc6000
	s_nop 0
	v_addc_co_u32_e32 v11, vcc, 0, v9, vcc
	global_load_dword v34, v[10:11], off nt
	v_add_co_u32_e32 v10, vcc, s0, v8
	s_mov_b32 s0, 0xd1000
	s_nop 0
	v_addc_co_u32_e32 v11, vcc, 0, v9, vcc
	global_load_dword v35, v[10:11], off nt
	v_add_co_u32_e32 v10, vcc, s0, v8
	s_mov_b32 s0, 0xdc000
	s_nop 0
	v_addc_co_u32_e32 v11, vcc, 0, v9, vcc
	global_load_dword v36, v[10:11], off nt
	v_add_co_u32_e32 v10, vcc, s0, v8
	s_mov_b32 s0, 0xe7000
	s_nop 0
	v_addc_co_u32_e32 v11, vcc, 0, v9, vcc
	global_load_dword v37, v[10:11], off nt
	v_add_co_u32_e32 v10, vcc, s0, v8
	s_mov_b32 s0, 0xf2000
	s_nop 0
	v_addc_co_u32_e32 v11, vcc, 0, v9, vcc
	global_load_dword v38, v[10:11], off nt
	v_add_co_u32_e32 v10, vcc, s0, v8
	s_mov_b32 s0, 0xfd000
	s_nop 0
	v_addc_co_u32_e32 v11, vcc, 0, v9, vcc
	global_load_dword v39, v[10:11], off nt
	v_add_co_u32_e32 v10, vcc, s0, v8
	s_mov_b32 s0, 0x108000
	s_nop 0
	v_addc_co_u32_e32 v11, vcc, 0, v9, vcc
	global_load_dword v40, v[10:11], off nt
	v_add_co_u32_e32 v10, vcc, s0, v8
	s_mov_b32 s0, 0x113000
	s_nop 0
	v_addc_co_u32_e32 v11, vcc, 0, v9, vcc
	global_load_dword v41, v[10:11], off nt
	v_add_co_u32_e32 v10, vcc, s0, v8
	s_mov_b32 s0, 0x11e000
	s_nop 0
	v_addc_co_u32_e32 v11, vcc, 0, v9, vcc
	global_load_dword v42, v[10:11], off nt
	v_add_co_u32_e32 v10, vcc, s0, v8
	s_mov_b32 s0, 0x129000
	s_nop 0
	v_addc_co_u32_e32 v11, vcc, 0, v9, vcc
	global_load_dword v43, v[10:11], off nt
	v_add_co_u32_e32 v10, vcc, s0, v8
	s_mov_b32 s0, 0x134000
	s_nop 0
	v_addc_co_u32_e32 v11, vcc, 0, v9, vcc
	global_load_dword v44, v[10:11], off nt
	v_add_co_u32_e32 v10, vcc, s0, v8
	s_mov_b32 s0, 0x13f000
	s_nop 0
	v_addc_co_u32_e32 v11, vcc, 0, v9, vcc
	global_load_dword v45, v[10:11], off nt
	v_add_co_u32_e32 v10, vcc, s0, v8
	s_mov_b32 s0, 0x14a000
	s_nop 0
	v_addc_co_u32_e32 v11, vcc, 0, v9, vcc
	global_load_dword v46, v[10:11], off nt
	v_add_co_u32_e32 v10, vcc, s0, v8
	s_mov_b32 s0, 0x155000
	s_nop 0
	v_addc_co_u32_e32 v11, vcc, 0, v9, vcc
	v_add_co_u32_e32 v8, vcc, s0, v8
	global_load_dword v10, v[10:11], off nt
	s_nop 0
	v_addc_co_u32_e32 v9, vcc, 0, v9, vcc
	global_load_dword v8, v[8:9], off nt
	v_add_u32_e32 v9, 0x400, v5
	s_waitcnt vmcnt(0)
	ds_write2_b32 v5, v17, v18 offset1:66
	ds_write2_b32 v5, v19, v20 offset0:132 offset1:198
	ds_write2_b32 v9, v21, v22 offset0:8 offset1:74
	ds_write2_b32 v9, v23, v24 offset0:140 offset1:206
	v_add_u32_e32 v9, 0x800, v5
	ds_write2_b32 v9, v25, v26 offset0:16 offset1:82
	ds_write2_b32 v9, v27, v28 offset0:148 offset1:214
	v_add_u32_e32 v9, 0xc00, v5
	ds_write2_b32 v9, v29, v30 offset0:24 offset1:90
	ds_write2_b32 v9, v31, v32 offset0:156 offset1:222
	v_add_u32_e32 v9, 0x1000, v5
	ds_write2_b32 v9, v33, v34 offset0:32 offset1:98
	ds_write2_b32 v9, v35, v36 offset0:164 offset1:230
	v_add_u32_e32 v9, 0x1400, v5
	ds_write2_b32 v9, v37, v38 offset0:40 offset1:106
	ds_write2_b32 v9, v39, v40 offset0:172 offset1:238
	v_add_u32_e32 v9, 0x1800, v5
	ds_write2_b32 v9, v41, v42 offset0:48 offset1:114
	ds_write2_b32 v9, v43, v44 offset0:180 offset1:246
	v_add_u32_e32 v9, 0x1c00, v5
	ds_write2_b32 v9, v45, v46 offset0:56 offset1:122
	ds_write2_b32 v9, v10, v8 offset0:188 offset1:254
	s_waitcnt lgkmcnt(0)
	ds_read2_b32 v[10:11], v13 offset0:33 offset1:41
	ds_read2_b32 v[22:23], v13 offset1:8
	ds_read2_b32 v[24:25], v13 offset0:66 offset1:74
	ds_read2_b32 v[26:27], v13 offset0:99 offset1:107
	ds_read2_b32 v[28:29], v13 offset0:132 offset1:140
	ds_read2_b32 v[30:31], v13 offset0:165 offset1:173
	ds_read2_b32 v[32:33], v13 offset0:198 offset1:206
	ds_read2_b32 v[34:35], v13 offset0:231 offset1:239
	s_waitcnt lgkmcnt(7)
	v_bfe_u32 v18, v10, 16, 1
	s_waitcnt lgkmcnt(6)
	v_bfe_u32 v17, v22, 16, 1
	v_add3_u32 v17, v22, v17, s53
	v_lshrrev_b32_e32 v17, 16, v17
	v_add3_u32 v10, v10, v18, s53
	v_and_or_b32 v18, v10, s77, v17
	s_waitcnt lgkmcnt(5)
	v_bfe_u32 v10, v24, 16, 1
	v_add3_u32 v10, v24, v10, s53
	s_waitcnt lgkmcnt(4)
	v_bfe_u32 v17, v26, 16, 1
	v_lshrrev_b32_e32 v10, 16, v10
	v_add3_u32 v17, v26, v17, s53
	v_and_or_b32 v19, v17, s77, v10
	s_waitcnt lgkmcnt(3)
	v_bfe_u32 v10, v28, 16, 1
	v_add3_u32 v10, v28, v10, s53
	s_waitcnt lgkmcnt(2)
	v_bfe_u32 v17, v30, 16, 1
	v_lshrrev_b32_e32 v10, 16, v10
	v_add3_u32 v17, v30, v17, s53
	v_and_or_b32 v20, v17, s77, v10
	s_waitcnt lgkmcnt(1)
	v_bfe_u32 v10, v32, 16, 1
	s_lshl_b32 s0, s14, 7
	v_add3_u32 v10, v32, v10, s53
	s_waitcnt lgkmcnt(0)
	v_bfe_u32 v17, v34, 16, 1
	s_add_u32 s0, s3, s0
	v_lshrrev_b32_e32 v10, 16, v10
	v_add3_u32 v17, v34, v17, s53
	s_addc_u32 s1, s11, 0
	v_lshlrev_b32_e32 v202, 1, v4
	v_and_or_b32 v21, v17, s77, v10
	v_or_b32_e32 v10, s2, v12
	v_lshl_add_u64 v[8:9], s[0:1], 0, v[202:203]
	v_lshlrev_b32_e32 v202, 12, v10
	v_bfe_u32 v10, v23, 16, 1
	v_add3_u32 v10, v23, v10, s53
	v_bfe_u32 v17, v11, 16, 1
	v_lshl_add_u64 v[36:37], v[8:9], 0, v[202:203]
	v_lshrrev_b32_e32 v10, 16, v10
	v_add3_u32 v11, v11, v17, s53
	global_store_dwordx4 v[36:37], v[18:21], off nt
	v_readlane_b32 s17, v251, 15
	v_readlane_b32 s20, v251, 18
	v_and_or_b32 v18, v11, s77, v10
	v_bfe_u32 v10, v25, 16, 1
	v_add3_u32 v10, v25, v10, s53
	v_bfe_u32 v11, v27, 16, 1
	v_lshrrev_b32_e32 v10, 16, v10
	v_add3_u32 v11, v27, v11, s53
	v_and_or_b32 v19, v11, s77, v10
	v_bfe_u32 v10, v29, 16, 1
	v_add3_u32 v10, v29, v10, s53
	v_bfe_u32 v11, v31, 16, 1
	v_lshrrev_b32_e32 v10, 16, v10
	v_add3_u32 v11, v31, v11, s53
	v_and_or_b32 v20, v11, s77, v10
	v_bfe_u32 v10, v33, 16, 1
	v_add3_u32 v10, v33, v10, s53
	v_bfe_u32 v11, v35, 16, 1
	v_lshrrev_b32_e32 v10, 16, v10
	v_add3_u32 v11, v35, v11, s53
	v_and_or_b32 v21, v11, s77, v10
	v_or_b32_e32 v10, s2, v14
	v_lshlrev_b32_e32 v202, 12, v10
	v_lshl_add_u64 v[10:11], v[8:9], 0, v[202:203]
	global_store_dwordx4 v[10:11], v[18:21], off nt
	ds_read2_b32 v[10:11], v13 offset0:49 offset1:57
	ds_read2_b32 v[22:23], v13 offset0:16 offset1:24
	ds_read2_b32 v[24:25], v13 offset0:82 offset1:90
	ds_read2_b32 v[26:27], v13 offset0:115 offset1:123
	ds_read2_b32 v[28:29], v13 offset0:148 offset1:156
	ds_read2_b32 v[30:31], v13 offset0:181 offset1:189
	ds_read2_b32 v[32:33], v13 offset0:214 offset1:222
	ds_read2_b32 v[34:35], v13 offset0:247 offset1:255
	s_waitcnt lgkmcnt(7)
	v_bfe_u32 v18, v10, 16, 1
	s_waitcnt lgkmcnt(6)
	v_bfe_u32 v17, v22, 16, 1
	v_add3_u32 v17, v22, v17, s53
	v_lshrrev_b32_e32 v17, 16, v17
	v_add3_u32 v10, v10, v18, s53
	v_and_or_b32 v18, v10, s77, v17
	s_waitcnt lgkmcnt(5)
	v_bfe_u32 v10, v24, 16, 1
	v_add3_u32 v10, v24, v10, s53
	s_waitcnt lgkmcnt(4)
	v_bfe_u32 v17, v26, 16, 1
	v_lshrrev_b32_e32 v10, 16, v10
	v_add3_u32 v17, v26, v17, s53
	v_and_or_b32 v19, v17, s77, v10
	s_waitcnt lgkmcnt(3)
	v_bfe_u32 v10, v28, 16, 1
	v_add3_u32 v10, v28, v10, s53
	s_waitcnt lgkmcnt(2)
	v_bfe_u32 v17, v30, 16, 1
	v_lshrrev_b32_e32 v10, 16, v10
	v_add3_u32 v17, v30, v17, s53
	v_and_or_b32 v20, v17, s77, v10
	s_waitcnt lgkmcnt(1)
	v_bfe_u32 v10, v32, 16, 1
	v_add3_u32 v10, v32, v10, s53
	s_waitcnt lgkmcnt(0)
	v_bfe_u32 v17, v34, 16, 1
	v_lshrrev_b32_e32 v10, 16, v10
	v_add3_u32 v17, v34, v17, s53
	v_and_or_b32 v21, v17, s77, v10
	v_or_b32_e32 v10, s2, v15
	v_lshlrev_b32_e32 v202, 12, v10
	v_bfe_u32 v10, v23, 16, 1
	v_add3_u32 v10, v23, v10, s53
	v_bfe_u32 v17, v11, 16, 1
	v_lshl_add_u64 v[36:37], v[8:9], 0, v[202:203]
	v_lshrrev_b32_e32 v10, 16, v10
	v_add3_u32 v11, v11, v17, s53
	global_store_dwordx4 v[36:37], v[18:21], off nt
	v_readlane_b32 s21, v251, 19
	v_readlane_b32 s22, v251, 20
	v_and_or_b32 v18, v11, s77, v10
	v_bfe_u32 v10, v25, 16, 1
	v_add3_u32 v10, v25, v10, s53
	v_bfe_u32 v11, v27, 16, 1
	v_lshrrev_b32_e32 v10, 16, v10
	v_add3_u32 v11, v27, v11, s53
	v_and_or_b32 v19, v11, s77, v10
	v_bfe_u32 v10, v29, 16, 1
	v_add3_u32 v10, v29, v10, s53
	v_bfe_u32 v11, v31, 16, 1
	v_lshrrev_b32_e32 v10, 16, v10
	v_add3_u32 v11, v31, v11, s53
	v_and_or_b32 v20, v11, s77, v10
	v_bfe_u32 v10, v33, 16, 1
	v_add3_u32 v10, v33, v10, s53
	v_bfe_u32 v11, v35, 16, 1
	v_lshrrev_b32_e32 v10, 16, v10
	v_add3_u32 v11, v35, v11, s53
	v_and_or_b32 v21, v11, s77, v10
	v_or_b32_e32 v10, s2, v16
	v_lshlrev_b32_e32 v202, 12, v10
	v_lshl_add_u64 v[8:9], v[8:9], 0, v[202:203]
	global_store_dwordx4 v[8:9], v[18:21], off nt
	s_waitcnt lgkmcnt(0)
	v_readlane_b32 s23, v251, 21
	v_readlane_b32 s24, v251, 22
	v_readlane_b32 s25, v251, 23
	v_readlane_b32 s26, v251, 24
	v_readlane_b32 s27, v251, 25
	v_readlane_b32 s28, v251, 26
	v_readlane_b32 s29, v251, 27
	v_readlane_b32 s30, v251, 28
	v_readlane_b32 s31, v251, 29

.LBB0_1476:
	s_andn2_b64 vcc, exec, s[2:3]
	s_cbranch_vccnz .LBB0_1478
	v_readlane_b32 s16, v251, 14
	v_readlane_b32 s17, v251, 15
	s_add_u32 s0, s16, s10
	s_addc_u32 s1, s17, s9
	v_readlane_b32 s2, v251, 56
	s_add_u32 s3, s2, s10
	v_readlane_b32 s2, v251, 57
	s_addc_u32 s9, s2, s9
	s_and_b32 s2, 0xffff, s5
	s_mul_i32 s2, s2, 0xba2f
	s_lshr_b32 s10, s2, 23
	s_mul_i32 s2, s10, 0xb0
	s_sub_i32 s2, s5, s2
	s_and_b32 s5, s2, 0xffff
	s_lshl_b32 s2, s5, 5
	s_lshl_b32 s11, s5, 6
	s_and_b32 s11, s11, 0x3f00
	s_and_b32 s2, s2, 0x60
	s_or_b32 s2, s2, s11
	s_lshl_b32 s5, s5, 7
	v_lshl_or_b32 v10, s10, 6, v3
	s_add_u32 s0, s0, s5
	s_addc_u32 s1, s1, 0
	v_lshlrev_b32_e32 v202, 2, v2
	v_mul_u32_u24_e32 v10, 0x1600, v10
	v_lshl_add_u64 v[8:9], s[0:1], 0, v[202:203]
	v_lshlrev_b32_e32 v202, 2, v10
	v_lshl_add_u64 v[8:9], v[8:9], 0, v[202:203]
	s_mov_b32 s0, 0xb000
	v_add_co_u32_e32 v10, vcc, s0, v8
	s_mov_b32 s0, 0x16000
	s_nop 0
	v_addc_co_u32_e32 v11, vcc, 0, v9, vcc
	global_load_dword v17, v[8:9], off nt
	global_load_dword v18, v[10:11], off nt
	v_add_co_u32_e32 v10, vcc, s0, v8
	s_mov_b32 s0, 0x21000
	s_nop 0
	v_addc_co_u32_e32 v11, vcc, 0, v9, vcc
	global_load_dword v19, v[10:11], off nt
	v_add_co_u32_e32 v10, vcc, s0, v8
	s_mov_b32 s0, 0x2c000
	s_nop 0
	v_addc_co_u32_e32 v11, vcc, 0, v9, vcc
	global_load_dword v20, v[10:11], off nt
	v_add_co_u32_e32 v10, vcc, s0, v8
	s_mov_b32 s0, 0x37000
	s_nop 0
	v_addc_co_u32_e32 v11, vcc, 0, v9, vcc
	global_load_dword v21, v[10:11], off nt
	v_add_co_u32_e32 v10, vcc, s0, v8
	s_mov_b32 s0, 0x42000
	s_nop 0
	v_addc_co_u32_e32 v11, vcc, 0, v9, vcc
	global_load_dword v22, v[10:11], off nt
	v_add_co_u32_e32 v10, vcc, s0, v8
	s_mov_b32 s0, 0x4d000
	s_nop 0
	v_addc_co_u32_e32 v11, vcc, 0, v9, vcc
	global_load_dword v23, v[10:11], off nt
	v_add_co_u32_e32 v10, vcc, s0, v8
	s_mov_b32 s0, 0x58000
	s_nop 0
	v_addc_co_u32_e32 v11, vcc, 0, v9, vcc
	global_load_dword v24, v[10:11], off nt
	v_add_co_u32_e32 v10, vcc, s0, v8
	s_mov_b32 s0, 0x63000
	s_nop 0
	v_addc_co_u32_e32 v11, vcc, 0, v9, vcc
	global_load_dword v25, v[10:11], off nt
	v_add_co_u32_e32 v10, vcc, s0, v8
	s_mov_b32 s0, 0x6e000
	s_nop 0
	v_addc_co_u32_e32 v11, vcc, 0, v9, vcc
	global_load_dword v26, v[10:11], off nt
	v_add_co_u32_e32 v10, vcc, s0, v8
	s_mov_b32 s0, 0x79000
	s_nop 0
	v_addc_co_u32_e32 v11, vcc, 0, v9, vcc
	global_load_dword v27, v[10:11], off nt
	v_add_co_u32_e32 v10, vcc, s0, v8
	s_mov_b32 s0, 0x84000
	s_nop 0
	v_addc_co_u32_e32 v11, vcc, 0, v9, vcc
	global_load_dword v28, v[10:11], off nt
	v_add_co_u32_e32 v10, vcc, s0, v8
	s_mov_b32 s0, 0x8f000
	s_nop 0
	v_addc_co_u32_e32 v11, vcc, 0, v9, vcc
	global_load_dword v29, v[10:11], off nt
	v_add_co_u32_e32 v10, vcc, s0, v8
	s_mov_b32 s0, 0x9a000
	s_nop 0
	v_addc_co_u32_e32 v11, vcc, 0, v9, vcc
	global_load_dword v30, v[10:11], off nt
	v_add_co_u32_e32 v10, vcc, s0, v8
	s_mov_b32 s0, 0xa5000
	s_nop 0
	v_addc_co_u32_e32 v11, vcc, 0, v9, vcc
	global_load_dword v31, v[10:11], off nt
	v_add_co_u32_e32 v10, vcc, s0, v8
	s_mov_b32 s0, 0xb0000
	s_nop 0
	v_addc_co_u32_e32 v11, vcc, 0, v9, vcc
	global_load_dword v32, v[10:11], off nt
	v_add_co_u32_e32 v10, vcc, s0, v8
	s_mov_b32 s0, 0xbb000
	s_nop 0
	v_addc_co_u32_e32 v11, vcc, 0, v9, vcc
	global_load_dword v33, v[10:11], off nt
	v_add_co_u32_e32 v10, vcc, s0, v8
	s_mov_b32 s0, 0xc6000
	s_nop 0
	v_addc_co_u32_e32 v11, vcc, 0, v9, vcc
	global_load_dword v34, v[10:11], off nt
	v_add_co_u32_e32 v10, vcc, s0, v8
	s_mov_b32 s0, 0xd1000
	s_nop 0
	v_addc_co_u32_e32 v11, vcc, 0, v9, vcc
	global_load_dword v35, v[10:11], off nt
	v_add_co_u32_e32 v10, vcc, s0, v8
	s_mov_b32 s0, 0xdc000
	s_nop 0
	v_addc_co_u32_e32 v11, vcc, 0, v9, vcc
	global_load_dword v36, v[10:11], off nt
	v_add_co_u32_e32 v10, vcc, s0, v8
	s_mov_b32 s0, 0xe7000
	s_nop 0
	v_addc_co_u32_e32 v11, vcc, 0, v9, vcc
	global_load_dword v37, v[10:11], off nt
	v_add_co_u32_e32 v10, vcc, s0, v8
	s_mov_b32 s0, 0xf2000
	s_nop 0
	v_addc_co_u32_e32 v11, vcc, 0, v9, vcc
	global_load_dword v38, v[10:11], off nt
	v_add_co_u32_e32 v10, vcc, s0, v8
	s_mov_b32 s0, 0xfd000
	s_nop 0
	v_addc_co_u32_e32 v11, vcc, 0, v9, vcc
	global_load_dword v39, v[10:11], off nt
	v_add_co_u32_e32 v10, vcc, s0, v8
	s_mov_b32 s0, 0x108000
	s_nop 0
	v_addc_co_u32_e32 v11, vcc, 0, v9, vcc
	global_load_dword v40, v[10:11], off nt
	v_add_co_u32_e32 v10, vcc, s0, v8
	s_mov_b32 s0, 0x113000
	s_nop 0
	v_addc_co_u32_e32 v11, vcc, 0, v9, vcc
	global_load_dword v41, v[10:11], off nt
	v_add_co_u32_e32 v10, vcc, s0, v8
	s_mov_b32 s0, 0x11e000
	s_nop 0
	v_addc_co_u32_e32 v11, vcc, 0, v9, vcc
	global_load_dword v42, v[10:11], off nt
	v_add_co_u32_e32 v10, vcc, s0, v8
	s_mov_b32 s0, 0x129000
	s_nop 0
	v_addc_co_u32_e32 v11, vcc, 0, v9, vcc
	global_load_dword v43, v[10:11], off nt
	v_add_co_u32_e32 v10, vcc, s0, v8
	s_mov_b32 s0, 0x134000
	s_nop 0
	v_addc_co_u32_e32 v11, vcc, 0, v9, vcc
	global_load_dword v44, v[10:11], off nt
	v_add_co_u32_e32 v10, vcc, s0, v8
	s_mov_b32 s0, 0x13f000
	s_nop 0
	v_addc_co_u32_e32 v11, vcc, 0, v9, vcc
	global_load_dword v45, v[10:11], off nt
	v_add_co_u32_e32 v10, vcc, s0, v8
	s_mov_b32 s0, 0x14a000
	s_nop 0
	v_addc_co_u32_e32 v11, vcc, 0, v9, vcc
	global_load_dword v46, v[10:11], off nt
	v_add_co_u32_e32 v10, vcc, s0, v8
	s_mov_b32 s0, 0x155000
	s_nop 0
	v_addc_co_u32_e32 v11, vcc, 0, v9, vcc
	v_add_co_u32_e32 v8, vcc, s0, v8
	global_load_dword v10, v[10:11], off nt
	s_nop 0
	v_addc_co_u32_e32 v9, vcc, 0, v9, vcc
	global_load_dword v8, v[8:9], off nt
	v_add_u32_e32 v9, 0x400, v5
	s_waitcnt vmcnt(0)
	ds_write2_b32 v5, v17, v18 offset1:66
	ds_write2_b32 v5, v19, v20 offset0:132 offset1:198
	ds_write2_b32 v9, v21, v22 offset0:8 offset1:74
	ds_write2_b32 v9, v23, v24 offset0:140 offset1:206
	v_add_u32_e32 v9, 0x800, v5
	ds_write2_b32 v9, v25, v26 offset0:16 offset1:82
	ds_write2_b32 v9, v27, v28 offset0:148 offset1:214
	v_add_u32_e32 v9, 0xc00, v5
	ds_write2_b32 v9, v29, v30 offset0:24 offset1:90
	ds_write2_b32 v9, v31, v32 offset0:156 offset1:222
	v_add_u32_e32 v9, 0x1000, v5
	ds_write2_b32 v9, v33, v34 offset0:32 offset1:98
	ds_write2_b32 v9, v35, v36 offset0:164 offset1:230
	v_add_u32_e32 v9, 0x1400, v5
	ds_write2_b32 v9, v37, v38 offset0:40 offset1:106
	ds_write2_b32 v9, v39, v40 offset0:172 offset1:238
	v_add_u32_e32 v9, 0x1800, v5
	ds_write2_b32 v9, v41, v42 offset0:48 offset1:114
	ds_write2_b32 v9, v43, v44 offset0:180 offset1:246
	v_add_u32_e32 v9, 0x1c00, v5
	ds_write2_b32 v9, v45, v46 offset0:56 offset1:122
	ds_write2_b32 v9, v10, v8 offset0:188 offset1:254
	s_waitcnt lgkmcnt(0)
	ds_read2_b32 v[10:11], v13 offset0:33 offset1:41
	ds_read2_b32 v[22:23], v13 offset1:8
	ds_read2_b32 v[24:25], v13 offset0:66 offset1:74
	ds_read2_b32 v[26:27], v13 offset0:99 offset1:107
	ds_read2_b32 v[28:29], v13 offset0:132 offset1:140
	ds_read2_b32 v[30:31], v13 offset0:165 offset1:173
	ds_read2_b32 v[32:33], v13 offset0:198 offset1:206
	ds_read2_b32 v[34:35], v13 offset0:231 offset1:239
	s_waitcnt lgkmcnt(7)
	v_bfe_u32 v18, v10, 16, 1
	s_waitcnt lgkmcnt(6)
	v_bfe_u32 v17, v22, 16, 1
	v_add3_u32 v17, v22, v17, s53
	v_lshrrev_b32_e32 v17, 16, v17
	v_add3_u32 v10, v10, v18, s53
	v_and_or_b32 v18, v10, s77, v17
	s_waitcnt lgkmcnt(5)
	v_bfe_u32 v10, v24, 16, 1
	v_add3_u32 v10, v24, v10, s53
	s_waitcnt lgkmcnt(4)
	v_bfe_u32 v17, v26, 16, 1
	v_lshrrev_b32_e32 v10, 16, v10
	v_add3_u32 v17, v26, v17, s53
	v_and_or_b32 v19, v17, s77, v10
	s_waitcnt lgkmcnt(3)
	v_bfe_u32 v10, v28, 16, 1
	v_add3_u32 v10, v28, v10, s53
	s_waitcnt lgkmcnt(2)
	v_bfe_u32 v17, v30, 16, 1
	v_lshrrev_b32_e32 v10, 16, v10
	v_add3_u32 v17, v30, v17, s53
	v_and_or_b32 v20, v17, s77, v10
	s_waitcnt lgkmcnt(1)
	v_bfe_u32 v10, v32, 16, 1
	s_lshl_b32 s0, s10, 7
	v_add3_u32 v10, v32, v10, s53
	s_waitcnt lgkmcnt(0)
	v_bfe_u32 v17, v34, 16, 1
	s_add_u32 s0, s3, s0
	v_lshrrev_b32_e32 v10, 16, v10
	v_add3_u32 v17, v34, v17, s53
	s_addc_u32 s1, s9, 0
	v_lshlrev_b32_e32 v202, 1, v4
	v_and_or_b32 v21, v17, s77, v10
	v_or_b32_e32 v10, s2, v12
	v_lshl_add_u64 v[8:9], s[0:1], 0, v[202:203]
	v_lshlrev_b32_e32 v202, 12, v10
	v_bfe_u32 v10, v23, 16, 1
	v_add3_u32 v10, v23, v10, s53
	v_bfe_u32 v17, v11, 16, 1
	v_lshl_add_u64 v[36:37], v[8:9], 0, v[202:203]
	v_lshrrev_b32_e32 v10, 16, v10
	v_add3_u32 v11, v11, v17, s53
	global_store_dwordx4 v[36:37], v[18:21], off nt
	v_readlane_b32 s18, v251, 16
	v_readlane_b32 s19, v251, 17
	v_and_or_b32 v18, v11, s77, v10
	v_bfe_u32 v10, v25, 16, 1
	v_add3_u32 v10, v25, v10, s53
	v_bfe_u32 v11, v27, 16, 1
	v_lshrrev_b32_e32 v10, 16, v10
	v_add3_u32 v11, v27, v11, s53
	v_and_or_b32 v19, v11, s77, v10
	v_bfe_u32 v10, v29, 16, 1
	v_add3_u32 v10, v29, v10, s53
	v_bfe_u32 v11, v31, 16, 1
	v_lshrrev_b32_e32 v10, 16, v10
	v_add3_u32 v11, v31, v11, s53
	v_and_or_b32 v20, v11, s77, v10
	v_bfe_u32 v10, v33, 16, 1
	v_add3_u32 v10, v33, v10, s53
	v_bfe_u32 v11, v35, 16, 1
	v_lshrrev_b32_e32 v10, 16, v10
	v_add3_u32 v11, v35, v11, s53
	v_and_or_b32 v21, v11, s77, v10
	v_or_b32_e32 v10, s2, v14
	v_lshlrev_b32_e32 v202, 12, v10
	v_lshl_add_u64 v[10:11], v[8:9], 0, v[202:203]
	global_store_dwordx4 v[10:11], v[18:21], off nt
	ds_read2_b32 v[10:11], v13 offset0:49 offset1:57
	ds_read2_b32 v[22:23], v13 offset0:16 offset1:24
	ds_read2_b32 v[24:25], v13 offset0:82 offset1:90
	ds_read2_b32 v[26:27], v13 offset0:115 offset1:123
	ds_read2_b32 v[28:29], v13 offset0:148 offset1:156
	ds_read2_b32 v[30:31], v13 offset0:181 offset1:189
	ds_read2_b32 v[32:33], v13 offset0:214 offset1:222
	ds_read2_b32 v[34:35], v13 offset0:247 offset1:255
	s_waitcnt lgkmcnt(7)
	v_bfe_u32 v18, v10, 16, 1
	s_waitcnt lgkmcnt(6)
	v_bfe_u32 v17, v22, 16, 1
	v_add3_u32 v17, v22, v17, s53
	v_lshrrev_b32_e32 v17, 16, v17
	v_add3_u32 v10, v10, v18, s53
	v_and_or_b32 v18, v10, s77, v17
	s_waitcnt lgkmcnt(5)
	v_bfe_u32 v10, v24, 16, 1
	v_add3_u32 v10, v24, v10, s53
	s_waitcnt lgkmcnt(4)
	v_bfe_u32 v17, v26, 16, 1
	v_lshrrev_b32_e32 v10, 16, v10
	v_add3_u32 v17, v26, v17, s53
	v_and_or_b32 v19, v17, s77, v10
	s_waitcnt lgkmcnt(3)
	v_bfe_u32 v10, v28, 16, 1
	v_add3_u32 v10, v28, v10, s53
	s_waitcnt lgkmcnt(2)
	v_bfe_u32 v17, v30, 16, 1
	v_lshrrev_b32_e32 v10, 16, v10
	v_add3_u32 v17, v30, v17, s53
	v_and_or_b32 v20, v17, s77, v10
	s_waitcnt lgkmcnt(1)
	v_bfe_u32 v10, v32, 16, 1
	v_add3_u32 v10, v32, v10, s53
	s_waitcnt lgkmcnt(0)
	v_bfe_u32 v17, v34, 16, 1
	v_lshrrev_b32_e32 v10, 16, v10
	v_add3_u32 v17, v34, v17, s53
	v_and_or_b32 v21, v17, s77, v10
	v_or_b32_e32 v10, s2, v15
	v_lshlrev_b32_e32 v202, 12, v10
	v_bfe_u32 v10, v23, 16, 1
	v_add3_u32 v10, v23, v10, s53
	v_bfe_u32 v17, v11, 16, 1
	v_lshl_add_u64 v[36:37], v[8:9], 0, v[202:203]
	v_lshrrev_b32_e32 v10, 16, v10
	v_add3_u32 v11, v11, v17, s53
	global_store_dwordx4 v[36:37], v[18:21], off nt
	v_readlane_b32 s20, v251, 18
	v_readlane_b32 s21, v251, 19
	v_and_or_b32 v18, v11, s77, v10
	v_bfe_u32 v10, v25, 16, 1
	v_add3_u32 v10, v25, v10, s53
	v_bfe_u32 v11, v27, 16, 1
	v_lshrrev_b32_e32 v10, 16, v10
	v_add3_u32 v11, v27, v11, s53
	v_and_or_b32 v19, v11, s77, v10
	v_bfe_u32 v10, v29, 16, 1
	v_add3_u32 v10, v29, v10, s53
	v_bfe_u32 v11, v31, 16, 1
	v_lshrrev_b32_e32 v10, 16, v10
	v_add3_u32 v11, v31, v11, s53
	v_and_or_b32 v20, v11, s77, v10
	v_bfe_u32 v10, v33, 16, 1
	v_add3_u32 v10, v33, v10, s53
	v_bfe_u32 v11, v35, 16, 1
	v_lshrrev_b32_e32 v10, 16, v10
	v_add3_u32 v11, v35, v11, s53
	v_and_or_b32 v21, v11, s77, v10
	v_or_b32_e32 v10, s2, v16
	v_lshlrev_b32_e32 v202, 12, v10
	v_lshl_add_u64 v[8:9], v[8:9], 0, v[202:203]
	global_store_dwordx4 v[8:9], v[18:21], off nt
	s_waitcnt lgkmcnt(0)
	v_readlane_b32 s22, v251, 20
	v_readlane_b32 s23, v251, 21
	v_readlane_b32 s24, v251, 22
	v_readlane_b32 s25, v251, 23
	v_readlane_b32 s26, v251, 24
	v_readlane_b32 s27, v251, 25
	v_readlane_b32 s28, v251, 26
	v_readlane_b32 s29, v251, 27
	v_readlane_b32 s30, v251, 28
	v_readlane_b32 s31, v251, 29

.LBB0_1479:
	s_andn2_b64 vcc, exec, s[2:3]
	s_cbranch_vccnz .LBB0_1481
	s_add_i32 s0, s4, 0xffffc000
	s_lshr_b32 s86, s0, 12
	s_lshl_b64 s[0:1], s[86:87], 25
	v_readlane_b32 s16, v251, 30
	v_readlane_b32 s17, v251, 31
	s_add_u32 s10, s16, s0
	s_addc_u32 s11, s17, s1
	s_lshl_b64 s[0:1], s[86:87], 24
	v_readlane_b32 s2, v251, 58
	s_add_u32 s3, s2, s0
	v_readlane_b32 s0, v251, 59
	s_addc_u32 s5, s0, s1
	s_lshl_b32 s0, s4, 5
	s_and_b32 s2, s0, 0x7e0
	s_and_b32 s9, s4, 0xfc0
	s_lshl_b32 s0, s2, 2
	s_add_u32 s0, s10, s0
	v_or_b32_e32 v10, s9, v3
	s_addc_u32 s1, s11, 0
	v_lshlrev_b32_e32 v202, 2, v2
	v_lshl_add_u64 v[8:9], s[0:1], 0, v[202:203]
	v_lshlrev_b32_e32 v202, 13, v10
	v_lshl_add_u64 v[8:9], v[8:9], 0, v[202:203]
	v_add_co_u32_e32 v10, vcc, s89, v8
	s_mov_b32 s0, 0x8000
	s_nop 0
	v_addc_co_u32_e32 v11, vcc, 0, v9, vcc
	global_load_dword v17, v[8:9], off nt
	global_load_dword v18, v[10:11], off nt
	v_add_co_u32_e32 v10, vcc, s0, v8
	s_mov_b32 s0, 0xc000
	s_nop 0
	v_addc_co_u32_e32 v11, vcc, 0, v9, vcc
	global_load_dword v19, v[10:11], off nt
	v_add_co_u32_e32 v10, vcc, s0, v8
	s_mov_b32 s0, 0x10000
	s_nop 0
	v_addc_co_u32_e32 v11, vcc, 0, v9, vcc
	global_load_dword v20, v[10:11], off nt
	v_add_co_u32_e32 v10, vcc, s0, v8
	s_mov_b32 s0, 0x14000
	s_nop 0
	v_addc_co_u32_e32 v11, vcc, 0, v9, vcc
	global_load_dword v21, v[10:11], off nt
	v_add_co_u32_e32 v10, vcc, s0, v8
	s_mov_b32 s0, 0x18000
	s_nop 0
	v_addc_co_u32_e32 v11, vcc, 0, v9, vcc
	global_load_dword v22, v[10:11], off nt
	v_add_co_u32_e32 v10, vcc, s0, v8
	s_mov_b32 s0, 0x1c000
	s_nop 0
	v_addc_co_u32_e32 v11, vcc, 0, v9, vcc
	global_load_dword v23, v[10:11], off nt
	v_add_co_u32_e32 v10, vcc, s0, v8
	s_mov_b32 s0, 0x20000
	s_nop 0
	v_addc_co_u32_e32 v11, vcc, 0, v9, vcc
	global_load_dword v24, v[10:11], off nt
	v_add_co_u32_e32 v10, vcc, s0, v8
	s_mov_b32 s0, 0x24000
	s_nop 0
	v_addc_co_u32_e32 v11, vcc, 0, v9, vcc
	global_load_dword v25, v[10:11], off nt
	v_add_co_u32_e32 v10, vcc, s0, v8
	s_mov_b32 s0, 0x28000
	s_nop 0
	v_addc_co_u32_e32 v11, vcc, 0, v9, vcc
	global_load_dword v26, v[10:11], off nt
	v_add_co_u32_e32 v10, vcc, s0, v8
	s_mov_b32 s0, 0x2c000
	s_nop 0
	v_addc_co_u32_e32 v11, vcc, 0, v9, vcc
	global_load_dword v27, v[10:11], off nt
	v_add_co_u32_e32 v10, vcc, s0, v8
	s_mov_b32 s0, 0x30000
	s_nop 0
	v_addc_co_u32_e32 v11, vcc, 0, v9, vcc
	global_load_dword v28, v[10:11], off nt
	v_add_co_u32_e32 v10, vcc, s0, v8
	s_mov_b32 s0, 0x34000
	s_nop 0
	v_addc_co_u32_e32 v11, vcc, 0, v9, vcc
	global_load_dword v29, v[10:11], off nt
	v_add_co_u32_e32 v10, vcc, s0, v8
	s_mov_b32 s0, 0x38000
	s_nop 0
	v_addc_co_u32_e32 v11, vcc, 0, v9, vcc
	global_load_dword v30, v[10:11], off nt
	v_add_co_u32_e32 v10, vcc, s0, v8
	s_mov_b32 s0, 0x3c000
	s_nop 0
	v_addc_co_u32_e32 v11, vcc, 0, v9, vcc
	global_load_dword v31, v[10:11], off nt
	v_add_co_u32_e32 v10, vcc, s0, v8
	s_mov_b32 s0, 0x40000
	s_nop 0
	v_addc_co_u32_e32 v11, vcc, 0, v9, vcc
	global_load_dword v32, v[10:11], off nt
	v_add_co_u32_e32 v10, vcc, s0, v8
	s_mov_b32 s0, 0x44000
	s_nop 0
	v_addc_co_u32_e32 v11, vcc, 0, v9, vcc
	global_load_dword v33, v[10:11], off nt
	v_add_co_u32_e32 v10, vcc, s0, v8
	s_mov_b32 s0, 0x48000
	s_nop 0
	v_addc_co_u32_e32 v11, vcc, 0, v9, vcc
	global_load_dword v34, v[10:11], off nt
	v_add_co_u32_e32 v10, vcc, s0, v8
	s_mov_b32 s0, 0x4c000
	s_nop 0
	v_addc_co_u32_e32 v11, vcc, 0, v9, vcc
	global_load_dword v35, v[10:11], off nt
	v_add_co_u32_e32 v10, vcc, s0, v8
	s_mov_b32 s0, 0x50000
	s_nop 0
	v_addc_co_u32_e32 v11, vcc, 0, v9, vcc
	global_load_dword v36, v[10:11], off nt
	v_add_co_u32_e32 v10, vcc, s0, v8
	s_mov_b32 s0, 0x54000
	s_nop 0
	v_addc_co_u32_e32 v11, vcc, 0, v9, vcc
	global_load_dword v37, v[10:11], off nt
	v_add_co_u32_e32 v10, vcc, s0, v8
	s_mov_b32 s0, 0x58000
	s_nop 0
	v_addc_co_u32_e32 v11, vcc, 0, v9, vcc
	global_load_dword v38, v[10:11], off nt
	v_add_co_u32_e32 v10, vcc, s0, v8
	s_mov_b32 s0, 0x5c000
	s_nop 0
	v_addc_co_u32_e32 v11, vcc, 0, v9, vcc
	global_load_dword v39, v[10:11], off nt
	v_add_co_u32_e32 v10, vcc, s0, v8
	s_mov_b32 s0, 0x60000
	s_nop 0
	v_addc_co_u32_e32 v11, vcc, 0, v9, vcc
	global_load_dword v40, v[10:11], off nt
	v_add_co_u32_e32 v10, vcc, s0, v8
	s_mov_b32 s0, 0x64000
	s_nop 0
	v_addc_co_u32_e32 v11, vcc, 0, v9, vcc
	global_load_dword v41, v[10:11], off nt
	v_add_co_u32_e32 v10, vcc, s0, v8
	s_mov_b32 s0, 0x68000
	s_nop 0
	v_addc_co_u32_e32 v11, vcc, 0, v9, vcc
	global_load_dword v42, v[10:11], off nt
	v_add_co_u32_e32 v10, vcc, s0, v8
	s_mov_b32 s0, 0x6c000
	s_nop 0
	v_addc_co_u32_e32 v11, vcc, 0, v9, vcc
	global_load_dword v43, v[10:11], off nt
	v_add_co_u32_e32 v10, vcc, s0, v8
	s_mov_b32 s0, 0x70000
	s_nop 0
	v_addc_co_u32_e32 v11, vcc, 0, v9, vcc
	global_load_dword v44, v[10:11], off nt
	v_add_co_u32_e32 v10, vcc, s0, v8
	s_mov_b32 s0, 0x74000
	s_nop 0
	v_addc_co_u32_e32 v11, vcc, 0, v9, vcc
	global_load_dword v45, v[10:11], off nt
	v_add_co_u32_e32 v10, vcc, s0, v8
	s_mov_b32 s0, 0x78000
	s_nop 0
	v_addc_co_u32_e32 v11, vcc, 0, v9, vcc
	global_load_dword v46, v[10:11], off nt
	v_add_co_u32_e32 v10, vcc, s0, v8
	s_mov_b32 s0, 0x7c000
	s_nop 0
	v_addc_co_u32_e32 v11, vcc, 0, v9, vcc
	v_add_co_u32_e32 v8, vcc, s0, v8
	global_load_dword v10, v[10:11], off nt
	s_nop 0
	v_addc_co_u32_e32 v9, vcc, 0, v9, vcc
	global_load_dword v8, v[8:9], off nt
	v_add_u32_e32 v9, 0x400, v5
	s_waitcnt vmcnt(0)
	ds_write2_b32 v5, v17, v18 offset1:66
	ds_write2_b32 v5, v19, v20 offset0:132 offset1:198
	ds_write2_b32 v9, v21, v22 offset0:8 offset1:74
	ds_write2_b32 v9, v23, v24 offset0:140 offset1:206
	v_add_u32_e32 v9, 0x800, v5
	ds_write2_b32 v9, v25, v26 offset0:16 offset1:82
	ds_write2_b32 v9, v27, v28 offset0:148 offset1:214
	v_add_u32_e32 v9, 0xc00, v5
	ds_write2_b32 v9, v29, v30 offset0:24 offset1:90
	ds_write2_b32 v9, v31, v32 offset0:156 offset1:222
	v_add_u32_e32 v9, 0x1000, v5
	ds_write2_b32 v9, v33, v34 offset0:32 offset1:98
	ds_write2_b32 v9, v35, v36 offset0:164 offset1:230
	v_add_u32_e32 v9, 0x1400, v5
	ds_write2_b32 v9, v37, v38 offset0:40 offset1:106
	ds_write2_b32 v9, v39, v40 offset0:172 offset1:238
	v_add_u32_e32 v9, 0x1800, v5
	ds_write2_b32 v9, v41, v42 offset0:48 offset1:114
	ds_write2_b32 v9, v43, v44 offset0:180 offset1:246
	v_add_u32_e32 v9, 0x1c00, v5
	ds_write2_b32 v9, v45, v46 offset0:56 offset1:122
	ds_write2_b32 v9, v10, v8 offset0:188 offset1:254
	s_waitcnt lgkmcnt(0)
	ds_read2_b32 v[10:11], v13 offset0:33 offset1:41
	ds_read2_b32 v[22:23], v13 offset1:8
	ds_read2_b32 v[24:25], v13 offset0:66 offset1:74
	ds_read2_b32 v[26:27], v13 offset0:99 offset1:107
	ds_read2_b32 v[28:29], v13 offset0:132 offset1:140
	ds_read2_b32 v[30:31], v13 offset0:165 offset1:173
	ds_read2_b32 v[32:33], v13 offset0:198 offset1:206
	ds_read2_b32 v[34:35], v13 offset0:231 offset1:239
	s_waitcnt lgkmcnt(7)
	v_bfe_u32 v18, v10, 16, 1
	s_waitcnt lgkmcnt(6)
	v_bfe_u32 v17, v22, 16, 1
	v_add3_u32 v17, v22, v17, s53
	v_lshrrev_b32_e32 v17, 16, v17
	v_add3_u32 v10, v10, v18, s53
	v_and_or_b32 v18, v10, s77, v17
	s_waitcnt lgkmcnt(5)
	v_bfe_u32 v10, v24, 16, 1
	v_add3_u32 v10, v24, v10, s53
	s_waitcnt lgkmcnt(4)
	v_bfe_u32 v17, v26, 16, 1
	v_lshrrev_b32_e32 v10, 16, v10
	v_add3_u32 v17, v26, v17, s53
	v_and_or_b32 v19, v17, s77, v10
	s_waitcnt lgkmcnt(3)
	v_bfe_u32 v10, v28, 16, 1
	v_add3_u32 v10, v28, v10, s53
	s_waitcnt lgkmcnt(2)
	v_bfe_u32 v17, v30, 16, 1
	v_lshrrev_b32_e32 v10, 16, v10
	v_add3_u32 v17, v30, v17, s53
	v_and_or_b32 v20, v17, s77, v10
	s_waitcnt lgkmcnt(1)
	v_bfe_u32 v10, v32, 16, 1
	s_lshl_b32 s0, s9, 1
	v_add3_u32 v10, v32, v10, s53
	s_waitcnt lgkmcnt(0)
	v_bfe_u32 v17, v34, 16, 1
	s_add_u32 s0, s3, s0
	v_lshrrev_b32_e32 v10, 16, v10
	v_add3_u32 v17, v34, v17, s53
	s_addc_u32 s1, s5, 0
	v_lshlrev_b32_e32 v202, 1, v4
	v_and_or_b32 v21, v17, s77, v10
	v_or_b32_e32 v10, s2, v12
	v_lshl_add_u64 v[8:9], s[0:1], 0, v[202:203]
	v_lshlrev_b32_e32 v202, 13, v10
	v_bfe_u32 v10, v23, 16, 1
	v_add3_u32 v10, v23, v10, s53
	v_bfe_u32 v17, v11, 16, 1
	v_lshl_add_u64 v[36:37], v[8:9], 0, v[202:203]
	v_lshrrev_b32_e32 v10, 16, v10
	v_add3_u32 v11, v11, v17, s53
	global_store_dwordx4 v[36:37], v[18:21], off nt
	v_readlane_b32 s18, v251, 32
	v_readlane_b32 s19, v251, 33
	v_and_or_b32 v18, v11, s77, v10
	v_bfe_u32 v10, v25, 16, 1
	v_add3_u32 v10, v25, v10, s53
	v_bfe_u32 v11, v27, 16, 1
	v_lshrrev_b32_e32 v10, 16, v10
	v_add3_u32 v11, v27, v11, s53
	v_and_or_b32 v19, v11, s77, v10
	v_bfe_u32 v10, v29, 16, 1
	v_add3_u32 v10, v29, v10, s53
	v_bfe_u32 v11, v31, 16, 1
	v_lshrrev_b32_e32 v10, 16, v10
	v_add3_u32 v11, v31, v11, s53
	v_and_or_b32 v20, v11, s77, v10
	v_bfe_u32 v10, v33, 16, 1
	v_add3_u32 v10, v33, v10, s53
	v_bfe_u32 v11, v35, 16, 1
	v_lshrrev_b32_e32 v10, 16, v10
	v_add3_u32 v11, v35, v11, s53
	v_and_or_b32 v21, v11, s77, v10
	v_or_b32_e32 v10, s2, v14
	v_lshlrev_b32_e32 v202, 13, v10
	v_lshl_add_u64 v[10:11], v[8:9], 0, v[202:203]
	global_store_dwordx4 v[10:11], v[18:21], off nt
	ds_read2_b32 v[10:11], v13 offset0:49 offset1:57
	ds_read2_b32 v[22:23], v13 offset0:16 offset1:24
	ds_read2_b32 v[24:25], v13 offset0:82 offset1:90
	ds_read2_b32 v[26:27], v13 offset0:115 offset1:123
	ds_read2_b32 v[28:29], v13 offset0:148 offset1:156
	ds_read2_b32 v[30:31], v13 offset0:181 offset1:189
	ds_read2_b32 v[32:33], v13 offset0:214 offset1:222
	ds_read2_b32 v[34:35], v13 offset0:247 offset1:255
	s_waitcnt lgkmcnt(7)
	v_bfe_u32 v18, v10, 16, 1
	s_waitcnt lgkmcnt(6)
	v_bfe_u32 v17, v22, 16, 1
	v_add3_u32 v17, v22, v17, s53
	v_lshrrev_b32_e32 v17, 16, v17
	v_add3_u32 v10, v10, v18, s53
	v_and_or_b32 v18, v10, s77, v17
	s_waitcnt lgkmcnt(5)
	v_bfe_u32 v10, v24, 16, 1
	v_add3_u32 v10, v24, v10, s53
	s_waitcnt lgkmcnt(4)
	v_bfe_u32 v17, v26, 16, 1
	v_lshrrev_b32_e32 v10, 16, v10
	v_add3_u32 v17, v26, v17, s53
	v_and_or_b32 v19, v17, s77, v10
	s_waitcnt lgkmcnt(3)
	v_bfe_u32 v10, v28, 16, 1
	v_add3_u32 v10, v28, v10, s53
	s_waitcnt lgkmcnt(2)
	v_bfe_u32 v17, v30, 16, 1
	v_lshrrev_b32_e32 v10, 16, v10
	v_add3_u32 v17, v30, v17, s53
	v_and_or_b32 v20, v17, s77, v10
	s_waitcnt lgkmcnt(1)
	v_bfe_u32 v10, v32, 16, 1
	v_add3_u32 v10, v32, v10, s53
	s_waitcnt lgkmcnt(0)
	v_bfe_u32 v17, v34, 16, 1
	v_lshrrev_b32_e32 v10, 16, v10
	v_add3_u32 v17, v34, v17, s53
	v_and_or_b32 v21, v17, s77, v10
	v_or_b32_e32 v10, s2, v15
	v_lshlrev_b32_e32 v202, 13, v10
	v_bfe_u32 v10, v23, 16, 1
	v_add3_u32 v10, v23, v10, s53
	v_bfe_u32 v17, v11, 16, 1
	v_lshl_add_u64 v[36:37], v[8:9], 0, v[202:203]
	v_lshrrev_b32_e32 v10, 16, v10
	v_add3_u32 v11, v11, v17, s53
	global_store_dwordx4 v[36:37], v[18:21], off nt
	v_readlane_b32 s20, v251, 34
	v_readlane_b32 s21, v251, 35
	v_and_or_b32 v18, v11, s77, v10
	v_bfe_u32 v10, v25, 16, 1
	v_add3_u32 v10, v25, v10, s53
	v_bfe_u32 v11, v27, 16, 1
	v_lshrrev_b32_e32 v10, 16, v10
	v_add3_u32 v11, v27, v11, s53
	v_and_or_b32 v19, v11, s77, v10
	v_bfe_u32 v10, v29, 16, 1
	v_add3_u32 v10, v29, v10, s53
	v_bfe_u32 v11, v31, 16, 1
	v_lshrrev_b32_e32 v10, 16, v10
	v_add3_u32 v11, v31, v11, s53
	v_and_or_b32 v20, v11, s77, v10
	v_bfe_u32 v10, v33, 16, 1
	v_add3_u32 v10, v33, v10, s53
	v_bfe_u32 v11, v35, 16, 1
	v_lshrrev_b32_e32 v10, 16, v10
	v_add3_u32 v11, v35, v11, s53
	v_and_or_b32 v21, v11, s77, v10
	v_or_b32_e32 v10, s2, v16
	v_lshlrev_b32_e32 v202, 13, v10
	v_lshl_add_u64 v[8:9], v[8:9], 0, v[202:203]
	global_store_dwordx4 v[8:9], v[18:21], off nt
	s_waitcnt lgkmcnt(0)
	v_readlane_b32 s22, v251, 36
	v_readlane_b32 s23, v251, 37
	v_readlane_b32 s24, v251, 38
	v_readlane_b32 s25, v251, 39
	v_readlane_b32 s26, v251, 40
	v_readlane_b32 s27, v251, 41
	v_readlane_b32 s28, v251, 42
	v_readlane_b32 s29, v251, 43
	v_readlane_b32 s30, v251, 44
	v_readlane_b32 s31, v251, 45

.LBB0_1482:
	s_andn2_b64 vcc, exec, s[2:3]
	s_cbranch_vccnz .LBB0_1439
	s_ashr_i32 s0, s4, 31
	s_lshr_b32 s0, s0, 19
	s_add_i32 s1, s4, s0
	s_ashr_i32 s0, s1, 13
	s_and_b32 s1, s1, 0xe000
	s_sub_i32 s4, s4, s1
	s_ashr_i32 s1, s0, 31
	v_readlane_b32 s16, v251, 14
	s_lshl_b64 s[2:3], s[0:1], 26
	v_readlane_b32 s22, v251, 20
	v_readlane_b32 s23, v251, 21
	s_add_u32 s5, s22, s2
	s_addc_u32 s11, s23, s3
	s_lshl_b64 s[0:1], s[0:1], 25
	v_readlane_b32 s2, v251, 60
	s_add_u32 s9, s2, s0
	v_readlane_b32 s0, v251, 61
	s_addc_u32 s10, s0, s1
	s_sext_i32_i16 s0, s4
	s_bfe_u32 s0, s0, 0x80017
	s_add_i32 s0, s4, s0
	s_sext_i32_i16 s1, s0
	s_and_b32 s0, s0, 0xff00
	s_sub_i32 s0, s4, s0
	s_sext_i32_i16 s0, s0
	s_lshl_b32 s2, s0, 5
	s_ashr_i32 s1, s1, 8
	s_ashr_i32 s3, s2, 31
	s_lshl_b32 s4, s1, 6
	s_lshl_b64 s[0:1], s[2:3], 2
	v_or_b32_e32 v8, s4, v3
	s_add_u32 s0, s5, s0
	s_addc_u32 s1, s11, s1
	v_lshlrev_b32_e32 v202, 2, v2
	v_ashrrev_i32_e32 v9, 31, v8
	v_lshl_add_u64 v[10:11], s[0:1], 0, v[202:203]
	v_lshlrev_b64 v[18:19], 15, v[8:9]
	v_lshl_add_u64 v[18:19], v[10:11], 0, v[18:19]
	global_load_dword v17, v[18:19], off nt
	v_or_b32_e32 v18, 2, v8
	v_ashrrev_i32_e32 v19, 31, v18
	v_lshlrev_b64 v[18:19], 15, v[18:19]
	v_lshl_add_u64 v[18:19], v[10:11], 0, v[18:19]
	global_load_dword v20, v[18:19], off nt
	v_or_b32_e32 v18, 4, v8
	v_ashrrev_i32_e32 v19, 31, v18
	v_lshlrev_b64 v[18:19], 15, v[18:19]
	v_lshl_add_u64 v[18:19], v[10:11], 0, v[18:19]
	global_load_dword v21, v[18:19], off nt
	v_or_b32_e32 v18, 6, v8
	v_ashrrev_i32_e32 v19, 31, v18
	v_lshlrev_b64 v[18:19], 15, v[18:19]
	v_lshl_add_u64 v[18:19], v[10:11], 0, v[18:19]
	global_load_dword v22, v[18:19], off nt
	v_or_b32_e32 v18, 8, v8
	v_ashrrev_i32_e32 v19, 31, v18
	v_lshlrev_b64 v[18:19], 15, v[18:19]
	v_lshl_add_u64 v[18:19], v[10:11], 0, v[18:19]
	global_load_dword v23, v[18:19], off nt
	v_or_b32_e32 v18, 10, v8
	v_ashrrev_i32_e32 v19, 31, v18
	v_lshlrev_b64 v[18:19], 15, v[18:19]
	v_lshl_add_u64 v[18:19], v[10:11], 0, v[18:19]
	global_load_dword v24, v[18:19], off nt
	v_or_b32_e32 v18, 12, v8
	v_ashrrev_i32_e32 v19, 31, v18
	v_lshlrev_b64 v[18:19], 15, v[18:19]
	v_lshl_add_u64 v[18:19], v[10:11], 0, v[18:19]
	global_load_dword v25, v[18:19], off nt
	v_or_b32_e32 v18, 14, v8
	v_ashrrev_i32_e32 v19, 31, v18
	v_lshlrev_b64 v[18:19], 15, v[18:19]
	v_lshl_add_u64 v[18:19], v[10:11], 0, v[18:19]
	global_load_dword v26, v[18:19], off nt
	v_or_b32_e32 v18, 16, v8
	v_ashrrev_i32_e32 v19, 31, v18
	v_lshlrev_b64 v[18:19], 15, v[18:19]
	v_lshl_add_u64 v[18:19], v[10:11], 0, v[18:19]
	global_load_dword v27, v[18:19], off nt
	v_or_b32_e32 v18, 18, v8
	v_ashrrev_i32_e32 v19, 31, v18
	v_lshlrev_b64 v[18:19], 15, v[18:19]
	v_lshl_add_u64 v[18:19], v[10:11], 0, v[18:19]
	global_load_dword v28, v[18:19], off nt
	v_or_b32_e32 v18, 20, v8
	v_ashrrev_i32_e32 v19, 31, v18
	v_lshlrev_b64 v[18:19], 15, v[18:19]
	v_lshl_add_u64 v[18:19], v[10:11], 0, v[18:19]
	global_load_dword v29, v[18:19], off nt
	v_or_b32_e32 v18, 22, v8
	v_ashrrev_i32_e32 v19, 31, v18
	v_lshlrev_b64 v[18:19], 15, v[18:19]
	v_lshl_add_u64 v[18:19], v[10:11], 0, v[18:19]
	global_load_dword v30, v[18:19], off nt
	v_or_b32_e32 v18, 24, v8
	v_ashrrev_i32_e32 v19, 31, v18
	v_lshlrev_b64 v[18:19], 15, v[18:19]
	v_lshl_add_u64 v[18:19], v[10:11], 0, v[18:19]
	global_load_dword v31, v[18:19], off nt
	v_or_b32_e32 v18, 26, v8
	v_ashrrev_i32_e32 v19, 31, v18
	v_lshlrev_b64 v[18:19], 15, v[18:19]
	v_lshl_add_u64 v[18:19], v[10:11], 0, v[18:19]
	global_load_dword v32, v[18:19], off nt
	v_or_b32_e32 v18, 28, v8
	v_ashrrev_i32_e32 v19, 31, v18
	v_lshlrev_b64 v[18:19], 15, v[18:19]
	v_lshl_add_u64 v[18:19], v[10:11], 0, v[18:19]
	global_load_dword v33, v[18:19], off nt
	v_or_b32_e32 v18, 30, v8
	v_ashrrev_i32_e32 v19, 31, v18
	v_lshlrev_b64 v[18:19], 15, v[18:19]
	v_lshl_add_u64 v[18:19], v[10:11], 0, v[18:19]
	global_load_dword v34, v[18:19], off nt
	v_or_b32_e32 v18, 32, v8
	v_ashrrev_i32_e32 v19, 31, v18
	v_lshlrev_b64 v[18:19], 15, v[18:19]
	v_lshl_add_u64 v[18:19], v[10:11], 0, v[18:19]
	global_load_dword v35, v[18:19], off nt
	v_or_b32_e32 v18, 34, v8
	v_ashrrev_i32_e32 v19, 31, v18
	v_lshlrev_b64 v[18:19], 15, v[18:19]
	v_lshl_add_u64 v[18:19], v[10:11], 0, v[18:19]
	global_load_dword v36, v[18:19], off nt
	v_or_b32_e32 v18, 36, v8
	v_ashrrev_i32_e32 v19, 31, v18
	v_lshlrev_b64 v[18:19], 15, v[18:19]
	v_lshl_add_u64 v[18:19], v[10:11], 0, v[18:19]
	global_load_dword v37, v[18:19], off nt
	v_or_b32_e32 v18, 38, v8
	v_ashrrev_i32_e32 v19, 31, v18
	v_lshlrev_b64 v[18:19], 15, v[18:19]
	v_lshl_add_u64 v[18:19], v[10:11], 0, v[18:19]
	global_load_dword v38, v[18:19], off nt
	v_or_b32_e32 v18, 40, v8
	v_ashrrev_i32_e32 v19, 31, v18
	v_lshlrev_b64 v[18:19], 15, v[18:19]
	v_lshl_add_u64 v[18:19], v[10:11], 0, v[18:19]
	global_load_dword v39, v[18:19], off nt
	v_or_b32_e32 v18, 42, v8
	v_ashrrev_i32_e32 v19, 31, v18
	v_lshlrev_b64 v[18:19], 15, v[18:19]
	v_lshl_add_u64 v[18:19], v[10:11], 0, v[18:19]
	global_load_dword v40, v[18:19], off nt
	v_or_b32_e32 v18, 44, v8
	v_ashrrev_i32_e32 v19, 31, v18
	v_lshlrev_b64 v[18:19], 15, v[18:19]
	v_lshl_add_u64 v[18:19], v[10:11], 0, v[18:19]
	global_load_dword v41, v[18:19], off nt
	v_or_b32_e32 v18, 46, v8
	v_ashrrev_i32_e32 v19, 31, v18
	v_lshlrev_b64 v[18:19], 15, v[18:19]
	v_lshl_add_u64 v[18:19], v[10:11], 0, v[18:19]
	global_load_dword v42, v[18:19], off nt
	v_or_b32_e32 v18, 48, v8
	v_ashrrev_i32_e32 v19, 31, v18
	v_lshlrev_b64 v[18:19], 15, v[18:19]
	v_lshl_add_u64 v[18:19], v[10:11], 0, v[18:19]
	global_load_dword v43, v[18:19], off nt
	v_or_b32_e32 v18, 50, v8
	v_ashrrev_i32_e32 v19, 31, v18
	v_lshlrev_b64 v[18:19], 15, v[18:19]
	v_lshl_add_u64 v[18:19], v[10:11], 0, v[18:19]
	global_load_dword v44, v[18:19], off nt
	v_or_b32_e32 v18, 52, v8
	v_ashrrev_i32_e32 v19, 31, v18
	v_lshlrev_b64 v[18:19], 15, v[18:19]
	v_lshl_add_u64 v[18:19], v[10:11], 0, v[18:19]
	global_load_dword v45, v[18:19], off nt
	v_or_b32_e32 v18, 54, v8
	v_ashrrev_i32_e32 v19, 31, v18
	v_lshlrev_b64 v[18:19], 15, v[18:19]
	v_lshl_add_u64 v[18:19], v[10:11], 0, v[18:19]
	global_load_dword v46, v[18:19], off nt
	v_or_b32_e32 v18, 56, v8
	v_ashrrev_i32_e32 v19, 31, v18
	v_lshlrev_b64 v[18:19], 15, v[18:19]
	v_lshl_add_u64 v[18:19], v[10:11], 0, v[18:19]
	global_load_dword v47, v[18:19], off nt
	v_or_b32_e32 v18, 58, v8
	v_ashrrev_i32_e32 v19, 31, v18
	v_lshlrev_b64 v[18:19], 15, v[18:19]
	v_lshl_add_u64 v[18:19], v[10:11], 0, v[18:19]
	global_load_dword v48, v[18:19], off nt
	v_or_b32_e32 v18, 60, v8
	v_or_b32_e32 v8, 62, v8
	v_ashrrev_i32_e32 v19, 31, v18
	v_ashrrev_i32_e32 v9, 31, v8
	v_lshlrev_b64 v[18:19], 15, v[18:19]
	v_lshlrev_b64 v[8:9], 15, v[8:9]
	v_lshl_add_u64 v[18:19], v[10:11], 0, v[18:19]
	v_lshl_add_u64 v[8:9], v[10:11], 0, v[8:9]
	global_load_dword v18, v[18:19], off nt
	s_ashr_i32 s5, s4, 31
	global_load_dword v8, v[8:9], off nt
	v_add_u32_e32 v9, 0x400, v5
	s_waitcnt vmcnt(0)
	ds_write2_b32 v5, v17, v20 offset1:66
	ds_write2_b32 v5, v21, v22 offset0:132 offset1:198
	ds_write2_b32 v9, v23, v24 offset0:8 offset1:74
	ds_write2_b32 v9, v25, v26 offset0:140 offset1:206
	v_add_u32_e32 v9, 0x800, v5
	ds_write2_b32 v9, v27, v28 offset0:16 offset1:82
	ds_write2_b32 v9, v29, v30 offset0:148 offset1:214
	v_add_u32_e32 v9, 0xc00, v5
	ds_write2_b32 v9, v31, v32 offset0:24 offset1:90
	ds_write2_b32 v9, v33, v34 offset0:156 offset1:222
	v_add_u32_e32 v9, 0x1000, v5
	ds_write2_b32 v9, v35, v36 offset0:32 offset1:98
	ds_write2_b32 v9, v37, v38 offset0:164 offset1:230
	v_add_u32_e32 v9, 0x1400, v5
	ds_write2_b32 v9, v39, v40 offset0:40 offset1:106
	ds_write2_b32 v9, v41, v42 offset0:172 offset1:238
	v_add_u32_e32 v9, 0x1800, v5
	ds_write2_b32 v9, v43, v44 offset0:48 offset1:114
	ds_write2_b32 v9, v45, v46 offset0:180 offset1:246
	v_add_u32_e32 v9, 0x1c00, v5
	ds_write2_b32 v9, v47, v48 offset0:56 offset1:122
	ds_write2_b32 v9, v18, v8 offset0:188 offset1:254
	s_waitcnt lgkmcnt(0)
	ds_read2_b32 v[10:11], v13 offset0:33 offset1:41
	ds_read2_b32 v[22:23], v13 offset1:8
	ds_read2_b32 v[24:25], v13 offset0:66 offset1:74
	ds_read2_b32 v[26:27], v13 offset0:99 offset1:107
	ds_read2_b32 v[28:29], v13 offset0:132 offset1:140
	ds_read2_b32 v[30:31], v13 offset0:165 offset1:173
	ds_read2_b32 v[32:33], v13 offset0:198 offset1:206
	ds_read2_b32 v[34:35], v13 offset0:231 offset1:239
	s_waitcnt lgkmcnt(7)
	v_bfe_u32 v18, v10, 16, 1
	s_waitcnt lgkmcnt(6)
	v_bfe_u32 v17, v22, 16, 1
	v_add3_u32 v17, v22, v17, s53
	v_lshrrev_b32_e32 v17, 16, v17
	v_add3_u32 v10, v10, v18, s53
	v_and_or_b32 v18, v10, s77, v17
	s_waitcnt lgkmcnt(5)
	v_bfe_u32 v10, v24, 16, 1
	v_add3_u32 v10, v24, v10, s53
	s_waitcnt lgkmcnt(4)
	v_bfe_u32 v17, v26, 16, 1
	v_lshrrev_b32_e32 v10, 16, v10
	v_add3_u32 v17, v26, v17, s53
	v_and_or_b32 v19, v17, s77, v10
	s_waitcnt lgkmcnt(3)
	v_bfe_u32 v10, v28, 16, 1
	v_add3_u32 v10, v28, v10, s53
	s_waitcnt lgkmcnt(2)
	v_bfe_u32 v17, v30, 16, 1
	v_lshrrev_b32_e32 v10, 16, v10
	v_add3_u32 v17, v30, v17, s53
	v_and_or_b32 v20, v17, s77, v10
	s_waitcnt lgkmcnt(1)
	v_bfe_u32 v10, v32, 16, 1
	s_lshl_b64 s[0:1], s[4:5], 1
	v_add3_u32 v10, v32, v10, s53
	s_waitcnt lgkmcnt(0)
	v_bfe_u32 v17, v34, 16, 1
	s_add_u32 s0, s9, s0
	v_lshrrev_b32_e32 v10, 16, v10
	v_add3_u32 v17, v34, v17, s53
	v_or_b32_e32 v36, s2, v12
	s_addc_u32 s1, s10, s1
	v_lshlrev_b32_e32 v202, 1, v4
	v_and_or_b32 v21, v17, s77, v10
	v_ashrrev_i32_e32 v37, 31, v36
	v_bfe_u32 v10, v23, 16, 1
	v_lshl_add_u64 v[8:9], s[0:1], 0, v[202:203]
	v_lshlrev_b64 v[36:37], 12, v[36:37]
	v_add3_u32 v10, v23, v10, s53
	v_bfe_u32 v17, v11, 16, 1
	v_lshl_add_u64 v[36:37], v[8:9], 0, v[36:37]
	v_lshrrev_b32_e32 v10, 16, v10
	v_add3_u32 v11, v11, v17, s53
	global_store_dwordx4 v[36:37], v[18:21], off nt
	v_or_b32_e32 v36, s2, v15
	v_ashrrev_i32_e32 v37, 31, v36
	v_and_or_b32 v18, v11, s77, v10
	v_bfe_u32 v10, v25, 16, 1
	v_add3_u32 v10, v25, v10, s53
	v_bfe_u32 v11, v27, 16, 1
	v_lshrrev_b32_e32 v10, 16, v10
	v_add3_u32 v11, v27, v11, s53
	v_and_or_b32 v19, v11, s77, v10
	v_bfe_u32 v10, v29, 16, 1
	v_add3_u32 v10, v29, v10, s53
	v_bfe_u32 v11, v31, 16, 1
	v_lshrrev_b32_e32 v10, 16, v10
	v_add3_u32 v11, v31, v11, s53
	v_and_or_b32 v20, v11, s77, v10
	v_bfe_u32 v10, v33, 16, 1
	v_add3_u32 v10, v33, v10, s53
	v_bfe_u32 v11, v35, 16, 1
	v_lshrrev_b32_e32 v10, 16, v10
	v_add3_u32 v11, v35, v11, s53
	v_and_or_b32 v21, v11, s77, v10
	v_or_b32_e32 v10, s2, v14
	v_ashrrev_i32_e32 v11, 31, v10
	v_lshlrev_b64 v[10:11], 12, v[10:11]
	v_lshl_add_u64 v[10:11], v[8:9], 0, v[10:11]
	global_store_dwordx4 v[10:11], v[18:21], off nt
	ds_read2_b32 v[10:11], v13 offset0:49 offset1:57
	ds_read2_b32 v[22:23], v13 offset0:16 offset1:24
	ds_read2_b32 v[24:25], v13 offset0:82 offset1:90
	ds_read2_b32 v[26:27], v13 offset0:115 offset1:123
	ds_read2_b32 v[28:29], v13 offset0:148 offset1:156
	ds_read2_b32 v[30:31], v13 offset0:181 offset1:189
	ds_read2_b32 v[32:33], v13 offset0:214 offset1:222
	ds_read2_b32 v[34:35], v13 offset0:247 offset1:255
	s_waitcnt lgkmcnt(7)
	v_bfe_u32 v18, v10, 16, 1
	s_waitcnt lgkmcnt(6)
	v_bfe_u32 v17, v22, 16, 1
	v_add3_u32 v17, v22, v17, s53
	v_lshrrev_b32_e32 v17, 16, v17
	v_add3_u32 v10, v10, v18, s53
	v_and_or_b32 v18, v10, s77, v17
	s_waitcnt lgkmcnt(5)
	v_bfe_u32 v10, v24, 16, 1
	v_add3_u32 v10, v24, v10, s53
	s_waitcnt lgkmcnt(4)
	v_bfe_u32 v17, v26, 16, 1
	v_lshrrev_b32_e32 v10, 16, v10
	v_add3_u32 v17, v26, v17, s53
	v_and_or_b32 v19, v17, s77, v10
	s_waitcnt lgkmcnt(3)
	v_bfe_u32 v10, v28, 16, 1
	v_add3_u32 v10, v28, v10, s53
	s_waitcnt lgkmcnt(2)
	v_bfe_u32 v17, v30, 16, 1
	v_lshrrev_b32_e32 v10, 16, v10
	v_add3_u32 v17, v30, v17, s53
	v_and_or_b32 v20, v17, s77, v10
	s_waitcnt lgkmcnt(1)
	v_bfe_u32 v10, v32, 16, 1
	v_add3_u32 v10, v32, v10, s53
	s_waitcnt lgkmcnt(0)
	v_bfe_u32 v17, v34, 16, 1
	v_lshrrev_b32_e32 v10, 16, v10
	v_add3_u32 v17, v34, v17, s53
	v_and_or_b32 v21, v17, s77, v10
	v_bfe_u32 v10, v23, 16, 1
	v_lshlrev_b64 v[36:37], 12, v[36:37]
	v_add3_u32 v10, v23, v10, s53
	v_bfe_u32 v17, v11, 16, 1
	v_lshl_add_u64 v[36:37], v[8:9], 0, v[36:37]
	v_lshrrev_b32_e32 v10, 16, v10
	v_add3_u32 v11, v11, v17, s53
	global_store_dwordx4 v[36:37], v[18:21], off nt
	v_readlane_b32 s17, v251, 15
	v_readlane_b32 s18, v251, 16
	v_and_or_b32 v18, v11, s77, v10
	v_bfe_u32 v10, v25, 16, 1
	v_add3_u32 v10, v25, v10, s53
	v_bfe_u32 v11, v27, 16, 1
	v_lshrrev_b32_e32 v10, 16, v10
	v_add3_u32 v11, v27, v11, s53
	v_and_or_b32 v19, v11, s77, v10
	v_bfe_u32 v10, v29, 16, 1
	v_add3_u32 v10, v29, v10, s53
	v_bfe_u32 v11, v31, 16, 1
	v_lshrrev_b32_e32 v10, 16, v10
	v_add3_u32 v11, v31, v11, s53
	v_and_or_b32 v20, v11, s77, v10
	v_bfe_u32 v10, v33, 16, 1
	v_add3_u32 v10, v33, v10, s53
	v_bfe_u32 v11, v35, 16, 1
	v_lshrrev_b32_e32 v10, 16, v10
	v_add3_u32 v11, v35, v11, s53
	v_and_or_b32 v21, v11, s77, v10
	v_or_b32_e32 v10, s2, v16
	v_ashrrev_i32_e32 v11, 31, v10
	v_lshlrev_b64 v[10:11], 12, v[10:11]
	v_lshl_add_u64 v[8:9], v[8:9], 0, v[10:11]
	global_store_dwordx4 v[8:9], v[18:21], off nt
	s_waitcnt lgkmcnt(0)
	v_readlane_b32 s19, v251, 17
	v_readlane_b32 s20, v251, 18
	v_readlane_b32 s21, v251, 19
	v_readlane_b32 s24, v251, 22
	v_readlane_b32 s25, v251, 23
	v_readlane_b32 s26, v251, 24
	v_readlane_b32 s27, v251, 25
	v_readlane_b32 s28, v251, 26
	v_readlane_b32 s29, v251, 27
	v_readlane_b32 s30, v251, 28
	v_readlane_b32 s31, v251, 29
	s_branch .LBB0_1439

.LBB0_1633:
	s_cmpk_gt_i32 s4, 0x3fff
	s_mov_b64 s[2:3], -1
	s_cbranch_scc0 .LBB0_1654
	s_cmpk_gt_u32 s4, 0x5fff
	s_cbranch_scc0 .LBB0_1651
	s_cmp_gt_u32 s4, 0x167ff
	s_cbranch_scc0 .LBB0_1641
	s_cmp_gt_u32 s4, 0x177ff
	s_cbranch_scc0 .LBB0_1638
	s_add_i32 s2, s4, 0xfffe8800
	v_readlane_b32 s16, v251, 6
	s_and_b32 s86, s2, 0xfffff800
	v_readlane_b32 s17, v251, 7
	v_readlane_b32 s18, v251, 8
	v_readlane_b32 s19, v251, 9
	v_readlane_b32 s20, v251, 10
	v_readlane_b32 s21, v251, 11
	s_lshl_b64 s[0:1], s[86:87], 2
	v_readlane_b32 s22, v251, 12
	v_readlane_b32 s23, v251, 13
	s_mov_b64 s[16:17], s[20:21]
	s_add_u32 s0, s16, s0
	s_addc_u32 s1, s17, s1
	s_lshl_b32 s10, s4, 5
	s_lshr_b32 s2, s2, 4
	s_lshl_b32 s11, s4, 6
	s_and_b32 s10, s10, 0x60
	s_and_b32 s2, s2, 0xfffff80
	s_and_b32 s5, s4, 63
	s_and_b32 s11, s11, 0xf00
	s_or_b32 s2, s2, s10
	s_and_b32 s3, s4, 0x7c0
	s_or_b32 s2, s2, s11
	s_lshl_b32 s5, s5, 7
	s_add_u32 s0, s0, s5
	v_or_b32_e32 v10, s3, v3
	s_addc_u32 s1, s1, 0
	v_lshlrev_b32_e32 v202, 2, v2
	v_lshl_add_u64 v[8:9], s[0:1], 0, v[202:203]
	v_lshlrev_b32_e32 v202, 14, v10
	v_lshl_add_u64 v[8:9], v[8:9], 0, v[202:203]
	s_mov_b32 s0, 0x8000
	v_add_co_u32_e32 v10, vcc, s0, v8
	s_mov_b32 s0, 0x10000
	s_nop 0
	v_addc_co_u32_e32 v11, vcc, 0, v9, vcc
	global_load_dword v17, v[8:9], off nt
	global_load_dword v18, v[10:11], off nt
	v_add_co_u32_e32 v10, vcc, s0, v8
	s_mov_b32 s0, 0x18000
	s_nop 0
	v_addc_co_u32_e32 v11, vcc, 0, v9, vcc
	global_load_dword v19, v[10:11], off nt
	v_add_co_u32_e32 v10, vcc, s0, v8
	s_mov_b32 s0, 0x20000
	s_nop 0
	v_addc_co_u32_e32 v11, vcc, 0, v9, vcc
	global_load_dword v20, v[10:11], off nt
	v_add_co_u32_e32 v10, vcc, s0, v8
	s_mov_b32 s0, 0x28000
	s_nop 0
	v_addc_co_u32_e32 v11, vcc, 0, v9, vcc
	global_load_dword v21, v[10:11], off nt
	v_add_co_u32_e32 v10, vcc, s0, v8
	s_mov_b32 s0, 0x30000
	s_nop 0
	v_addc_co_u32_e32 v11, vcc, 0, v9, vcc
	global_load_dword v22, v[10:11], off nt
	v_add_co_u32_e32 v10, vcc, s0, v8
	s_mov_b32 s0, 0x38000
	s_nop 0
	v_addc_co_u32_e32 v11, vcc, 0, v9, vcc
	global_load_dword v23, v[10:11], off nt
	v_add_co_u32_e32 v10, vcc, s0, v8
	s_mov_b32 s0, 0x40000
	s_nop 0
	v_addc_co_u32_e32 v11, vcc, 0, v9, vcc
	global_load_dword v24, v[10:11], off nt
	v_add_co_u32_e32 v10, vcc, s0, v8
	s_mov_b32 s0, 0x48000
	s_nop 0
	v_addc_co_u32_e32 v11, vcc, 0, v9, vcc
	global_load_dword v25, v[10:11], off nt
	v_add_co_u32_e32 v10, vcc, s0, v8
	s_mov_b32 s0, 0x50000
	s_nop 0
	v_addc_co_u32_e32 v11, vcc, 0, v9, vcc
	global_load_dword v26, v[10:11], off nt
	v_add_co_u32_e32 v10, vcc, s0, v8
	s_mov_b32 s0, 0x58000
	s_nop 0
	v_addc_co_u32_e32 v11, vcc, 0, v9, vcc
	global_load_dword v27, v[10:11], off nt
	v_add_co_u32_e32 v10, vcc, s0, v8
	s_mov_b32 s0, 0x60000
	s_nop 0
	v_addc_co_u32_e32 v11, vcc, 0, v9, vcc
	global_load_dword v28, v[10:11], off nt
	v_add_co_u32_e32 v10, vcc, s0, v8
	s_mov_b32 s0, 0x68000
	s_nop 0
	v_addc_co_u32_e32 v11, vcc, 0, v9, vcc
	global_load_dword v29, v[10:11], off nt
	v_add_co_u32_e32 v10, vcc, s0, v8
	s_mov_b32 s0, 0x70000
	s_nop 0
	v_addc_co_u32_e32 v11, vcc, 0, v9, vcc
	global_load_dword v30, v[10:11], off nt
	v_add_co_u32_e32 v10, vcc, s0, v8
	s_mov_b32 s0, 0x78000
	s_nop 0
	v_addc_co_u32_e32 v11, vcc, 0, v9, vcc
	global_load_dword v31, v[10:11], off nt
	v_add_co_u32_e32 v10, vcc, s0, v8
	s_mov_b32 s0, 0x80000
	s_nop 0
	v_addc_co_u32_e32 v11, vcc, 0, v9, vcc
	global_load_dword v32, v[10:11], off nt
	v_add_co_u32_e32 v10, vcc, s0, v8
	s_mov_b32 s0, 0x88000
	s_nop 0
	v_addc_co_u32_e32 v11, vcc, 0, v9, vcc
	global_load_dword v33, v[10:11], off nt
	v_add_co_u32_e32 v10, vcc, s0, v8
	s_mov_b32 s0, 0x90000
	s_nop 0
	v_addc_co_u32_e32 v11, vcc, 0, v9, vcc
	global_load_dword v34, v[10:11], off nt
	v_add_co_u32_e32 v10, vcc, s0, v8
	s_mov_b32 s0, 0x98000
	s_nop 0
	v_addc_co_u32_e32 v11, vcc, 0, v9, vcc
	global_load_dword v35, v[10:11], off nt
	v_add_co_u32_e32 v10, vcc, s0, v8
	s_mov_b32 s0, 0xa0000
	s_nop 0
	v_addc_co_u32_e32 v11, vcc, 0, v9, vcc
	global_load_dword v36, v[10:11], off nt
	v_add_co_u32_e32 v10, vcc, s0, v8
	s_mov_b32 s0, 0xa8000
	s_nop 0
	v_addc_co_u32_e32 v11, vcc, 0, v9, vcc
	global_load_dword v37, v[10:11], off nt
	v_add_co_u32_e32 v10, vcc, s0, v8
	s_mov_b32 s0, 0xb0000
	s_nop 0
	v_addc_co_u32_e32 v11, vcc, 0, v9, vcc
	global_load_dword v38, v[10:11], off nt
	v_add_co_u32_e32 v10, vcc, s0, v8
	s_mov_b32 s0, 0xb8000
	s_nop 0
	v_addc_co_u32_e32 v11, vcc, 0, v9, vcc
	global_load_dword v39, v[10:11], off nt
	v_add_co_u32_e32 v10, vcc, s0, v8
	s_mov_b32 s0, 0xc0000
	s_nop 0
	v_addc_co_u32_e32 v11, vcc, 0, v9, vcc
	global_load_dword v40, v[10:11], off nt
	v_add_co_u32_e32 v10, vcc, s0, v8
	s_mov_b32 s0, 0xc8000
	s_nop 0
	v_addc_co_u32_e32 v11, vcc, 0, v9, vcc
	global_load_dword v41, v[10:11], off nt
	v_add_co_u32_e32 v10, vcc, s0, v8
	s_mov_b32 s0, 0xd0000
	s_nop 0
	v_addc_co_u32_e32 v11, vcc, 0, v9, vcc
	global_load_dword v42, v[10:11], off nt
	v_add_co_u32_e32 v10, vcc, s0, v8
	s_mov_b32 s0, 0xd8000
	s_nop 0
	v_addc_co_u32_e32 v11, vcc, 0, v9, vcc
	global_load_dword v43, v[10:11], off nt
	v_add_co_u32_e32 v10, vcc, s0, v8
	s_mov_b32 s0, 0xe0000
	s_nop 0
	v_addc_co_u32_e32 v11, vcc, 0, v9, vcc
	global_load_dword v44, v[10:11], off nt
	v_add_co_u32_e32 v10, vcc, s0, v8
	s_mov_b32 s0, 0xe8000
	s_nop 0
	v_addc_co_u32_e32 v11, vcc, 0, v9, vcc
	global_load_dword v45, v[10:11], off nt
	v_add_co_u32_e32 v10, vcc, s0, v8
	s_mov_b32 s0, 0xf0000
	s_nop 0
	v_addc_co_u32_e32 v11, vcc, 0, v9, vcc
	global_load_dword v46, v[10:11], off nt
	v_add_co_u32_e32 v10, vcc, s0, v8
	s_mov_b32 s0, 0xf8000
	s_nop 0
	v_addc_co_u32_e32 v11, vcc, 0, v9, vcc
	v_add_co_u32_e32 v8, vcc, s0, v8
	global_load_dword v10, v[10:11], off nt
	s_nop 0
	v_addc_co_u32_e32 v9, vcc, 0, v9, vcc
	global_load_dword v8, v[8:9], off nt
	v_add_u32_e32 v9, 0x400, v5
	s_waitcnt vmcnt(0)
	ds_write2_b32 v5, v17, v18 offset1:66
	ds_write2_b32 v5, v19, v20 offset0:132 offset1:198
	ds_write2_b32 v9, v21, v22 offset0:8 offset1:74
	ds_write2_b32 v9, v23, v24 offset0:140 offset1:206
	v_add_u32_e32 v9, 0x800, v5
	ds_write2_b32 v9, v25, v26 offset0:16 offset1:82
	ds_write2_b32 v9, v27, v28 offset0:148 offset1:214
	v_add_u32_e32 v9, 0xc00, v5
	ds_write2_b32 v9, v29, v30 offset0:24 offset1:90
	ds_write2_b32 v9, v31, v32 offset0:156 offset1:222
	v_add_u32_e32 v9, 0x1000, v5
	ds_write2_b32 v9, v33, v34 offset0:32 offset1:98
	ds_write2_b32 v9, v35, v36 offset0:164 offset1:230
	v_add_u32_e32 v9, 0x1400, v5
	ds_write2_b32 v9, v37, v38 offset0:40 offset1:106
	ds_write2_b32 v9, v39, v40 offset0:172 offset1:238
	v_add_u32_e32 v9, 0x1800, v5
	ds_write2_b32 v9, v41, v42 offset0:48 offset1:114
	ds_write2_b32 v9, v43, v44 offset0:180 offset1:246
	v_add_u32_e32 v9, 0x1c00, v5
	ds_write2_b32 v9, v45, v46 offset0:56 offset1:122
	ds_write2_b32 v9, v10, v8 offset0:188 offset1:254
	s_waitcnt lgkmcnt(0)
	ds_read2_b32 v[10:11], v13 offset0:33 offset1:41
	ds_read2_b32 v[22:23], v13 offset1:8
	ds_read2_b32 v[24:25], v13 offset0:66 offset1:74
	ds_read2_b32 v[26:27], v13 offset0:99 offset1:107
	ds_read2_b32 v[28:29], v13 offset0:132 offset1:140
	ds_read2_b32 v[30:31], v13 offset0:165 offset1:173
	ds_read2_b32 v[32:33], v13 offset0:198 offset1:206
	ds_read2_b32 v[34:35], v13 offset0:231 offset1:239
	s_waitcnt lgkmcnt(7)
	v_bfe_u32 v18, v10, 16, 1
	s_waitcnt lgkmcnt(6)
	v_bfe_u32 v17, v22, 16, 1
	v_add3_u32 v17, v22, v17, s53
	v_lshrrev_b32_e32 v17, 16, v17
	v_add3_u32 v10, v10, v18, s53
	v_and_or_b32 v18, v10, s77, v17
	s_waitcnt lgkmcnt(5)
	v_bfe_u32 v10, v24, 16, 1
	v_add3_u32 v10, v24, v10, s53
	s_waitcnt lgkmcnt(4)
	v_bfe_u32 v17, v26, 16, 1
	v_lshrrev_b32_e32 v10, 16, v10
	v_add3_u32 v17, v26, v17, s53
	v_and_or_b32 v19, v17, s77, v10
	s_waitcnt lgkmcnt(3)
	v_bfe_u32 v10, v28, 16, 1
	v_add3_u32 v10, v28, v10, s53
	s_waitcnt lgkmcnt(2)
	v_bfe_u32 v17, v30, 16, 1
	v_lshrrev_b32_e32 v10, 16, v10
	v_add3_u32 v17, v30, v17, s53
	v_and_or_b32 v20, v17, s77, v10
	s_waitcnt lgkmcnt(1)
	v_bfe_u32 v10, v32, 16, 1
	v_add3_u32 v10, v32, v10, s53
	s_waitcnt lgkmcnt(0)
	v_bfe_u32 v17, v34, 16, 1
	v_lshrrev_b32_e32 v10, 16, v10
	v_add3_u32 v17, v34, v17, s53
	v_and_or_b32 v21, v17, s77, v10
	v_or_b32_e32 v10, s2, v12
	s_lshl_b32 s86, s3, 1
	v_lshlrev_b32_e32 v202, 12, v10
	v_bfe_u32 v10, v23, 16, 1
	v_lshl_add_u64 v[8:9], v[6:7], 0, s[86:87]
	v_add3_u32 v10, v23, v10, s53
	v_bfe_u32 v17, v11, 16, 1
	v_lshl_add_u64 v[36:37], v[8:9], 0, v[202:203]
	v_lshrrev_b32_e32 v10, 16, v10
	v_add3_u32 v11, v11, v17, s53
	global_store_dwordx4 v[36:37], v[18:21], off nt
	s_mov_b64 s[18:19], s[22:23]
	s_nop 0
	v_and_or_b32 v18, v11, s77, v10
	v_bfe_u32 v10, v25, 16, 1
	v_add3_u32 v10, v25, v10, s53
	v_bfe_u32 v11, v27, 16, 1
	v_lshrrev_b32_e32 v10, 16, v10
	v_add3_u32 v11, v27, v11, s53
	v_and_or_b32 v19, v11, s77, v10
	v_bfe_u32 v10, v29, 16, 1
	v_add3_u32 v10, v29, v10, s53
	v_bfe_u32 v11, v31, 16, 1
	v_lshrrev_b32_e32 v10, 16, v10
	v_add3_u32 v11, v31, v11, s53
	v_and_or_b32 v20, v11, s77, v10
	v_bfe_u32 v10, v33, 16, 1
	v_add3_u32 v10, v33, v10, s53
	v_bfe_u32 v11, v35, 16, 1
	v_lshrrev_b32_e32 v10, 16, v10
	v_add3_u32 v11, v35, v11, s53
	v_and_or_b32 v21, v11, s77, v10
	v_or_b32_e32 v10, s2, v14
	v_lshlrev_b32_e32 v202, 12, v10
	v_lshl_add_u64 v[10:11], v[8:9], 0, v[202:203]
	global_store_dwordx4 v[10:11], v[18:21], off nt
	ds_read2_b32 v[10:11], v13 offset0:49 offset1:57
	ds_read2_b32 v[22:23], v13 offset0:16 offset1:24
	ds_read2_b32 v[24:25], v13 offset0:82 offset1:90
	ds_read2_b32 v[26:27], v13 offset0:115 offset1:123
	ds_read2_b32 v[28:29], v13 offset0:148 offset1:156
	ds_read2_b32 v[30:31], v13 offset0:181 offset1:189
	ds_read2_b32 v[32:33], v13 offset0:214 offset1:222
	ds_read2_b32 v[34:35], v13 offset0:247 offset1:255
	s_waitcnt lgkmcnt(7)
	v_bfe_u32 v18, v10, 16, 1
	s_waitcnt lgkmcnt(6)
	v_bfe_u32 v17, v22, 16, 1
	v_add3_u32 v17, v22, v17, s53
	v_lshrrev_b32_e32 v17, 16, v17
	v_add3_u32 v10, v10, v18, s53
	v_and_or_b32 v18, v10, s77, v17
	s_waitcnt lgkmcnt(5)
	v_bfe_u32 v10, v24, 16, 1
	v_add3_u32 v10, v24, v10, s53
	s_waitcnt lgkmcnt(4)
	v_bfe_u32 v17, v26, 16, 1
	v_lshrrev_b32_e32 v10, 16, v10
	v_add3_u32 v17, v26, v17, s53
	v_and_or_b32 v19, v17, s77, v10
	s_waitcnt lgkmcnt(3)
	v_bfe_u32 v10, v28, 16, 1
	v_add3_u32 v10, v28, v10, s53
	s_waitcnt lgkmcnt(2)
	v_bfe_u32 v17, v30, 16, 1
	v_lshrrev_b32_e32 v10, 16, v10
	v_add3_u32 v17, v30, v17, s53
	v_and_or_b32 v20, v17, s77, v10
	s_waitcnt lgkmcnt(1)
	v_bfe_u32 v10, v32, 16, 1
	v_add3_u32 v10, v32, v10, s53
	s_waitcnt lgkmcnt(0)
	v_bfe_u32 v17, v34, 16, 1
	v_lshrrev_b32_e32 v10, 16, v10
	v_add3_u32 v17, v34, v17, s53
	v_and_or_b32 v21, v17, s77, v10
	v_or_b32_e32 v10, s2, v15
	v_lshlrev_b32_e32 v202, 12, v10
	v_bfe_u32 v10, v23, 16, 1
	v_add3_u32 v10, v23, v10, s53
	v_bfe_u32 v17, v11, 16, 1
	v_lshl_add_u64 v[36:37], v[8:9], 0, v[202:203]
	v_lshrrev_b32_e32 v10, 16, v10
	v_add3_u32 v11, v11, v17, s53
	global_store_dwordx4 v[36:37], v[18:21], off nt
	s_nop 1
	v_and_or_b32 v18, v11, s77, v10
	v_bfe_u32 v10, v25, 16, 1
	v_add3_u32 v10, v25, v10, s53
	v_bfe_u32 v11, v27, 16, 1
	v_lshrrev_b32_e32 v10, 16, v10
	v_add3_u32 v11, v27, v11, s53
	v_and_or_b32 v19, v11, s77, v10
	v_bfe_u32 v10, v29, 16, 1
	v_add3_u32 v10, v29, v10, s53
	v_bfe_u32 v11, v31, 16, 1
	v_lshrrev_b32_e32 v10, 16, v10
	v_add3_u32 v11, v31, v11, s53
	v_and_or_b32 v20, v11, s77, v10
	v_bfe_u32 v10, v33, 16, 1
	v_add3_u32 v10, v33, v10, s53
	v_bfe_u32 v11, v35, 16, 1
	v_lshrrev_b32_e32 v10, 16, v10
	v_add3_u32 v11, v35, v11, s53
	v_and_or_b32 v21, v11, s77, v10
	v_or_b32_e32 v10, s2, v16
	v_lshlrev_b32_e32 v202, 11, v10
	v_lshl_add_u64 v[8:9], v[202:203], 1, v[8:9]
	global_store_dwordx4 v[8:9], v[18:21], off nt
	s_waitcnt lgkmcnt(0)
	s_mov_b64 s[2:3], 0
.LBB0_1638:
	s_andn2_b64 vcc, exec, s[2:3]
	s_cbranch_vccnz .LBB0_1640
	s_and_b32 s0, s4, 0x1f800
	s_add_i32 s86, s0, 0xfffe9800
	v_readlane_b32 s16, v251, 30
	s_lshl_b64 s[0:1], s[86:87], 13
	v_readlane_b32 s18, v251, 32
	v_readlane_b32 s19, v251, 33
	s_add_u32 s11, s18, s0
	s_addc_u32 s14, s19, s1
	s_lshl_b64 s[0:1], s[86:87], 12
	v_readlane_b32 s2, v251, 52
	s_add_u32 s3, s2, s0
	v_readlane_b32 s0, v251, 53
	s_addc_u32 s5, s0, s1
	s_lshl_b32 s0, s4, 5
	s_and_b32 s2, s0, 0x7e0
	s_and_b32 s10, s4, 0x7c0
	s_lshl_b32 s0, s2, 2
	s_add_u32 s0, s11, s0
	v_or_b32_e32 v10, s10, v3
	s_addc_u32 s1, s14, 0
	v_lshlrev_b32_e32 v202, 2, v2
	v_lshl_add_u64 v[8:9], s[0:1], 0, v[202:203]
	v_lshlrev_b32_e32 v202, 13, v10
	v_lshl_add_u64 v[8:9], v[8:9], 0, v[202:203]
	v_add_co_u32_e32 v10, vcc, s89, v8
	s_mov_b32 s0, 0x8000
	s_nop 0
	v_addc_co_u32_e32 v11, vcc, 0, v9, vcc
	global_load_dword v17, v[8:9], off nt
	global_load_dword v18, v[10:11], off nt
	v_add_co_u32_e32 v10, vcc, s0, v8
	s_mov_b32 s0, 0xc000
	s_nop 0
	v_addc_co_u32_e32 v11, vcc, 0, v9, vcc
	global_load_dword v19, v[10:11], off nt
	v_add_co_u32_e32 v10, vcc, s0, v8
	s_mov_b32 s0, 0x10000
	s_nop 0
	v_addc_co_u32_e32 v11, vcc, 0, v9, vcc
	global_load_dword v20, v[10:11], off nt
	v_add_co_u32_e32 v10, vcc, s0, v8
	s_mov_b32 s0, 0x14000
	s_nop 0
	v_addc_co_u32_e32 v11, vcc, 0, v9, vcc
	global_load_dword v21, v[10:11], off nt
	v_add_co_u32_e32 v10, vcc, s0, v8
	s_mov_b32 s0, 0x18000
	s_nop 0
	v_addc_co_u32_e32 v11, vcc, 0, v9, vcc
	global_load_dword v22, v[10:11], off nt
	v_add_co_u32_e32 v10, vcc, s0, v8
	s_mov_b32 s0, 0x1c000
	s_nop 0
	v_addc_co_u32_e32 v11, vcc, 0, v9, vcc
	global_load_dword v23, v[10:11], off nt
	v_add_co_u32_e32 v10, vcc, s0, v8
	s_mov_b32 s0, 0x20000
	s_nop 0
	v_addc_co_u32_e32 v11, vcc, 0, v9, vcc
	global_load_dword v24, v[10:11], off nt
	v_add_co_u32_e32 v10, vcc, s0, v8
	s_mov_b32 s0, 0x24000
	s_nop 0
	v_addc_co_u32_e32 v11, vcc, 0, v9, vcc
	global_load_dword v25, v[10:11], off nt
	v_add_co_u32_e32 v10, vcc, s0, v8
	s_mov_b32 s0, 0x28000
	s_nop 0
	v_addc_co_u32_e32 v11, vcc, 0, v9, vcc
	global_load_dword v26, v[10:11], off nt
	v_add_co_u32_e32 v10, vcc, s0, v8
	s_mov_b32 s0, 0x2c000
	s_nop 0
	v_addc_co_u32_e32 v11, vcc, 0, v9, vcc
	global_load_dword v27, v[10:11], off nt
	v_add_co_u32_e32 v10, vcc, s0, v8
	s_mov_b32 s0, 0x30000
	s_nop 0
	v_addc_co_u32_e32 v11, vcc, 0, v9, vcc
	global_load_dword v28, v[10:11], off nt
	v_add_co_u32_e32 v10, vcc, s0, v8
	s_mov_b32 s0, 0x34000
	s_nop 0
	v_addc_co_u32_e32 v11, vcc, 0, v9, vcc
	global_load_dword v29, v[10:11], off nt
	v_add_co_u32_e32 v10, vcc, s0, v8
	s_mov_b32 s0, 0x38000
	s_nop 0
	v_addc_co_u32_e32 v11, vcc, 0, v9, vcc
	global_load_dword v30, v[10:11], off nt
	v_add_co_u32_e32 v10, vcc, s0, v8
	s_mov_b32 s0, 0x3c000
	s_nop 0
	v_addc_co_u32_e32 v11, vcc, 0, v9, vcc
	global_load_dword v31, v[10:11], off nt
	v_add_co_u32_e32 v10, vcc, s0, v8
	s_mov_b32 s0, 0x40000
	s_nop 0
	v_addc_co_u32_e32 v11, vcc, 0, v9, vcc
	global_load_dword v32, v[10:11], off nt
	v_add_co_u32_e32 v10, vcc, s0, v8
	s_mov_b32 s0, 0x44000
	s_nop 0
	v_addc_co_u32_e32 v11, vcc, 0, v9, vcc
	global_load_dword v33, v[10:11], off nt
	v_add_co_u32_e32 v10, vcc, s0, v8
	s_mov_b32 s0, 0x48000
	s_nop 0
	v_addc_co_u32_e32 v11, vcc, 0, v9, vcc
	global_load_dword v34, v[10:11], off nt
	v_add_co_u32_e32 v10, vcc, s0, v8
	s_mov_b32 s0, 0x4c000
	s_nop 0
	v_addc_co_u32_e32 v11, vcc, 0, v9, vcc
	global_load_dword v35, v[10:11], off nt
	v_add_co_u32_e32 v10, vcc, s0, v8
	s_mov_b32 s0, 0x50000
	s_nop 0
	v_addc_co_u32_e32 v11, vcc, 0, v9, vcc
	global_load_dword v36, v[10:11], off nt
	v_add_co_u32_e32 v10, vcc, s0, v8
	s_mov_b32 s0, 0x54000
	s_nop 0
	v_addc_co_u32_e32 v11, vcc, 0, v9, vcc
	global_load_dword v37, v[10:11], off nt
	v_add_co_u32_e32 v10, vcc, s0, v8
	s_mov_b32 s0, 0x58000
	s_nop 0
	v_addc_co_u32_e32 v11, vcc, 0, v9, vcc
	global_load_dword v38, v[10:11], off nt
	v_add_co_u32_e32 v10, vcc, s0, v8
	s_mov_b32 s0, 0x5c000
	s_nop 0
	v_addc_co_u32_e32 v11, vcc, 0, v9, vcc
	global_load_dword v39, v[10:11], off nt
	v_add_co_u32_e32 v10, vcc, s0, v8
	s_mov_b32 s0, 0x60000
	s_nop 0
	v_addc_co_u32_e32 v11, vcc, 0, v9, vcc
	global_load_dword v40, v[10:11], off nt
	v_add_co_u32_e32 v10, vcc, s0, v8
	s_mov_b32 s0, 0x64000
	s_nop 0
	v_addc_co_u32_e32 v11, vcc, 0, v9, vcc
	global_load_dword v41, v[10:11], off nt
	v_add_co_u32_e32 v10, vcc, s0, v8
	s_mov_b32 s0, 0x68000
	s_nop 0
	v_addc_co_u32_e32 v11, vcc, 0, v9, vcc
	global_load_dword v42, v[10:11], off nt
	v_add_co_u32_e32 v10, vcc, s0, v8
	s_mov_b32 s0, 0x6c000
	s_nop 0
	v_addc_co_u32_e32 v11, vcc, 0, v9, vcc
	global_load_dword v43, v[10:11], off nt
	v_add_co_u32_e32 v10, vcc, s0, v8
	s_mov_b32 s0, 0x70000
	s_nop 0
	v_addc_co_u32_e32 v11, vcc, 0, v9, vcc
	global_load_dword v44, v[10:11], off nt
	v_add_co_u32_e32 v10, vcc, s0, v8
	s_mov_b32 s0, 0x74000
	s_nop 0
	v_addc_co_u32_e32 v11, vcc, 0, v9, vcc
	global_load_dword v45, v[10:11], off nt
	v_add_co_u32_e32 v10, vcc, s0, v8
	s_mov_b32 s0, 0x78000
	s_nop 0
	v_addc_co_u32_e32 v11, vcc, 0, v9, vcc
	global_load_dword v46, v[10:11], off nt
	v_add_co_u32_e32 v10, vcc, s0, v8
	s_mov_b32 s0, 0x7c000
	s_nop 0
	v_addc_co_u32_e32 v11, vcc, 0, v9, vcc
	v_add_co_u32_e32 v8, vcc, s0, v8
	global_load_dword v10, v[10:11], off nt
	s_nop 0
	v_addc_co_u32_e32 v9, vcc, 0, v9, vcc
	global_load_dword v8, v[8:9], off nt
	v_add_u32_e32 v9, 0x400, v5
	s_waitcnt vmcnt(0)
	ds_write2_b32 v5, v17, v18 offset1:66
	ds_write2_b32 v5, v19, v20 offset0:132 offset1:198
	ds_write2_b32 v9, v21, v22 offset0:8 offset1:74
	ds_write2_b32 v9, v23, v24 offset0:140 offset1:206
	v_add_u32_e32 v9, 0x800, v5
	ds_write2_b32 v9, v25, v26 offset0:16 offset1:82
	ds_write2_b32 v9, v27, v28 offset0:148 offset1:214
	v_add_u32_e32 v9, 0xc00, v5
	ds_write2_b32 v9, v29, v30 offset0:24 offset1:90
	ds_write2_b32 v9, v31, v32 offset0:156 offset1:222
	v_add_u32_e32 v9, 0x1000, v5
	ds_write2_b32 v9, v33, v34 offset0:32 offset1:98
	ds_write2_b32 v9, v35, v36 offset0:164 offset1:230
	v_add_u32_e32 v9, 0x1400, v5
	ds_write2_b32 v9, v37, v38 offset0:40 offset1:106
	ds_write2_b32 v9, v39, v40 offset0:172 offset1:238
	v_add_u32_e32 v9, 0x1800, v5
	ds_write2_b32 v9, v41, v42 offset0:48 offset1:114
	ds_write2_b32 v9, v43, v44 offset0:180 offset1:246
	v_add_u32_e32 v9, 0x1c00, v5
	ds_write2_b32 v9, v45, v46 offset0:56 offset1:122
	ds_write2_b32 v9, v10, v8 offset0:188 offset1:254
	s_waitcnt lgkmcnt(0)
	ds_read2_b32 v[10:11], v13 offset0:33 offset1:41
	ds_read2_b32 v[22:23], v13 offset1:8
	ds_read2_b32 v[24:25], v13 offset0:66 offset1:74
	ds_read2_b32 v[26:27], v13 offset0:99 offset1:107
	ds_read2_b32 v[28:29], v13 offset0:132 offset1:140
	ds_read2_b32 v[30:31], v13 offset0:165 offset1:173
	ds_read2_b32 v[32:33], v13 offset0:198 offset1:206
	ds_read2_b32 v[34:35], v13 offset0:231 offset1:239
	s_waitcnt lgkmcnt(7)
	v_bfe_u32 v18, v10, 16, 1
	s_waitcnt lgkmcnt(6)
	v_bfe_u32 v17, v22, 16, 1
	v_add3_u32 v17, v22, v17, s53
	v_lshrrev_b32_e32 v17, 16, v17
	v_add3_u32 v10, v10, v18, s53
	v_and_or_b32 v18, v10, s77, v17
	s_waitcnt lgkmcnt(5)
	v_bfe_u32 v10, v24, 16, 1
	v_add3_u32 v10, v24, v10, s53
	s_waitcnt lgkmcnt(4)
	v_bfe_u32 v17, v26, 16, 1
	v_lshrrev_b32_e32 v10, 16, v10
	v_add3_u32 v17, v26, v17, s53
	v_and_or_b32 v19, v17, s77, v10
	s_waitcnt lgkmcnt(3)
	v_bfe_u32 v10, v28, 16, 1
	v_add3_u32 v10, v28, v10, s53
	s_waitcnt lgkmcnt(2)
	v_bfe_u32 v17, v30, 16, 1
	v_lshrrev_b32_e32 v10, 16, v10
	v_add3_u32 v17, v30, v17, s53
	v_and_or_b32 v20, v17, s77, v10
	s_waitcnt lgkmcnt(1)
	v_bfe_u32 v10, v32, 16, 1
	s_lshl_b32 s0, s10, 1
	v_add3_u32 v10, v32, v10, s53
	s_waitcnt lgkmcnt(0)
	v_bfe_u32 v17, v34, 16, 1
	s_add_u32 s0, s3, s0
	v_lshrrev_b32_e32 v10, 16, v10
	v_add3_u32 v17, v34, v17, s53
	s_addc_u32 s1, s5, 0
	v_lshlrev_b32_e32 v202, 1, v4
	v_and_or_b32 v21, v17, s77, v10
	v_or_b32_e32 v10, s2, v12
	v_lshl_add_u64 v[8:9], s[0:1], 0, v[202:203]
	v_lshlrev_b32_e32 v202, 12, v10
	v_bfe_u32 v10, v23, 16, 1
	v_add3_u32 v10, v23, v10, s53
	v_bfe_u32 v17, v11, 16, 1
	v_lshl_add_u64 v[36:37], v[8:9], 0, v[202:203]
	v_lshrrev_b32_e32 v10, 16, v10
	v_add3_u32 v11, v11, v17, s53
	global_store_dwordx4 v[36:37], v[18:21], off nt
	v_readlane_b32 s17, v251, 31
	v_readlane_b32 s20, v251, 34
	v_and_or_b32 v18, v11, s77, v10
	v_bfe_u32 v10, v25, 16, 1
	v_add3_u32 v10, v25, v10, s53
	v_bfe_u32 v11, v27, 16, 1
	v_lshrrev_b32_e32 v10, 16, v10
	v_add3_u32 v11, v27, v11, s53
	v_and_or_b32 v19, v11, s77, v10
	v_bfe_u32 v10, v29, 16, 1
	v_add3_u32 v10, v29, v10, s53
	v_bfe_u32 v11, v31, 16, 1
	v_lshrrev_b32_e32 v10, 16, v10
	v_add3_u32 v11, v31, v11, s53
	v_and_or_b32 v20, v11, s77, v10
	v_bfe_u32 v10, v33, 16, 1
	v_add3_u32 v10, v33, v10, s53
	v_bfe_u32 v11, v35, 16, 1
	v_lshrrev_b32_e32 v10, 16, v10
	v_add3_u32 v11, v35, v11, s53
	v_and_or_b32 v21, v11, s77, v10
	v_or_b32_e32 v10, s2, v14
	v_lshlrev_b32_e32 v202, 12, v10
	v_lshl_add_u64 v[10:11], v[8:9], 0, v[202:203]
	global_store_dwordx4 v[10:11], v[18:21], off nt
	ds_read2_b32 v[10:11], v13 offset0:49 offset1:57
	ds_read2_b32 v[22:23], v13 offset0:16 offset1:24
	ds_read2_b32 v[24:25], v13 offset0:82 offset1:90
	ds_read2_b32 v[26:27], v13 offset0:115 offset1:123
	ds_read2_b32 v[28:29], v13 offset0:148 offset1:156
	ds_read2_b32 v[30:31], v13 offset0:181 offset1:189
	ds_read2_b32 v[32:33], v13 offset0:214 offset1:222
	ds_read2_b32 v[34:35], v13 offset0:247 offset1:255
	s_waitcnt lgkmcnt(7)
	v_bfe_u32 v18, v10, 16, 1
	s_waitcnt lgkmcnt(6)
	v_bfe_u32 v17, v22, 16, 1
	v_add3_u32 v17, v22, v17, s53
	v_lshrrev_b32_e32 v17, 16, v17
	v_add3_u32 v10, v10, v18, s53
	v_and_or_b32 v18, v10, s77, v17
	s_waitcnt lgkmcnt(5)
	v_bfe_u32 v10, v24, 16, 1
	v_add3_u32 v10, v24, v10, s53
	s_waitcnt lgkmcnt(4)
	v_bfe_u32 v17, v26, 16, 1
	v_lshrrev_b32_e32 v10, 16, v10
	v_add3_u32 v17, v26, v17, s53
	v_and_or_b32 v19, v17, s77, v10
	s_waitcnt lgkmcnt(3)
	v_bfe_u32 v10, v28, 16, 1
	v_add3_u32 v10, v28, v10, s53
	s_waitcnt lgkmcnt(2)
	v_bfe_u32 v17, v30, 16, 1
	v_lshrrev_b32_e32 v10, 16, v10
	v_add3_u32 v17, v30, v17, s53
	v_and_or_b32 v20, v17, s77, v10
	s_waitcnt lgkmcnt(1)
	v_bfe_u32 v10, v32, 16, 1
	v_add3_u32 v10, v32, v10, s53
	s_waitcnt lgkmcnt(0)
	v_bfe_u32 v17, v34, 16, 1
	v_lshrrev_b32_e32 v10, 16, v10
	v_add3_u32 v17, v34, v17, s53
	v_and_or_b32 v21, v17, s77, v10
	v_or_b32_e32 v10, s2, v15
	v_lshlrev_b32_e32 v202, 12, v10
	v_bfe_u32 v10, v23, 16, 1
	v_add3_u32 v10, v23, v10, s53
	v_bfe_u32 v17, v11, 16, 1
	v_lshl_add_u64 v[36:37], v[8:9], 0, v[202:203]
	v_lshrrev_b32_e32 v10, 16, v10
	v_add3_u32 v11, v11, v17, s53
	global_store_dwordx4 v[36:37], v[18:21], off nt
	v_readlane_b32 s21, v251, 35
	v_readlane_b32 s22, v251, 36
	v_and_or_b32 v18, v11, s77, v10
	v_bfe_u32 v10, v25, 16, 1
	v_add3_u32 v10, v25, v10, s53
	v_bfe_u32 v11, v27, 16, 1
	v_lshrrev_b32_e32 v10, 16, v10
	v_add3_u32 v11, v27, v11, s53
	v_and_or_b32 v19, v11, s77, v10
	v_bfe_u32 v10, v29, 16, 1
	v_add3_u32 v10, v29, v10, s53
	v_bfe_u32 v11, v31, 16, 1
	v_lshrrev_b32_e32 v10, 16, v10
	v_add3_u32 v11, v31, v11, s53
	v_and_or_b32 v20, v11, s77, v10
	v_bfe_u32 v10, v33, 16, 1
	v_add3_u32 v10, v33, v10, s53
	v_bfe_u32 v11, v35, 16, 1
	v_lshrrev_b32_e32 v10, 16, v10
	v_add3_u32 v11, v35, v11, s53
	v_and_or_b32 v21, v11, s77, v10
	v_or_b32_e32 v10, s2, v16
	v_lshlrev_b32_e32 v202, 12, v10
	v_lshl_add_u64 v[8:9], v[8:9], 0, v[202:203]
	global_store_dwordx4 v[8:9], v[18:21], off nt
	s_waitcnt lgkmcnt(0)
	v_readlane_b32 s23, v251, 37
	v_readlane_b32 s24, v251, 38
	v_readlane_b32 s25, v251, 39
	v_readlane_b32 s26, v251, 40
	v_readlane_b32 s27, v251, 41
	v_readlane_b32 s28, v251, 42
	v_readlane_b32 s29, v251, 43
	v_readlane_b32 s30, v251, 44
	v_readlane_b32 s31, v251, 45

.LBB0_1641:
	s_andn2_b64 vcc, exec, s[2:3]
	s_cbranch_vccnz .LBB0_1650
	s_add_i32 s1, s4, 0xffffa000
	s_mul_hi_u32 s0, s1, 0x3e0f83e1
	s_lshr_b32 s0, s0, 12
	s_mul_i32 s2, s0, 0x4200
	s_sub_i32 s1, s1, s2
	s_mul_i32 s2, s1, 0xba2f
	s_lshr_b32 s2, s2, 28
	s_mulk_i32 s2, 0x1600
	s_sub_i32 s5, s1, s2
	s_cmpk_gt_u32 s1, 0x15ff
	s_mul_hi_u32 s10, s0, 0x2c00000
	s_mul_i32 s11, s0, 0x2c00000
	s_mov_b64 s[2:3], -1
	s_cbranch_scc0 .LBB0_1648
	s_addk_i32 s1, 0xea00
	s_cmpk_gt_u32 s1, 0x15ff
	s_cbranch_scc0 .LBB0_1645
	v_readlane_b32 s16, v251, 14
	v_readlane_b32 s20, v251, 18
	v_readlane_b32 s21, v251, 19
	s_add_u32 s1, s20, s11
	s_addc_u32 s16, s21, s10
	s_mul_hi_u32 s2, s0, 0x1600000
	s_mul_i32 s0, s0, 0x1600000
	v_readlane_b32 s3, v251, 54
	s_add_u32 s3, s3, s0
	v_readlane_b32 s0, v251, 55
	s_addc_u32 s14, s0, s2
	s_lshl_b32 s0, s5, 5
	s_and_b32 s2, s0, 0x7e0
	s_and_b32 s15, s5, 0x1fc0
	s_lshl_b32 s0, s2, 2
	s_add_u32 s0, s1, s0
	v_or_b32_e32 v10, s15, v3
	s_addc_u32 s1, s16, 0
	v_lshlrev_b32_e32 v202, 2, v2
	v_lshl_add_u64 v[8:9], s[0:1], 0, v[202:203]
	v_lshlrev_b32_e32 v202, 13, v10
	v_lshl_add_u64 v[8:9], v[8:9], 0, v[202:203]
	v_add_co_u32_e32 v10, vcc, s89, v8
	s_mov_b32 s0, 0x8000
	s_nop 0
	v_addc_co_u32_e32 v11, vcc, 0, v9, vcc
	global_load_dword v17, v[8:9], off nt
	global_load_dword v18, v[10:11], off nt
	v_add_co_u32_e32 v10, vcc, s0, v8
	s_mov_b32 s0, 0xc000
	s_nop 0
	v_addc_co_u32_e32 v11, vcc, 0, v9, vcc
	global_load_dword v19, v[10:11], off nt
	v_add_co_u32_e32 v10, vcc, s0, v8
	s_mov_b32 s0, 0x10000
	s_nop 0
	v_addc_co_u32_e32 v11, vcc, 0, v9, vcc
	global_load_dword v20, v[10:11], off nt
	v_add_co_u32_e32 v10, vcc, s0, v8
	s_mov_b32 s0, 0x14000
	s_nop 0
	v_addc_co_u32_e32 v11, vcc, 0, v9, vcc
	global_load_dword v21, v[10:11], off nt
	v_add_co_u32_e32 v10, vcc, s0, v8
	s_mov_b32 s0, 0x18000
	s_nop 0
	v_addc_co_u32_e32 v11, vcc, 0, v9, vcc
	global_load_dword v22, v[10:11], off nt
	v_add_co_u32_e32 v10, vcc, s0, v8
	s_mov_b32 s0, 0x1c000
	s_nop 0
	v_addc_co_u32_e32 v11, vcc, 0, v9, vcc
	global_load_dword v23, v[10:11], off nt
	v_add_co_u32_e32 v10, vcc, s0, v8
	s_mov_b32 s0, 0x20000
	s_nop 0
	v_addc_co_u32_e32 v11, vcc, 0, v9, vcc
	global_load_dword v24, v[10:11], off nt
	v_add_co_u32_e32 v10, vcc, s0, v8
	s_mov_b32 s0, 0x24000
	s_nop 0
	v_addc_co_u32_e32 v11, vcc, 0, v9, vcc
	global_load_dword v25, v[10:11], off nt
	v_add_co_u32_e32 v10, vcc, s0, v8
	s_mov_b32 s0, 0x28000
	s_nop 0
	v_addc_co_u32_e32 v11, vcc, 0, v9, vcc
	global_load_dword v26, v[10:11], off nt
	v_add_co_u32_e32 v10, vcc, s0, v8
	s_mov_b32 s0, 0x2c000
	s_nop 0
	v_addc_co_u32_e32 v11, vcc, 0, v9, vcc
	global_load_dword v27, v[10:11], off nt
	v_add_co_u32_e32 v10, vcc, s0, v8
	s_mov_b32 s0, 0x30000
	s_nop 0
	v_addc_co_u32_e32 v11, vcc, 0, v9, vcc
	global_load_dword v28, v[10:11], off nt
	v_add_co_u32_e32 v10, vcc, s0, v8
	s_mov_b32 s0, 0x34000
	s_nop 0
	v_addc_co_u32_e32 v11, vcc, 0, v9, vcc
	global_load_dword v29, v[10:11], off nt
	v_add_co_u32_e32 v10, vcc, s0, v8
	s_mov_b32 s0, 0x38000
	s_nop 0
	v_addc_co_u32_e32 v11, vcc, 0, v9, vcc
	global_load_dword v30, v[10:11], off nt
	v_add_co_u32_e32 v10, vcc, s0, v8
	s_mov_b32 s0, 0x3c000
	s_nop 0
	v_addc_co_u32_e32 v11, vcc, 0, v9, vcc
	global_load_dword v31, v[10:11], off nt
	v_add_co_u32_e32 v10, vcc, s0, v8
	s_mov_b32 s0, 0x40000
	s_nop 0
	v_addc_co_u32_e32 v11, vcc, 0, v9, vcc
	global_load_dword v32, v[10:11], off nt
	v_add_co_u32_e32 v10, vcc, s0, v8
	s_mov_b32 s0, 0x44000
	s_nop 0
	v_addc_co_u32_e32 v11, vcc, 0, v9, vcc
	global_load_dword v33, v[10:11], off nt
	v_add_co_u32_e32 v10, vcc, s0, v8
	s_mov_b32 s0, 0x48000
	s_nop 0
	v_addc_co_u32_e32 v11, vcc, 0, v9, vcc
	global_load_dword v34, v[10:11], off nt
	v_add_co_u32_e32 v10, vcc, s0, v8
	s_mov_b32 s0, 0x4c000
	s_nop 0
	v_addc_co_u32_e32 v11, vcc, 0, v9, vcc
	global_load_dword v35, v[10:11], off nt
	v_add_co_u32_e32 v10, vcc, s0, v8
	s_mov_b32 s0, 0x50000
	s_nop 0
	v_addc_co_u32_e32 v11, vcc, 0, v9, vcc
	global_load_dword v36, v[10:11], off nt
	v_add_co_u32_e32 v10, vcc, s0, v8
	s_mov_b32 s0, 0x54000
	s_nop 0
	v_addc_co_u32_e32 v11, vcc, 0, v9, vcc
	global_load_dword v37, v[10:11], off nt
	v_add_co_u32_e32 v10, vcc, s0, v8
	s_mov_b32 s0, 0x58000
	s_nop 0
	v_addc_co_u32_e32 v11, vcc, 0, v9, vcc
	global_load_dword v38, v[10:11], off nt
	v_add_co_u32_e32 v10, vcc, s0, v8
	s_mov_b32 s0, 0x5c000
	s_nop 0
	v_addc_co_u32_e32 v11, vcc, 0, v9, vcc
	global_load_dword v39, v[10:11], off nt
	v_add_co_u32_e32 v10, vcc, s0, v8
	s_mov_b32 s0, 0x60000
	s_nop 0
	v_addc_co_u32_e32 v11, vcc, 0, v9, vcc
	global_load_dword v40, v[10:11], off nt
	v_add_co_u32_e32 v10, vcc, s0, v8
	s_mov_b32 s0, 0x64000
	s_nop 0
	v_addc_co_u32_e32 v11, vcc, 0, v9, vcc
	global_load_dword v41, v[10:11], off nt
	v_add_co_u32_e32 v10, vcc, s0, v8
	s_mov_b32 s0, 0x68000
	s_nop 0
	v_addc_co_u32_e32 v11, vcc, 0, v9, vcc
	global_load_dword v42, v[10:11], off nt
	v_add_co_u32_e32 v10, vcc, s0, v8
	s_mov_b32 s0, 0x6c000
	s_nop 0
	v_addc_co_u32_e32 v11, vcc, 0, v9, vcc
	global_load_dword v43, v[10:11], off nt
	v_add_co_u32_e32 v10, vcc, s0, v8
	s_mov_b32 s0, 0x70000
	s_nop 0
	v_addc_co_u32_e32 v11, vcc, 0, v9, vcc
	global_load_dword v44, v[10:11], off nt
	v_add_co_u32_e32 v10, vcc, s0, v8
	s_mov_b32 s0, 0x74000
	s_nop 0
	v_addc_co_u32_e32 v11, vcc, 0, v9, vcc
	global_load_dword v45, v[10:11], off nt
	v_add_co_u32_e32 v10, vcc, s0, v8
	s_mov_b32 s0, 0x78000
	s_nop 0
	v_addc_co_u32_e32 v11, vcc, 0, v9, vcc
	global_load_dword v46, v[10:11], off nt
	v_add_co_u32_e32 v10, vcc, s0, v8
	s_mov_b32 s0, 0x7c000
	s_nop 0
	v_addc_co_u32_e32 v11, vcc, 0, v9, vcc
	v_add_co_u32_e32 v8, vcc, s0, v8
	global_load_dword v10, v[10:11], off nt
	s_nop 0
	v_addc_co_u32_e32 v9, vcc, 0, v9, vcc
	global_load_dword v8, v[8:9], off nt
	v_add_u32_e32 v9, 0x400, v5
	s_waitcnt vmcnt(0)
	ds_write2_b32 v5, v17, v18 offset1:66
	ds_write2_b32 v5, v19, v20 offset0:132 offset1:198
	ds_write2_b32 v9, v21, v22 offset0:8 offset1:74
	ds_write2_b32 v9, v23, v24 offset0:140 offset1:206
	v_add_u32_e32 v9, 0x800, v5
	ds_write2_b32 v9, v25, v26 offset0:16 offset1:82
	ds_write2_b32 v9, v27, v28 offset0:148 offset1:214
	v_add_u32_e32 v9, 0xc00, v5
	ds_write2_b32 v9, v29, v30 offset0:24 offset1:90
	ds_write2_b32 v9, v31, v32 offset0:156 offset1:222
	v_add_u32_e32 v9, 0x1000, v5
	ds_write2_b32 v9, v33, v34 offset0:32 offset1:98
	ds_write2_b32 v9, v35, v36 offset0:164 offset1:230
	v_add_u32_e32 v9, 0x1400, v5
	ds_write2_b32 v9, v37, v38 offset0:40 offset1:106
	ds_write2_b32 v9, v39, v40 offset0:172 offset1:238
	v_add_u32_e32 v9, 0x1800, v5
	ds_write2_b32 v9, v41, v42 offset0:48 offset1:114
	ds_write2_b32 v9, v43, v44 offset0:180 offset1:246
	v_add_u32_e32 v9, 0x1c00, v5
	ds_write2_b32 v9, v45, v46 offset0:56 offset1:122
	ds_write2_b32 v9, v10, v8 offset0:188 offset1:254
	s_waitcnt lgkmcnt(0)
	ds_read2_b32 v[10:11], v13 offset0:33 offset1:41
	ds_read2_b32 v[22:23], v13 offset1:8
	ds_read2_b32 v[24:25], v13 offset0:66 offset1:74
	ds_read2_b32 v[26:27], v13 offset0:99 offset1:107
	ds_read2_b32 v[28:29], v13 offset0:132 offset1:140
	ds_read2_b32 v[30:31], v13 offset0:165 offset1:173
	ds_read2_b32 v[32:33], v13 offset0:198 offset1:206
	ds_read2_b32 v[34:35], v13 offset0:231 offset1:239
	s_waitcnt lgkmcnt(7)
	v_bfe_u32 v18, v10, 16, 1
	s_waitcnt lgkmcnt(6)
	v_bfe_u32 v17, v22, 16, 1
	v_add3_u32 v17, v22, v17, s53
	v_lshrrev_b32_e32 v17, 16, v17
	v_add3_u32 v10, v10, v18, s53
	v_and_or_b32 v18, v10, s77, v17
	s_waitcnt lgkmcnt(5)
	v_bfe_u32 v10, v24, 16, 1
	v_add3_u32 v10, v24, v10, s53
	s_waitcnt lgkmcnt(4)
	v_bfe_u32 v17, v26, 16, 1
	v_lshrrev_b32_e32 v10, 16, v10
	v_add3_u32 v17, v26, v17, s53
	v_and_or_b32 v19, v17, s77, v10
	s_waitcnt lgkmcnt(3)
	v_bfe_u32 v10, v28, 16, 1
	v_add3_u32 v10, v28, v10, s53
	s_waitcnt lgkmcnt(2)
	v_bfe_u32 v17, v30, 16, 1
	v_lshrrev_b32_e32 v10, 16, v10
	v_add3_u32 v17, v30, v17, s53
	v_and_or_b32 v20, v17, s77, v10
	s_waitcnt lgkmcnt(1)
	v_bfe_u32 v10, v32, 16, 1
	v_add3_u32 v10, v32, v10, s53
	s_waitcnt lgkmcnt(0)
	v_bfe_u32 v17, v34, 16, 1
	s_lshl_b32 s0, s15, 1
	v_lshrrev_b32_e32 v10, 16, v10
	v_add3_u32 v17, v34, v17, s53
	s_add_u32 s0, s3, s0
	v_and_or_b32 v21, v17, s77, v10
	v_or_b32_e32 v10, s2, v12
	s_addc_u32 s1, s14, 0
	v_lshlrev_b32_e32 v202, 1, v4
	v_mul_u32_u24_e32 v10, 0x1600, v10
	v_lshl_add_u64 v[8:9], s[0:1], 0, v[202:203]
	v_lshlrev_b32_e32 v202, 1, v10
	v_bfe_u32 v10, v23, 16, 1
	v_add3_u32 v10, v23, v10, s53
	v_bfe_u32 v17, v11, 16, 1
	v_lshl_add_u64 v[36:37], v[8:9], 0, v[202:203]
	v_lshrrev_b32_e32 v10, 16, v10
	v_add3_u32 v11, v11, v17, s53
	global_store_dwordx4 v[36:37], v[18:21], off nt
	v_readlane_b32 s17, v251, 15
	v_readlane_b32 s18, v251, 16
	v_and_or_b32 v18, v11, s77, v10
	v_bfe_u32 v10, v25, 16, 1
	v_add3_u32 v10, v25, v10, s53
	v_bfe_u32 v11, v27, 16, 1
	v_lshrrev_b32_e32 v10, 16, v10
	v_add3_u32 v11, v27, v11, s53
	v_and_or_b32 v19, v11, s77, v10
	v_bfe_u32 v10, v29, 16, 1
	v_add3_u32 v10, v29, v10, s53
	v_bfe_u32 v11, v31, 16, 1
	v_lshrrev_b32_e32 v10, 16, v10
	v_add3_u32 v11, v31, v11, s53
	v_and_or_b32 v20, v11, s77, v10
	v_bfe_u32 v10, v33, 16, 1
	v_add3_u32 v10, v33, v10, s53
	v_bfe_u32 v11, v35, 16, 1
	v_lshrrev_b32_e32 v10, 16, v10
	v_add3_u32 v11, v35, v11, s53
	v_and_or_b32 v21, v11, s77, v10
	v_or_b32_e32 v10, s2, v14
	v_mul_u32_u24_e32 v10, 0x1600, v10
	v_lshlrev_b32_e32 v202, 1, v10
	v_lshl_add_u64 v[10:11], v[8:9], 0, v[202:203]
	global_store_dwordx4 v[10:11], v[18:21], off nt
	ds_read2_b32 v[10:11], v13 offset0:16 offset1:24
	ds_read2_b32 v[22:23], v13 offset0:49 offset1:57
	ds_read2_b32 v[24:25], v13 offset0:82 offset1:90
	ds_read2_b32 v[26:27], v13 offset0:115 offset1:123
	ds_read2_b32 v[28:29], v13 offset0:148 offset1:156
	ds_read2_b32 v[30:31], v13 offset0:181 offset1:189
	ds_read2_b32 v[32:33], v13 offset0:214 offset1:222
	ds_read2_b32 v[34:35], v13 offset0:247 offset1:255
	s_waitcnt lgkmcnt(7)
	v_bfe_u32 v17, v10, 16, 1
	v_add3_u32 v10, v10, v17, s53
	s_waitcnt lgkmcnt(6)
	v_bfe_u32 v17, v22, 16, 1
	v_lshrrev_b32_e32 v10, 16, v10
	v_add3_u32 v17, v22, v17, s53
	v_and_or_b32 v18, v17, s77, v10
	s_waitcnt lgkmcnt(5)
	v_bfe_u32 v10, v24, 16, 1
	v_add3_u32 v10, v24, v10, s53
	s_waitcnt lgkmcnt(4)
	v_bfe_u32 v17, v26, 16, 1
	v_lshrrev_b32_e32 v10, 16, v10
	v_add3_u32 v17, v26, v17, s53
	v_and_or_b32 v19, v17, s77, v10
	s_waitcnt lgkmcnt(3)
	v_bfe_u32 v10, v28, 16, 1
	v_add3_u32 v10, v28, v10, s53
	s_waitcnt lgkmcnt(2)
	v_bfe_u32 v17, v30, 16, 1
	v_lshrrev_b32_e32 v10, 16, v10
	v_add3_u32 v17, v30, v17, s53
	v_and_or_b32 v20, v17, s77, v10
	s_waitcnt lgkmcnt(1)
	v_bfe_u32 v10, v32, 16, 1
	v_add3_u32 v10, v32, v10, s53
	s_waitcnt lgkmcnt(0)
	v_bfe_u32 v17, v34, 16, 1
	v_lshrrev_b32_e32 v10, 16, v10
	v_add3_u32 v17, v34, v17, s53
	v_and_or_b32 v21, v17, s77, v10
	v_or_b32_e32 v10, s2, v15
	v_mul_u32_u24_e32 v10, 0x1600, v10
	v_lshlrev_b32_e32 v202, 1, v10
	v_bfe_u32 v10, v11, 16, 1
	v_add3_u32 v10, v11, v10, s53
	v_bfe_u32 v11, v23, 16, 1
	v_lshl_add_u64 v[36:37], v[8:9], 0, v[202:203]
	v_lshrrev_b32_e32 v10, 16, v10
	v_add3_u32 v11, v23, v11, s53
	global_store_dwordx4 v[36:37], v[18:21], off nt
	v_readlane_b32 s19, v251, 17
	v_readlane_b32 s22, v251, 20
	v_and_or_b32 v18, v11, s77, v10
	v_bfe_u32 v10, v25, 16, 1
	v_add3_u32 v10, v25, v10, s53
	v_bfe_u32 v11, v27, 16, 1
	v_lshrrev_b32_e32 v10, 16, v10
	v_add3_u32 v11, v27, v11, s53
	v_and_or_b32 v19, v11, s77, v10
	v_bfe_u32 v10, v29, 16, 1
	v_add3_u32 v10, v29, v10, s53
	v_bfe_u32 v11, v31, 16, 1
	v_lshrrev_b32_e32 v10, 16, v10
	v_add3_u32 v11, v31, v11, s53
	v_and_or_b32 v20, v11, s77, v10
	v_bfe_u32 v10, v33, 16, 1
	v_add3_u32 v10, v33, v10, s53
	v_bfe_u32 v11, v35, 16, 1
	v_lshrrev_b32_e32 v10, 16, v10
	v_add3_u32 v11, v35, v11, s53
	v_and_or_b32 v21, v11, s77, v10
	v_or_b32_e32 v10, s2, v16
	v_mul_u32_u24_e32 v10, 0x1600, v10
	v_lshlrev_b32_e32 v202, 1, v10
	v_lshl_add_u64 v[8:9], v[8:9], 0, v[202:203]
	global_store_dwordx4 v[8:9], v[18:21], off nt
	s_waitcnt lgkmcnt(0)
	v_readlane_b32 s23, v251, 21
	v_readlane_b32 s24, v251, 22
	v_readlane_b32 s25, v251, 23
	v_readlane_b32 s26, v251, 24
	v_readlane_b32 s27, v251, 25
	v_readlane_b32 s28, v251, 26
	v_readlane_b32 s29, v251, 27
	v_readlane_b32 s30, v251, 28
	v_readlane_b32 s31, v251, 29
	s_mov_b64 s[2:3], 0
.LBB0_1645:
	s_andn2_b64 vcc, exec, s[2:3]
	s_cbranch_vccnz .LBB0_1647
	v_readlane_b32 s16, v251, 14
	v_readlane_b32 s18, v251, 16
	v_readlane_b32 s19, v251, 17
	s_add_u32 s0, s18, s11
	s_addc_u32 s1, s19, s10
	v_readlane_b32 s2, v251, 56
	s_add_u32 s3, s2, s11
	v_readlane_b32 s2, v251, 57
	s_addc_u32 s14, s2, s10
	s_and_b32 s2, 0xffff, s5
	s_mul_i32 s2, s2, 0xba2f
	s_lshr_b32 s15, s2, 23
	s_mul_i32 s2, s15, 0xb0
	s_sub_i32 s2, s5, s2
	v_readlane_b32 s17, v251, 15
	s_and_b32 s16, s2, 0xffff
	s_lshl_b32 s2, s16, 5
	s_lshl_b32 s17, s16, 6
	s_and_b32 s17, s17, 0x3f00
	s_and_b32 s2, s2, 0x60
	s_or_b32 s2, s17, s2
	s_bitset1_b32 s2, 7
	s_lshl_b32 s16, s16, 7
	v_lshl_or_b32 v10, s15, 6, v3
	s_add_u32 s0, s0, s16
	s_addc_u32 s1, s1, 0
	v_lshlrev_b32_e32 v202, 2, v2
	v_mul_u32_u24_e32 v10, 0x1600, v10
	v_lshl_add_u64 v[8:9], s[0:1], 0, v[202:203]
	v_lshlrev_b32_e32 v202, 2, v10
	v_lshl_add_u64 v[8:9], v[8:9], 0, v[202:203]
	s_mov_b32 s0, 0xb000
	v_add_co_u32_e32 v10, vcc, s0, v8
	s_mov_b32 s0, 0x16000
	s_nop 0
	v_addc_co_u32_e32 v11, vcc, 0, v9, vcc
	global_load_dword v17, v[8:9], off nt
	global_load_dword v18, v[10:11], off nt
	v_add_co_u32_e32 v10, vcc, s0, v8
	s_mov_b32 s0, 0x21000
	s_nop 0
	v_addc_co_u32_e32 v11, vcc, 0, v9, vcc
	global_load_dword v19, v[10:11], off nt
	v_add_co_u32_e32 v10, vcc, s0, v8
	s_mov_b32 s0, 0x2c000
	s_nop 0
	v_addc_co_u32_e32 v11, vcc, 0, v9, vcc
	global_load_dword v20, v[10:11], off nt
	v_add_co_u32_e32 v10, vcc, s0, v8
	s_mov_b32 s0, 0x37000
	s_nop 0
	v_addc_co_u32_e32 v11, vcc, 0, v9, vcc
	global_load_dword v21, v[10:11], off nt
	v_add_co_u32_e32 v10, vcc, s0, v8
	s_mov_b32 s0, 0x42000
	s_nop 0
	v_addc_co_u32_e32 v11, vcc, 0, v9, vcc
	global_load_dword v22, v[10:11], off nt
	v_add_co_u32_e32 v10, vcc, s0, v8
	s_mov_b32 s0, 0x4d000
	s_nop 0
	v_addc_co_u32_e32 v11, vcc, 0, v9, vcc
	global_load_dword v23, v[10:11], off nt
	v_add_co_u32_e32 v10, vcc, s0, v8
	s_mov_b32 s0, 0x58000
	s_nop 0
	v_addc_co_u32_e32 v11, vcc, 0, v9, vcc
	global_load_dword v24, v[10:11], off nt
	v_add_co_u32_e32 v10, vcc, s0, v8
	s_mov_b32 s0, 0x63000
	s_nop 0
	v_addc_co_u32_e32 v11, vcc, 0, v9, vcc
	global_load_dword v25, v[10:11], off nt
	v_add_co_u32_e32 v10, vcc, s0, v8
	s_mov_b32 s0, 0x6e000
	s_nop 0
	v_addc_co_u32_e32 v11, vcc, 0, v9, vcc
	global_load_dword v26, v[10:11], off nt
	v_add_co_u32_e32 v10, vcc, s0, v8
	s_mov_b32 s0, 0x79000
	s_nop 0
	v_addc_co_u32_e32 v11, vcc, 0, v9, vcc
	global_load_dword v27, v[10:11], off nt
	v_add_co_u32_e32 v10, vcc, s0, v8
	s_mov_b32 s0, 0x84000
	s_nop 0
	v_addc_co_u32_e32 v11, vcc, 0, v9, vcc
	global_load_dword v28, v[10:11], off nt
	v_add_co_u32_e32 v10, vcc, s0, v8
	s_mov_b32 s0, 0x8f000
	s_nop 0
	v_addc_co_u32_e32 v11, vcc, 0, v9, vcc
	global_load_dword v29, v[10:11], off nt
	v_add_co_u32_e32 v10, vcc, s0, v8
	s_mov_b32 s0, 0x9a000
	s_nop 0
	v_addc_co_u32_e32 v11, vcc, 0, v9, vcc
	global_load_dword v30, v[10:11], off nt
	v_add_co_u32_e32 v10, vcc, s0, v8
	s_mov_b32 s0, 0xa5000
	s_nop 0
	v_addc_co_u32_e32 v11, vcc, 0, v9, vcc
	global_load_dword v31, v[10:11], off nt
	v_add_co_u32_e32 v10, vcc, s0, v8
	s_mov_b32 s0, 0xb0000
	s_nop 0
	v_addc_co_u32_e32 v11, vcc, 0, v9, vcc
	global_load_dword v32, v[10:11], off nt
	v_add_co_u32_e32 v10, vcc, s0, v8
	s_mov_b32 s0, 0xbb000
	s_nop 0
	v_addc_co_u32_e32 v11, vcc, 0, v9, vcc
	global_load_dword v33, v[10:11], off nt
	v_add_co_u32_e32 v10, vcc, s0, v8
	s_mov_b32 s0, 0xc6000
	s_nop 0
	v_addc_co_u32_e32 v11, vcc, 0, v9, vcc
	global_load_dword v34, v[10:11], off nt
	v_add_co_u32_e32 v10, vcc, s0, v8
	s_mov_b32 s0, 0xd1000
	s_nop 0
	v_addc_co_u32_e32 v11, vcc, 0, v9, vcc
	global_load_dword v35, v[10:11], off nt
	v_add_co_u32_e32 v10, vcc, s0, v8
	s_mov_b32 s0, 0xdc000
	s_nop 0
	v_addc_co_u32_e32 v11, vcc, 0, v9, vcc
	global_load_dword v36, v[10:11], off nt
	v_add_co_u32_e32 v10, vcc, s0, v8
	s_mov_b32 s0, 0xe7000
	s_nop 0
	v_addc_co_u32_e32 v11, vcc, 0, v9, vcc
	global_load_dword v37, v[10:11], off nt
	v_add_co_u32_e32 v10, vcc, s0, v8
	s_mov_b32 s0, 0xf2000
	s_nop 0
	v_addc_co_u32_e32 v11, vcc, 0, v9, vcc
	global_load_dword v38, v[10:11], off nt
	v_add_co_u32_e32 v10, vcc, s0, v8
	s_mov_b32 s0, 0xfd000
	s_nop 0
	v_addc_co_u32_e32 v11, vcc, 0, v9, vcc
	global_load_dword v39, v[10:11], off nt
	v_add_co_u32_e32 v10, vcc, s0, v8
	s_mov_b32 s0, 0x108000
	s_nop 0
	v_addc_co_u32_e32 v11, vcc, 0, v9, vcc
	global_load_dword v40, v[10:11], off nt
	v_add_co_u32_e32 v10, vcc, s0, v8
	s_mov_b32 s0, 0x113000
	s_nop 0
	v_addc_co_u32_e32 v11, vcc, 0, v9, vcc
	global_load_dword v41, v[10:11], off nt
	v_add_co_u32_e32 v10, vcc, s0, v8
	s_mov_b32 s0, 0x11e000
	s_nop 0
	v_addc_co_u32_e32 v11, vcc, 0, v9, vcc
	global_load_dword v42, v[10:11], off nt
	v_add_co_u32_e32 v10, vcc, s0, v8
	s_mov_b32 s0, 0x129000
	s_nop 0
	v_addc_co_u32_e32 v11, vcc, 0, v9, vcc
	global_load_dword v43, v[10:11], off nt
	v_add_co_u32_e32 v10, vcc, s0, v8
	s_mov_b32 s0, 0x134000
	s_nop 0
	v_addc_co_u32_e32 v11, vcc, 0, v9, vcc
	global_load_dword v44, v[10:11], off nt
	v_add_co_u32_e32 v10, vcc, s0, v8
	s_mov_b32 s0, 0x13f000
	s_nop 0
	v_addc_co_u32_e32 v11, vcc, 0, v9, vcc
	global_load_dword v45, v[10:11], off nt
	v_add_co_u32_e32 v10, vcc, s0, v8
	s_mov_b32 s0, 0x14a000
	s_nop 0
	v_addc_co_u32_e32 v11, vcc, 0, v9, vcc
	global_load_dword v46, v[10:11], off nt
	v_add_co_u32_e32 v10, vcc, s0, v8
	s_mov_b32 s0, 0x155000
	s_nop 0
	v_addc_co_u32_e32 v11, vcc, 0, v9, vcc
	v_add_co_u32_e32 v8, vcc, s0, v8
	global_load_dword v10, v[10:11], off nt
	s_nop 0
	v_addc_co_u32_e32 v9, vcc, 0, v9, vcc
	global_load_dword v8, v[8:9], off nt
	v_add_u32_e32 v9, 0x400, v5
	s_waitcnt vmcnt(0)
	ds_write2_b32 v5, v17, v18 offset1:66
	ds_write2_b32 v5, v19, v20 offset0:132 offset1:198
	ds_write2_b32 v9, v21, v22 offset0:8 offset1:74
	ds_write2_b32 v9, v23, v24 offset0:140 offset1:206
	v_add_u32_e32 v9, 0x800, v5
	ds_write2_b32 v9, v25, v26 offset0:16 offset1:82
	ds_write2_b32 v9, v27, v28 offset0:148 offset1:214
	v_add_u32_e32 v9, 0xc00, v5
	ds_write2_b32 v9, v29, v30 offset0:24 offset1:90
	ds_write2_b32 v9, v31, v32 offset0:156 offset1:222
	v_add_u32_e32 v9, 0x1000, v5
	ds_write2_b32 v9, v33, v34 offset0:32 offset1:98
	ds_write2_b32 v9, v35, v36 offset0:164 offset1:230
	v_add_u32_e32 v9, 0x1400, v5
	ds_write2_b32 v9, v37, v38 offset0:40 offset1:106
	ds_write2_b32 v9, v39, v40 offset0:172 offset1:238
	v_add_u32_e32 v9, 0x1800, v5
	ds_write2_b32 v9, v41, v42 offset0:48 offset1:114
	ds_write2_b32 v9, v43, v44 offset0:180 offset1:246
	v_add_u32_e32 v9, 0x1c00, v5
	ds_write2_b32 v9, v45, v46 offset0:56 offset1:122
	ds_write2_b32 v9, v10, v8 offset0:188 offset1:254
	s_waitcnt lgkmcnt(0)
	ds_read2_b32 v[10:11], v13 offset0:33 offset1:41
	ds_read2_b32 v[22:23], v13 offset1:8
	ds_read2_b32 v[24:25], v13 offset0:66 offset1:74
	ds_read2_b32 v[26:27], v13 offset0:99 offset1:107
	ds_read2_b32 v[28:29], v13 offset0:132 offset1:140
	ds_read2_b32 v[30:31], v13 offset0:165 offset1:173
	ds_read2_b32 v[32:33], v13 offset0:198 offset1:206
	ds_read2_b32 v[34:35], v13 offset0:231 offset1:239
	s_waitcnt lgkmcnt(7)
	v_bfe_u32 v18, v10, 16, 1
	s_waitcnt lgkmcnt(6)
	v_bfe_u32 v17, v22, 16, 1
	v_add3_u32 v17, v22, v17, s53
	v_lshrrev_b32_e32 v17, 16, v17
	v_add3_u32 v10, v10, v18, s53
	v_and_or_b32 v18, v10, s77, v17
	s_waitcnt lgkmcnt(5)
	v_bfe_u32 v10, v24, 16, 1
	v_add3_u32 v10, v24, v10, s53
	s_waitcnt lgkmcnt(4)
	v_bfe_u32 v17, v26, 16, 1
	v_lshrrev_b32_e32 v10, 16, v10
	v_add3_u32 v17, v26, v17, s53
	v_and_or_b32 v19, v17, s77, v10
	s_waitcnt lgkmcnt(3)
	v_bfe_u32 v10, v28, 16, 1
	v_add3_u32 v10, v28, v10, s53
	s_waitcnt lgkmcnt(2)
	v_bfe_u32 v17, v30, 16, 1
	v_lshrrev_b32_e32 v10, 16, v10
	v_add3_u32 v17, v30, v17, s53
	v_and_or_b32 v20, v17, s77, v10
	s_waitcnt lgkmcnt(1)
	v_bfe_u32 v10, v32, 16, 1
	s_lshl_b32 s0, s15, 7
	v_add3_u32 v10, v32, v10, s53
	s_waitcnt lgkmcnt(0)
	v_bfe_u32 v17, v34, 16, 1
	s_add_u32 s0, s3, s0
	v_lshrrev_b32_e32 v10, 16, v10
	v_add3_u32 v17, v34, v17, s53
	s_addc_u32 s1, s14, 0
	v_lshlrev_b32_e32 v202, 1, v4
	v_and_or_b32 v21, v17, s77, v10
	v_or_b32_e32 v10, s2, v12
	v_lshl_add_u64 v[8:9], s[0:1], 0, v[202:203]
	v_lshlrev_b32_e32 v202, 12, v10
	v_bfe_u32 v10, v23, 16, 1
	v_add3_u32 v10, v23, v10, s53
	v_bfe_u32 v17, v11, 16, 1
	v_lshl_add_u64 v[36:37], v[8:9], 0, v[202:203]
	v_lshrrev_b32_e32 v10, 16, v10
	v_add3_u32 v11, v11, v17, s53
	global_store_dwordx4 v[36:37], v[18:21], off nt
	v_readlane_b32 s20, v251, 18
	v_readlane_b32 s21, v251, 19
	v_and_or_b32 v18, v11, s77, v10
	v_bfe_u32 v10, v25, 16, 1
	v_add3_u32 v10, v25, v10, s53
	v_bfe_u32 v11, v27, 16, 1
	v_lshrrev_b32_e32 v10, 16, v10
	v_add3_u32 v11, v27, v11, s53
	v_and_or_b32 v19, v11, s77, v10
	v_bfe_u32 v10, v29, 16, 1
	v_add3_u32 v10, v29, v10, s53
	v_bfe_u32 v11, v31, 16, 1
	v_lshrrev_b32_e32 v10, 16, v10
	v_add3_u32 v11, v31, v11, s53
	v_and_or_b32 v20, v11, s77, v10
	v_bfe_u32 v10, v33, 16, 1
	v_add3_u32 v10, v33, v10, s53
	v_bfe_u32 v11, v35, 16, 1
	v_lshrrev_b32_e32 v10, 16, v10
	v_add3_u32 v11, v35, v11, s53
	v_and_or_b32 v21, v11, s77, v10
	v_or_b32_e32 v10, s2, v14
	v_lshlrev_b32_e32 v202, 12, v10
	v_lshl_add_u64 v[10:11], v[8:9], 0, v[202:203]
	global_store_dwordx4 v[10:11], v[18:21], off nt
	ds_read2_b32 v[10:11], v13 offset0:49 offset1:57
	ds_read2_b32 v[22:23], v13 offset0:16 offset1:24
	ds_read2_b32 v[24:25], v13 offset0:82 offset1:90
	ds_read2_b32 v[26:27], v13 offset0:115 offset1:123
	ds_read2_b32 v[28:29], v13 offset0:148 offset1:156
	ds_read2_b32 v[30:31], v13 offset0:181 offset1:189
	ds_read2_b32 v[32:33], v13 offset0:214 offset1:222
	ds_read2_b32 v[34:35], v13 offset0:247 offset1:255
	s_waitcnt lgkmcnt(7)
	v_bfe_u32 v18, v10, 16, 1
	s_waitcnt lgkmcnt(6)
	v_bfe_u32 v17, v22, 16, 1
	v_add3_u32 v17, v22, v17, s53
	v_lshrrev_b32_e32 v17, 16, v17
	v_add3_u32 v10, v10, v18, s53
	v_and_or_b32 v18, v10, s77, v17
	s_waitcnt lgkmcnt(5)
	v_bfe_u32 v10, v24, 16, 1
	v_add3_u32 v10, v24, v10, s53
	s_waitcnt lgkmcnt(4)
	v_bfe_u32 v17, v26, 16, 1
	v_lshrrev_b32_e32 v10, 16, v10
	v_add3_u32 v17, v26, v17, s53
	v_and_or_b32 v19, v17, s77, v10
	s_waitcnt lgkmcnt(3)
	v_bfe_u32 v10, v28, 16, 1
	v_add3_u32 v10, v28, v10, s53
	s_waitcnt lgkmcnt(2)
	v_bfe_u32 v17, v30, 16, 1
	v_lshrrev_b32_e32 v10, 16, v10
	v_add3_u32 v17, v30, v17, s53
	v_and_or_b32 v20, v17, s77, v10
	s_waitcnt lgkmcnt(1)
	v_bfe_u32 v10, v32, 16, 1
	v_add3_u32 v10, v32, v10, s53
	s_waitcnt lgkmcnt(0)
	v_bfe_u32 v17, v34, 16, 1
	v_lshrrev_b32_e32 v10, 16, v10
	v_add3_u32 v17, v34, v17, s53
	v_and_or_b32 v21, v17, s77, v10
	v_or_b32_e32 v10, s2, v15
	v_lshlrev_b32_e32 v202, 12, v10
	v_bfe_u32 v10, v23, 16, 1
	v_add3_u32 v10, v23, v10, s53
	v_bfe_u32 v17, v11, 16, 1
	v_lshl_add_u64 v[36:37], v[8:9], 0, v[202:203]
	v_lshrrev_b32_e32 v10, 16, v10
	v_add3_u32 v11, v11, v17, s53
	global_store_dwordx4 v[36:37], v[18:21], off nt
	v_readlane_b32 s22, v251, 20
	v_readlane_b32 s23, v251, 21
	v_and_or_b32 v18, v11, s77, v10
	v_bfe_u32 v10, v25, 16, 1
	v_add3_u32 v10, v25, v10, s53
	v_bfe_u32 v11, v27, 16, 1
	v_lshrrev_b32_e32 v10, 16, v10
	v_add3_u32 v11, v27, v11, s53
	v_and_or_b32 v19, v11, s77, v10
	v_bfe_u32 v10, v29, 16, 1
	v_add3_u32 v10, v29, v10, s53
	v_bfe_u32 v11, v31, 16, 1
	v_lshrrev_b32_e32 v10, 16, v10
	v_add3_u32 v11, v31, v11, s53
	v_and_or_b32 v20, v11, s77, v10
	v_bfe_u32 v10, v33, 16, 1
	v_add3_u32 v10, v33, v10, s53
	v_bfe_u32 v11, v35, 16, 1
	v_lshrrev_b32_e32 v10, 16, v10
	v_add3_u32 v11, v35, v11, s53
	v_and_or_b32 v21, v11, s77, v10
	v_or_b32_e32 v10, s2, v16
	v_lshlrev_b32_e32 v202, 12, v10
	v_lshl_add_u64 v[8:9], v[8:9], 0, v[202:203]
	global_store_dwordx4 v[8:9], v[18:21], off nt
	s_waitcnt lgkmcnt(0)
	v_readlane_b32 s24, v251, 22
	v_readlane_b32 s25, v251, 23
	v_readlane_b32 s26, v251, 24
	v_readlane_b32 s27, v251, 25
	v_readlane_b32 s28, v251, 26
	v_readlane_b32 s29, v251, 27
	v_readlane_b32 s30, v251, 28
	v_readlane_b32 s31, v251, 29

.LBB0_1648:
	s_andn2_b64 vcc, exec, s[2:3]
	s_cbranch_vccnz .LBB0_1650
	v_readlane_b32 s16, v251, 14
	v_readlane_b32 s17, v251, 15
	s_add_u32 s0, s16, s11
	s_addc_u32 s1, s17, s10
	v_readlane_b32 s2, v251, 56
	s_add_u32 s3, s2, s11
	v_readlane_b32 s2, v251, 57
	s_addc_u32 s10, s2, s10
	s_and_b32 s2, 0xffff, s5
	s_mul_i32 s2, s2, 0xba2f
	s_lshr_b32 s11, s2, 23
	s_mul_i32 s2, s11, 0xb0
	s_sub_i32 s2, s5, s2
	s_and_b32 s5, s2, 0xffff
	s_lshl_b32 s2, s5, 5
	s_lshl_b32 s14, s5, 6
	s_and_b32 s14, s14, 0x3f00
	s_and_b32 s2, s2, 0x60
	s_or_b32 s2, s2, s14
	s_lshl_b32 s5, s5, 7
	v_lshl_or_b32 v10, s11, 6, v3
	s_add_u32 s0, s0, s5
	s_addc_u32 s1, s1, 0
	v_lshlrev_b32_e32 v202, 2, v2
	v_mul_u32_u24_e32 v10, 0x1600, v10
	v_lshl_add_u64 v[8:9], s[0:1], 0, v[202:203]
	v_lshlrev_b32_e32 v202, 2, v10
	v_lshl_add_u64 v[8:9], v[8:9], 0, v[202:203]
	s_mov_b32 s0, 0xb000
	v_add_co_u32_e32 v10, vcc, s0, v8
	s_mov_b32 s0, 0x16000
	s_nop 0
	v_addc_co_u32_e32 v11, vcc, 0, v9, vcc
	global_load_dword v17, v[8:9], off nt
	global_load_dword v18, v[10:11], off nt
	v_add_co_u32_e32 v10, vcc, s0, v8
	s_mov_b32 s0, 0x21000
	s_nop 0
	v_addc_co_u32_e32 v11, vcc, 0, v9, vcc
	global_load_dword v19, v[10:11], off nt
	v_add_co_u32_e32 v10, vcc, s0, v8
	s_mov_b32 s0, 0x2c000
	s_nop 0
	v_addc_co_u32_e32 v11, vcc, 0, v9, vcc
	global_load_dword v20, v[10:11], off nt
	v_add_co_u32_e32 v10, vcc, s0, v8
	s_mov_b32 s0, 0x37000
	s_nop 0
	v_addc_co_u32_e32 v11, vcc, 0, v9, vcc
	global_load_dword v21, v[10:11], off nt
	v_add_co_u32_e32 v10, vcc, s0, v8
	s_mov_b32 s0, 0x42000
	s_nop 0
	v_addc_co_u32_e32 v11, vcc, 0, v9, vcc
	global_load_dword v22, v[10:11], off nt
	v_add_co_u32_e32 v10, vcc, s0, v8
	s_mov_b32 s0, 0x4d000
	s_nop 0
	v_addc_co_u32_e32 v11, vcc, 0, v9, vcc
	global_load_dword v23, v[10:11], off nt
	v_add_co_u32_e32 v10, vcc, s0, v8
	s_mov_b32 s0, 0x58000
	s_nop 0
	v_addc_co_u32_e32 v11, vcc, 0, v9, vcc
	global_load_dword v24, v[10:11], off nt
	v_add_co_u32_e32 v10, vcc, s0, v8
	s_mov_b32 s0, 0x63000
	s_nop 0
	v_addc_co_u32_e32 v11, vcc, 0, v9, vcc
	global_load_dword v25, v[10:11], off nt
	v_add_co_u32_e32 v10, vcc, s0, v8
	s_mov_b32 s0, 0x6e000
	s_nop 0
	v_addc_co_u32_e32 v11, vcc, 0, v9, vcc
	global_load_dword v26, v[10:11], off nt
	v_add_co_u32_e32 v10, vcc, s0, v8
	s_mov_b32 s0, 0x79000
	s_nop 0
	v_addc_co_u32_e32 v11, vcc, 0, v9, vcc
	global_load_dword v27, v[10:11], off nt
	v_add_co_u32_e32 v10, vcc, s0, v8
	s_mov_b32 s0, 0x84000
	s_nop 0
	v_addc_co_u32_e32 v11, vcc, 0, v9, vcc
	global_load_dword v28, v[10:11], off nt
	v_add_co_u32_e32 v10, vcc, s0, v8
	s_mov_b32 s0, 0x8f000
	s_nop 0
	v_addc_co_u32_e32 v11, vcc, 0, v9, vcc
	global_load_dword v29, v[10:11], off nt
	v_add_co_u32_e32 v10, vcc, s0, v8
	s_mov_b32 s0, 0x9a000
	s_nop 0
	v_addc_co_u32_e32 v11, vcc, 0, v9, vcc
	global_load_dword v30, v[10:11], off nt
	v_add_co_u32_e32 v10, vcc, s0, v8
	s_mov_b32 s0, 0xa5000
	s_nop 0
	v_addc_co_u32_e32 v11, vcc, 0, v9, vcc
	global_load_dword v31, v[10:11], off nt
	v_add_co_u32_e32 v10, vcc, s0, v8
	s_mov_b32 s0, 0xb0000
	s_nop 0
	v_addc_co_u32_e32 v11, vcc, 0, v9, vcc
	global_load_dword v32, v[10:11], off nt
	v_add_co_u32_e32 v10, vcc, s0, v8
	s_mov_b32 s0, 0xbb000
	s_nop 0
	v_addc_co_u32_e32 v11, vcc, 0, v9, vcc
	global_load_dword v33, v[10:11], off nt
	v_add_co_u32_e32 v10, vcc, s0, v8
	s_mov_b32 s0, 0xc6000
	s_nop 0
	v_addc_co_u32_e32 v11, vcc, 0, v9, vcc
	global_load_dword v34, v[10:11], off nt
	v_add_co_u32_e32 v10, vcc, s0, v8
	s_mov_b32 s0, 0xd1000
	s_nop 0
	v_addc_co_u32_e32 v11, vcc, 0, v9, vcc
	global_load_dword v35, v[10:11], off nt
	v_add_co_u32_e32 v10, vcc, s0, v8
	s_mov_b32 s0, 0xdc000
	s_nop 0
	v_addc_co_u32_e32 v11, vcc, 0, v9, vcc
	global_load_dword v36, v[10:11], off nt
	v_add_co_u32_e32 v10, vcc, s0, v8
	s_mov_b32 s0, 0xe7000
	s_nop 0
	v_addc_co_u32_e32 v11, vcc, 0, v9, vcc
	global_load_dword v37, v[10:11], off nt
	v_add_co_u32_e32 v10, vcc, s0, v8
	s_mov_b32 s0, 0xf2000
	s_nop 0
	v_addc_co_u32_e32 v11, vcc, 0, v9, vcc
	global_load_dword v38, v[10:11], off nt
	v_add_co_u32_e32 v10, vcc, s0, v8
	s_mov_b32 s0, 0xfd000
	s_nop 0
	v_addc_co_u32_e32 v11, vcc, 0, v9, vcc
	global_load_dword v39, v[10:11], off nt
	v_add_co_u32_e32 v10, vcc, s0, v8
	s_mov_b32 s0, 0x108000
	s_nop 0
	v_addc_co_u32_e32 v11, vcc, 0, v9, vcc
	global_load_dword v40, v[10:11], off nt
	v_add_co_u32_e32 v10, vcc, s0, v8
	s_mov_b32 s0, 0x113000
	s_nop 0
	v_addc_co_u32_e32 v11, vcc, 0, v9, vcc
	global_load_dword v41, v[10:11], off nt
	v_add_co_u32_e32 v10, vcc, s0, v8
	s_mov_b32 s0, 0x11e000
	s_nop 0
	v_addc_co_u32_e32 v11, vcc, 0, v9, vcc
	global_load_dword v42, v[10:11], off nt
	v_add_co_u32_e32 v10, vcc, s0, v8
	s_mov_b32 s0, 0x129000
	s_nop 0
	v_addc_co_u32_e32 v11, vcc, 0, v9, vcc
	global_load_dword v43, v[10:11], off nt
	v_add_co_u32_e32 v10, vcc, s0, v8
	s_mov_b32 s0, 0x134000
	s_nop 0
	v_addc_co_u32_e32 v11, vcc, 0, v9, vcc
	global_load_dword v44, v[10:11], off nt
	v_add_co_u32_e32 v10, vcc, s0, v8
	s_mov_b32 s0, 0x13f000
	s_nop 0
	v_addc_co_u32_e32 v11, vcc, 0, v9, vcc
	global_load_dword v45, v[10:11], off nt
	v_add_co_u32_e32 v10, vcc, s0, v8
	s_mov_b32 s0, 0x14a000
	s_nop 0
	v_addc_co_u32_e32 v11, vcc, 0, v9, vcc
	global_load_dword v46, v[10:11], off nt
	v_add_co_u32_e32 v10, vcc, s0, v8
	s_mov_b32 s0, 0x155000
	s_nop 0
	v_addc_co_u32_e32 v11, vcc, 0, v9, vcc
	v_add_co_u32_e32 v8, vcc, s0, v8
	global_load_dword v10, v[10:11], off nt
	s_nop 0
	v_addc_co_u32_e32 v9, vcc, 0, v9, vcc
	global_load_dword v8, v[8:9], off nt
	v_add_u32_e32 v9, 0x400, v5
	s_waitcnt vmcnt(0)
	ds_write2_b32 v5, v17, v18 offset1:66
	ds_write2_b32 v5, v19, v20 offset0:132 offset1:198
	ds_write2_b32 v9, v21, v22 offset0:8 offset1:74
	ds_write2_b32 v9, v23, v24 offset0:140 offset1:206
	v_add_u32_e32 v9, 0x800, v5
	ds_write2_b32 v9, v25, v26 offset0:16 offset1:82
	ds_write2_b32 v9, v27, v28 offset0:148 offset1:214
	v_add_u32_e32 v9, 0xc00, v5
	ds_write2_b32 v9, v29, v30 offset0:24 offset1:90
	ds_write2_b32 v9, v31, v32 offset0:156 offset1:222
	v_add_u32_e32 v9, 0x1000, v5
	ds_write2_b32 v9, v33, v34 offset0:32 offset1:98
	ds_write2_b32 v9, v35, v36 offset0:164 offset1:230
	v_add_u32_e32 v9, 0x1400, v5
	ds_write2_b32 v9, v37, v38 offset0:40 offset1:106
	ds_write2_b32 v9, v39, v40 offset0:172 offset1:238
	v_add_u32_e32 v9, 0x1800, v5
	ds_write2_b32 v9, v41, v42 offset0:48 offset1:114
	ds_write2_b32 v9, v43, v44 offset0:180 offset1:246
	v_add_u32_e32 v9, 0x1c00, v5
	ds_write2_b32 v9, v45, v46 offset0:56 offset1:122
	ds_write2_b32 v9, v10, v8 offset0:188 offset1:254
	s_waitcnt lgkmcnt(0)
	ds_read2_b32 v[10:11], v13 offset0:33 offset1:41
	ds_read2_b32 v[22:23], v13 offset1:8
	ds_read2_b32 v[24:25], v13 offset0:66 offset1:74
	ds_read2_b32 v[26:27], v13 offset0:99 offset1:107
	ds_read2_b32 v[28:29], v13 offset0:132 offset1:140
	ds_read2_b32 v[30:31], v13 offset0:165 offset1:173
	ds_read2_b32 v[32:33], v13 offset0:198 offset1:206
	ds_read2_b32 v[34:35], v13 offset0:231 offset1:239
	s_waitcnt lgkmcnt(7)
	v_bfe_u32 v18, v10, 16, 1
	s_waitcnt lgkmcnt(6)
	v_bfe_u32 v17, v22, 16, 1
	v_add3_u32 v17, v22, v17, s53
	v_lshrrev_b32_e32 v17, 16, v17
	v_add3_u32 v10, v10, v18, s53
	v_and_or_b32 v18, v10, s77, v17
	s_waitcnt lgkmcnt(5)
	v_bfe_u32 v10, v24, 16, 1
	v_add3_u32 v10, v24, v10, s53
	s_waitcnt lgkmcnt(4)
	v_bfe_u32 v17, v26, 16, 1
	v_lshrrev_b32_e32 v10, 16, v10
	v_add3_u32 v17, v26, v17, s53
	v_and_or_b32 v19, v17, s77, v10
	s_waitcnt lgkmcnt(3)
	v_bfe_u32 v10, v28, 16, 1
	v_add3_u32 v10, v28, v10, s53
	s_waitcnt lgkmcnt(2)
	v_bfe_u32 v17, v30, 16, 1
	v_lshrrev_b32_e32 v10, 16, v10
	v_add3_u32 v17, v30, v17, s53
	v_and_or_b32 v20, v17, s77, v10
	s_waitcnt lgkmcnt(1)
	v_bfe_u32 v10, v32, 16, 1
	s_lshl_b32 s0, s11, 7
	v_add3_u32 v10, v32, v10, s53
	s_waitcnt lgkmcnt(0)
	v_bfe_u32 v17, v34, 16, 1
	s_add_u32 s0, s3, s0
	v_lshrrev_b32_e32 v10, 16, v10
	v_add3_u32 v17, v34, v17, s53
	s_addc_u32 s1, s10, 0
	v_lshlrev_b32_e32 v202, 1, v4
	v_and_or_b32 v21, v17, s77, v10
	v_or_b32_e32 v10, s2, v12
	v_lshl_add_u64 v[8:9], s[0:1], 0, v[202:203]
	v_lshlrev_b32_e32 v202, 12, v10
	v_bfe_u32 v10, v23, 16, 1
	v_add3_u32 v10, v23, v10, s53
	v_bfe_u32 v17, v11, 16, 1
	v_lshl_add_u64 v[36:37], v[8:9], 0, v[202:203]
	v_lshrrev_b32_e32 v10, 16, v10
	v_add3_u32 v11, v11, v17, s53
	global_store_dwordx4 v[36:37], v[18:21], off nt
	v_readlane_b32 s18, v251, 16
	v_readlane_b32 s19, v251, 17
	v_and_or_b32 v18, v11, s77, v10
	v_bfe_u32 v10, v25, 16, 1
	v_add3_u32 v10, v25, v10, s53
	v_bfe_u32 v11, v27, 16, 1
	v_lshrrev_b32_e32 v10, 16, v10
	v_add3_u32 v11, v27, v11, s53
	v_and_or_b32 v19, v11, s77, v10
	v_bfe_u32 v10, v29, 16, 1
	v_add3_u32 v10, v29, v10, s53
	v_bfe_u32 v11, v31, 16, 1
	v_lshrrev_b32_e32 v10, 16, v10
	v_add3_u32 v11, v31, v11, s53
	v_and_or_b32 v20, v11, s77, v10
	v_bfe_u32 v10, v33, 16, 1
	v_add3_u32 v10, v33, v10, s53
	v_bfe_u32 v11, v35, 16, 1
	v_lshrrev_b32_e32 v10, 16, v10
	v_add3_u32 v11, v35, v11, s53
	v_and_or_b32 v21, v11, s77, v10
	v_or_b32_e32 v10, s2, v14
	v_lshlrev_b32_e32 v202, 12, v10
	v_lshl_add_u64 v[10:11], v[8:9], 0, v[202:203]
	global_store_dwordx4 v[10:11], v[18:21], off nt
	ds_read2_b32 v[10:11], v13 offset0:49 offset1:57
	ds_read2_b32 v[22:23], v13 offset0:16 offset1:24
	ds_read2_b32 v[24:25], v13 offset0:82 offset1:90
	ds_read2_b32 v[26:27], v13 offset0:115 offset1:123
	ds_read2_b32 v[28:29], v13 offset0:148 offset1:156
	ds_read2_b32 v[30:31], v13 offset0:181 offset1:189
	ds_read2_b32 v[32:33], v13 offset0:214 offset1:222
	ds_read2_b32 v[34:35], v13 offset0:247 offset1:255
	s_waitcnt lgkmcnt(7)
	v_bfe_u32 v18, v10, 16, 1
	s_waitcnt lgkmcnt(6)
	v_bfe_u32 v17, v22, 16, 1
	v_add3_u32 v17, v22, v17, s53
	v_lshrrev_b32_e32 v17, 16, v17
	v_add3_u32 v10, v10, v18, s53
	v_and_or_b32 v18, v10, s77, v17
	s_waitcnt lgkmcnt(5)
	v_bfe_u32 v10, v24, 16, 1
	v_add3_u32 v10, v24, v10, s53
	s_waitcnt lgkmcnt(4)
	v_bfe_u32 v17, v26, 16, 1
	v_lshrrev_b32_e32 v10, 16, v10
	v_add3_u32 v17, v26, v17, s53
	v_and_or_b32 v19, v17, s77, v10
	s_waitcnt lgkmcnt(3)
	v_bfe_u32 v10, v28, 16, 1
	v_add3_u32 v10, v28, v10, s53
	s_waitcnt lgkmcnt(2)
	v_bfe_u32 v17, v30, 16, 1
	v_lshrrev_b32_e32 v10, 16, v10
	v_add3_u32 v17, v30, v17, s53
	v_and_or_b32 v20, v17, s77, v10
	s_waitcnt lgkmcnt(1)
	v_bfe_u32 v10, v32, 16, 1
	v_add3_u32 v10, v32, v10, s53
	s_waitcnt lgkmcnt(0)
	v_bfe_u32 v17, v34, 16, 1
	v_lshrrev_b32_e32 v10, 16, v10
	v_add3_u32 v17, v34, v17, s53
	v_and_or_b32 v21, v17, s77, v10
	v_or_b32_e32 v10, s2, v15
	v_lshlrev_b32_e32 v202, 12, v10
	v_bfe_u32 v10, v23, 16, 1
	v_add3_u32 v10, v23, v10, s53
	v_bfe_u32 v17, v11, 16, 1
	v_lshl_add_u64 v[36:37], v[8:9], 0, v[202:203]
	v_lshrrev_b32_e32 v10, 16, v10
	v_add3_u32 v11, v11, v17, s53
	global_store_dwordx4 v[36:37], v[18:21], off nt
	v_readlane_b32 s20, v251, 18
	v_readlane_b32 s21, v251, 19
	v_and_or_b32 v18, v11, s77, v10
	v_bfe_u32 v10, v25, 16, 1
	v_add3_u32 v10, v25, v10, s53
	v_bfe_u32 v11, v27, 16, 1
	v_lshrrev_b32_e32 v10, 16, v10
	v_add3_u32 v11, v27, v11, s53
	v_and_or_b32 v19, v11, s77, v10
	v_bfe_u32 v10, v29, 16, 1
	v_add3_u32 v10, v29, v10, s53
	v_bfe_u32 v11, v31, 16, 1
	v_lshrrev_b32_e32 v10, 16, v10
	v_add3_u32 v11, v31, v11, s53
	v_and_or_b32 v20, v11, s77, v10
	v_bfe_u32 v10, v33, 16, 1
	v_add3_u32 v10, v33, v10, s53
	v_bfe_u32 v11, v35, 16, 1
	v_lshrrev_b32_e32 v10, 16, v10
	v_add3_u32 v11, v35, v11, s53
	v_and_or_b32 v21, v11, s77, v10
	v_or_b32_e32 v10, s2, v16
	v_lshlrev_b32_e32 v202, 12, v10
	v_lshl_add_u64 v[8:9], v[8:9], 0, v[202:203]
	global_store_dwordx4 v[8:9], v[18:21], off nt
	s_waitcnt lgkmcnt(0)
	v_readlane_b32 s22, v251, 20
	v_readlane_b32 s23, v251, 21
	v_readlane_b32 s24, v251, 22
	v_readlane_b32 s25, v251, 23
	v_readlane_b32 s26, v251, 24
	v_readlane_b32 s27, v251, 25
	v_readlane_b32 s28, v251, 26
	v_readlane_b32 s29, v251, 27
	v_readlane_b32 s30, v251, 28
	v_readlane_b32 s31, v251, 29

.LBB0_1651:
	s_andn2_b64 vcc, exec, s[2:3]
	s_cbranch_vccnz .LBB0_1653
	s_add_i32 s0, s4, 0xffffc000
	s_lshr_b32 s86, s0, 12
	s_lshl_b64 s[0:1], s[86:87], 25
	v_readlane_b32 s16, v251, 30
	v_readlane_b32 s17, v251, 31
	s_add_u32 s11, s16, s0
	s_addc_u32 s14, s17, s1
	s_lshl_b64 s[0:1], s[86:87], 24
	v_readlane_b32 s2, v251, 58
	s_add_u32 s3, s2, s0
	v_readlane_b32 s0, v251, 59
	s_addc_u32 s5, s0, s1
	s_lshl_b32 s0, s4, 5
	s_and_b32 s2, s0, 0x7e0
	s_and_b32 s10, s4, 0xfc0
	s_lshl_b32 s0, s2, 2
	s_add_u32 s0, s11, s0
	v_or_b32_e32 v10, s10, v3
	s_addc_u32 s1, s14, 0
	v_lshlrev_b32_e32 v202, 2, v2
	v_lshl_add_u64 v[8:9], s[0:1], 0, v[202:203]
	v_lshlrev_b32_e32 v202, 13, v10
	v_lshl_add_u64 v[8:9], v[8:9], 0, v[202:203]
	v_add_co_u32_e32 v10, vcc, s89, v8
	s_mov_b32 s0, 0x8000
	s_nop 0
	v_addc_co_u32_e32 v11, vcc, 0, v9, vcc
	global_load_dword v17, v[8:9], off nt
	global_load_dword v18, v[10:11], off nt
	v_add_co_u32_e32 v10, vcc, s0, v8
	s_mov_b32 s0, 0xc000
	s_nop 0
	v_addc_co_u32_e32 v11, vcc, 0, v9, vcc
	global_load_dword v19, v[10:11], off nt
	v_add_co_u32_e32 v10, vcc, s0, v8
	s_mov_b32 s0, 0x10000
	s_nop 0
	v_addc_co_u32_e32 v11, vcc, 0, v9, vcc
	global_load_dword v20, v[10:11], off nt
	v_add_co_u32_e32 v10, vcc, s0, v8
	s_mov_b32 s0, 0x14000
	s_nop 0
	v_addc_co_u32_e32 v11, vcc, 0, v9, vcc
	global_load_dword v21, v[10:11], off nt
	v_add_co_u32_e32 v10, vcc, s0, v8
	s_mov_b32 s0, 0x18000
	s_nop 0
	v_addc_co_u32_e32 v11, vcc, 0, v9, vcc
	global_load_dword v22, v[10:11], off nt
	v_add_co_u32_e32 v10, vcc, s0, v8
	s_mov_b32 s0, 0x1c000
	s_nop 0
	v_addc_co_u32_e32 v11, vcc, 0, v9, vcc
	global_load_dword v23, v[10:11], off nt
	v_add_co_u32_e32 v10, vcc, s0, v8
	s_mov_b32 s0, 0x20000
	s_nop 0
	v_addc_co_u32_e32 v11, vcc, 0, v9, vcc
	global_load_dword v24, v[10:11], off nt
	v_add_co_u32_e32 v10, vcc, s0, v8
	s_mov_b32 s0, 0x24000
	s_nop 0
	v_addc_co_u32_e32 v11, vcc, 0, v9, vcc
	global_load_dword v25, v[10:11], off nt
	v_add_co_u32_e32 v10, vcc, s0, v8
	s_mov_b32 s0, 0x28000
	s_nop 0
	v_addc_co_u32_e32 v11, vcc, 0, v9, vcc
	global_load_dword v26, v[10:11], off nt
	v_add_co_u32_e32 v10, vcc, s0, v8
	s_mov_b32 s0, 0x2c000
	s_nop 0
	v_addc_co_u32_e32 v11, vcc, 0, v9, vcc
	global_load_dword v27, v[10:11], off nt
	v_add_co_u32_e32 v10, vcc, s0, v8
	s_mov_b32 s0, 0x30000
	s_nop 0
	v_addc_co_u32_e32 v11, vcc, 0, v9, vcc
	global_load_dword v28, v[10:11], off nt
	v_add_co_u32_e32 v10, vcc, s0, v8
	s_mov_b32 s0, 0x34000
	s_nop 0
	v_addc_co_u32_e32 v11, vcc, 0, v9, vcc
	global_load_dword v29, v[10:11], off nt
	v_add_co_u32_e32 v10, vcc, s0, v8
	s_mov_b32 s0, 0x38000
	s_nop 0
	v_addc_co_u32_e32 v11, vcc, 0, v9, vcc
	global_load_dword v30, v[10:11], off nt
	v_add_co_u32_e32 v10, vcc, s0, v8
	s_mov_b32 s0, 0x3c000
	s_nop 0
	v_addc_co_u32_e32 v11, vcc, 0, v9, vcc
	global_load_dword v31, v[10:11], off nt
	v_add_co_u32_e32 v10, vcc, s0, v8
	s_mov_b32 s0, 0x40000
	s_nop 0
	v_addc_co_u32_e32 v11, vcc, 0, v9, vcc
	global_load_dword v32, v[10:11], off nt
	v_add_co_u32_e32 v10, vcc, s0, v8
	s_mov_b32 s0, 0x44000
	s_nop 0
	v_addc_co_u32_e32 v11, vcc, 0, v9, vcc
	global_load_dword v33, v[10:11], off nt
	v_add_co_u32_e32 v10, vcc, s0, v8
	s_mov_b32 s0, 0x48000
	s_nop 0
	v_addc_co_u32_e32 v11, vcc, 0, v9, vcc
	global_load_dword v34, v[10:11], off nt
	v_add_co_u32_e32 v10, vcc, s0, v8
	s_mov_b32 s0, 0x4c000
	s_nop 0
	v_addc_co_u32_e32 v11, vcc, 0, v9, vcc
	global_load_dword v35, v[10:11], off nt
	v_add_co_u32_e32 v10, vcc, s0, v8
	s_mov_b32 s0, 0x50000
	s_nop 0
	v_addc_co_u32_e32 v11, vcc, 0, v9, vcc
	global_load_dword v36, v[10:11], off nt
	v_add_co_u32_e32 v10, vcc, s0, v8
	s_mov_b32 s0, 0x54000
	s_nop 0
	v_addc_co_u32_e32 v11, vcc, 0, v9, vcc
	global_load_dword v37, v[10:11], off nt
	v_add_co_u32_e32 v10, vcc, s0, v8
	s_mov_b32 s0, 0x58000
	s_nop 0
	v_addc_co_u32_e32 v11, vcc, 0, v9, vcc
	global_load_dword v38, v[10:11], off nt
	v_add_co_u32_e32 v10, vcc, s0, v8
	s_mov_b32 s0, 0x5c000
	s_nop 0
	v_addc_co_u32_e32 v11, vcc, 0, v9, vcc
	global_load_dword v39, v[10:11], off nt
	v_add_co_u32_e32 v10, vcc, s0, v8
	s_mov_b32 s0, 0x60000
	s_nop 0
	v_addc_co_u32_e32 v11, vcc, 0, v9, vcc
	global_load_dword v40, v[10:11], off nt
	v_add_co_u32_e32 v10, vcc, s0, v8
	s_mov_b32 s0, 0x64000
	s_nop 0
	v_addc_co_u32_e32 v11, vcc, 0, v9, vcc
	global_load_dword v41, v[10:11], off nt
	v_add_co_u32_e32 v10, vcc, s0, v8
	s_mov_b32 s0, 0x68000
	s_nop 0
	v_addc_co_u32_e32 v11, vcc, 0, v9, vcc
	global_load_dword v42, v[10:11], off nt
	v_add_co_u32_e32 v10, vcc, s0, v8
	s_mov_b32 s0, 0x6c000
	s_nop 0
	v_addc_co_u32_e32 v11, vcc, 0, v9, vcc
	global_load_dword v43, v[10:11], off nt
	v_add_co_u32_e32 v10, vcc, s0, v8
	s_mov_b32 s0, 0x70000
	s_nop 0
	v_addc_co_u32_e32 v11, vcc, 0, v9, vcc
	global_load_dword v44, v[10:11], off nt
	v_add_co_u32_e32 v10, vcc, s0, v8
	s_mov_b32 s0, 0x74000
	s_nop 0
	v_addc_co_u32_e32 v11, vcc, 0, v9, vcc
	global_load_dword v45, v[10:11], off nt
	v_add_co_u32_e32 v10, vcc, s0, v8
	s_mov_b32 s0, 0x78000
	s_nop 0
	v_addc_co_u32_e32 v11, vcc, 0, v9, vcc
	global_load_dword v46, v[10:11], off nt
	v_add_co_u32_e32 v10, vcc, s0, v8
	s_mov_b32 s0, 0x7c000
	s_nop 0
	v_addc_co_u32_e32 v11, vcc, 0, v9, vcc
	v_add_co_u32_e32 v8, vcc, s0, v8
	global_load_dword v10, v[10:11], off nt
	s_nop 0
	v_addc_co_u32_e32 v9, vcc, 0, v9, vcc
	global_load_dword v8, v[8:9], off nt
	v_add_u32_e32 v9, 0x400, v5
	s_waitcnt vmcnt(0)
	ds_write2_b32 v5, v17, v18 offset1:66
	ds_write2_b32 v5, v19, v20 offset0:132 offset1:198
	ds_write2_b32 v9, v21, v22 offset0:8 offset1:74
	ds_write2_b32 v9, v23, v24 offset0:140 offset1:206
	v_add_u32_e32 v9, 0x800, v5
	ds_write2_b32 v9, v25, v26 offset0:16 offset1:82
	ds_write2_b32 v9, v27, v28 offset0:148 offset1:214
	v_add_u32_e32 v9, 0xc00, v5
	ds_write2_b32 v9, v29, v30 offset0:24 offset1:90
	ds_write2_b32 v9, v31, v32 offset0:156 offset1:222
	v_add_u32_e32 v9, 0x1000, v5
	ds_write2_b32 v9, v33, v34 offset0:32 offset1:98
	ds_write2_b32 v9, v35, v36 offset0:164 offset1:230
	v_add_u32_e32 v9, 0x1400, v5
	ds_write2_b32 v9, v37, v38 offset0:40 offset1:106
	ds_write2_b32 v9, v39, v40 offset0:172 offset1:238
	v_add_u32_e32 v9, 0x1800, v5
	ds_write2_b32 v9, v41, v42 offset0:48 offset1:114
	ds_write2_b32 v9, v43, v44 offset0:180 offset1:246
	v_add_u32_e32 v9, 0x1c00, v5
	ds_write2_b32 v9, v45, v46 offset0:56 offset1:122
	ds_write2_b32 v9, v10, v8 offset0:188 offset1:254
	s_waitcnt lgkmcnt(0)
	ds_read2_b32 v[10:11], v13 offset0:33 offset1:41
	ds_read2_b32 v[22:23], v13 offset1:8
	ds_read2_b32 v[24:25], v13 offset0:66 offset1:74
	ds_read2_b32 v[26:27], v13 offset0:99 offset1:107
	ds_read2_b32 v[28:29], v13 offset0:132 offset1:140
	ds_read2_b32 v[30:31], v13 offset0:165 offset1:173
	ds_read2_b32 v[32:33], v13 offset0:198 offset1:206
	ds_read2_b32 v[34:35], v13 offset0:231 offset1:239
	s_waitcnt lgkmcnt(7)
	v_bfe_u32 v18, v10, 16, 1
	s_waitcnt lgkmcnt(6)
	v_bfe_u32 v17, v22, 16, 1
	v_add3_u32 v17, v22, v17, s53
	v_lshrrev_b32_e32 v17, 16, v17
	v_add3_u32 v10, v10, v18, s53
	v_and_or_b32 v18, v10, s77, v17
	s_waitcnt lgkmcnt(5)
	v_bfe_u32 v10, v24, 16, 1
	v_add3_u32 v10, v24, v10, s53
	s_waitcnt lgkmcnt(4)
	v_bfe_u32 v17, v26, 16, 1
	v_lshrrev_b32_e32 v10, 16, v10
	v_add3_u32 v17, v26, v17, s53
	v_and_or_b32 v19, v17, s77, v10
	s_waitcnt lgkmcnt(3)
	v_bfe_u32 v10, v28, 16, 1
	v_add3_u32 v10, v28, v10, s53
	s_waitcnt lgkmcnt(2)
	v_bfe_u32 v17, v30, 16, 1
	v_lshrrev_b32_e32 v10, 16, v10
	v_add3_u32 v17, v30, v17, s53
	v_and_or_b32 v20, v17, s77, v10
	s_waitcnt lgkmcnt(1)
	v_bfe_u32 v10, v32, 16, 1
	s_lshl_b32 s0, s10, 1
	v_add3_u32 v10, v32, v10, s53
	s_waitcnt lgkmcnt(0)
	v_bfe_u32 v17, v34, 16, 1
	s_add_u32 s0, s3, s0
	v_lshrrev_b32_e32 v10, 16, v10
	v_add3_u32 v17, v34, v17, s53
	s_addc_u32 s1, s5, 0
	v_lshlrev_b32_e32 v202, 1, v4
	v_and_or_b32 v21, v17, s77, v10
	v_or_b32_e32 v10, s2, v12
	v_lshl_add_u64 v[8:9], s[0:1], 0, v[202:203]
	v_lshlrev_b32_e32 v202, 13, v10
	v_bfe_u32 v10, v23, 16, 1
	v_add3_u32 v10, v23, v10, s53
	v_bfe_u32 v17, v11, 16, 1
	v_lshl_add_u64 v[36:37], v[8:9], 0, v[202:203]
	v_lshrrev_b32_e32 v10, 16, v10
	v_add3_u32 v11, v11, v17, s53
	global_store_dwordx4 v[36:37], v[18:21], off nt
	v_readlane_b32 s18, v251, 32
	v_readlane_b32 s19, v251, 33
	v_and_or_b32 v18, v11, s77, v10
	v_bfe_u32 v10, v25, 16, 1
	v_add3_u32 v10, v25, v10, s53
	v_bfe_u32 v11, v27, 16, 1
	v_lshrrev_b32_e32 v10, 16, v10
	v_add3_u32 v11, v27, v11, s53
	v_and_or_b32 v19, v11, s77, v10
	v_bfe_u32 v10, v29, 16, 1
	v_add3_u32 v10, v29, v10, s53
	v_bfe_u32 v11, v31, 16, 1
	v_lshrrev_b32_e32 v10, 16, v10
	v_add3_u32 v11, v31, v11, s53
	v_and_or_b32 v20, v11, s77, v10
	v_bfe_u32 v10, v33, 16, 1
	v_add3_u32 v10, v33, v10, s53
	v_bfe_u32 v11, v35, 16, 1
	v_lshrrev_b32_e32 v10, 16, v10
	v_add3_u32 v11, v35, v11, s53
	v_and_or_b32 v21, v11, s77, v10
	v_or_b32_e32 v10, s2, v14
	v_lshlrev_b32_e32 v202, 13, v10
	v_lshl_add_u64 v[10:11], v[8:9], 0, v[202:203]
	global_store_dwordx4 v[10:11], v[18:21], off nt
	ds_read2_b32 v[10:11], v13 offset0:49 offset1:57
	ds_read2_b32 v[22:23], v13 offset0:16 offset1:24
	ds_read2_b32 v[24:25], v13 offset0:82 offset1:90
	ds_read2_b32 v[26:27], v13 offset0:115 offset1:123
	ds_read2_b32 v[28:29], v13 offset0:148 offset1:156
	ds_read2_b32 v[30:31], v13 offset0:181 offset1:189
	ds_read2_b32 v[32:33], v13 offset0:214 offset1:222
	ds_read2_b32 v[34:35], v13 offset0:247 offset1:255
	s_waitcnt lgkmcnt(7)
	v_bfe_u32 v18, v10, 16, 1
	s_waitcnt lgkmcnt(6)
	v_bfe_u32 v17, v22, 16, 1
	v_add3_u32 v17, v22, v17, s53
	v_lshrrev_b32_e32 v17, 16, v17
	v_add3_u32 v10, v10, v18, s53
	v_and_or_b32 v18, v10, s77, v17
	s_waitcnt lgkmcnt(5)
	v_bfe_u32 v10, v24, 16, 1
	v_add3_u32 v10, v24, v10, s53
	s_waitcnt lgkmcnt(4)
	v_bfe_u32 v17, v26, 16, 1
	v_lshrrev_b32_e32 v10, 16, v10
	v_add3_u32 v17, v26, v17, s53
	v_and_or_b32 v19, v17, s77, v10
	s_waitcnt lgkmcnt(3)
	v_bfe_u32 v10, v28, 16, 1
	v_add3_u32 v10, v28, v10, s53
	s_waitcnt lgkmcnt(2)
	v_bfe_u32 v17, v30, 16, 1
	v_lshrrev_b32_e32 v10, 16, v10
	v_add3_u32 v17, v30, v17, s53
	v_and_or_b32 v20, v17, s77, v10
	s_waitcnt lgkmcnt(1)
	v_bfe_u32 v10, v32, 16, 1
	v_add3_u32 v10, v32, v10, s53
	s_waitcnt lgkmcnt(0)
	v_bfe_u32 v17, v34, 16, 1
	v_lshrrev_b32_e32 v10, 16, v10
	v_add3_u32 v17, v34, v17, s53
	v_and_or_b32 v21, v17, s77, v10
	v_or_b32_e32 v10, s2, v15
	v_lshlrev_b32_e32 v202, 13, v10
	v_bfe_u32 v10, v23, 16, 1
	v_add3_u32 v10, v23, v10, s53
	v_bfe_u32 v17, v11, 16, 1
	v_lshl_add_u64 v[36:37], v[8:9], 0, v[202:203]
	v_lshrrev_b32_e32 v10, 16, v10
	v_add3_u32 v11, v11, v17, s53
	global_store_dwordx4 v[36:37], v[18:21], off nt
	v_readlane_b32 s20, v251, 34
	v_readlane_b32 s21, v251, 35
	v_and_or_b32 v18, v11, s77, v10
	v_bfe_u32 v10, v25, 16, 1
	v_add3_u32 v10, v25, v10, s53
	v_bfe_u32 v11, v27, 16, 1
	v_lshrrev_b32_e32 v10, 16, v10
	v_add3_u32 v11, v27, v11, s53
	v_and_or_b32 v19, v11, s77, v10
	v_bfe_u32 v10, v29, 16, 1
	v_add3_u32 v10, v29, v10, s53
	v_bfe_u32 v11, v31, 16, 1
	v_lshrrev_b32_e32 v10, 16, v10
	v_add3_u32 v11, v31, v11, s53
	v_and_or_b32 v20, v11, s77, v10
	v_bfe_u32 v10, v33, 16, 1
	v_add3_u32 v10, v33, v10, s53
	v_bfe_u32 v11, v35, 16, 1
	v_lshrrev_b32_e32 v10, 16, v10
	v_add3_u32 v11, v35, v11, s53
	v_and_or_b32 v21, v11, s77, v10
	v_or_b32_e32 v10, s2, v16
	v_lshlrev_b32_e32 v202, 13, v10
	v_lshl_add_u64 v[8:9], v[8:9], 0, v[202:203]
	global_store_dwordx4 v[8:9], v[18:21], off nt
	s_waitcnt lgkmcnt(0)
	v_readlane_b32 s22, v251, 36
	v_readlane_b32 s23, v251, 37
	v_readlane_b32 s24, v251, 38
	v_readlane_b32 s25, v251, 39
	v_readlane_b32 s26, v251, 40
	v_readlane_b32 s27, v251, 41
	v_readlane_b32 s28, v251, 42
	v_readlane_b32 s29, v251, 43
	v_readlane_b32 s30, v251, 44
	v_readlane_b32 s31, v251, 45

.LBB0_1654:
	s_andn2_b64 vcc, exec, s[2:3]
	s_cbranch_vccnz .LBB0_1605
	s_ashr_i32 s0, s4, 31
	s_lshr_b32 s0, s0, 19
	s_add_i32 s1, s4, s0
	s_ashr_i32 s0, s1, 13
	s_and_b32 s1, s1, 0xe000
	s_sub_i32 s4, s4, s1
	s_ashr_i32 s1, s0, 31
	v_readlane_b32 s16, v251, 14
	s_lshl_b64 s[2:3], s[0:1], 26
	v_readlane_b32 s22, v251, 20
	v_readlane_b32 s23, v251, 21
	s_add_u32 s5, s22, s2
	s_addc_u32 s14, s23, s3
	s_lshl_b64 s[0:1], s[0:1], 25
	v_readlane_b32 s2, v251, 60
	s_add_u32 s10, s2, s0
	v_readlane_b32 s0, v251, 61
	s_addc_u32 s11, s0, s1
	s_sext_i32_i16 s0, s4
	s_bfe_u32 s0, s0, 0x80017
	s_add_i32 s0, s4, s0
	s_sext_i32_i16 s1, s0
	s_and_b32 s0, s0, 0xff00
	s_sub_i32 s0, s4, s0
	s_sext_i32_i16 s0, s0
	s_lshl_b32 s2, s0, 5
	s_ashr_i32 s1, s1, 8
	s_ashr_i32 s3, s2, 31
	s_lshl_b32 s4, s1, 6
	s_lshl_b64 s[0:1], s[2:3], 2
	v_or_b32_e32 v8, s4, v3
	s_add_u32 s0, s5, s0
	s_addc_u32 s1, s14, s1
	v_lshlrev_b32_e32 v202, 2, v2
	v_ashrrev_i32_e32 v9, 31, v8
	v_lshl_add_u64 v[10:11], s[0:1], 0, v[202:203]
	v_lshlrev_b64 v[18:19], 15, v[8:9]
	v_lshl_add_u64 v[18:19], v[10:11], 0, v[18:19]
	global_load_dword v17, v[18:19], off nt
	v_or_b32_e32 v18, 2, v8
	v_ashrrev_i32_e32 v19, 31, v18
	v_lshlrev_b64 v[18:19], 15, v[18:19]
	v_lshl_add_u64 v[18:19], v[10:11], 0, v[18:19]
	global_load_dword v20, v[18:19], off nt
	v_or_b32_e32 v18, 4, v8
	v_ashrrev_i32_e32 v19, 31, v18
	v_lshlrev_b64 v[18:19], 15, v[18:19]
	v_lshl_add_u64 v[18:19], v[10:11], 0, v[18:19]
	global_load_dword v21, v[18:19], off nt
	v_or_b32_e32 v18, 6, v8
	v_ashrrev_i32_e32 v19, 31, v18
	v_lshlrev_b64 v[18:19], 15, v[18:19]
	v_lshl_add_u64 v[18:19], v[10:11], 0, v[18:19]
	global_load_dword v22, v[18:19], off nt
	v_or_b32_e32 v18, 8, v8
	v_ashrrev_i32_e32 v19, 31, v18
	v_lshlrev_b64 v[18:19], 15, v[18:19]
	v_lshl_add_u64 v[18:19], v[10:11], 0, v[18:19]
	global_load_dword v23, v[18:19], off nt
	v_or_b32_e32 v18, 10, v8
	v_ashrrev_i32_e32 v19, 31, v18
	v_lshlrev_b64 v[18:19], 15, v[18:19]
	v_lshl_add_u64 v[18:19], v[10:11], 0, v[18:19]
	global_load_dword v24, v[18:19], off nt
	v_or_b32_e32 v18, 12, v8
	v_ashrrev_i32_e32 v19, 31, v18
	v_lshlrev_b64 v[18:19], 15, v[18:19]
	v_lshl_add_u64 v[18:19], v[10:11], 0, v[18:19]
	global_load_dword v25, v[18:19], off nt
	v_or_b32_e32 v18, 14, v8
	v_ashrrev_i32_e32 v19, 31, v18
	v_lshlrev_b64 v[18:19], 15, v[18:19]
	v_lshl_add_u64 v[18:19], v[10:11], 0, v[18:19]
	global_load_dword v26, v[18:19], off nt
	v_or_b32_e32 v18, 16, v8
	v_ashrrev_i32_e32 v19, 31, v18
	v_lshlrev_b64 v[18:19], 15, v[18:19]
	v_lshl_add_u64 v[18:19], v[10:11], 0, v[18:19]
	global_load_dword v27, v[18:19], off nt
	v_or_b32_e32 v18, 18, v8
	v_ashrrev_i32_e32 v19, 31, v18
	v_lshlrev_b64 v[18:19], 15, v[18:19]
	v_lshl_add_u64 v[18:19], v[10:11], 0, v[18:19]
	global_load_dword v28, v[18:19], off nt
	v_or_b32_e32 v18, 20, v8
	v_ashrrev_i32_e32 v19, 31, v18
	v_lshlrev_b64 v[18:19], 15, v[18:19]
	v_lshl_add_u64 v[18:19], v[10:11], 0, v[18:19]
	global_load_dword v29, v[18:19], off nt
	v_or_b32_e32 v18, 22, v8
	v_ashrrev_i32_e32 v19, 31, v18
	v_lshlrev_b64 v[18:19], 15, v[18:19]
	v_lshl_add_u64 v[18:19], v[10:11], 0, v[18:19]
	global_load_dword v30, v[18:19], off nt
	v_or_b32_e32 v18, 24, v8
	v_ashrrev_i32_e32 v19, 31, v18
	v_lshlrev_b64 v[18:19], 15, v[18:19]
	v_lshl_add_u64 v[18:19], v[10:11], 0, v[18:19]
	global_load_dword v31, v[18:19], off nt
	v_or_b32_e32 v18, 26, v8
	v_ashrrev_i32_e32 v19, 31, v18
	v_lshlrev_b64 v[18:19], 15, v[18:19]
	v_lshl_add_u64 v[18:19], v[10:11], 0, v[18:19]
	global_load_dword v32, v[18:19], off nt
	v_or_b32_e32 v18, 28, v8
	v_ashrrev_i32_e32 v19, 31, v18
	v_lshlrev_b64 v[18:19], 15, v[18:19]
	v_lshl_add_u64 v[18:19], v[10:11], 0, v[18:19]
	global_load_dword v33, v[18:19], off nt
	v_or_b32_e32 v18, 30, v8
	v_ashrrev_i32_e32 v19, 31, v18
	v_lshlrev_b64 v[18:19], 15, v[18:19]
	v_lshl_add_u64 v[18:19], v[10:11], 0, v[18:19]
	global_load_dword v34, v[18:19], off nt
	v_or_b32_e32 v18, 32, v8
	v_ashrrev_i32_e32 v19, 31, v18
	v_lshlrev_b64 v[18:19], 15, v[18:19]
	v_lshl_add_u64 v[18:19], v[10:11], 0, v[18:19]
	global_load_dword v35, v[18:19], off nt
	v_or_b32_e32 v18, 34, v8
	v_ashrrev_i32_e32 v19, 31, v18
	v_lshlrev_b64 v[18:19], 15, v[18:19]
	v_lshl_add_u64 v[18:19], v[10:11], 0, v[18:19]
	global_load_dword v36, v[18:19], off nt
	v_or_b32_e32 v18, 36, v8
	v_ashrrev_i32_e32 v19, 31, v18
	v_lshlrev_b64 v[18:19], 15, v[18:19]
	v_lshl_add_u64 v[18:19], v[10:11], 0, v[18:19]
	global_load_dword v37, v[18:19], off nt
	v_or_b32_e32 v18, 38, v8
	v_ashrrev_i32_e32 v19, 31, v18
	v_lshlrev_b64 v[18:19], 15, v[18:19]
	v_lshl_add_u64 v[18:19], v[10:11], 0, v[18:19]
	global_load_dword v38, v[18:19], off nt
	v_or_b32_e32 v18, 40, v8
	v_ashrrev_i32_e32 v19, 31, v18
	v_lshlrev_b64 v[18:19], 15, v[18:19]
	v_lshl_add_u64 v[18:19], v[10:11], 0, v[18:19]
	global_load_dword v39, v[18:19], off nt
	v_or_b32_e32 v18, 42, v8
	v_ashrrev_i32_e32 v19, 31, v18
	v_lshlrev_b64 v[18:19], 15, v[18:19]
	v_lshl_add_u64 v[18:19], v[10:11], 0, v[18:19]
	global_load_dword v40, v[18:19], off nt
	v_or_b32_e32 v18, 44, v8
	v_ashrrev_i32_e32 v19, 31, v18
	v_lshlrev_b64 v[18:19], 15, v[18:19]
	v_lshl_add_u64 v[18:19], v[10:11], 0, v[18:19]
	global_load_dword v41, v[18:19], off nt
	v_or_b32_e32 v18, 46, v8
	v_ashrrev_i32_e32 v19, 31, v18
	v_lshlrev_b64 v[18:19], 15, v[18:19]
	v_lshl_add_u64 v[18:19], v[10:11], 0, v[18:19]
	global_load_dword v42, v[18:19], off nt
	v_or_b32_e32 v18, 48, v8
	v_ashrrev_i32_e32 v19, 31, v18
	v_lshlrev_b64 v[18:19], 15, v[18:19]
	v_lshl_add_u64 v[18:19], v[10:11], 0, v[18:19]
	global_load_dword v43, v[18:19], off nt
	v_or_b32_e32 v18, 50, v8
	v_ashrrev_i32_e32 v19, 31, v18
	v_lshlrev_b64 v[18:19], 15, v[18:19]
	v_lshl_add_u64 v[18:19], v[10:11], 0, v[18:19]
	global_load_dword v44, v[18:19], off nt
	v_or_b32_e32 v18, 52, v8
	v_ashrrev_i32_e32 v19, 31, v18
	v_lshlrev_b64 v[18:19], 15, v[18:19]
	v_lshl_add_u64 v[18:19], v[10:11], 0, v[18:19]
	global_load_dword v45, v[18:19], off nt
	v_or_b32_e32 v18, 54, v8
	v_ashrrev_i32_e32 v19, 31, v18
	v_lshlrev_b64 v[18:19], 15, v[18:19]
	v_lshl_add_u64 v[18:19], v[10:11], 0, v[18:19]
	global_load_dword v46, v[18:19], off nt
	v_or_b32_e32 v18, 56, v8
	v_ashrrev_i32_e32 v19, 31, v18
	v_lshlrev_b64 v[18:19], 15, v[18:19]
	v_lshl_add_u64 v[18:19], v[10:11], 0, v[18:19]
	global_load_dword v47, v[18:19], off nt
	v_or_b32_e32 v18, 58, v8
	v_ashrrev_i32_e32 v19, 31, v18
	v_lshlrev_b64 v[18:19], 15, v[18:19]
	v_lshl_add_u64 v[18:19], v[10:11], 0, v[18:19]
	global_load_dword v48, v[18:19], off nt
	v_or_b32_e32 v18, 60, v8
	v_or_b32_e32 v8, 62, v8
	v_ashrrev_i32_e32 v19, 31, v18
	v_ashrrev_i32_e32 v9, 31, v8
	v_lshlrev_b64 v[18:19], 15, v[18:19]
	v_lshlrev_b64 v[8:9], 15, v[8:9]
	v_lshl_add_u64 v[18:19], v[10:11], 0, v[18:19]
	v_lshl_add_u64 v[8:9], v[10:11], 0, v[8:9]
	global_load_dword v18, v[18:19], off nt
	s_ashr_i32 s5, s4, 31
	global_load_dword v8, v[8:9], off nt
	v_add_u32_e32 v9, 0x400, v5
	s_waitcnt vmcnt(0)
	ds_write2_b32 v5, v17, v20 offset1:66
	ds_write2_b32 v5, v21, v22 offset0:132 offset1:198
	ds_write2_b32 v9, v23, v24 offset0:8 offset1:74
	ds_write2_b32 v9, v25, v26 offset0:140 offset1:206
	v_add_u32_e32 v9, 0x800, v5
	ds_write2_b32 v9, v27, v28 offset0:16 offset1:82
	ds_write2_b32 v9, v29, v30 offset0:148 offset1:214
	v_add_u32_e32 v9, 0xc00, v5
	ds_write2_b32 v9, v31, v32 offset0:24 offset1:90
	ds_write2_b32 v9, v33, v34 offset0:156 offset1:222
	v_add_u32_e32 v9, 0x1000, v5
	ds_write2_b32 v9, v35, v36 offset0:32 offset1:98
	ds_write2_b32 v9, v37, v38 offset0:164 offset1:230
	v_add_u32_e32 v9, 0x1400, v5
	ds_write2_b32 v9, v39, v40 offset0:40 offset1:106
	ds_write2_b32 v9, v41, v42 offset0:172 offset1:238
	v_add_u32_e32 v9, 0x1800, v5
	ds_write2_b32 v9, v43, v44 offset0:48 offset1:114
	ds_write2_b32 v9, v45, v46 offset0:180 offset1:246
	v_add_u32_e32 v9, 0x1c00, v5
	ds_write2_b32 v9, v47, v48 offset0:56 offset1:122
	ds_write2_b32 v9, v18, v8 offset0:188 offset1:254
	s_waitcnt lgkmcnt(0)
	ds_read2_b32 v[10:11], v13 offset0:33 offset1:41
	ds_read2_b32 v[22:23], v13 offset1:8
	ds_read2_b32 v[24:25], v13 offset0:66 offset1:74
	ds_read2_b32 v[26:27], v13 offset0:99 offset1:107
	ds_read2_b32 v[28:29], v13 offset0:132 offset1:140
	ds_read2_b32 v[30:31], v13 offset0:165 offset1:173
	ds_read2_b32 v[32:33], v13 offset0:198 offset1:206
	ds_read2_b32 v[34:35], v13 offset0:231 offset1:239
	s_waitcnt lgkmcnt(7)
	v_bfe_u32 v18, v10, 16, 1
	s_waitcnt lgkmcnt(6)
	v_bfe_u32 v17, v22, 16, 1
	v_add3_u32 v17, v22, v17, s53
	v_lshrrev_b32_e32 v17, 16, v17
	v_add3_u32 v10, v10, v18, s53
	v_and_or_b32 v18, v10, s77, v17
	s_waitcnt lgkmcnt(5)
	v_bfe_u32 v10, v24, 16, 1
	v_add3_u32 v10, v24, v10, s53
	s_waitcnt lgkmcnt(4)
	v_bfe_u32 v17, v26, 16, 1
	v_lshrrev_b32_e32 v10, 16, v10
	v_add3_u32 v17, v26, v17, s53
	v_and_or_b32 v19, v17, s77, v10
	s_waitcnt lgkmcnt(3)
	v_bfe_u32 v10, v28, 16, 1
	v_add3_u32 v10, v28, v10, s53
	s_waitcnt lgkmcnt(2)
	v_bfe_u32 v17, v30, 16, 1
	v_lshrrev_b32_e32 v10, 16, v10
	v_add3_u32 v17, v30, v17, s53
	v_and_or_b32 v20, v17, s77, v10
	s_waitcnt lgkmcnt(1)
	v_bfe_u32 v10, v32, 16, 1
	s_lshl_b64 s[0:1], s[4:5], 1
	v_add3_u32 v10, v32, v10, s53
	s_waitcnt lgkmcnt(0)
	v_bfe_u32 v17, v34, 16, 1
	s_add_u32 s0, s10, s0
	v_lshrrev_b32_e32 v10, 16, v10
	v_add3_u32 v17, v34, v17, s53
	v_or_b32_e32 v36, s2, v12
	s_addc_u32 s1, s11, s1
	v_lshlrev_b32_e32 v202, 1, v4
	v_and_or_b32 v21, v17, s77, v10
	v_ashrrev_i32_e32 v37, 31, v36
	v_bfe_u32 v10, v23, 16, 1
	v_lshl_add_u64 v[8:9], s[0:1], 0, v[202:203]
	v_lshlrev_b64 v[36:37], 12, v[36:37]
	v_add3_u32 v10, v23, v10, s53
	v_bfe_u32 v17, v11, 16, 1
	v_lshl_add_u64 v[36:37], v[8:9], 0, v[36:37]
	v_lshrrev_b32_e32 v10, 16, v10
	v_add3_u32 v11, v11, v17, s53
	global_store_dwordx4 v[36:37], v[18:21], off nt
	v_or_b32_e32 v36, s2, v15
	v_ashrrev_i32_e32 v37, 31, v36
	v_and_or_b32 v18, v11, s77, v10
	v_bfe_u32 v10, v25, 16, 1
	v_add3_u32 v10, v25, v10, s53
	v_bfe_u32 v11, v27, 16, 1
	v_lshrrev_b32_e32 v10, 16, v10
	v_add3_u32 v11, v27, v11, s53
	v_and_or_b32 v19, v11, s77, v10
	v_bfe_u32 v10, v29, 16, 1
	v_add3_u32 v10, v29, v10, s53
	v_bfe_u32 v11, v31, 16, 1
	v_lshrrev_b32_e32 v10, 16, v10
	v_add3_u32 v11, v31, v11, s53
	v_and_or_b32 v20, v11, s77, v10
	v_bfe_u32 v10, v33, 16, 1
	v_add3_u32 v10, v33, v10, s53
	v_bfe_u32 v11, v35, 16, 1
	v_lshrrev_b32_e32 v10, 16, v10
	v_add3_u32 v11, v35, v11, s53
	v_and_or_b32 v21, v11, s77, v10
	v_or_b32_e32 v10, s2, v14
	v_ashrrev_i32_e32 v11, 31, v10
	v_lshlrev_b64 v[10:11], 12, v[10:11]
	v_lshl_add_u64 v[10:11], v[8:9], 0, v[10:11]
	global_store_dwordx4 v[10:11], v[18:21], off nt
	ds_read2_b32 v[10:11], v13 offset0:49 offset1:57
	ds_read2_b32 v[22:23], v13 offset0:16 offset1:24
	ds_read2_b32 v[24:25], v13 offset0:82 offset1:90
	ds_read2_b32 v[26:27], v13 offset0:115 offset1:123
	ds_read2_b32 v[28:29], v13 offset0:148 offset1:156
	ds_read2_b32 v[30:31], v13 offset0:181 offset1:189
	ds_read2_b32 v[32:33], v13 offset0:214 offset1:222
	ds_read2_b32 v[34:35], v13 offset0:247 offset1:255
	s_waitcnt lgkmcnt(7)
	v_bfe_u32 v18, v10, 16, 1
	s_waitcnt lgkmcnt(6)
	v_bfe_u32 v17, v22, 16, 1
	v_add3_u32 v17, v22, v17, s53
	v_lshrrev_b32_e32 v17, 16, v17
	v_add3_u32 v10, v10, v18, s53
	v_and_or_b32 v18, v10, s77, v17
	s_waitcnt lgkmcnt(5)
	v_bfe_u32 v10, v24, 16, 1
	v_add3_u32 v10, v24, v10, s53
	s_waitcnt lgkmcnt(4)
	v_bfe_u32 v17, v26, 16, 1
	v_lshrrev_b32_e32 v10, 16, v10
	v_add3_u32 v17, v26, v17, s53
	v_and_or_b32 v19, v17, s77, v10
	s_waitcnt lgkmcnt(3)
	v_bfe_u32 v10, v28, 16, 1
	v_add3_u32 v10, v28, v10, s53
	s_waitcnt lgkmcnt(2)
	v_bfe_u32 v17, v30, 16, 1
	v_lshrrev_b32_e32 v10, 16, v10
	v_add3_u32 v17, v30, v17, s53
	v_and_or_b32 v20, v17, s77, v10
	s_waitcnt lgkmcnt(1)
	v_bfe_u32 v10, v32, 16, 1
	v_add3_u32 v10, v32, v10, s53
	s_waitcnt lgkmcnt(0)
	v_bfe_u32 v17, v34, 16, 1
	v_lshrrev_b32_e32 v10, 16, v10
	v_add3_u32 v17, v34, v17, s53
	v_and_or_b32 v21, v17, s77, v10
	v_bfe_u32 v10, v23, 16, 1
	v_lshlrev_b64 v[36:37], 12, v[36:37]
	v_add3_u32 v10, v23, v10, s53
	v_bfe_u32 v17, v11, 16, 1
	v_lshl_add_u64 v[36:37], v[8:9], 0, v[36:37]
	v_lshrrev_b32_e32 v10, 16, v10
	v_add3_u32 v11, v11, v17, s53
	global_store_dwordx4 v[36:37], v[18:21], off nt
	v_readlane_b32 s17, v251, 15
	v_readlane_b32 s18, v251, 16
	v_and_or_b32 v18, v11, s77, v10
	v_bfe_u32 v10, v25, 16, 1
	v_add3_u32 v10, v25, v10, s53
	v_bfe_u32 v11, v27, 16, 1
	v_lshrrev_b32_e32 v10, 16, v10
	v_add3_u32 v11, v27, v11, s53
	v_and_or_b32 v19, v11, s77, v10
	v_bfe_u32 v10, v29, 16, 1
	v_add3_u32 v10, v29, v10, s53
	v_bfe_u32 v11, v31, 16, 1
	v_lshrrev_b32_e32 v10, 16, v10
	v_add3_u32 v11, v31, v11, s53
	v_and_or_b32 v20, v11, s77, v10
	v_bfe_u32 v10, v33, 16, 1
	v_add3_u32 v10, v33, v10, s53
	v_bfe_u32 v11, v35, 16, 1
	v_lshrrev_b32_e32 v10, 16, v10
	v_add3_u32 v11, v35, v11, s53
	v_and_or_b32 v21, v11, s77, v10
	v_or_b32_e32 v10, s2, v16
	v_ashrrev_i32_e32 v11, 31, v10
	v_lshlrev_b64 v[10:11], 12, v[10:11]
	v_lshl_add_u64 v[8:9], v[8:9], 0, v[10:11]
	global_store_dwordx4 v[8:9], v[18:21], off nt
	s_waitcnt lgkmcnt(0)
	v_readlane_b32 s19, v251, 17
	v_readlane_b32 s20, v251, 18
	v_readlane_b32 s21, v251, 19
	v_readlane_b32 s24, v251, 22
	v_readlane_b32 s25, v251, 23
	v_readlane_b32 s26, v251, 24
	v_readlane_b32 s27, v251, 25
	v_readlane_b32 s28, v251, 26
	v_readlane_b32 s29, v251, 27
	v_readlane_b32 s30, v251, 28
	v_readlane_b32 s31, v251, 29
	s_branch .LBB0_1605
